# hw-bf16-cvt_pk-instead-of-bit-trick-plus-acc-init-hoist
# speedup vs baseline: 1.0988x; 1.0074x over previous
.LBB0_28:
	s_movk_i32 s0, 0x4000
	v_cmp_gt_i32_e32 vcc, s0, v104
	s_or_b64 s[0:1], s[6:7], vcc
	s_and_saveexec_b64 s[8:9], s[0:1]
	s_cbranch_execz .LBB0_27
	s_movk_i32 s0, 0x4000
	v_cmp_gt_i32_e32 vcc, s0, v104
	v_min_i32_e32 v0, 0x4000, v104
	v_ashrrev_i32_e32 v1, 31, v104
	v_readlane_b32 s0, v253, 42
	v_ashrrev_i32_e32 v172, 13, v0
	v_add_u32_e32 v0, 0xffffc000, v104
	v_cndmask_b32_e32 v105, 0, v1, vcc
	v_mov_b32_e32 v2, s0
	v_mov_b32_e32 v3, s89
	v_readlane_b32 s0, v255, 17
	v_cndmask_b32_e32 v0, v0, v104, vcc
	v_mov_b32_e32 v1, v105
	v_cndmask_b32_e32 v3, v2, v3, vcc
	v_mov_b32_e32 v2, s0
	v_mov_b32_e32 v4, s88
	v_cndmask_b32_e32 v2, v2, v4, vcc
	v_lshlrev_b64 v[0:1], 12, v[0:1]
	v_lshl_add_u64 v[120:121], v[2:3], 0, v[0:1]
	v_add_u32_e32 v0, s10, v172
	v_mul_hi_i32_i24_e32 v33, 0x6000, v0
	v_mul_i32_i24_e32 v32, 0x6000, v0
	v_lshl_add_u64 v[0:1], v[120:121], 0, v[192:193]
	s_movk_i32 s12, 0x1000
	v_add_co_u32_e32 v2, vcc, s12, v0
	s_movk_i32 s13, 0x2000
	s_nop 0
	v_addc_co_u32_e32 v3, vcc, 0, v1, vcc
	v_add_co_u32_e32 v4, vcc, s13, v0
	global_load_dwordx4 v[92:95], v[0:1], off nt
	global_load_dwordx4 v[88:91], v[0:1], off offset:1024 nt
	global_load_dwordx4 v[84:87], v[0:1], off offset:2048 nt
	global_load_dwordx4 v[80:83], v[0:1], off offset:3072 nt
	v_addc_co_u32_e32 v5, vcc, 0, v1, vcc
	v_add_co_u32_e32 v0, vcc, s73, v0
	global_load_dwordx4 v[76:79], v[4:5], off offset:-4096 nt
	global_load_dwordx4 v[72:75], v[2:3], off offset:1024 nt
	global_load_dwordx4 v[68:71], v[2:3], off offset:2048 nt
	global_load_dwordx4 v[64:67], v[2:3], off offset:3072 nt
	global_load_dwordx4 v[28:31], v[4:5], off nt
	global_load_dwordx4 v[24:27], v[4:5], off offset:1024 nt
	global_load_dwordx4 v[20:23], v[4:5], off offset:2048 nt
	global_load_dwordx4 v[16:19], v[4:5], off offset:3072 nt
	v_addc_co_u32_e32 v1, vcc, 0, v1, vcc
	global_load_dwordx4 v[12:15], v[0:1], off nt
	global_load_dwordx4 v[8:11], v[0:1], off offset:1024 nt
	global_load_dwordx4 v[4:7], v[0:1], off offset:2048 nt
	s_nop 0
	global_load_dwordx4 v[0:3], v[0:1], off offset:3072 nt
	v_add_u32_e32 v34, 1, v104
	v_ashrrev_i32_e32 v35, 31, v34
	v_lshlrev_b64 v[116:117], 11, v[34:35]
	v_add_u32_e32 v34, 2, v104
	v_ashrrev_i32_e32 v35, 31, v34
	v_lshlrev_b64 v[114:115], 11, v[34:35]
	v_add_u32_e32 v34, 3, v104
	v_ashrrev_i32_e32 v35, 31, v34
	v_cmp_lt_i32_e32 vcc, v211, v210
	v_lshlrev_b64 v[112:113], 11, v[34:35]
	v_lshl_add_u64 v[32:33], s[90:91], 0, v[32:33]
	v_cndmask_b32_e32 v34, v209, v211, vcc
	v_cmp_lt_i32_e32 vcc, v212, v210
	v_lshlrev_b32_e32 v107, 2, v34
	v_lshl_add_u64 v[36:37], v[32:33], 0, v[192:193]
	v_cndmask_b32_e32 v34, v209, v212, vcc
	v_cmp_lt_i32_e32 vcc, v206, v210
	v_lshlrev_b32_e32 v109, 2, v34
	s_mov_b64 s[0:1], 0x345d000
	v_cndmask_b32_e32 v34, v209, v206, vcc
	v_cmp_lt_i32_e32 vcc, v213, v210
	v_lshlrev_b32_e32 v111, 2, v34
	v_lshl_add_u64 v[62:63], v[36:37], 0, s[0:1]
	v_cndmask_b32_e32 v34, v209, v213, vcc
	v_cmp_lt_i32_e32 vcc, v216, v210
	v_lshlrev_b32_e32 v169, 2, v34
	s_mov_b32 s0, 0x345d000
	v_cndmask_b32_e32 v34, v209, v216, vcc
	v_cmp_lt_i32_e32 vcc, v217, v210
	v_lshlrev_b32_e32 v170, 2, v34
	v_lshlrev_b64 v[118:119], 11, v[104:105]
	v_cndmask_b32_e32 v34, v209, v217, vcc
	v_add_co_u32_e32 v36, vcc, s0, v36
	v_lshl_add_u64 v[60:61], v[96:97], 0, v[118:119]
	s_nop 0
	v_addc_co_u32_e32 v37, vcc, 0, v37, vcc
	v_lshlrev_b32_e32 v171, 2, v34
	global_load_dwordx4 v[32:35], v[98:99], off
	v_lshl_add_u64 v[140:141], v[96:97], 0, v[116:117]
	global_load_dwordx4 v[36:39], v[36:37], off
	s_nop 0
	global_load_dwordx4 v[40:43], v[98:99], off offset:1024
	global_load_dwordx4 v[44:47], v[62:63], off offset:1024
	global_load_dwordx4 v[48:51], v[98:99], off offset:2048
	global_load_dwordx4 v[52:55], v[62:63], off offset:2048
	s_mov_b32 s0, 0x358637bd
	s_mov_b32 s16, 0x3a800000
	s_mov_b32 s14, 0x800000
	v_lshl_add_u64 v[134:135], v[96:97], 0, v[114:115]
	v_lshl_add_u64 v[124:125], v[96:97], 0, v[112:113]
	s_waitcnt vmcnt(21)
	v_mov_b32_e32 v138, v92
	s_waitcnt vmcnt(17)
	v_mov_b32_e32 v136, v76
	s_waitcnt vmcnt(16)
	v_mov_b32_e32 v142, v72
	v_mov_b32_e32 v143, v74
	v_mov_b32_e32 v74, v73
	v_mov_b32_e32 v137, v78
	s_waitcnt vmcnt(12)
	v_mov_b32_e32 v72, v24
	v_mov_b32_e32 v73, v26
	v_mov_b32_e32 v26, v25
	v_mov_b32_e32 v24, v68
	v_mov_b32_e32 v25, v70
	v_mov_b32_e32 v70, v69
	s_waitcnt vmcnt(7)
	v_mov_b32_e32 v68, v4
	v_mov_b32_e32 v69, v6
	v_mov_b32_e32 v6, v5
	global_load_dwordx4 v[56:59], v[98:99], off offset:3072
	global_load_dwordx2 v[4:5], v[60:61], off offset:1536 nt
	v_mov_b32_e32 v78, v77
	v_mov_b32_e32 v144, v84
	v_mov_b32_e32 v145, v86
	v_mov_b32_e32 v86, v85
	v_mov_b32_e32 v84, v20
	v_mov_b32_e32 v85, v22
	v_mov_b32_e32 v22, v21
	v_mov_b32_e32 v139, v94
	v_mov_b32_e32 v94, v93
	s_waitcnt vmcnt(7)
	v_mov_b32_e32 v130, v32
	v_mov_b32_e32 v131, v34
	s_waitcnt vmcnt(6)
	v_mov_b32_e32 v122, v36
	s_waitcnt vmcnt(4)
	v_mov_b32_e32 v76, v44
	v_mov_b32_e32 v77, v46
	v_mov_b32_e32 v46, v45
	v_mov_b32_e32 v44, v8
	v_mov_b32_e32 v45, v10
	v_mov_b32_e32 v10, v9
	s_waitcnt vmcnt(2)
	v_mov_b32_e32 v8, v52
	v_mov_b32_e32 v9, v54
	v_mov_b32_e32 v54, v53
	v_mov_b32_e32 v123, v38
	v_mov_b32_e32 v38, v37
	v_mov_b32_e32 v36, v28
	v_mov_b32_e32 v37, v30
	v_mov_b32_e32 v30, v29
	v_mov_b32_e32 v28, v12
	v_mov_b32_e32 v29, v14
	v_mov_b32_e32 v14, v13
	v_mov_b32_e32 v12, v88
	v_mov_b32_e32 v13, v90
	v_mov_b32_e32 v90, v89
	v_mov_b32_e32 v34, v33
	v_mov_b32_e32 v32, v80
	v_mov_b32_e32 v33, v82
	v_mov_b32_e32 v82, v81
	s_waitcnt vmcnt(0)
	v_and_b32_e32 v21, 0xffff0000, v5
	v_and_b32_e32 v20, 0xffff0000, v4
	v_lshlrev_b32_e32 v52, 16, v4
	v_lshlrev_b32_e32 v53, 16, v5
	global_load_dwordx2 v[4:5], v[60:61], off offset:1024 nt
	v_mov_b32_e32 v93, v52
	v_mov_b32_e32 v127, v53
	v_mov_b32_e32 v89, v21
	s_waitcnt vmcnt(0)
	v_and_b32_e32 v146, 0xffff0000, v4
	v_and_b32_e32 v147, 0xffff0000, v5
	v_lshlrev_b32_e32 v148, 16, v4
	v_lshlrev_b32_e32 v149, 16, v5
	v_mov_b32_e32 v4, v146
	v_mov_b32_e32 v5, v20
	v_pk_mul_f32 v[4:5], v[4:5], v[4:5]
	v_mov_b32_e32 v92, v148
	v_mov_b32_e32 v126, v149
	v_pk_fma_f32 v[4:5], v[92:93], v[92:93], v[4:5]
	v_mov_b32_e32 v88, v147
	v_pk_fma_f32 v[4:5], v[126:127], v[126:127], v[4:5]
	s_nop 0
	v_pk_fma_f32 v[88:89], v[88:89], v[88:89], v[4:5]
	global_load_dwordx2 v[4:5], v[60:61], off offset:512 nt
	s_waitcnt vmcnt(0)
	v_and_b32_e32 v151, 0xffff0000, v5
	v_and_b32_e32 v150, 0xffff0000, v4
	v_lshlrev_b32_e32 v152, 16, v4
	v_lshlrev_b32_e32 v153, 16, v5
	global_load_dwordx2 v[4:5], v[60:61], off nt
	v_mov_b32_e32 v127, v152
	v_mov_b32_e32 v129, v153
	v_mov_b32_e32 v61, v151
	s_waitcnt vmcnt(0)
	v_and_b32_e32 v92, 0xffff0000, v4
	v_and_b32_e32 v93, 0xffff0000, v5
	v_lshlrev_b32_e32 v154, 16, v4
	v_lshlrev_b32_e32 v155, 16, v5
	v_mov_b32_e32 v4, v92
	v_mov_b32_e32 v5, v150
	v_pk_mul_f32 v[4:5], v[4:5], v[4:5]
	v_mov_b32_e32 v126, v154
	v_mov_b32_e32 v128, v155
	v_pk_fma_f32 v[4:5], v[126:127], v[126:127], v[4:5]
	v_mov_b32_e32 v60, v93
	v_pk_fma_f32 v[4:5], v[128:129], v[128:129], v[4:5]
	v_mov_b32_e32 v128, v40
	v_mov_b32_e32 v129, v42
	v_mov_b32_e32 v42, v41
	global_load_dwordx2 v[40:41], v[140:141], off offset:1536 nt
	v_pk_fma_f32 v[156:157], v[60:61], v[60:61], v[4:5]
	global_load_dwordx4 v[60:63], v[62:63], off offset:3072
	v_mov_b32_e32 v126, v48
	v_mov_b32_e32 v127, v50
	v_mov_b32_e32 v50, v49
	v_mov_b32_e32 v4, v56
	v_mov_b32_e32 v5, v58
	v_mov_b32_e32 v58, v57
	s_waitcnt vmcnt(1)
	v_and_b32_e32 v159, 0xffff0000, v41
	v_and_b32_e32 v158, 0xffff0000, v40
	v_lshlrev_b32_e32 v160, 16, v40
	v_lshlrev_b32_e32 v161, 16, v41
	global_load_dwordx2 v[40:41], v[140:141], off offset:1024 nt
	s_waitcnt vmcnt(1)
	v_mov_b32_e32 v132, v60
	v_mov_b32_e32 v133, v62
	v_mov_b32_e32 v62, v61
	v_mov_b32_e32 v61, v160
	v_mov_b32_e32 v81, v161
	v_mov_b32_e32 v57, v159
	s_waitcnt vmcnt(0)
	v_and_b32_e32 v48, 0xffff0000, v40
	v_and_b32_e32 v49, 0xffff0000, v41
	v_lshlrev_b32_e32 v162, 16, v40
	v_lshlrev_b32_e32 v163, 16, v41
	v_mov_b32_e32 v40, v48
	v_mov_b32_e32 v41, v158
	v_pk_mul_f32 v[40:41], v[40:41], v[40:41]
	v_mov_b32_e32 v60, v162
	v_mov_b32_e32 v80, v163
	v_pk_fma_f32 v[40:41], v[60:61], v[60:61], v[40:41]
	v_mov_b32_e32 v56, v49
	v_pk_fma_f32 v[40:41], v[80:81], v[80:81], v[40:41]
	s_nop 0
	v_pk_fma_f32 v[40:41], v[56:57], v[56:57], v[40:41]
	global_load_dwordx2 v[56:57], v[140:141], off offset:512 nt
	s_waitcnt vmcnt(0)
	v_and_b32_e32 v165, 0xffff0000, v57
	v_and_b32_e32 v164, 0xffff0000, v56
	v_lshlrev_b32_e32 v166, 16, v56
	v_lshlrev_b32_e32 v167, 16, v57
	global_load_dwordx2 v[56:57], v[140:141], off nt
	v_mov_b32_e32 v81, v166
	v_mov_b32_e32 v141, v167
	v_mov_b32_e32 v61, v165
	s_waitcnt vmcnt(0)
	v_and_b32_e32 v174, 0xffff0000, v56
	v_and_b32_e32 v175, 0xffff0000, v57
	v_lshlrev_b32_e32 v176, 16, v56
	v_lshlrev_b32_e32 v177, 16, v57
	v_mov_b32_e32 v56, v174
	v_mov_b32_e32 v57, v164
	v_pk_mul_f32 v[56:57], v[56:57], v[56:57]
	v_mov_b32_e32 v80, v176
	v_mov_b32_e32 v140, v177
	v_pk_fma_f32 v[56:57], v[80:81], v[80:81], v[56:57]
	v_mov_b32_e32 v60, v175
	v_pk_fma_f32 v[56:57], v[140:141], v[140:141], v[56:57]
	v_mov_b64_e32 v[140:141], s[0:1]
	v_pk_fma_f32 v[56:57], v[60:61], v[60:61], v[56:57]
	v_mov_b32_e32 v61, v156
	v_mov_b32_e32 v60, v56
	v_mov_b32_e32 v156, v57
	v_pk_add_f32 v[56:57], v[60:61], v[156:157]
	v_mov_b32_e32 v60, v40
	v_mov_b32_e32 v61, v88
	v_pk_add_f32 v[56:57], v[56:57], v[60:61]
	v_mov_b32_e32 v88, v41
	v_pk_add_f32 v[40:41], v[56:57], v[88:89]
	ds_bpermute_b32 v57, v107, v41
	ds_bpermute_b32 v56, v107, v40
	s_waitcnt lgkmcnt(0)
	v_pk_add_f32 v[40:41], v[40:41], v[56:57]
	ds_bpermute_b32 v57, v109, v41
	ds_bpermute_b32 v56, v109, v40
	s_waitcnt lgkmcnt(0)
	v_pk_add_f32 v[40:41], v[40:41], v[56:57]
	ds_bpermute_b32 v57, v111, v41
	ds_bpermute_b32 v56, v111, v40
	s_waitcnt lgkmcnt(0)
	v_pk_add_f32 v[40:41], v[40:41], v[56:57]
	ds_bpermute_b32 v57, v169, v41
	ds_bpermute_b32 v56, v169, v40
	s_waitcnt lgkmcnt(0)
	v_pk_add_f32 v[40:41], v[40:41], v[56:57]
	ds_bpermute_b32 v57, v170, v41
	ds_bpermute_b32 v56, v170, v40
	s_waitcnt lgkmcnt(0)
	v_pk_add_f32 v[40:41], v[40:41], v[56:57]
	ds_bpermute_b32 v57, v171, v41
	ds_bpermute_b32 v56, v171, v40
	s_waitcnt lgkmcnt(0)
	v_pk_add_f32 v[40:41], v[40:41], v[56:57]
	s_nop 0
	v_pk_fma_f32 v[156:157], v[40:41], s[16:17], v[140:141] op_sel_hi:[1,0,0]
	s_nop 0
	v_mul_f32_e32 v40, 0x4b800000, v157
	v_cmp_gt_f32_e64 s[0:1], s14, v157
	v_cmp_gt_f32_e32 vcc, s14, v156
	s_nop 0
	v_cndmask_b32_e64 v40, v157, v40, s[0:1]
	v_rsq_f32_e32 v40, v40
	s_nop 0
	v_mul_f32_e32 v41, 0x45800000, v40
	v_cndmask_b32_e64 v178, v40, v41, s[0:1]
	v_pk_mul_f32 v[40:41], v[178:179], v[154:155] op_sel_hi:[0,1]
	v_pk_mul_f32 v[40:41], v[40:41], v[130:131]
	v_pk_mul_f32 v[56:57], v[178:179], v[92:93] op_sel_hi:[0,1]
	v_pk_fma_f32 v[92:93], v[40:41], v[122:123], v[138:139]
	v_pk_mul_f32 v[40:41], v[178:179], v[152:153] op_sel_hi:[0,1]
	v_pk_mul_f32 v[56:57], v[56:57], v[34:35]
	v_pk_mul_f32 v[40:41], v[40:41], v[128:129]
	v_pk_fma_f32 v[88:89], v[56:57], v[38:39], v[94:95]
	v_pk_mul_f32 v[56:57], v[178:179], v[150:151] op_sel_hi:[0,1]
	v_pk_fma_f32 v[80:81], v[40:41], v[76:77], v[12:13]
	v_pk_mul_f32 v[12:13], v[178:179], v[148:149] op_sel_hi:[0,1]
	v_pk_mul_f32 v[56:57], v[56:57], v[42:43]
	v_pk_mul_f32 v[12:13], v[12:13], v[126:127]
	v_pk_fma_f32 v[60:61], v[56:57], v[46:47], v[90:91]
	v_pk_fma_f32 v[56:57], v[12:13], v[8:9], v[144:145]
	v_pk_mul_f32 v[12:13], v[178:179], v[52:53] op_sel_hi:[0,1]
	v_pk_mul_f32 v[20:21], v[178:179], v[20:21] op_sel_hi:[0,1]
	v_pk_mul_f32 v[12:13], v[12:13], v[4:5]
	v_pk_mul_f32 v[20:21], v[20:21], v[58:59]
	v_pk_fma_f32 v[32:33], v[12:13], v[132:133], v[32:33]
	v_pk_fma_f32 v[12:13], v[20:21], v[62:63], v[82:83]
	v_mul_f32_e32 v20, 0x4b800000, v156
	v_cndmask_b32_e32 v20, v156, v20, vcc
	v_rsq_f32_e32 v20, v20
	v_pk_mul_f32 v[40:41], v[178:179], v[146:147] op_sel_hi:[0,1]
	v_pk_mul_f32 v[40:41], v[40:41], v[50:51]
	v_mul_f32_e32 v21, 0x45800000, v20
	v_cndmask_b32_e32 v20, v20, v21, vcc
	v_pk_mul_f32 v[48:49], v[20:21], v[48:49] op_sel_hi:[0,1]
	v_pk_mul_f32 v[48:49], v[48:49], v[50:51]
	v_pk_mul_f32 v[82:83], v[20:21], v[174:175] op_sel_hi:[0,1]
	v_pk_fma_f32 v[48:49], v[48:49], v[54:55], v[70:71]
	v_mov_b32_e32 v70, v64
	v_mov_b32_e32 v71, v66
	v_mov_b32_e32 v66, v65
	global_load_dwordx2 v[64:65], v[134:135], off offset:1536 nt
	v_pk_mul_f32 v[82:83], v[82:83], v[34:35]
	v_pk_mul_f32 v[52:53], v[20:21], v[176:177] op_sel_hi:[0,1]
	v_pk_fma_f32 v[82:83], v[82:83], v[38:39], v[78:79]
	v_pk_mul_f32 v[78:79], v[20:21], v[164:165] op_sel_hi:[0,1]
	v_pk_mul_f32 v[90:91], v[78:79], v[42:43]
	v_pk_mul_f32 v[52:53], v[52:53], v[130:131]
	v_pk_fma_f32 v[74:75], v[90:91], v[46:47], v[74:75]
	v_pk_fma_f32 v[40:41], v[40:41], v[54:55], v[86:87]
	v_pk_fma_f32 v[86:87], v[52:53], v[122:123], v[136:137]
	v_pk_mul_f32 v[52:53], v[20:21], v[166:167] op_sel_hi:[0,1]
	v_pk_mul_f32 v[52:53], v[52:53], v[128:129]
	s_waitcnt vmcnt(0)
	v_and_b32_e32 v91, 0xffff0000, v65
	v_and_b32_e32 v90, 0xffff0000, v64
	v_lshlrev_b32_e32 v94, 16, v64
	v_lshlrev_b32_e32 v95, 16, v65
	global_load_dwordx2 v[64:65], v[134:135], off offset:1024 nt
	v_pk_fma_f32 v[78:79], v[52:53], v[76:77], v[142:143]
	v_pk_mul_f32 v[52:53], v[20:21], v[162:163] op_sel_hi:[0,1]
	v_pk_mul_f32 v[52:53], v[52:53], v[126:127]
	v_mov_b32_e32 v143, v95
	v_pk_fma_f32 v[52:53], v[52:53], v[8:9], v[24:25]
	v_pk_mul_f32 v[24:25], v[20:21], v[160:161] op_sel_hi:[0,1]
	v_pk_mul_f32 v[24:25], v[24:25], v[4:5]
	v_pk_mul_f32 v[20:21], v[20:21], v[158:159] op_sel_hi:[0,1]
	v_pk_fma_f32 v[24:25], v[24:25], v[132:133], v[70:71]
	v_mov_b32_e32 v71, v94
	v_pk_mul_f32 v[20:21], v[20:21], v[58:59]
	s_waitcnt vmcnt(0)
	v_and_b32_e32 v136, 0xffff0000, v64
	v_and_b32_e32 v137, 0xffff0000, v65
	v_lshlrev_b32_e32 v138, 16, v64
	v_lshlrev_b32_e32 v139, 16, v65
	v_mov_b32_e32 v64, v136
	v_mov_b32_e32 v65, v90
	v_pk_mul_f32 v[64:65], v[64:65], v[64:65]
	v_mov_b32_e32 v70, v138
	v_pk_fma_f32 v[64:65], v[70:71], v[70:71], v[64:65]
	global_load_dwordx2 v[70:71], v[134:135], off offset:512 nt
	v_mov_b32_e32 v142, v139
	global_load_dwordx2 v[134:135], v[134:135], off nt
	v_pk_fma_f32 v[20:21], v[20:21], v[62:63], v[66:67]
	v_mov_b32_e32 v66, v137
	v_mov_b32_e32 v67, v91
	v_pk_fma_f32 v[64:65], v[142:143], v[142:143], v[64:65]
	s_waitcnt vmcnt(1)
	v_lshlrev_b32_e32 v142, 16, v70
	v_pk_fma_f32 v[66:67], v[66:67], v[66:67], v[64:65]
	v_and_b32_e32 v64, 0xffff0000, v70
	s_waitcnt vmcnt(0)
	v_and_b32_e32 v70, 0xffff0000, v134
	v_and_b32_e32 v65, 0xffff0000, v71
	v_lshlrev_b32_e32 v143, 16, v71
	v_and_b32_e32 v71, 0xffff0000, v135
	v_lshlrev_b32_e32 v144, 16, v134
	v_lshlrev_b32_e32 v145, 16, v135
	v_mov_b32_e32 v134, v70
	v_mov_b32_e32 v135, v64
	v_pk_mul_f32 v[134:135], v[134:135], v[134:135]
	v_mov_b32_e32 v148, v144
	v_mov_b32_e32 v149, v142
	v_mov_b32_e32 v150, v145
	v_mov_b32_e32 v151, v143
	v_pk_fma_f32 v[134:135], v[148:149], v[148:149], v[134:135]
	v_mov_b32_e32 v146, v71
	v_mov_b32_e32 v147, v65
	v_pk_fma_f32 v[134:135], v[150:151], v[150:151], v[134:135]
	s_nop 0
	v_pk_fma_f32 v[154:155], v[146:147], v[146:147], v[134:135]
	v_mov_b32_e32 v134, v16
	v_mov_b32_e32 v135, v18
	v_mov_b32_e32 v18, v17
	global_load_dwordx2 v[16:17], v[124:125], off offset:1536 nt
	s_waitcnt vmcnt(0)
	v_and_b32_e32 v147, 0xffff0000, v17
	v_and_b32_e32 v146, 0xffff0000, v16
	v_lshlrev_b32_e32 v148, 16, v16
	v_lshlrev_b32_e32 v149, 16, v17
	global_load_dwordx2 v[16:17], v[124:125], off offset:1024 nt
	v_mov_b32_e32 v159, v148
	v_mov_b32_e32 v161, v149
	v_mov_b32_e32 v157, v147
	s_waitcnt vmcnt(0)
	v_and_b32_e32 v150, 0xffff0000, v16
	v_and_b32_e32 v151, 0xffff0000, v17
	v_lshlrev_b32_e32 v152, 16, v16
	v_lshlrev_b32_e32 v153, 16, v17
	v_mov_b32_e32 v16, v150
	v_mov_b32_e32 v17, v146
	v_pk_mul_f32 v[16:17], v[16:17], v[16:17]
	v_mov_b32_e32 v158, v152
	v_pk_fma_f32 v[16:17], v[158:159], v[158:159], v[16:17]
	global_load_dwordx2 v[158:159], v[124:125], off offset:512 nt
	v_mov_b32_e32 v160, v153
	global_load_dwordx2 v[124:125], v[124:125], off nt
	v_mov_b32_e32 v156, v151
	v_pk_fma_f32 v[16:17], v[160:161], v[160:161], v[16:17]
	s_waitcnt vmcnt(0)
	v_and_b32_e32 v160, 0xffff0000, v124
	v_pk_fma_f32 v[16:17], v[156:157], v[156:157], v[16:17]
	v_and_b32_e32 v156, 0xffff0000, v158
	v_lshlrev_b32_e32 v158, 16, v158
	v_lshlrev_b32_e32 v124, 16, v124
	v_mov_b32_e32 v162, v160
	v_mov_b32_e32 v163, v156
	v_and_b32_e32 v157, 0xffff0000, v159
	v_lshlrev_b32_e32 v159, 16, v159
	v_and_b32_e32 v161, 0xffff0000, v125
	v_lshlrev_b32_e32 v125, 16, v125
	v_pk_mul_f32 v[162:163], v[162:163], v[162:163]
	v_mov_b32_e32 v166, v124
	v_mov_b32_e32 v167, v158
	v_mov_b32_e32 v174, v125
	v_mov_b32_e32 v175, v159
	v_pk_fma_f32 v[162:163], v[166:167], v[166:167], v[162:163]
	v_mov_b32_e32 v164, v161
	v_mov_b32_e32 v165, v157
	v_pk_fma_f32 v[162:163], v[174:175], v[174:175], v[162:163]
	s_nop 0
	v_pk_fma_f32 v[162:163], v[164:165], v[164:165], v[162:163]
	v_mov_b32_e32 v165, v154
	v_mov_b32_e32 v164, v162
	v_mov_b32_e32 v154, v163
	v_pk_add_f32 v[154:155], v[164:165], v[154:155]
	v_mov_b32_e32 v162, v16
	v_mov_b32_e32 v163, v66
	v_pk_add_f32 v[154:155], v[154:155], v[162:163]
	v_mov_b32_e32 v66, v17
	v_pk_add_f32 v[16:17], v[154:155], v[66:67]
	ds_bpermute_b32 v67, v107, v17
	ds_bpermute_b32 v66, v107, v16
	s_waitcnt lgkmcnt(0)
	v_pk_add_f32 v[16:17], v[16:17], v[66:67]
	ds_bpermute_b32 v67, v109, v17
	ds_bpermute_b32 v66, v109, v16
	s_waitcnt lgkmcnt(0)
	v_pk_add_f32 v[16:17], v[16:17], v[66:67]
	ds_bpermute_b32 v67, v111, v17
	ds_bpermute_b32 v66, v111, v16
	s_waitcnt lgkmcnt(0)
	v_pk_add_f32 v[16:17], v[16:17], v[66:67]
	ds_bpermute_b32 v67, v169, v17
	ds_bpermute_b32 v66, v169, v16
	s_waitcnt lgkmcnt(0)
	v_pk_add_f32 v[16:17], v[16:17], v[66:67]
	ds_bpermute_b32 v67, v170, v17
	ds_bpermute_b32 v66, v170, v16
	s_waitcnt lgkmcnt(0)
	v_pk_add_f32 v[16:17], v[16:17], v[66:67]
	ds_bpermute_b32 v67, v171, v17
	ds_bpermute_b32 v66, v171, v16
	s_waitcnt lgkmcnt(0)
	v_pk_add_f32 v[16:17], v[16:17], v[66:67]
	s_nop 0
	v_pk_fma_f32 v[140:141], v[16:17], s[16:17], v[140:141] op_sel_hi:[1,0,0]
	s_nop 0
	v_mul_f32_e32 v16, 0x4b800000, v141
	v_cmp_gt_f32_e64 s[0:1], s14, v141
	v_cmp_gt_f32_e32 vcc, s14, v140
	s_nop 0
	v_cndmask_b32_e64 v16, v141, v16, s[0:1]
	v_rsq_f32_e32 v16, v16
	s_nop 0
	v_mul_f32_e32 v17, 0x45800000, v16
	v_cndmask_b32_e64 v16, v16, v17, s[0:1]
	v_pk_mul_f32 v[66:67], v[16:17], v[144:145] op_sel_hi:[0,1]
	v_pk_mul_f32 v[70:71], v[16:17], v[70:71] op_sel_hi:[0,1]
	v_pk_mul_f32 v[66:67], v[130:131], v[66:67]
	v_pk_mul_f32 v[144:145], v[34:35], v[70:71]
	v_pk_fma_f32 v[70:71], v[122:123], v[66:67], v[36:37]
	v_pk_fma_f32 v[66:67], v[144:145], v[38:39], v[30:31]
	v_pk_mul_f32 v[30:31], v[16:17], v[142:143] op_sel_hi:[0,1]
	v_pk_mul_f32 v[36:37], v[16:17], v[64:65] op_sel_hi:[0,1]
	v_pk_mul_f32 v[30:31], v[30:31], v[128:129]
	v_pk_mul_f32 v[36:37], v[36:37], v[42:43]
	v_pk_fma_f32 v[64:65], v[30:31], v[76:77], v[72:73]
	v_pk_fma_f32 v[36:37], v[36:37], v[46:47], v[26:27]
	v_pk_mul_f32 v[26:27], v[16:17], v[138:139] op_sel_hi:[0,1]
	v_pk_mul_f32 v[30:31], v[16:17], v[136:137] op_sel_hi:[0,1]
	v_pk_mul_f32 v[26:27], v[26:27], v[126:127]
	v_pk_mul_f32 v[72:73], v[30:31], v[50:51]
	v_pk_fma_f32 v[30:31], v[26:27], v[8:9], v[84:85]
	v_pk_fma_f32 v[26:27], v[72:73], v[54:55], v[22:23]
	v_pk_mul_f32 v[22:23], v[16:17], v[94:95] op_sel_hi:[0,1]
	v_pk_mul_f32 v[16:17], v[16:17], v[90:91] op_sel_hi:[0,1]
	v_pk_mul_f32 v[16:17], v[16:17], v[58:59]
	v_pk_mul_f32 v[22:23], v[22:23], v[4:5]
	v_pk_fma_f32 v[16:17], v[16:17], v[62:63], v[18:19]
	v_mul_f32_e32 v18, 0x4b800000, v140
	v_cndmask_b32_e32 v18, v140, v18, vcc
	v_rsq_f32_e32 v18, v18
	v_pk_fma_f32 v[22:23], v[22:23], v[132:133], v[134:135]
	v_mul_f32_e32 v19, 0x45800000, v18
	v_cndmask_b32_e32 v18, v18, v19, vcc
	v_pk_mul_f32 v[72:73], v[18:19], v[124:125] op_sel_hi:[0,1]
	v_pk_mul_f32 v[84:85], v[18:19], v[160:161] op_sel_hi:[0,1]
	v_pk_mul_f32 v[72:73], v[130:131], v[72:73]
	v_pk_mul_f32 v[34:35], v[34:35], v[84:85]
	v_pk_fma_f32 v[84:85], v[122:123], v[72:73], v[28:29]
	v_pk_fma_f32 v[72:73], v[38:39], v[34:35], v[14:15]
	v_pk_mul_f32 v[14:15], v[18:19], v[158:159] op_sel_hi:[0,1]
	v_pk_mul_f32 v[28:29], v[18:19], v[156:157] op_sel_hi:[0,1]
	v_pk_mul_f32 v[14:15], v[128:129], v[14:15]
	v_pk_mul_f32 v[28:29], v[42:43], v[28:29]
	v_pk_fma_f32 v[42:43], v[14:15], v[76:77], v[44:45]
	v_pk_fma_f32 v[38:39], v[28:29], v[46:47], v[10:11]
	v_pk_mul_f32 v[10:11], v[18:19], v[152:153] op_sel_hi:[0,1]
	v_pk_mul_f32 v[14:15], v[18:19], v[150:151] op_sel_hi:[0,1]
	v_pk_mul_f32 v[10:11], v[10:11], v[126:127]
	v_pk_mul_f32 v[14:15], v[14:15], v[50:51]
	v_pk_fma_f32 v[34:35], v[10:11], v[8:9], v[68:69]
	v_pk_fma_f32 v[28:29], v[14:15], v[54:55], v[6:7]
	v_pk_mul_f32 v[6:7], v[18:19], v[148:149] op_sel_hi:[0,1]
	v_mov_b32_e32 v8, v0
	v_mov_b32_e32 v9, v2
	v_mov_b32_e32 v2, v1
	v_lshlrev_b64 v[0:1], 12, v[104:105]
	v_pk_mul_f32 v[4:5], v[6:7], v[4:5]
	v_pk_mul_f32 v[6:7], v[18:19], v[146:147] op_sel_hi:[0,1]
	v_lshl_add_u64 v[0:1], s[88:89], 0, v[0:1]
	v_pk_mul_f32 v[6:7], v[6:7], v[58:59]
	v_cndmask_b32_e64 v1, v121, v1, s[2:3]
	v_cndmask_b32_e64 v0, v120, v0, s[2:3]
	v_pk_fma_f32 v[14:15], v[4:5], v[132:133], v[8:9]
	v_pk_fma_f32 v[18:19], v[6:7], v[62:63], v[2:3]
	v_lshl_add_u64 v[4:5], v[0:1], 0, v[192:193]
	v_mov_b32_e32 v0, v92
	v_mov_b32_e32 v1, v88
	v_mov_b32_e32 v2, v93
	v_mov_b32_e32 v3, v89
	global_store_dwordx4 v[4:5], v[0:3], off nt
	v_add_co_u32_e32 v6, vcc, s12, v4
	s_nop 0
	v_mov_b32_e32 v0, v80
	v_mov_b32_e32 v1, v60
	v_mov_b32_e32 v2, v81
	v_mov_b32_e32 v3, v61
	global_store_dwordx4 v[4:5], v[0:3], off offset:1024 nt
	v_addc_co_u32_e32 v7, vcc, 0, v5, vcc
	s_nop 0
	v_mov_b32_e32 v0, v56
	v_mov_b32_e32 v1, v40
	v_mov_b32_e32 v2, v57
	v_mov_b32_e32 v3, v41
	global_store_dwordx4 v[4:5], v[0:3], off offset:2048 nt
	v_add_co_u32_e32 v8, vcc, s13, v4
	s_nop 0
	v_mov_b32_e32 v0, v32
	v_mov_b32_e32 v1, v12
	v_mov_b32_e32 v2, v33
	v_mov_b32_e32 v3, v13
	global_store_dwordx4 v[4:5], v[0:3], off offset:3072 nt
	v_addc_co_u32_e32 v9, vcc, 0, v5, vcc
	s_nop 0
	v_mov_b32_e32 v0, v86
	v_mov_b32_e32 v1, v82
	v_mov_b32_e32 v2, v87
	v_mov_b32_e32 v3, v83
	global_store_dwordx4 v[8:9], v[0:3], off offset:-4096 nt
	v_add_co_u32_e32 v4, vcc, s73, v4
	s_nop 0
	v_mov_b32_e32 v0, v78
	v_mov_b32_e32 v1, v74
	v_mov_b32_e32 v2, v79
	v_mov_b32_e32 v3, v75
	global_store_dwordx4 v[6:7], v[0:3], off offset:1024 nt
	v_addc_co_u32_e32 v5, vcc, 0, v5, vcc
	s_nop 0
	v_mov_b32_e32 v0, v52
	v_mov_b32_e32 v1, v48
	v_mov_b32_e32 v2, v53
	v_mov_b32_e32 v3, v49
	global_store_dwordx4 v[6:7], v[0:3], off offset:2048 nt
	s_andn2_b64 vcc, exec, s[4:5]
	s_nop 0
	v_mov_b32_e32 v0, v24
	v_mov_b32_e32 v1, v20
	v_mov_b32_e32 v2, v25
	v_mov_b32_e32 v3, v21
	global_store_dwordx4 v[6:7], v[0:3], off offset:3072 nt
	s_nop 1
	v_mov_b32_e32 v0, v70
	v_mov_b32_e32 v1, v66
	v_mov_b32_e32 v2, v71
	v_mov_b32_e32 v3, v67
	global_store_dwordx4 v[8:9], v[0:3], off nt
	s_nop 1
	v_mov_b32_e32 v0, v64
	v_mov_b32_e32 v1, v36
	v_mov_b32_e32 v2, v65
	v_mov_b32_e32 v3, v37
	global_store_dwordx4 v[8:9], v[0:3], off offset:1024 nt
	s_nop 1
	v_mov_b32_e32 v0, v30
	v_mov_b32_e32 v1, v26
	v_mov_b32_e32 v2, v31
	v_mov_b32_e32 v3, v27
	global_store_dwordx4 v[8:9], v[0:3], off offset:2048 nt
	s_nop 1
	v_mov_b32_e32 v0, v22
	v_mov_b32_e32 v1, v16
	v_mov_b32_e32 v2, v23
	v_mov_b32_e32 v3, v17
	global_store_dwordx4 v[8:9], v[0:3], off offset:3072 nt
	s_nop 1
	v_mov_b32_e32 v0, v84
	v_mov_b32_e32 v1, v72
	v_mov_b32_e32 v2, v85
	v_mov_b32_e32 v3, v73
	global_store_dwordx4 v[4:5], v[0:3], off nt
	s_nop 1
	v_mov_b32_e32 v0, v42
	v_mov_b32_e32 v1, v38
	v_mov_b32_e32 v2, v43
	v_mov_b32_e32 v3, v39
	global_store_dwordx4 v[4:5], v[0:3], off offset:1024 nt
	s_nop 1
	v_mov_b32_e32 v0, v34
	v_mov_b32_e32 v1, v28
	v_mov_b32_e32 v2, v35
	v_mov_b32_e32 v3, v29
	global_store_dwordx4 v[4:5], v[0:3], off offset:2048 nt
	s_nop 1
	v_mov_b32_e32 v0, v14
	v_mov_b32_e32 v1, v18
	v_mov_b32_e32 v2, v15
	v_mov_b32_e32 v3, v19
	global_store_dwordx4 v[4:5], v[0:3], off offset:3072 nt
	s_cbranch_vccnz .LBB0_27
	v_mov_b32_e32 v4, v88
	v_mov_b32_e32 v5, v60
	v_mov_b32_e32 v2, v92
	v_mov_b32_e32 v3, v80
	v_pk_mul_f32 v[4:5], v[4:5], v[4:5]
	v_mov_b32_e32 v6, v40
	v_pk_fma_f32 v[2:3], v[2:3], v[2:3], v[4:5]
	v_mov_b32_e32 v4, v93
	v_mov_b32_e32 v5, v81
	v_pk_fma_f32 v[2:3], v[4:5], v[4:5], v[2:3]
	v_mov_b32_e32 v4, v89
	v_mov_b32_e32 v5, v61
	v_mov_b32_e32 v7, v12
	v_pk_fma_f32 v[2:3], v[4:5], v[4:5], v[2:3]
	v_mov_b32_e32 v4, v56
	v_mov_b32_e32 v5, v32
	v_pk_mul_f32 v[6:7], v[6:7], v[6:7]
	v_mov_b32_e32 v8, v82
	v_pk_fma_f32 v[4:5], v[4:5], v[4:5], v[6:7]
	v_mov_b32_e32 v6, v57
	v_mov_b32_e32 v7, v33
	v_pk_fma_f32 v[4:5], v[6:7], v[6:7], v[4:5]
	v_mov_b32_e32 v6, v41
	v_mov_b32_e32 v7, v13
	v_mov_b32_e32 v9, v74
	v_pk_fma_f32 v[4:5], v[6:7], v[6:7], v[4:5]
	v_mov_b32_e32 v6, v86
	v_mov_b32_e32 v7, v78
	v_pk_mul_f32 v[8:9], v[8:9], v[8:9]
	v_mov_b32_e32 v10, v48
	v_pk_fma_f32 v[6:7], v[6:7], v[6:7], v[8:9]
	v_mov_b32_e32 v8, v87
	v_mov_b32_e32 v9, v79
	v_pk_fma_f32 v[6:7], v[8:9], v[8:9], v[6:7]
	v_mov_b32_e32 v8, v83
	v_mov_b32_e32 v9, v75
	v_mov_b32_e32 v11, v20
	v_pk_fma_f32 v[6:7], v[8:9], v[8:9], v[6:7]
	v_mov_b32_e32 v8, v52
	v_mov_b32_e32 v9, v24
	v_pk_mul_f32 v[10:11], v[10:11], v[10:11]
	s_mov_b32 s0, 0x358637bd
	v_pk_fma_f32 v[8:9], v[8:9], v[8:9], v[10:11]
	v_mov_b32_e32 v10, v53
	v_mov_b32_e32 v11, v25
	v_pk_fma_f32 v[8:9], v[10:11], v[10:11], v[8:9]
	v_mov_b32_e32 v10, v49
	v_mov_b32_e32 v11, v21
	v_pk_fma_f32 v[8:9], v[10:11], v[10:11], v[8:9]
	v_mov_b32_e32 v10, v6
	v_mov_b32_e32 v11, v2
	v_mov_b32_e32 v2, v7
	v_pk_add_f32 v[2:3], v[10:11], v[2:3]
	v_mov_b32_e32 v6, v8
	v_mov_b32_e32 v7, v4
	v_pk_add_f32 v[2:3], v[2:3], v[6:7]
	v_mov_b32_e32 v4, v9
	v_pk_add_f32 v[2:3], v[2:3], v[4:5]
	ds_bpermute_b32 v5, v107, v3
	ds_bpermute_b32 v4, v107, v2
	s_mov_b32 s14, 0x3a800000
	s_mov_b32 s12, 0x800000
	v_mov_b32_e32 v7, v36
	v_mov_b32_e32 v8, v26
	s_waitcnt lgkmcnt(0)
	v_pk_add_f32 v[2:3], v[2:3], v[4:5]
	ds_bpermute_b32 v5, v109, v3
	ds_bpermute_b32 v4, v109, v2
	v_mov_b32_e32 v9, v16
	v_pk_mul_f32 v[8:9], v[8:9], v[8:9]
	v_mov_b32_e32 v10, v72
	v_mov_b32_e32 v11, v38
	s_waitcnt lgkmcnt(0)
	v_pk_add_f32 v[2:3], v[2:3], v[4:5]
	ds_bpermute_b32 v5, v111, v3
	ds_bpermute_b32 v4, v111, v2
	v_pk_mul_f32 v[10:11], v[10:11], v[10:11]
	v_mov_b32_e32 v50, v28
	v_mov_b32_e32 v51, v18
	v_pk_mul_f32 v[50:51], v[50:51], v[50:51]
	s_waitcnt lgkmcnt(0)
	v_pk_add_f32 v[2:3], v[2:3], v[4:5]
	ds_bpermute_b32 v5, v169, v3
	ds_bpermute_b32 v4, v169, v2
	v_add_u32_e32 v0, v172, v168
	v_mul_hi_i32_i24_e32 v1, 0x6000, v0
	v_mul_i32_i24_e32 v0, 0x6000, v0
	v_lshl_add_u64 v[0:1], s[96:97], 0, v[0:1]
	s_waitcnt lgkmcnt(0)
	v_pk_add_f32 v[2:3], v[2:3], v[4:5]
	ds_bpermute_b32 v5, v170, v3
	ds_bpermute_b32 v4, v170, v2
	v_lshl_add_u64 v[62:63], v[0:1], 0, v[192:193]
	v_lshl_add_u64 v[58:59], v[102:103], 0, v[118:119]
	s_waitcnt lgkmcnt(0)
	v_pk_add_f32 v[2:3], v[2:3], v[4:5]
	ds_bpermute_b32 v5, v171, v3
	ds_bpermute_b32 v4, v171, v2
	s_waitcnt lgkmcnt(0)
	v_pk_add_f32 v[2:3], v[2:3], v[4:5]
	v_mov_b64_e32 v[4:5], s[0:1]
	v_pk_fma_f32 v[2:3], v[2:3], s[14:15], v[4:5] op_sel_hi:[1,0,0]
	s_nop 0
	v_mul_f32_e32 v6, 0x4b800000, v3
	v_cmp_gt_f32_e64 s[0:1], s12, v3
	v_cmp_gt_f32_e32 vcc, s12, v2
	s_nop 0
	v_cndmask_b32_e64 v3, v3, v6, s[0:1]
	v_rsq_f32_e32 v3, v3
	s_nop 0
	v_mul_f32_e32 v6, 0x45800000, v3
	v_cndmask_b32_e64 v46, v3, v6, s[0:1]
	v_mul_f32_e32 v3, 0x4b800000, v2
	v_cndmask_b32_e32 v2, v2, v3, vcc
	v_rsq_f32_e32 v2, v2
	v_mov_b32_e32 v6, v66
	v_pk_mul_f32 v[6:7], v[6:7], v[6:7]
	v_pk_mul_f32 v[88:89], v[88:89], v[46:47] op_sel_hi:[1,0]
	v_mul_f32_e32 v3, 0x45800000, v2
	v_cndmask_b32_e32 v44, v2, v3, vcc
	v_mov_b32_e32 v2, v70
	v_mov_b32_e32 v3, v64
	v_pk_fma_f32 v[2:3], v[2:3], v[2:3], v[6:7]
	v_mov_b32_e32 v6, v71
	v_mov_b32_e32 v7, v65
	v_pk_fma_f32 v[2:3], v[6:7], v[6:7], v[2:3]
	v_mov_b32_e32 v6, v67
	v_mov_b32_e32 v7, v37
	v_pk_fma_f32 v[2:3], v[6:7], v[6:7], v[2:3]
	v_mov_b32_e32 v6, v30
	v_mov_b32_e32 v7, v22
	v_pk_fma_f32 v[6:7], v[6:7], v[6:7], v[8:9]
	v_mov_b32_e32 v8, v31
	v_mov_b32_e32 v9, v23
	v_pk_fma_f32 v[6:7], v[8:9], v[8:9], v[6:7]
	v_mov_b32_e32 v8, v27
	v_mov_b32_e32 v9, v17
	v_pk_fma_f32 v[6:7], v[8:9], v[8:9], v[6:7]
	v_mov_b32_e32 v8, v84
	v_mov_b32_e32 v9, v42
	v_pk_fma_f32 v[8:9], v[8:9], v[8:9], v[10:11]
	v_mov_b32_e32 v10, v85
	v_mov_b32_e32 v11, v43
	v_pk_fma_f32 v[8:9], v[10:11], v[10:11], v[8:9]
	v_mov_b32_e32 v10, v73
	v_mov_b32_e32 v11, v39
	v_pk_fma_f32 v[8:9], v[10:11], v[10:11], v[8:9]
	v_mov_b32_e32 v10, v34
	v_mov_b32_e32 v11, v14
	v_pk_fma_f32 v[10:11], v[10:11], v[10:11], v[50:51]
	v_mov_b32_e32 v50, v35
	v_mov_b32_e32 v51, v15
	v_pk_fma_f32 v[10:11], v[50:51], v[50:51], v[10:11]
	v_mov_b32_e32 v50, v29
	v_mov_b32_e32 v51, v19
	v_pk_fma_f32 v[10:11], v[50:51], v[50:51], v[10:11]
	v_mov_b32_e32 v50, v8
	v_mov_b32_e32 v51, v2
	v_mov_b32_e32 v2, v9
	v_pk_add_f32 v[2:3], v[50:51], v[2:3]
	v_mov_b32_e32 v8, v10
	v_mov_b32_e32 v9, v6
	v_pk_add_f32 v[2:3], v[2:3], v[8:9]
	v_mov_b32_e32 v6, v11
	v_pk_add_f32 v[2:3], v[2:3], v[6:7]
	ds_bpermute_b32 v7, v107, v3
	ds_bpermute_b32 v6, v107, v2
	v_mov_b32_e32 v107, v193
	s_waitcnt lgkmcnt(0)
	v_pk_add_f32 v[2:3], v[2:3], v[6:7]
	ds_bpermute_b32 v7, v109, v3
	ds_bpermute_b32 v6, v109, v2
	v_mov_b32_e32 v109, v193
	s_waitcnt lgkmcnt(0)
	v_pk_add_f32 v[2:3], v[2:3], v[6:7]
	ds_bpermute_b32 v7, v111, v3
	ds_bpermute_b32 v6, v111, v2
	v_mov_b32_e32 v111, v193
	s_waitcnt lgkmcnt(0)
	v_pk_add_f32 v[2:3], v[2:3], v[6:7]
	ds_bpermute_b32 v7, v169, v3
	ds_bpermute_b32 v6, v169, v2
	s_waitcnt lgkmcnt(0)
	v_pk_add_f32 v[2:3], v[2:3], v[6:7]
	ds_bpermute_b32 v7, v170, v3
	ds_bpermute_b32 v6, v170, v2
	s_waitcnt lgkmcnt(0)
	v_pk_add_f32 v[2:3], v[2:3], v[6:7]
	ds_bpermute_b32 v7, v171, v3
	ds_bpermute_b32 v6, v171, v2
	s_waitcnt lgkmcnt(0)
	v_pk_add_f32 v[2:3], v[2:3], v[6:7]
	s_nop 0
	v_pk_fma_f32 v[2:3], v[2:3], s[14:15], v[4:5] op_sel_hi:[1,0,0]
	s_nop 0
	v_mul_f32_e32 v4, 0x4b800000, v3
	v_cmp_gt_f32_e64 s[0:1], s12, v3
	v_cmp_gt_f32_e32 vcc, s12, v2
	s_nop 0
	v_cndmask_b32_e64 v3, v3, v4, s[0:1]
	v_rsq_f32_e32 v3, v3
	s_nop 0
	v_mul_f32_e32 v4, 0x45800000, v3
	v_cndmask_b32_e64 v54, v3, v4, s[0:1]
	v_mul_f32_e32 v3, 0x4b800000, v2
	v_cndmask_b32_e32 v2, v2, v3, vcc
	v_rsq_f32_e32 v2, v2
	s_mov_b64 s[0:1], 0x1000
	v_lshl_add_u64 v[68:69], v[0:1], 0, s[0:1]
	v_lshl_add_u64 v[4:5], v[68:69], 0, v[192:193]
	v_mul_f32_e32 v3, 0x45800000, v2
	v_cndmask_b32_e32 v50, v2, v3, vcc
	global_load_dwordx4 v[0:3], v[100:101], off
	global_load_dwordx4 v[8:11], v[4:5], off
	s_nop 0
	global_load_dwordx4 v[4:7], v[62:63], off
	v_pk_mul_f32 v[66:67], v[66:67], v[54:55] op_sel_hi:[1,0]
	v_pk_mul_f32 v[36:37], v[36:37], v[54:55] op_sel_hi:[1,0]
	v_pk_mul_f32 v[26:27], v[26:27], v[54:55] op_sel_hi:[1,0]
	s_waitcnt vmcnt(2)
	v_mov_b32_e32 v90, v0
	s_waitcnt vmcnt(1)
	v_mov_b32_e32 v76, v8
	v_mov_b32_e32 v77, v10
	v_mov_b32_e32 v10, v9
	v_pk_mul_f32 v[8:9], v[92:93], v[46:47] op_sel_hi:[1,0]
	v_mov_b32_e32 v91, v2
	v_pk_add_f32 v[76:77], v[76:77], 1.0 op_sel_hi:[1,0]
	v_pk_mul_f32 v[8:9], v[8:9], v[90:91]
	s_waitcnt vmcnt(0)
	v_mov_b32_e32 v92, v4
	v_mov_b32_e32 v93, v6
	v_mov_b32_e32 v2, v1
	v_pk_add_f32 v[10:11], v[10:11], 1.0 op_sel_hi:[1,0]
	v_pk_fma_f32 v[8:9], v[8:9], v[76:77], v[92:93]
	v_pk_mul_f32 v[0:1], v[88:89], v[2:3]
	v_mov_b32_e32 v6, v5
	v_pk_fma_f32 v[0:1], v[0:1], v[10:11], v[6:7]
	v_cvt_pk_bf16_f32 v0, v8, v0
	v_cvt_pk_bf16_f32 v1, v9, v1
	v_pk_mul_f32 v[4:5], v[86:87], v[44:45] op_sel_hi:[1,0]
	v_pk_mul_f32 v[8:9], v[82:83], v[44:45] op_sel_hi:[1,0]
	v_pk_mul_f32 v[4:5], v[4:5], v[90:91]
	v_pk_mul_f32 v[8:9], v[8:9], v[2:3]
	v_pk_fma_f32 v[4:5], v[4:5], v[76:77], v[92:93]
	v_pk_fma_f32 v[8:9], v[8:9], v[10:11], v[6:7]
	v_cvt_pk_bf16_f32 v5, v5, v9
	v_cvt_pk_bf16_f32 v4, v4, v8
	v_pk_mul_f32 v[8:9], v[70:71], v[54:55] op_sel_hi:[1,0]
	v_pk_mul_f32 v[66:67], v[2:3], v[66:67]
	v_pk_mul_f32 v[8:9], v[90:91], v[8:9]
	v_pk_fma_f32 v[66:67], v[66:67], v[10:11], v[6:7]
	v_pk_fma_f32 v[8:9], v[8:9], v[76:77], v[92:93]
	v_pk_mul_f32 v[70:71], v[72:73], v[50:51] op_sel_hi:[1,0]
	v_cvt_pk_bf16_f32 v9, v9, v67
	v_and_b32_sdwa v47, v8, v218 dst_sel:DWORD dst_unused:UNUSED_PAD src0_sel:WORD_1 src1_sel:DWORD
	v_add3_u32 v8, v8, v47, s80
	v_and_b32_sdwa v47, v66, v218 dst_sel:DWORD dst_unused:UNUSED_PAD src0_sel:WORD_1 src1_sel:DWORD
	v_add3_u32 v47, v66, v47, s80
	v_pk_mul_f32 v[66:67], v[84:85], v[50:51] op_sel_hi:[1,0]
	v_pk_mul_f32 v[2:3], v[2:3], v[70:71]
	v_pk_mul_f32 v[66:67], v[90:91], v[66:67]
	v_pk_fma_f32 v[2:3], v[10:11], v[2:3], v[6:7]
	v_pk_fma_f32 v[66:67], v[76:77], v[66:67], v[92:93]
	global_store_dwordx2 v[58:59], v[0:1], off nt
	v_lshl_add_u64 v[0:1], v[102:103], 0, v[116:117]
	v_and_b32_e32 v47, 0xffff0000, v47
	v_cvt_pk_bf16_f32 v3, v67, v3
	v_cvt_pk_bf16_f32 v2, v66, v2
	global_store_dwordx2 v[0:1], v[4:5], off nt
	v_lshl_add_u64 v[4:5], v[102:103], 0, v[114:115]
	v_or_b32_sdwa v8, v47, v8 dst_sel:DWORD dst_unused:UNUSED_PAD src0_sel:DWORD src1_sel:WORD_1
	global_store_dwordx2 v[4:5], v[8:9], off nt
	v_lshl_add_u64 v[8:9], v[102:103], 0, v[112:113]
	global_store_dwordx2 v[8:9], v[2:3], off nt
	v_lshl_add_u64 v[2:3], v[68:69], 0, v[106:107]
	global_load_dwordx4 v[70:73], v[100:101], off offset:1024
	global_load_dwordx4 v[82:85], v[2:3], off
	global_load_dwordx4 v[86:89], v[62:63], off offset:1024
	v_pk_mul_f32 v[10:11], v[80:81], v[46:47] op_sel_hi:[1,0]
	v_pk_mul_f32 v[60:61], v[60:61], v[46:47] op_sel_hi:[1,0]
	s_waitcnt vmcnt(2)
	v_mov_b32_e32 v66, v70
	s_waitcnt vmcnt(1)
	v_mov_b32_e32 v2, v82
	v_mov_b32_e32 v3, v84
	v_mov_b32_e32 v67, v72
	v_pk_add_f32 v[2:3], v[2:3], 1.0 op_sel_hi:[1,0]
	v_mov_b32_e32 v84, v83
	v_pk_mul_f32 v[10:11], v[10:11], v[66:67]
	s_waitcnt vmcnt(0)
	v_mov_b32_e32 v76, v86
	v_mov_b32_e32 v77, v88
	v_mov_b32_e32 v72, v71
	v_pk_add_f32 v[6:7], v[84:85], 1.0 op_sel_hi:[1,0]
	v_pk_fma_f32 v[10:11], v[10:11], v[2:3], v[76:77]
	v_pk_mul_f32 v[60:61], v[60:61], v[72:73]
	v_mov_b32_e32 v88, v87
	v_pk_fma_f32 v[60:61], v[60:61], v[6:7], v[88:89]
	v_and_b32_sdwa v45, v11, v218 dst_sel:DWORD dst_unused:UNUSED_PAD src0_sel:WORD_1 src1_sel:DWORD
	v_cvt_pk_bf16_f32 v10, v10, v60
	v_add3_u32 v11, v11, v45, s80
	v_and_b32_sdwa v45, v61, v218 dst_sel:DWORD dst_unused:UNUSED_PAD src0_sel:WORD_1 src1_sel:DWORD
	v_add3_u32 v45, v61, v45, s80
	v_and_b32_e32 v45, 0xffff0000, v45
	v_or_b32_sdwa v11, v45, v11 dst_sel:DWORD dst_unused:UNUSED_PAD src0_sel:DWORD src1_sel:WORD_1
	global_store_dwordx2 v[58:59], v[10:11], off offset:512 nt
	v_pk_mul_f32 v[10:11], v[78:79], v[44:45] op_sel_hi:[1,0]
	v_pk_mul_f32 v[60:61], v[74:75], v[44:45] op_sel_hi:[1,0]
	v_pk_mul_f32 v[10:11], v[10:11], v[66:67]
	v_pk_mul_f32 v[60:61], v[60:61], v[72:73]
	v_pk_fma_f32 v[10:11], v[10:11], v[2:3], v[76:77]
	v_pk_fma_f32 v[60:61], v[60:61], v[6:7], v[88:89]
	v_cvt_pk_bf16_f32 v11, v11, v61
	v_cvt_pk_bf16_f32 v10, v10, v60
	global_store_dwordx2 v[0:1], v[10:11], off offset:512 nt
	v_pk_mul_f32 v[10:11], v[64:65], v[54:55] op_sel_hi:[1,0]
	v_pk_mul_f32 v[36:37], v[36:37], v[72:73]
	v_pk_mul_f32 v[10:11], v[10:11], v[66:67]
	v_pk_fma_f32 v[36:37], v[36:37], v[6:7], v[88:89]
	v_pk_fma_f32 v[10:11], v[10:11], v[2:3], v[76:77]
	s_nop 0
	v_and_b32_sdwa v45, v11, v218 dst_sel:DWORD dst_unused:UNUSED_PAD src0_sel:WORD_1 src1_sel:DWORD
	v_and_b32_sdwa v47, v10, v218 dst_sel:DWORD dst_unused:UNUSED_PAD src0_sel:WORD_1 src1_sel:DWORD
	v_add3_u32 v10, v10, v47, s80
	v_add3_u32 v11, v11, v45, s80
	v_and_b32_sdwa v45, v37, v218 dst_sel:DWORD dst_unused:UNUSED_PAD src0_sel:WORD_1 src1_sel:DWORD
	v_and_b32_sdwa v47, v36, v218 dst_sel:DWORD dst_unused:UNUSED_PAD src0_sel:WORD_1 src1_sel:DWORD
	v_add3_u32 v37, v37, v45, s80
	v_add3_u32 v36, v36, v47, s80
	v_and_b32_e32 v37, 0xffff0000, v37
	v_and_b32_e32 v36, 0xffff0000, v36
	v_or_b32_sdwa v11, v37, v11 dst_sel:DWORD dst_unused:UNUSED_PAD src0_sel:DWORD src1_sel:WORD_1
	v_or_b32_sdwa v10, v36, v10 dst_sel:DWORD dst_unused:UNUSED_PAD src0_sel:DWORD src1_sel:WORD_1
	global_store_dwordx2 v[4:5], v[10:11], off offset:512 nt
	v_pk_mul_f32 v[10:11], v[42:43], v[50:51] op_sel_hi:[1,0]
	v_pk_mul_f32 v[40:41], v[40:41], v[46:47] op_sel_hi:[1,0]
	v_pk_mul_f32 v[10:11], v[10:11], v[66:67]
	v_pk_mul_f32 v[12:13], v[12:13], v[46:47] op_sel_hi:[1,0]
	v_pk_fma_f32 v[2:3], v[10:11], v[2:3], v[76:77]
	v_pk_mul_f32 v[10:11], v[38:39], v[50:51] op_sel_hi:[1,0]
	s_nop 0
	v_pk_mul_f32 v[10:11], v[10:11], v[72:73]
	s_nop 0
	v_pk_fma_f32 v[6:7], v[10:11], v[6:7], v[88:89]
	v_cvt_pk_bf16_f32 v3, v3, v7
	v_cvt_pk_bf16_f32 v2, v2, v6
	global_store_dwordx2 v[8:9], v[2:3], off offset:512 nt
	v_lshl_add_u64 v[2:3], v[68:69], 0, v[108:109]
	global_load_dwordx4 v[36:39], v[100:101], off offset:2048
	global_load_dwordx4 v[64:67], v[2:3], off
	global_load_dwordx4 v[70:73], v[62:63], off offset:2048
	v_pk_mul_f32 v[10:11], v[56:57], v[46:47] op_sel_hi:[1,0]
	s_waitcnt vmcnt(2)
	v_mov_b32_e32 v42, v36
	s_waitcnt vmcnt(1)
	v_mov_b32_e32 v2, v64
	v_mov_b32_e32 v3, v66
	v_mov_b32_e32 v43, v38
	v_pk_add_f32 v[2:3], v[2:3], 1.0 op_sel_hi:[1,0]
	v_mov_b32_e32 v66, v65
	v_pk_mul_f32 v[10:11], v[10:11], v[42:43]
	s_waitcnt vmcnt(0)
	v_mov_b32_e32 v56, v70
	v_mov_b32_e32 v57, v72
	v_mov_b32_e32 v38, v37
	v_pk_add_f32 v[6:7], v[66:67], 1.0 op_sel_hi:[1,0]
	v_pk_fma_f32 v[10:11], v[10:11], v[2:3], v[56:57]
	v_pk_mul_f32 v[36:37], v[40:41], v[38:39]
	v_mov_b32_e32 v72, v71
	v_pk_fma_f32 v[36:37], v[36:37], v[6:7], v[72:73]
	v_cvt_pk_bf16_f32 v11, v11, v37
	v_cvt_pk_bf16_f32 v10, v10, v36
	global_store_dwordx2 v[58:59], v[10:11], off offset:1024 nt
	v_pk_mul_f32 v[10:11], v[52:53], v[44:45] op_sel_hi:[1,0]
	v_pk_mul_f32 v[36:37], v[48:49], v[44:45] op_sel_hi:[1,0]
	v_pk_mul_f32 v[10:11], v[10:11], v[42:43]
	v_pk_mul_f32 v[36:37], v[36:37], v[38:39]
	v_pk_fma_f32 v[10:11], v[10:11], v[2:3], v[56:57]
	v_pk_fma_f32 v[36:37], v[36:37], v[6:7], v[72:73]
	v_cvt_pk_bf16_f32 v11, v11, v37
	v_cvt_pk_bf16_f32 v10, v10, v36
	global_store_dwordx2 v[0:1], v[10:11], off offset:1024 nt
	v_pk_mul_f32 v[10:11], v[30:31], v[54:55] op_sel_hi:[1,0]
	v_pk_mul_f32 v[26:27], v[26:27], v[38:39]
	v_pk_mul_f32 v[10:11], v[10:11], v[42:43]
	v_pk_fma_f32 v[26:27], v[26:27], v[6:7], v[72:73]
	v_pk_fma_f32 v[10:11], v[10:11], v[2:3], v[56:57]
	s_nop 0
	v_cvt_pk_bf16_f32 v11, v11, v27
	v_cvt_pk_bf16_f32 v10, v10, v26
	global_store_dwordx2 v[4:5], v[10:11], off offset:1024 nt
	v_pk_mul_f32 v[10:11], v[34:35], v[50:51] op_sel_hi:[1,0]
	s_nop 0
	v_pk_mul_f32 v[10:11], v[10:11], v[42:43]
	s_nop 0
	v_pk_fma_f32 v[2:3], v[10:11], v[2:3], v[56:57]
	v_pk_mul_f32 v[10:11], v[28:29], v[50:51] op_sel_hi:[1,0]
	s_nop 0
	v_pk_mul_f32 v[10:11], v[10:11], v[38:39]
	s_nop 0
	v_pk_fma_f32 v[6:7], v[10:11], v[6:7], v[72:73]
	v_cvt_pk_bf16_f32 v3, v3, v7
	v_cvt_pk_bf16_f32 v2, v2, v6
	global_store_dwordx2 v[8:9], v[2:3], off offset:1024 nt
	v_lshl_add_u64 v[2:3], v[68:69], 0, v[110:111]
	global_load_dwordx4 v[26:29], v[100:101], off offset:3072
	global_load_dwordx4 v[34:37], v[2:3], off
	global_load_dwordx4 v[38:41], v[62:63], off offset:3072
	v_pk_mul_f32 v[10:11], v[32:33], v[46:47] op_sel_hi:[1,0]
	s_waitcnt vmcnt(2)
	v_mov_b32_e32 v30, v26
	s_waitcnt vmcnt(1)
	v_mov_b32_e32 v2, v34
	v_mov_b32_e32 v3, v36
	v_mov_b32_e32 v31, v28
	v_pk_add_f32 v[2:3], v[2:3], 1.0 op_sel_hi:[1,0]
	v_mov_b32_e32 v36, v35
	v_pk_mul_f32 v[10:11], v[10:11], v[30:31]
	s_waitcnt vmcnt(0)
	v_mov_b32_e32 v32, v38
	v_mov_b32_e32 v33, v40
	v_mov_b32_e32 v28, v27
	v_pk_add_f32 v[6:7], v[36:37], 1.0 op_sel_hi:[1,0]
	v_pk_fma_f32 v[10:11], v[10:11], v[2:3], v[32:33]
	v_pk_mul_f32 v[12:13], v[12:13], v[28:29]
	v_mov_b32_e32 v40, v39
	v_pk_fma_f32 v[12:13], v[12:13], v[6:7], v[40:41]
	v_cvt_pk_bf16_f32 v11, v11, v13
	v_cvt_pk_bf16_f32 v10, v10, v12
	global_store_dwordx2 v[58:59], v[10:11], off offset:1536 nt
	v_pk_mul_f32 v[10:11], v[24:25], v[44:45] op_sel_hi:[1,0]
	v_pk_mul_f32 v[12:13], v[20:21], v[44:45] op_sel_hi:[1,0]
	v_pk_mul_f32 v[10:11], v[10:11], v[30:31]
	v_pk_mul_f32 v[12:13], v[12:13], v[28:29]
	v_pk_fma_f32 v[10:11], v[10:11], v[2:3], v[32:33]
	v_pk_fma_f32 v[12:13], v[12:13], v[6:7], v[40:41]
	v_cvt_pk_bf16_f32 v11, v11, v13
	v_cvt_pk_bf16_f32 v10, v10, v12
	global_store_dwordx2 v[0:1], v[10:11], off offset:1536 nt
	v_pk_mul_f32 v[0:1], v[22:23], v[54:55] op_sel_hi:[1,0]
	v_pk_mul_f32 v[10:11], v[16:17], v[54:55] op_sel_hi:[1,0]
	v_pk_mul_f32 v[0:1], v[0:1], v[30:31]
	v_pk_mul_f32 v[10:11], v[10:11], v[28:29]
	v_pk_fma_f32 v[0:1], v[0:1], v[2:3], v[32:33]
	v_pk_fma_f32 v[10:11], v[10:11], v[6:7], v[40:41]
	v_cvt_pk_bf16_f32 v1, v1, v11
	v_cvt_pk_bf16_f32 v0, v0, v10
	global_store_dwordx2 v[4:5], v[0:1], off offset:1536 nt
	v_pk_mul_f32 v[0:1], v[14:15], v[50:51] op_sel_hi:[1,0]
	s_nop 0
	v_pk_mul_f32 v[0:1], v[0:1], v[30:31]
	s_nop 0
	v_pk_fma_f32 v[0:1], v[0:1], v[2:3], v[32:33]
	v_pk_mul_f32 v[2:3], v[18:19], v[50:51] op_sel_hi:[1,0]
	v_and_b32_sdwa v4, v1, v218 dst_sel:DWORD dst_unused:UNUSED_PAD src0_sel:WORD_1 src1_sel:DWORD
	v_pk_mul_f32 v[2:3], v[2:3], v[28:29]
	v_and_b32_sdwa v5, v0, v218 dst_sel:DWORD dst_unused:UNUSED_PAD src0_sel:WORD_1 src1_sel:DWORD
	v_pk_fma_f32 v[2:3], v[2:3], v[6:7], v[40:41]
	v_add3_u32 v0, v0, v5, s80
	v_add3_u32 v1, v1, v4, s80
	v_and_b32_sdwa v4, v3, v218 dst_sel:DWORD dst_unused:UNUSED_PAD src0_sel:WORD_1 src1_sel:DWORD
	v_and_b32_sdwa v5, v2, v218 dst_sel:DWORD dst_unused:UNUSED_PAD src0_sel:WORD_1 src1_sel:DWORD
	v_add3_u32 v3, v3, v4, s80
	v_add3_u32 v2, v2, v5, s80
	v_and_b32_e32 v3, 0xffff0000, v3
	v_and_b32_e32 v2, 0xffff0000, v2
	v_or_b32_sdwa v1, v3, v1 dst_sel:DWORD dst_unused:UNUSED_PAD src0_sel:DWORD src1_sel:WORD_1
	v_or_b32_sdwa v0, v2, v0 dst_sel:DWORD dst_unused:UNUSED_PAD src0_sel:DWORD src1_sel:WORD_1
	global_store_dwordx2 v[8:9], v[0:1], off offset:1536 nt
	s_branch .LBB0_27

.LBB0_34:
	v_cmp_gt_i32_e32 vcc, 0, v40
	v_min_i32_e32 v0, 0x4000, v26
	v_mov_b32_e32 v2, s23
	v_mov_b32_e32 v3, s89
	v_ashrrev_i32_e32 v31, 13, v0
	v_cndmask_b32_e32 v1, 0, v27, vcc
	v_cndmask_b32_e32 v0, v40, v26, vcc
	v_cndmask_b32_e32 v3, v2, v3, vcc
	v_mov_b32_e32 v2, s22
	v_mov_b32_e32 v4, s88
	v_cndmask_b32_e32 v2, v2, v4, vcc
	v_lshlrev_b64 v[0:1], 12, v[0:1]
	v_lshl_add_u64 v[0:1], v[2:3], 0, v[0:1]
	v_lshl_add_u64 v[36:37], v[0:1], 0, v[192:193]
	global_load_dwordx4 v[12:15], v[36:37], off nt
	global_load_dwordx4 v[8:11], v[36:37], off offset:1024 nt
	global_load_dwordx4 v[4:7], v[36:37], off offset:2048 nt
	global_load_dwordx4 v[0:3], v[36:37], off offset:3072 nt
	global_load_dwordx2 v[56:57], v[28:29], off nt
	global_load_dwordx2 v[64:65], v[28:29], off offset:512 nt
	global_load_dwordx2 v[72:73], v[28:29], off offset:1024 nt
	global_load_dwordx2 v[80:81], v[28:29], off offset:1536 nt
	v_mul_hi_i32_i24_e32 v39, 0x6000, v31
	v_mul_i32_i24_e32 v38, 0x6000, v31
	v_lshl_add_u64 v[38:39], s[90:91], 0, v[38:39]
	s_waitcnt vmcnt(11)
	v_lshl_add_u64 v[52:53], v[38:39], 0, v[192:193]
	v_lshl_add_u64 v[76:77], v[52:53], 0, s[34:35]
	v_add_co_u32_e32 v52, vcc, s24, v52
	global_load_dwordx4 v[48:51], v[16:17], off
	s_nop 0
	v_addc_co_u32_e32 v53, vcc, 0, v53, vcc
	global_load_dwordx4 v[52:55], v[52:53], off
	s_mov_b32 s4, 0xf823c000
	v_add_u32_e32 v40, s20, v40
	v_lshl_add_u64 v[26:27], v[26:27], 0, s[20:21]
	s_waitcnt vmcnt(5)
	v_and_b32_e32 v39, 0xffff0000, v56
	s_waitcnt vmcnt(4)
	v_and_b32_e32 v85, 0xffff0000, v64
	v_lshlrev_b32_e32 v38, 16, v56
	v_lshlrev_b32_e32 v84, 16, v64
	v_mov_b32_e32 v66, v39
	v_mov_b32_e32 v67, v85
	v_lshlrev_b32_e32 v82, 16, v57
	v_and_b32_e32 v87, 0xffff0000, v65
	v_lshlrev_b32_e32 v86, 16, v65
	v_mov_b32_e32 v64, v38
	v_mov_b32_e32 v65, v84
	v_pk_mul_f32 v[66:67], v[66:67], v[66:67]
	v_and_b32_e32 v83, 0xffff0000, v57
	global_load_dwordx4 v[56:59], v[16:17], off offset:1024
	global_load_dwordx4 v[60:63], v[76:77], off offset:1024
	v_pk_fma_f32 v[64:65], v[64:65], v[64:65], v[66:67]
	v_mov_b32_e32 v66, v82
	v_mov_b32_e32 v67, v86
	v_mov_b32_e32 v68, v83
	v_mov_b32_e32 v69, v87
	v_pk_fma_f32 v[64:65], v[66:67], v[66:67], v[64:65]
	s_waitcnt vmcnt(5)
	v_and_b32_e32 v91, 0xffff0000, v72
	v_pk_fma_f32 v[88:89], v[68:69], v[68:69], v[64:65]
	global_load_dwordx4 v[64:67], v[16:17], off offset:2048
	global_load_dwordx4 v[68:71], v[76:77], off offset:2048
	v_lshlrev_b32_e32 v90, 16, v72
	v_and_b32_e32 v93, 0xffff0000, v73
	v_lshlrev_b32_e32 v92, 16, v73
	global_load_dwordx4 v[72:75], v[16:17], off offset:3072
	s_nop 0
	global_load_dwordx4 v[76:79], v[76:77], off offset:3072
	s_waitcnt vmcnt(8)
	v_and_b32_e32 v95, 0xffff0000, v80
	v_lshlrev_b32_e32 v94, 16, v80
	v_mov_b32_e32 v98, v91
	v_mov_b32_e32 v99, v95
	v_and_b32_e32 v97, 0xffff0000, v81
	v_lshlrev_b32_e32 v96, 16, v81
	v_mov_b32_e32 v80, v90
	v_mov_b32_e32 v81, v94
	v_pk_mul_f32 v[98:99], v[98:99], v[98:99]
	v_mov_b32_e32 v100, v93
	v_pk_fma_f32 v[80:81], v[80:81], v[80:81], v[98:99]
	v_mov_b32_e32 v98, v92
	v_mov_b32_e32 v99, v96
	v_mov_b32_e32 v101, v97
	v_pk_fma_f32 v[80:81], v[98:99], v[98:99], v[80:81]
	v_add_f32_e32 v33, v88, v89
	v_pk_fma_f32 v[80:81], v[100:101], v[100:101], v[80:81]
	s_nop 0
	v_add_f32_e32 v33, v33, v80
	v_add_f32_e32 v33, v33, v81
	ds_bpermute_b32 v35, v41, v33
	s_waitcnt lgkmcnt(0)
	v_add_f32_e32 v33, v33, v35
	ds_bpermute_b32 v35, v42, v33
	s_waitcnt lgkmcnt(0)
	v_add_f32_e32 v33, v33, v35
	ds_bpermute_b32 v35, v43, v33
	s_waitcnt lgkmcnt(0)
	v_add_f32_e32 v33, v33, v35
	ds_bpermute_b32 v35, v44, v33
	s_waitcnt lgkmcnt(0)
	v_add_f32_e32 v33, v33, v35
	ds_bpermute_b32 v35, v45, v33
	s_waitcnt lgkmcnt(0)
	v_add_f32_e32 v33, v33, v35
	ds_bpermute_b32 v35, v46, v33
	s_waitcnt lgkmcnt(0)
	v_add_f32_e32 v33, v33, v35
	v_fmamk_f32 v33, v33, 0x3a800000, v219
	v_cmp_gt_f32_e32 vcc, s25, v33
	v_mul_f32_e32 v35, 0x4b800000, v33
	s_nop 0
	v_cndmask_b32_e32 v33, v33, v35, vcc
	v_rsq_f32_e32 v33, v33
	s_nop 0
	v_mul_f32_e32 v35, 0x45800000, v33
	v_cndmask_b32_e32 v80, v33, v35, vcc
	v_pk_mul_f32 v[38:39], v[80:81], v[38:39] op_sel_hi:[0,1]
	s_waitcnt vmcnt(7)
	v_pk_mul_f32 v[38:39], v[48:49], v[38:39]
	v_pk_mul_f32 v[48:49], v[80:81], v[82:83] op_sel_hi:[0,1]
	v_pk_mul_f32 v[50:51], v[50:51], v[48:49]
	s_waitcnt vmcnt(6)
	v_pk_fma_f32 v[48:49], v[52:53], v[38:39], v[12:13]
	v_pk_mul_f32 v[12:13], v[80:81], v[84:85] op_sel_hi:[0,1]
	v_pk_fma_f32 v[50:51], v[54:55], v[50:51], v[14:15]
	s_waitcnt vmcnt(5)
	v_pk_mul_f32 v[12:13], v[56:57], v[12:13]
	v_pk_mul_f32 v[14:15], v[80:81], v[86:87] op_sel_hi:[0,1]
	v_pk_mul_f32 v[14:15], v[58:59], v[14:15]
	s_waitcnt vmcnt(4)
	v_pk_fma_f32 v[8:9], v[60:61], v[12:13], v[8:9]
	v_pk_mul_f32 v[12:13], v[80:81], v[90:91] op_sel_hi:[0,1]
	v_pk_fma_f32 v[10:11], v[62:63], v[14:15], v[10:11]
	s_waitcnt vmcnt(3)
	v_pk_mul_f32 v[12:13], v[12:13], v[64:65]
	v_pk_mul_f32 v[14:15], v[80:81], v[92:93] op_sel_hi:[0,1]
	v_pk_mul_f32 v[14:15], v[14:15], v[66:67]
	s_waitcnt vmcnt(2)
	v_pk_fma_f32 v[4:5], v[12:13], v[68:69], v[4:5]
	v_pk_mul_f32 v[12:13], v[80:81], v[94:95] op_sel_hi:[0,1]
	v_pk_fma_f32 v[6:7], v[14:15], v[70:71], v[6:7]
	s_waitcnt vmcnt(1)
	v_pk_mul_f32 v[12:13], v[12:13], v[72:73]
	v_pk_mul_f32 v[14:15], v[80:81], v[96:97] op_sel_hi:[0,1]
	v_pk_mul_f32 v[14:15], v[14:15], v[74:75]
	s_waitcnt vmcnt(0)
	v_pk_fma_f32 v[0:1], v[12:13], v[76:77], v[0:1]
	v_add_u32_e32 v12, 3, v31
	v_pk_fma_f32 v[2:3], v[14:15], v[78:79], v[2:3]
	global_store_dwordx4 v[36:37], v[48:51], off nt
	global_store_dwordx4 v[36:37], v[8:11], off offset:1024 nt
	global_store_dwordx4 v[36:37], v[4:7], off offset:2048 nt
	global_store_dwordx4 v[36:37], v[0:3], off offset:3072 nt
	v_mul_hi_i32_i24_e32 v13, 0x6000, v12
	v_mul_i32_i24_e32 v12, 0x6000, v12
	v_mov_b32_e32 v36, v49
	v_mov_b32_e32 v37, v9
	v_lshl_add_u64 v[14:15], s[96:97], 0, v[12:13]
	v_mov_b32_e32 v12, v48
	v_mov_b32_e32 v13, v8
	v_pk_mul_f32 v[36:37], v[36:37], v[36:37]
	v_mov_b32_e32 v38, v5
	v_pk_fma_f32 v[12:13], v[12:13], v[12:13], v[36:37]
	v_mov_b32_e32 v36, v50
	v_mov_b32_e32 v37, v10
	v_pk_fma_f32 v[12:13], v[36:37], v[36:37], v[12:13]
	v_mov_b32_e32 v36, v51
	v_mov_b32_e32 v37, v11
	v_mov_b32_e32 v39, v1
	v_pk_fma_f32 v[12:13], v[36:37], v[36:37], v[12:13]
	v_mov_b32_e32 v36, v4
	v_mov_b32_e32 v37, v0
	v_pk_mul_f32 v[38:39], v[38:39], v[38:39]
	v_add_f32_e32 v12, v12, v13
	v_pk_fma_f32 v[36:37], v[36:37], v[36:37], v[38:39]
	v_mov_b32_e32 v38, v6
	v_mov_b32_e32 v39, v2
	v_pk_fma_f32 v[36:37], v[38:39], v[38:39], v[36:37]
	v_mov_b32_e32 v38, v7
	v_mov_b32_e32 v39, v3
	v_pk_fma_f32 v[36:37], v[38:39], v[38:39], v[36:37]
	s_nop 0
	v_add_f32_e32 v12, v12, v36
	v_add_f32_e32 v12, v12, v37
	v_lshl_add_u64 v[36:37], v[14:15], 0, s[28:29]
	v_lshl_add_u64 v[38:39], v[36:37], 0, v[192:193]
	v_lshl_add_u64 v[14:15], v[14:15], 0, v[192:193]
	global_load_dwordx4 v[52:55], v[18:19], off
	global_load_dwordx4 v[56:59], v[38:39], off
	global_load_dwordx4 v[60:63], v[14:15], off
	ds_bpermute_b32 v13, v41, v12
	v_mov_b32_e32 v38, v48
	v_mov_b32_e32 v39, v50
	v_mov_b32_e32 v50, v49
	s_waitcnt lgkmcnt(0)
	v_add_f32_e32 v12, v12, v13
	ds_bpermute_b32 v13, v42, v12
	s_waitcnt lgkmcnt(0)
	v_add_f32_e32 v12, v12, v13
	ds_bpermute_b32 v13, v43, v12
	s_waitcnt lgkmcnt(0)
	v_add_f32_e32 v12, v12, v13
	ds_bpermute_b32 v13, v44, v12
	s_waitcnt lgkmcnt(0)
	v_add_f32_e32 v12, v12, v13
	ds_bpermute_b32 v13, v45, v12
	s_waitcnt lgkmcnt(0)
	v_add_f32_e32 v12, v12, v13
	ds_bpermute_b32 v13, v46, v12
	s_waitcnt lgkmcnt(0)
	v_add_f32_e32 v12, v12, v13
	v_fmamk_f32 v12, v12, 0x3a800000, v219
	v_cmp_gt_f32_e32 vcc, s25, v12
	v_mul_f32_e32 v13, 0x4b800000, v12
	s_waitcnt vmcnt(2)
	v_mov_b32_e32 v64, v52
	v_cndmask_b32_e32 v12, v12, v13, vcc
	v_rsq_f32_e32 v12, v12
	v_mov_b32_e32 v65, v54
	v_mov_b32_e32 v54, v53
	s_waitcnt vmcnt(0)
	v_mov_b32_e32 v67, v62
	v_mul_f32_e32 v13, 0x45800000, v12
	v_cndmask_b32_e32 v12, v12, v13, vcc
	v_pk_mul_f32 v[38:39], v[38:39], v[12:13] op_sel_hi:[1,0]
	v_pk_mul_f32 v[48:49], v[50:51], v[12:13] op_sel_hi:[1,0]
	v_pk_mul_f32 v[38:39], v[64:65], v[38:39]
	v_mov_b32_e32 v65, v58
	v_mov_b32_e32 v58, v57
	v_mov_b32_e32 v64, v56
	v_pk_mul_f32 v[48:49], v[54:55], v[48:49]
	v_pk_add_f32 v[50:51], v[58:59], 1.0 op_sel_hi:[1,0]
	v_mov_b32_e32 v62, v61
	v_pk_add_f32 v[64:65], v[64:65], 1.0 op_sel_hi:[1,0]
	v_mov_b32_e32 v66, v60
	v_pk_fma_f32 v[48:49], v[50:51], v[48:49], v[62:63]
	v_pk_fma_f32 v[38:39], v[64:65], v[38:39], v[66:67]
	v_and_b32_sdwa v33, v49, v218 dst_sel:DWORD dst_unused:UNUSED_PAD src0_sel:WORD_1 src1_sel:DWORD
	v_and_b32_sdwa v13, v39, v218 dst_sel:DWORD dst_unused:UNUSED_PAD src0_sel:WORD_1 src1_sel:DWORD
	v_cvt_pk_bf16_f32 v38, v38, v48
	v_add3_u32 v33, v49, v33, s80
	v_add3_u32 v13, v39, v13, s80
	v_and_b32_e32 v33, 0xffff0000, v33
	v_add_co_u32_e32 v48, vcc, s4, v28
	v_or_b32_sdwa v39, v33, v13 dst_sel:DWORD dst_unused:UNUSED_PAD src0_sel:DWORD src1_sel:WORD_1
	s_nop 0
	v_addc_co_u32_e32 v49, vcc, -1, v29, vcc
	global_store_dwordx2 v[48:49], v[38:39], off nt
	v_mov_b32_e32 v31, v193
	v_lshl_add_u64 v[38:39], v[36:37], 0, v[30:31]
	global_load_dwordx4 v[48:51], v[20:21], off
	global_load_dwordx4 v[52:55], v[38:39], off
	global_load_dwordx4 v[56:59], v[14:15], off offset:1024
	v_mov_b32_e32 v38, v8
	v_mov_b32_e32 v39, v10
	v_pk_mul_f32 v[38:39], v[38:39], v[12:13] op_sel_hi:[1,0]
	v_mov_b32_e32 v10, v9
	v_pk_mul_f32 v[8:9], v[10:11], v[12:13] op_sel_hi:[1,0]
	s_mov_b32 s4, 0xf823d000
	v_mov_b32_e32 v33, v193
	v_mov_b32_e32 v35, v193
	s_waitcnt vmcnt(2)
	v_mov_b32_e32 v60, v48
	v_mov_b32_e32 v61, v50
	v_pk_mul_f32 v[38:39], v[38:39], v[60:61]
	s_waitcnt vmcnt(1)
	v_mov_b32_e32 v60, v52
	v_mov_b32_e32 v61, v54
	v_pk_add_f32 v[60:61], v[60:61], 1.0 op_sel_hi:[1,0]
	s_waitcnt vmcnt(0)
	v_mov_b32_e32 v62, v56
	v_mov_b32_e32 v63, v58
	v_mov_b32_e32 v50, v49
	v_mov_b32_e32 v54, v53
	v_pk_fma_f32 v[38:39], v[38:39], v[60:61], v[62:63]
	v_pk_mul_f32 v[8:9], v[8:9], v[50:51]
	v_pk_add_f32 v[10:11], v[54:55], 1.0 op_sel_hi:[1,0]
	v_mov_b32_e32 v58, v57
	v_pk_fma_f32 v[8:9], v[8:9], v[10:11], v[58:59]
	v_and_b32_sdwa v11, v38, v218 dst_sel:DWORD dst_unused:UNUSED_PAD src0_sel:WORD_1 src1_sel:DWORD
	v_add3_u32 v13, v38, v11, s80
	v_and_b32_sdwa v31, v8, v218 dst_sel:DWORD dst_unused:UNUSED_PAD src0_sel:WORD_1 src1_sel:DWORD
	v_cvt_pk_bf16_f32 v11, v39, v9
	v_add3_u32 v8, v8, v31, s80
	v_and_b32_e32 v8, 0xffff0000, v8
	v_or_b32_sdwa v10, v8, v13 dst_sel:DWORD dst_unused:UNUSED_PAD src0_sel:DWORD src1_sel:WORD_1
	v_add_co_u32_e32 v8, vcc, s4, v28
	s_nop 1
	v_addc_co_u32_e32 v9, vcc, -1, v29, vcc
	global_store_dwordx2 v[8:9], v[10:11], off offset:-3584 nt
	v_lshl_add_u64 v[10:11], v[36:37], 0, v[32:33]
	global_load_dwordx4 v[48:51], v[22:23], off
	global_load_dwordx4 v[52:55], v[10:11], off
	global_load_dwordx4 v[56:59], v[14:15], off offset:2048
	v_mov_b32_e32 v10, v4
	v_mov_b32_e32 v11, v6
	v_pk_mul_f32 v[10:11], v[10:11], v[12:13] op_sel_hi:[1,0]
	v_mov_b32_e32 v6, v5
	v_pk_mul_f32 v[4:5], v[6:7], v[12:13] op_sel_hi:[1,0]
	v_cmp_lt_i32_e32 vcc, s26, v40
	v_lshl_add_u64 v[28:29], v[28:29], 0, s[30:31]
	s_or_b64 s[2:3], vcc, s[2:3]
	s_waitcnt vmcnt(2)
	v_mov_b32_e32 v38, v48
	v_mov_b32_e32 v39, v50
	v_pk_mul_f32 v[10:11], v[10:11], v[38:39]
	s_waitcnt vmcnt(1)
	v_mov_b32_e32 v38, v52
	v_mov_b32_e32 v39, v54
	v_pk_add_f32 v[38:39], v[38:39], 1.0 op_sel_hi:[1,0]
	s_waitcnt vmcnt(0)
	v_mov_b32_e32 v60, v56
	v_mov_b32_e32 v61, v58
	v_mov_b32_e32 v50, v49
	v_mov_b32_e32 v54, v53
	v_pk_fma_f32 v[10:11], v[10:11], v[38:39], v[60:61]
	v_pk_mul_f32 v[4:5], v[4:5], v[50:51]
	v_pk_add_f32 v[6:7], v[54:55], 1.0 op_sel_hi:[1,0]
	v_mov_b32_e32 v58, v57
	v_pk_fma_f32 v[4:5], v[4:5], v[6:7], v[58:59]
	v_cvt_pk_bf16_f32 v4, v10, v4
	v_cvt_pk_bf16_f32 v5, v11, v5
	global_store_dwordx2 v[8:9], v[4:5], off offset:-3072 nt
	v_lshl_add_u64 v[10:11], v[36:37], 0, v[34:35]
	global_load_dwordx4 v[4:7], v[24:25], off
	global_load_dwordx4 v[36:39], v[10:11], off
	global_load_dwordx4 v[48:51], v[14:15], off offset:3072
	v_mov_b32_e32 v10, v0
	v_mov_b32_e32 v11, v2
	v_pk_mul_f32 v[10:11], v[10:11], v[12:13] op_sel_hi:[1,0]
	v_mov_b32_e32 v2, v1
	v_pk_mul_f32 v[0:1], v[2:3], v[12:13] op_sel_hi:[1,0]
	s_waitcnt vmcnt(2)
	v_mov_b32_e32 v14, v4
	v_mov_b32_e32 v15, v6
	v_pk_mul_f32 v[10:11], v[10:11], v[14:15]
	s_waitcnt vmcnt(1)
	v_mov_b32_e32 v15, v38
	v_mov_b32_e32 v6, v5
	v_mov_b32_e32 v38, v37
	v_mov_b32_e32 v14, v36
	s_waitcnt vmcnt(0)
	v_mov_b32_e32 v53, v50
	v_pk_mul_f32 v[0:1], v[0:1], v[6:7]
	v_pk_add_f32 v[2:3], v[38:39], 1.0 op_sel_hi:[1,0]
	v_mov_b32_e32 v50, v49
	v_pk_add_f32 v[14:15], v[14:15], 1.0 op_sel_hi:[1,0]
	v_mov_b32_e32 v52, v48
	v_pk_fma_f32 v[0:1], v[0:1], v[2:3], v[50:51]
	v_pk_fma_f32 v[10:11], v[10:11], v[14:15], v[52:53]
	v_cvt_pk_bf16_f32 v1, v11, v1
	v_cvt_pk_bf16_f32 v0, v10, v0
	global_store_dwordx2 v[8:9], v[0:1], off offset:-2560 nt
	s_andn2_b64 exec, exec, s[2:3]
	s_cbranch_execnz .LBB0_34

.LBB0_69:
	v_and_b32_e32 v20, 56, v19
	v_lshlrev_b32_e32 v20, 2, v20
	v_add_u32_e32 v23, s0, v4
	ds_read_b32 v22, v20 offset:8192
	ds_read2_b32 v[20:21], v23 offset1:32
	s_addk_i32 s0, 0x400
	s_cmpk_lg_i32 s0, 0x2000
	s_waitcnt lgkmcnt(0)
	v_fmac_f32_e32 v0, v22, v20
	v_add_u32_e32 v20, v17, v19
	v_and_b32_e32 v20, 63, v20
	v_lshlrev_b32_e32 v20, 2, v20
	ds_read_b32 v20, v20 offset:8192
	s_waitcnt lgkmcnt(0)
	v_fmac_f32_e32 v0, v20, v21
	v_add_u32_e32 v20, v18, v19
	v_and_b32_e32 v20, 62, v20
	v_lshlrev_b32_e32 v20, 2, v20
	ds_read_b32 v22, v20 offset:8192
	ds_read2_b32 v[20:21], v23 offset0:64 offset1:96
	s_waitcnt lgkmcnt(0)
	v_fmac_f32_e32 v0, v22, v20
	v_add_u32_e32 v20, v6, v19
	v_and_b32_e32 v20, 61, v20
	v_lshlrev_b32_e32 v20, 2, v20
	ds_read_b32 v20, v20 offset:8192
	s_waitcnt lgkmcnt(0)
	v_fmac_f32_e32 v0, v20, v21
	v_add_u32_e32 v20, v7, v19
	v_and_b32_e32 v20, 60, v20
	v_lshlrev_b32_e32 v20, 2, v20
	ds_read_b32 v22, v20 offset:8192
	ds_read2_b32 v[20:21], v23 offset0:128 offset1:160
	s_waitcnt lgkmcnt(0)
	v_fmac_f32_e32 v0, v22, v20
	v_add_u32_e32 v20, v8, v19
	v_and_b32_e32 v20, 59, v20
	v_lshlrev_b32_e32 v20, 2, v20
	ds_read_b32 v20, v20 offset:8192
	s_waitcnt lgkmcnt(0)
	v_fmac_f32_e32 v0, v20, v21
	v_add_u32_e32 v20, v9, v19
	v_and_b32_e32 v20, 58, v20
	v_lshlrev_b32_e32 v20, 2, v20
	ds_read_b32 v22, v20 offset:8192
	ds_read2_b32 v[20:21], v23 offset0:192 offset1:224
	s_waitcnt lgkmcnt(0)
	v_fmac_f32_e32 v0, v22, v20
	v_add_u32_e32 v20, v10, v19
	v_and_b32_e32 v20, 57, v20
	v_lshlrev_b32_e32 v20, 2, v20
	ds_read_b32 v20, v20 offset:8192
	v_add_u32_e32 v19, v19, v11
	s_waitcnt lgkmcnt(0)
	v_fmac_f32_e32 v0, v20, v21
	s_cbranch_scc1 .LBB0_69
	v_bfe_u32 v9, v3, 16, 1
	v_and_b32_e32 v6, 56, v2
	v_add3_u32 v9, v3, v9, s80
	v_bfe_u32 v3, v5, 16, 1
	v_add3_u32 v3, v5, v3, s80
	v_and_b32_e32 v5, 0xffff0000, v3
	v_cvt_pk_bf16_f32 v3, v12, v13
	v_bfe_u32 v8, v0, 16, 1
	v_add3_u32 v0, v0, v8, s80
	v_and_b32_e32 v8, 0xffff0000, v0
	v_add_u32_e32 v0, s4, v1
	v_ashrrev_i32_e32 v1, 31, v0
	v_readlane_b32 s0, v253, 22
	v_lshlrev_b64 v[0:1], 10, v[0:1]
	v_readlane_b32 s1, v253, 23
	s_nop 1
	v_lshl_add_u64 v[0:1], s[0:1], 0, v[0:1]
	s_and_b32 s0, s3, 0x7fffff00
	s_lshl_b32 s78, s0, 1
	v_cvt_pk_bf16_f32 v4, v14, v15
	v_or_b32_sdwa v2, v5, v9 dst_sel:DWORD dst_unused:UNUSED_PAD src0_sel:DWORD src1_sel:WORD_1
	v_bfe_u32 v5, v16, 16, 1
	v_lshl_add_u64 v[0:1], v[0:1], 0, s[78:79]
	s_lshl_b32 s78, s2, 1
	v_lshl_add_u64 v[0:1], v[0:1], 0, s[78:79]
	v_lshlrev_b32_e32 v192, 1, v6
	v_add3_u32 v5, v16, v5, s80
	v_lshl_add_u64 v[0:1], v[0:1], 0, v[192:193]
	v_or_b32_sdwa v5, v8, v5 dst_sel:DWORD dst_unused:UNUSED_PAD src0_sel:DWORD src1_sel:WORD_1
	global_store_dwordx4 v[0:1], v[2:5], off
	s_barrier
	s_mov_b64 s[0:1], 0
.LBB0_71:
	s_and_b64 vcc, exec, s[0:1]
	s_cbranch_vccz .LBB0_73
	s_add_i32 s2, s8, 0xffffee86
	s_bfe_u32 s1, s2, 0x10003
	s_and_b32 s0, s2, 7
	s_lshr_b32 s2, s2, 4
	s_mul_i32 s3, s1, 24
	s_add_i32 s4, s2, s3
	s_lshl_b32 s3, s4, 6
	s_addk_i32 s3, 0xc00
	v_ashrrev_i32_e32 v0, 6, v32
	v_and_or_b32 v192, v32, 63, s3
	v_lshl_add_u32 v6, s0, 2, v0
	v_lshlrev_b64 v[0:1], 2, v[192:193]
	v_lshl_add_u64 v[2:3], s[54:55], 0, v[0:1]
	v_lshl_add_u64 v[0:1], s[56:57], 0, v[0:1]
	s_lshl_b32 s4, s4, 2
	global_load_dword v5, v[0:1], off
	v_mov_b32_e32 v0, s4
	global_load_dword v0, v0, s[58:59] offset:192
	s_mov_b32 s6, 0x3fb8aa3b
	global_load_dword v4, v[2:3], off
	s_mov_b32 s7, 0xc2ce8ed0
	s_mov_b32 s9, 0x42b17218
	s_cmp_eq_u32 s1, 0
	s_mov_b32 s4, 0x6dc9c883
	s_mov_b32 s5, 0x3fc45f30
	v_lshlrev_b32_e32 v14, 3, v32
	s_waitcnt vmcnt(1)
	v_mul_f32_e32 v1, 0x3fb8aa3b, v0
	v_fma_f32 v2, v0, s6, -v1
	v_rndne_f32_e32 v3, v1
	v_fmac_f32_e32 v2, 0x32a5705f, v0
	v_sub_f32_e32 v1, v1, v3
	v_add_f32_e32 v1, v1, v2
	v_exp_f32_e32 v1, v1
	v_cvt_i32_f32_e32 v2, v3
	v_cmp_ngt_f32_e32 vcc, s7, v0
	v_ldexp_f32 v1, v1, v2
	s_nop 0
	v_cndmask_b32_e32 v1, 0, v1, vcc
	v_cmp_nlt_f32_e32 vcc, s9, v0
	v_sub_u32_e32 v0, 31, v6
	s_nop 0
	v_cndmask_b32_e32 v10, v228, v1, vcc
	s_cselect_b64 vcc, -1, 0
	v_cndmask_b32_e32 v0, v6, v0, vcc
	v_cvt_f32_i32_e32 v1, v0
	v_cvt_f64_f32_e32 v[8:9], v10
	s_lshl_b32 s2, s2, 8
	s_lshl_b32 s1, s1, 7
	s_waitcnt vmcnt(0)
	v_mul_f32_e32 v1, v4, v1
	v_mul_f32_e32 v1, v1, v10
	v_mul_f32_e32 v2, 0x3fb8aa3b, v1
	v_fma_f32 v3, v1, s6, -v2
	v_rndne_f32_e32 v6, v2
	v_fmac_f32_e32 v3, 0x32a5705f, v1
	v_sub_f32_e32 v2, v2, v6
	v_add_f32_e32 v2, v2, v3
	v_exp_f32_e32 v2, v2
	v_cvt_i32_f32_e32 v3, v6
	v_cmp_ngt_f32_e32 vcc, s7, v1
	v_cvt_f64_f32_e32 v[6:7], v5
	s_or_b32 s1, s1, s2
	v_ldexp_f32 v2, v2, v3
	v_cndmask_b32_e32 v2, 0, v2, vcc
	v_cmp_nlt_f32_e32 vcc, s9, v1
	v_cvt_f64_i32_e32 v[0:1], v0
	v_mul_f64 v[0:1], v[0:1], v[6:7]
	v_mul_f64 v[0:1], v[0:1], v[8:9]
	v_cndmask_b32_e32 v11, v228, v2, vcc
	v_mul_f64 v[2:3], v[0:1], s[4:5]
	v_rndne_f64_e32 v[2:3], v[2:3]
	v_fma_f64 v[0:1], v[0:1], s[4:5], -v[2:3]
	v_cvt_f32_f64_e32 v1, v[0:1]
	v_cos_f32_e32 v0, v1
	v_sin_f32_e32 v1, v1
	v_mul_f64 v[6:7], v[6:7], v[8:9]
	v_mul_f64 v[8:9], v[6:7], s[4:5]
	v_mul_f32_e32 v0, v11, v0
	v_mul_f32_e32 v2, v11, v1
	v_mul_f32_e32 v1, v4, v10
	v_mul_f32_e32 v3, 0x3fb8aa3b, v1
	v_fma_f32 v10, v1, s6, -v3
	v_rndne_f32_e32 v11, v3
	v_fmac_f32_e32 v10, 0x32a5705f, v1
	v_sub_f32_e32 v3, v3, v11
	v_add_f32_e32 v3, v3, v10
	v_exp_f32_e32 v3, v3
	v_cvt_i32_f32_e32 v10, v11
	v_cmp_ngt_f32_e32 vcc, s7, v1
	v_rndne_f64_e32 v[8:9], v[8:9]
	v_fma_f64 v[6:7], v[6:7], s[4:5], -v[8:9]
	v_ldexp_f32 v3, v3, v10
	v_cndmask_b32_e32 v3, 0, v3, vcc
	v_cmp_nlt_f32_e32 vcc, s9, v1
	v_mov_b32_e32 v10, v5
	s_lshl_b32 s78, s0, 7
	v_cndmask_b32_e32 v1, v228, v3, vcc
	v_cvt_f32_f64_e32 v3, v[6:7]
	v_cos_f32_e32 v6, v3
	v_sin_f32_e32 v3, v3
	v_fma_f32 v8, v1, v6, -1.0
	v_mul_f32_e32 v9, v1, v3
	v_pk_mul_f32 v[6:7], v[4:5], v[4:5]
	v_pk_mul_f32 v[12:13], v[10:11], v[8:9] op_sel:[0,1] op_sel_hi:[0,0]
	v_pk_fma_f32 v[10:11], v[4:5], v[8:9], v[12:13]
	v_pk_fma_f32 v[8:9], v[4:5], v[8:9], v[12:13] op_sel_hi:[0,1,1] neg_lo:[0,0,1] neg_hi:[0,0,1]
	v_pk_add_f32 v[4:5], v[6:7], v[6:7] op_sel:[0,1] op_sel_hi:[0,1]
	v_rcp_f32_e32 v3, v5
	s_nop 0
	v_mul_f32_e32 v5, v9, v3
	v_div_scale_f32 v1, s[4:5], v4, v4, v10
	v_rcp_f32_e32 v3, v1
	s_nop 0
	v_fma_f32 v6, -v1, v3, 1.0
	v_fmac_f32_e32 v3, v6, v3
	v_div_scale_f32 v6, vcc, v10, v4, v10
	v_mul_f32_e32 v7, v6, v3
	v_fma_f32 v8, -v1, v7, v6
	v_fmac_f32_e32 v7, v8, v3
	v_fma_f32 v1, -v1, v7, v6
	v_div_fmas_f32 v1, v1, v3, v7
	v_div_fixup_f32 v4, v1, v4, v10
	v_pk_mul_f32 v[2:3], v[2:3], v[4:5] op_sel:[0,1] op_sel_hi:[0,0]
	v_pk_fma_f32 v[6:7], v[0:1], v[4:5], v[2:3] neg_lo:[0,0,1] neg_hi:[0,0,1]
	v_pk_fma_f32 v[0:1], v[0:1], v[4:5], v[2:3] op_sel_hi:[0,1,1]
	v_ashrrev_i32_e32 v2, 1, v32
	v_ashrrev_i32_e32 v5, 2, v32
	v_add_u32_e32 v2, s1, v2
	v_add_u32_e32 v0, s3, v5
	v_ashrrev_i32_e32 v3, 31, v2
	v_readlane_b32 s2, v253, 24
	v_lshlrev_b64 v[2:3], 10, v[2:3]
	v_readlane_b32 s3, v253, 25
	v_and_b32_e32 v4, 1, v32
	v_lshlrev_b32_e32 v192, 6, v4
	v_lshl_add_u64 v[2:3], s[2:3], 0, v[2:3]
	v_lshl_add_u64 v[2:3], v[2:3], 0, s[78:79]
	v_mov_b32_e32 v7, v1
	v_ashrrev_i32_e32 v1, 31, v0
	v_lshl_add_u64 v[34:35], v[2:3], 0, v[192:193]
	v_and_b32_e32 v2, 2, v32
	v_cmp_eq_u32_e32 vcc, 0, v2
	v_lshlrev_b32_e32 v2, 3, v5
	v_lshlrev_b64 v[0:1], 6, v[0:1]
	v_lshl_add_u32 v2, v4, 10, v2
	v_lshl_add_u64 v[38:39], s[60:61], 0, v[0:1]
	ds_write_b64 v14, v[6:7]
	s_waitcnt lgkmcnt(0)
	s_barrier
	v_lshl_add_u64 v[36:37], s[62:63], 0, v[0:1]
	ds_read2st64_b64 v[0:3], v2 offset1:1
	global_load_dwordx4 v[4:7], v[38:39], off offset:48
	global_load_dwordx4 v[12:15], v[38:39], off offset:32
	global_load_dwordx4 v[20:23], v[38:39], off offset:16
	global_load_dwordx4 v[28:31], v[38:39], off
	global_load_dwordx4 v[8:11], v[36:37], off offset:48
	global_load_dwordx4 v[16:19], v[36:37], off offset:32
	global_load_dwordx4 v[24:27], v[36:37], off offset:16
	global_load_dwordx4 v[40:43], v[36:37], off
	s_waitcnt vmcnt(4)
	v_mov_b32_e32 v44, v28
	v_mov_b32_e32 v45, v30
	v_mov_b32_e32 v49, v30
	v_mov_b32_e32 v30, v29
	s_waitcnt vmcnt(0)
	v_mov_b32_e32 v46, v40
	v_mov_b32_e32 v47, v42
	s_waitcnt lgkmcnt(0)
	v_pk_mul_f32 v[46:47], v[0:1], v[46:47] op_sel:[1,0]
	v_mov_b32_e32 v48, v40
	v_pk_fma_f32 v[44:45], v[0:1], v[44:45], v[46:47] op_sel_hi:[0,1,1] neg_lo:[0,0,1] neg_hi:[0,0,1]
	v_mov_b32_e32 v46, v28
	v_mov_b32_e32 v47, v42
	v_pk_mul_f32 v[46:47], v[0:1], v[46:47] op_sel:[1,0] op_sel_hi:[0,1]
	v_pk_fma_f32 v[46:47], v[0:1], v[48:49], v[46:47]
	v_mov_b32_e32 v42, v41
	v_cndmask_b32_e32 v33, v46, v44, vcc
	v_cndmask_b32_e32 v40, v47, v45, vcc
	v_pk_mul_f32 v[44:45], v[0:1], v[42:43] op_sel:[1,0]
	v_mov_b32_e32 v42, v29
	v_pk_fma_f32 v[44:45], v[0:1], v[30:31], v[44:45] op_sel_hi:[0,1,1] neg_lo:[0,0,1] neg_hi:[0,0,1]
	v_pk_mul_f32 v[28:29], v[0:1], v[42:43] op_sel:[1,0] op_sel_hi:[0,1]
	v_mov_b32_e32 v30, v41
	v_pk_fma_f32 v[28:29], v[0:1], v[30:31], v[28:29]
	v_cndmask_b32_e32 v28, v28, v44, vcc
	v_cndmask_b32_e32 v29, v29, v45, vcc
	v_cvt_pk_bf16_f32 v28, v33, v28
	v_cvt_pk_bf16_f32 v29, v40, v29
	v_mov_b32_e32 v40, v24
	v_mov_b32_e32 v41, v26
	v_mov_b32_e32 v30, v20
	v_mov_b32_e32 v31, v22
	v_pk_mul_f32 v[40:41], v[0:1], v[40:41] op_sel:[1,0]
	v_mov_b32_e32 v42, v24
	v_pk_fma_f32 v[30:31], v[0:1], v[30:31], v[40:41] op_sel_hi:[0,1,1] neg_lo:[0,0,1] neg_hi:[0,0,1]
	v_mov_b32_e32 v40, v20
	v_mov_b32_e32 v41, v26
	v_pk_mul_f32 v[40:41], v[0:1], v[40:41] op_sel:[1,0] op_sel_hi:[0,1]
	v_mov_b32_e32 v43, v22
	v_pk_fma_f32 v[40:41], v[0:1], v[42:43], v[40:41]
	v_mov_b32_e32 v26, v25
	v_cndmask_b32_e32 v24, v40, v30, vcc
	v_cndmask_b32_e32 v33, v41, v31, vcc
	v_mov_b32_e32 v22, v21
	v_pk_mul_f32 v[30:31], v[0:1], v[26:27] op_sel:[1,0]
	v_mov_b32_e32 v26, v21
	v_pk_fma_f32 v[30:31], v[0:1], v[22:23], v[30:31] op_sel_hi:[0,1,1] neg_lo:[0,0,1] neg_hi:[0,0,1]
	v_pk_mul_f32 v[20:21], v[0:1], v[26:27] op_sel:[1,0] op_sel_hi:[0,1]
	v_mov_b32_e32 v22, v25
	v_pk_fma_f32 v[20:21], v[0:1], v[22:23], v[20:21]
	v_and_b32_sdwa v23, v24, v218 dst_sel:DWORD dst_unused:UNUSED_PAD src0_sel:WORD_1 src1_sel:DWORD
	v_cndmask_b32_e32 v20, v20, v30, vcc
	v_cndmask_b32_e32 v21, v21, v31, vcc
	v_add3_u32 v23, v24, v23, s80
	v_and_b32_sdwa v25, v20, v218 dst_sel:DWORD dst_unused:UNUSED_PAD src0_sel:WORD_1 src1_sel:DWORD
	v_cvt_pk_bf16_f32 v31, v33, v21
	v_add3_u32 v20, v20, v25, s80
	v_and_b32_e32 v20, 0xffff0000, v20
	v_or_b32_sdwa v30, v20, v23 dst_sel:DWORD dst_unused:UNUSED_PAD src0_sel:DWORD src1_sel:WORD_1
	v_mov_b32_e32 v22, v16
	v_mov_b32_e32 v23, v18
	v_mov_b32_e32 v20, v12
	v_mov_b32_e32 v21, v14
	v_pk_mul_f32 v[22:23], v[0:1], v[22:23] op_sel:[1,0]
	v_mov_b32_e32 v24, v16
	v_pk_fma_f32 v[20:21], v[0:1], v[20:21], v[22:23] op_sel_hi:[0,1,1] neg_lo:[0,0,1] neg_hi:[0,0,1]
	v_mov_b32_e32 v22, v12
	v_mov_b32_e32 v23, v18
	v_pk_mul_f32 v[22:23], v[0:1], v[22:23] op_sel:[1,0] op_sel_hi:[0,1]
	v_mov_b32_e32 v25, v14
	v_pk_fma_f32 v[22:23], v[0:1], v[24:25], v[22:23]
	v_mov_b32_e32 v18, v17
	v_cndmask_b32_e32 v16, v22, v20, vcc
	v_cndmask_b32_e32 v22, v23, v21, vcc
	v_mov_b32_e32 v14, v13
	v_pk_mul_f32 v[20:21], v[0:1], v[18:19] op_sel:[1,0]
	v_mov_b32_e32 v18, v13
	v_pk_fma_f32 v[20:21], v[0:1], v[14:15], v[20:21] op_sel_hi:[0,1,1] neg_lo:[0,0,1] neg_hi:[0,0,1]
	v_pk_mul_f32 v[12:13], v[0:1], v[18:19] op_sel:[1,0] op_sel_hi:[0,1]
	v_mov_b32_e32 v14, v17
	v_pk_fma_f32 v[12:13], v[0:1], v[14:15], v[12:13]
	v_and_b32_sdwa v15, v16, v218 dst_sel:DWORD dst_unused:UNUSED_PAD src0_sel:WORD_1 src1_sel:DWORD
	v_cndmask_b32_e32 v12, v12, v20, vcc
	v_cndmask_b32_e32 v13, v13, v21, vcc
	v_add3_u32 v15, v16, v15, s80
	v_and_b32_sdwa v17, v12, v218 dst_sel:DWORD dst_unused:UNUSED_PAD src0_sel:WORD_1 src1_sel:DWORD
	v_cvt_pk_bf16_f32 v13, v22, v13
	v_add3_u32 v12, v12, v17, s80
	v_and_b32_e32 v12, 0xffff0000, v12
	v_mov_b32_e32 v16, v8
	v_mov_b32_e32 v17, v10
	v_or_b32_sdwa v12, v12, v15 dst_sel:DWORD dst_unused:UNUSED_PAD src0_sel:DWORD src1_sel:WORD_1
	v_mov_b32_e32 v14, v4
	v_mov_b32_e32 v15, v6
	v_pk_mul_f32 v[16:17], v[0:1], v[16:17] op_sel:[1,0]
	v_mov_b32_e32 v18, v8
	v_pk_fma_f32 v[14:15], v[0:1], v[14:15], v[16:17] op_sel_hi:[0,1,1] neg_lo:[0,0,1] neg_hi:[0,0,1]
	v_mov_b32_e32 v16, v4
	v_mov_b32_e32 v17, v10
	v_pk_mul_f32 v[16:17], v[0:1], v[16:17] op_sel:[1,0] op_sel_hi:[0,1]
	v_mov_b32_e32 v19, v6
	v_pk_fma_f32 v[16:17], v[0:1], v[18:19], v[16:17]
	v_mov_b32_e32 v10, v9
	v_cndmask_b32_e32 v8, v16, v14, vcc
	v_cndmask_b32_e32 v16, v17, v15, vcc
	v_mov_b32_e32 v6, v5
	v_pk_mul_f32 v[14:15], v[0:1], v[10:11] op_sel:[1,0]
	v_mov_b32_e32 v10, v5
	v_pk_fma_f32 v[14:15], v[0:1], v[6:7], v[14:15] op_sel_hi:[0,1,1] neg_lo:[0,0,1] neg_hi:[0,0,1]
	v_pk_mul_f32 v[4:5], v[0:1], v[10:11] op_sel:[1,0] op_sel_hi:[0,1]
	v_mov_b32_e32 v6, v9
	v_pk_fma_f32 v[0:1], v[0:1], v[6:7], v[4:5]
	v_cndmask_b32_e32 v0, v0, v14, vcc
	v_cndmask_b32_e32 v1, v1, v15, vcc
	v_cvt_pk_bf16_f32 v15, v16, v1
	v_cvt_pk_bf16_f32 v14, v8, v0
	global_store_dwordx4 v[34:35], v[28:31], off
	global_store_dwordx4 v[34:35], v[12:15], off offset:16
	global_load_dwordx4 v[4:7], v[38:39], off offset:48
	global_load_dwordx4 v[8:11], v[38:39], off offset:32
	s_nop 0
	global_load_dwordx4 v[12:15], v[38:39], off offset:16
	global_load_dwordx4 v[16:19], v[38:39], off
	global_load_dwordx4 v[20:23], v[36:37], off offset:48
	global_load_dwordx4 v[24:27], v[36:37], off offset:32
	global_load_dwordx4 v[28:31], v[36:37], off offset:16
	s_nop 0
	global_load_dwordx4 v[36:39], v[36:37], off
	s_waitcnt vmcnt(4)
	v_mov_b32_e32 v0, v16
	v_mov_b32_e32 v1, v18
	v_mov_b32_e32 v43, v18
	v_mov_b32_e32 v18, v17
	s_waitcnt vmcnt(0)
	v_mov_b32_e32 v40, v36
	v_mov_b32_e32 v41, v38
	v_pk_mul_f32 v[40:41], v[2:3], v[40:41] op_sel:[1,0]
	v_mov_b32_e32 v42, v36
	v_pk_fma_f32 v[0:1], v[2:3], v[0:1], v[40:41] op_sel_hi:[0,1,1] neg_lo:[0,0,1] neg_hi:[0,0,1]
	v_mov_b32_e32 v40, v16
	v_mov_b32_e32 v41, v38
	v_pk_mul_f32 v[40:41], v[2:3], v[40:41] op_sel:[1,0] op_sel_hi:[0,1]
	v_pk_fma_f32 v[40:41], v[2:3], v[42:43], v[40:41]
	v_mov_b32_e32 v38, v37
	v_cndmask_b32_e32 v33, v40, v0, vcc
	v_cndmask_b32_e32 v36, v41, v1, vcc
	v_pk_mul_f32 v[0:1], v[2:3], v[38:39] op_sel:[1,0]
	v_mov_b32_e32 v38, v17
	v_pk_fma_f32 v[0:1], v[2:3], v[18:19], v[0:1] op_sel_hi:[0,1,1] neg_lo:[0,0,1] neg_hi:[0,0,1]
	v_pk_mul_f32 v[16:17], v[2:3], v[38:39] op_sel:[1,0] op_sel_hi:[0,1]
	v_mov_b32_e32 v18, v37
	v_pk_fma_f32 v[16:17], v[2:3], v[18:19], v[16:17]
	v_mov_b32_e32 v37, v14
	v_cndmask_b32_e32 v0, v16, v0, vcc
	v_cndmask_b32_e32 v1, v17, v1, vcc
	v_and_b32_sdwa v17, v33, v218 dst_sel:DWORD dst_unused:UNUSED_PAD src0_sel:WORD_1 src1_sel:DWORD
	v_add3_u32 v18, v33, v17, s80
	v_and_b32_sdwa v19, v0, v218 dst_sel:DWORD dst_unused:UNUSED_PAD src0_sel:WORD_1 src1_sel:DWORD
	v_cvt_pk_bf16_f32 v17, v36, v1
	v_add3_u32 v0, v0, v19, s80
	v_and_b32_e32 v0, 0xffff0000, v0
	v_or_b32_sdwa v16, v0, v18 dst_sel:DWORD dst_unused:UNUSED_PAD src0_sel:DWORD src1_sel:WORD_1
	v_mov_b32_e32 v18, v28
	v_mov_b32_e32 v19, v30
	v_mov_b32_e32 v0, v12
	v_mov_b32_e32 v1, v14
	v_pk_mul_f32 v[18:19], v[2:3], v[18:19] op_sel:[1,0]
	v_mov_b32_e32 v36, v28
	v_pk_fma_f32 v[0:1], v[2:3], v[0:1], v[18:19] op_sel_hi:[0,1,1] neg_lo:[0,0,1] neg_hi:[0,0,1]
	v_mov_b32_e32 v18, v12
	v_mov_b32_e32 v19, v30
	v_pk_mul_f32 v[18:19], v[2:3], v[18:19] op_sel:[1,0] op_sel_hi:[0,1]
	v_pk_fma_f32 v[18:19], v[2:3], v[36:37], v[18:19]
	v_mov_b32_e32 v30, v29
	v_cndmask_b32_e32 v18, v18, v0, vcc
	v_cndmask_b32_e32 v19, v19, v1, vcc
	v_mov_b32_e32 v14, v13
	v_pk_mul_f32 v[0:1], v[2:3], v[30:31] op_sel:[1,0]
	v_mov_b32_e32 v30, v13
	v_pk_fma_f32 v[0:1], v[2:3], v[14:15], v[0:1] op_sel_hi:[0,1,1] neg_lo:[0,0,1] neg_hi:[0,0,1]
	v_pk_mul_f32 v[12:13], v[2:3], v[30:31] op_sel:[1,0] op_sel_hi:[0,1]
	v_mov_b32_e32 v14, v29
	v_pk_fma_f32 v[12:13], v[2:3], v[14:15], v[12:13]
	s_nop 0
	v_cndmask_b32_e32 v0, v12, v0, vcc
	v_cndmask_b32_e32 v1, v13, v1, vcc
	v_cvt_pk_bf16_f32 v19, v19, v1
	v_cvt_pk_bf16_f32 v18, v18, v0
	v_mov_b32_e32 v12, v24
	v_mov_b32_e32 v13, v26
	v_mov_b32_e32 v0, v8
	v_mov_b32_e32 v1, v10
	v_pk_mul_f32 v[12:13], v[2:3], v[12:13] op_sel:[1,0]
	v_mov_b32_e32 v14, v24
	v_pk_fma_f32 v[0:1], v[2:3], v[0:1], v[12:13] op_sel_hi:[0,1,1] neg_lo:[0,0,1] neg_hi:[0,0,1]
	v_mov_b32_e32 v12, v8
	v_mov_b32_e32 v13, v26
	v_pk_mul_f32 v[12:13], v[2:3], v[12:13] op_sel:[1,0] op_sel_hi:[0,1]
	v_mov_b32_e32 v15, v10
	v_pk_fma_f32 v[12:13], v[2:3], v[14:15], v[12:13]
	v_mov_b32_e32 v26, v25
	v_cndmask_b32_e32 v12, v12, v0, vcc
	v_cndmask_b32_e32 v13, v13, v1, vcc
	v_mov_b32_e32 v10, v9
	v_pk_mul_f32 v[0:1], v[2:3], v[26:27] op_sel:[1,0]
	v_mov_b32_e32 v26, v9
	v_pk_fma_f32 v[0:1], v[2:3], v[10:11], v[0:1] op_sel_hi:[0,1,1] neg_lo:[0,0,1] neg_hi:[0,0,1]
	v_pk_mul_f32 v[8:9], v[2:3], v[26:27] op_sel:[1,0] op_sel_hi:[0,1]
	v_mov_b32_e32 v10, v25
	v_pk_fma_f32 v[8:9], v[2:3], v[10:11], v[8:9]
	s_nop 0
	v_cndmask_b32_e32 v0, v8, v0, vcc
	v_cndmask_b32_e32 v1, v9, v1, vcc
	v_cvt_pk_bf16_f32 v1, v13, v1
	v_cvt_pk_bf16_f32 v0, v12, v0
	v_mov_b32_e32 v10, v20
	v_mov_b32_e32 v11, v22
	v_mov_b32_e32 v8, v4
	v_mov_b32_e32 v9, v6
	v_pk_mul_f32 v[10:11], v[2:3], v[10:11] op_sel:[1,0]
	v_mov_b32_e32 v12, v20
	v_pk_fma_f32 v[8:9], v[2:3], v[8:9], v[10:11] op_sel_hi:[0,1,1] neg_lo:[0,0,1] neg_hi:[0,0,1]
	v_mov_b32_e32 v10, v4
	v_mov_b32_e32 v11, v22
	v_pk_mul_f32 v[10:11], v[2:3], v[10:11] op_sel:[1,0] op_sel_hi:[0,1]
	v_mov_b32_e32 v13, v6
	v_pk_fma_f32 v[10:11], v[2:3], v[12:13], v[10:11]
	v_mov_b32_e32 v22, v21
	v_cndmask_b32_e32 v10, v10, v8, vcc
	v_cndmask_b32_e32 v11, v11, v9, vcc
	v_mov_b32_e32 v6, v5
	v_pk_mul_f32 v[8:9], v[2:3], v[22:23] op_sel:[1,0]
	v_mov_b32_e32 v22, v5
	v_pk_fma_f32 v[8:9], v[2:3], v[6:7], v[8:9] op_sel_hi:[0,1,1] neg_lo:[0,0,1] neg_hi:[0,0,1]
	v_pk_mul_f32 v[4:5], v[2:3], v[22:23] op_sel:[1,0] op_sel_hi:[0,1]
	v_mov_b32_e32 v6, v21
	v_pk_fma_f32 v[2:3], v[2:3], v[6:7], v[4:5]
	v_cndmask_b32_e32 v2, v2, v8, vcc
	v_cndmask_b32_e32 v3, v3, v9, vcc
	v_cvt_pk_bf16_f32 v3, v11, v3
	v_cvt_pk_bf16_f32 v2, v10, v2
	global_store_dwordx4 v[34:35], v[16:19], off offset:32
	global_store_dwordx4 v[34:35], v[0:3], off offset:48
	s_barrier

.LBB0_95:
	s_andn2_b64 vcc, exec, s[0:1]
	s_cbranch_vccnz .LBB0_47
	s_lshl_b32 s9, s8, 1
	s_cmpk_gt_i32 s8, 0xdf
	s_mov_b64 s[0:1], -1
	s_cbranch_scc0 .LBB0_114
	s_cmpk_gt_u32 s8, 0x15f
	s_cbranch_scc0 .LBB0_111
	s_cmpk_gt_u32 s8, 0x171
	s_cbranch_scc0 .LBB0_108
	s_cmpk_gt_u32 s8, 0x2d1
	s_cbranch_scc0 .LBB0_105
	s_cmpk_gt_u32 s8, 0x431
	s_cbranch_scc0 .LBB0_102
	s_add_i32 s0, s9, 0xfffff79c
	v_mov_b32_e32 v34, v208
	s_ashr_i32 s1, s0, 31
	v_readlane_b32 s2, v253, 49
	v_lshlrev_b32_e32 v0, 4, v34
	s_lshr_b32 s1, s1, 28
	v_and_b32_e32 v192, 0xf0, v0
	v_readlane_b32 s3, v253, 50
	s_add_i32 s1, s0, s1
	v_ashrrev_i32_e32 v32, 4, v34
	v_lshl_add_u64 v[16:17], s[2:3], 0, v[192:193]
	s_lshl_b32 s2, s1, 2
	s_and_b32 s1, s1, 0x3fffff0
	s_sub_i32 s0, s0, s1
	s_and_b32 s6, s2, 0xffffffc0
	s_lshl_b32 s2, s0, 6
	s_add_i32 s0, s9, 0xfffff79d
	s_ashr_i32 s1, s0, 31
	s_lshr_b32 s1, s1, 28
	s_ashr_i32 s3, s2, 31
	s_add_i32 s1, s0, s1
	v_lshl_add_u64 v[12:13], s[2:3], 2, v[16:17]
	s_lshl_b32 s3, s1, 2
	s_and_b32 s1, s1, 0x3fffff0
	v_add_u32_e32 v35, 0x100, v34
	s_sub_i32 s0, s0, s1
	v_add_u32_e32 v0, s6, v32
	v_ashrrev_i32_e32 v36, 4, v35
	v_add_u32_e32 v8, 0x200, v34
	v_add_u32_e32 v14, 0x300, v34
	s_lshl_b32 s0, s0, 6
	v_ashrrev_i32_e32 v1, 31, v0
	v_add_u32_e32 v4, s6, v36
	v_ashrrev_i32_e32 v37, 4, v8
	v_ashrrev_i32_e32 v38, 4, v14
	s_and_b32 s4, s3, 0xffffffc0
	s_ashr_i32 s1, s0, 31
	v_lshlrev_b64 v[0:1], 12, v[0:1]
	v_ashrrev_i32_e32 v5, 31, v4
	v_add_u32_e32 v8, s6, v37
	v_add_u32_e32 v14, s6, v38
	v_lshl_add_u64 v[28:29], s[0:1], 2, v[16:17]
	v_add_u32_e32 v16, s4, v32
	v_lshl_add_u64 v[0:1], v[12:13], 0, v[0:1]
	v_lshlrev_b64 v[4:5], 12, v[4:5]
	v_ashrrev_i32_e32 v9, 31, v8
	v_ashrrev_i32_e32 v15, 31, v14
	v_ashrrev_i32_e32 v17, 31, v16
	global_load_dwordx4 v[0:3], v[0:1], off nt
	v_lshl_add_u64 v[4:5], v[12:13], 0, v[4:5]
	v_lshlrev_b64 v[8:9], 12, v[8:9]
	v_lshlrev_b64 v[14:15], 12, v[14:15]
	v_lshlrev_b64 v[16:17], 12, v[16:17]
	v_add_u32_e32 v20, s4, v36
	global_load_dwordx4 v[4:7], v[4:5], off nt
	v_lshl_add_u64 v[8:9], v[12:13], 0, v[8:9]
	v_lshl_add_u64 v[12:13], v[12:13], 0, v[14:15]
	v_lshl_add_u64 v[16:17], v[28:29], 0, v[16:17]
	v_ashrrev_i32_e32 v21, 31, v20
	v_add_u32_e32 v24, s4, v37
	global_load_dwordx4 v[8:11], v[8:9], off nt
	v_lshlrev_b64 v[20:21], 12, v[20:21]
	global_load_dwordx4 v[12:15], v[12:13], off nt
	v_ashrrev_i32_e32 v25, 31, v24
	global_load_dwordx4 v[16:19], v[16:17], off nt
	v_lshl_add_u64 v[20:21], v[28:29], 0, v[20:21]
	v_lshlrev_b64 v[24:25], 12, v[24:25]
	v_add_u32_e32 v30, s4, v38
	global_load_dwordx4 v[20:23], v[20:21], off nt
	v_lshl_add_u64 v[24:25], v[28:29], 0, v[24:25]
	v_ashrrev_i32_e32 v31, 31, v30
	global_load_dwordx4 v[24:27], v[24:25], off nt
	v_lshlrev_b64 v[30:31], 12, v[30:31]
	v_lshl_add_u64 v[28:29], v[28:29], 0, v[30:31]
	global_load_dwordx4 v[28:31], v[28:29], off nt
	s_movk_i32 s1, 0x104
	v_mad_u64_u32 v[32:33], s[10:11], v32, s1, v[192:193]
	s_ashr_i32 s7, s6, 31
	s_ashr_i32 s5, s4, 31
	s_waitcnt vmcnt(7)
	ds_write2_b32 v32, v0, v1 offset1:1
	ds_write2_b32 v32, v2, v3 offset0:2 offset1:3
	v_mad_u64_u32 v[0:1], s[10:11], v36, s1, v[192:193]
	s_waitcnt vmcnt(6)
	ds_write2_b32 v0, v4, v5 offset1:1
	ds_write2_b32 v0, v6, v7 offset0:2 offset1:3
	v_mad_u64_u32 v[2:3], s[10:11], v37, s1, v[192:193]
	v_mad_u64_u32 v[4:5], s[10:11], v38, s1, v[192:193]
	v_add_u32_e32 v1, 0x4100, v32
	s_waitcnt vmcnt(5)
	ds_write2_b32 v2, v8, v9 offset1:1
	ds_write2_b32 v2, v10, v11 offset0:2 offset1:3
	s_waitcnt vmcnt(4)
	ds_write2_b32 v4, v12, v13 offset1:1
	ds_write2_b32 v4, v14, v15 offset0:2 offset1:3
	v_ashrrev_i32_e32 v14, 3, v34
	s_waitcnt vmcnt(3)
	ds_write2_b32 v1, v16, v17 offset1:1
	v_add_u32_e32 v1, 0x4108, v32
	ds_write2_b32 v1, v18, v19 offset1:1
	v_add_u32_e32 v1, 0x4100, v0
	v_add_u32_e32 v0, 0x4108, v0
	s_waitcnt vmcnt(2)
	ds_write2_b32 v0, v22, v23 offset1:1
	v_add_u32_e32 v0, 0x4100, v2
	ds_write2_b32 v1, v20, v21 offset1:1
	s_waitcnt vmcnt(1)
	ds_write2_b32 v0, v24, v25 offset1:1
	v_add_u32_e32 v0, 0x4108, v2
	ds_write2_b32 v0, v26, v27 offset1:1
	v_add_u32_e32 v0, 0x4100, v4
	s_waitcnt vmcnt(0)
	ds_write2_b32 v0, v28, v29 offset1:1
	v_add_u32_e32 v0, 0x4108, v4
	ds_write2_b32 v0, v30, v31 offset1:1
	v_lshlrev_b32_e32 v0, 3, v34
	v_and_b32_e32 v0, 56, v0
	v_mul_u32_u24_e32 v1, 0x41, v0
	v_lshlrev_b32_e32 v15, 2, v1
	v_lshl_add_u32 v16, v14, 2, v15
	s_waitcnt lgkmcnt(0)
	s_barrier
	v_lshlrev_b32_e32 v192, 1, v0
	ds_read2_b32 v[0:1], v16 offset1:65
	ds_read2_b32 v[2:3], v16 offset0:130 offset1:195
	v_add_u32_e32 v10, 0x400, v16
	ds_read2_b32 v[8:9], v10 offset0:4 offset1:69
	ds_read2_b32 v[10:11], v10 offset0:134 offset1:199
	v_readlane_b32 s10, v253, 28
	s_waitcnt lgkmcnt(3)
	v_cvt_pk_bf16_f32 v0, v0, v1
	s_waitcnt lgkmcnt(2)
	v_and_b32_sdwa v17, v2, v218 dst_sel:DWORD dst_unused:UNUSED_PAD src0_sel:WORD_1 src1_sel:DWORD
	v_add3_u32 v2, v2, v17, s80
	v_and_b32_sdwa v17, v3, v218 dst_sel:DWORD dst_unused:UNUSED_PAD src0_sel:WORD_1 src1_sel:DWORD
	v_add3_u32 v3, v3, v17, s80
	v_and_b32_e32 v3, 0xffff0000, v3
	v_or_b32_sdwa v1, v3, v2 dst_sel:DWORD dst_unused:UNUSED_PAD src0_sel:DWORD src1_sel:WORD_1
	s_waitcnt lgkmcnt(0)
	v_and_b32_sdwa v3, v8, v218 dst_sel:DWORD dst_unused:UNUSED_PAD src0_sel:WORD_1 src1_sel:DWORD
	v_readlane_b32 s11, v253, 29
	v_add3_u32 v8, v8, v3, s80
	v_cvt_pk_bf16_f32 v3, v10, v11
	v_and_b32_sdwa v10, v9, v218 dst_sel:DWORD dst_unused:UNUSED_PAD src0_sel:WORD_1 src1_sel:DWORD
	v_lshl_add_u64 v[4:5], s[10:11], 0, v[192:193]
	v_add3_u32 v9, v9, v10, s80
	v_lshl_add_u64 v[6:7], s[6:7], 1, v[4:5]
	v_add_u32_e32 v12, s2, v14
	s_movk_i32 s1, 0x1600
	v_and_b32_e32 v9, 0xffff0000, v9
	v_mad_i64_i32 v[12:13], s[6:7], v12, s1, v[6:7]
	v_or_b32_sdwa v2, v9, v8 dst_sel:DWORD dst_unused:UNUSED_PAD src0_sel:DWORD src1_sel:WORD_1
	global_store_dwordx4 v[12:13], v[0:3], off
	v_ashrrev_i32_e32 v12, 3, v35
	v_lshl_add_u32 v15, v12, 2, v15
	ds_read2_b32 v[0:1], v15 offset1:65
	ds_read2_b32 v[2:3], v15 offset0:130 offset1:195
	v_add_u32_e32 v10, 0x400, v15
	v_add_u32_e32 v13, s2, v12
	ds_read2_b32 v[8:9], v10 offset0:4 offset1:69
	ds_read2_b32 v[10:11], v10 offset0:134 offset1:199
	v_mad_i64_i32 v[6:7], s[2:3], v13, s1, v[6:7]
	s_waitcnt lgkmcnt(2)
	v_and_b32_sdwa v13, v2, v218 dst_sel:DWORD dst_unused:UNUSED_PAD src0_sel:WORD_1 src1_sel:DWORD
	v_cvt_pk_bf16_f32 v0, v0, v1
	v_add3_u32 v2, v2, v13, s80
	v_and_b32_sdwa v13, v3, v218 dst_sel:DWORD dst_unused:UNUSED_PAD src0_sel:WORD_1 src1_sel:DWORD
	v_add3_u32 v3, v3, v13, s80
	v_and_b32_e32 v3, 0xffff0000, v3
	v_or_b32_sdwa v1, v3, v2 dst_sel:DWORD dst_unused:UNUSED_PAD src0_sel:DWORD src1_sel:WORD_1
	s_waitcnt lgkmcnt(0)
	v_and_b32_sdwa v3, v8, v218 dst_sel:DWORD dst_unused:UNUSED_PAD src0_sel:WORD_1 src1_sel:DWORD
	v_add3_u32 v8, v8, v3, s80
	v_cvt_pk_bf16_f32 v3, v10, v11
	v_and_b32_sdwa v10, v9, v218 dst_sel:DWORD dst_unused:UNUSED_PAD src0_sel:WORD_1 src1_sel:DWORD
	v_add3_u32 v9, v9, v10, s80
	v_and_b32_e32 v9, 0xffff0000, v9
	v_or_b32_sdwa v2, v9, v8 dst_sel:DWORD dst_unused:UNUSED_PAD src0_sel:DWORD src1_sel:WORD_1
	global_store_dwordx4 v[6:7], v[0:3], off
	v_add_u32_e32 v6, 0x4400, v16
	v_add_u32_e32 v8, 0x4600, v16
	v_add_u32_e32 v2, 0x4200, v16
	v_add_u32_e32 v0, 0x4000, v16
	ds_read2_b32 v[2:3], v2 offset0:66 offset1:131
	ds_read2_b32 v[0:1], v0 offset0:64 offset1:129
	ds_read2_b32 v[6:7], v6 offset0:68 offset1:133
	ds_read2_b32 v[8:9], v8 offset0:70 offset1:135
	v_add_u32_e32 v10, s0, v14
	s_waitcnt lgkmcnt(3)
	v_and_b32_sdwa v13, v2, v218 dst_sel:DWORD dst_unused:UNUSED_PAD src0_sel:WORD_1 src1_sel:DWORD
	s_waitcnt lgkmcnt(2)
	v_cvt_pk_bf16_f32 v0, v0, v1
	v_add3_u32 v2, v2, v13, s80
	v_and_b32_sdwa v13, v3, v218 dst_sel:DWORD dst_unused:UNUSED_PAD src0_sel:WORD_1 src1_sel:DWORD
	v_add3_u32 v3, v3, v13, s80
	v_and_b32_e32 v3, 0xffff0000, v3
	v_or_b32_sdwa v1, v3, v2 dst_sel:DWORD dst_unused:UNUSED_PAD src0_sel:DWORD src1_sel:WORD_1
	s_waitcnt lgkmcnt(0)
	v_and_b32_sdwa v3, v6, v218 dst_sel:DWORD dst_unused:UNUSED_PAD src0_sel:WORD_1 src1_sel:DWORD
	v_add3_u32 v6, v6, v3, s80
	v_cvt_pk_bf16_f32 v3, v8, v9
	v_and_b32_sdwa v8, v7, v218 dst_sel:DWORD dst_unused:UNUSED_PAD src0_sel:WORD_1 src1_sel:DWORD
	v_add3_u32 v7, v7, v8, s80
	v_lshl_add_u64 v[4:5], s[4:5], 1, v[4:5]
	v_and_b32_e32 v7, 0xffff0000, v7
	v_mad_i64_i32 v[10:11], s[2:3], v10, s1, v[4:5]
	v_or_b32_sdwa v2, v7, v6 dst_sel:DWORD dst_unused:UNUSED_PAD src0_sel:DWORD src1_sel:WORD_1
	global_store_dwordx4 v[10:11], v[0:3], off
	v_add_u32_e32 v6, 0x4400, v15
	v_add_u32_e32 v8, 0x4600, v15
	v_add_u32_e32 v2, 0x4200, v15
	v_add_u32_e32 v0, 0x4000, v15
	ds_read2_b32 v[2:3], v2 offset0:66 offset1:131
	ds_read2_b32 v[0:1], v0 offset0:64 offset1:129
	v_add_u32_e32 v10, s0, v12
	ds_read2_b32 v[6:7], v6 offset0:68 offset1:133
	ds_read2_b32 v[8:9], v8 offset0:70 offset1:135
	v_mad_i64_i32 v[4:5], s[0:1], v10, s1, v[4:5]
	s_waitcnt lgkmcnt(3)
	v_and_b32_sdwa v10, v2, v218 dst_sel:DWORD dst_unused:UNUSED_PAD src0_sel:WORD_1 src1_sel:DWORD
	s_waitcnt lgkmcnt(2)
	v_cvt_pk_bf16_f32 v0, v0, v1
	v_add3_u32 v2, v2, v10, s80
	v_and_b32_sdwa v10, v3, v218 dst_sel:DWORD dst_unused:UNUSED_PAD src0_sel:WORD_1 src1_sel:DWORD
	v_add3_u32 v3, v3, v10, s80
	v_and_b32_e32 v3, 0xffff0000, v3
	v_or_b32_sdwa v1, v3, v2 dst_sel:DWORD dst_unused:UNUSED_PAD src0_sel:DWORD src1_sel:WORD_1
	s_waitcnt lgkmcnt(0)
	v_and_b32_sdwa v3, v6, v218 dst_sel:DWORD dst_unused:UNUSED_PAD src0_sel:WORD_1 src1_sel:DWORD
	v_add3_u32 v6, v6, v3, s80
	v_cvt_pk_bf16_f32 v3, v8, v9
	v_and_b32_sdwa v8, v7, v218 dst_sel:DWORD dst_unused:UNUSED_PAD src0_sel:WORD_1 src1_sel:DWORD
	v_add3_u32 v7, v7, v8, s80
	v_and_b32_e32 v7, 0xffff0000, v7
	v_or_b32_sdwa v2, v7, v6 dst_sel:DWORD dst_unused:UNUSED_PAD src0_sel:DWORD src1_sel:WORD_1
	global_store_dwordx4 v[4:5], v[0:3], off
	s_barrier
	s_mov_b64 s[0:1], 0
.LBB0_102:
	s_andn2_b64 vcc, exec, s[0:1]
	s_cbranch_vccnz .LBB0_104
	v_mov_b32_e32 v34, v208
	s_add_i32 s0, s9, 0xfffffa5c
	v_readlane_b32 s2, v253, 51
	v_lshlrev_b32_e32 v0, 4, v34
	v_and_b32_e32 v192, 0xf0, v0
	v_readlane_b32 s3, v253, 52
	s_mul_hi_i32 s1, s0, 0x2e8ba2e9
	v_add_u32_e32 v35, 0x100, v34
	v_lshl_add_u64 v[16:17], s[2:3], 0, v[192:193]
	s_lshr_b32 s2, s1, 31
	s_ashr_i32 s1, s1, 3
	s_add_i32 s1, s1, s2
	s_lshl_b32 s6, s1, 6
	s_mul_i32 s1, s1, 44
	s_sub_i32 s0, s0, s1
	s_lshl_b32 s4, s0, 6
	v_add_u32_e32 v8, 0x200, v34
	v_add_u32_e32 v14, 0x300, v34
	v_ashrrev_i32_e32 v32, 4, v34
	s_ashr_i32 s5, s4, 31
	v_ashrrev_i32_e32 v36, 4, v35
	v_ashrrev_i32_e32 v37, 4, v8
	v_ashrrev_i32_e32 v38, 4, v14
	v_lshl_add_u64 v[12:13], s[4:5], 2, v[16:17]
	v_add_u32_e32 v0, s6, v32
	s_movk_i32 s3, 0x2c00
	v_add_u32_e32 v4, s6, v36
	v_add_u32_e32 v8, s6, v37
	v_add_u32_e32 v14, s6, v38
	v_mad_i64_i32 v[0:1], s[0:1], v0, s3, v[12:13]
	v_mad_i64_i32 v[4:5], s[0:1], v4, s3, v[12:13]
	v_mad_i64_i32 v[8:9], s[0:1], v8, s3, v[12:13]
	v_mad_i64_i32 v[12:13], s[0:1], v14, s3, v[12:13]
	s_add_i32 s0, s9, 0xfffffa5d
	s_mul_hi_i32 s1, s0, 0x2e8ba2e9
	s_lshr_b32 s2, s1, 31
	s_ashr_i32 s1, s1, 3
	s_add_i32 s1, s1, s2
	s_lshl_b32 s2, s1, 6
	s_mul_i32 s1, s1, 44
	s_sub_i32 s0, s0, s1
	s_lshl_b32 s0, s0, 6
	s_ashr_i32 s1, s0, 31
	global_load_dwordx4 v[0:3], v[0:1], off nt
	v_lshl_add_u64 v[28:29], s[0:1], 2, v[16:17]
	v_add_u32_e32 v16, s2, v32
	global_load_dwordx4 v[4:7], v[4:5], off nt
	v_mad_i64_i32 v[16:17], s[10:11], v16, s3, v[28:29]
	global_load_dwordx4 v[8:11], v[8:9], off nt
	v_add_u32_e32 v20, s2, v36
	global_load_dwordx4 v[12:15], v[12:13], off nt
	v_mad_i64_i32 v[20:21], s[10:11], v20, s3, v[28:29]
	global_load_dwordx4 v[16:19], v[16:17], off nt
	v_add_u32_e32 v24, s2, v37
	global_load_dwordx4 v[20:23], v[20:21], off nt
	v_mad_i64_i32 v[24:25], s[10:11], v24, s3, v[28:29]
	global_load_dwordx4 v[24:27], v[24:25], off nt
	v_add_u32_e32 v30, s2, v38
	v_mad_i64_i32 v[28:29], s[10:11], v30, s3, v[28:29]
	global_load_dwordx4 v[28:31], v[28:29], off nt
	s_movk_i32 s1, 0x104
	v_mad_u64_u32 v[32:33], s[10:11], v32, s1, v[192:193]
	s_ashr_i32 s7, s6, 31
	s_ashr_i32 s3, s2, 31
	s_waitcnt vmcnt(7)
	ds_write2_b32 v32, v0, v1 offset1:1
	ds_write2_b32 v32, v2, v3 offset0:2 offset1:3
	v_mad_u64_u32 v[0:1], s[10:11], v36, s1, v[192:193]
	s_waitcnt vmcnt(6)
	ds_write2_b32 v0, v4, v5 offset1:1
	ds_write2_b32 v0, v6, v7 offset0:2 offset1:3
	v_mad_u64_u32 v[2:3], s[10:11], v37, s1, v[192:193]
	v_mad_u64_u32 v[4:5], s[10:11], v38, s1, v[192:193]
	v_add_u32_e32 v1, 0x4100, v32
	s_waitcnt vmcnt(5)
	ds_write2_b32 v2, v8, v9 offset1:1
	ds_write2_b32 v2, v10, v11 offset0:2 offset1:3
	s_waitcnt vmcnt(4)
	ds_write2_b32 v4, v12, v13 offset1:1
	ds_write2_b32 v4, v14, v15 offset0:2 offset1:3
	s_waitcnt vmcnt(3)
	ds_write2_b32 v1, v16, v17 offset1:1
	v_add_u32_e32 v1, 0x4108, v32
	ds_write2_b32 v1, v18, v19 offset1:1
	v_add_u32_e32 v1, 0x4100, v0
	v_add_u32_e32 v0, 0x4108, v0
	s_waitcnt vmcnt(2)
	ds_write2_b32 v0, v22, v23 offset1:1
	v_add_u32_e32 v0, 0x4100, v2
	ds_write2_b32 v1, v20, v21 offset1:1
	s_waitcnt vmcnt(1)
	ds_write2_b32 v0, v24, v25 offset1:1
	v_add_u32_e32 v0, 0x4108, v2
	ds_write2_b32 v0, v26, v27 offset1:1
	v_add_u32_e32 v0, 0x4100, v4
	s_waitcnt vmcnt(0)
	ds_write2_b32 v0, v28, v29 offset1:1
	v_add_u32_e32 v0, 0x4108, v4
	ds_write2_b32 v0, v30, v31 offset1:1
	v_lshlrev_b32_e32 v0, 3, v34
	v_and_b32_e32 v0, 56, v0
	v_mul_u32_u24_e32 v1, 0x41, v0
	v_ashrrev_i32_e32 v16, 3, v34
	v_lshlrev_b32_e32 v17, 2, v1
	v_lshl_add_u32 v19, v16, 2, v17
	s_waitcnt lgkmcnt(0)
	s_barrier
	ds_read2_b32 v[2:3], v19 offset1:65
	ds_read2_b32 v[8:9], v19 offset0:130 offset1:195
	v_lshlrev_b32_e32 v192, 1, v0
	v_readlane_b32 s10, v253, 30
	v_add_lshl_u32 v0, v16, s4, 1
	v_and_or_b32 v18, v16, 31, 32
	s_movk_i32 s1, 0xffc0
	v_readlane_b32 s11, v253, 31
	v_and_or_b32 v0, v0, s1, v18
	v_add_u32_e32 v1, 0x400, v19
	v_lshl_add_u64 v[4:5], s[10:11], 0, v[192:193]
	ds_read2_b32 v[10:11], v1 offset0:4 offset1:69
	ds_read2_b32 v[12:13], v1 offset0:134 offset1:199
	v_ashrrev_i32_e32 v1, 31, v0
	v_lshl_add_u64 v[6:7], s[6:7], 1, v[4:5]
	v_lshlrev_b64 v[0:1], 11, v[0:1]
	v_lshl_add_u64 v[14:15], v[6:7], 0, v[0:1]
	s_waitcnt lgkmcnt(2)
	v_and_b32_sdwa v1, v2, v218 dst_sel:DWORD dst_unused:UNUSED_PAD src0_sel:WORD_1 src1_sel:DWORD
	v_add3_u32 v2, v2, v1, s80
	v_cvt_pk_bf16_f32 v1, v8, v9
	v_and_b32_sdwa v8, v3, v218 dst_sel:DWORD dst_unused:UNUSED_PAD src0_sel:WORD_1 src1_sel:DWORD
	v_add3_u32 v3, v3, v8, s80
	v_and_b32_e32 v3, 0xffff0000, v3
	v_or_b32_sdwa v0, v3, v2 dst_sel:DWORD dst_unused:UNUSED_PAD src0_sel:DWORD src1_sel:WORD_1
	s_waitcnt lgkmcnt(1)
	s_waitcnt lgkmcnt(0)
	v_cvt_pk_bf16_f32 v3, v12, v13
	v_cvt_pk_bf16_f32 v2, v10, v11
	global_store_dwordx4 v[14:15], v[0:3], off
	v_ashrrev_i32_e32 v14, 3, v35
	v_lshl_add_u32 v17, v14, 2, v17
	ds_read2_b32 v[2:3], v17 offset1:65
	ds_read2_b32 v[8:9], v17 offset0:130 offset1:195
	v_add_lshl_u32 v0, v14, s4, 1
	v_and_or_b32 v15, v14, 31, 32
	v_and_or_b32 v0, v0, s1, v15
	v_add_u32_e32 v1, 0x400, v17
	ds_read2_b32 v[10:11], v1 offset0:4 offset1:69
	ds_read2_b32 v[12:13], v1 offset0:134 offset1:199
	v_ashrrev_i32_e32 v1, 31, v0
	v_lshlrev_b64 v[0:1], 11, v[0:1]
	v_lshl_add_u64 v[6:7], v[6:7], 0, v[0:1]
	s_waitcnt lgkmcnt(2)
	v_and_b32_sdwa v1, v2, v218 dst_sel:DWORD dst_unused:UNUSED_PAD src0_sel:WORD_1 src1_sel:DWORD
	v_add3_u32 v2, v2, v1, s80
	v_cvt_pk_bf16_f32 v1, v8, v9
	v_and_b32_sdwa v8, v3, v218 dst_sel:DWORD dst_unused:UNUSED_PAD src0_sel:WORD_1 src1_sel:DWORD
	v_add3_u32 v3, v3, v8, s80
	v_and_b32_e32 v3, 0xffff0000, v3
	v_or_b32_sdwa v0, v3, v2 dst_sel:DWORD dst_unused:UNUSED_PAD src0_sel:DWORD src1_sel:WORD_1
	s_waitcnt lgkmcnt(1)
	s_waitcnt lgkmcnt(0)
	v_cvt_pk_bf16_f32 v3, v12, v13
	v_cvt_pk_bf16_f32 v2, v10, v11
	global_store_dwordx4 v[6:7], v[0:3], off
	v_lshl_add_u64 v[4:5], s[2:3], 1, v[4:5]
	s_nop 0
	v_add_u32_e32 v1, 0x4000, v19
	ds_read2_b32 v[2:3], v1 offset0:64 offset1:129
	v_add_u32_e32 v1, 0x4200, v19
	ds_read2_b32 v[6:7], v1 offset0:66 offset1:131
	v_add_lshl_u32 v0, v16, s0, 1
	v_add_u32_e32 v1, 0x4400, v19
	v_and_or_b32 v0, v0, s1, v18
	ds_read2_b32 v[8:9], v1 offset0:68 offset1:133
	v_add_u32_e32 v1, 0x4600, v19
	ds_read2_b32 v[10:11], v1 offset0:70 offset1:135
	v_ashrrev_i32_e32 v1, 31, v0
	v_lshlrev_b64 v[0:1], 11, v[0:1]
	v_lshl_add_u64 v[12:13], v[4:5], 0, v[0:1]
	s_waitcnt lgkmcnt(2)
	v_and_b32_sdwa v1, v2, v218 dst_sel:DWORD dst_unused:UNUSED_PAD src0_sel:WORD_1 src1_sel:DWORD
	v_add3_u32 v2, v2, v1, s80
	v_cvt_pk_bf16_f32 v1, v6, v7
	v_and_b32_sdwa v6, v3, v218 dst_sel:DWORD dst_unused:UNUSED_PAD src0_sel:WORD_1 src1_sel:DWORD
	v_add3_u32 v3, v3, v6, s80
	v_and_b32_e32 v3, 0xffff0000, v3
	v_or_b32_sdwa v0, v3, v2 dst_sel:DWORD dst_unused:UNUSED_PAD src0_sel:DWORD src1_sel:WORD_1
	s_waitcnt lgkmcnt(1)
	s_waitcnt lgkmcnt(0)
	v_cvt_pk_bf16_f32 v3, v10, v11
	v_cvt_pk_bf16_f32 v2, v8, v9
	global_store_dwordx4 v[12:13], v[0:3], off
	s_nop 1
	v_add_u32_e32 v1, 0x4000, v17
	ds_read2_b32 v[2:3], v1 offset0:64 offset1:129
	v_add_u32_e32 v1, 0x4200, v17
	ds_read2_b32 v[6:7], v1 offset0:66 offset1:131
	v_add_lshl_u32 v0, v14, s0, 1
	v_add_u32_e32 v1, 0x4400, v17
	v_and_or_b32 v0, v0, s1, v15
	ds_read2_b32 v[8:9], v1 offset0:68 offset1:133
	v_add_u32_e32 v1, 0x4600, v17
	ds_read2_b32 v[10:11], v1 offset0:70 offset1:135
	v_ashrrev_i32_e32 v1, 31, v0
	v_lshlrev_b64 v[0:1], 11, v[0:1]
	v_lshl_add_u64 v[4:5], v[4:5], 0, v[0:1]
	s_waitcnt lgkmcnt(2)
	v_and_b32_sdwa v1, v2, v218 dst_sel:DWORD dst_unused:UNUSED_PAD src0_sel:WORD_1 src1_sel:DWORD
	v_add3_u32 v2, v2, v1, s80
	v_cvt_pk_bf16_f32 v1, v6, v7
	v_and_b32_sdwa v6, v3, v218 dst_sel:DWORD dst_unused:UNUSED_PAD src0_sel:WORD_1 src1_sel:DWORD
	v_add3_u32 v3, v3, v6, s80
	v_and_b32_e32 v3, 0xffff0000, v3
	v_or_b32_sdwa v0, v3, v2 dst_sel:DWORD dst_unused:UNUSED_PAD src0_sel:DWORD src1_sel:WORD_1
	s_waitcnt lgkmcnt(1)
	s_waitcnt lgkmcnt(0)
	v_cvt_pk_bf16_f32 v3, v10, v11
	v_cvt_pk_bf16_f32 v2, v8, v9
	global_store_dwordx4 v[4:5], v[0:3], off
	s_barrier

.LBB0_105:
	s_andn2_b64 vcc, exec, s[0:1]
	s_cbranch_vccnz .LBB0_107
	v_mov_b32_e32 v34, v208
	s_add_i32 s0, s9, 0xfffffd1c
	v_readlane_b32 s2, v253, 53
	v_lshlrev_b32_e32 v0, 4, v34
	v_and_b32_e32 v192, 0xf0, v0
	v_readlane_b32 s3, v253, 54
	s_mul_hi_i32 s1, s0, 0x2e8ba2e9
	v_add_u32_e32 v35, 0x100, v34
	v_lshl_add_u64 v[16:17], s[2:3], 0, v[192:193]
	s_lshr_b32 s2, s1, 31
	s_ashr_i32 s1, s1, 3
	s_add_i32 s1, s1, s2
	s_lshl_b32 s6, s1, 6
	s_mul_i32 s1, s1, 44
	s_sub_i32 s0, s0, s1
	s_lshl_b32 s4, s0, 6
	v_add_u32_e32 v8, 0x200, v34
	v_add_u32_e32 v14, 0x300, v34
	v_ashrrev_i32_e32 v32, 4, v34
	s_ashr_i32 s5, s4, 31
	v_ashrrev_i32_e32 v36, 4, v35
	v_ashrrev_i32_e32 v37, 4, v8
	v_ashrrev_i32_e32 v38, 4, v14
	v_lshl_add_u64 v[12:13], s[4:5], 2, v[16:17]
	v_add_u32_e32 v0, s6, v32
	s_movk_i32 s3, 0x2c00
	v_add_u32_e32 v4, s6, v36
	v_add_u32_e32 v8, s6, v37
	v_add_u32_e32 v14, s6, v38
	v_mad_i64_i32 v[0:1], s[0:1], v0, s3, v[12:13]
	v_mad_i64_i32 v[4:5], s[0:1], v4, s3, v[12:13]
	v_mad_i64_i32 v[8:9], s[0:1], v8, s3, v[12:13]
	v_mad_i64_i32 v[12:13], s[0:1], v14, s3, v[12:13]
	s_add_i32 s0, s9, 0xfffffd1d
	s_mul_hi_i32 s1, s0, 0x2e8ba2e9
	s_lshr_b32 s2, s1, 31
	s_ashr_i32 s1, s1, 3
	s_add_i32 s1, s1, s2
	s_lshl_b32 s2, s1, 6
	s_mul_i32 s1, s1, 44
	s_sub_i32 s0, s0, s1
	s_lshl_b32 s0, s0, 6
	s_ashr_i32 s1, s0, 31
	global_load_dwordx4 v[0:3], v[0:1], off nt
	v_lshl_add_u64 v[28:29], s[0:1], 2, v[16:17]
	v_add_u32_e32 v16, s2, v32
	global_load_dwordx4 v[4:7], v[4:5], off nt
	v_mad_i64_i32 v[16:17], s[10:11], v16, s3, v[28:29]
	global_load_dwordx4 v[8:11], v[8:9], off nt
	v_add_u32_e32 v20, s2, v36
	global_load_dwordx4 v[12:15], v[12:13], off nt
	v_mad_i64_i32 v[20:21], s[10:11], v20, s3, v[28:29]
	global_load_dwordx4 v[16:19], v[16:17], off nt
	v_add_u32_e32 v24, s2, v37
	global_load_dwordx4 v[20:23], v[20:21], off nt
	v_mad_i64_i32 v[24:25], s[10:11], v24, s3, v[28:29]
	global_load_dwordx4 v[24:27], v[24:25], off nt
	v_add_u32_e32 v30, s2, v38
	v_mad_i64_i32 v[28:29], s[10:11], v30, s3, v[28:29]
	global_load_dwordx4 v[28:31], v[28:29], off nt
	s_movk_i32 s1, 0x104
	v_mad_u64_u32 v[32:33], s[10:11], v32, s1, v[192:193]
	s_ashr_i32 s7, s6, 31
	s_ashr_i32 s3, s2, 31
	s_waitcnt vmcnt(7)
	ds_write2_b32 v32, v0, v1 offset1:1
	ds_write2_b32 v32, v2, v3 offset0:2 offset1:3
	v_mad_u64_u32 v[0:1], s[10:11], v36, s1, v[192:193]
	s_waitcnt vmcnt(6)
	ds_write2_b32 v0, v4, v5 offset1:1
	ds_write2_b32 v0, v6, v7 offset0:2 offset1:3
	v_mad_u64_u32 v[2:3], s[10:11], v37, s1, v[192:193]
	v_mad_u64_u32 v[4:5], s[10:11], v38, s1, v[192:193]
	v_add_u32_e32 v1, 0x4100, v32
	s_waitcnt vmcnt(5)
	ds_write2_b32 v2, v8, v9 offset1:1
	ds_write2_b32 v2, v10, v11 offset0:2 offset1:3
	s_waitcnt vmcnt(4)
	ds_write2_b32 v4, v12, v13 offset1:1
	ds_write2_b32 v4, v14, v15 offset0:2 offset1:3
	s_waitcnt vmcnt(3)
	ds_write2_b32 v1, v16, v17 offset1:1
	v_add_u32_e32 v1, 0x4108, v32
	ds_write2_b32 v1, v18, v19 offset1:1
	v_add_u32_e32 v1, 0x4100, v0
	v_add_u32_e32 v0, 0x4108, v0
	s_waitcnt vmcnt(2)
	ds_write2_b32 v0, v22, v23 offset1:1
	v_add_u32_e32 v0, 0x4100, v2
	ds_write2_b32 v1, v20, v21 offset1:1
	s_waitcnt vmcnt(1)
	ds_write2_b32 v0, v24, v25 offset1:1
	v_add_u32_e32 v0, 0x4108, v2
	ds_write2_b32 v0, v26, v27 offset1:1
	v_add_u32_e32 v0, 0x4100, v4
	s_waitcnt vmcnt(0)
	ds_write2_b32 v0, v28, v29 offset1:1
	v_add_u32_e32 v0, 0x4108, v4
	ds_write2_b32 v0, v30, v31 offset1:1
	v_lshlrev_b32_e32 v0, 3, v34
	v_and_b32_e32 v0, 56, v0
	v_mul_u32_u24_e32 v1, 0x41, v0
	v_ashrrev_i32_e32 v16, 3, v34
	v_lshlrev_b32_e32 v17, 2, v1
	v_lshl_add_u32 v19, v16, 2, v17
	s_waitcnt lgkmcnt(0)
	s_barrier
	ds_read2_b32 v[2:3], v19 offset1:65
	ds_read2_b32 v[8:9], v19 offset0:130 offset1:195
	v_lshlrev_b32_e32 v192, 1, v0
	v_readlane_b32 s10, v253, 30
	v_add_lshl_u32 v0, v16, s4, 1
	v_and_b32_e32 v18, 31, v16
	s_movk_i32 s1, 0xffc0
	v_readlane_b32 s11, v253, 31
	v_and_or_b32 v0, v0, s1, v18
	v_add_u32_e32 v1, 0x400, v19
	v_lshl_add_u64 v[4:5], s[10:11], 0, v[192:193]
	ds_read2_b32 v[10:11], v1 offset0:4 offset1:69
	ds_read2_b32 v[12:13], v1 offset0:134 offset1:199
	v_ashrrev_i32_e32 v1, 31, v0
	v_lshl_add_u64 v[6:7], s[6:7], 1, v[4:5]
	v_lshlrev_b64 v[0:1], 11, v[0:1]
	v_lshl_add_u64 v[14:15], v[6:7], 0, v[0:1]
	s_waitcnt lgkmcnt(2)
	v_and_b32_sdwa v1, v2, v218 dst_sel:DWORD dst_unused:UNUSED_PAD src0_sel:WORD_1 src1_sel:DWORD
	v_add3_u32 v2, v2, v1, s80
	v_cvt_pk_bf16_f32 v1, v8, v9
	v_and_b32_sdwa v8, v3, v218 dst_sel:DWORD dst_unused:UNUSED_PAD src0_sel:WORD_1 src1_sel:DWORD
	v_add3_u32 v3, v3, v8, s80
	v_and_b32_e32 v3, 0xffff0000, v3
	v_or_b32_sdwa v0, v3, v2 dst_sel:DWORD dst_unused:UNUSED_PAD src0_sel:DWORD src1_sel:WORD_1
	s_waitcnt lgkmcnt(1)
	s_waitcnt lgkmcnt(0)
	v_cvt_pk_bf16_f32 v3, v12, v13
	v_cvt_pk_bf16_f32 v2, v10, v11
	global_store_dwordx4 v[14:15], v[0:3], off
	v_ashrrev_i32_e32 v14, 3, v35
	v_lshl_add_u32 v17, v14, 2, v17
	ds_read2_b32 v[2:3], v17 offset1:65
	ds_read2_b32 v[8:9], v17 offset0:130 offset1:195
	v_add_lshl_u32 v0, v14, s4, 1
	v_and_b32_e32 v15, 31, v14
	v_and_or_b32 v0, v0, s1, v15
	v_add_u32_e32 v1, 0x400, v17
	ds_read2_b32 v[10:11], v1 offset0:4 offset1:69
	ds_read2_b32 v[12:13], v1 offset0:134 offset1:199
	v_ashrrev_i32_e32 v1, 31, v0
	v_lshlrev_b64 v[0:1], 11, v[0:1]
	v_lshl_add_u64 v[6:7], v[6:7], 0, v[0:1]
	s_waitcnt lgkmcnt(2)
	v_and_b32_sdwa v1, v2, v218 dst_sel:DWORD dst_unused:UNUSED_PAD src0_sel:WORD_1 src1_sel:DWORD
	v_add3_u32 v2, v2, v1, s80
	v_cvt_pk_bf16_f32 v1, v8, v9
	v_and_b32_sdwa v8, v3, v218 dst_sel:DWORD dst_unused:UNUSED_PAD src0_sel:WORD_1 src1_sel:DWORD
	v_add3_u32 v3, v3, v8, s80
	v_and_b32_e32 v3, 0xffff0000, v3
	v_or_b32_sdwa v0, v3, v2 dst_sel:DWORD dst_unused:UNUSED_PAD src0_sel:DWORD src1_sel:WORD_1
	s_waitcnt lgkmcnt(1)
	s_waitcnt lgkmcnt(0)
	v_cvt_pk_bf16_f32 v3, v12, v13
	v_cvt_pk_bf16_f32 v2, v10, v11
	global_store_dwordx4 v[6:7], v[0:3], off
	v_lshl_add_u64 v[4:5], s[2:3], 1, v[4:5]
	s_nop 0
	v_add_u32_e32 v1, 0x4000, v19
	ds_read2_b32 v[2:3], v1 offset0:64 offset1:129
	v_add_u32_e32 v1, 0x4200, v19
	ds_read2_b32 v[6:7], v1 offset0:66 offset1:131
	v_add_lshl_u32 v0, v16, s0, 1
	v_add_u32_e32 v1, 0x4400, v19
	v_and_or_b32 v0, v0, s1, v18
	ds_read2_b32 v[8:9], v1 offset0:68 offset1:133
	v_add_u32_e32 v1, 0x4600, v19
	ds_read2_b32 v[10:11], v1 offset0:70 offset1:135
	v_ashrrev_i32_e32 v1, 31, v0
	v_lshlrev_b64 v[0:1], 11, v[0:1]
	v_lshl_add_u64 v[12:13], v[4:5], 0, v[0:1]
	s_waitcnt lgkmcnt(2)
	v_and_b32_sdwa v1, v2, v218 dst_sel:DWORD dst_unused:UNUSED_PAD src0_sel:WORD_1 src1_sel:DWORD
	v_add3_u32 v2, v2, v1, s80
	v_cvt_pk_bf16_f32 v1, v6, v7
	v_and_b32_sdwa v6, v3, v218 dst_sel:DWORD dst_unused:UNUSED_PAD src0_sel:WORD_1 src1_sel:DWORD
	v_add3_u32 v3, v3, v6, s80
	v_and_b32_e32 v3, 0xffff0000, v3
	v_or_b32_sdwa v0, v3, v2 dst_sel:DWORD dst_unused:UNUSED_PAD src0_sel:DWORD src1_sel:WORD_1
	s_waitcnt lgkmcnt(1)
	s_waitcnt lgkmcnt(0)
	v_cvt_pk_bf16_f32 v3, v10, v11
	v_cvt_pk_bf16_f32 v2, v8, v9
	global_store_dwordx4 v[12:13], v[0:3], off
	s_nop 1
	v_add_u32_e32 v1, 0x4000, v17
	ds_read2_b32 v[2:3], v1 offset0:64 offset1:129
	v_add_u32_e32 v1, 0x4200, v17
	ds_read2_b32 v[6:7], v1 offset0:66 offset1:131
	v_add_lshl_u32 v0, v14, s0, 1
	v_add_u32_e32 v1, 0x4400, v17
	v_and_or_b32 v0, v0, s1, v15
	ds_read2_b32 v[8:9], v1 offset0:68 offset1:133
	v_add_u32_e32 v1, 0x4600, v17
	ds_read2_b32 v[10:11], v1 offset0:70 offset1:135
	v_ashrrev_i32_e32 v1, 31, v0
	v_lshlrev_b64 v[0:1], 11, v[0:1]
	v_lshl_add_u64 v[4:5], v[4:5], 0, v[0:1]
	s_waitcnt lgkmcnt(2)
	v_and_b32_sdwa v1, v2, v218 dst_sel:DWORD dst_unused:UNUSED_PAD src0_sel:WORD_1 src1_sel:DWORD
	v_add3_u32 v2, v2, v1, s80
	v_cvt_pk_bf16_f32 v1, v6, v7
	v_and_b32_sdwa v6, v3, v218 dst_sel:DWORD dst_unused:UNUSED_PAD src0_sel:WORD_1 src1_sel:DWORD
	v_add3_u32 v3, v3, v6, s80
	v_and_b32_e32 v3, 0xffff0000, v3
	v_or_b32_sdwa v0, v3, v2 dst_sel:DWORD dst_unused:UNUSED_PAD src0_sel:DWORD src1_sel:WORD_1
	s_waitcnt lgkmcnt(1)
	s_waitcnt lgkmcnt(0)
	v_cvt_pk_bf16_f32 v3, v10, v11
	v_cvt_pk_bf16_f32 v2, v8, v9
	global_store_dwordx4 v[4:5], v[0:3], off
	s_barrier

.LBB0_108:
	s_andn2_b64 vcc, exec, s[0:1]
	s_cbranch_vccnz .LBB0_110
	v_mov_b32_e32 v34, v208
	s_add_i32 s0, s9, 0xfffffd40
	v_readlane_b32 s2, v253, 55
	v_lshlrev_b32_e32 v0, 4, v34
	v_and_b32_e32 v192, 0xf0, v0
	v_readlane_b32 s3, v253, 56
	s_mul_hi_i32 s1, s0, 0x2aaaaaab
	v_add_u32_e32 v35, 0x100, v34
	v_lshl_add_u64 v[16:17], s[2:3], 0, v[192:193]
	s_lshr_b32 s2, s1, 31
	s_add_i32 s1, s1, s2
	s_lshl_b32 s6, s1, 6
	s_mul_i32 s1, s1, 6
	s_sub_i32 s0, s0, s1
	s_lshl_b32 s4, s0, 6
	v_add_u32_e32 v8, 0x200, v34
	v_add_u32_e32 v14, 0x300, v34
	v_ashrrev_i32_e32 v32, 4, v34
	s_ashr_i32 s5, s4, 31
	v_ashrrev_i32_e32 v36, 4, v35
	v_ashrrev_i32_e32 v37, 4, v8
	v_ashrrev_i32_e32 v38, 4, v14
	v_lshl_add_u64 v[12:13], s[4:5], 2, v[16:17]
	v_add_u32_e32 v0, s6, v32
	v_add_u32_e32 v4, s6, v36
	v_add_u32_e32 v8, s6, v37
	v_add_u32_e32 v14, s6, v38
	v_mad_i64_i32 v[0:1], s[0:1], v0, s68, v[12:13]
	v_mad_i64_i32 v[4:5], s[0:1], v4, s68, v[12:13]
	v_mad_i64_i32 v[8:9], s[0:1], v8, s68, v[12:13]
	v_mad_i64_i32 v[12:13], s[0:1], v14, s68, v[12:13]
	s_add_i32 s0, s9, 0xfffffd41
	s_mul_hi_i32 s1, s0, 0x2aaaaaab
	s_lshr_b32 s2, s1, 31
	s_add_i32 s1, s1, s2
	s_lshl_b32 s2, s1, 6
	s_mul_i32 s1, s1, 6
	s_sub_i32 s0, s0, s1
	s_lshl_b32 s0, s0, 6
	s_ashr_i32 s1, s0, 31
	global_load_dwordx4 v[0:3], v[0:1], off nt
	v_lshl_add_u64 v[28:29], s[0:1], 2, v[16:17]
	v_add_u32_e32 v16, s2, v32
	global_load_dwordx4 v[4:7], v[4:5], off nt
	v_mad_i64_i32 v[16:17], s[10:11], v16, s68, v[28:29]
	global_load_dwordx4 v[8:11], v[8:9], off nt
	v_add_u32_e32 v20, s2, v36
	global_load_dwordx4 v[12:15], v[12:13], off nt
	v_mad_i64_i32 v[20:21], s[10:11], v20, s68, v[28:29]
	global_load_dwordx4 v[16:19], v[16:17], off nt
	v_add_u32_e32 v24, s2, v37
	global_load_dwordx4 v[20:23], v[20:21], off nt
	v_mad_i64_i32 v[24:25], s[10:11], v24, s68, v[28:29]
	global_load_dwordx4 v[24:27], v[24:25], off nt
	v_add_u32_e32 v30, s2, v38
	v_mad_i64_i32 v[28:29], s[10:11], v30, s68, v[28:29]
	global_load_dwordx4 v[28:31], v[28:29], off nt
	s_movk_i32 s1, 0x104
	v_mad_u64_u32 v[32:33], s[10:11], v32, s1, v[192:193]
	s_ashr_i32 s7, s6, 31
	s_ashr_i32 s3, s2, 31
	s_waitcnt vmcnt(7)
	ds_write2_b32 v32, v0, v1 offset1:1
	ds_write2_b32 v32, v2, v3 offset0:2 offset1:3
	v_mad_u64_u32 v[0:1], s[10:11], v36, s1, v[192:193]
	s_waitcnt vmcnt(6)
	ds_write2_b32 v0, v4, v5 offset1:1
	ds_write2_b32 v0, v6, v7 offset0:2 offset1:3
	v_mad_u64_u32 v[2:3], s[10:11], v37, s1, v[192:193]
	v_mad_u64_u32 v[4:5], s[10:11], v38, s1, v[192:193]
	v_add_u32_e32 v1, 0x4100, v32
	s_waitcnt vmcnt(5)
	ds_write2_b32 v2, v8, v9 offset1:1
	ds_write2_b32 v2, v10, v11 offset0:2 offset1:3
	s_waitcnt vmcnt(4)
	ds_write2_b32 v4, v12, v13 offset1:1
	ds_write2_b32 v4, v14, v15 offset0:2 offset1:3
	s_waitcnt vmcnt(3)
	ds_write2_b32 v1, v16, v17 offset1:1
	v_add_u32_e32 v1, 0x4108, v32
	ds_write2_b32 v1, v18, v19 offset1:1
	v_add_u32_e32 v1, 0x4100, v0
	v_add_u32_e32 v0, 0x4108, v0
	s_waitcnt vmcnt(2)
	ds_write2_b32 v0, v22, v23 offset1:1
	v_add_u32_e32 v0, 0x4100, v2
	ds_write2_b32 v1, v20, v21 offset1:1
	s_waitcnt vmcnt(1)
	ds_write2_b32 v0, v24, v25 offset1:1
	v_add_u32_e32 v0, 0x4108, v2
	ds_write2_b32 v0, v26, v27 offset1:1
	v_add_u32_e32 v0, 0x4100, v4
	s_waitcnt vmcnt(0)
	ds_write2_b32 v0, v28, v29 offset1:1
	v_add_u32_e32 v0, 0x4108, v4
	ds_write2_b32 v0, v30, v31 offset1:1
	v_lshlrev_b32_e32 v0, 3, v34
	v_and_b32_e32 v0, 56, v0
	v_mul_u32_u24_e32 v1, 0x41, v0
	v_ashrrev_i32_e32 v14, 3, v34
	v_lshlrev_b32_e32 v15, 2, v1
	v_lshl_add_u32 v16, v14, 2, v15
	s_waitcnt lgkmcnt(0)
	s_barrier
	v_lshlrev_b32_e32 v192, 1, v0
	ds_read2_b32 v[0:1], v16 offset1:65
	ds_read2_b32 v[2:3], v16 offset0:130 offset1:195
	v_add_u32_e32 v10, 0x400, v16
	ds_read2_b32 v[8:9], v10 offset0:4 offset1:69
	ds_read2_b32 v[10:11], v10 offset0:134 offset1:199
	v_readlane_b32 s10, v253, 32
	s_waitcnt lgkmcnt(3)
	v_cvt_pk_bf16_f32 v0, v0, v1
	s_waitcnt lgkmcnt(2)
	v_and_b32_sdwa v17, v2, v218 dst_sel:DWORD dst_unused:UNUSED_PAD src0_sel:WORD_1 src1_sel:DWORD
	v_add3_u32 v2, v2, v17, s80
	v_and_b32_sdwa v17, v3, v218 dst_sel:DWORD dst_unused:UNUSED_PAD src0_sel:WORD_1 src1_sel:DWORD
	v_add3_u32 v3, v3, v17, s80
	v_and_b32_e32 v3, 0xffff0000, v3
	v_or_b32_sdwa v1, v3, v2 dst_sel:DWORD dst_unused:UNUSED_PAD src0_sel:DWORD src1_sel:WORD_1
	s_waitcnt lgkmcnt(0)
	v_and_b32_sdwa v3, v8, v218 dst_sel:DWORD dst_unused:UNUSED_PAD src0_sel:WORD_1 src1_sel:DWORD
	v_readlane_b32 s11, v253, 33
	v_add3_u32 v8, v8, v3, s80
	v_cvt_pk_bf16_f32 v3, v10, v11
	v_and_b32_sdwa v10, v9, v218 dst_sel:DWORD dst_unused:UNUSED_PAD src0_sel:WORD_1 src1_sel:DWORD
	v_lshl_add_u64 v[4:5], s[10:11], 0, v[192:193]
	v_add3_u32 v9, v9, v10, s80
	v_lshl_add_u64 v[6:7], s[6:7], 1, v[4:5]
	v_add_u32_e32 v12, s4, v14
	s_movk_i32 s1, 0x300
	v_and_b32_e32 v9, 0xffff0000, v9
	v_mad_i64_i32 v[12:13], s[6:7], v12, s1, v[6:7]
	v_or_b32_sdwa v2, v9, v8 dst_sel:DWORD dst_unused:UNUSED_PAD src0_sel:DWORD src1_sel:WORD_1
	global_store_dwordx4 v[12:13], v[0:3], off
	v_ashrrev_i32_e32 v12, 3, v35
	v_lshl_add_u32 v15, v12, 2, v15
	ds_read2_b32 v[0:1], v15 offset1:65
	ds_read2_b32 v[2:3], v15 offset0:130 offset1:195
	v_add_u32_e32 v10, 0x400, v15
	v_add_u32_e32 v13, s4, v12
	ds_read2_b32 v[8:9], v10 offset0:4 offset1:69
	ds_read2_b32 v[10:11], v10 offset0:134 offset1:199
	v_mad_i64_i32 v[6:7], s[4:5], v13, s1, v[6:7]
	s_waitcnt lgkmcnt(2)
	v_and_b32_sdwa v13, v2, v218 dst_sel:DWORD dst_unused:UNUSED_PAD src0_sel:WORD_1 src1_sel:DWORD
	v_cvt_pk_bf16_f32 v0, v0, v1
	v_add3_u32 v2, v2, v13, s80
	v_and_b32_sdwa v13, v3, v218 dst_sel:DWORD dst_unused:UNUSED_PAD src0_sel:WORD_1 src1_sel:DWORD
	v_add3_u32 v3, v3, v13, s80
	v_and_b32_e32 v3, 0xffff0000, v3
	v_or_b32_sdwa v1, v3, v2 dst_sel:DWORD dst_unused:UNUSED_PAD src0_sel:DWORD src1_sel:WORD_1
	s_waitcnt lgkmcnt(0)
	v_and_b32_sdwa v3, v8, v218 dst_sel:DWORD dst_unused:UNUSED_PAD src0_sel:WORD_1 src1_sel:DWORD
	v_add3_u32 v8, v8, v3, s80
	v_cvt_pk_bf16_f32 v3, v10, v11
	v_and_b32_sdwa v10, v9, v218 dst_sel:DWORD dst_unused:UNUSED_PAD src0_sel:WORD_1 src1_sel:DWORD
	v_add3_u32 v9, v9, v10, s80
	v_and_b32_e32 v9, 0xffff0000, v9
	v_or_b32_sdwa v2, v9, v8 dst_sel:DWORD dst_unused:UNUSED_PAD src0_sel:DWORD src1_sel:WORD_1
	global_store_dwordx4 v[6:7], v[0:3], off
	v_add_u32_e32 v6, 0x4400, v16
	v_add_u32_e32 v8, 0x4600, v16
	v_add_u32_e32 v2, 0x4200, v16
	v_add_u32_e32 v0, 0x4000, v16
	ds_read2_b32 v[2:3], v2 offset0:66 offset1:131
	ds_read2_b32 v[0:1], v0 offset0:64 offset1:129
	ds_read2_b32 v[6:7], v6 offset0:68 offset1:133
	ds_read2_b32 v[8:9], v8 offset0:70 offset1:135
	v_add_u32_e32 v10, s0, v14
	s_waitcnt lgkmcnt(3)
	v_and_b32_sdwa v13, v2, v218 dst_sel:DWORD dst_unused:UNUSED_PAD src0_sel:WORD_1 src1_sel:DWORD
	s_waitcnt lgkmcnt(2)
	v_cvt_pk_bf16_f32 v0, v0, v1
	v_add3_u32 v2, v2, v13, s80
	v_and_b32_sdwa v13, v3, v218 dst_sel:DWORD dst_unused:UNUSED_PAD src0_sel:WORD_1 src1_sel:DWORD
	v_add3_u32 v3, v3, v13, s80
	v_and_b32_e32 v3, 0xffff0000, v3
	v_or_b32_sdwa v1, v3, v2 dst_sel:DWORD dst_unused:UNUSED_PAD src0_sel:DWORD src1_sel:WORD_1
	s_waitcnt lgkmcnt(0)
	v_and_b32_sdwa v3, v6, v218 dst_sel:DWORD dst_unused:UNUSED_PAD src0_sel:WORD_1 src1_sel:DWORD
	v_add3_u32 v6, v6, v3, s80
	v_cvt_pk_bf16_f32 v3, v8, v9
	v_and_b32_sdwa v8, v7, v218 dst_sel:DWORD dst_unused:UNUSED_PAD src0_sel:WORD_1 src1_sel:DWORD
	v_add3_u32 v7, v7, v8, s80
	v_lshl_add_u64 v[4:5], s[2:3], 1, v[4:5]
	v_and_b32_e32 v7, 0xffff0000, v7
	v_mad_i64_i32 v[10:11], s[2:3], v10, s1, v[4:5]
	v_or_b32_sdwa v2, v7, v6 dst_sel:DWORD dst_unused:UNUSED_PAD src0_sel:DWORD src1_sel:WORD_1
	global_store_dwordx4 v[10:11], v[0:3], off
	v_add_u32_e32 v6, 0x4400, v15
	v_add_u32_e32 v8, 0x4600, v15
	v_add_u32_e32 v2, 0x4200, v15
	v_add_u32_e32 v0, 0x4000, v15
	ds_read2_b32 v[2:3], v2 offset0:66 offset1:131
	ds_read2_b32 v[0:1], v0 offset0:64 offset1:129
	v_add_u32_e32 v10, s0, v12
	ds_read2_b32 v[6:7], v6 offset0:68 offset1:133
	ds_read2_b32 v[8:9], v8 offset0:70 offset1:135
	v_mad_i64_i32 v[4:5], s[0:1], v10, s1, v[4:5]
	s_waitcnt lgkmcnt(3)
	v_and_b32_sdwa v10, v2, v218 dst_sel:DWORD dst_unused:UNUSED_PAD src0_sel:WORD_1 src1_sel:DWORD
	s_waitcnt lgkmcnt(2)
	v_cvt_pk_bf16_f32 v0, v0, v1
	v_add3_u32 v2, v2, v10, s80
	v_and_b32_sdwa v10, v3, v218 dst_sel:DWORD dst_unused:UNUSED_PAD src0_sel:WORD_1 src1_sel:DWORD
	v_add3_u32 v3, v3, v10, s80
	v_and_b32_e32 v3, 0xffff0000, v3
	v_or_b32_sdwa v1, v3, v2 dst_sel:DWORD dst_unused:UNUSED_PAD src0_sel:DWORD src1_sel:WORD_1
	s_waitcnt lgkmcnt(0)
	v_and_b32_sdwa v3, v6, v218 dst_sel:DWORD dst_unused:UNUSED_PAD src0_sel:WORD_1 src1_sel:DWORD
	v_add3_u32 v6, v6, v3, s80
	v_cvt_pk_bf16_f32 v3, v8, v9
	v_and_b32_sdwa v8, v7, v218 dst_sel:DWORD dst_unused:UNUSED_PAD src0_sel:WORD_1 src1_sel:DWORD
	v_add3_u32 v7, v7, v8, s80
	v_and_b32_e32 v7, 0xffff0000, v7
	v_or_b32_sdwa v2, v7, v6 dst_sel:DWORD dst_unused:UNUSED_PAD src0_sel:DWORD src1_sel:WORD_1
	global_store_dwordx4 v[4:5], v[0:3], off
	s_barrier

.LBB0_111:
	s_andn2_b64 vcc, exec, s[0:1]
	s_cbranch_vccnz .LBB0_113
	s_add_i32 s0, s9, 0xfffffe40
	v_mov_b32_e32 v34, v208
	s_ashr_i32 s1, s0, 31
	v_readlane_b32 s2, v253, 57
	v_lshlrev_b32_e32 v0, 4, v34
	s_lshr_b32 s1, s1, 28
	v_and_b32_e32 v192, 0xf0, v0
	v_readlane_b32 s3, v253, 58
	s_add_i32 s1, s0, s1
	v_ashrrev_i32_e32 v32, 4, v34
	v_lshl_add_u64 v[16:17], s[2:3], 0, v[192:193]
	s_lshl_b32 s2, s1, 2
	s_and_b32 s1, s1, 0x3fffff0
	s_sub_i32 s0, s0, s1
	s_and_b32 s6, s2, 0xffffffc0
	s_lshl_b32 s2, s0, 6
	s_add_i32 s0, s9, 0xfffffe41
	s_ashr_i32 s1, s0, 31
	s_lshr_b32 s1, s1, 28
	s_ashr_i32 s3, s2, 31
	s_add_i32 s1, s0, s1
	v_lshl_add_u64 v[12:13], s[2:3], 2, v[16:17]
	s_lshl_b32 s3, s1, 2
	s_and_b32 s1, s1, 0x3fffff0
	v_add_u32_e32 v35, 0x100, v34
	s_sub_i32 s0, s0, s1
	v_add_u32_e32 v0, s6, v32
	v_ashrrev_i32_e32 v36, 4, v35
	v_add_u32_e32 v8, 0x200, v34
	v_add_u32_e32 v14, 0x300, v34
	s_lshl_b32 s0, s0, 6
	v_ashrrev_i32_e32 v1, 31, v0
	v_add_u32_e32 v4, s6, v36
	v_ashrrev_i32_e32 v37, 4, v8
	v_ashrrev_i32_e32 v38, 4, v14
	s_and_b32 s4, s3, 0xffffffc0
	s_ashr_i32 s1, s0, 31
	v_lshlrev_b64 v[0:1], 12, v[0:1]
	v_ashrrev_i32_e32 v5, 31, v4
	v_add_u32_e32 v8, s6, v37
	v_add_u32_e32 v14, s6, v38
	v_lshl_add_u64 v[28:29], s[0:1], 2, v[16:17]
	v_add_u32_e32 v16, s4, v32
	v_lshl_add_u64 v[0:1], v[12:13], 0, v[0:1]
	v_lshlrev_b64 v[4:5], 12, v[4:5]
	v_ashrrev_i32_e32 v9, 31, v8
	v_ashrrev_i32_e32 v15, 31, v14
	v_ashrrev_i32_e32 v17, 31, v16
	global_load_dwordx4 v[0:3], v[0:1], off nt
	v_lshl_add_u64 v[4:5], v[12:13], 0, v[4:5]
	v_lshlrev_b64 v[8:9], 12, v[8:9]
	v_lshlrev_b64 v[14:15], 12, v[14:15]
	v_lshlrev_b64 v[16:17], 12, v[16:17]
	v_add_u32_e32 v20, s4, v36
	global_load_dwordx4 v[4:7], v[4:5], off nt
	v_lshl_add_u64 v[8:9], v[12:13], 0, v[8:9]
	v_lshl_add_u64 v[12:13], v[12:13], 0, v[14:15]
	v_lshl_add_u64 v[16:17], v[28:29], 0, v[16:17]
	v_ashrrev_i32_e32 v21, 31, v20
	v_add_u32_e32 v24, s4, v37
	global_load_dwordx4 v[8:11], v[8:9], off nt
	v_lshlrev_b64 v[20:21], 12, v[20:21]
	global_load_dwordx4 v[12:15], v[12:13], off nt
	v_ashrrev_i32_e32 v25, 31, v24
	global_load_dwordx4 v[16:19], v[16:17], off nt
	v_lshl_add_u64 v[20:21], v[28:29], 0, v[20:21]
	v_lshlrev_b64 v[24:25], 12, v[24:25]
	v_add_u32_e32 v30, s4, v38
	global_load_dwordx4 v[20:23], v[20:21], off nt
	v_lshl_add_u64 v[24:25], v[28:29], 0, v[24:25]
	v_ashrrev_i32_e32 v31, 31, v30
	global_load_dwordx4 v[24:27], v[24:25], off nt
	v_lshlrev_b64 v[30:31], 12, v[30:31]
	v_lshl_add_u64 v[28:29], v[28:29], 0, v[30:31]
	global_load_dwordx4 v[28:31], v[28:29], off nt
	s_movk_i32 s1, 0x104
	v_mad_u64_u32 v[32:33], s[10:11], v32, s1, v[192:193]
	s_ashr_i32 s7, s6, 31
	s_ashr_i32 s5, s4, 31
	s_waitcnt vmcnt(7)
	ds_write2_b32 v32, v0, v1 offset1:1
	ds_write2_b32 v32, v2, v3 offset0:2 offset1:3
	v_mad_u64_u32 v[0:1], s[10:11], v36, s1, v[192:193]
	s_waitcnt vmcnt(6)
	ds_write2_b32 v0, v4, v5 offset1:1
	ds_write2_b32 v0, v6, v7 offset0:2 offset1:3
	v_mad_u64_u32 v[2:3], s[10:11], v37, s1, v[192:193]
	v_mad_u64_u32 v[4:5], s[10:11], v38, s1, v[192:193]
	v_add_u32_e32 v1, 0x4100, v32
	s_waitcnt vmcnt(5)
	ds_write2_b32 v2, v8, v9 offset1:1
	ds_write2_b32 v2, v10, v11 offset0:2 offset1:3
	s_waitcnt vmcnt(4)
	ds_write2_b32 v4, v12, v13 offset1:1
	ds_write2_b32 v4, v14, v15 offset0:2 offset1:3
	v_readlane_b32 s10, v253, 34
	s_waitcnt vmcnt(3)
	ds_write2_b32 v1, v16, v17 offset1:1
	v_add_u32_e32 v1, 0x4108, v32
	ds_write2_b32 v1, v18, v19 offset1:1
	v_add_u32_e32 v1, 0x4100, v0
	v_add_u32_e32 v0, 0x4108, v0
	s_waitcnt vmcnt(2)
	ds_write2_b32 v0, v22, v23 offset1:1
	v_add_u32_e32 v0, 0x4100, v2
	ds_write2_b32 v1, v20, v21 offset1:1
	s_waitcnt vmcnt(1)
	ds_write2_b32 v0, v24, v25 offset1:1
	v_add_u32_e32 v0, 0x4108, v2
	ds_write2_b32 v0, v26, v27 offset1:1
	v_add_u32_e32 v0, 0x4100, v4
	s_waitcnt vmcnt(0)
	ds_write2_b32 v0, v28, v29 offset1:1
	v_add_u32_e32 v0, 0x4108, v4
	ds_write2_b32 v0, v30, v31 offset1:1
	v_lshlrev_b32_e32 v0, 3, v34
	v_and_b32_e32 v0, 56, v0
	v_mul_u32_u24_e32 v1, 0x41, v0
	v_ashrrev_i32_e32 v16, 3, v34
	v_lshlrev_b32_e32 v17, 2, v1
	v_lshl_add_u32 v18, v16, 2, v17
	s_waitcnt lgkmcnt(0)
	s_barrier
	ds_read2_b32 v[2:3], v18 offset1:65
	ds_read2_b32 v[8:9], v18 offset0:130 offset1:195
	v_lshlrev_b32_e32 v192, 1, v0
	v_readlane_b32 s11, v253, 35
	v_add_u32_e32 v0, s2, v16
	v_add_u32_e32 v1, 0x400, v18
	v_lshl_add_u64 v[4:5], s[10:11], 0, v[192:193]
	ds_read2_b32 v[10:11], v1 offset0:4 offset1:69
	ds_read2_b32 v[12:13], v1 offset0:134 offset1:199
	v_ashrrev_i32_e32 v1, 31, v0
	v_lshl_add_u64 v[6:7], s[6:7], 1, v[4:5]
	v_lshlrev_b64 v[0:1], 11, v[0:1]
	v_lshl_add_u64 v[14:15], v[6:7], 0, v[0:1]
	s_waitcnt lgkmcnt(2)
	v_and_b32_sdwa v1, v2, v218 dst_sel:DWORD dst_unused:UNUSED_PAD src0_sel:WORD_1 src1_sel:DWORD
	v_add3_u32 v2, v2, v1, s80
	v_cvt_pk_bf16_f32 v1, v8, v9
	v_and_b32_sdwa v8, v3, v218 dst_sel:DWORD dst_unused:UNUSED_PAD src0_sel:WORD_1 src1_sel:DWORD
	v_add3_u32 v3, v3, v8, s80
	v_and_b32_e32 v3, 0xffff0000, v3
	v_or_b32_sdwa v0, v3, v2 dst_sel:DWORD dst_unused:UNUSED_PAD src0_sel:DWORD src1_sel:WORD_1
	s_waitcnt lgkmcnt(1)
	s_waitcnt lgkmcnt(0)
	v_cvt_pk_bf16_f32 v3, v12, v13
	v_cvt_pk_bf16_f32 v2, v10, v11
	global_store_dwordx4 v[14:15], v[0:3], off
	v_ashrrev_i32_e32 v14, 3, v35
	v_lshl_add_u32 v15, v14, 2, v17
	ds_read2_b32 v[2:3], v15 offset1:65
	ds_read2_b32 v[8:9], v15 offset0:130 offset1:195
	v_add_u32_e32 v0, s2, v14
	v_add_u32_e32 v1, 0x400, v15
	ds_read2_b32 v[10:11], v1 offset0:4 offset1:69
	ds_read2_b32 v[12:13], v1 offset0:134 offset1:199
	v_ashrrev_i32_e32 v1, 31, v0
	v_lshlrev_b64 v[0:1], 11, v[0:1]
	v_lshl_add_u64 v[6:7], v[6:7], 0, v[0:1]
	s_waitcnt lgkmcnt(2)
	v_and_b32_sdwa v1, v2, v218 dst_sel:DWORD dst_unused:UNUSED_PAD src0_sel:WORD_1 src1_sel:DWORD
	v_add3_u32 v2, v2, v1, s80
	v_cvt_pk_bf16_f32 v1, v8, v9
	v_and_b32_sdwa v8, v3, v218 dst_sel:DWORD dst_unused:UNUSED_PAD src0_sel:WORD_1 src1_sel:DWORD
	v_add3_u32 v3, v3, v8, s80
	v_and_b32_e32 v3, 0xffff0000, v3
	v_or_b32_sdwa v0, v3, v2 dst_sel:DWORD dst_unused:UNUSED_PAD src0_sel:DWORD src1_sel:WORD_1
	s_waitcnt lgkmcnt(1)
	s_waitcnt lgkmcnt(0)
	v_cvt_pk_bf16_f32 v3, v12, v13
	v_cvt_pk_bf16_f32 v2, v10, v11
	global_store_dwordx4 v[6:7], v[0:3], off
	v_lshl_add_u64 v[4:5], s[4:5], 1, v[4:5]
	s_nop 0
	v_add_u32_e32 v1, 0x4000, v18
	ds_read2_b32 v[2:3], v1 offset0:64 offset1:129
	v_add_u32_e32 v1, 0x4200, v18
	ds_read2_b32 v[6:7], v1 offset0:66 offset1:131
	v_add_u32_e32 v1, 0x4400, v18
	v_add_u32_e32 v0, s0, v16
	ds_read2_b32 v[8:9], v1 offset0:68 offset1:133
	v_add_u32_e32 v1, 0x4600, v18
	ds_read2_b32 v[10:11], v1 offset0:70 offset1:135
	v_ashrrev_i32_e32 v1, 31, v0
	v_lshlrev_b64 v[0:1], 11, v[0:1]
	v_lshl_add_u64 v[12:13], v[4:5], 0, v[0:1]
	s_waitcnt lgkmcnt(2)
	v_and_b32_sdwa v1, v2, v218 dst_sel:DWORD dst_unused:UNUSED_PAD src0_sel:WORD_1 src1_sel:DWORD
	v_add3_u32 v2, v2, v1, s80
	v_cvt_pk_bf16_f32 v1, v6, v7
	v_and_b32_sdwa v6, v3, v218 dst_sel:DWORD dst_unused:UNUSED_PAD src0_sel:WORD_1 src1_sel:DWORD
	v_add3_u32 v3, v3, v6, s80
	v_and_b32_e32 v3, 0xffff0000, v3
	v_or_b32_sdwa v0, v3, v2 dst_sel:DWORD dst_unused:UNUSED_PAD src0_sel:DWORD src1_sel:WORD_1
	s_waitcnt lgkmcnt(1)
	s_waitcnt lgkmcnt(0)
	v_cvt_pk_bf16_f32 v3, v10, v11
	v_cvt_pk_bf16_f32 v2, v8, v9
	global_store_dwordx4 v[12:13], v[0:3], off
	s_nop 1
	v_add_u32_e32 v1, 0x4000, v15
	ds_read2_b32 v[2:3], v1 offset0:64 offset1:129
	v_add_u32_e32 v1, 0x4200, v15
	ds_read2_b32 v[6:7], v1 offset0:66 offset1:131
	v_add_u32_e32 v1, 0x4400, v15
	v_add_u32_e32 v0, s0, v14
	ds_read2_b32 v[8:9], v1 offset0:68 offset1:133
	v_add_u32_e32 v1, 0x4600, v15
	ds_read2_b32 v[10:11], v1 offset0:70 offset1:135
	v_ashrrev_i32_e32 v1, 31, v0
	v_lshlrev_b64 v[0:1], 11, v[0:1]
	v_lshl_add_u64 v[4:5], v[4:5], 0, v[0:1]
	s_waitcnt lgkmcnt(2)
	v_and_b32_sdwa v1, v2, v218 dst_sel:DWORD dst_unused:UNUSED_PAD src0_sel:WORD_1 src1_sel:DWORD
	v_add3_u32 v2, v2, v1, s80
	v_cvt_pk_bf16_f32 v1, v6, v7
	v_and_b32_sdwa v6, v3, v218 dst_sel:DWORD dst_unused:UNUSED_PAD src0_sel:WORD_1 src1_sel:DWORD
	v_add3_u32 v3, v3, v6, s80
	v_and_b32_e32 v3, 0xffff0000, v3
	v_or_b32_sdwa v0, v3, v2 dst_sel:DWORD dst_unused:UNUSED_PAD src0_sel:DWORD src1_sel:WORD_1
	s_waitcnt lgkmcnt(1)
	s_waitcnt lgkmcnt(0)
	v_cvt_pk_bf16_f32 v3, v10, v11
	v_cvt_pk_bf16_f32 v2, v8, v9
	global_store_dwordx4 v[4:5], v[0:3], off
	s_barrier

.LBB0_114:
	s_andn2_b64 vcc, exec, s[0:1]
	s_cbranch_vccnz .LBB0_47
	v_mov_b32_e32 v34, v208
	v_readlane_b32 s0, v253, 59
	v_lshlrev_b32_e32 v0, 4, v34
	v_and_b32_e32 v192, 0xf0, v0
	v_readlane_b32 s1, v253, 60
	v_add_u32_e32 v35, 0x100, v34
	v_add_u32_e32 v8, 0x200, v34
	v_lshl_add_u64 v[16:17], s[0:1], 0, v[192:193]
	s_mul_hi_i32 s0, s8, 0x92492493
	s_add_i32 s0, s0, s8
	s_lshr_b32 s1, s0, 31
	s_lshr_b32 s0, s0, 3
	s_add_i32 s0, s0, s1
	s_lshl_b32 s6, s0, 6
	s_mul_hi_i32 s0, s9, 0x92492493
	s_add_i32 s0, s0, s9
	s_lshr_b32 s1, s0, 31
	s_lshr_b32 s0, s0, 4
	s_add_i32 s0, s0, s1
	s_mul_i32 s0, s0, 28
	s_sub_i32 s0, s9, s0
	s_lshl_b32 s4, s0, 6
	v_add_u32_e32 v14, 0x300, v34
	v_ashrrev_i32_e32 v32, 4, v34
	s_ashr_i32 s5, s4, 31
	v_ashrrev_i32_e32 v36, 4, v35
	v_ashrrev_i32_e32 v37, 4, v8
	v_ashrrev_i32_e32 v38, 4, v14
	v_lshl_add_u64 v[12:13], s[4:5], 2, v[16:17]
	v_add_u32_e32 v0, s6, v32
	s_movk_i32 s3, 0x1c00
	v_add_u32_e32 v4, s6, v36
	v_add_u32_e32 v8, s6, v37
	v_add_u32_e32 v14, s6, v38
	v_mad_i64_i32 v[0:1], s[0:1], v0, s3, v[12:13]
	v_mad_i64_i32 v[4:5], s[0:1], v4, s3, v[12:13]
	v_mad_i64_i32 v[8:9], s[0:1], v8, s3, v[12:13]
	v_mad_i64_i32 v[12:13], s[0:1], v14, s3, v[12:13]
	s_or_b32 s0, s9, 1
	s_mul_hi_i32 s1, s0, 0x92492493
	s_add_i32 s1, s1, s0
	s_lshr_b32 s2, s1, 31
	s_ashr_i32 s1, s1, 4
	s_add_i32 s1, s1, s2
	s_lshl_b32 s2, s1, 6
	s_mul_i32 s1, s1, 28
	s_sub_i32 s0, s0, s1
	s_lshl_b32 s0, s0, 6
	s_ashr_i32 s1, s0, 31
	global_load_dwordx4 v[0:3], v[0:1], off nt
	v_lshl_add_u64 v[28:29], s[0:1], 2, v[16:17]
	v_add_u32_e32 v16, s2, v32
	global_load_dwordx4 v[4:7], v[4:5], off nt
	v_mad_i64_i32 v[16:17], s[10:11], v16, s3, v[28:29]
	global_load_dwordx4 v[8:11], v[8:9], off nt
	v_add_u32_e32 v20, s2, v36
	global_load_dwordx4 v[12:15], v[12:13], off nt
	v_mad_i64_i32 v[20:21], s[10:11], v20, s3, v[28:29]
	global_load_dwordx4 v[16:19], v[16:17], off nt
	v_add_u32_e32 v24, s2, v37
	global_load_dwordx4 v[20:23], v[20:21], off nt
	v_mad_i64_i32 v[24:25], s[10:11], v24, s3, v[28:29]
	global_load_dwordx4 v[24:27], v[24:25], off nt
	v_add_u32_e32 v30, s2, v38
	v_mad_i64_i32 v[28:29], s[10:11], v30, s3, v[28:29]
	global_load_dwordx4 v[28:31], v[28:29], off nt
	s_movk_i32 s1, 0x104
	v_mad_u64_u32 v[32:33], s[10:11], v32, s1, v[192:193]
	s_ashr_i32 s7, s6, 31
	s_ashr_i32 s3, s2, 31
	s_waitcnt vmcnt(7)
	ds_write2_b32 v32, v0, v1 offset1:1
	ds_write2_b32 v32, v2, v3 offset0:2 offset1:3
	v_mad_u64_u32 v[0:1], s[10:11], v36, s1, v[192:193]
	s_waitcnt vmcnt(6)
	ds_write2_b32 v0, v4, v5 offset1:1
	ds_write2_b32 v0, v6, v7 offset0:2 offset1:3
	v_mad_u64_u32 v[2:3], s[10:11], v37, s1, v[192:193]
	v_mad_u64_u32 v[4:5], s[10:11], v38, s1, v[192:193]
	v_add_u32_e32 v1, 0x4100, v32
	s_waitcnt vmcnt(5)
	ds_write2_b32 v2, v8, v9 offset1:1
	ds_write2_b32 v2, v10, v11 offset0:2 offset1:3
	s_waitcnt vmcnt(4)
	ds_write2_b32 v4, v12, v13 offset1:1
	ds_write2_b32 v4, v14, v15 offset0:2 offset1:3
	s_waitcnt vmcnt(3)
	ds_write2_b32 v1, v16, v17 offset1:1
	v_add_u32_e32 v1, 0x4108, v32
	ds_write2_b32 v1, v18, v19 offset1:1
	v_add_u32_e32 v1, 0x4100, v0
	v_add_u32_e32 v0, 0x4108, v0
	s_waitcnt vmcnt(2)
	ds_write2_b32 v0, v22, v23 offset1:1
	v_add_u32_e32 v0, 0x4100, v2
	ds_write2_b32 v1, v20, v21 offset1:1
	s_waitcnt vmcnt(1)
	ds_write2_b32 v0, v24, v25 offset1:1
	v_add_u32_e32 v0, 0x4108, v2
	ds_write2_b32 v0, v26, v27 offset1:1
	v_add_u32_e32 v0, 0x4100, v4
	s_waitcnt vmcnt(0)
	ds_write2_b32 v0, v28, v29 offset1:1
	v_add_u32_e32 v0, 0x4108, v4
	ds_write2_b32 v0, v30, v31 offset1:1
	v_lshlrev_b32_e32 v0, 3, v34
	v_and_b32_e32 v0, 56, v0
	v_mul_u32_u24_e32 v1, 0x41, v0
	v_ashrrev_i32_e32 v16, 3, v34
	v_lshlrev_b32_e32 v17, 2, v1
	v_lshl_add_u32 v18, v16, 2, v17
	s_waitcnt lgkmcnt(0)
	s_barrier
	ds_read2_b32 v[2:3], v18 offset1:65
	ds_read2_b32 v[8:9], v18 offset0:130 offset1:195
	v_lshlrev_b32_e32 v192, 1, v0
	v_add_u32_e32 v0, s4, v16
	v_add_u32_e32 v1, 0x400, v18
	v_lshl_add_u64 v[4:5], s[90:91], 0, v[192:193]
	ds_read2_b32 v[10:11], v1 offset0:4 offset1:69
	ds_read2_b32 v[12:13], v1 offset0:134 offset1:199
	v_ashrrev_i32_e32 v1, 31, v0
	v_lshl_add_u64 v[6:7], s[6:7], 1, v[4:5]
	v_lshlrev_b64 v[0:1], 11, v[0:1]
	v_lshl_add_u64 v[14:15], v[6:7], 0, v[0:1]
	s_waitcnt lgkmcnt(2)
	v_and_b32_sdwa v1, v2, v218 dst_sel:DWORD dst_unused:UNUSED_PAD src0_sel:WORD_1 src1_sel:DWORD
	v_add3_u32 v2, v2, v1, s80
	v_cvt_pk_bf16_f32 v1, v8, v9
	v_and_b32_sdwa v8, v3, v218 dst_sel:DWORD dst_unused:UNUSED_PAD src0_sel:WORD_1 src1_sel:DWORD
	v_add3_u32 v3, v3, v8, s80
	v_and_b32_e32 v3, 0xffff0000, v3
	v_or_b32_sdwa v0, v3, v2 dst_sel:DWORD dst_unused:UNUSED_PAD src0_sel:DWORD src1_sel:WORD_1
	s_waitcnt lgkmcnt(1)
	s_waitcnt lgkmcnt(0)
	v_cvt_pk_bf16_f32 v3, v12, v13
	v_cvt_pk_bf16_f32 v2, v10, v11
	global_store_dwordx4 v[14:15], v[0:3], off
	v_ashrrev_i32_e32 v14, 3, v35
	v_lshl_add_u32 v15, v14, 2, v17
	ds_read2_b32 v[2:3], v15 offset1:65
	ds_read2_b32 v[8:9], v15 offset0:130 offset1:195
	v_add_u32_e32 v0, s4, v14
	v_add_u32_e32 v1, 0x400, v15
	ds_read2_b32 v[10:11], v1 offset0:4 offset1:69
	ds_read2_b32 v[12:13], v1 offset0:134 offset1:199
	v_ashrrev_i32_e32 v1, 31, v0
	v_lshlrev_b64 v[0:1], 11, v[0:1]
	v_lshl_add_u64 v[6:7], v[6:7], 0, v[0:1]
	s_waitcnt lgkmcnt(2)
	v_and_b32_sdwa v1, v2, v218 dst_sel:DWORD dst_unused:UNUSED_PAD src0_sel:WORD_1 src1_sel:DWORD
	v_add3_u32 v2, v2, v1, s80
	v_cvt_pk_bf16_f32 v1, v8, v9
	v_and_b32_sdwa v8, v3, v218 dst_sel:DWORD dst_unused:UNUSED_PAD src0_sel:WORD_1 src1_sel:DWORD
	v_add3_u32 v3, v3, v8, s80
	v_and_b32_e32 v3, 0xffff0000, v3
	v_or_b32_sdwa v0, v3, v2 dst_sel:DWORD dst_unused:UNUSED_PAD src0_sel:DWORD src1_sel:WORD_1
	s_waitcnt lgkmcnt(1)
	s_waitcnt lgkmcnt(0)
	v_cvt_pk_bf16_f32 v3, v12, v13
	v_cvt_pk_bf16_f32 v2, v10, v11
	global_store_dwordx4 v[6:7], v[0:3], off
	v_lshl_add_u64 v[4:5], s[2:3], 1, v[4:5]
	s_nop 0
	v_add_u32_e32 v1, 0x4000, v18
	ds_read2_b32 v[2:3], v1 offset0:64 offset1:129
	v_add_u32_e32 v1, 0x4200, v18
	ds_read2_b32 v[6:7], v1 offset0:66 offset1:131
	v_add_u32_e32 v1, 0x4400, v18
	v_add_u32_e32 v0, s0, v16
	ds_read2_b32 v[8:9], v1 offset0:68 offset1:133
	v_add_u32_e32 v1, 0x4600, v18
	ds_read2_b32 v[10:11], v1 offset0:70 offset1:135
	v_ashrrev_i32_e32 v1, 31, v0
	v_lshlrev_b64 v[0:1], 11, v[0:1]
	v_lshl_add_u64 v[12:13], v[4:5], 0, v[0:1]
	s_waitcnt lgkmcnt(2)
	v_and_b32_sdwa v1, v2, v218 dst_sel:DWORD dst_unused:UNUSED_PAD src0_sel:WORD_1 src1_sel:DWORD
	v_add3_u32 v2, v2, v1, s80
	v_cvt_pk_bf16_f32 v1, v6, v7
	v_and_b32_sdwa v6, v3, v218 dst_sel:DWORD dst_unused:UNUSED_PAD src0_sel:WORD_1 src1_sel:DWORD
	v_add3_u32 v3, v3, v6, s80
	v_and_b32_e32 v3, 0xffff0000, v3
	v_or_b32_sdwa v0, v3, v2 dst_sel:DWORD dst_unused:UNUSED_PAD src0_sel:DWORD src1_sel:WORD_1
	s_waitcnt lgkmcnt(1)
	s_waitcnt lgkmcnt(0)
	v_cvt_pk_bf16_f32 v3, v10, v11
	v_cvt_pk_bf16_f32 v2, v8, v9
	global_store_dwordx4 v[12:13], v[0:3], off
	s_nop 1
	v_add_u32_e32 v1, 0x4000, v15
	ds_read2_b32 v[2:3], v1 offset0:64 offset1:129
	v_add_u32_e32 v1, 0x4200, v15
	ds_read2_b32 v[6:7], v1 offset0:66 offset1:131
	v_add_u32_e32 v1, 0x4400, v15
	v_add_u32_e32 v0, s0, v14
	ds_read2_b32 v[8:9], v1 offset0:68 offset1:133
	v_add_u32_e32 v1, 0x4600, v15
	ds_read2_b32 v[10:11], v1 offset0:70 offset1:135
	v_ashrrev_i32_e32 v1, 31, v0
	v_lshlrev_b64 v[0:1], 11, v[0:1]
	v_lshl_add_u64 v[4:5], v[4:5], 0, v[0:1]
	s_waitcnt lgkmcnt(2)
	v_and_b32_sdwa v1, v2, v218 dst_sel:DWORD dst_unused:UNUSED_PAD src0_sel:WORD_1 src1_sel:DWORD
	v_add3_u32 v2, v2, v1, s80
	v_cvt_pk_bf16_f32 v1, v6, v7
	v_and_b32_sdwa v6, v3, v218 dst_sel:DWORD dst_unused:UNUSED_PAD src0_sel:WORD_1 src1_sel:DWORD
	v_add3_u32 v3, v3, v6, s80
	v_and_b32_e32 v3, 0xffff0000, v3
	v_or_b32_sdwa v0, v3, v2 dst_sel:DWORD dst_unused:UNUSED_PAD src0_sel:DWORD src1_sel:WORD_1
	s_waitcnt lgkmcnt(1)
	s_waitcnt lgkmcnt(0)
	v_cvt_pk_bf16_f32 v3, v10, v11
	v_cvt_pk_bf16_f32 v2, v8, v9
	global_store_dwordx4 v[4:5], v[0:3], off
	s_barrier
	s_branch .LBB0_47

.LBB0_121:
	s_abs_i32 s4, s0
	v_readlane_b32 s5, v254, 29
	s_mul_hi_u32 s5, s4, s5
	s_mul_i32 s6, s5, s8
	s_sub_i32 s4, s4, s6
	s_ashr_i32 s1, s0, 31
	s_add_i32 s6, s5, 1
	s_sub_i32 s7, s4, s8
	s_cmp_ge_u32 s4, s8
	s_cselect_b32 s5, s6, s5
	s_cselect_b32 s4, s7, s4
	s_add_i32 s6, s5, 1
	s_cmp_ge_u32 s4, s8
	s_cselect_b32 s4, s6, s5
	s_xor_b32 s4, s4, s1
	s_sub_i32 s4, s4, s1
	s_lshr_b32 s1, s1, 30
	s_add_i32 s1, s0, s1
	s_ashr_i32 s5, s1, 2
	s_abs_i32 s5, s5
	v_readlane_b32 s7, v254, 31
	s_mul_hi_u32 s7, s5, s7
	v_readlane_b32 s8, v254, 30
	s_mul_i32 s7, s7, s8
	s_and_b32 s6, s1, 0xfffffc
	s_sub_i32 s5, s5, s7
	s_sub_i32 s6, s0, s6
	s_ashr_i32 s1, s1, 31
	s_sub_i32 s7, s5, s8
	s_cmp_ge_u32 s5, s8
	s_cselect_b32 s5, s7, s5
	s_sub_i32 s7, s5, s8
	s_cmp_ge_u32 s5, s8
	s_cselect_b32 s5, s7, s5
	s_xor_b32 s5, s5, s1
	s_sub_i32 s1, s5, s1
	v_readlane_b32 s5, v254, 25
	s_add_i32 s5, s5, s1
	s_lshl_b32 s1, s4, 10
	s_lshl_b32 s4, s6, 8
	v_mov_b32_e32 v203, v208
	v_readlane_b32 s6, v253, 28
	s_add_i32 s1, s1, s4
	v_readlane_b32 s7, v253, 29
	v_ashrrev_i32_e32 v4, 2, v203
	s_mul_i32 s4, s5, 0xc0
	v_add_u32_e32 v2, s1, v4
	v_mov_b64_e32 v[0:1], s[6:7]
	s_movk_i32 s5, 0x1600
	v_mad_i64_i32 v[0:1], s[6:7], v2, s5, v[0:1]
	v_lshlrev_b32_e32 v5, 4, v203
	v_readlane_b32 s6, v253, 61
	v_and_b32_e32 v192, 48, v5
	v_readlane_b32 s7, v253, 62
	v_lshl_add_u64 v[100:101], v[0:1], 0, v[192:193]
	v_add_u32_e32 v2, s4, v4
	v_mov_b64_e32 v[0:1], s[6:7]
	v_mad_i64_i32 v[0:1], s[6:7], v2, s5, v[0:1]
	s_mov_b32 s5, 0x58000
	v_add_co_u32_e32 v8, vcc, s5, v100
	s_mov_b32 s6, 0xb0000
	s_nop 0
	v_addc_co_u32_e32 v9, vcc, 0, v101, vcc
	v_add_co_u32_e32 v12, vcc, s6, v100
	s_mov_b32 s7, 0x108000
	s_nop 0
	v_addc_co_u32_e32 v13, vcc, 0, v101, vcc
	v_add_co_u32_e32 v16, vcc, s7, v100
	v_lshl_add_u64 v[102:103], v[0:1], 0, v[192:193]
	s_nop 0
	v_addc_co_u32_e32 v17, vcc, 0, v101, vcc
	v_bfe_u32 v6, v203, 5, 1
	v_lshrrev_b32_e32 v7, 2, v203
	v_bfe_u32 v10, v203, 2, 2
	v_add_co_u32_e32 v24, vcc, s5, v102
	v_lshlrev_b32_e32 v11, 1, v203
	v_bitop3_b32 v7, v6, v7, 3 bitop3:0x78
	v_bitop3_b32 v6, v6, v10, 2 bitop3:0x36
	v_and_b32_e32 v10, 0xffffffe0, v4
	v_addc_co_u32_e32 v25, vcc, 0, v103, vcc
	v_and_b32_e32 v192, 31, v203
	v_and_b32_e32 v204, 0x80, v11
	v_lshl_add_u32 v205, v10, 1, v10
	v_add_co_u32_e32 v28, vcc, s6, v102
	v_or_b32_e32 v11, v204, v192
	v_or_b32_e32 v10, v205, v192
	global_load_dwordx4 v[0:3], v[100:101], off
	global_load_dwordx4 v[32:35], v[8:9], off
	global_load_dwordx4 v[36:39], v[12:13], off
	global_load_dwordx4 v[40:43], v[16:17], off
	global_load_dwordx4 v[44:47], v[102:103], off
	v_addc_co_u32_e32 v29, vcc, 0, v103, vcc
	v_bitop3_b32 v5, v5, 48, v203 bitop3:0x48
	v_lshlrev_b32_e32 v11, 6, v11
	v_lshlrev_b32_e32 v7, 4, v7
	v_lshlrev_b32_e32 v6, 4, v6
	v_lshl_add_u32 v10, v10, 6, v214
	global_load_dwordx4 v[48:51], v[24:25], off
	global_load_dwordx4 v[52:55], v[28:29], off
	v_or_b32_e32 v114, v11, v7
	v_or_b32_e32 v115, v11, v6
	v_or_b32_e32 v116, v10, v7
	v_or_b32_e32 v117, v10, v6
	v_lshl_or_b32 v118, v4, 6, v5
	global_load_dwordx4 v[4:7], v[100:101], off offset:64
	s_nop 0
	global_load_dwordx4 v[8:11], v[8:9], off offset:64
	s_nop 0
	global_load_dwordx4 v[12:15], v[12:13], off offset:64
	s_nop 0
	global_load_dwordx4 v[16:19], v[16:17], off offset:64
	s_nop 0
	global_load_dwordx4 v[20:23], v[102:103], off offset:64
	s_nop 0
	global_load_dwordx4 v[24:27], v[24:25], off offset:64
	s_nop 0
	global_load_dwordx4 v[28:31], v[28:29], off offset:64
	v_accvgpr_mov_b32 a193, a192
	v_accvgpr_mov_b32 a194, a192
	v_accvgpr_mov_b32 a195, a192
	v_accvgpr_mov_b32 a196, a192
	v_accvgpr_mov_b32 a197, a192
	v_accvgpr_mov_b32 a198, a192
	v_accvgpr_mov_b32 a199, a192
	v_accvgpr_mov_b32 a200, a192
	v_accvgpr_mov_b32 a201, a192
	v_accvgpr_mov_b32 a202, a192
	v_accvgpr_mov_b32 a203, a192
	v_accvgpr_mov_b32 a204, a192
	v_accvgpr_mov_b32 a205, a192
	v_accvgpr_mov_b32 a206, a192
	v_accvgpr_mov_b32 a207, a192
	v_accvgpr_mov_b32 a0, a192
	v_accvgpr_mov_b32 a16, a192
	v_accvgpr_mov_b32 a32, a192
	v_accvgpr_write_b32 a63, 0
	v_accvgpr_write_b32 a62, 0
	v_accvgpr_write_b32 a61, 0
	v_accvgpr_write_b32 a60, 0
	v_accvgpr_write_b32 a59, 0
	v_accvgpr_write_b32 a58, 0
	v_accvgpr_write_b32 a57, 0
	v_accvgpr_write_b32 a56, 0
	v_accvgpr_write_b32 a55, 0
	v_accvgpr_write_b32 a54, 0
	v_accvgpr_write_b32 a53, 0
	v_accvgpr_write_b32 a52, 0
	v_accvgpr_write_b32 a51, 0
	v_accvgpr_write_b32 a50, 0
	v_accvgpr_write_b32 a49, 0
	v_accvgpr_write_b32 a48, 0
	v_accvgpr_write_b32 a79, 0
	v_accvgpr_write_b32 a78, 0
	v_accvgpr_write_b32 a77, 0
	v_accvgpr_write_b32 a76, 0
	v_accvgpr_write_b32 a75, 0
	v_accvgpr_write_b32 a74, 0
	v_accvgpr_write_b32 a73, 0
	v_accvgpr_write_b32 a72, 0
	v_accvgpr_write_b32 a71, 0
	v_accvgpr_write_b32 a70, 0
	v_accvgpr_write_b32 a69, 0
	v_accvgpr_write_b32 a68, 0
	v_accvgpr_write_b32 a67, 0
	v_accvgpr_write_b32 a66, 0
	v_accvgpr_write_b32 a65, 0
	v_accvgpr_write_b32 a64, 0
	v_accvgpr_write_b32 a95, 0
	v_accvgpr_write_b32 a94, 0
	v_accvgpr_write_b32 a93, 0
	v_accvgpr_write_b32 a92, 0
	v_accvgpr_write_b32 a91, 0
	v_accvgpr_write_b32 a90, 0
	v_accvgpr_write_b32 a89, 0
	v_accvgpr_write_b32 a88, 0
	v_accvgpr_write_b32 a87, 0
	v_accvgpr_write_b32 a86, 0
	v_accvgpr_write_b32 a85, 0
	v_accvgpr_write_b32 a84, 0
	v_accvgpr_write_b32 a83, 0
	v_accvgpr_write_b32 a82, 0
	v_accvgpr_write_b32 a81, 0
	v_accvgpr_write_b32 a80, 0
	v_accvgpr_write_b32 a111, 0
	v_accvgpr_write_b32 a110, 0
	v_accvgpr_write_b32 a109, 0
	v_accvgpr_write_b32 a108, 0
	v_accvgpr_write_b32 a107, 0
	v_accvgpr_write_b32 a106, 0
	v_accvgpr_write_b32 a105, 0
	v_accvgpr_write_b32 a104, 0
	v_accvgpr_write_b32 a103, 0
	v_accvgpr_write_b32 a102, 0
	v_accvgpr_write_b32 a101, 0
	v_accvgpr_write_b32 a100, 0
	v_accvgpr_write_b32 a99, 0
	v_accvgpr_write_b32 a98, 0
	v_accvgpr_write_b32 a97, 0
	v_accvgpr_write_b32 a96, 0
	v_accvgpr_write_b32 a127, 0
	v_accvgpr_write_b32 a126, 0
	v_accvgpr_write_b32 a125, 0
	v_accvgpr_write_b32 a124, 0
	v_accvgpr_write_b32 a123, 0
	v_accvgpr_write_b32 a122, 0
	v_accvgpr_write_b32 a121, 0
	v_accvgpr_write_b32 a120, 0
	v_accvgpr_write_b32 a119, 0
	v_accvgpr_write_b32 a118, 0
	v_accvgpr_write_b32 a117, 0
	v_accvgpr_write_b32 a116, 0
	v_accvgpr_write_b32 a115, 0
	v_accvgpr_write_b32 a114, 0
	v_accvgpr_write_b32 a113, 0
	v_accvgpr_write_b32 a112, 0
	v_accvgpr_write_b32 a143, 0
	v_accvgpr_write_b32 a142, 0
	v_accvgpr_write_b32 a141, 0
	v_accvgpr_write_b32 a140, 0
	v_accvgpr_write_b32 a139, 0
	v_accvgpr_write_b32 a138, 0
	v_accvgpr_write_b32 a137, 0
	v_accvgpr_write_b32 a136, 0
	v_accvgpr_write_b32 a135, 0
	v_accvgpr_write_b32 a134, 0
	v_accvgpr_write_b32 a133, 0
	v_accvgpr_write_b32 a132, 0
	v_accvgpr_write_b32 a131, 0
	v_accvgpr_write_b32 a130, 0
	v_accvgpr_write_b32 a129, 0
	v_accvgpr_write_b32 a128, 0
	v_accvgpr_write_b32 a159, 0
	v_accvgpr_write_b32 a158, 0
	v_accvgpr_write_b32 a157, 0
	v_accvgpr_write_b32 a156, 0
	v_accvgpr_write_b32 a155, 0
	v_accvgpr_write_b32 a154, 0
	v_accvgpr_write_b32 a153, 0
	v_accvgpr_write_b32 a152, 0
	v_accvgpr_write_b32 a151, 0
	v_accvgpr_write_b32 a150, 0
	v_accvgpr_write_b32 a149, 0
	v_accvgpr_write_b32 a148, 0
	v_accvgpr_write_b32 a147, 0
	v_accvgpr_write_b32 a146, 0
	v_accvgpr_write_b32 a145, 0
	v_accvgpr_write_b32 a144, 0
	v_accvgpr_write_b32 a175, 0
	v_accvgpr_write_b32 a174, 0
	v_accvgpr_write_b32 a173, 0
	v_accvgpr_write_b32 a172, 0
	v_accvgpr_write_b32 a171, 0
	v_accvgpr_write_b32 a170, 0
	v_accvgpr_write_b32 a169, 0
	v_accvgpr_write_b32 a168, 0
	v_accvgpr_write_b32 a167, 0
	v_accvgpr_write_b32 a166, 0
	v_accvgpr_write_b32 a165, 0
	v_accvgpr_write_b32 a164, 0
	v_accvgpr_write_b32 a163, 0
	v_accvgpr_write_b32 a162, 0
	v_accvgpr_write_b32 a161, 0
	v_accvgpr_write_b32 a160, 0
	v_accvgpr_write_b32 a191, 0
	v_accvgpr_write_b32 a190, 0
	v_accvgpr_write_b32 a189, 0
	v_accvgpr_write_b32 a188, 0
	v_accvgpr_write_b32 a187, 0
	v_accvgpr_write_b32 a186, 0
	v_accvgpr_write_b32 a185, 0
	v_accvgpr_write_b32 a184, 0
	v_accvgpr_write_b32 a183, 0
	v_accvgpr_write_b32 a182, 0
	v_accvgpr_write_b32 a181, 0
	v_accvgpr_write_b32 a180, 0
	v_accvgpr_write_b32 a179, 0
	v_accvgpr_write_b32 a178, 0
	v_accvgpr_write_b32 a177, 0
	v_accvgpr_write_b32 a176, 0
	v_accvgpr_mov_b32 a1, a193
	v_accvgpr_mov_b32 a2, a194
	v_accvgpr_mov_b32 a3, a195
	v_accvgpr_mov_b32 a4, a196
	v_accvgpr_mov_b32 a5, a197
	v_accvgpr_mov_b32 a6, a198
	v_accvgpr_mov_b32 a7, a199
	v_accvgpr_mov_b32 a8, a200
	v_accvgpr_mov_b32 a9, a201
	v_accvgpr_mov_b32 a10, a202
	v_accvgpr_mov_b32 a11, a203
	v_accvgpr_mov_b32 a12, a204
	v_accvgpr_mov_b32 a13, a205
	v_accvgpr_mov_b32 a14, a206
	v_accvgpr_mov_b32 a15, a207
	v_accvgpr_mov_b32 a17, a193
	v_accvgpr_mov_b32 a18, a194
	v_accvgpr_mov_b32 a19, a195
	v_accvgpr_mov_b32 a20, a196
	v_accvgpr_mov_b32 a21, a197
	v_accvgpr_mov_b32 a22, a198
	v_accvgpr_mov_b32 a23, a199
	v_accvgpr_mov_b32 a24, a200
	v_accvgpr_mov_b32 a25, a201
	v_accvgpr_mov_b32 a26, a202
	v_accvgpr_mov_b32 a27, a203
	v_accvgpr_mov_b32 a28, a204
	v_accvgpr_mov_b32 a29, a205
	v_accvgpr_mov_b32 a30, a206
	v_accvgpr_mov_b32 a31, a207
	v_accvgpr_mov_b32 a33, a193
	v_accvgpr_mov_b32 a34, a194
	v_accvgpr_mov_b32 a35, a195
	v_accvgpr_mov_b32 a36, a196
	v_accvgpr_mov_b32 a37, a197
	v_accvgpr_mov_b32 a38, a198
	v_accvgpr_mov_b32 a39, a199
	v_accvgpr_mov_b32 a40, a200
	v_accvgpr_mov_b32 a41, a201
	v_accvgpr_mov_b32 a42, a202
	v_accvgpr_mov_b32 a43, a203
	v_accvgpr_mov_b32 a44, a204
	v_accvgpr_mov_b32 a45, a205
	v_accvgpr_mov_b32 a46, a206
	v_accvgpr_mov_b32 a47, a207
	s_waitcnt vmcnt(13)
	ds_write_b128 v118, v[0:3] offset:0
	s_waitcnt vmcnt(12)
	ds_write_b128 v118, v[32:35] offset:0x1000
	s_waitcnt vmcnt(11)
	ds_write_b128 v118, v[36:39] offset:0x2000
	s_mov_b64 s[8:9], 0x58000
	s_mov_b64 s[10:11], 0xb0000
	s_waitcnt vmcnt(10)
	ds_write_b128 v118, v[40:43] offset:0x3000
	s_waitcnt vmcnt(9)
	ds_write_b128 v118, v[44:47] offset:0x4000
	s_waitcnt vmcnt(8)
	ds_write_b128 v118, v[48:51] offset:0x5000
	s_waitcnt vmcnt(7)
	ds_write_b128 v118, v[52:55] offset:0x6000
	s_waitcnt lgkmcnt(0)
	s_mov_b64 s[12:13], 0x108000
	v_mov_b32_e32 v0, 0
	v_lshl_add_u64 v[104:105], v[100:101], 0, s[8:9]
	s_mov_b32 s6, 0
	v_lshl_add_u64 v[106:107], v[100:101], 0, s[10:11]
	v_lshl_add_u64 v[108:109], v[100:101], 0, s[12:13]
	v_lshl_add_u64 v[110:111], v[102:103], 0, s[8:9]
	v_lshl_add_u64 v[112:113], v[102:103], 0, s[10:11]
	s_mov_b32 s5, -2
	v_mov_b32_e32 v1, v0
	v_mov_b32_e32 v2, v0
	v_mov_b32_e32 v3, v0
	v_mov_b32_e32 v194, v0
	v_mov_b32_e32 v195, v0
	v_mov_b32_e32 v196, v0
	v_mov_b32_e32 v197, v0
	v_mov_b32_e32 v32, v0
	v_mov_b32_e32 v33, v0
	v_mov_b32_e32 v34, v0
	v_mov_b32_e32 v35, v0
	s_barrier

.LBB0_140:
	s_abs_i32 s2, s0
	v_readlane_b32 s3, v254, 36
	s_mul_hi_u32 s3, s2, s3
	s_mul_i32 s4, s3, s6
	s_sub_i32 s2, s2, s4
	s_ashr_i32 s1, s0, 31
	s_add_i32 s4, s3, 1
	s_sub_i32 s5, s2, s6
	s_cmp_ge_u32 s2, s6
	s_cselect_b32 s3, s4, s3
	s_cselect_b32 s2, s5, s2
	s_add_i32 s4, s3, 1
	s_cmp_ge_u32 s2, s6
	s_cselect_b32 s2, s4, s3
	s_xor_b32 s2, s2, s1
	s_sub_i32 s2, s2, s1
	s_lshr_b32 s1, s1, 30
	s_add_i32 s1, s0, s1
	s_ashr_i32 s3, s1, 2
	s_abs_i32 s3, s3
	v_readlane_b32 s5, v254, 38
	s_mul_hi_u32 s5, s3, s5
	v_readlane_b32 s6, v254, 37
	s_mul_i32 s5, s5, s6
	s_and_b32 s4, s1, 0xfffffc
	s_sub_i32 s3, s3, s5
	s_sub_i32 s4, s0, s4
	s_ashr_i32 s1, s1, 31
	s_sub_i32 s5, s3, s6
	s_cmp_ge_u32 s3, s6
	s_cselect_b32 s3, s5, s3
	s_sub_i32 s5, s3, s6
	s_cmp_ge_u32 s3, s6
	s_cselect_b32 s3, s5, s3
	s_xor_b32 s3, s3, s1
	s_sub_i32 s1, s3, s1
	v_readlane_b32 s3, v254, 32
	s_add_i32 s3, s3, s1
	s_lshl_b32 s1, s2, 10
	s_lshl_b32 s2, s4, 8
	v_mov_b32_e32 v136, v208
	v_readlane_b32 s4, v253, 28
	s_add_i32 s1, s1, s2
	v_readlane_b32 s5, v253, 29
	v_ashrrev_i32_e32 v4, 2, v136
	s_lshl_b32 s2, s3, 7
	v_add_u32_e32 v2, s1, v4
	v_mov_b64_e32 v[0:1], s[4:5]
	s_movk_i32 s3, 0x1600
	v_mad_i64_i32 v[0:1], s[4:5], v2, s3, v[0:1]
	v_lshlrev_b32_e32 v5, 4, v136
	v_readlane_b32 s4, v253, 61
	s_addk_i32 s2, 0x3000
	v_and_b32_e32 v192, 48, v5
	v_readlane_b32 s5, v253, 62
	v_lshl_add_u64 v[68:69], v[0:1], 0, v[192:193]
	v_add_u32_e32 v2, s2, v4
	v_mov_b64_e32 v[0:1], s[4:5]
	v_mad_i64_i32 v[0:1], s[4:5], v2, s3, v[0:1]
	s_mov_b32 s3, 0x58000
	v_add_co_u32_e32 v8, vcc, s3, v68
	s_mov_b32 s4, 0xb0000
	s_nop 0
	v_addc_co_u32_e32 v9, vcc, 0, v69, vcc
	v_add_co_u32_e32 v12, vcc, s4, v68
	s_mov_b32 s4, 0x108000
	s_nop 0
	v_addc_co_u32_e32 v13, vcc, 0, v69, vcc
	v_bfe_u32 v6, v136, 5, 1
	v_lshrrev_b32_e32 v7, 2, v136
	v_bfe_u32 v10, v136, 2, 2
	v_add_co_u32_e32 v16, vcc, s4, v68
	v_lshlrev_b32_e32 v11, 1, v136
	v_bitop3_b32 v7, v6, v7, 3 bitop3:0x78
	v_bitop3_b32 v6, v6, v10, 2 bitop3:0x36
	v_ashrrev_i32_e32 v10, 1, v136
	v_lshl_add_u64 v[70:71], v[0:1], 0, v[192:193]
	v_addc_co_u32_e32 v17, vcc, 0, v69, vcc
	v_and_b32_e32 v137, 31, v136
	s_waitcnt vmcnt(7)
	v_and_b32_e32 v138, 0x80, v11
	v_and_b32_e32 v139, 0xffffffc0, v10
	v_add_co_u32_e32 v24, vcc, s3, v70
	v_or_b32_e32 v11, v138, v137
	v_or_b32_e32 v10, v139, v137
	global_load_dwordx4 v[0:3], v[68:69], off
	global_load_dwordx4 v[28:31], v[8:9], off
	global_load_dwordx4 v[32:35], v[12:13], off
	global_load_dwordx4 v[36:39], v[16:17], off
	global_load_dwordx4 v[40:43], v[70:71], off
	v_addc_co_u32_e32 v25, vcc, 0, v71, vcc
	v_bitop3_b32 v5, v5, 48, v136 bitop3:0x48
	v_lshlrev_b32_e32 v11, 6, v11
	v_lshlrev_b32_e32 v7, 4, v7
	v_lshlrev_b32_e32 v6, 4, v6
	v_lshl_add_u32 v10, v10, 6, v214
	global_load_dwordx4 v[44:47], v[24:25], off
	v_or_b32_e32 v80, v11, v7
	v_or_b32_e32 v81, v11, v6
	v_or_b32_e32 v82, v10, v7
	v_or_b32_e32 v83, v10, v6
	v_lshl_or_b32 v84, v4, 6, v5
	global_load_dwordx4 v[4:7], v[68:69], off offset:64
	s_nop 0
	global_load_dwordx4 v[8:11], v[8:9], off offset:64
	s_nop 0
	global_load_dwordx4 v[12:15], v[12:13], off offset:64
	s_nop 0
	global_load_dwordx4 v[16:19], v[16:17], off offset:64
	s_nop 0
	global_load_dwordx4 v[20:23], v[70:71], off offset:64
	s_nop 0
	global_load_dwordx4 v[24:27], v[24:25], off offset:64
	v_accvgpr_mov_b32 a193, a192
	v_accvgpr_mov_b32 a194, a192
	v_accvgpr_mov_b32 a195, a192
	v_accvgpr_mov_b32 a196, a192
	v_accvgpr_mov_b32 a197, a192
	v_accvgpr_mov_b32 a198, a192
	v_accvgpr_mov_b32 a199, a192
	v_accvgpr_mov_b32 a200, a192
	v_accvgpr_mov_b32 a201, a192
	v_accvgpr_mov_b32 a202, a192
	v_accvgpr_mov_b32 a203, a192
	v_accvgpr_mov_b32 a204, a192
	v_accvgpr_mov_b32 a205, a192
	v_accvgpr_mov_b32 a206, a192
	v_accvgpr_mov_b32 a207, a192
	v_accvgpr_mov_b32 a0, a192
	v_accvgpr_mov_b32 a16, a192
	v_accvgpr_write_b32 a47, 0
	v_accvgpr_write_b32 a46, 0
	v_accvgpr_write_b32 a45, 0
	v_accvgpr_write_b32 a44, 0
	v_accvgpr_write_b32 a43, 0
	v_accvgpr_write_b32 a42, 0
	v_accvgpr_write_b32 a41, 0
	v_accvgpr_write_b32 a40, 0
	v_accvgpr_write_b32 a39, 0
	v_accvgpr_write_b32 a38, 0
	v_accvgpr_write_b32 a37, 0
	v_accvgpr_write_b32 a36, 0
	v_accvgpr_write_b32 a35, 0
	v_accvgpr_write_b32 a34, 0
	v_accvgpr_write_b32 a33, 0
	v_accvgpr_write_b32 a32, 0
	v_accvgpr_write_b32 a63, 0
	v_accvgpr_write_b32 a62, 0
	v_accvgpr_write_b32 a61, 0
	v_accvgpr_write_b32 a60, 0
	v_accvgpr_write_b32 a59, 0
	v_accvgpr_write_b32 a58, 0
	v_accvgpr_write_b32 a57, 0
	v_accvgpr_write_b32 a56, 0
	v_accvgpr_write_b32 a55, 0
	v_accvgpr_write_b32 a54, 0
	v_accvgpr_write_b32 a53, 0
	v_accvgpr_write_b32 a52, 0
	v_accvgpr_write_b32 a51, 0
	v_accvgpr_write_b32 a50, 0
	v_accvgpr_write_b32 a49, 0
	v_accvgpr_write_b32 a48, 0
	v_accvgpr_write_b32 a79, 0
	v_accvgpr_write_b32 a78, 0
	v_accvgpr_write_b32 a77, 0
	v_accvgpr_write_b32 a76, 0
	v_accvgpr_write_b32 a75, 0
	v_accvgpr_write_b32 a74, 0
	v_accvgpr_write_b32 a73, 0
	v_accvgpr_write_b32 a72, 0
	v_accvgpr_write_b32 a71, 0
	v_accvgpr_write_b32 a70, 0
	v_accvgpr_write_b32 a69, 0
	v_accvgpr_write_b32 a68, 0
	v_accvgpr_write_b32 a67, 0
	v_accvgpr_write_b32 a66, 0
	v_accvgpr_write_b32 a65, 0
	v_accvgpr_write_b32 a64, 0
	v_accvgpr_write_b32 a95, 0
	v_accvgpr_write_b32 a94, 0
	v_accvgpr_write_b32 a93, 0
	v_accvgpr_write_b32 a92, 0
	v_accvgpr_write_b32 a91, 0
	v_accvgpr_write_b32 a90, 0
	v_accvgpr_write_b32 a89, 0
	v_accvgpr_write_b32 a88, 0
	v_accvgpr_write_b32 a87, 0
	v_accvgpr_write_b32 a86, 0
	v_accvgpr_write_b32 a85, 0
	v_accvgpr_write_b32 a84, 0
	v_accvgpr_write_b32 a83, 0
	v_accvgpr_write_b32 a82, 0
	v_accvgpr_write_b32 a81, 0
	v_accvgpr_write_b32 a80, 0
	v_accvgpr_write_b32 a111, 0
	v_accvgpr_write_b32 a110, 0
	v_accvgpr_write_b32 a109, 0
	v_accvgpr_write_b32 a108, 0
	v_accvgpr_write_b32 a107, 0
	v_accvgpr_write_b32 a106, 0
	v_accvgpr_write_b32 a105, 0
	v_accvgpr_write_b32 a104, 0
	v_accvgpr_write_b32 a103, 0
	v_accvgpr_write_b32 a102, 0
	v_accvgpr_write_b32 a101, 0
	v_accvgpr_write_b32 a100, 0
	v_accvgpr_write_b32 a99, 0
	v_accvgpr_write_b32 a98, 0
	v_accvgpr_write_b32 a97, 0
	v_accvgpr_write_b32 a96, 0
	v_accvgpr_write_b32 a127, 0
	v_accvgpr_write_b32 a126, 0
	v_accvgpr_write_b32 a125, 0
	v_accvgpr_write_b32 a124, 0
	v_accvgpr_write_b32 a123, 0
	v_accvgpr_write_b32 a122, 0
	v_accvgpr_write_b32 a121, 0
	v_accvgpr_write_b32 a120, 0
	v_accvgpr_write_b32 a119, 0
	v_accvgpr_write_b32 a118, 0
	v_accvgpr_write_b32 a117, 0
	v_accvgpr_write_b32 a116, 0
	v_accvgpr_write_b32 a115, 0
	v_accvgpr_write_b32 a114, 0
	v_accvgpr_write_b32 a113, 0
	v_accvgpr_write_b32 a112, 0
	v_accvgpr_mov_b32 a1, a193
	v_accvgpr_mov_b32 a2, a194
	v_accvgpr_mov_b32 a3, a195
	v_accvgpr_mov_b32 a4, a196
	v_accvgpr_mov_b32 a5, a197
	v_accvgpr_mov_b32 a6, a198
	v_accvgpr_mov_b32 a7, a199
	v_accvgpr_mov_b32 a8, a200
	v_accvgpr_mov_b32 a9, a201
	v_accvgpr_mov_b32 a10, a202
	v_accvgpr_mov_b32 a11, a203
	v_accvgpr_mov_b32 a12, a204
	v_accvgpr_mov_b32 a13, a205
	v_accvgpr_mov_b32 a14, a206
	v_accvgpr_mov_b32 a15, a207
	v_accvgpr_mov_b32 a17, a193
	v_accvgpr_mov_b32 a18, a194
	v_accvgpr_mov_b32 a19, a195
	v_accvgpr_mov_b32 a20, a196
	v_accvgpr_mov_b32 a21, a197
	v_accvgpr_mov_b32 a22, a198
	v_accvgpr_mov_b32 a23, a199
	v_accvgpr_mov_b32 a24, a200
	v_accvgpr_mov_b32 a25, a201
	v_accvgpr_mov_b32 a26, a202
	v_accvgpr_mov_b32 a27, a203
	v_accvgpr_mov_b32 a28, a204
	v_accvgpr_mov_b32 a29, a205
	v_accvgpr_mov_b32 a30, a206
	v_accvgpr_mov_b32 a31, a207
	s_waitcnt vmcnt(11)
	ds_write_b128 v84, v[0:3] offset:0
	s_waitcnt vmcnt(10)
	ds_write_b128 v84, v[28:31] offset:0x1000
	s_waitcnt vmcnt(9)
	ds_write_b128 v84, v[32:35] offset:0x2000
	s_mov_b64 s[8:9], 0xb0000
	s_mov_b64 s[6:7], 0x58000
	v_lshl_add_u64 v[74:75], v[68:69], 0, s[8:9]
	s_mov_b64 s[8:9], 0x108000
	v_mov_b32_e32 v0, 0
	s_waitcnt vmcnt(8)
	ds_write_b128 v84, v[36:39] offset:0x3000
	s_waitcnt vmcnt(7)
	ds_write_b128 v84, v[40:43] offset:0x4000
	s_waitcnt vmcnt(6)
	ds_write_b128 v84, v[44:47] offset:0x5000
	s_waitcnt lgkmcnt(0)
	v_lshl_add_u64 v[72:73], v[68:69], 0, s[6:7]
	s_mov_b32 s4, 0
	v_lshl_add_u64 v[76:77], v[68:69], 0, s[8:9]
	v_lshl_add_u64 v[78:79], v[70:71], 0, s[6:7]
	s_mov_b32 s3, -2
	v_mov_b32_e32 v1, v0
	v_mov_b32_e32 v2, v0
	v_mov_b32_e32 v3, v0
	v_mov_b32_e32 v28, v0
	v_mov_b32_e32 v29, v0
	v_mov_b32_e32 v30, v0
	v_mov_b32_e32 v31, v0
	v_mov_b32_e32 v32, v0
	v_mov_b32_e32 v33, v0
	v_mov_b32_e32 v34, v0
	v_mov_b32_e32 v35, v0
	v_mov_b32_e32 v36, v0
	v_mov_b32_e32 v37, v0
	v_mov_b32_e32 v38, v0
	v_mov_b32_e32 v39, v0
	s_barrier

.LBB0_150:
	s_nop 1
	v_accvgpr_read_b32 v142, a80
	v_accvgpr_read_b32 v139, a83
	v_accvgpr_read_b32 v141, a81
	v_accvgpr_read_b32 v137, a84
	v_mul_f32_e32 v116, 0xbfb8aa3b, v142
	v_mfma_f32_32x32x16_bf16 a[16:31], v[132:135], v[112:115], a[16:31]
	v_mul_f32_e32 v112, 0xbfb8aa3b, v139
	v_accvgpr_read_b32 v140, a82
	v_accvgpr_read_b32 v136, a85
	v_exp_f32_e32 v142, v116
	v_mul_f32_e32 v116, 0xbfb8aa3b, v141
	v_exp_f32_e32 v215, v112
	v_mul_f32_e32 v112, 0xbfb8aa3b, v137
	v_accvgpr_read_b32 v127, a86
	v_exp_f32_e32 v214, v116
	v_mul_f32_e32 v116, 0xbfb8aa3b, v140
	v_exp_f32_e32 v220, v112
	v_mul_f32_e32 v112, 0xbfb8aa3b, v136
	v_accvgpr_read_b32 v126, a87
	v_exp_f32_e32 v143, v116
	v_exp_f32_e32 v116, v112
	v_mul_f32_e32 v112, 0xbfb8aa3b, v127
	v_accvgpr_read_b32 v125, a88
	v_exp_f32_e32 v221, v112
	v_mul_f32_e32 v112, 0xbfb8aa3b, v126
	v_accvgpr_read_b32 v124, a89
	v_exp_f32_e32 v117, v112
	v_mul_f32_e32 v112, 0xbfb8aa3b, v125
	v_accvgpr_read_b32 v123, a90
	v_exp_f32_e32 v126, v112
	v_mul_f32_e32 v112, 0xbfb8aa3b, v124
	v_accvgpr_read_b32 v122, a91
	v_exp_f32_e32 v124, v112
	v_mul_f32_e32 v112, 0xbfb8aa3b, v123
	v_accvgpr_read_b32 v121, a92
	v_accvgpr_read_b32 v119, a94
	v_mfma_f32_32x32x16_bf16 a[32:47], v[132:135], v[80:83], a[32:47]
	v_accvgpr_read_b32 v80, a80
	v_exp_f32_e32 v127, v112
	v_mul_f32_e32 v112, 0xbfb8aa3b, v122
	v_accvgpr_read_b32 v120, a93
	v_accvgpr_read_b32 v82, a82
	v_exp_f32_e32 v125, v112
	v_mul_f32_e32 v112, 0xbfb8aa3b, v121
	v_mul_f32_e32 v113, 0xbfb8aa3b, v119
	v_pk_add_f32 v[118:119], v[142:143], 1.0 op_sel_hi:[1,0]
	v_exp_f32_e32 v114, v112
	v_mul_f32_e32 v112, 0xbfb8aa3b, v120
	v_rcp_f32_e32 v121, v119
	v_accvgpr_read_b32 v83, a83
	v_accvgpr_read_b32 v81, a81
	v_accvgpr_read_b32 v90, a90
	v_rcp_f32_e32 v136, v118
	v_mul_f32_e32 v137, v82, v121
	v_accvgpr_read_b32 v138, a95
	v_pk_add_f32 v[120:121], v[214:215], 1.0 op_sel_hi:[1,0]
	v_rcp_f32_e32 v123, v121
	v_mul_f32_e32 v136, v80, v136
	v_exp_f32_e32 v115, v113
	v_rcp_f32_e32 v119, v120
	v_mul_f32_e32 v139, v83, v123
	v_pk_add_f32 v[82:83], v[126:127], 1.0 op_sel_hi:[1,0]
	v_rcp_f32_e32 v122, v83
	v_mul_f32_e32 v113, 0xbfb8aa3b, v138
	v_mul_f32_e32 v138, v81, v119
	v_accvgpr_read_b32 v88, a88
	v_rcp_f32_e32 v119, v82
	v_mul_f32_e32 v141, v90, v122
	v_accvgpr_read_b32 v91, a91
	v_pk_add_f32 v[80:81], v[124:125], 1.0 op_sel_hi:[1,0]
	v_rcp_f32_e32 v120, v81
	v_mul_f32_e32 v140, v88, v119
	v_accvgpr_read_b32 v89, a89
	v_accvgpr_read_b32 v86, a86
	v_rcp_f32_e32 v90, v80
	v_mul_f32_e32 v143, v91, v120
	v_pk_add_f32 v[82:83], v[220:221], 1.0 op_sel_hi:[1,0]
	v_rcp_f32_e32 v118, v83
	v_mul_f32_e32 v142, v89, v90
	v_accvgpr_read_b32 v84, a84
	v_rcp_f32_e32 v89, v82
	v_mul_f32_e32 v215, v86, v118
	v_accvgpr_read_b32 v87, a87
	v_pk_add_f32 v[80:81], v[116:117], 1.0 op_sel_hi:[1,0]
	v_rcp_f32_e32 v90, v81
	v_mul_f32_e32 v214, v84, v89
	v_accvgpr_read_b32 v85, a85
	v_accvgpr_read_b32 v94, a94
	v_rcp_f32_e32 v86, v80
	v_mul_f32_e32 v221, v87, v90
	v_pk_add_f32 v[82:83], v[114:115], 1.0 op_sel_hi:[1,0]
	v_rcp_f32_e32 v88, v83
	v_mul_f32_e32 v220, v85, v86
	v_accvgpr_read_b32 v92, a92
	v_rcp_f32_e32 v85, v82
	v_mul_f32_e32 v223, v94, v88
	v_exp_f32_e32 v112, v112
	v_exp_f32_e32 v113, v113
	v_accvgpr_read_b32 v95, a95
	v_pk_add_f32 v[80:81], v[112:113], 1.0 op_sel_hi:[1,0]
	v_accvgpr_read_b32 v96, a96
	v_rcp_f32_e32 v87, v81
	v_accvgpr_read_b32 v98, a98
	v_mfma_f32_32x32x16_bf16 a[0:15], v[132:135], v[128:131], a[0:15]
	v_or_b32_e32 v129, s2, v161
	v_accvgpr_read_b32 v97, a97
	v_or_b32_e32 v128, s1, v162
	v_add_u32_e32 v133, v163, v129
	v_mov_b32_e32 v162, v96
	v_mov_b32_e32 v163, v98
	v_accvgpr_read_b32 v99, a99
	v_mul_f32_e32 v222, v92, v85
	v_pk_mul_f32 v[136:137], v[162:163], v[136:137]
	v_mov_b32_e32 v98, v97
	v_pk_mul_f32 v[96:97], v[98:99], v[138:139]
	v_and_b32_sdwa v99, v136, v218 dst_sel:DWORD dst_unused:UNUSED_PAD src0_sel:WORD_1 src1_sel:DWORD
	v_add3_u32 v99, v136, v99, s80
	v_cvt_pk_bf16_f32 v136, v137, v97
	v_and_b32_sdwa v137, v96, v218 dst_sel:DWORD dst_unused:UNUSED_PAD src0_sel:WORD_1 src1_sel:DWORD
	v_accvgpr_read_b32 v93, a93
	v_add3_u32 v96, v96, v137, s80
	v_accvgpr_read_b32 v104, a104
	v_accvgpr_read_b32 v106, a106
	v_and_b32_e32 v96, 0xffff0000, v96
	v_accvgpr_read_b32 v105, a105
	v_rcp_f32_e32 v85, v80
	v_or_b32_sdwa v137, v96, v99 dst_sel:DWORD dst_unused:UNUSED_PAD src0_sel:DWORD src1_sel:WORD_1
	v_mov_b32_e32 v96, v104
	v_mov_b32_e32 v97, v106
	v_accvgpr_read_b32 v107, a107
	v_pk_mul_f32 v[96:97], v[96:97], v[140:141]
	v_mov_b32_e32 v106, v105
	v_pk_mul_f32 v[98:99], v[106:107], v[142:143]
	v_cvt_pk_bf16_f32 v106, v97, v99
	v_cvt_pk_bf16_f32 v107, v96, v98
	v_accvgpr_read_b32 v100, a100
	v_accvgpr_read_b32 v102, a102
	v_accvgpr_read_b32 v101, a101
	v_mul_f32_e32 v227, v95, v87
	v_mov_b32_e32 v104, v100
	v_mov_b32_e32 v105, v102
	v_accvgpr_read_b32 v103, a103
	v_pk_mul_f32 v[104:105], v[104:105], v[214:215]
	v_mov_b32_e32 v102, v101
	v_pk_mul_f32 v[100:101], v[102:103], v[220:221]
	v_and_b32_sdwa v103, v104, v218 dst_sel:DWORD dst_unused:UNUSED_PAD src0_sel:WORD_1 src1_sel:DWORD
	v_add3_u32 v103, v104, v103, s80
	v_cvt_pk_bf16_f32 v104, v105, v101
	v_and_b32_sdwa v105, v100, v218 dst_sel:DWORD dst_unused:UNUSED_PAD src0_sel:WORD_1 src1_sel:DWORD
	v_add3_u32 v100, v100, v105, s80
	v_accvgpr_read_b32 v108, a108
	v_accvgpr_read_b32 v110, a110
	v_and_b32_e32 v100, 0xffff0000, v100
	v_accvgpr_read_b32 v109, a109
	v_or_b32_sdwa v105, v100, v103 dst_sel:DWORD dst_unused:UNUSED_PAD src0_sel:DWORD src1_sel:WORD_1
	v_mov_b32_e32 v100, v108
	v_mov_b32_e32 v101, v110
	v_accvgpr_read_b32 v111, a111
	v_mul_f32_e32 v226, v93, v85
	v_cmp_lt_i32_e32 vcc, v211, v210
	v_readlane_b32 s2, v253, 61
	v_pk_mul_f32 v[100:101], v[100:101], v[222:223]
	v_mov_b32_e32 v110, v109
	v_cndmask_b32_e32 v129, v209, v211, vcc
	v_readlane_b32 s3, v253, 62
	v_pk_mul_f32 v[102:103], v[110:111], v[226:227]
	v_cvt_pk_bf16_f32 v103, v101, v103
	v_cvt_pk_bf16_f32 v102, v100, v102
	v_lshlrev_b32_e32 v132, 2, v129
	v_ashrrev_i32_e32 v130, 1, v128
	v_mov_b64_e32 v[128:129], s[2:3]
	s_movk_i32 s1, 0x1600
	v_mad_i64_i32 v[134:135], s[2:3], v133, s1, v[128:129]
	v_and_b32_e32 v96, 63, v160
	v_cmp_gt_u32_e64 s[2:3], 32, v96
	s_nop 1
	v_cndmask_b32_e64 v96, v137, v107, s[2:3]
	v_cndmask_b32_e64 v97, v136, v106, s[2:3]
	ds_bpermute_b32 v138, v132, v97
	ds_bpermute_b32 v139, v132, v96
	v_cndmask_b32_e64 v100, v105, v102, s[2:3]
	v_cndmask_b32_e64 v101, v104, v103, s[2:3]
	ds_bpermute_b32 v108, v132, v101
	ds_bpermute_b32 v109, v132, v100
	v_ashrrev_i32_e32 v131, 31, v130
	v_lshlrev_b64 v[130:131], 1, v[130:131]
	v_lshl_add_u64 v[96:97], v[134:135], 0, v[130:131]
	v_and_b32_e32 v192, 32, v160
	v_lshl_add_u64 v[96:97], v[96:97], 0, v[192:193]
	s_waitcnt lgkmcnt(3)
	v_cndmask_b32_e64 v99, v138, v136, s[2:3]
	s_waitcnt lgkmcnt(2)
	v_cndmask_b32_e64 v98, v139, v137, s[2:3]
	v_cndmask_b32_e64 v101, v106, v138, s[2:3]
	v_cndmask_b32_e64 v100, v107, v139, s[2:3]
	v_accvgpr_read_b32 v225, a48
	global_store_dwordx4 v[96:97], v[98:101], off
	v_accvgpr_read_b32 v224, a49
	v_accvgpr_read_b32 v252, a50
	s_waitcnt lgkmcnt(1)
	v_cndmask_b32_e64 v99, v108, v104, s[2:3]
	s_waitcnt lgkmcnt(0)
	v_cndmask_b32_e64 v98, v109, v105, s[2:3]
	v_cndmask_b32_e64 v101, v103, v108, s[2:3]
	v_cndmask_b32_e64 v100, v102, v109, s[2:3]
	global_store_dwordx4 v[96:97], v[98:101], off offset:16
	v_accvgpr_read_b32 v127, a63
	v_accvgpr_read_b32 v114, a50
	v_mul_f32_e32 v98, 0xbfb8aa3b, v225
	v_exp_f32_e32 v104, v98
	v_mul_f32_e32 v98, 0xbfb8aa3b, v224
	v_exp_f32_e32 v106, v98
	v_mul_f32_e32 v98, 0xbfb8aa3b, v252
	v_exp_f32_e32 v105, v98
	v_accvgpr_read_b32 v112, a48
	v_accvgpr_read_b32 v251, a51
	v_mul_f32_e32 v98, 0xbfb8aa3b, v251
	v_pk_add_f32 v[104:105], v[104:105], 1.0 op_sel_hi:[1,0]
	v_exp_f32_e32 v107, v98
	v_rcp_f32_e32 v139, v105
	v_accvgpr_read_b32 v115, a51
	v_pk_add_f32 v[106:107], v[106:107], 1.0 op_sel_hi:[1,0]
	v_accvgpr_read_b32 v64, a112
	v_rcp_f32_e32 v142, v104
	v_mul_f32_e32 v105, v114, v139
	v_accvgpr_read_b32 v66, a114
	v_mul_f32_e32 v104, v112, v142
	v_rcp_f32_e32 v114, v107
	v_mov_b32_e32 v138, v64
	v_mov_b32_e32 v139, v66
	v_pk_mul_f32 v[104:105], v[138:139], v[104:105]
	v_accvgpr_read_b32 v113, a49
	v_rcp_f32_e32 v138, v106
	v_accvgpr_read_b32 v250, a52
	v_accvgpr_read_b32 v249, a53
	v_mul_f32_e32 v98, 0xbfb8aa3b, v250
	v_mul_f32_e32 v107, v115, v114
	v_accvgpr_read_b32 v248, a54
	v_exp_f32_e32 v108, v98
	v_mul_f32_e32 v98, 0xbfb8aa3b, v249
	v_accvgpr_read_b32 v247, a55
	v_exp_f32_e32 v102, v98
	v_mul_f32_e32 v98, 0xbfb8aa3b, v248
	v_accvgpr_read_b32 v246, a56
	v_exp_f32_e32 v109, v98
	v_mul_f32_e32 v98, 0xbfb8aa3b, v247
	v_accvgpr_read_b32 v245, a57
	v_exp_f32_e32 v103, v98
	v_mul_f32_e32 v98, 0xbfb8aa3b, v246
	v_accvgpr_read_b32 v244, a58
	v_exp_f32_e32 v110, v98
	v_mul_f32_e32 v98, 0xbfb8aa3b, v245
	v_accvgpr_read_b32 v65, a113
	v_exp_f32_e32 v134, v98
	v_mul_f32_e32 v98, 0xbfb8aa3b, v244
	v_accvgpr_read_b32 v67, a115
	v_exp_f32_e32 v111, v98
	v_mul_f32_e32 v106, v113, v138
	v_mov_b32_e32 v66, v65
	v_pk_mul_f32 v[64:65], v[66:67], v[106:107]
	v_and_b32_sdwa v67, v104, v218 dst_sel:DWORD dst_unused:UNUSED_PAD src0_sel:WORD_1 src1_sel:DWORD
	v_and_b32_sdwa v66, v105, v218 dst_sel:DWORD dst_unused:UNUSED_PAD src0_sel:WORD_1 src1_sel:DWORD
	v_add3_u32 v67, v104, v67, s80
	v_and_b32_sdwa v104, v65, v218 dst_sel:DWORD dst_unused:UNUSED_PAD src0_sel:WORD_1 src1_sel:DWORD
	v_add3_u32 v66, v105, v66, s80
	v_and_b32_sdwa v105, v64, v218 dst_sel:DWORD dst_unused:UNUSED_PAD src0_sel:WORD_1 src1_sel:DWORD
	v_add3_u32 v65, v65, v104, s80
	v_accvgpr_read_b32 v122, a58
	v_add3_u32 v104, v64, v105, s80
	v_and_b32_e32 v105, 0xffff0000, v65
	v_pk_add_f32 v[64:65], v[110:111], 1.0 op_sel_hi:[1,0]
	v_or_b32_sdwa v110, v105, v66 dst_sel:DWORD dst_unused:UNUSED_PAD src0_sel:DWORD src1_sel:WORD_1
	v_rcp_f32_e32 v107, v65
	v_and_b32_e32 v104, 0xffff0000, v104
	v_or_b32_sdwa v111, v104, v67 dst_sel:DWORD dst_unused:UNUSED_PAD src0_sel:DWORD src1_sel:WORD_1
	v_accvgpr_read_b32 v120, a56
	v_rcp_f32_e32 v105, v64
	v_mul_f32_e32 v65, v122, v107
	v_accvgpr_read_b32 v243, a59
	v_mul_f32_e32 v98, 0xbfb8aa3b, v243
	v_exp_f32_e32 v135, v98
	v_accvgpr_read_b32 v123, a59
	v_mul_f32_e32 v64, v120, v105
	v_pk_add_f32 v[66:67], v[134:135], 1.0 op_sel_hi:[1,0]
	v_accvgpr_read_b32 v72, a120
	v_rcp_f32_e32 v107, v67
	v_mov_b32_e32 v104, v72
	v_accvgpr_read_b32 v74, a122
	v_mov_b32_e32 v105, v74
	v_accvgpr_read_b32 v121, a57
	v_pk_mul_f32 v[64:65], v[104:105], v[64:65]
	v_rcp_f32_e32 v105, v66
	v_mul_f32_e32 v67, v123, v107
	v_accvgpr_read_b32 v73, a121
	v_accvgpr_read_b32 v75, a123
	v_mul_f32_e32 v66, v121, v105
	v_mov_b32_e32 v74, v73
	v_pk_mul_f32 v[66:67], v[74:75], v[66:67]
	v_cvt_pk_bf16_f32 v104, v65, v67
	v_cvt_pk_bf16_f32 v105, v64, v66
	v_accvgpr_read_b32 v118, a54
	v_pk_add_f32 v[72:73], v[108:109], 1.0 op_sel_hi:[1,0]
	v_rcp_f32_e32 v75, v73
	v_cndmask_b32_e64 v65, v110, v104, s[2:3]
	ds_bpermute_b32 v107, v132, v65
	v_accvgpr_read_b32 v116, a52
	s_waitcnt lgkmcnt(0)
	v_cndmask_b32_e64 v67, v107, v110, s[2:3]
	v_rcp_f32_e32 v110, v72
	v_mul_f32_e32 v73, v118, v75
	v_accvgpr_read_b32 v119, a55
	v_mul_f32_e32 v72, v116, v110
	v_pk_add_f32 v[74:75], v[102:103], 1.0 op_sel_hi:[1,0]
	v_accvgpr_read_b32 v68, a116
	v_rcp_f32_e32 v109, v75
	v_mov_b32_e32 v102, v68
	v_accvgpr_read_b32 v70, a118
	v_mov_b32_e32 v103, v70
	v_accvgpr_read_b32 v117, a53
	v_pk_mul_f32 v[72:73], v[102:103], v[72:73]
	v_rcp_f32_e32 v103, v74
	v_mul_f32_e32 v75, v119, v109
	v_accvgpr_read_b32 v242, a60
	v_accvgpr_read_b32 v240, a62
	v_accvgpr_read_b32 v69, a117
	v_mul_f32_e32 v98, 0xbfb8aa3b, v242
	v_mul_f32_e32 v99, 0xbfb8aa3b, v240
	v_accvgpr_read_b32 v71, a119
	v_exp_f32_e32 v100, v98
	v_exp_f32_e32 v101, v99
	v_mul_f32_e32 v74, v117, v103
	v_mov_b32_e32 v70, v69
	v_pk_mul_f32 v[68:69], v[70:71], v[74:75]
	v_and_b32_sdwa v71, v72, v218 dst_sel:DWORD dst_unused:UNUSED_PAD src0_sel:WORD_1 src1_sel:DWORD
	v_and_b32_sdwa v70, v73, v218 dst_sel:DWORD dst_unused:UNUSED_PAD src0_sel:WORD_1 src1_sel:DWORD
	v_add3_u32 v71, v72, v71, s80
	v_and_b32_sdwa v72, v69, v218 dst_sel:DWORD dst_unused:UNUSED_PAD src0_sel:WORD_1 src1_sel:DWORD
	v_add3_u32 v70, v73, v70, s80
	v_and_b32_sdwa v73, v68, v218 dst_sel:DWORD dst_unused:UNUSED_PAD src0_sel:WORD_1 src1_sel:DWORD
	v_add3_u32 v69, v69, v72, s80
	v_accvgpr_read_b32 v126, a62
	v_add3_u32 v72, v68, v73, s80
	v_and_b32_e32 v73, 0xffff0000, v69
	v_pk_add_f32 v[68:69], v[100:101], 1.0 op_sel_hi:[1,0]
	v_or_b32_sdwa v100, v73, v70 dst_sel:DWORD dst_unused:UNUSED_PAD src0_sel:DWORD src1_sel:WORD_1
	v_rcp_f32_e32 v75, v69
	v_and_b32_e32 v72, 0xffff0000, v72
	v_or_b32_sdwa v101, v72, v71 dst_sel:DWORD dst_unused:UNUSED_PAD src0_sel:DWORD src1_sel:WORD_1
	v_accvgpr_read_b32 v124, a60
	v_rcp_f32_e32 v73, v68
	v_mul_f32_e32 v69, v126, v75
	v_accvgpr_read_b32 v241, a61
	v_accvgpr_read_b32 v239, a63
	v_mul_f32_e32 v98, 0xbfb8aa3b, v241
	v_mul_f32_e32 v99, 0xbfb8aa3b, v239
	v_exp_f32_e32 v98, v98
	v_exp_f32_e32 v99, v99
	v_mul_f32_e32 v68, v124, v73
	v_pk_add_f32 v[70:71], v[98:99], 1.0 op_sel_hi:[1,0]
	v_accvgpr_read_b32 v76, a124
	v_rcp_f32_e32 v75, v71
	v_accvgpr_read_b32 v78, a126
	v_mov_b32_e32 v72, v76
	v_mov_b32_e32 v73, v78
	v_pk_mul_f32 v[68:69], v[72:73], v[68:69]
	v_accvgpr_read_b32 v125, a61
	v_rcp_f32_e32 v76, v70
	v_mul_f32_e32 v71, v127, v75
	v_accvgpr_read_b32 v77, a125
	v_accvgpr_read_b32 v79, a127
	v_mul_f32_e32 v70, v125, v76
	v_mov_b32_e32 v78, v77
	v_pk_mul_f32 v[70:71], v[78:79], v[70:71]
	v_cvt_pk_bf16_f32 v71, v69, v71
	v_cvt_pk_bf16_f32 v70, v68, v70
	v_cndmask_b32_e64 v64, v111, v105, s[2:3]
	ds_bpermute_b32 v106, v132, v64
	v_cndmask_b32_e64 v68, v101, v70, s[2:3]
	v_cndmask_b32_e64 v69, v100, v71, s[2:3]
	ds_bpermute_b32 v72, v132, v69
	ds_bpermute_b32 v73, v132, v68
	v_add_u32_e32 v136, 32, v133
	v_mad_i64_i32 v[136:137], s[4:5], v136, s1, v[128:129]
	v_lshl_add_u64 v[136:137], v[136:137], 0, v[130:131]
	v_lshl_add_u64 v[64:65], v[136:137], 0, v[192:193]
	s_waitcnt lgkmcnt(2)
	v_cndmask_b32_e64 v66, v106, v111, s[2:3]
	v_cndmask_b32_e64 v69, v104, v107, s[2:3]
	v_cndmask_b32_e64 v68, v105, v106, s[2:3]
	v_accvgpr_read_b32 v237, a65
	global_store_dwordx4 v[64:65], v[66:69], off
	v_accvgpr_read_b32 v238, a64
	v_accvgpr_read_b32 v236, a66
	s_waitcnt lgkmcnt(1)
	v_cndmask_b32_e64 v67, v72, v100, s[2:3]
	s_waitcnt lgkmcnt(0)
	v_cndmask_b32_e64 v66, v73, v101, s[2:3]
	v_cndmask_b32_e64 v69, v71, v72, s[2:3]
	v_cndmask_b32_e64 v68, v70, v73, s[2:3]
	global_store_dwordx4 v[64:65], v[66:69], off offset:16
	v_accvgpr_read_b32 v95, a79
	v_accvgpr_read_b32 v82, a66
	v_mul_f32_e32 v67, 0xbfb8aa3b, v237
	v_mul_f32_e32 v66, 0xbfb8aa3b, v238
	v_exp_f32_e32 v74, v67
	v_mul_f32_e32 v67, 0xbfb8aa3b, v236
	v_exp_f32_e32 v66, v66
	v_exp_f32_e32 v67, v67
	v_accvgpr_read_b32 v80, a64
	v_accvgpr_read_b32 v235, a67
	v_mul_f32_e32 v68, 0xbfb8aa3b, v235
	v_pk_add_f32 v[66:67], v[66:67], 1.0 op_sel_hi:[1,0]
	v_exp_f32_e32 v75, v68
	v_rcp_f32_e32 v103, v67
	v_accvgpr_read_b32 v83, a67
	v_pk_add_f32 v[74:75], v[74:75], 1.0 op_sel_hi:[1,0]
	v_accvgpr_read_b32 v48, a128
	v_rcp_f32_e32 v106, v66
	v_mul_f32_e32 v67, v82, v103
	v_accvgpr_read_b32 v50, a130
	v_mul_f32_e32 v66, v80, v106
	v_rcp_f32_e32 v82, v75
	v_mov_b32_e32 v102, v48
	v_mov_b32_e32 v103, v50
	v_pk_mul_f32 v[66:67], v[102:103], v[66:67]
	v_accvgpr_read_b32 v81, a65
	v_rcp_f32_e32 v102, v74
	v_accvgpr_read_b32 v234, a68
	v_accvgpr_read_b32 v233, a69
	v_mul_f32_e32 v68, 0xbfb8aa3b, v234
	v_mul_f32_e32 v75, v83, v82
	v_accvgpr_read_b32 v232, a70
	v_exp_f32_e32 v76, v68
	v_mul_f32_e32 v68, 0xbfb8aa3b, v233
	v_accvgpr_read_b32 v231, a71
	v_exp_f32_e32 v72, v68
	v_mul_f32_e32 v68, 0xbfb8aa3b, v232
	v_accvgpr_read_b32 v207, a72
	v_exp_f32_e32 v77, v68
	v_mul_f32_e32 v68, 0xbfb8aa3b, v231
	v_accvgpr_read_b32 v205, a73
	v_exp_f32_e32 v73, v68
	v_mul_f32_e32 v68, 0xbfb8aa3b, v207
	v_accvgpr_read_b32 v204, a74
	v_exp_f32_e32 v78, v68
	v_mul_f32_e32 v68, 0xbfb8aa3b, v205
	v_accvgpr_read_b32 v49, a129
	v_exp_f32_e32 v98, v68
	v_mul_f32_e32 v68, 0xbfb8aa3b, v204
	v_accvgpr_read_b32 v51, a131
	v_exp_f32_e32 v79, v68
	v_mul_f32_e32 v74, v81, v102
	v_mov_b32_e32 v50, v49
	v_pk_mul_f32 v[48:49], v[50:51], v[74:75]
	v_and_b32_sdwa v51, v66, v218 dst_sel:DWORD dst_unused:UNUSED_PAD src0_sel:WORD_1 src1_sel:DWORD
	v_and_b32_sdwa v50, v67, v218 dst_sel:DWORD dst_unused:UNUSED_PAD src0_sel:WORD_1 src1_sel:DWORD
	v_add3_u32 v51, v66, v51, s80
	v_and_b32_sdwa v66, v49, v218 dst_sel:DWORD dst_unused:UNUSED_PAD src0_sel:WORD_1 src1_sel:DWORD
	v_add3_u32 v50, v67, v50, s80
	v_and_b32_sdwa v67, v48, v218 dst_sel:DWORD dst_unused:UNUSED_PAD src0_sel:WORD_1 src1_sel:DWORD
	v_add3_u32 v49, v49, v66, s80
	v_accvgpr_read_b32 v90, a74
	v_add3_u32 v66, v48, v67, s80
	v_and_b32_e32 v67, 0xffff0000, v49
	v_pk_add_f32 v[48:49], v[78:79], 1.0 op_sel_hi:[1,0]
	v_or_b32_sdwa v78, v67, v50 dst_sel:DWORD dst_unused:UNUSED_PAD src0_sel:DWORD src1_sel:WORD_1
	v_rcp_f32_e32 v75, v49
	v_and_b32_e32 v66, 0xffff0000, v66
	v_or_b32_sdwa v79, v66, v51 dst_sel:DWORD dst_unused:UNUSED_PAD src0_sel:DWORD src1_sel:WORD_1
	v_accvgpr_read_b32 v88, a72
	v_rcp_f32_e32 v67, v48
	v_mul_f32_e32 v49, v90, v75
	v_accvgpr_read_b32 v203, a75
	v_mul_f32_e32 v68, 0xbfb8aa3b, v203
	v_exp_f32_e32 v99, v68
	v_accvgpr_read_b32 v91, a75
	v_mul_f32_e32 v48, v88, v67
	v_pk_add_f32 v[50:51], v[98:99], 1.0 op_sel_hi:[1,0]
	v_accvgpr_read_b32 v56, a136
	v_rcp_f32_e32 v75, v51
	v_mov_b32_e32 v66, v56
	v_accvgpr_read_b32 v58, a138
	v_mov_b32_e32 v67, v58
	v_accvgpr_read_b32 v89, a73
	v_pk_mul_f32 v[48:49], v[66:67], v[48:49]
	v_rcp_f32_e32 v67, v50
	v_mul_f32_e32 v51, v91, v75
	v_accvgpr_read_b32 v57, a137
	v_accvgpr_read_b32 v59, a139
	v_mul_f32_e32 v50, v89, v67
	v_mov_b32_e32 v58, v57
	v_pk_mul_f32 v[50:51], v[58:59], v[50:51]
	v_cvt_pk_bf16_f32 v74, v49, v51
	v_cvt_pk_bf16_f32 v75, v48, v50
	v_accvgpr_read_b32 v86, a70
	v_pk_add_f32 v[50:51], v[76:77], 1.0 op_sel_hi:[1,0]
	v_accvgpr_read_b32 v84, a68
	v_rcp_f32_e32 v57, v51
	v_accvgpr_read_b32 v87, a71
	v_accvgpr_read_b32 v52, a132
	v_accvgpr_read_b32 v54, a134
	v_rcp_f32_e32 v76, v50
	v_mul_f32_e32 v51, v86, v57
	v_accvgpr_read_b32 v85, a69
	v_mul_f32_e32 v50, v84, v76
	v_pk_add_f32 v[56:57], v[72:73], 1.0 op_sel_hi:[1,0]
	v_mov_b32_e32 v58, v52
	v_rcp_f32_e32 v73, v57
	v_mov_b32_e32 v59, v54
	v_pk_mul_f32 v[50:51], v[58:59], v[50:51]
	v_accvgpr_read_b32 v201, a76
	v_rcp_f32_e32 v59, v56
	v_mul_f32_e32 v57, v87, v73
	v_accvgpr_read_b32 v199, a78
	v_accvgpr_read_b32 v53, a133
	v_mul_f32_e32 v68, 0xbfb8aa3b, v201
	v_mul_f32_e32 v69, 0xbfb8aa3b, v199
	v_accvgpr_read_b32 v55, a135
	v_exp_f32_e32 v70, v68
	v_exp_f32_e32 v71, v69
	v_mul_f32_e32 v56, v85, v59
	v_mov_b32_e32 v54, v53
	v_pk_mul_f32 v[52:53], v[54:55], v[56:57]
	v_cvt_pk_bf16_f32 v59, v50, v52
	v_cvt_pk_bf16_f32 v58, v51, v53
	v_accvgpr_read_b32 v94, a78
	v_pk_add_f32 v[50:51], v[70:71], 1.0 op_sel_hi:[1,0]
	v_rcp_f32_e32 v57, v51
	v_accvgpr_read_b32 v92, a76
	v_rcp_f32_e32 v55, v50
	v_mul_f32_e32 v51, v94, v57
	v_accvgpr_read_b32 v200, a77
	v_accvgpr_read_b32 v198, a79
	v_mul_f32_e32 v68, 0xbfb8aa3b, v200
	v_mul_f32_e32 v69, 0xbfb8aa3b, v198
	v_exp_f32_e32 v68, v68
	v_exp_f32_e32 v69, v69
	v_mul_f32_e32 v50, v92, v55
	v_pk_add_f32 v[52:53], v[68:69], 1.0 op_sel_hi:[1,0]
	v_accvgpr_read_b32 v60, a140
	v_rcp_f32_e32 v57, v53
	v_accvgpr_read_b32 v62, a142
	v_mov_b32_e32 v54, v60
	v_mov_b32_e32 v55, v62
	v_pk_mul_f32 v[50:51], v[54:55], v[50:51]
	v_accvgpr_read_b32 v93, a77
	v_rcp_f32_e32 v60, v52
	v_mul_f32_e32 v53, v95, v57
	v_accvgpr_read_b32 v61, a141
	v_accvgpr_read_b32 v63, a143
	v_mul_f32_e32 v52, v93, v60
	v_mov_b32_e32 v62, v61
	v_cndmask_b32_e64 v49, v78, v74, s[2:3]
	v_pk_mul_f32 v[52:53], v[62:63], v[52:53]
	v_cvt_pk_bf16_f32 v53, v51, v53
	ds_bpermute_b32 v81, v132, v49
	v_cndmask_b32_e64 v48, v79, v75, s[2:3]
	v_cvt_pk_bf16_f32 v52, v50, v52
	ds_bpermute_b32 v80, v132, v48
	v_accvgpr_read_b32 v197, a144
	v_accvgpr_read_b32 v196, a145
	v_cndmask_b32_e64 v51, v58, v53, s[2:3]
	v_mul_f32_e32 v68, 0xbfb8aa3b, v197
	v_accvgpr_read_b32 v195, a146
	ds_bpermute_b32 v54, v132, v51
	s_waitcnt lgkmcnt(2)
	v_cndmask_b32_e64 v51, v74, v81, s[2:3]
	v_exp_f32_e32 v74, v68
	v_mul_f32_e32 v68, 0xbfb8aa3b, v196
	v_cndmask_b32_e64 v50, v59, v52, s[2:3]
	v_exp_f32_e32 v76, v68
	v_mul_f32_e32 v68, 0xbfb8aa3b, v195
	ds_bpermute_b32 v55, v132, v50
	s_waitcnt lgkmcnt(2)
	v_cndmask_b32_e64 v50, v75, v80, s[2:3]
	v_exp_f32_e32 v75, v68
	v_accvgpr_read_b32 v32, a144
	v_accvgpr_read_b32 v34, a146
	v_accvgpr_read_b32 v194, a147
	v_pk_add_f32 v[74:75], v[74:75], 1.0 op_sel_hi:[1,0]
	v_mul_f32_e32 v68, 0xbfb8aa3b, v194
	v_rcp_f32_e32 v84, v75
	v_exp_f32_e32 v77, v68
	v_add_u32_e32 v100, 64, v133
	v_accvgpr_read_b32 v35, a147
	v_rcp_f32_e32 v88, v74
	v_mul_f32_e32 v75, v34, v84
	v_mad_i64_i32 v[100:101], s[4:5], v100, s1, v[128:129]
	v_pk_add_f32 v[76:77], v[76:77], 1.0 op_sel_hi:[1,0]
	v_lshl_add_u64 v[100:101], v[100:101], 0, v[130:131]
	v_mul_f32_e32 v74, v32, v88
	v_lshl_add_u64 v[66:67], v[100:101], 0, v[192:193]
	v_cndmask_b32_e64 v49, v81, v78, s[2:3]
	v_cndmask_b32_e64 v48, v80, v79, s[2:3]
	v_rcp_f32_e32 v34, v77
	global_store_dwordx4 v[66:67], v[48:51], off
	v_accvgpr_read_b32 v33, a145
	v_accvgpr_read_b32 v191, a148
	s_waitcnt lgkmcnt(1)
	v_cndmask_b32_e64 v49, v54, v58, s[2:3]
	s_waitcnt lgkmcnt(0)
	v_cndmask_b32_e64 v48, v55, v59, s[2:3]
	v_cndmask_b32_e64 v51, v53, v54, s[2:3]
	v_cndmask_b32_e64 v50, v52, v55, s[2:3]
	global_store_dwordx4 v[66:67], v[48:51], off offset:16
	v_accvgpr_read_b32 v63, a47
	v_accvgpr_read_b32 v190, a149
	v_accvgpr_read_b32 v48, a32
	v_mov_b32_e32 v84, v48
	v_accvgpr_read_b32 v50, a34
	v_mov_b32_e32 v85, v50
	v_rcp_f32_e32 v69, v76
	v_mul_f32_e32 v68, 0xbfb8aa3b, v191
	v_mul_f32_e32 v35, v35, v34
	v_accvgpr_read_b32 v189, a150
	v_exp_f32_e32 v78, v68
	v_mul_f32_e32 v68, 0xbfb8aa3b, v190
	v_accvgpr_read_b32 v188, a151
	v_exp_f32_e32 v72, v68
	v_mul_f32_e32 v68, 0xbfb8aa3b, v189
	v_accvgpr_read_b32 v187, a152
	v_exp_f32_e32 v79, v68
	v_mul_f32_e32 v68, 0xbfb8aa3b, v188
	v_accvgpr_read_b32 v186, a153
	v_exp_f32_e32 v73, v68
	v_mul_f32_e32 v68, 0xbfb8aa3b, v187
	v_accvgpr_read_b32 v185, a154
	v_exp_f32_e32 v80, v68
	v_mul_f32_e32 v68, 0xbfb8aa3b, v186
	v_accvgpr_read_b32 v49, a33
	v_exp_f32_e32 v82, v68
	v_mul_f32_e32 v68, 0xbfb8aa3b, v185
	v_accvgpr_read_b32 v51, a35
	v_exp_f32_e32 v81, v68
	v_mul_f32_e32 v34, v33, v69
	v_mov_b32_e32 v50, v49
	v_pk_mul_f32 v[32:33], v[34:35], v[50:51]
	v_accvgpr_read_b32 v42, a154
	v_and_b32_sdwa v48, v33, v218 dst_sel:DWORD dst_unused:UNUSED_PAD src0_sel:WORD_1 src1_sel:DWORD
	v_and_b32_sdwa v49, v32, v218 dst_sel:DWORD dst_unused:UNUSED_PAD src0_sel:WORD_1 src1_sel:DWORD
	v_add3_u32 v33, v33, v48, s80
	v_add3_u32 v48, v32, v49, s80
	v_and_b32_e32 v49, 0xffff0000, v33
	v_pk_add_f32 v[32:33], v[80:81], 1.0 op_sel_hi:[1,0]
	v_pk_mul_f32 v[74:75], v[74:75], v[84:85]
	v_rcp_f32_e32 v51, v33
	v_and_b32_sdwa v34, v75, v218 dst_sel:DWORD dst_unused:UNUSED_PAD src0_sel:WORD_1 src1_sel:DWORD
	v_and_b32_sdwa v35, v74, v218 dst_sel:DWORD dst_unused:UNUSED_PAD src0_sel:WORD_1 src1_sel:DWORD
	v_add3_u32 v34, v75, v34, s80
	v_add3_u32 v35, v74, v35, s80
	v_or_b32_sdwa v74, v49, v34 dst_sel:DWORD dst_unused:UNUSED_PAD src0_sel:DWORD src1_sel:WORD_1
	v_and_b32_e32 v48, 0xffff0000, v48
	v_or_b32_sdwa v75, v48, v35 dst_sel:DWORD dst_unused:UNUSED_PAD src0_sel:DWORD src1_sel:WORD_1
	v_accvgpr_read_b32 v40, a152
	v_rcp_f32_e32 v49, v32
	v_mul_f32_e32 v33, v42, v51
	v_accvgpr_read_b32 v184, a155
	v_mul_f32_e32 v68, 0xbfb8aa3b, v184
	v_exp_f32_e32 v83, v68
	v_accvgpr_read_b32 v43, a155
	v_mul_f32_e32 v32, v40, v49
	v_pk_add_f32 v[34:35], v[82:83], 1.0 op_sel_hi:[1,0]
	v_accvgpr_read_b32 v58, a42
	v_rcp_f32_e32 v42, v35
	v_accvgpr_read_b32 v56, a40
	v_mov_b32_e32 v48, v56
	v_mov_b32_e32 v49, v58
	v_pk_mul_f32 v[32:33], v[32:33], v[48:49]
	v_accvgpr_read_b32 v41, a153
	v_rcp_f32_e32 v50, v34
	v_mul_f32_e32 v35, v43, v42
	v_accvgpr_read_b32 v57, a41
	v_accvgpr_read_b32 v59, a43
	v_mul_f32_e32 v34, v41, v50
	v_mov_b32_e32 v58, v57
	v_pk_mul_f32 v[34:35], v[34:35], v[58:59]
	v_cvt_pk_bf16_f32 v48, v33, v35
	v_cvt_pk_bf16_f32 v49, v32, v34
	v_accvgpr_read_b32 v38, a150
	v_pk_add_f32 v[34:35], v[78:79], 1.0 op_sel_hi:[1,0]
	v_accvgpr_read_b32 v36, a148
	v_rcp_f32_e32 v41, v35
	v_accvgpr_read_b32 v39, a151
	v_accvgpr_read_b32 v54, a38
	v_accvgpr_read_b32 v52, a36
	v_rcp_f32_e32 v56, v34
	v_mul_f32_e32 v35, v38, v41
	v_mov_b32_e32 v43, v54
	v_pk_add_f32 v[40:41], v[72:73], 1.0 op_sel_hi:[1,0]
	v_mul_f32_e32 v34, v36, v56
	v_rcp_f32_e32 v38, v41
	v_mov_b32_e32 v42, v52
	v_pk_mul_f32 v[34:35], v[34:35], v[42:43]
	v_accvgpr_read_b32 v37, a149
	v_rcp_f32_e32 v52, v40
	v_mul_f32_e32 v39, v39, v38
	v_accvgpr_read_b32 v183, a156
	v_accvgpr_read_b32 v181, a158
	v_accvgpr_read_b32 v53, a37
	v_mul_f32_e32 v68, 0xbfb8aa3b, v183
	v_mul_f32_e32 v71, 0xbfb8aa3b, v181
	v_accvgpr_read_b32 v55, a39
	v_exp_f32_e32 v70, v68
	v_exp_f32_e32 v71, v71
	v_mul_f32_e32 v38, v37, v52
	v_mov_b32_e32 v54, v53
	v_pk_mul_f32 v[36:37], v[38:39], v[54:55]
	v_cvt_pk_bf16_f32 v43, v34, v36
	v_cvt_pk_bf16_f32 v42, v35, v37
	v_accvgpr_read_b32 v46, a158
	v_pk_add_f32 v[34:35], v[70:71], 1.0 op_sel_hi:[1,0]
	v_rcp_f32_e32 v41, v35
	v_accvgpr_read_b32 v44, a156
	v_rcp_f32_e32 v39, v34
	v_mul_f32_e32 v35, v46, v41
	v_accvgpr_read_b32 v182, a157
	v_accvgpr_read_b32 v180, a159
	v_mul_f32_e32 v68, 0xbfb8aa3b, v182
	v_mul_f32_e32 v86, 0xbfb8aa3b, v180
	v_exp_f32_e32 v68, v68
	v_exp_f32_e32 v69, v86
	v_accvgpr_read_b32 v47, a159
	v_mul_f32_e32 v34, v44, v39
	v_pk_add_f32 v[36:37], v[68:69], 1.0 op_sel_hi:[1,0]
	v_accvgpr_read_b32 v62, a46
	v_rcp_f32_e32 v41, v37
	v_accvgpr_read_b32 v60, a44
	v_mov_b32_e32 v38, v60
	v_mov_b32_e32 v39, v62
	v_pk_mul_f32 v[34:35], v[34:35], v[38:39]
	v_accvgpr_read_b32 v45, a157
	v_rcp_f32_e32 v44, v36
	v_mul_f32_e32 v37, v47, v41
	v_accvgpr_read_b32 v61, a45
	v_mul_f32_e32 v36, v45, v44
	v_mov_b32_e32 v62, v61
	v_cndmask_b32_e64 v33, v74, v48, s[2:3]
	v_pk_mul_f32 v[36:37], v[36:37], v[62:63]
	v_cvt_pk_bf16_f32 v37, v35, v37
	ds_bpermute_b32 v51, v132, v33
	v_accvgpr_read_b32 v179, a160
	v_cndmask_b32_e64 v35, v42, v37, s[2:3]
	v_accvgpr_read_b32 v178, a161
	ds_bpermute_b32 v38, v132, v35
	s_waitcnt lgkmcnt(1)
	v_cndmask_b32_e64 v35, v48, v51, s[2:3]
	v_mul_f32_e32 v48, 0xbfb8aa3b, v179
	v_accvgpr_read_b32 v177, a162
	v_exp_f32_e32 v54, v48
	v_mul_f32_e32 v48, 0xbfb8aa3b, v178
	v_cndmask_b32_e64 v32, v75, v49, s[2:3]
	v_cvt_pk_bf16_f32 v36, v34, v36
	v_exp_f32_e32 v56, v48
	v_mul_f32_e32 v48, 0xbfb8aa3b, v177
	ds_bpermute_b32 v50, v132, v32
	v_exp_f32_e32 v55, v48
	s_waitcnt vmcnt(9)
	v_accvgpr_read_b32 v16, a160
	v_accvgpr_read_b32 v18, a162
	v_cndmask_b32_e64 v34, v43, v36, s[2:3]
	v_pk_add_f32 v[54:55], v[54:55], 1.0 op_sel_hi:[1,0]
	ds_bpermute_b32 v39, v132, v34
	s_waitcnt lgkmcnt(1)
	v_cndmask_b32_e64 v34, v49, v50, s[2:3]
	v_rcp_f32_e32 v68, v55
	v_accvgpr_read_b32 v176, a163
	v_mul_f32_e32 v48, 0xbfb8aa3b, v176
	v_exp_f32_e32 v57, v48
	v_rcp_f32_e32 v72, v54
	v_mul_f32_e32 v55, v18, v68
	v_accvgpr_read_b32 v19, a163
	v_pk_add_f32 v[56:57], v[56:57], 1.0 op_sel_hi:[1,0]
	v_mul_f32_e32 v54, v16, v72
	v_cndmask_b32_e64 v33, v51, v74, s[2:3]
	v_cndmask_b32_e64 v32, v50, v75, s[2:3]
	v_rcp_f32_e32 v18, v57
	global_store_dwordx4 v[96:97], v[32:35], off offset:64
	v_accvgpr_read_b32 v17, a161
	v_accvgpr_read_b32 v175, a164
	v_cndmask_b32_e64 v33, v38, v42, s[2:3]
	s_waitcnt lgkmcnt(0)
	v_cndmask_b32_e64 v32, v39, v43, s[2:3]
	v_cndmask_b32_e64 v35, v37, v38, s[2:3]
	v_cndmask_b32_e64 v34, v36, v39, s[2:3]
	global_store_dwordx4 v[96:97], v[32:35], off offset:80
	v_accvgpr_read_b32 v47, a31
	v_accvgpr_read_b32 v174, a165
	v_accvgpr_read_b32 v32, a16
	v_mov_b32_e32 v68, v32
	v_accvgpr_read_b32 v34, a18
	v_mov_b32_e32 v69, v34
	v_rcp_f32_e32 v49, v56
	v_mul_f32_e32 v48, 0xbfb8aa3b, v175
	v_mul_f32_e32 v19, v19, v18
	v_accvgpr_read_b32 v173, a166
	v_exp_f32_e32 v58, v48
	v_mul_f32_e32 v48, 0xbfb8aa3b, v174
	v_accvgpr_read_b32 v172, a167
	v_exp_f32_e32 v52, v48
	v_mul_f32_e32 v48, 0xbfb8aa3b, v173
	v_accvgpr_read_b32 v171, a168
	v_exp_f32_e32 v59, v48
	v_mul_f32_e32 v48, 0xbfb8aa3b, v172
	v_accvgpr_read_b32 v170, a169
	v_exp_f32_e32 v53, v48
	v_mul_f32_e32 v48, 0xbfb8aa3b, v171
	v_accvgpr_read_b32 v169, a170
	v_exp_f32_e32 v60, v48
	v_mul_f32_e32 v48, 0xbfb8aa3b, v170
	v_accvgpr_read_b32 v33, a17
	v_exp_f32_e32 v62, v48
	v_mul_f32_e32 v48, 0xbfb8aa3b, v169
	v_accvgpr_read_b32 v35, a19
	v_exp_f32_e32 v61, v48
	v_mul_f32_e32 v18, v17, v49
	v_mov_b32_e32 v34, v33
	v_pk_mul_f32 v[16:17], v[18:19], v[34:35]
	v_accvgpr_read_b32 v26, a170
	v_and_b32_sdwa v32, v17, v218 dst_sel:DWORD dst_unused:UNUSED_PAD src0_sel:WORD_1 src1_sel:DWORD
	v_and_b32_sdwa v33, v16, v218 dst_sel:DWORD dst_unused:UNUSED_PAD src0_sel:WORD_1 src1_sel:DWORD
	v_add3_u32 v17, v17, v32, s80
	v_add3_u32 v32, v16, v33, s80
	v_and_b32_e32 v33, 0xffff0000, v17
	v_pk_add_f32 v[16:17], v[60:61], 1.0 op_sel_hi:[1,0]
	v_pk_mul_f32 v[54:55], v[54:55], v[68:69]
	v_rcp_f32_e32 v35, v17
	v_and_b32_sdwa v18, v55, v218 dst_sel:DWORD dst_unused:UNUSED_PAD src0_sel:WORD_1 src1_sel:DWORD
	v_and_b32_sdwa v19, v54, v218 dst_sel:DWORD dst_unused:UNUSED_PAD src0_sel:WORD_1 src1_sel:DWORD
	v_add3_u32 v18, v55, v18, s80
	v_add3_u32 v19, v54, v19, s80
	v_or_b32_sdwa v54, v33, v18 dst_sel:DWORD dst_unused:UNUSED_PAD src0_sel:DWORD src1_sel:WORD_1
	v_and_b32_e32 v32, 0xffff0000, v32
	v_or_b32_sdwa v55, v32, v19 dst_sel:DWORD dst_unused:UNUSED_PAD src0_sel:DWORD src1_sel:WORD_1
	v_accvgpr_read_b32 v24, a168
	v_rcp_f32_e32 v33, v16
	v_mul_f32_e32 v17, v26, v35
	v_accvgpr_read_b32 v168, a171
	v_mul_f32_e32 v48, 0xbfb8aa3b, v168
	v_exp_f32_e32 v63, v48
	v_accvgpr_read_b32 v27, a171
	v_mul_f32_e32 v16, v24, v33
	v_pk_add_f32 v[18:19], v[62:63], 1.0 op_sel_hi:[1,0]
	v_accvgpr_read_b32 v42, a26
	v_rcp_f32_e32 v26, v19
	v_accvgpr_read_b32 v40, a24
	v_mov_b32_e32 v32, v40
	v_mov_b32_e32 v33, v42
	v_pk_mul_f32 v[16:17], v[16:17], v[32:33]
	v_accvgpr_read_b32 v25, a169
	v_rcp_f32_e32 v34, v18
	v_mul_f32_e32 v19, v27, v26
	v_accvgpr_read_b32 v41, a25
	v_accvgpr_read_b32 v43, a27
	v_mul_f32_e32 v18, v25, v34
	v_mov_b32_e32 v42, v41
	v_pk_mul_f32 v[18:19], v[18:19], v[42:43]
	v_cvt_pk_bf16_f32 v32, v17, v19
	v_cvt_pk_bf16_f32 v33, v16, v18
	v_accvgpr_read_b32 v22, a166
	v_pk_add_f32 v[18:19], v[58:59], 1.0 op_sel_hi:[1,0]
	v_accvgpr_read_b32 v20, a164
	v_rcp_f32_e32 v25, v19
	v_accvgpr_read_b32 v23, a167
	v_accvgpr_read_b32 v38, a22
	v_accvgpr_read_b32 v36, a20
	v_rcp_f32_e32 v40, v18
	v_mul_f32_e32 v19, v22, v25
	v_mov_b32_e32 v27, v38
	v_pk_add_f32 v[24:25], v[52:53], 1.0 op_sel_hi:[1,0]
	v_mul_f32_e32 v18, v20, v40
	v_rcp_f32_e32 v22, v25
	v_mov_b32_e32 v26, v36
	v_pk_mul_f32 v[18:19], v[18:19], v[26:27]
	v_accvgpr_read_b32 v21, a165
	v_rcp_f32_e32 v36, v24
	v_mul_f32_e32 v23, v23, v22
	v_accvgpr_read_b32 v167, a172
	v_accvgpr_read_b32 v165, a174
	v_accvgpr_read_b32 v37, a21
	v_mul_f32_e32 v48, 0xbfb8aa3b, v167
	v_mul_f32_e32 v51, 0xbfb8aa3b, v165
	v_accvgpr_read_b32 v39, a23
	v_exp_f32_e32 v50, v48
	v_exp_f32_e32 v51, v51
	v_mul_f32_e32 v22, v21, v36
	v_mov_b32_e32 v38, v37
	v_pk_mul_f32 v[20:21], v[22:23], v[38:39]
	v_cvt_pk_bf16_f32 v27, v18, v20
	v_cvt_pk_bf16_f32 v26, v19, v21
	v_accvgpr_read_b32 v30, a174
	v_pk_add_f32 v[18:19], v[50:51], 1.0 op_sel_hi:[1,0]
	v_rcp_f32_e32 v25, v19
	v_accvgpr_read_b32 v28, a172
	v_rcp_f32_e32 v23, v18
	v_mul_f32_e32 v19, v30, v25
	v_accvgpr_read_b32 v166, a173
	v_accvgpr_read_b32 v164, a175
	v_mul_f32_e32 v48, 0xbfb8aa3b, v166
	v_mul_f32_e32 v70, 0xbfb8aa3b, v164
	v_exp_f32_e32 v48, v48
	v_exp_f32_e32 v49, v70
	v_accvgpr_read_b32 v31, a175
	v_mul_f32_e32 v18, v28, v23
	v_pk_add_f32 v[20:21], v[48:49], 1.0 op_sel_hi:[1,0]
	v_accvgpr_read_b32 v46, a30
	v_rcp_f32_e32 v25, v21
	v_accvgpr_read_b32 v44, a28
	v_mov_b32_e32 v22, v44
	v_mov_b32_e32 v23, v46
	v_pk_mul_f32 v[18:19], v[18:19], v[22:23]
	v_accvgpr_read_b32 v29, a173
	v_rcp_f32_e32 v28, v20
	v_mul_f32_e32 v21, v31, v25
	v_accvgpr_read_b32 v45, a29
	v_mul_f32_e32 v20, v29, v28
	v_mov_b32_e32 v46, v45
	v_cndmask_b32_e64 v17, v54, v32, s[2:3]
	v_pk_mul_f32 v[20:21], v[20:21], v[46:47]
	v_cvt_pk_bf16_f32 v21, v19, v21
	ds_bpermute_b32 v35, v132, v17
	v_accvgpr_read_b32 v159, a176
	v_cndmask_b32_e64 v19, v26, v21, s[2:3]
	v_accvgpr_read_b32 v158, a177
	ds_bpermute_b32 v22, v132, v19
	s_waitcnt lgkmcnt(1)
	v_cndmask_b32_e64 v19, v32, v35, s[2:3]
	v_mul_f32_e32 v32, 0xbfb8aa3b, v159
	v_accvgpr_read_b32 v157, a178
	v_exp_f32_e32 v38, v32
	v_mul_f32_e32 v32, 0xbfb8aa3b, v158
	v_cndmask_b32_e64 v16, v55, v33, s[2:3]
	v_cvt_pk_bf16_f32 v20, v18, v20
	v_exp_f32_e32 v40, v32
	v_mul_f32_e32 v32, 0xbfb8aa3b, v157
	ds_bpermute_b32 v34, v132, v16
	v_exp_f32_e32 v39, v32
	s_waitcnt vmcnt(8)
	v_accvgpr_read_b32 v0, a176
	v_accvgpr_read_b32 v2, a178
	v_cndmask_b32_e64 v18, v27, v20, s[2:3]
	v_pk_add_f32 v[38:39], v[38:39], 1.0 op_sel_hi:[1,0]
	ds_bpermute_b32 v23, v132, v18
	s_waitcnt lgkmcnt(1)
	v_cndmask_b32_e64 v18, v33, v34, s[2:3]
	v_rcp_f32_e32 v48, v39
	v_accvgpr_read_b32 v156, a179
	v_mul_f32_e32 v32, 0xbfb8aa3b, v156
	v_exp_f32_e32 v41, v32
	v_rcp_f32_e32 v52, v38
	v_mul_f32_e32 v39, v2, v48
	v_accvgpr_read_b32 v3, a179
	v_pk_add_f32 v[40:41], v[40:41], 1.0 op_sel_hi:[1,0]
	v_mul_f32_e32 v38, v0, v52
	v_cndmask_b32_e64 v17, v35, v54, s[2:3]
	v_cndmask_b32_e64 v16, v34, v55, s[2:3]
	v_rcp_f32_e32 v2, v41
	global_store_dwordx4 v[64:65], v[16:19], off offset:64
	v_accvgpr_read_b32 v1, a177
	v_accvgpr_read_b32 v155, a180
	v_cndmask_b32_e64 v17, v22, v26, s[2:3]
	s_waitcnt lgkmcnt(0)
	v_cndmask_b32_e64 v16, v23, v27, s[2:3]
	v_cndmask_b32_e64 v19, v21, v22, s[2:3]
	v_cndmask_b32_e64 v18, v20, v23, s[2:3]
	global_store_dwordx4 v[64:65], v[16:19], off offset:80
	v_accvgpr_read_b32 v31, a15
	v_accvgpr_read_b32 v154, a181
	v_accvgpr_read_b32 v16, a0
	v_mov_b32_e32 v48, v16
	v_accvgpr_read_b32 v18, a2
	v_mov_b32_e32 v49, v18
	v_rcp_f32_e32 v33, v40
	v_mul_f32_e32 v32, 0xbfb8aa3b, v155
	v_mul_f32_e32 v3, v3, v2
	v_accvgpr_read_b32 v153, a182
	v_exp_f32_e32 v42, v32
	v_mul_f32_e32 v32, 0xbfb8aa3b, v154
	v_accvgpr_read_b32 v152, a183
	v_exp_f32_e32 v36, v32
	v_mul_f32_e32 v32, 0xbfb8aa3b, v153
	v_accvgpr_read_b32 v151, a184
	v_exp_f32_e32 v43, v32
	v_mul_f32_e32 v32, 0xbfb8aa3b, v152
	v_accvgpr_read_b32 v150, a185
	v_exp_f32_e32 v37, v32
	v_mul_f32_e32 v32, 0xbfb8aa3b, v151
	v_accvgpr_read_b32 v149, a186
	v_exp_f32_e32 v44, v32
	v_mul_f32_e32 v32, 0xbfb8aa3b, v150
	v_accvgpr_read_b32 v17, a1
	v_exp_f32_e32 v46, v32
	v_mul_f32_e32 v32, 0xbfb8aa3b, v149
	v_accvgpr_read_b32 v19, a3
	v_exp_f32_e32 v45, v32
	v_mul_f32_e32 v2, v1, v33
	v_mov_b32_e32 v18, v17
	v_pk_mul_f32 v[0:1], v[2:3], v[18:19]
	v_accvgpr_read_b32 v10, a186
	v_and_b32_sdwa v16, v1, v218 dst_sel:DWORD dst_unused:UNUSED_PAD src0_sel:WORD_1 src1_sel:DWORD
	v_and_b32_sdwa v17, v0, v218 dst_sel:DWORD dst_unused:UNUSED_PAD src0_sel:WORD_1 src1_sel:DWORD
	v_add3_u32 v1, v1, v16, s80
	v_add3_u32 v16, v0, v17, s80
	v_and_b32_e32 v17, 0xffff0000, v1
	v_pk_add_f32 v[0:1], v[44:45], 1.0 op_sel_hi:[1,0]
	v_pk_mul_f32 v[38:39], v[38:39], v[48:49]
	v_rcp_f32_e32 v19, v1
	v_and_b32_sdwa v2, v39, v218 dst_sel:DWORD dst_unused:UNUSED_PAD src0_sel:WORD_1 src1_sel:DWORD
	v_and_b32_sdwa v3, v38, v218 dst_sel:DWORD dst_unused:UNUSED_PAD src0_sel:WORD_1 src1_sel:DWORD
	v_add3_u32 v2, v39, v2, s80
	v_add3_u32 v3, v38, v3, s80
	v_or_b32_sdwa v38, v17, v2 dst_sel:DWORD dst_unused:UNUSED_PAD src0_sel:DWORD src1_sel:WORD_1
	v_and_b32_e32 v16, 0xffff0000, v16
	v_or_b32_sdwa v39, v16, v3 dst_sel:DWORD dst_unused:UNUSED_PAD src0_sel:DWORD src1_sel:WORD_1
	v_accvgpr_read_b32 v8, a184
	v_rcp_f32_e32 v17, v0
	v_mul_f32_e32 v1, v10, v19
	v_accvgpr_read_b32 v148, a187
	v_mul_f32_e32 v32, 0xbfb8aa3b, v148
	v_exp_f32_e32 v47, v32
	v_accvgpr_read_b32 v11, a187
	v_mul_f32_e32 v0, v8, v17
	v_pk_add_f32 v[2:3], v[46:47], 1.0 op_sel_hi:[1,0]
	v_accvgpr_read_b32 v26, a10
	v_rcp_f32_e32 v10, v3
	v_accvgpr_read_b32 v24, a8
	v_mov_b32_e32 v16, v24
	v_mov_b32_e32 v17, v26
	v_pk_mul_f32 v[0:1], v[0:1], v[16:17]
	v_accvgpr_read_b32 v9, a185
	v_rcp_f32_e32 v18, v2
	v_mul_f32_e32 v3, v11, v10
	v_accvgpr_read_b32 v25, a9
	v_accvgpr_read_b32 v27, a11
	v_mul_f32_e32 v2, v9, v18
	v_mov_b32_e32 v26, v25
	v_pk_mul_f32 v[2:3], v[2:3], v[26:27]
	v_cvt_pk_bf16_f32 v16, v1, v3
	v_cvt_pk_bf16_f32 v17, v0, v2
	v_accvgpr_read_b32 v6, a182
	v_pk_add_f32 v[2:3], v[42:43], 1.0 op_sel_hi:[1,0]
	v_accvgpr_read_b32 v4, a180
	v_rcp_f32_e32 v9, v3
	v_accvgpr_read_b32 v7, a183
	v_accvgpr_read_b32 v22, a6
	v_accvgpr_read_b32 v20, a4
	v_rcp_f32_e32 v24, v2
	v_mul_f32_e32 v3, v6, v9
	v_mov_b32_e32 v11, v22
	v_pk_add_f32 v[8:9], v[36:37], 1.0 op_sel_hi:[1,0]
	v_mul_f32_e32 v2, v4, v24
	v_rcp_f32_e32 v6, v9
	v_mov_b32_e32 v10, v20
	v_pk_mul_f32 v[2:3], v[2:3], v[10:11]
	v_accvgpr_read_b32 v5, a181
	v_rcp_f32_e32 v20, v8
	v_mul_f32_e32 v7, v7, v6
	v_accvgpr_read_b32 v147, a188
	v_accvgpr_read_b32 v145, a190
	v_accvgpr_read_b32 v21, a5
	v_mul_f32_e32 v32, 0xbfb8aa3b, v147
	v_mul_f32_e32 v35, 0xbfb8aa3b, v145
	v_accvgpr_read_b32 v23, a7
	v_exp_f32_e32 v34, v32
	v_exp_f32_e32 v35, v35
	v_mul_f32_e32 v6, v5, v20
	v_mov_b32_e32 v22, v21
	v_pk_mul_f32 v[4:5], v[6:7], v[22:23]
	v_cvt_pk_bf16_f32 v11, v2, v4
	v_cvt_pk_bf16_f32 v10, v3, v5
	v_accvgpr_read_b32 v14, a190
	v_pk_add_f32 v[2:3], v[34:35], 1.0 op_sel_hi:[1,0]
	v_rcp_f32_e32 v9, v3
	v_accvgpr_read_b32 v12, a188
	v_rcp_f32_e32 v7, v2
	v_mul_f32_e32 v3, v14, v9
	v_accvgpr_read_b32 v146, a189
	v_accvgpr_read_b32 v144, a191
	v_mul_f32_e32 v32, 0xbfb8aa3b, v146
	v_mul_f32_e32 v50, 0xbfb8aa3b, v144
	v_exp_f32_e32 v32, v32
	v_exp_f32_e32 v33, v50
	v_accvgpr_read_b32 v15, a191
	v_mul_f32_e32 v2, v12, v7
	v_pk_add_f32 v[4:5], v[32:33], 1.0 op_sel_hi:[1,0]
	v_accvgpr_read_b32 v30, a14
	v_rcp_f32_e32 v9, v5
	v_accvgpr_read_b32 v28, a12
	v_mov_b32_e32 v6, v28
	v_mov_b32_e32 v7, v30
	v_pk_mul_f32 v[2:3], v[2:3], v[6:7]
	v_accvgpr_read_b32 v13, a189
	v_rcp_f32_e32 v12, v4
	v_mul_f32_e32 v5, v15, v9
	v_accvgpr_read_b32 v29, a13
	v_mul_f32_e32 v4, v13, v12
	v_mov_b32_e32 v30, v29
	v_pk_mul_f32 v[4:5], v[4:5], v[30:31]
	v_cvt_pk_bf16_f32 v5, v3, v5
	v_cvt_pk_bf16_f32 v4, v2, v4
	v_cndmask_b32_e64 v0, v39, v17, s[2:3]
	v_cndmask_b32_e64 v1, v38, v16, s[2:3]
	ds_bpermute_b32 v18, v132, v0
	ds_bpermute_b32 v19, v132, v1
	v_cndmask_b32_e64 v2, v11, v4, s[2:3]
	v_cndmask_b32_e64 v3, v10, v5, s[2:3]
	ds_bpermute_b32 v6, v132, v3
	ds_bpermute_b32 v7, v132, v2
	v_mov_b32_e32 v229, 0x4000
	s_waitcnt lgkmcnt(2)
	v_cndmask_b32_e64 v1, v19, v38, s[2:3]
	v_cndmask_b32_e64 v0, v18, v39, s[2:3]
	v_cndmask_b32_e64 v3, v16, v19, s[2:3]
	v_cndmask_b32_e64 v2, v17, v18, s[2:3]
	s_add_i32 s0, s0, s93
	global_store_dwordx4 v[66:67], v[0:3], off offset:64
	s_cmpk_gt_i32 s0, 0x78f
	v_mov_b32_e32 v214, v229
	s_waitcnt lgkmcnt(1)
	v_cndmask_b32_e64 v1, v6, v10, s[2:3]
	s_waitcnt lgkmcnt(0)
	v_cndmask_b32_e64 v0, v7, v11, s[2:3]
	v_cndmask_b32_e64 v3, v5, v6, s[2:3]
	v_cndmask_b32_e64 v2, v4, v7, s[2:3]
	global_store_dwordx4 v[66:67], v[0:3], off offset:80
	s_cbranch_scc1 .LBB0_156

.LBB0_160:
	s_nop 1
	v_accvgpr_read_b32 v142, a80
	v_accvgpr_read_b32 v139, a83
	v_accvgpr_read_b32 v141, a81
	v_accvgpr_read_b32 v137, a84
	v_mul_f32_e32 v116, 0xbfb8aa3b, v142
	v_mfma_f32_32x32x16_bf16 a[16:31], v[132:135], v[112:115], a[16:31]
	v_mul_f32_e32 v112, 0xbfb8aa3b, v139
	v_accvgpr_read_b32 v140, a82
	v_accvgpr_read_b32 v136, a85
	v_exp_f32_e32 v142, v116
	v_mul_f32_e32 v116, 0xbfb8aa3b, v141
	v_exp_f32_e32 v221, v112
	v_mul_f32_e32 v112, 0xbfb8aa3b, v137
	v_accvgpr_read_b32 v127, a86
	v_exp_f32_e32 v220, v116
	v_mul_f32_e32 v116, 0xbfb8aa3b, v140
	v_exp_f32_e32 v226, v112
	v_mul_f32_e32 v112, 0xbfb8aa3b, v136
	v_accvgpr_read_b32 v126, a87
	v_exp_f32_e32 v143, v116
	v_exp_f32_e32 v116, v112
	v_mul_f32_e32 v112, 0xbfb8aa3b, v127
	v_accvgpr_read_b32 v125, a88
	v_exp_f32_e32 v227, v112
	v_mul_f32_e32 v112, 0xbfb8aa3b, v126
	v_accvgpr_read_b32 v124, a89
	v_exp_f32_e32 v117, v112
	v_mul_f32_e32 v112, 0xbfb8aa3b, v125
	v_accvgpr_read_b32 v123, a90
	v_exp_f32_e32 v126, v112
	v_mul_f32_e32 v112, 0xbfb8aa3b, v124
	v_accvgpr_read_b32 v122, a91
	v_exp_f32_e32 v124, v112
	v_mul_f32_e32 v112, 0xbfb8aa3b, v123
	v_accvgpr_read_b32 v121, a92
	v_accvgpr_read_b32 v119, a94
	v_mfma_f32_32x32x16_bf16 a[32:47], v[132:135], v[80:83], a[32:47]
	v_accvgpr_read_b32 v80, a80
	v_exp_f32_e32 v127, v112
	v_mul_f32_e32 v112, 0xbfb8aa3b, v122
	v_accvgpr_read_b32 v120, a93
	v_accvgpr_read_b32 v82, a82
	v_exp_f32_e32 v125, v112
	v_mul_f32_e32 v112, 0xbfb8aa3b, v121
	v_mul_f32_e32 v113, 0xbfb8aa3b, v119
	v_pk_add_f32 v[118:119], v[142:143], 1.0 op_sel_hi:[1,0]
	v_exp_f32_e32 v114, v112
	v_mul_f32_e32 v112, 0xbfb8aa3b, v120
	v_rcp_f32_e32 v121, v119
	v_accvgpr_read_b32 v83, a83
	v_accvgpr_read_b32 v81, a81
	v_accvgpr_read_b32 v90, a90
	v_rcp_f32_e32 v136, v118
	v_mul_f32_e32 v137, v82, v121
	v_accvgpr_read_b32 v138, a95
	v_pk_add_f32 v[120:121], v[220:221], 1.0 op_sel_hi:[1,0]
	v_rcp_f32_e32 v123, v121
	v_mul_f32_e32 v136, v80, v136
	v_exp_f32_e32 v115, v113
	v_rcp_f32_e32 v119, v120
	v_mul_f32_e32 v139, v83, v123
	v_pk_add_f32 v[82:83], v[126:127], 1.0 op_sel_hi:[1,0]
	v_rcp_f32_e32 v122, v83
	v_mul_f32_e32 v113, 0xbfb8aa3b, v138
	v_mul_f32_e32 v138, v81, v119
	v_accvgpr_read_b32 v88, a88
	v_rcp_f32_e32 v119, v82
	v_mul_f32_e32 v141, v90, v122
	v_accvgpr_read_b32 v91, a91
	v_pk_add_f32 v[80:81], v[124:125], 1.0 op_sel_hi:[1,0]
	v_rcp_f32_e32 v120, v81
	v_mul_f32_e32 v140, v88, v119
	v_accvgpr_read_b32 v89, a89
	v_accvgpr_read_b32 v86, a86
	v_rcp_f32_e32 v90, v80
	v_mul_f32_e32 v143, v91, v120
	v_pk_add_f32 v[82:83], v[226:227], 1.0 op_sel_hi:[1,0]
	v_rcp_f32_e32 v118, v83
	v_mul_f32_e32 v142, v89, v90
	v_accvgpr_read_b32 v84, a84
	v_rcp_f32_e32 v89, v82
	v_mul_f32_e32 v221, v86, v118
	v_accvgpr_read_b32 v87, a87
	v_pk_add_f32 v[80:81], v[116:117], 1.0 op_sel_hi:[1,0]
	v_rcp_f32_e32 v90, v81
	v_mul_f32_e32 v220, v84, v89
	v_accvgpr_read_b32 v85, a85
	v_accvgpr_read_b32 v94, a94
	v_rcp_f32_e32 v86, v80
	v_mul_f32_e32 v227, v87, v90
	v_pk_add_f32 v[82:83], v[114:115], 1.0 op_sel_hi:[1,0]
	v_rcp_f32_e32 v88, v83
	v_mul_f32_e32 v226, v85, v86
	v_accvgpr_read_b32 v92, a92
	v_rcp_f32_e32 v85, v82
	v_mul_f32_e32 v215, v94, v88
	v_exp_f32_e32 v112, v112
	v_exp_f32_e32 v113, v113
	v_accvgpr_read_b32 v95, a95
	v_pk_add_f32 v[80:81], v[112:113], 1.0 op_sel_hi:[1,0]
	v_accvgpr_read_b32 v96, a96
	v_rcp_f32_e32 v87, v81
	v_accvgpr_read_b32 v98, a98
	v_mfma_f32_32x32x16_bf16 a[0:15], v[132:135], v[128:131], a[0:15]
	v_or_b32_e32 v129, s2, v161
	v_accvgpr_read_b32 v97, a97
	v_or_b32_e32 v128, s1, v162
	v_add_u32_e32 v133, v163, v129
	v_mov_b32_e32 v162, v96
	v_mov_b32_e32 v163, v98
	v_accvgpr_read_b32 v99, a99
	v_mul_f32_e32 v214, v92, v85
	v_pk_mul_f32 v[136:137], v[162:163], v[136:137]
	v_mov_b32_e32 v98, v97
	v_pk_mul_f32 v[96:97], v[98:99], v[138:139]
	v_and_b32_sdwa v99, v136, v218 dst_sel:DWORD dst_unused:UNUSED_PAD src0_sel:WORD_1 src1_sel:DWORD
	v_add3_u32 v99, v136, v99, s80
	v_cvt_pk_bf16_f32 v136, v137, v97
	v_and_b32_sdwa v137, v96, v218 dst_sel:DWORD dst_unused:UNUSED_PAD src0_sel:WORD_1 src1_sel:DWORD
	v_accvgpr_read_b32 v93, a93
	v_add3_u32 v96, v96, v137, s80
	v_accvgpr_read_b32 v104, a104
	v_accvgpr_read_b32 v106, a106
	v_and_b32_e32 v96, 0xffff0000, v96
	v_accvgpr_read_b32 v105, a105
	v_rcp_f32_e32 v85, v80
	v_or_b32_sdwa v137, v96, v99 dst_sel:DWORD dst_unused:UNUSED_PAD src0_sel:DWORD src1_sel:WORD_1
	v_mov_b32_e32 v96, v104
	v_mov_b32_e32 v97, v106
	v_accvgpr_read_b32 v107, a107
	v_pk_mul_f32 v[96:97], v[96:97], v[140:141]
	v_mov_b32_e32 v106, v105
	v_pk_mul_f32 v[98:99], v[106:107], v[142:143]
	v_cvt_pk_bf16_f32 v106, v97, v99
	v_cvt_pk_bf16_f32 v107, v96, v98
	v_accvgpr_read_b32 v100, a100
	v_accvgpr_read_b32 v102, a102
	v_accvgpr_read_b32 v101, a101
	v_mul_f32_e32 v223, v95, v87
	v_mov_b32_e32 v104, v100
	v_mov_b32_e32 v105, v102
	v_accvgpr_read_b32 v103, a103
	v_pk_mul_f32 v[104:105], v[104:105], v[220:221]
	v_mov_b32_e32 v102, v101
	v_pk_mul_f32 v[100:101], v[102:103], v[226:227]
	v_and_b32_sdwa v103, v104, v218 dst_sel:DWORD dst_unused:UNUSED_PAD src0_sel:WORD_1 src1_sel:DWORD
	v_add3_u32 v103, v104, v103, s80
	v_cvt_pk_bf16_f32 v104, v105, v101
	v_and_b32_sdwa v105, v100, v218 dst_sel:DWORD dst_unused:UNUSED_PAD src0_sel:WORD_1 src1_sel:DWORD
	v_add3_u32 v100, v100, v105, s80
	v_accvgpr_read_b32 v108, a108
	v_accvgpr_read_b32 v110, a110
	v_and_b32_e32 v100, 0xffff0000, v100
	v_accvgpr_read_b32 v109, a109
	v_or_b32_sdwa v105, v100, v103 dst_sel:DWORD dst_unused:UNUSED_PAD src0_sel:DWORD src1_sel:WORD_1
	v_mov_b32_e32 v100, v108
	v_mov_b32_e32 v101, v110
	v_accvgpr_read_b32 v111, a111
	v_mul_f32_e32 v222, v93, v85
	v_cmp_lt_i32_e32 vcc, v211, v210
	v_readlane_b32 s2, v253, 61
	v_pk_mul_f32 v[100:101], v[100:101], v[214:215]
	v_mov_b32_e32 v110, v109
	v_cndmask_b32_e32 v129, v209, v211, vcc
	v_readlane_b32 s3, v253, 62
	v_pk_mul_f32 v[102:103], v[110:111], v[222:223]
	v_cvt_pk_bf16_f32 v103, v101, v103
	v_cvt_pk_bf16_f32 v102, v100, v102
	v_lshlrev_b32_e32 v132, 2, v129
	v_ashrrev_i32_e32 v130, 1, v128
	v_mov_b64_e32 v[128:129], s[2:3]
	s_movk_i32 s1, 0x1600
	v_mad_i64_i32 v[134:135], s[2:3], v133, s1, v[128:129]
	v_and_b32_e32 v96, 63, v160
	v_cmp_gt_u32_e64 s[2:3], 32, v96
	s_nop 1
	v_cndmask_b32_e64 v96, v137, v107, s[2:3]
	v_cndmask_b32_e64 v97, v136, v106, s[2:3]
	ds_bpermute_b32 v138, v132, v97
	ds_bpermute_b32 v139, v132, v96
	v_cndmask_b32_e64 v100, v105, v102, s[2:3]
	v_cndmask_b32_e64 v101, v104, v103, s[2:3]
	ds_bpermute_b32 v108, v132, v101
	ds_bpermute_b32 v109, v132, v100
	v_ashrrev_i32_e32 v131, 31, v130
	v_lshlrev_b64 v[130:131], 1, v[130:131]
	v_lshl_add_u64 v[96:97], v[134:135], 0, v[130:131]
	v_and_b32_e32 v192, 32, v160
	v_lshl_add_u64 v[96:97], v[96:97], 0, v[192:193]
	s_waitcnt lgkmcnt(3)
	v_cndmask_b32_e64 v99, v138, v136, s[2:3]
	s_waitcnt lgkmcnt(2)
	v_cndmask_b32_e64 v98, v139, v137, s[2:3]
	v_cndmask_b32_e64 v101, v106, v138, s[2:3]
	v_cndmask_b32_e64 v100, v107, v139, s[2:3]
	v_accvgpr_read_b32 v225, a48
	global_store_dwordx4 v[96:97], v[98:101], off
	v_accvgpr_read_b32 v224, a49
	v_accvgpr_read_b32 v252, a50
	s_waitcnt lgkmcnt(1)
	v_cndmask_b32_e64 v99, v108, v104, s[2:3]
	s_waitcnt lgkmcnt(0)
	v_cndmask_b32_e64 v98, v109, v105, s[2:3]
	v_cndmask_b32_e64 v101, v103, v108, s[2:3]
	v_cndmask_b32_e64 v100, v102, v109, s[2:3]
	global_store_dwordx4 v[96:97], v[98:101], off offset:16
	v_accvgpr_read_b32 v127, a63
	v_accvgpr_read_b32 v114, a50
	v_mul_f32_e32 v98, 0xbfb8aa3b, v225
	v_exp_f32_e32 v104, v98
	v_mul_f32_e32 v98, 0xbfb8aa3b, v224
	v_exp_f32_e32 v106, v98
	v_mul_f32_e32 v98, 0xbfb8aa3b, v252
	v_exp_f32_e32 v105, v98
	v_accvgpr_read_b32 v112, a48
	v_accvgpr_read_b32 v251, a51
	v_mul_f32_e32 v98, 0xbfb8aa3b, v251
	v_pk_add_f32 v[104:105], v[104:105], 1.0 op_sel_hi:[1,0]
	v_exp_f32_e32 v107, v98
	v_rcp_f32_e32 v139, v105
	v_accvgpr_read_b32 v115, a51
	v_pk_add_f32 v[106:107], v[106:107], 1.0 op_sel_hi:[1,0]
	v_accvgpr_read_b32 v64, a112
	v_rcp_f32_e32 v142, v104
	v_mul_f32_e32 v105, v114, v139
	v_accvgpr_read_b32 v66, a114
	v_mul_f32_e32 v104, v112, v142
	v_rcp_f32_e32 v114, v107
	v_mov_b32_e32 v138, v64
	v_mov_b32_e32 v139, v66
	v_pk_mul_f32 v[104:105], v[138:139], v[104:105]
	v_accvgpr_read_b32 v113, a49
	v_rcp_f32_e32 v138, v106
	v_accvgpr_read_b32 v250, a52
	v_accvgpr_read_b32 v249, a53
	v_mul_f32_e32 v98, 0xbfb8aa3b, v250
	v_mul_f32_e32 v107, v115, v114
	v_accvgpr_read_b32 v248, a54
	v_exp_f32_e32 v108, v98
	v_mul_f32_e32 v98, 0xbfb8aa3b, v249
	v_accvgpr_read_b32 v247, a55
	v_exp_f32_e32 v102, v98
	v_mul_f32_e32 v98, 0xbfb8aa3b, v248
	v_accvgpr_read_b32 v246, a56
	v_exp_f32_e32 v109, v98
	v_mul_f32_e32 v98, 0xbfb8aa3b, v247
	v_accvgpr_read_b32 v245, a57
	v_exp_f32_e32 v103, v98
	v_mul_f32_e32 v98, 0xbfb8aa3b, v246
	v_accvgpr_read_b32 v244, a58
	v_exp_f32_e32 v110, v98
	v_mul_f32_e32 v98, 0xbfb8aa3b, v245
	v_accvgpr_read_b32 v65, a113
	v_exp_f32_e32 v134, v98
	v_mul_f32_e32 v98, 0xbfb8aa3b, v244
	v_accvgpr_read_b32 v67, a115
	v_exp_f32_e32 v111, v98
	v_mul_f32_e32 v106, v113, v138
	v_mov_b32_e32 v66, v65
	v_pk_mul_f32 v[64:65], v[66:67], v[106:107]
	v_and_b32_sdwa v67, v104, v218 dst_sel:DWORD dst_unused:UNUSED_PAD src0_sel:WORD_1 src1_sel:DWORD
	v_and_b32_sdwa v66, v105, v218 dst_sel:DWORD dst_unused:UNUSED_PAD src0_sel:WORD_1 src1_sel:DWORD
	v_add3_u32 v67, v104, v67, s80
	v_and_b32_sdwa v104, v65, v218 dst_sel:DWORD dst_unused:UNUSED_PAD src0_sel:WORD_1 src1_sel:DWORD
	v_add3_u32 v66, v105, v66, s80
	v_and_b32_sdwa v105, v64, v218 dst_sel:DWORD dst_unused:UNUSED_PAD src0_sel:WORD_1 src1_sel:DWORD
	v_add3_u32 v65, v65, v104, s80
	v_accvgpr_read_b32 v122, a58
	v_add3_u32 v104, v64, v105, s80
	v_and_b32_e32 v105, 0xffff0000, v65
	v_pk_add_f32 v[64:65], v[110:111], 1.0 op_sel_hi:[1,0]
	v_or_b32_sdwa v110, v105, v66 dst_sel:DWORD dst_unused:UNUSED_PAD src0_sel:DWORD src1_sel:WORD_1
	v_rcp_f32_e32 v107, v65
	v_and_b32_e32 v104, 0xffff0000, v104
	v_or_b32_sdwa v111, v104, v67 dst_sel:DWORD dst_unused:UNUSED_PAD src0_sel:DWORD src1_sel:WORD_1
	v_accvgpr_read_b32 v120, a56
	v_rcp_f32_e32 v105, v64
	v_mul_f32_e32 v65, v122, v107
	v_accvgpr_read_b32 v243, a59
	v_mul_f32_e32 v98, 0xbfb8aa3b, v243
	v_exp_f32_e32 v135, v98
	v_accvgpr_read_b32 v123, a59
	v_mul_f32_e32 v64, v120, v105
	v_pk_add_f32 v[66:67], v[134:135], 1.0 op_sel_hi:[1,0]
	v_accvgpr_read_b32 v72, a120
	v_rcp_f32_e32 v107, v67
	v_mov_b32_e32 v104, v72
	v_accvgpr_read_b32 v74, a122
	v_mov_b32_e32 v105, v74
	v_accvgpr_read_b32 v121, a57
	v_pk_mul_f32 v[64:65], v[104:105], v[64:65]
	v_rcp_f32_e32 v105, v66
	v_mul_f32_e32 v67, v123, v107
	v_accvgpr_read_b32 v73, a121
	v_accvgpr_read_b32 v75, a123
	v_mul_f32_e32 v66, v121, v105
	v_mov_b32_e32 v74, v73
	v_pk_mul_f32 v[66:67], v[74:75], v[66:67]
	v_cvt_pk_bf16_f32 v104, v65, v67
	v_cvt_pk_bf16_f32 v105, v64, v66
	v_cndmask_b32_e64 v64, v111, v105, s[2:3]
	v_cndmask_b32_e64 v65, v110, v104, s[2:3]
	v_accvgpr_read_b32 v118, a54
	ds_bpermute_b32 v106, v132, v64
	ds_bpermute_b32 v107, v132, v65
	v_pk_add_f32 v[64:65], v[108:109], 1.0 op_sel_hi:[1,0]
	v_accvgpr_read_b32 v116, a52
	v_rcp_f32_e32 v75, v65
	s_waitcnt lgkmcnt(0)
	v_cndmask_b32_e64 v73, v107, v110, s[2:3]
	v_accvgpr_read_b32 v119, a55
	v_accvgpr_read_b32 v68, a116
	v_rcp_f32_e32 v110, v64
	v_mul_f32_e32 v65, v118, v75
	v_accvgpr_read_b32 v70, a118
	v_mul_f32_e32 v64, v116, v110
	v_pk_add_f32 v[74:75], v[102:103], 1.0 op_sel_hi:[1,0]
	v_mov_b32_e32 v102, v68
	v_rcp_f32_e32 v109, v75
	v_mov_b32_e32 v103, v70
	v_accvgpr_read_b32 v117, a53
	v_pk_mul_f32 v[64:65], v[102:103], v[64:65]
	v_rcp_f32_e32 v103, v74
	v_mul_f32_e32 v75, v119, v109
	v_accvgpr_read_b32 v242, a60
	v_accvgpr_read_b32 v240, a62
	v_accvgpr_read_b32 v69, a117
	v_mul_f32_e32 v98, 0xbfb8aa3b, v242
	v_mul_f32_e32 v99, 0xbfb8aa3b, v240
	v_accvgpr_read_b32 v71, a119
	v_exp_f32_e32 v100, v98
	v_exp_f32_e32 v101, v99
	v_mul_f32_e32 v74, v117, v103
	v_mov_b32_e32 v70, v69
	v_pk_mul_f32 v[68:69], v[70:71], v[74:75]
	v_and_b32_sdwa v71, v64, v218 dst_sel:DWORD dst_unused:UNUSED_PAD src0_sel:WORD_1 src1_sel:DWORD
	v_and_b32_sdwa v70, v65, v218 dst_sel:DWORD dst_unused:UNUSED_PAD src0_sel:WORD_1 src1_sel:DWORD
	v_add3_u32 v71, v64, v71, s80
	v_and_b32_sdwa v64, v69, v218 dst_sel:DWORD dst_unused:UNUSED_PAD src0_sel:WORD_1 src1_sel:DWORD
	v_add3_u32 v70, v65, v70, s80
	v_and_b32_sdwa v65, v68, v218 dst_sel:DWORD dst_unused:UNUSED_PAD src0_sel:WORD_1 src1_sel:DWORD
	v_add3_u32 v64, v69, v64, s80
	v_accvgpr_read_b32 v126, a62
	v_add3_u32 v68, v68, v65, s80
	v_and_b32_e32 v69, 0xffff0000, v64
	v_pk_add_f32 v[64:65], v[100:101], 1.0 op_sel_hi:[1,0]
	v_and_b32_e32 v68, 0xffff0000, v68
	v_rcp_f32_e32 v75, v65
	v_or_b32_sdwa v101, v68, v71 dst_sel:DWORD dst_unused:UNUSED_PAD src0_sel:DWORD src1_sel:WORD_1
	v_or_b32_sdwa v100, v69, v70 dst_sel:DWORD dst_unused:UNUSED_PAD src0_sel:DWORD src1_sel:WORD_1
	v_accvgpr_read_b32 v124, a60
	v_rcp_f32_e32 v71, v64
	v_mul_f32_e32 v65, v126, v75
	v_accvgpr_read_b32 v241, a61
	v_accvgpr_read_b32 v239, a63
	v_mul_f32_e32 v98, 0xbfb8aa3b, v241
	v_mul_f32_e32 v99, 0xbfb8aa3b, v239
	v_exp_f32_e32 v98, v98
	v_exp_f32_e32 v99, v99
	v_mul_f32_e32 v64, v124, v71
	v_pk_add_f32 v[68:69], v[98:99], 1.0 op_sel_hi:[1,0]
	v_accvgpr_read_b32 v76, a124
	v_rcp_f32_e32 v75, v69
	v_accvgpr_read_b32 v78, a126
	v_mov_b32_e32 v70, v76
	v_mov_b32_e32 v71, v78
	v_pk_mul_f32 v[64:65], v[70:71], v[64:65]
	v_accvgpr_read_b32 v125, a61
	v_rcp_f32_e32 v76, v68
	v_mul_f32_e32 v69, v127, v75
	v_accvgpr_read_b32 v77, a125
	v_accvgpr_read_b32 v79, a127
	v_mul_f32_e32 v68, v125, v76
	v_mov_b32_e32 v78, v77
	v_pk_mul_f32 v[68:69], v[78:79], v[68:69]
	v_cvt_pk_bf16_f32 v65, v65, v69
	v_cvt_pk_bf16_f32 v64, v64, v68
	v_cndmask_b32_e64 v69, v100, v65, s[2:3]
	v_cndmask_b32_e64 v68, v101, v64, s[2:3]
	ds_bpermute_b32 v70, v132, v69
	ds_bpermute_b32 v76, v132, v68
	v_add_u32_e32 v136, 32, v133
	v_mad_i64_i32 v[136:137], s[4:5], v136, s1, v[128:129]
	v_accvgpr_read_b32 v237, a65
	v_lshl_add_u64 v[136:137], v[136:137], 0, v[130:131]
	v_accvgpr_read_b32 v238, a64
	v_accvgpr_read_b32 v236, a66
	v_lshl_add_u64 v[66:67], v[136:137], 0, v[192:193]
	v_cndmask_b32_e64 v72, v106, v111, s[2:3]
	v_cndmask_b32_e64 v75, v104, v107, s[2:3]
	v_cndmask_b32_e64 v74, v105, v106, s[2:3]
	s_waitcnt lgkmcnt(1)
	v_cndmask_b32_e64 v71, v65, v70, s[2:3]
	v_mul_f32_e32 v65, 0xbfb8aa3b, v237
	global_store_dwordx4 v[66:67], v[72:75], off
	v_cndmask_b32_e64 v69, v70, v100, s[2:3]
	s_waitcnt lgkmcnt(0)
	v_cndmask_b32_e64 v70, v64, v76, s[2:3]
	v_mul_f32_e32 v64, 0xbfb8aa3b, v238
	v_exp_f32_e32 v74, v65
	v_mul_f32_e32 v65, 0xbfb8aa3b, v236
	v_exp_f32_e32 v64, v64
	v_exp_f32_e32 v65, v65
	v_accvgpr_read_b32 v95, a79
	v_accvgpr_read_b32 v82, a66
	v_accvgpr_read_b32 v80, a64
	v_pk_add_f32 v[64:65], v[64:65], 1.0 op_sel_hi:[1,0]
	v_accvgpr_read_b32 v235, a67
	v_rcp_f32_e32 v103, v65
	v_cndmask_b32_e64 v68, v76, v101, s[2:3]
	global_store_dwordx4 v[66:67], v[68:71], off offset:16
	v_accvgpr_read_b32 v83, a67
	v_rcp_f32_e32 v106, v64
	v_mul_f32_e32 v65, v82, v103
	v_mul_f32_e32 v68, 0xbfb8aa3b, v235
	v_exp_f32_e32 v75, v68
	s_nop 0
	v_pk_add_f32 v[74:75], v[74:75], 1.0 op_sel_hi:[1,0]
	v_mul_f32_e32 v64, v80, v106
	v_rcp_f32_e32 v82, v75
	v_accvgpr_read_b32 v48, a128
	v_mov_b32_e32 v102, v48
	v_accvgpr_read_b32 v50, a130
	v_mov_b32_e32 v103, v50
	v_pk_mul_f32 v[64:65], v[102:103], v[64:65]
	v_accvgpr_read_b32 v81, a65
	v_rcp_f32_e32 v102, v74
	v_accvgpr_read_b32 v234, a68
	v_accvgpr_read_b32 v233, a69
	v_mul_f32_e32 v68, 0xbfb8aa3b, v234
	v_mul_f32_e32 v75, v83, v82
	v_accvgpr_read_b32 v232, a70
	v_exp_f32_e32 v76, v68
	v_mul_f32_e32 v68, 0xbfb8aa3b, v233
	v_accvgpr_read_b32 v231, a71
	v_exp_f32_e32 v72, v68
	v_mul_f32_e32 v68, 0xbfb8aa3b, v232
	v_accvgpr_read_b32 v207, a72
	v_exp_f32_e32 v77, v68
	v_mul_f32_e32 v68, 0xbfb8aa3b, v231
	v_accvgpr_read_b32 v205, a73
	v_exp_f32_e32 v73, v68
	v_mul_f32_e32 v68, 0xbfb8aa3b, v207
	v_accvgpr_read_b32 v204, a74
	v_exp_f32_e32 v78, v68
	v_mul_f32_e32 v68, 0xbfb8aa3b, v205
	v_accvgpr_read_b32 v49, a129
	v_exp_f32_e32 v98, v68
	v_mul_f32_e32 v68, 0xbfb8aa3b, v204
	v_accvgpr_read_b32 v51, a131
	v_exp_f32_e32 v79, v68
	v_mul_f32_e32 v74, v81, v102
	v_mov_b32_e32 v50, v49
	v_pk_mul_f32 v[48:49], v[50:51], v[74:75]
	v_and_b32_sdwa v51, v64, v218 dst_sel:DWORD dst_unused:UNUSED_PAD src0_sel:WORD_1 src1_sel:DWORD
	v_and_b32_sdwa v50, v65, v218 dst_sel:DWORD dst_unused:UNUSED_PAD src0_sel:WORD_1 src1_sel:DWORD
	v_add3_u32 v51, v64, v51, s80
	v_and_b32_sdwa v64, v49, v218 dst_sel:DWORD dst_unused:UNUSED_PAD src0_sel:WORD_1 src1_sel:DWORD
	v_add3_u32 v50, v65, v50, s80
	v_and_b32_sdwa v65, v48, v218 dst_sel:DWORD dst_unused:UNUSED_PAD src0_sel:WORD_1 src1_sel:DWORD
	v_add3_u32 v49, v49, v64, s80
	v_accvgpr_read_b32 v90, a74
	v_add3_u32 v64, v48, v65, s80
	v_and_b32_e32 v65, 0xffff0000, v49
	v_pk_add_f32 v[48:49], v[78:79], 1.0 op_sel_hi:[1,0]
	v_or_b32_sdwa v78, v65, v50 dst_sel:DWORD dst_unused:UNUSED_PAD src0_sel:DWORD src1_sel:WORD_1
	v_rcp_f32_e32 v75, v49
	v_and_b32_e32 v64, 0xffff0000, v64
	v_or_b32_sdwa v79, v64, v51 dst_sel:DWORD dst_unused:UNUSED_PAD src0_sel:DWORD src1_sel:WORD_1
	v_accvgpr_read_b32 v88, a72
	v_rcp_f32_e32 v65, v48
	v_mul_f32_e32 v49, v90, v75
	v_accvgpr_read_b32 v203, a75
	v_mul_f32_e32 v68, 0xbfb8aa3b, v203
	v_exp_f32_e32 v99, v68
	v_accvgpr_read_b32 v91, a75
	v_mul_f32_e32 v48, v88, v65
	v_pk_add_f32 v[50:51], v[98:99], 1.0 op_sel_hi:[1,0]
	v_accvgpr_read_b32 v56, a136
	v_rcp_f32_e32 v75, v51
	v_mov_b32_e32 v64, v56
	v_accvgpr_read_b32 v58, a138
	v_mov_b32_e32 v65, v58
	v_accvgpr_read_b32 v89, a73
	v_pk_mul_f32 v[48:49], v[64:65], v[48:49]
	v_rcp_f32_e32 v65, v50
	v_mul_f32_e32 v51, v91, v75
	v_accvgpr_read_b32 v57, a137
	v_accvgpr_read_b32 v59, a139
	v_mul_f32_e32 v50, v89, v65
	v_mov_b32_e32 v58, v57
	v_pk_mul_f32 v[50:51], v[58:59], v[50:51]
	v_cvt_pk_bf16_f32 v74, v49, v51
	v_cvt_pk_bf16_f32 v75, v48, v50
	v_accvgpr_read_b32 v86, a70
	v_pk_add_f32 v[50:51], v[76:77], 1.0 op_sel_hi:[1,0]
	v_accvgpr_read_b32 v84, a68
	v_rcp_f32_e32 v57, v51
	v_accvgpr_read_b32 v87, a71
	v_accvgpr_read_b32 v52, a132
	v_accvgpr_read_b32 v54, a134
	v_rcp_f32_e32 v76, v50
	v_mul_f32_e32 v51, v86, v57
	v_accvgpr_read_b32 v85, a69
	v_mul_f32_e32 v50, v84, v76
	v_pk_add_f32 v[56:57], v[72:73], 1.0 op_sel_hi:[1,0]
	v_mov_b32_e32 v58, v52
	v_rcp_f32_e32 v73, v57
	v_mov_b32_e32 v59, v54
	v_pk_mul_f32 v[50:51], v[58:59], v[50:51]
	v_accvgpr_read_b32 v201, a76
	v_rcp_f32_e32 v59, v56
	v_mul_f32_e32 v57, v87, v73
	v_accvgpr_read_b32 v199, a78
	v_accvgpr_read_b32 v53, a133
	v_mul_f32_e32 v68, 0xbfb8aa3b, v201
	v_mul_f32_e32 v69, 0xbfb8aa3b, v199
	v_accvgpr_read_b32 v55, a135
	v_exp_f32_e32 v70, v68
	v_exp_f32_e32 v71, v69
	v_mul_f32_e32 v56, v85, v59
	v_mov_b32_e32 v54, v53
	v_pk_mul_f32 v[52:53], v[54:55], v[56:57]
	v_cvt_pk_bf16_f32 v59, v50, v52
	v_cvt_pk_bf16_f32 v58, v51, v53
	v_accvgpr_read_b32 v94, a78
	v_pk_add_f32 v[50:51], v[70:71], 1.0 op_sel_hi:[1,0]
	v_rcp_f32_e32 v57, v51
	v_accvgpr_read_b32 v92, a76
	v_rcp_f32_e32 v55, v50
	v_mul_f32_e32 v51, v94, v57
	v_accvgpr_read_b32 v200, a77
	v_accvgpr_read_b32 v198, a79
	v_mul_f32_e32 v68, 0xbfb8aa3b, v200
	v_mul_f32_e32 v69, 0xbfb8aa3b, v198
	v_exp_f32_e32 v68, v68
	v_exp_f32_e32 v69, v69
	v_mul_f32_e32 v50, v92, v55
	v_pk_add_f32 v[52:53], v[68:69], 1.0 op_sel_hi:[1,0]
	v_accvgpr_read_b32 v60, a140
	v_rcp_f32_e32 v57, v53
	v_accvgpr_read_b32 v62, a142
	v_mov_b32_e32 v54, v60
	v_mov_b32_e32 v55, v62
	v_pk_mul_f32 v[50:51], v[54:55], v[50:51]
	v_accvgpr_read_b32 v93, a77
	v_rcp_f32_e32 v60, v52
	v_mul_f32_e32 v53, v95, v57
	v_accvgpr_read_b32 v61, a141
	v_accvgpr_read_b32 v63, a143
	v_mul_f32_e32 v52, v93, v60
	v_mov_b32_e32 v62, v61
	v_cndmask_b32_e64 v49, v78, v74, s[2:3]
	v_pk_mul_f32 v[52:53], v[62:63], v[52:53]
	v_cvt_pk_bf16_f32 v53, v51, v53
	ds_bpermute_b32 v81, v132, v49
	v_cndmask_b32_e64 v48, v79, v75, s[2:3]
	v_cvt_pk_bf16_f32 v52, v50, v52
	ds_bpermute_b32 v80, v132, v48
	v_accvgpr_read_b32 v197, a144
	v_accvgpr_read_b32 v196, a145
	v_cndmask_b32_e64 v51, v58, v53, s[2:3]
	v_mul_f32_e32 v68, 0xbfb8aa3b, v197
	v_accvgpr_read_b32 v195, a146
	ds_bpermute_b32 v54, v132, v51
	s_waitcnt lgkmcnt(2)
	v_cndmask_b32_e64 v51, v74, v81, s[2:3]
	v_exp_f32_e32 v74, v68
	v_mul_f32_e32 v68, 0xbfb8aa3b, v196
	v_cndmask_b32_e64 v50, v59, v52, s[2:3]
	v_exp_f32_e32 v76, v68
	v_mul_f32_e32 v68, 0xbfb8aa3b, v195
	ds_bpermute_b32 v55, v132, v50
	s_waitcnt lgkmcnt(2)
	v_cndmask_b32_e64 v50, v75, v80, s[2:3]
	v_exp_f32_e32 v75, v68
	v_accvgpr_read_b32 v32, a144
	v_accvgpr_read_b32 v34, a146
	v_accvgpr_read_b32 v194, a147
	v_pk_add_f32 v[74:75], v[74:75], 1.0 op_sel_hi:[1,0]
	v_mul_f32_e32 v68, 0xbfb8aa3b, v194
	v_rcp_f32_e32 v84, v75
	v_exp_f32_e32 v77, v68
	v_add_u32_e32 v100, 64, v133
	v_accvgpr_read_b32 v35, a147
	v_rcp_f32_e32 v88, v74
	v_mul_f32_e32 v75, v34, v84
	v_mad_i64_i32 v[100:101], s[4:5], v100, s1, v[128:129]
	v_pk_add_f32 v[76:77], v[76:77], 1.0 op_sel_hi:[1,0]
	v_lshl_add_u64 v[100:101], v[100:101], 0, v[130:131]
	v_mul_f32_e32 v74, v32, v88
	v_lshl_add_u64 v[64:65], v[100:101], 0, v[192:193]
	v_cndmask_b32_e64 v49, v81, v78, s[2:3]
	v_cndmask_b32_e64 v48, v80, v79, s[2:3]
	v_rcp_f32_e32 v34, v77
	global_store_dwordx4 v[64:65], v[48:51], off
	v_accvgpr_read_b32 v33, a145
	v_accvgpr_read_b32 v191, a148
	s_waitcnt lgkmcnt(1)
	v_cndmask_b32_e64 v49, v54, v58, s[2:3]
	s_waitcnt lgkmcnt(0)
	v_cndmask_b32_e64 v48, v55, v59, s[2:3]
	v_cndmask_b32_e64 v51, v53, v54, s[2:3]
	v_cndmask_b32_e64 v50, v52, v55, s[2:3]
	global_store_dwordx4 v[64:65], v[48:51], off offset:16
	v_accvgpr_read_b32 v63, a47
	v_accvgpr_read_b32 v190, a149
	v_accvgpr_read_b32 v48, a32
	v_mov_b32_e32 v84, v48
	v_accvgpr_read_b32 v50, a34
	v_mov_b32_e32 v85, v50
	v_rcp_f32_e32 v69, v76
	v_mul_f32_e32 v68, 0xbfb8aa3b, v191
	v_mul_f32_e32 v35, v35, v34
	v_accvgpr_read_b32 v189, a150
	v_exp_f32_e32 v78, v68
	v_mul_f32_e32 v68, 0xbfb8aa3b, v190
	v_accvgpr_read_b32 v188, a151
	v_exp_f32_e32 v72, v68
	v_mul_f32_e32 v68, 0xbfb8aa3b, v189
	v_accvgpr_read_b32 v187, a152
	v_exp_f32_e32 v79, v68
	v_mul_f32_e32 v68, 0xbfb8aa3b, v188
	v_accvgpr_read_b32 v186, a153
	v_exp_f32_e32 v73, v68
	v_mul_f32_e32 v68, 0xbfb8aa3b, v187
	v_accvgpr_read_b32 v185, a154
	v_exp_f32_e32 v80, v68
	v_mul_f32_e32 v68, 0xbfb8aa3b, v186
	v_accvgpr_read_b32 v49, a33
	v_exp_f32_e32 v82, v68
	v_mul_f32_e32 v68, 0xbfb8aa3b, v185
	v_accvgpr_read_b32 v51, a35
	v_exp_f32_e32 v81, v68
	v_mul_f32_e32 v34, v33, v69
	v_mov_b32_e32 v50, v49
	v_pk_mul_f32 v[32:33], v[34:35], v[50:51]
	v_accvgpr_read_b32 v42, a154
	v_and_b32_sdwa v48, v33, v218 dst_sel:DWORD dst_unused:UNUSED_PAD src0_sel:WORD_1 src1_sel:DWORD
	v_and_b32_sdwa v49, v32, v218 dst_sel:DWORD dst_unused:UNUSED_PAD src0_sel:WORD_1 src1_sel:DWORD
	v_add3_u32 v33, v33, v48, s80
	v_add3_u32 v48, v32, v49, s80
	v_and_b32_e32 v49, 0xffff0000, v33
	v_pk_add_f32 v[32:33], v[80:81], 1.0 op_sel_hi:[1,0]
	v_pk_mul_f32 v[74:75], v[74:75], v[84:85]
	v_rcp_f32_e32 v51, v33
	v_and_b32_sdwa v34, v75, v218 dst_sel:DWORD dst_unused:UNUSED_PAD src0_sel:WORD_1 src1_sel:DWORD
	v_and_b32_sdwa v35, v74, v218 dst_sel:DWORD dst_unused:UNUSED_PAD src0_sel:WORD_1 src1_sel:DWORD
	v_add3_u32 v34, v75, v34, s80
	v_add3_u32 v35, v74, v35, s80
	v_or_b32_sdwa v74, v49, v34 dst_sel:DWORD dst_unused:UNUSED_PAD src0_sel:DWORD src1_sel:WORD_1
	v_and_b32_e32 v48, 0xffff0000, v48
	v_or_b32_sdwa v75, v48, v35 dst_sel:DWORD dst_unused:UNUSED_PAD src0_sel:DWORD src1_sel:WORD_1
	v_accvgpr_read_b32 v40, a152
	v_rcp_f32_e32 v49, v32
	v_mul_f32_e32 v33, v42, v51
	v_accvgpr_read_b32 v184, a155
	v_mul_f32_e32 v68, 0xbfb8aa3b, v184
	v_exp_f32_e32 v83, v68
	v_accvgpr_read_b32 v43, a155
	v_mul_f32_e32 v32, v40, v49
	v_pk_add_f32 v[34:35], v[82:83], 1.0 op_sel_hi:[1,0]
	v_accvgpr_read_b32 v58, a42
	v_rcp_f32_e32 v42, v35
	v_accvgpr_read_b32 v56, a40
	v_mov_b32_e32 v48, v56
	v_mov_b32_e32 v49, v58
	v_pk_mul_f32 v[32:33], v[32:33], v[48:49]
	v_accvgpr_read_b32 v41, a153
	v_rcp_f32_e32 v50, v34
	v_mul_f32_e32 v35, v43, v42
	v_accvgpr_read_b32 v57, a41
	v_accvgpr_read_b32 v59, a43
	v_mul_f32_e32 v34, v41, v50
	v_mov_b32_e32 v58, v57
	v_pk_mul_f32 v[34:35], v[34:35], v[58:59]
	v_cvt_pk_bf16_f32 v48, v33, v35
	v_cvt_pk_bf16_f32 v49, v32, v34
	v_accvgpr_read_b32 v38, a150
	v_pk_add_f32 v[34:35], v[78:79], 1.0 op_sel_hi:[1,0]
	v_accvgpr_read_b32 v36, a148
	v_rcp_f32_e32 v41, v35
	v_accvgpr_read_b32 v39, a151
	v_accvgpr_read_b32 v54, a38
	v_accvgpr_read_b32 v52, a36
	v_rcp_f32_e32 v56, v34
	v_mul_f32_e32 v35, v38, v41
	v_mov_b32_e32 v43, v54
	v_pk_add_f32 v[40:41], v[72:73], 1.0 op_sel_hi:[1,0]
	v_mul_f32_e32 v34, v36, v56
	v_rcp_f32_e32 v38, v41
	v_mov_b32_e32 v42, v52
	v_pk_mul_f32 v[34:35], v[34:35], v[42:43]
	v_accvgpr_read_b32 v37, a149
	v_rcp_f32_e32 v52, v40
	v_mul_f32_e32 v39, v39, v38
	v_accvgpr_read_b32 v183, a156
	v_accvgpr_read_b32 v181, a158
	v_accvgpr_read_b32 v53, a37
	v_mul_f32_e32 v68, 0xbfb8aa3b, v183
	v_mul_f32_e32 v71, 0xbfb8aa3b, v181
	v_accvgpr_read_b32 v55, a39
	v_exp_f32_e32 v70, v68
	v_exp_f32_e32 v71, v71
	v_mul_f32_e32 v38, v37, v52
	v_mov_b32_e32 v54, v53
	v_pk_mul_f32 v[36:37], v[38:39], v[54:55]
	v_cvt_pk_bf16_f32 v43, v34, v36
	v_cvt_pk_bf16_f32 v42, v35, v37
	v_accvgpr_read_b32 v46, a158
	v_pk_add_f32 v[34:35], v[70:71], 1.0 op_sel_hi:[1,0]
	v_rcp_f32_e32 v41, v35
	v_accvgpr_read_b32 v44, a156
	v_rcp_f32_e32 v39, v34
	v_mul_f32_e32 v35, v46, v41
	v_accvgpr_read_b32 v182, a157
	v_accvgpr_read_b32 v180, a159
	v_mul_f32_e32 v68, 0xbfb8aa3b, v182
	v_mul_f32_e32 v86, 0xbfb8aa3b, v180
	v_exp_f32_e32 v68, v68
	v_exp_f32_e32 v69, v86
	v_accvgpr_read_b32 v47, a159
	v_mul_f32_e32 v34, v44, v39
	v_pk_add_f32 v[36:37], v[68:69], 1.0 op_sel_hi:[1,0]
	v_accvgpr_read_b32 v62, a46
	v_rcp_f32_e32 v41, v37
	v_accvgpr_read_b32 v60, a44
	v_mov_b32_e32 v38, v60
	v_mov_b32_e32 v39, v62
	v_pk_mul_f32 v[34:35], v[34:35], v[38:39]
	v_accvgpr_read_b32 v45, a157
	v_rcp_f32_e32 v44, v36
	v_mul_f32_e32 v37, v47, v41
	v_accvgpr_read_b32 v61, a45
	v_mul_f32_e32 v36, v45, v44
	v_mov_b32_e32 v62, v61
	v_cndmask_b32_e64 v33, v74, v48, s[2:3]
	v_pk_mul_f32 v[36:37], v[36:37], v[62:63]
	v_cvt_pk_bf16_f32 v37, v35, v37
	ds_bpermute_b32 v51, v132, v33
	v_accvgpr_read_b32 v179, a160
	v_cndmask_b32_e64 v35, v42, v37, s[2:3]
	v_accvgpr_read_b32 v178, a161
	ds_bpermute_b32 v38, v132, v35
	s_waitcnt lgkmcnt(1)
	v_cndmask_b32_e64 v35, v48, v51, s[2:3]
	v_mul_f32_e32 v48, 0xbfb8aa3b, v179
	v_accvgpr_read_b32 v177, a162
	v_exp_f32_e32 v54, v48
	v_mul_f32_e32 v48, 0xbfb8aa3b, v178
	v_cndmask_b32_e64 v32, v75, v49, s[2:3]
	v_cvt_pk_bf16_f32 v36, v34, v36
	v_exp_f32_e32 v56, v48
	v_mul_f32_e32 v48, 0xbfb8aa3b, v177
	ds_bpermute_b32 v50, v132, v32
	v_exp_f32_e32 v55, v48
	s_waitcnt vmcnt(6)
	v_accvgpr_read_b32 v16, a160
	v_accvgpr_read_b32 v18, a162
	v_cndmask_b32_e64 v34, v43, v36, s[2:3]
	v_pk_add_f32 v[54:55], v[54:55], 1.0 op_sel_hi:[1,0]
	ds_bpermute_b32 v39, v132, v34
	s_waitcnt lgkmcnt(1)
	v_cndmask_b32_e64 v34, v49, v50, s[2:3]
	v_rcp_f32_e32 v68, v55
	v_accvgpr_read_b32 v176, a163
	v_mul_f32_e32 v48, 0xbfb8aa3b, v176
	v_exp_f32_e32 v57, v48
	v_rcp_f32_e32 v72, v54
	v_mul_f32_e32 v55, v18, v68
	v_accvgpr_read_b32 v19, a163
	v_pk_add_f32 v[56:57], v[56:57], 1.0 op_sel_hi:[1,0]
	v_mul_f32_e32 v54, v16, v72
	v_cndmask_b32_e64 v33, v51, v74, s[2:3]
	v_cndmask_b32_e64 v32, v50, v75, s[2:3]
	v_rcp_f32_e32 v18, v57
	global_store_dwordx4 v[96:97], v[32:35], off offset:64
	v_accvgpr_read_b32 v17, a161
	v_accvgpr_read_b32 v175, a164
	v_cndmask_b32_e64 v33, v38, v42, s[2:3]
	s_waitcnt lgkmcnt(0)
	v_cndmask_b32_e64 v32, v39, v43, s[2:3]
	v_cndmask_b32_e64 v35, v37, v38, s[2:3]
	v_cndmask_b32_e64 v34, v36, v39, s[2:3]
	global_store_dwordx4 v[96:97], v[32:35], off offset:80
	v_accvgpr_read_b32 v47, a31
	v_accvgpr_read_b32 v174, a165
	v_accvgpr_read_b32 v32, a16
	v_mov_b32_e32 v68, v32
	v_accvgpr_read_b32 v34, a18
	v_mov_b32_e32 v69, v34
	v_rcp_f32_e32 v49, v56
	v_mul_f32_e32 v48, 0xbfb8aa3b, v175
	v_mul_f32_e32 v19, v19, v18
	v_accvgpr_read_b32 v173, a166
	v_exp_f32_e32 v58, v48
	v_mul_f32_e32 v48, 0xbfb8aa3b, v174
	v_accvgpr_read_b32 v172, a167
	v_exp_f32_e32 v52, v48
	v_mul_f32_e32 v48, 0xbfb8aa3b, v173
	v_accvgpr_read_b32 v171, a168
	v_exp_f32_e32 v59, v48
	v_mul_f32_e32 v48, 0xbfb8aa3b, v172
	v_accvgpr_read_b32 v170, a169
	v_exp_f32_e32 v53, v48
	v_mul_f32_e32 v48, 0xbfb8aa3b, v171
	v_accvgpr_read_b32 v169, a170
	v_exp_f32_e32 v60, v48
	v_mul_f32_e32 v48, 0xbfb8aa3b, v170
	v_accvgpr_read_b32 v33, a17
	v_exp_f32_e32 v62, v48
	v_mul_f32_e32 v48, 0xbfb8aa3b, v169
	v_accvgpr_read_b32 v35, a19
	v_exp_f32_e32 v61, v48
	v_mul_f32_e32 v18, v17, v49
	v_mov_b32_e32 v34, v33
	v_pk_mul_f32 v[16:17], v[18:19], v[34:35]
	v_accvgpr_read_b32 v26, a170
	v_and_b32_sdwa v32, v17, v218 dst_sel:DWORD dst_unused:UNUSED_PAD src0_sel:WORD_1 src1_sel:DWORD
	v_and_b32_sdwa v33, v16, v218 dst_sel:DWORD dst_unused:UNUSED_PAD src0_sel:WORD_1 src1_sel:DWORD
	v_add3_u32 v17, v17, v32, s80
	v_add3_u32 v32, v16, v33, s80
	v_and_b32_e32 v33, 0xffff0000, v17
	v_pk_add_f32 v[16:17], v[60:61], 1.0 op_sel_hi:[1,0]
	v_pk_mul_f32 v[54:55], v[54:55], v[68:69]
	v_rcp_f32_e32 v35, v17
	v_and_b32_sdwa v18, v55, v218 dst_sel:DWORD dst_unused:UNUSED_PAD src0_sel:WORD_1 src1_sel:DWORD
	v_and_b32_sdwa v19, v54, v218 dst_sel:DWORD dst_unused:UNUSED_PAD src0_sel:WORD_1 src1_sel:DWORD
	v_add3_u32 v18, v55, v18, s80
	v_add3_u32 v19, v54, v19, s80
	v_or_b32_sdwa v54, v33, v18 dst_sel:DWORD dst_unused:UNUSED_PAD src0_sel:DWORD src1_sel:WORD_1
	v_and_b32_e32 v32, 0xffff0000, v32
	v_or_b32_sdwa v55, v32, v19 dst_sel:DWORD dst_unused:UNUSED_PAD src0_sel:DWORD src1_sel:WORD_1
	v_accvgpr_read_b32 v24, a168
	v_rcp_f32_e32 v33, v16
	v_mul_f32_e32 v17, v26, v35
	v_accvgpr_read_b32 v168, a171
	v_mul_f32_e32 v48, 0xbfb8aa3b, v168
	v_exp_f32_e32 v63, v48
	v_accvgpr_read_b32 v27, a171
	v_mul_f32_e32 v16, v24, v33
	v_pk_add_f32 v[18:19], v[62:63], 1.0 op_sel_hi:[1,0]
	v_accvgpr_read_b32 v42, a26
	v_rcp_f32_e32 v26, v19
	v_accvgpr_read_b32 v40, a24
	v_mov_b32_e32 v32, v40
	v_mov_b32_e32 v33, v42
	v_pk_mul_f32 v[16:17], v[16:17], v[32:33]
	v_accvgpr_read_b32 v25, a169
	v_rcp_f32_e32 v34, v18
	v_mul_f32_e32 v19, v27, v26
	v_accvgpr_read_b32 v41, a25
	v_accvgpr_read_b32 v43, a27
	v_mul_f32_e32 v18, v25, v34
	v_mov_b32_e32 v42, v41
	v_pk_mul_f32 v[18:19], v[18:19], v[42:43]
	v_cvt_pk_bf16_f32 v32, v17, v19
	v_cvt_pk_bf16_f32 v33, v16, v18
	v_accvgpr_read_b32 v22, a166
	v_pk_add_f32 v[18:19], v[58:59], 1.0 op_sel_hi:[1,0]
	v_accvgpr_read_b32 v20, a164
	v_rcp_f32_e32 v25, v19
	v_accvgpr_read_b32 v23, a167
	v_accvgpr_read_b32 v38, a22
	v_accvgpr_read_b32 v36, a20
	v_rcp_f32_e32 v40, v18
	v_mul_f32_e32 v19, v22, v25
	v_mov_b32_e32 v27, v38
	v_pk_add_f32 v[24:25], v[52:53], 1.0 op_sel_hi:[1,0]
	v_mul_f32_e32 v18, v20, v40
	v_rcp_f32_e32 v22, v25
	v_mov_b32_e32 v26, v36
	v_pk_mul_f32 v[18:19], v[18:19], v[26:27]
	v_accvgpr_read_b32 v21, a165
	v_rcp_f32_e32 v36, v24
	v_mul_f32_e32 v23, v23, v22
	v_accvgpr_read_b32 v167, a172
	v_accvgpr_read_b32 v165, a174
	v_accvgpr_read_b32 v37, a21
	v_mul_f32_e32 v48, 0xbfb8aa3b, v167
	v_mul_f32_e32 v51, 0xbfb8aa3b, v165
	v_accvgpr_read_b32 v39, a23
	v_exp_f32_e32 v50, v48
	v_exp_f32_e32 v51, v51
	v_mul_f32_e32 v22, v21, v36
	v_mov_b32_e32 v38, v37
	v_pk_mul_f32 v[20:21], v[22:23], v[38:39]
	v_cvt_pk_bf16_f32 v27, v18, v20
	v_cvt_pk_bf16_f32 v26, v19, v21
	v_accvgpr_read_b32 v30, a174
	v_pk_add_f32 v[18:19], v[50:51], 1.0 op_sel_hi:[1,0]
	v_rcp_f32_e32 v25, v19
	v_accvgpr_read_b32 v28, a172
	v_rcp_f32_e32 v23, v18
	v_mul_f32_e32 v19, v30, v25
	v_accvgpr_read_b32 v166, a173
	v_accvgpr_read_b32 v164, a175
	v_mul_f32_e32 v48, 0xbfb8aa3b, v166
	v_mul_f32_e32 v70, 0xbfb8aa3b, v164
	v_exp_f32_e32 v48, v48
	v_exp_f32_e32 v49, v70
	v_accvgpr_read_b32 v31, a175
	v_mul_f32_e32 v18, v28, v23
	v_pk_add_f32 v[20:21], v[48:49], 1.0 op_sel_hi:[1,0]
	v_accvgpr_read_b32 v46, a30
	v_rcp_f32_e32 v25, v21
	v_accvgpr_read_b32 v44, a28
	v_mov_b32_e32 v22, v44
	v_mov_b32_e32 v23, v46
	v_pk_mul_f32 v[18:19], v[18:19], v[22:23]
	v_accvgpr_read_b32 v29, a173
	v_rcp_f32_e32 v28, v20
	v_mul_f32_e32 v21, v31, v25
	v_accvgpr_read_b32 v45, a29
	v_mul_f32_e32 v20, v29, v28
	v_mov_b32_e32 v46, v45
	v_cndmask_b32_e64 v17, v54, v32, s[2:3]
	v_pk_mul_f32 v[20:21], v[20:21], v[46:47]
	v_cvt_pk_bf16_f32 v21, v19, v21
	ds_bpermute_b32 v35, v132, v17
	v_accvgpr_read_b32 v159, a176
	v_cndmask_b32_e64 v19, v26, v21, s[2:3]
	v_accvgpr_read_b32 v158, a177
	ds_bpermute_b32 v22, v132, v19
	s_waitcnt lgkmcnt(1)
	v_cndmask_b32_e64 v19, v32, v35, s[2:3]
	v_mul_f32_e32 v32, 0xbfb8aa3b, v159
	v_accvgpr_read_b32 v157, a178
	v_exp_f32_e32 v38, v32
	v_mul_f32_e32 v32, 0xbfb8aa3b, v158
	v_cndmask_b32_e64 v16, v55, v33, s[2:3]
	v_cvt_pk_bf16_f32 v20, v18, v20
	v_exp_f32_e32 v40, v32
	v_mul_f32_e32 v32, 0xbfb8aa3b, v157
	ds_bpermute_b32 v34, v132, v16
	v_exp_f32_e32 v39, v32
	v_accvgpr_read_b32 v0, a176
	v_accvgpr_read_b32 v2, a178
	v_cndmask_b32_e64 v18, v27, v20, s[2:3]
	v_pk_add_f32 v[38:39], v[38:39], 1.0 op_sel_hi:[1,0]
	ds_bpermute_b32 v23, v132, v18
	s_waitcnt lgkmcnt(1)
	v_cndmask_b32_e64 v18, v33, v34, s[2:3]
	v_rcp_f32_e32 v48, v39
	v_accvgpr_read_b32 v156, a179
	v_mul_f32_e32 v32, 0xbfb8aa3b, v156
	v_exp_f32_e32 v41, v32
	v_rcp_f32_e32 v52, v38
	v_mul_f32_e32 v39, v2, v48
	v_accvgpr_read_b32 v3, a179
	v_pk_add_f32 v[40:41], v[40:41], 1.0 op_sel_hi:[1,0]
	v_mul_f32_e32 v38, v0, v52
	v_cndmask_b32_e64 v17, v35, v54, s[2:3]
	v_cndmask_b32_e64 v16, v34, v55, s[2:3]
	v_rcp_f32_e32 v2, v41
	global_store_dwordx4 v[66:67], v[16:19], off offset:64
	v_accvgpr_read_b32 v1, a177
	v_accvgpr_read_b32 v155, a180
	v_cndmask_b32_e64 v17, v22, v26, s[2:3]
	s_waitcnt lgkmcnt(0)
	v_cndmask_b32_e64 v16, v23, v27, s[2:3]
	v_cndmask_b32_e64 v19, v21, v22, s[2:3]
	v_cndmask_b32_e64 v18, v20, v23, s[2:3]
	global_store_dwordx4 v[66:67], v[16:19], off offset:80
	v_accvgpr_read_b32 v31, a15
	v_accvgpr_read_b32 v154, a181
	v_accvgpr_read_b32 v16, a0
	v_mov_b32_e32 v48, v16
	v_accvgpr_read_b32 v18, a2
	v_mov_b32_e32 v49, v18
	v_rcp_f32_e32 v33, v40
	v_mul_f32_e32 v32, 0xbfb8aa3b, v155
	v_mul_f32_e32 v3, v3, v2
	v_accvgpr_read_b32 v153, a182
	v_exp_f32_e32 v42, v32
	v_mul_f32_e32 v32, 0xbfb8aa3b, v154
	v_accvgpr_read_b32 v152, a183
	v_exp_f32_e32 v36, v32
	v_mul_f32_e32 v32, 0xbfb8aa3b, v153
	v_accvgpr_read_b32 v151, a184
	v_exp_f32_e32 v43, v32
	v_mul_f32_e32 v32, 0xbfb8aa3b, v152
	v_accvgpr_read_b32 v150, a185
	v_exp_f32_e32 v37, v32
	v_mul_f32_e32 v32, 0xbfb8aa3b, v151
	v_accvgpr_read_b32 v149, a186
	v_exp_f32_e32 v44, v32
	v_mul_f32_e32 v32, 0xbfb8aa3b, v150
	v_accvgpr_read_b32 v17, a1
	v_exp_f32_e32 v46, v32
	v_mul_f32_e32 v32, 0xbfb8aa3b, v149
	v_accvgpr_read_b32 v19, a3
	v_exp_f32_e32 v45, v32
	v_mul_f32_e32 v2, v1, v33
	v_mov_b32_e32 v18, v17
	v_pk_mul_f32 v[0:1], v[2:3], v[18:19]
	v_accvgpr_read_b32 v10, a186
	v_and_b32_sdwa v16, v1, v218 dst_sel:DWORD dst_unused:UNUSED_PAD src0_sel:WORD_1 src1_sel:DWORD
	v_and_b32_sdwa v17, v0, v218 dst_sel:DWORD dst_unused:UNUSED_PAD src0_sel:WORD_1 src1_sel:DWORD
	v_add3_u32 v1, v1, v16, s80
	v_add3_u32 v16, v0, v17, s80
	v_and_b32_e32 v17, 0xffff0000, v1
	v_pk_add_f32 v[0:1], v[44:45], 1.0 op_sel_hi:[1,0]
	v_pk_mul_f32 v[38:39], v[38:39], v[48:49]
	v_rcp_f32_e32 v19, v1
	v_and_b32_sdwa v2, v39, v218 dst_sel:DWORD dst_unused:UNUSED_PAD src0_sel:WORD_1 src1_sel:DWORD
	v_and_b32_sdwa v3, v38, v218 dst_sel:DWORD dst_unused:UNUSED_PAD src0_sel:WORD_1 src1_sel:DWORD
	v_add3_u32 v2, v39, v2, s80
	v_add3_u32 v3, v38, v3, s80
	v_or_b32_sdwa v38, v17, v2 dst_sel:DWORD dst_unused:UNUSED_PAD src0_sel:DWORD src1_sel:WORD_1
	v_and_b32_e32 v16, 0xffff0000, v16
	v_or_b32_sdwa v39, v16, v3 dst_sel:DWORD dst_unused:UNUSED_PAD src0_sel:DWORD src1_sel:WORD_1
	v_accvgpr_read_b32 v8, a184
	v_rcp_f32_e32 v17, v0
	v_mul_f32_e32 v1, v10, v19
	v_accvgpr_read_b32 v148, a187
	v_mul_f32_e32 v32, 0xbfb8aa3b, v148
	v_exp_f32_e32 v47, v32
	v_accvgpr_read_b32 v11, a187
	v_mul_f32_e32 v0, v8, v17
	v_pk_add_f32 v[2:3], v[46:47], 1.0 op_sel_hi:[1,0]
	v_accvgpr_read_b32 v26, a10
	v_rcp_f32_e32 v10, v3
	v_accvgpr_read_b32 v24, a8
	v_mov_b32_e32 v16, v24
	v_mov_b32_e32 v17, v26
	v_pk_mul_f32 v[0:1], v[0:1], v[16:17]
	v_accvgpr_read_b32 v9, a185
	v_rcp_f32_e32 v18, v2
	v_mul_f32_e32 v3, v11, v10
	v_accvgpr_read_b32 v25, a9
	v_accvgpr_read_b32 v27, a11
	v_mul_f32_e32 v2, v9, v18
	v_mov_b32_e32 v26, v25
	v_pk_mul_f32 v[2:3], v[2:3], v[26:27]
	v_cvt_pk_bf16_f32 v16, v1, v3
	v_cvt_pk_bf16_f32 v17, v0, v2
	v_accvgpr_read_b32 v6, a182
	v_pk_add_f32 v[2:3], v[42:43], 1.0 op_sel_hi:[1,0]
	v_accvgpr_read_b32 v4, a180
	v_rcp_f32_e32 v9, v3
	v_accvgpr_read_b32 v7, a183
	v_accvgpr_read_b32 v22, a6
	v_accvgpr_read_b32 v20, a4
	v_rcp_f32_e32 v24, v2
	v_mul_f32_e32 v3, v6, v9
	v_mov_b32_e32 v11, v22
	v_pk_add_f32 v[8:9], v[36:37], 1.0 op_sel_hi:[1,0]
	v_mul_f32_e32 v2, v4, v24
	v_rcp_f32_e32 v6, v9
	v_mov_b32_e32 v10, v20
	v_pk_mul_f32 v[2:3], v[2:3], v[10:11]
	v_accvgpr_read_b32 v5, a181
	v_rcp_f32_e32 v20, v8
	v_mul_f32_e32 v7, v7, v6
	v_accvgpr_read_b32 v147, a188
	v_accvgpr_read_b32 v145, a190
	v_accvgpr_read_b32 v21, a5
	v_mul_f32_e32 v32, 0xbfb8aa3b, v147
	v_mul_f32_e32 v35, 0xbfb8aa3b, v145
	v_accvgpr_read_b32 v23, a7
	v_exp_f32_e32 v34, v32
	v_exp_f32_e32 v35, v35
	v_mul_f32_e32 v6, v5, v20
	v_mov_b32_e32 v22, v21
	v_pk_mul_f32 v[4:5], v[6:7], v[22:23]
	v_cvt_pk_bf16_f32 v11, v2, v4
	v_cvt_pk_bf16_f32 v10, v3, v5
	v_accvgpr_read_b32 v14, a190
	v_pk_add_f32 v[2:3], v[34:35], 1.0 op_sel_hi:[1,0]
	v_rcp_f32_e32 v9, v3
	v_accvgpr_read_b32 v12, a188
	v_rcp_f32_e32 v7, v2
	v_mul_f32_e32 v3, v14, v9
	v_accvgpr_read_b32 v146, a189
	v_accvgpr_read_b32 v144, a191
	v_mul_f32_e32 v32, 0xbfb8aa3b, v146
	v_mul_f32_e32 v50, 0xbfb8aa3b, v144
	v_exp_f32_e32 v32, v32
	v_exp_f32_e32 v33, v50
	v_accvgpr_read_b32 v15, a191
	v_mul_f32_e32 v2, v12, v7
	v_pk_add_f32 v[4:5], v[32:33], 1.0 op_sel_hi:[1,0]
	v_accvgpr_read_b32 v30, a14
	v_rcp_f32_e32 v9, v5
	v_accvgpr_read_b32 v28, a12
	v_mov_b32_e32 v6, v28
	v_mov_b32_e32 v7, v30
	v_pk_mul_f32 v[2:3], v[2:3], v[6:7]
	v_accvgpr_read_b32 v13, a189
	v_rcp_f32_e32 v12, v4
	v_mul_f32_e32 v5, v15, v9
	v_accvgpr_read_b32 v29, a13
	v_mul_f32_e32 v4, v13, v12
	v_mov_b32_e32 v30, v29
	v_pk_mul_f32 v[4:5], v[4:5], v[30:31]
	v_cvt_pk_bf16_f32 v5, v3, v5
	v_cvt_pk_bf16_f32 v4, v2, v4
	v_cndmask_b32_e64 v0, v39, v17, s[2:3]
	v_cndmask_b32_e64 v1, v38, v16, s[2:3]
	ds_bpermute_b32 v18, v132, v0
	ds_bpermute_b32 v19, v132, v1
	v_cndmask_b32_e64 v2, v11, v4, s[2:3]
	v_cndmask_b32_e64 v3, v10, v5, s[2:3]
	ds_bpermute_b32 v6, v132, v3
	ds_bpermute_b32 v7, v132, v2
	v_readlane_b32 s1, v255, 6
	v_mov_b32_e32 v229, 0x4000
	s_waitcnt lgkmcnt(2)
	v_cndmask_b32_e64 v1, v19, v38, s[2:3]
	v_cndmask_b32_e64 v0, v18, v39, s[2:3]
	v_cndmask_b32_e64 v3, v16, v19, s[2:3]
	v_cndmask_b32_e64 v2, v17, v18, s[2:3]
	s_add_i32 s0, s0, s1
	v_readlane_b32 s1, v254, 40
	global_store_dwordx4 v[64:65], v[0:3], off offset:64
	s_cmp_ge_i32 s0, s1
	v_mov_b32_e32 v214, v229
	s_waitcnt lgkmcnt(1)
	v_cndmask_b32_e64 v1, v6, v10, s[2:3]
	s_waitcnt lgkmcnt(0)
	v_cndmask_b32_e64 v0, v7, v11, s[2:3]
	v_cndmask_b32_e64 v3, v5, v6, s[2:3]
	v_cndmask_b32_e64 v2, v4, v7, s[2:3]
	global_store_dwordx4 v[64:65], v[0:3], off offset:80
	s_cbranch_scc1 .LBB0_166
.LBB0_161:
	s_abs_i32 s2, s0
	v_readlane_b32 s3, v254, 44
	s_mul_hi_u32 s3, s2, s3
	v_readlane_b32 s6, v254, 43
	s_mul_i32 s4, s3, s6
	s_sub_i32 s2, s2, s4
	s_ashr_i32 s1, s0, 31
	s_add_i32 s4, s3, 1
	s_sub_i32 s5, s2, s6
	s_cmp_ge_u32 s2, s6
	s_cselect_b32 s3, s4, s3
	s_cselect_b32 s2, s5, s2
	s_add_i32 s4, s3, 1
	s_cmp_ge_u32 s2, s6
	s_cselect_b32 s2, s4, s3
	s_xor_b32 s2, s2, s1
	s_sub_i32 s1, s2, s1
	s_lshr_b32 s2, s0, 31
	s_add_i32 s2, s0, s2
	s_ashr_i32 s3, s2, 1
	s_abs_i32 s3, s3
	v_readlane_b32 s5, v254, 46
	s_mul_hi_u32 s5, s3, s5
	v_readlane_b32 s6, v254, 45
	s_mul_i32 s5, s5, s6
	s_and_b32 s4, s2, 0xfffffe
	s_sub_i32 s3, s3, s5
	s_sub_i32 s4, s0, s4
	s_ashr_i32 s2, s2, 31
	s_sub_i32 s5, s3, s6
	s_cmp_ge_u32 s3, s6
	s_cselect_b32 s3, s5, s3
	s_sub_i32 s5, s3, s6
	s_cmp_ge_u32 s3, s6
	s_cselect_b32 s3, s5, s3
	s_xor_b32 s3, s3, s2
	s_sub_i32 s2, s3, s2
	v_readlane_b32 s3, v254, 39
	s_add_i32 s2, s3, s2
	s_lshl_b32 s1, s1, 9
	s_lshl_b32 s3, s4, 8
	s_waitcnt vmcnt(2)
	v_mov_b32_e32 v160, v208
	s_add_i32 s1, s1, s3
	v_readlane_b32 s4, v253, 30
	v_ashrrev_i32_e32 v4, 2, v160
	v_add_u32_e32 v0, s1, v4
	v_ashrrev_i32_e32 v1, 31, v0
	v_lshlrev_b64 v[0:1], 11, v[0:1]
	v_readlane_b32 s5, v253, 31
	v_lshlrev_b32_e32 v5, 4, v160
	s_mulk_i32 s2, 0xc0
	v_lshl_add_u64 v[0:1], s[4:5], 0, v[0:1]
	v_and_b32_e32 v192, 48, v5
	v_lshl_add_u64 v[96:97], v[0:1], 0, v[192:193]
	v_add_u32_e32 v0, s2, v4
	v_ashrrev_i32_e32 v1, 31, v0
	v_readlane_b32 s4, v253, 16
	s_mov_b32 s3, 0x20000
	v_lshlrev_b64 v[0:1], 11, v[0:1]
	v_readlane_b32 s5, v253, 17
	v_add_co_u32_e32 v8, vcc, s3, v96
	s_nop 0
	v_lshl_add_u64 v[0:1], s[4:5], 0, v[0:1]
	v_addc_co_u32_e32 v9, vcc, 0, v97, vcc
	s_mov_b32 s4, 0x40000
	v_add_co_u32_e32 v12, vcc, s4, v96
	v_lshl_add_u64 v[98:99], v[0:1], 0, v[192:193]
	s_nop 0
	v_addc_co_u32_e32 v13, vcc, 0, v97, vcc
	v_add_co_u32_e32 v16, vcc, s75, v96
	v_bfe_u32 v6, v160, 5, 1
	s_nop 0
	v_addc_co_u32_e32 v17, vcc, 0, v97, vcc
	v_lshrrev_b32_e32 v7, 2, v160
	v_bfe_u32 v10, v160, 2, 2
	v_add_co_u32_e32 v24, vcc, s3, v98
	v_lshlrev_b32_e32 v11, 1, v160
	v_bitop3_b32 v7, v6, v7, 3 bitop3:0x78
	v_bitop3_b32 v6, v6, v10, 2 bitop3:0x36
	v_and_b32_e32 v10, 0xffffffe0, v4
	v_addc_co_u32_e32 v25, vcc, 0, v99, vcc
	v_and_b32_e32 v161, 31, v160
	s_waitcnt vmcnt(1)
	v_and_b32_e32 v162, 0x80, v11
	v_lshl_add_u32 v163, v10, 1, v10
	v_add_co_u32_e32 v28, vcc, s4, v98
	v_or_b32_e32 v11, v162, v161
	v_or_b32_e32 v10, v163, v161
	global_load_dwordx4 v[0:3], v[96:97], off
	global_load_dwordx4 v[32:35], v[8:9], off
	global_load_dwordx4 v[36:39], v[12:13], off
	global_load_dwordx4 v[40:43], v[16:17], off
	global_load_dwordx4 v[44:47], v[98:99], off
	v_addc_co_u32_e32 v29, vcc, 0, v99, vcc
	v_bitop3_b32 v5, v5, 48, v160 bitop3:0x48
	v_lshlrev_b32_e32 v11, 6, v11
	v_lshlrev_b32_e32 v7, 4, v7
	v_lshlrev_b32_e32 v6, 4, v6
	v_lshl_add_u32 v10, v10, 6, v214
	global_load_dwordx4 v[48:51], v[24:25], off
	global_load_dwordx4 v[52:55], v[28:29], off
	v_or_b32_e32 v110, v11, v7
	v_or_b32_e32 v111, v11, v6
	v_or_b32_e32 v116, v10, v7
	v_or_b32_e32 v117, v10, v6
	v_lshl_or_b32 v118, v4, 6, v5
	global_load_dwordx4 v[4:7], v[96:97], off offset:64
	s_nop 0
	global_load_dwordx4 v[8:11], v[8:9], off offset:64
	s_nop 0
	global_load_dwordx4 v[12:15], v[12:13], off offset:64
	s_nop 0
	global_load_dwordx4 v[16:19], v[16:17], off offset:64
	s_nop 0
	global_load_dwordx4 v[20:23], v[98:99], off offset:64
	s_nop 0
	global_load_dwordx4 v[24:27], v[24:25], off offset:64
	s_nop 0
	global_load_dwordx4 v[28:31], v[28:29], off offset:64
	v_accvgpr_mov_b32 a193, a192
	v_accvgpr_mov_b32 a194, a192
	v_accvgpr_mov_b32 a195, a192
	v_accvgpr_mov_b32 a196, a192
	v_accvgpr_mov_b32 a197, a192
	v_accvgpr_mov_b32 a198, a192
	v_accvgpr_mov_b32 a199, a192
	v_accvgpr_mov_b32 a200, a192
	v_accvgpr_mov_b32 a201, a192
	v_accvgpr_mov_b32 a202, a192
	v_accvgpr_mov_b32 a203, a192
	v_accvgpr_mov_b32 a204, a192
	v_accvgpr_mov_b32 a205, a192
	v_accvgpr_mov_b32 a206, a192
	v_accvgpr_mov_b32 a207, a192
	v_accvgpr_mov_b32 a0, a192
	v_accvgpr_mov_b32 a16, a192
	v_accvgpr_mov_b32 a32, a192
	v_accvgpr_write_b32 a95, 0
	v_accvgpr_write_b32 a94, 0
	v_accvgpr_write_b32 a93, 0
	v_accvgpr_write_b32 a92, 0
	v_accvgpr_write_b32 a91, 0
	v_accvgpr_write_b32 a90, 0
	v_accvgpr_write_b32 a89, 0
	v_accvgpr_write_b32 a88, 0
	v_accvgpr_write_b32 a87, 0
	v_accvgpr_write_b32 a86, 0
	v_accvgpr_write_b32 a85, 0
	v_accvgpr_write_b32 a84, 0
	v_accvgpr_write_b32 a83, 0
	v_accvgpr_write_b32 a82, 0
	v_accvgpr_write_b32 a81, 0
	v_accvgpr_write_b32 a80, 0
	v_accvgpr_write_b32 a63, 0
	v_accvgpr_write_b32 a62, 0
	v_accvgpr_write_b32 a61, 0
	v_accvgpr_write_b32 a60, 0
	v_accvgpr_write_b32 a59, 0
	v_accvgpr_write_b32 a58, 0
	v_accvgpr_write_b32 a57, 0
	v_accvgpr_write_b32 a56, 0
	v_accvgpr_write_b32 a55, 0
	v_accvgpr_write_b32 a54, 0
	v_accvgpr_write_b32 a53, 0
	v_accvgpr_write_b32 a52, 0
	v_accvgpr_write_b32 a51, 0
	v_accvgpr_write_b32 a50, 0
	v_accvgpr_write_b32 a49, 0
	v_accvgpr_write_b32 a48, 0
	v_accvgpr_write_b32 a79, 0
	v_accvgpr_write_b32 a78, 0
	v_accvgpr_write_b32 a77, 0
	v_accvgpr_write_b32 a76, 0
	v_accvgpr_write_b32 a75, 0
	v_accvgpr_write_b32 a74, 0
	v_accvgpr_write_b32 a73, 0
	v_accvgpr_write_b32 a72, 0
	v_accvgpr_write_b32 a71, 0
	v_accvgpr_write_b32 a70, 0
	v_accvgpr_write_b32 a69, 0
	v_accvgpr_write_b32 a68, 0
	v_accvgpr_write_b32 a67, 0
	v_accvgpr_write_b32 a66, 0
	v_accvgpr_write_b32 a65, 0
	v_accvgpr_write_b32 a64, 0
	v_accvgpr_write_b32 a111, 0
	v_accvgpr_write_b32 a110, 0
	v_accvgpr_write_b32 a109, 0
	v_accvgpr_write_b32 a108, 0
	v_accvgpr_write_b32 a107, 0
	v_accvgpr_write_b32 a106, 0
	v_accvgpr_write_b32 a105, 0
	v_accvgpr_write_b32 a104, 0
	v_accvgpr_write_b32 a103, 0
	v_accvgpr_write_b32 a102, 0
	v_accvgpr_write_b32 a101, 0
	v_accvgpr_write_b32 a100, 0
	v_accvgpr_write_b32 a99, 0
	v_accvgpr_write_b32 a98, 0
	v_accvgpr_write_b32 a97, 0
	v_accvgpr_write_b32 a96, 0
	v_accvgpr_write_b32 a127, 0
	v_accvgpr_write_b32 a126, 0
	v_accvgpr_write_b32 a125, 0
	v_accvgpr_write_b32 a124, 0
	v_accvgpr_write_b32 a123, 0
	v_accvgpr_write_b32 a122, 0
	v_accvgpr_write_b32 a121, 0
	v_accvgpr_write_b32 a120, 0
	v_accvgpr_write_b32 a119, 0
	v_accvgpr_write_b32 a118, 0
	v_accvgpr_write_b32 a117, 0
	v_accvgpr_write_b32 a116, 0
	v_accvgpr_write_b32 a115, 0
	v_accvgpr_write_b32 a114, 0
	v_accvgpr_write_b32 a113, 0
	v_accvgpr_write_b32 a112, 0
	v_accvgpr_write_b32 a143, 0
	v_accvgpr_write_b32 a142, 0
	v_accvgpr_write_b32 a141, 0
	v_accvgpr_write_b32 a140, 0
	v_accvgpr_write_b32 a139, 0
	v_accvgpr_write_b32 a138, 0
	v_accvgpr_write_b32 a137, 0
	v_accvgpr_write_b32 a136, 0
	v_accvgpr_write_b32 a135, 0
	v_accvgpr_write_b32 a134, 0
	v_accvgpr_write_b32 a133, 0
	v_accvgpr_write_b32 a132, 0
	v_accvgpr_write_b32 a131, 0
	v_accvgpr_write_b32 a130, 0
	v_accvgpr_write_b32 a129, 0
	v_accvgpr_write_b32 a128, 0
	v_accvgpr_write_b32 a159, 0
	v_accvgpr_write_b32 a158, 0
	v_accvgpr_write_b32 a157, 0
	v_accvgpr_write_b32 a156, 0
	v_accvgpr_write_b32 a155, 0
	v_accvgpr_write_b32 a154, 0
	v_accvgpr_write_b32 a153, 0
	v_accvgpr_write_b32 a152, 0
	v_accvgpr_write_b32 a151, 0
	v_accvgpr_write_b32 a150, 0
	v_accvgpr_write_b32 a149, 0
	v_accvgpr_write_b32 a148, 0
	v_accvgpr_write_b32 a147, 0
	v_accvgpr_write_b32 a146, 0
	v_accvgpr_write_b32 a145, 0
	v_accvgpr_write_b32 a144, 0
	v_accvgpr_write_b32 a175, 0
	v_accvgpr_write_b32 a174, 0
	v_accvgpr_write_b32 a173, 0
	v_accvgpr_write_b32 a172, 0
	v_accvgpr_write_b32 a171, 0
	v_accvgpr_write_b32 a170, 0
	v_accvgpr_write_b32 a169, 0
	v_accvgpr_write_b32 a168, 0
	v_accvgpr_write_b32 a167, 0
	v_accvgpr_write_b32 a166, 0
	v_accvgpr_write_b32 a165, 0
	v_accvgpr_write_b32 a164, 0
	v_accvgpr_write_b32 a163, 0
	v_accvgpr_write_b32 a162, 0
	v_accvgpr_write_b32 a161, 0
	v_accvgpr_write_b32 a160, 0
	v_accvgpr_write_b32 a191, 0
	v_accvgpr_write_b32 a190, 0
	v_accvgpr_write_b32 a189, 0
	v_accvgpr_write_b32 a188, 0
	v_accvgpr_write_b32 a187, 0
	v_accvgpr_write_b32 a186, 0
	v_accvgpr_write_b32 a185, 0
	v_accvgpr_write_b32 a184, 0
	v_accvgpr_write_b32 a183, 0
	v_accvgpr_write_b32 a182, 0
	v_accvgpr_write_b32 a181, 0
	v_accvgpr_write_b32 a180, 0
	v_accvgpr_write_b32 a179, 0
	v_accvgpr_write_b32 a178, 0
	v_accvgpr_write_b32 a177, 0
	v_accvgpr_write_b32 a176, 0
	v_accvgpr_mov_b32 a1, a193
	v_accvgpr_mov_b32 a2, a194
	v_accvgpr_mov_b32 a3, a195
	v_accvgpr_mov_b32 a4, a196
	v_accvgpr_mov_b32 a5, a197
	v_accvgpr_mov_b32 a6, a198
	v_accvgpr_mov_b32 a7, a199
	v_accvgpr_mov_b32 a8, a200
	v_accvgpr_mov_b32 a9, a201
	v_accvgpr_mov_b32 a10, a202
	v_accvgpr_mov_b32 a11, a203
	v_accvgpr_mov_b32 a12, a204
	v_accvgpr_mov_b32 a13, a205
	v_accvgpr_mov_b32 a14, a206
	v_accvgpr_mov_b32 a15, a207
	v_accvgpr_mov_b32 a17, a193
	v_accvgpr_mov_b32 a18, a194
	v_accvgpr_mov_b32 a19, a195
	v_accvgpr_mov_b32 a20, a196
	v_accvgpr_mov_b32 a21, a197
	v_accvgpr_mov_b32 a22, a198
	v_accvgpr_mov_b32 a23, a199
	v_accvgpr_mov_b32 a24, a200
	v_accvgpr_mov_b32 a25, a201
	v_accvgpr_mov_b32 a26, a202
	v_accvgpr_mov_b32 a27, a203
	v_accvgpr_mov_b32 a28, a204
	v_accvgpr_mov_b32 a29, a205
	v_accvgpr_mov_b32 a30, a206
	v_accvgpr_mov_b32 a31, a207
	v_accvgpr_mov_b32 a33, a193
	v_accvgpr_mov_b32 a34, a194
	v_accvgpr_mov_b32 a35, a195
	v_accvgpr_mov_b32 a36, a196
	v_accvgpr_mov_b32 a37, a197
	v_accvgpr_mov_b32 a38, a198
	v_accvgpr_mov_b32 a39, a199
	v_accvgpr_mov_b32 a40, a200
	v_accvgpr_mov_b32 a41, a201
	v_accvgpr_mov_b32 a42, a202
	v_accvgpr_mov_b32 a43, a203
	v_accvgpr_mov_b32 a44, a204
	v_accvgpr_mov_b32 a45, a205
	v_accvgpr_mov_b32 a46, a206
	v_accvgpr_mov_b32 a47, a207
	s_waitcnt vmcnt(13)
	ds_write_b128 v118, v[0:3] offset:0
	s_waitcnt vmcnt(12)
	ds_write_b128 v118, v[32:35] offset:0x1000
	s_waitcnt vmcnt(11)
	ds_write_b128 v118, v[36:39] offset:0x2000
	s_mov_b64 s[8:9], 0x20000
	s_mov_b64 s[6:7], 0x40000
	s_mov_b64 s[10:11], 0x60000
	s_waitcnt vmcnt(10)
	ds_write_b128 v118, v[40:43] offset:0x3000
	s_waitcnt vmcnt(9)
	ds_write_b128 v118, v[44:47] offset:0x4000
	s_waitcnt vmcnt(8)
	ds_write_b128 v118, v[48:51] offset:0x5000
	s_waitcnt vmcnt(7)
	ds_write_b128 v118, v[52:55] offset:0x6000
	s_waitcnt lgkmcnt(0)
	v_mov_b32_e32 v0, 0
	v_lshl_add_u64 v[100:101], v[96:97], 0, s[8:9]
	s_mov_b32 s4, 0
	v_lshl_add_u64 v[102:103], v[96:97], 0, s[6:7]
	v_lshl_add_u64 v[104:105], v[96:97], 0, s[10:11]
	v_lshl_add_u64 v[106:107], v[98:99], 0, s[8:9]
	v_lshl_add_u64 v[108:109], v[98:99], 0, s[6:7]
	s_mov_b32 s3, -2
	v_mov_b32_e32 v1, v0
	v_mov_b32_e32 v2, v0
	v_mov_b32_e32 v3, v0
	v_mov_b32_e32 v128, v0
	v_mov_b32_e32 v129, v0
	v_mov_b32_e32 v130, v0
	v_mov_b32_e32 v131, v0
	v_mov_b32_e32 v32, v0
	v_mov_b32_e32 v33, v0
	v_mov_b32_e32 v34, v0
	v_mov_b32_e32 v35, v0
	s_barrier

.LBB0_173:
	v_mov_b32_e32 v107, v193
	v_lshl_add_u64 v[28:29], v[0:1], 0, v[106:107]
	v_add_co_u32_e32 v4, vcc, 0x1000, v28
	v_min_i32_e32 v2, 0x4000, v104
	s_nop 0
	v_addc_co_u32_e32 v5, vcc, 0, v29, vcc
	v_ashrrev_i32_e32 v2, 13, v2
	v_add_co_u32_e32 v24, vcc, 0x2000, v28
	v_add_u32_e32 v2, s4, v2
	s_nop 0
	v_addc_co_u32_e32 v25, vcc, 0, v29, vcc
	v_mul_hi_i32_i24_e32 v123, 0x6000, v2
	v_mul_i32_i24_e32 v122, 0x6000, v2
	global_load_dwordx4 v[32:35], v[28:29], off nt
	global_load_dwordx4 v[16:19], v[28:29], off offset:1024 nt
	global_load_dwordx4 v[8:11], v[28:29], off offset:2048 nt
	global_load_dwordx4 v[0:3], v[28:29], off offset:3072 nt
	v_add_co_u32_e32 v28, vcc, 0x3000, v28
	v_lshlrev_b64 v[120:121], 11, v[104:105]
	s_nop 0
	v_addc_co_u32_e32 v29, vcc, 0, v29, vcc
	s_waitcnt vmcnt(4)
	v_lshl_add_u64 v[66:67], v[96:97], 0, v[120:121]
	global_load_dwordx4 v[36:39], v[4:5], off nt
	global_load_dwordx4 v[20:23], v[4:5], off offset:1024 nt
	global_load_dwordx4 v[12:15], v[4:5], off offset:2048 nt
	s_nop 0
	global_load_dwordx4 v[4:7], v[4:5], off offset:3072 nt
	s_nop 0
	global_load_dwordx4 v[60:63], v[24:25], off nt
	global_load_dwordx4 v[56:59], v[24:25], off offset:1024 nt
	global_load_dwordx4 v[40:43], v[24:25], off offset:2048 nt
	s_nop 0
	global_load_dwordx4 v[24:27], v[24:25], off offset:3072 nt
	s_nop 0
	global_load_dwordx4 v[52:55], v[28:29], off nt
	global_load_dwordx4 v[48:51], v[28:29], off offset:1024 nt
	global_load_dwordx4 v[44:47], v[28:29], off offset:2048 nt
	s_nop 0
	global_load_dwordx4 v[28:31], v[28:29], off offset:3072 nt
	s_nop 0
	global_load_dwordx2 v[72:73], v[66:67], off nt
	global_load_dwordx2 v[80:81], v[66:67], off offset:512 nt
	global_load_dwordx2 v[88:89], v[66:67], off offset:1024 nt
	global_load_dwordx2 v[126:127], v[66:67], off offset:1536 nt
	v_add_u32_e32 v66, 1, v104
	v_ashrrev_i32_e32 v67, 31, v66
	v_lshlrev_b64 v[118:119], 11, v[66:67]
	v_lshl_add_u64 v[66:67], v[96:97], 0, v[118:119]
	global_load_dwordx2 v[74:75], v[66:67], off nt
	global_load_dwordx2 v[82:83], v[66:67], off offset:512 nt
	global_load_dwordx2 v[90:91], v[66:67], off offset:1024 nt
	global_load_dwordx2 v[162:163], v[66:67], off offset:1536 nt
	v_add_u32_e32 v66, 2, v104
	v_ashrrev_i32_e32 v67, 31, v66
	v_lshlrev_b64 v[116:117], 11, v[66:67]
	v_lshl_add_u64 v[66:67], v[96:97], 0, v[116:117]
	global_load_dwordx2 v[76:77], v[66:67], off nt
	global_load_dwordx2 v[84:85], v[66:67], off offset:512 nt
	global_load_dwordx2 v[92:93], v[66:67], off offset:1024 nt
	global_load_dwordx2 v[132:133], v[66:67], off offset:1536 nt
	v_add_u32_e32 v66, 3, v104
	v_ashrrev_i32_e32 v67, 31, v66
	v_lshlrev_b64 v[114:115], 11, v[66:67]
	v_lshl_add_u64 v[66:67], v[96:97], 0, v[114:115]
	global_load_dwordx2 v[78:79], v[66:67], off nt
	global_load_dwordx2 v[86:87], v[66:67], off offset:512 nt
	global_load_dwordx2 v[178:179], v[66:67], off offset:1024 nt
	global_load_dwordx2 v[138:139], v[66:67], off offset:1536 nt
	v_lshl_add_u64 v[64:65], s[90:91], 0, v[122:123]
	v_lshl_add_u64 v[68:69], v[64:65], 0, v[106:107]
	s_mov_b64 s[0:1], 0x345a000
	v_lshl_add_u64 v[94:95], v[68:69], 0, s[0:1]
	s_mov_b32 s0, 0x345a000
	v_add_co_u32_e32 v68, vcc, s0, v68
	global_load_dwordx4 v[64:67], v[98:99], off
	s_nop 0
	v_addc_co_u32_e32 v69, vcc, 0, v69, vcc
	global_load_dwordx4 v[68:71], v[68:69], off
	s_mov_b32 s0, 0x358637bd
	s_mov_b32 s8, 0x3a800000
	s_mov_b32 s6, 0x800000
	v_mov_b32_e32 v111, v193
	v_mov_b32_e32 v113, v193
	s_add_i32 s5, s5, s93
	s_cmpk_gt_i32 s5, 0x3ff
	s_waitcnt vmcnt(17)
	v_and_b32_e32 v157, 0xffff0000, v72
	s_waitcnt vmcnt(16)
	v_and_b32_e32 v175, 0xffff0000, v80
	v_lshlrev_b32_e32 v156, 16, v72
	v_lshlrev_b32_e32 v174, 16, v80
	v_mov_b32_e32 v140, v157
	v_mov_b32_e32 v141, v175
	v_lshlrev_b32_e32 v168, 16, v73
	v_and_b32_e32 v177, 0xffff0000, v81
	v_lshlrev_b32_e32 v176, 16, v81
	v_mov_b32_e32 v80, v156
	v_mov_b32_e32 v81, v174
	v_pk_mul_f32 v[140:141], v[140:141], v[140:141]
	v_and_b32_e32 v169, 0xffff0000, v73
	s_waitcnt vmcnt(13)
	v_and_b32_e32 v165, 0xffff0000, v74
	v_pk_fma_f32 v[80:81], v[80:81], v[80:81], v[140:141]
	v_mov_b32_e32 v140, v168
	v_mov_b32_e32 v141, v176
	s_waitcnt vmcnt(12)
	v_and_b32_e32 v171, 0xffff0000, v82
	v_lshlrev_b32_e32 v164, 16, v74
	v_mov_b32_e32 v142, v169
	v_mov_b32_e32 v143, v177
	v_pk_fma_f32 v[80:81], v[140:141], v[140:141], v[80:81]
	v_lshlrev_b32_e32 v170, 16, v82
	v_and_b32_e32 v173, 0xffff0000, v83
	v_lshlrev_b32_e32 v172, 16, v83
	v_mov_b32_e32 v82, v165
	v_mov_b32_e32 v83, v171
	v_lshlrev_b32_e32 v166, 16, v75
	v_pk_fma_f32 v[188:189], v[142:143], v[142:143], v[80:81]
	v_mov_b32_e32 v80, v164
	v_mov_b32_e32 v81, v170
	v_pk_mul_f32 v[82:83], v[82:83], v[82:83]
	v_and_b32_e32 v167, 0xffff0000, v75
	s_waitcnt vmcnt(9)
	v_and_b32_e32 v137, 0xffff0000, v76
	v_pk_fma_f32 v[80:81], v[80:81], v[80:81], v[82:83]
	v_mov_b32_e32 v82, v166
	v_mov_b32_e32 v83, v172
	s_waitcnt vmcnt(8)
	v_and_b32_e32 v147, 0xffff0000, v84
	v_lshlrev_b32_e32 v136, 16, v76
	v_mov_b32_e32 v140, v167
	v_mov_b32_e32 v141, v173
	v_pk_fma_f32 v[80:81], v[82:83], v[82:83], v[80:81]
	v_lshlrev_b32_e32 v146, 16, v84
	v_mov_b32_e32 v82, v137
	v_mov_b32_e32 v83, v147
	v_lshlrev_b32_e32 v134, 16, v77
	v_pk_fma_f32 v[190:191], v[140:141], v[140:141], v[80:81]
	v_lshlrev_b32_e32 v144, 16, v85
	v_mov_b32_e32 v80, v136
	v_mov_b32_e32 v81, v146
	v_pk_mul_f32 v[82:83], v[82:83], v[82:83]
	v_and_b32_e32 v135, 0xffff0000, v77
	s_waitcnt vmcnt(5)
	v_and_b32_e32 v131, 0xffff0000, v78
	v_and_b32_e32 v145, 0xffff0000, v85
	v_pk_fma_f32 v[80:81], v[80:81], v[80:81], v[82:83]
	v_mov_b32_e32 v82, v134
	v_mov_b32_e32 v83, v144
	s_waitcnt vmcnt(4)
	v_and_b32_e32 v143, 0xffff0000, v86
	v_lshlrev_b32_e32 v130, 16, v78
	v_and_b32_e32 v129, 0xffff0000, v79
	v_lshlrev_b32_e32 v128, 16, v79
	global_load_dwordx4 v[72:75], v[98:99], off offset:1024
	global_load_dwordx4 v[76:79], v[94:95], off offset:1024
	v_mov_b32_e32 v84, v135
	v_mov_b32_e32 v85, v145
	v_pk_fma_f32 v[80:81], v[82:83], v[82:83], v[80:81]
	v_lshlrev_b32_e32 v142, 16, v86
	v_mov_b32_e32 v82, v131
	v_mov_b32_e32 v83, v143
	v_pk_fma_f32 v[158:159], v[84:85], v[84:85], v[80:81]
	v_lshlrev_b32_e32 v140, 16, v87
	v_mov_b32_e32 v80, v130
	v_mov_b32_e32 v81, v142
	v_pk_mul_f32 v[82:83], v[82:83], v[82:83]
	v_and_b32_e32 v141, 0xffff0000, v87
	v_pk_fma_f32 v[80:81], v[80:81], v[80:81], v[82:83]
	v_mov_b32_e32 v82, v128
	v_mov_b32_e32 v83, v140
	v_mov_b32_e32 v84, v129
	v_mov_b32_e32 v85, v141
	v_pk_fma_f32 v[80:81], v[82:83], v[82:83], v[80:81]
	v_and_b32_e32 v185, 0xffff0000, v88
	v_pk_fma_f32 v[160:161], v[84:85], v[84:85], v[80:81]
	global_load_dwordx4 v[80:83], v[98:99], off offset:2048
	global_load_dwordx4 v[84:87], v[94:95], off offset:2048
	v_lshlrev_b32_e32 v184, 16, v88
	v_and_b32_e32 v187, 0xffff0000, v89
	v_lshlrev_b32_e32 v186, 16, v89
	v_and_b32_e32 v181, 0xffff0000, v90
	v_lshlrev_b32_e32 v180, 16, v90
	v_and_b32_e32 v183, 0xffff0000, v91
	v_lshlrev_b32_e32 v182, 16, v91
	v_and_b32_e32 v155, 0xffff0000, v92
	v_lshlrev_b32_e32 v154, 16, v92
	v_and_b32_e32 v153, 0xffff0000, v93
	v_lshlrev_b32_e32 v152, 16, v93
	global_load_dwordx4 v[88:91], v[98:99], off offset:3072
	s_nop 0
	global_load_dwordx4 v[92:95], v[94:95], off offset:3072
	v_and_b32_e32 v205, 0xffff0000, v126
	s_waitcnt vmcnt(9)
	v_and_b32_e32 v151, 0xffff0000, v178
	v_lshlrev_b32_e32 v150, 16, v178
	v_and_b32_e32 v149, 0xffff0000, v179
	v_lshlrev_b32_e32 v148, 16, v179
	v_lshlrev_b32_e32 v204, 16, v126
	v_mov_b32_e32 v178, v185
	v_mov_b32_e32 v179, v205
	v_and_b32_e32 v225, 0xffff0000, v127
	v_lshlrev_b32_e32 v224, 16, v127
	v_mov_b32_e32 v126, v184
	v_mov_b32_e32 v127, v204
	v_pk_mul_f32 v[178:179], v[178:179], v[178:179]
	v_mov_b32_e32 v194, v187
	v_pk_fma_f32 v[126:127], v[126:127], v[126:127], v[178:179]
	v_mov_b32_e32 v178, v186
	v_mov_b32_e32 v179, v224
	v_pk_fma_f32 v[126:127], v[178:179], v[178:179], v[126:127]
	v_and_b32_e32 v179, 0xffff0000, v162
	v_mov_b32_e32 v195, v225
	v_lshlrev_b32_e32 v178, 16, v162
	v_mov_b32_e32 v232, v181
	v_mov_b32_e32 v233, v179
	v_pk_fma_f32 v[126:127], v[194:195], v[194:195], v[126:127]
	v_and_b32_e32 v195, 0xffff0000, v163
	v_lshlrev_b32_e32 v194, 16, v163
	v_mov_b32_e32 v162, v180
	v_mov_b32_e32 v163, v178
	v_pk_mul_f32 v[232:233], v[232:233], v[232:233]
	v_mov_b32_e32 v234, v183
	v_pk_fma_f32 v[162:163], v[162:163], v[162:163], v[232:233]
	v_mov_b32_e32 v232, v182
	v_mov_b32_e32 v233, v194
	v_mov_b32_e32 v235, v195
	v_pk_fma_f32 v[162:163], v[232:233], v[232:233], v[162:163]
	v_mov_b32_e32 v232, v190
	v_pk_fma_f32 v[162:163], v[234:235], v[234:235], v[162:163]
	v_mov_b32_e32 v233, v188
	v_mov_b32_e32 v188, v191
	v_pk_add_f32 v[188:189], v[232:233], v[188:189]
	v_mov_b32_e32 v190, v162
	v_mov_b32_e32 v191, v126
	v_pk_add_f32 v[188:189], v[188:189], v[190:191]
	v_mov_b32_e32 v126, v163
	v_pk_add_f32 v[126:127], v[188:189], v[126:127]
	ds_bpermute_b32 v163, v196, v127
	ds_bpermute_b32 v162, v196, v126
	s_waitcnt lgkmcnt(0)
	v_pk_add_f32 v[126:127], v[126:127], v[162:163]
	ds_bpermute_b32 v163, v197, v127
	ds_bpermute_b32 v162, v197, v126
	s_waitcnt lgkmcnt(0)
	v_pk_add_f32 v[126:127], v[126:127], v[162:163]
	ds_bpermute_b32 v163, v198, v127
	ds_bpermute_b32 v162, v198, v126
	s_waitcnt lgkmcnt(0)
	v_pk_add_f32 v[126:127], v[126:127], v[162:163]
	ds_bpermute_b32 v163, v199, v127
	ds_bpermute_b32 v162, v199, v126
	s_waitcnt lgkmcnt(0)
	v_pk_add_f32 v[126:127], v[126:127], v[162:163]
	ds_bpermute_b32 v163, v200, v127
	ds_bpermute_b32 v162, v200, v126
	s_waitcnt lgkmcnt(0)
	v_pk_add_f32 v[126:127], v[126:127], v[162:163]
	ds_bpermute_b32 v163, v201, v127
	ds_bpermute_b32 v162, v201, v126
	s_waitcnt lgkmcnt(0)
	v_pk_add_f32 v[162:163], v[126:127], v[162:163]
	v_mov_b64_e32 v[126:127], s[0:1]
	v_pk_fma_f32 v[162:163], v[162:163], s[8:9], v[126:127] op_sel_hi:[1,0,0]
	s_nop 0
	v_mul_f32_e32 v105, 0x4b800000, v163
	v_cmp_gt_f32_e64 s[0:1], s6, v163
	v_cmp_gt_f32_e32 vcc, s6, v162
	s_nop 0
	v_cndmask_b32_e64 v105, v163, v105, s[0:1]
	v_rsq_f32_e32 v105, v105
	s_nop 0
	v_mul_f32_e32 v109, 0x45800000, v105
	v_cndmask_b32_e64 v188, v105, v109, s[0:1]
	v_pk_mul_f32 v[156:157], v[188:189], v[156:157] op_sel_hi:[0,1]
	s_waitcnt vmcnt(7)
	v_pk_mul_f32 v[156:157], v[156:157], v[64:65]
	v_mul_f32_e32 v105, 0x4b800000, v162
	s_waitcnt vmcnt(6)
	v_pk_fma_f32 v[32:33], v[156:157], v[68:69], v[32:33]
	v_pk_mul_f32 v[156:157], v[188:189], v[168:169] op_sel_hi:[0,1]
	v_pk_mul_f32 v[156:157], v[156:157], v[66:67]
	v_cndmask_b32_e32 v105, v162, v105, vcc
	v_pk_fma_f32 v[34:35], v[156:157], v[70:71], v[34:35]
	v_pk_mul_f32 v[156:157], v[188:189], v[174:175] op_sel_hi:[0,1]
	s_waitcnt vmcnt(5)
	v_pk_mul_f32 v[156:157], v[156:157], v[72:73]
	v_rsq_f32_e32 v105, v105
	s_waitcnt vmcnt(4)
	v_pk_fma_f32 v[16:17], v[156:157], v[76:77], v[16:17]
	v_pk_mul_f32 v[156:157], v[188:189], v[176:177] op_sel_hi:[0,1]
	v_pk_mul_f32 v[156:157], v[156:157], v[74:75]
	v_mul_f32_e32 v109, 0x45800000, v105
	v_pk_fma_f32 v[18:19], v[156:157], v[78:79], v[18:19]
	v_pk_mul_f32 v[156:157], v[188:189], v[184:185] op_sel_hi:[0,1]
	s_waitcnt vmcnt(3)
	v_pk_mul_f32 v[156:157], v[156:157], v[80:81]
	v_mov_b32_e32 v168, v151
	s_waitcnt vmcnt(2)
	v_pk_fma_f32 v[8:9], v[156:157], v[84:85], v[8:9]
	v_pk_mul_f32 v[156:157], v[188:189], v[186:187] op_sel_hi:[0,1]
	v_pk_mul_f32 v[156:157], v[156:157], v[82:83]
	s_nop 0
	v_pk_fma_f32 v[10:11], v[156:157], v[86:87], v[10:11]
	v_pk_mul_f32 v[156:157], v[188:189], v[204:205] op_sel_hi:[0,1]
	s_waitcnt vmcnt(1)
	v_pk_mul_f32 v[156:157], v[156:157], v[88:89]
	s_waitcnt vmcnt(0)
	v_pk_fma_f32 v[0:1], v[156:157], v[92:93], v[0:1]
	v_pk_mul_f32 v[156:157], v[188:189], v[224:225] op_sel_hi:[0,1]
	v_pk_mul_f32 v[156:157], v[156:157], v[90:91]
	s_nop 0
	v_pk_fma_f32 v[2:3], v[156:157], v[94:95], v[2:3]
	v_cndmask_b32_e32 v156, v105, v109, vcc
	v_pk_mul_f32 v[162:163], v[156:157], v[164:165] op_sel_hi:[0,1]
	v_pk_mul_f32 v[162:163], v[162:163], v[64:65]
	v_and_b32_e32 v165, 0xffff0000, v133
	v_pk_fma_f32 v[36:37], v[162:163], v[68:69], v[36:37]
	v_pk_mul_f32 v[162:163], v[156:157], v[166:167] op_sel_hi:[0,1]
	v_pk_mul_f32 v[162:163], v[162:163], v[66:67]
	v_lshlrev_b32_e32 v164, 16, v133
	v_pk_fma_f32 v[38:39], v[162:163], v[70:71], v[38:39]
	v_pk_mul_f32 v[162:163], v[156:157], v[170:171] op_sel_hi:[0,1]
	v_pk_mul_f32 v[162:163], v[162:163], v[72:73]
	v_mov_b32_e32 v166, v153
	v_pk_fma_f32 v[20:21], v[162:163], v[76:77], v[20:21]
	v_pk_mul_f32 v[162:163], v[156:157], v[172:173] op_sel_hi:[0,1]
	v_pk_mul_f32 v[162:163], v[162:163], v[74:75]
	v_mov_b32_e32 v167, v165
	v_pk_fma_f32 v[22:23], v[162:163], v[78:79], v[22:23]
	v_pk_mul_f32 v[162:163], v[156:157], v[180:181] op_sel_hi:[0,1]
	v_pk_mul_f32 v[162:163], v[162:163], v[80:81]
	v_mov_b32_e32 v170, v149
	v_pk_fma_f32 v[12:13], v[162:163], v[84:85], v[12:13]
	v_pk_mul_f32 v[162:163], v[156:157], v[182:183] op_sel_hi:[0,1]
	v_pk_mul_f32 v[162:163], v[162:163], v[82:83]
	s_nop 0
	v_pk_fma_f32 v[14:15], v[162:163], v[86:87], v[14:15]
	v_pk_mul_f32 v[162:163], v[156:157], v[178:179] op_sel_hi:[0,1]
	v_pk_mul_f32 v[162:163], v[162:163], v[88:89]
	v_pk_mul_f32 v[156:157], v[156:157], v[194:195] op_sel_hi:[0,1]
	v_pk_fma_f32 v[4:5], v[162:163], v[92:93], v[4:5]
	v_pk_mul_f32 v[156:157], v[156:157], v[90:91]
	v_and_b32_e32 v163, 0xffff0000, v132
	v_pk_fma_f32 v[6:7], v[156:157], v[94:95], v[6:7]
	v_lshlrev_b32_e32 v162, 16, v132
	v_mov_b32_e32 v156, v155
	v_mov_b32_e32 v157, v163
	v_mov_b32_e32 v132, v154
	v_mov_b32_e32 v133, v162
	v_pk_mul_f32 v[156:157], v[156:157], v[156:157]
	s_nop 0
	v_pk_fma_f32 v[132:133], v[132:133], v[132:133], v[156:157]
	v_mov_b32_e32 v156, v152
	v_mov_b32_e32 v157, v164
	v_pk_fma_f32 v[132:133], v[156:157], v[156:157], v[132:133]
	v_and_b32_e32 v157, 0xffff0000, v138
	v_lshlrev_b32_e32 v156, 16, v138
	v_mov_b32_e32 v169, v157
	v_pk_fma_f32 v[166:167], v[166:167], v[166:167], v[132:133]
	v_and_b32_e32 v133, 0xffff0000, v139
	v_lshlrev_b32_e32 v132, 16, v139
	v_mov_b32_e32 v138, v150
	v_mov_b32_e32 v139, v156
	v_pk_mul_f32 v[168:169], v[168:169], v[168:169]
	v_mov_b32_e32 v171, v133
	v_pk_fma_f32 v[138:139], v[138:139], v[138:139], v[168:169]
	v_mov_b32_e32 v168, v148
	v_mov_b32_e32 v169, v132
	v_pk_fma_f32 v[138:139], v[168:169], v[168:169], v[138:139]
	v_mov_b32_e32 v168, v160
	v_pk_fma_f32 v[138:139], v[170:171], v[170:171], v[138:139]
	v_mov_b32_e32 v169, v158
	v_mov_b32_e32 v158, v161
	v_pk_add_f32 v[158:159], v[168:169], v[158:159]
	v_mov_b32_e32 v160, v138
	v_mov_b32_e32 v161, v166
	v_pk_add_f32 v[158:159], v[158:159], v[160:161]
	v_mov_b32_e32 v166, v139
	v_pk_add_f32 v[138:139], v[158:159], v[166:167]
	ds_bpermute_b32 v159, v196, v139
	ds_bpermute_b32 v158, v196, v138
	s_waitcnt lgkmcnt(0)
	v_pk_add_f32 v[138:139], v[138:139], v[158:159]
	ds_bpermute_b32 v159, v197, v139
	ds_bpermute_b32 v158, v197, v138
	s_waitcnt lgkmcnt(0)
	v_pk_add_f32 v[138:139], v[138:139], v[158:159]
	ds_bpermute_b32 v159, v198, v139
	ds_bpermute_b32 v158, v198, v138
	s_waitcnt lgkmcnt(0)
	v_pk_add_f32 v[138:139], v[138:139], v[158:159]
	ds_bpermute_b32 v159, v199, v139
	ds_bpermute_b32 v158, v199, v138
	s_waitcnt lgkmcnt(0)
	v_pk_add_f32 v[138:139], v[138:139], v[158:159]
	ds_bpermute_b32 v159, v200, v139
	ds_bpermute_b32 v158, v200, v138
	s_waitcnt lgkmcnt(0)
	v_pk_add_f32 v[138:139], v[138:139], v[158:159]
	ds_bpermute_b32 v159, v201, v139
	ds_bpermute_b32 v158, v201, v138
	s_waitcnt lgkmcnt(0)
	v_pk_add_f32 v[138:139], v[138:139], v[158:159]
	s_nop 0
	v_pk_fma_f32 v[138:139], v[138:139], s[8:9], v[126:127] op_sel_hi:[1,0,0]
	s_nop 0
	v_mul_f32_e32 v105, 0x4b800000, v139
	v_cmp_gt_f32_e64 s[0:1], s6, v139
	v_cmp_gt_f32_e32 vcc, s6, v138
	s_nop 0
	v_cndmask_b32_e64 v105, v139, v105, s[0:1]
	v_rsq_f32_e32 v105, v105
	s_nop 0
	v_mul_f32_e32 v109, 0x45800000, v105
	v_cndmask_b32_e64 v158, v105, v109, s[0:1]
	v_pk_mul_f32 v[134:135], v[158:159], v[134:135] op_sel_hi:[0,1]
	v_pk_mul_f32 v[134:135], v[66:67], v[134:135]
	v_mul_f32_e32 v105, 0x4b800000, v138
	v_pk_fma_f32 v[62:63], v[134:135], v[70:71], v[62:63]
	v_pk_mul_f32 v[134:135], v[158:159], v[146:147] op_sel_hi:[0,1]
	v_pk_mul_f32 v[134:135], v[134:135], v[72:73]
	v_cndmask_b32_e32 v105, v138, v105, vcc
	v_pk_fma_f32 v[56:57], v[134:135], v[76:77], v[56:57]
	v_pk_mul_f32 v[134:135], v[158:159], v[144:145] op_sel_hi:[0,1]
	v_pk_mul_f32 v[134:135], v[134:135], v[74:75]
	v_rsq_f32_e32 v105, v105
	v_pk_fma_f32 v[58:59], v[134:135], v[78:79], v[58:59]
	v_pk_mul_f32 v[134:135], v[158:159], v[154:155] op_sel_hi:[0,1]
	v_pk_mul_f32 v[134:135], v[134:135], v[80:81]
	v_mul_f32_e32 v109, 0x45800000, v105
	v_pk_fma_f32 v[40:41], v[134:135], v[84:85], v[40:41]
	v_pk_mul_f32 v[134:135], v[158:159], v[152:153] op_sel_hi:[0,1]
	v_pk_mul_f32 v[134:135], v[134:135], v[82:83]
	v_pk_mul_f32 v[136:137], v[158:159], v[136:137] op_sel_hi:[0,1]
	v_pk_fma_f32 v[42:43], v[134:135], v[86:87], v[42:43]
	v_pk_mul_f32 v[134:135], v[158:159], v[162:163] op_sel_hi:[0,1]
	v_pk_mul_f32 v[134:135], v[134:135], v[88:89]
	v_pk_mul_f32 v[136:137], v[64:65], v[136:137]
	v_pk_fma_f32 v[24:25], v[134:135], v[92:93], v[24:25]
	v_pk_mul_f32 v[134:135], v[158:159], v[164:165] op_sel_hi:[0,1]
	v_pk_mul_f32 v[134:135], v[134:135], v[90:91]
	s_movk_i32 s0, 0x1000
	v_pk_fma_f32 v[26:27], v[134:135], v[94:95], v[26:27]
	v_cndmask_b32_e32 v134, v105, v109, vcc
	v_pk_mul_f32 v[130:131], v[134:135], v[130:131] op_sel_hi:[0,1]
	v_pk_mul_f32 v[64:65], v[64:65], v[130:131]
	v_pk_fma_f32 v[60:61], v[68:69], v[136:137], v[60:61]
	v_pk_fma_f32 v[52:53], v[68:69], v[64:65], v[52:53]
	v_pk_mul_f32 v[64:65], v[134:135], v[128:129] op_sel_hi:[0,1]
	v_pk_mul_f32 v[64:65], v[66:67], v[64:65]
	v_mov_b32_e32 v109, v193
	v_pk_fma_f32 v[54:55], v[70:71], v[64:65], v[54:55]
	v_pk_mul_f32 v[64:65], v[134:135], v[142:143] op_sel_hi:[0,1]
	v_pk_mul_f32 v[64:65], v[72:73], v[64:65]
	v_mov_b32_e32 v70, v9
	v_pk_fma_f32 v[48:49], v[64:65], v[76:77], v[48:49]
	v_pk_mul_f32 v[64:65], v[134:135], v[140:141] op_sel_hi:[0,1]
	v_pk_mul_f32 v[64:65], v[64:65], v[74:75]
	v_mov_b32_e32 v71, v1
	v_pk_fma_f32 v[50:51], v[64:65], v[78:79], v[50:51]
	v_pk_mul_f32 v[64:65], v[134:135], v[150:151] op_sel_hi:[0,1]
	v_pk_mul_f32 v[64:65], v[64:65], v[80:81]
	v_pk_mul_f32 v[70:71], v[70:71], v[70:71]
	v_pk_fma_f32 v[44:45], v[64:65], v[84:85], v[44:45]
	v_pk_mul_f32 v[64:65], v[134:135], v[148:149] op_sel_hi:[0,1]
	v_pk_mul_f32 v[64:65], v[64:65], v[82:83]
	v_mov_b32_e32 v72, v37
	v_pk_fma_f32 v[46:47], v[64:65], v[86:87], v[46:47]
	v_pk_mul_f32 v[64:65], v[134:135], v[156:157] op_sel_hi:[0,1]
	v_pk_mul_f32 v[64:65], v[64:65], v[88:89]
	v_mov_b32_e32 v73, v21
	v_pk_fma_f32 v[28:29], v[64:65], v[92:93], v[28:29]
	v_pk_mul_f32 v[64:65], v[134:135], v[132:133] op_sel_hi:[0,1]
	v_pk_mul_f32 v[64:65], v[64:65], v[90:91]
	v_pk_mul_f32 v[72:73], v[72:73], v[72:73]
	v_pk_fma_f32 v[30:31], v[64:65], v[94:95], v[30:31]
	v_lshl_add_u64 v[64:65], v[124:125], 0, v[106:107]
	v_add_co_u32_e32 v66, vcc, s0, v64
	s_movk_i32 s0, 0x2000
	s_nop 0
	v_addc_co_u32_e32 v67, vcc, 0, v65, vcc
	v_add_co_u32_e32 v68, vcc, s0, v64
	global_store_dwordx4 v[64:65], v[32:35], off nt
	global_store_dwordx4 v[64:65], v[16:19], off offset:1024 nt
	global_store_dwordx4 v[64:65], v[8:11], off offset:2048 nt
	global_store_dwordx4 v[64:65], v[0:3], off offset:3072 nt
	v_addc_co_u32_e32 v69, vcc, 0, v65, vcc
	global_store_dwordx4 v[68:69], v[36:39], off offset:-4096 nt
	global_store_dwordx4 v[66:67], v[20:23], off offset:1024 nt
	global_store_dwordx4 v[66:67], v[12:15], off offset:2048 nt
	global_store_dwordx4 v[66:67], v[4:7], off offset:3072 nt
	global_store_dwordx4 v[68:69], v[60:63], off nt
	global_store_dwordx4 v[68:69], v[56:59], off offset:1024 nt
	global_store_dwordx4 v[68:69], v[40:43], off offset:2048 nt
	global_store_dwordx4 v[68:69], v[24:27], off offset:3072 nt
	v_mov_b32_e32 v68, v33
	v_mov_b32_e32 v69, v17
	v_mov_b32_e32 v66, v32
	v_mov_b32_e32 v67, v16
	v_pk_mul_f32 v[68:69], v[68:69], v[68:69]
	v_mov_b32_e32 v74, v13
	v_pk_fma_f32 v[66:67], v[66:67], v[66:67], v[68:69]
	v_mov_b32_e32 v68, v34
	v_mov_b32_e32 v69, v18
	v_pk_fma_f32 v[66:67], v[68:69], v[68:69], v[66:67]
	v_mov_b32_e32 v68, v35
	v_mov_b32_e32 v69, v19
	v_pk_fma_f32 v[66:67], v[68:69], v[68:69], v[66:67]
	v_mov_b32_e32 v68, v8
	v_mov_b32_e32 v69, v0
	v_pk_fma_f32 v[68:69], v[68:69], v[68:69], v[70:71]
	v_mov_b32_e32 v70, v10
	v_mov_b32_e32 v71, v2
	v_pk_fma_f32 v[68:69], v[70:71], v[70:71], v[68:69]
	v_mov_b32_e32 v70, v11
	v_mov_b32_e32 v71, v3
	v_pk_fma_f32 v[68:69], v[70:71], v[70:71], v[68:69]
	v_mov_b32_e32 v70, v36
	v_mov_b32_e32 v71, v20
	v_pk_fma_f32 v[70:71], v[70:71], v[70:71], v[72:73]
	v_mov_b32_e32 v72, v38
	v_mov_b32_e32 v73, v22
	v_pk_fma_f32 v[70:71], v[72:73], v[72:73], v[70:71]
	v_mov_b32_e32 v72, v39
	v_mov_b32_e32 v73, v23
	v_mov_b32_e32 v75, v5
	v_pk_fma_f32 v[70:71], v[72:73], v[72:73], v[70:71]
	v_mov_b32_e32 v72, v12
	v_mov_b32_e32 v73, v4
	v_pk_mul_f32 v[74:75], v[74:75], v[74:75]
	v_add_co_u32_e32 v64, vcc, s73, v64
	v_pk_fma_f32 v[72:73], v[72:73], v[72:73], v[74:75]
	v_mov_b32_e32 v74, v14
	v_mov_b32_e32 v75, v6
	v_pk_fma_f32 v[72:73], v[74:75], v[74:75], v[72:73]
	v_mov_b32_e32 v74, v15
	v_mov_b32_e32 v75, v7
	v_pk_fma_f32 v[72:73], v[74:75], v[74:75], v[72:73]
	v_mov_b32_e32 v74, v70
	v_mov_b32_e32 v75, v66
	v_mov_b32_e32 v66, v71
	v_pk_add_f32 v[66:67], v[74:75], v[66:67]
	v_mov_b32_e32 v70, v72
	v_mov_b32_e32 v71, v68
	v_pk_add_f32 v[66:67], v[66:67], v[70:71]
	v_mov_b32_e32 v68, v73
	v_pk_add_f32 v[66:67], v[66:67], v[68:69]
	ds_bpermute_b32 v69, v196, v67
	ds_bpermute_b32 v68, v196, v66
	v_addc_co_u32_e32 v65, vcc, 0, v65, vcc
	global_store_dwordx4 v[64:65], v[52:55], off nt
	global_store_dwordx4 v[64:65], v[48:51], off offset:1024 nt
	global_store_dwordx4 v[64:65], v[44:47], off offset:2048 nt
	global_store_dwordx4 v[64:65], v[28:31], off offset:3072 nt
	v_lshl_add_u64 v[64:65], s[96:97], 0, v[122:123]
	s_waitcnt lgkmcnt(0)
	v_pk_add_f32 v[66:67], v[66:67], v[68:69]
	ds_bpermute_b32 v69, v197, v67
	ds_bpermute_b32 v68, v197, v66
	s_mov_b64 s[0:1], 0x3000
	v_lshl_add_u64 v[76:77], v[64:65], 0, s[0:1]
	v_mov_b32_e32 v70, v41
	v_mov_b32_e32 v71, v25
	s_waitcnt lgkmcnt(0)
	v_pk_add_f32 v[66:67], v[66:67], v[68:69]
	ds_bpermute_b32 v69, v198, v67
	ds_bpermute_b32 v68, v198, v66
	v_pk_mul_f32 v[70:71], v[70:71], v[70:71]
	v_mov_b32_e32 v72, v53
	v_mov_b32_e32 v73, v49
	v_pk_mul_f32 v[72:73], v[72:73], v[72:73]
	s_waitcnt lgkmcnt(0)
	v_pk_add_f32 v[66:67], v[66:67], v[68:69]
	ds_bpermute_b32 v69, v199, v67
	ds_bpermute_b32 v68, v199, v66
	v_mov_b32_e32 v74, v45
	v_mov_b32_e32 v75, v29
	v_pk_mul_f32 v[74:75], v[74:75], v[74:75]
	v_lshl_add_u64 v[86:87], v[102:103], 0, v[120:121]
	s_waitcnt lgkmcnt(0)
	v_pk_add_f32 v[66:67], v[66:67], v[68:69]
	ds_bpermute_b32 v69, v200, v67
	ds_bpermute_b32 v68, v200, v66
	s_waitcnt lgkmcnt(0)
	v_pk_add_f32 v[66:67], v[66:67], v[68:69]
	ds_bpermute_b32 v69, v201, v67
	ds_bpermute_b32 v68, v201, v66
	s_waitcnt lgkmcnt(0)
	v_pk_add_f32 v[66:67], v[66:67], v[68:69]
	s_nop 0
	v_pk_fma_f32 v[66:67], v[66:67], s[8:9], v[126:127] op_sel_hi:[1,0,0]
	v_mov_b32_e32 v69, v57
	v_mul_f32_e32 v68, 0x4b800000, v67
	v_cmp_gt_f32_e64 s[0:1], s6, v67
	v_cmp_gt_f32_e32 vcc, s6, v66
	s_nop 0
	v_cndmask_b32_e64 v67, v67, v68, s[0:1]
	v_rsq_f32_e32 v67, v67
	s_nop 0
	v_mul_f32_e32 v68, 0x45800000, v67
	v_cndmask_b32_e64 v80, v67, v68, s[0:1]
	v_mul_f32_e32 v67, 0x4b800000, v66
	v_cndmask_b32_e32 v66, v66, v67, vcc
	v_rsq_f32_e32 v66, v66
	v_mov_b32_e32 v68, v61
	v_pk_mul_f32 v[68:69], v[68:69], v[68:69]
	v_mul_f32_e32 v67, 0x45800000, v66
	v_cndmask_b32_e32 v78, v66, v67, vcc
	v_mov_b32_e32 v66, v60
	v_mov_b32_e32 v67, v56
	v_pk_fma_f32 v[66:67], v[66:67], v[66:67], v[68:69]
	v_mov_b32_e32 v68, v62
	v_mov_b32_e32 v69, v58
	v_pk_fma_f32 v[66:67], v[68:69], v[68:69], v[66:67]
	v_mov_b32_e32 v68, v63
	v_mov_b32_e32 v69, v59
	v_pk_fma_f32 v[66:67], v[68:69], v[68:69], v[66:67]
	v_mov_b32_e32 v68, v40
	v_mov_b32_e32 v69, v24
	v_pk_fma_f32 v[68:69], v[68:69], v[68:69], v[70:71]
	v_mov_b32_e32 v70, v42
	v_mov_b32_e32 v71, v26
	v_pk_fma_f32 v[68:69], v[70:71], v[70:71], v[68:69]
	v_mov_b32_e32 v70, v43
	v_mov_b32_e32 v71, v27
	v_pk_fma_f32 v[68:69], v[70:71], v[70:71], v[68:69]
	v_mov_b32_e32 v70, v52
	v_mov_b32_e32 v71, v48
	v_pk_fma_f32 v[70:71], v[70:71], v[70:71], v[72:73]
	v_mov_b32_e32 v72, v54
	v_mov_b32_e32 v73, v50
	v_pk_fma_f32 v[70:71], v[72:73], v[72:73], v[70:71]
	v_mov_b32_e32 v72, v55
	v_mov_b32_e32 v73, v51
	v_pk_fma_f32 v[70:71], v[72:73], v[72:73], v[70:71]
	v_mov_b32_e32 v72, v44
	v_mov_b32_e32 v73, v28
	v_pk_fma_f32 v[72:73], v[72:73], v[72:73], v[74:75]
	v_mov_b32_e32 v74, v46
	v_mov_b32_e32 v75, v30
	v_pk_fma_f32 v[72:73], v[74:75], v[74:75], v[72:73]
	v_mov_b32_e32 v74, v47
	v_mov_b32_e32 v75, v31
	v_pk_fma_f32 v[72:73], v[74:75], v[74:75], v[72:73]
	v_mov_b32_e32 v74, v70
	v_mov_b32_e32 v75, v66
	v_mov_b32_e32 v66, v71
	v_pk_add_f32 v[66:67], v[74:75], v[66:67]
	v_mov_b32_e32 v70, v72
	v_mov_b32_e32 v71, v68
	v_pk_add_f32 v[66:67], v[66:67], v[70:71]
	v_mov_b32_e32 v68, v73
	v_pk_add_f32 v[66:67], v[66:67], v[68:69]
	ds_bpermute_b32 v69, v196, v67
	ds_bpermute_b32 v68, v196, v66
	v_lshl_add_u64 v[70:71], v[76:77], 0, v[106:107]
	s_waitcnt lgkmcnt(0)
	v_pk_add_f32 v[66:67], v[66:67], v[68:69]
	ds_bpermute_b32 v69, v197, v67
	ds_bpermute_b32 v68, v197, v66
	s_waitcnt lgkmcnt(0)
	v_pk_add_f32 v[66:67], v[66:67], v[68:69]
	ds_bpermute_b32 v69, v198, v67
	ds_bpermute_b32 v68, v198, v66
	s_waitcnt lgkmcnt(0)
	v_pk_add_f32 v[66:67], v[66:67], v[68:69]
	ds_bpermute_b32 v69, v199, v67
	ds_bpermute_b32 v68, v199, v66
	s_waitcnt lgkmcnt(0)
	v_pk_add_f32 v[66:67], v[66:67], v[68:69]
	ds_bpermute_b32 v69, v200, v67
	ds_bpermute_b32 v68, v200, v66
	s_waitcnt lgkmcnt(0)
	v_pk_add_f32 v[66:67], v[66:67], v[68:69]
	ds_bpermute_b32 v69, v201, v67
	ds_bpermute_b32 v68, v201, v66
	s_waitcnt lgkmcnt(0)
	v_pk_add_f32 v[66:67], v[66:67], v[68:69]
	s_nop 0
	v_pk_fma_f32 v[66:67], v[66:67], s[8:9], v[126:127] op_sel_hi:[1,0,0]
	s_nop 0
	v_mul_f32_e32 v68, 0x4b800000, v67
	v_cmp_gt_f32_e64 s[0:1], s6, v67
	v_cmp_gt_f32_e32 vcc, s6, v66
	s_nop 0
	v_cndmask_b32_e64 v67, v67, v68, s[0:1]
	v_rsq_f32_e32 v67, v67
	s_nop 0
	v_mul_f32_e32 v68, 0x45800000, v67
	v_cndmask_b32_e64 v84, v67, v68, s[0:1]
	v_mul_f32_e32 v67, 0x4b800000, v66
	v_cndmask_b32_e32 v66, v66, v67, vcc
	v_rsq_f32_e32 v66, v66
	s_mov_b64 s[0:1], 0x4000
	v_lshl_add_u64 v[88:89], v[64:65], 0, s[0:1]
	v_lshl_add_u64 v[68:69], v[88:89], 0, v[106:107]
	v_mul_f32_e32 v67, 0x45800000, v66
	v_cndmask_b32_e32 v82, v66, v67, vcc
	global_load_dwordx4 v[64:67], v[100:101], off
	global_load_dwordx4 v[72:75], v[68:69], off
	s_nop 0
	global_load_dwordx4 v[68:71], v[70:71], off
	v_readlane_b32 s0, v255, 7
	s_waitcnt vmcnt(2)
	v_mov_b32_e32 v93, v66
	s_waitcnt vmcnt(1)
	v_mov_b32_e32 v91, v74
	v_mov_b32_e32 v74, v73
	v_mov_b32_e32 v90, v72
	v_pk_add_f32 v[72:73], v[74:75], 1.0 op_sel_hi:[1,0]
	v_mov_b32_e32 v75, v34
	v_mov_b32_e32 v34, v33
	v_mov_b32_e32 v74, v32
	v_pk_mul_f32 v[32:33], v[34:35], v[80:81] op_sel_hi:[1,0]
	v_mov_b32_e32 v66, v65
	v_pk_mul_f32 v[74:75], v[74:75], v[80:81] op_sel_hi:[1,0]
	v_mov_b32_e32 v92, v64
	s_waitcnt vmcnt(0)
	v_mov_b32_e32 v95, v70
	v_pk_mul_f32 v[32:33], v[32:33], v[66:67]
	v_mov_b32_e32 v70, v69
	v_pk_add_f32 v[90:91], v[90:91], 1.0 op_sel_hi:[1,0]
	v_pk_mul_f32 v[74:75], v[74:75], v[92:93]
	v_mov_b32_e32 v94, v68
	v_pk_fma_f32 v[32:33], v[32:33], v[72:73], v[70:71]
	v_pk_fma_f32 v[74:75], v[74:75], v[90:91], v[94:95]
	v_cvt_pk_bf16_f32 v33, v75, v33
	v_cvt_pk_bf16_f32 v32, v74, v32
	v_mov_b32_e32 v34, v36
	v_mov_b32_e32 v35, v38
	v_pk_mul_f32 v[34:35], v[34:35], v[78:79] op_sel_hi:[1,0]
	v_mov_b32_e32 v38, v37
	v_pk_mul_f32 v[34:35], v[34:35], v[92:93]
	v_pk_mul_f32 v[36:37], v[38:39], v[78:79] op_sel_hi:[1,0]
	v_pk_fma_f32 v[34:35], v[34:35], v[90:91], v[94:95]
	v_pk_mul_f32 v[36:37], v[36:37], v[66:67]
	v_and_b32_sdwa v38, v35, v218 dst_sel:DWORD dst_unused:UNUSED_PAD src0_sel:WORD_1 src1_sel:DWORD
	v_pk_fma_f32 v[36:37], v[36:37], v[72:73], v[70:71]
	v_cvt_pk_bf16_f32 v34, v34, v36
	v_add3_u32 v35, v35, v38, s80
	v_and_b32_sdwa v38, v37, v218 dst_sel:DWORD dst_unused:UNUSED_PAD src0_sel:WORD_1 src1_sel:DWORD
	v_add3_u32 v37, v37, v38, s80
	v_and_b32_e32 v37, 0xffff0000, v37
	v_or_b32_sdwa v35, v37, v35 dst_sel:DWORD dst_unused:UNUSED_PAD src0_sel:DWORD src1_sel:WORD_1
	v_mov_b32_e32 v36, v60
	v_mov_b32_e32 v37, v62
	v_pk_mul_f32 v[36:37], v[36:37], v[84:85] op_sel_hi:[1,0]
	v_mov_b32_e32 v62, v61
	v_pk_mul_f32 v[36:37], v[92:93], v[36:37]
	v_pk_mul_f32 v[38:39], v[62:63], v[84:85] op_sel_hi:[1,0]
	v_pk_fma_f32 v[36:37], v[36:37], v[90:91], v[94:95]
	v_pk_mul_f32 v[38:39], v[66:67], v[38:39]
	v_and_b32_sdwa v60, v37, v218 dst_sel:DWORD dst_unused:UNUSED_PAD src0_sel:WORD_1 src1_sel:DWORD
	v_pk_fma_f32 v[38:39], v[38:39], v[72:73], v[70:71]
	v_cvt_pk_bf16_f32 v36, v36, v38
	v_add3_u32 v37, v37, v60, s80
	v_and_b32_sdwa v60, v39, v218 dst_sel:DWORD dst_unused:UNUSED_PAD src0_sel:WORD_1 src1_sel:DWORD
	v_add3_u32 v39, v39, v60, s80
	v_and_b32_e32 v39, 0xffff0000, v39
	v_or_b32_sdwa v37, v39, v37 dst_sel:DWORD dst_unused:UNUSED_PAD src0_sel:DWORD src1_sel:WORD_1
	v_mov_b32_e32 v38, v52
	v_mov_b32_e32 v39, v54
	v_pk_mul_f32 v[38:39], v[38:39], v[82:83] op_sel_hi:[1,0]
	v_mov_b32_e32 v54, v53
	v_pk_mul_f32 v[38:39], v[92:93], v[38:39]
	v_pk_mul_f32 v[52:53], v[54:55], v[82:83] op_sel_hi:[1,0]
	v_pk_fma_f32 v[38:39], v[90:91], v[38:39], v[94:95]
	v_pk_mul_f32 v[52:53], v[66:67], v[52:53]
	v_and_b32_sdwa v54, v39, v218 dst_sel:DWORD dst_unused:UNUSED_PAD src0_sel:WORD_1 src1_sel:DWORD
	v_pk_fma_f32 v[52:53], v[72:73], v[52:53], v[70:71]
	v_cvt_pk_bf16_f32 v38, v38, v52
	v_add3_u32 v39, v39, v54, s80
	v_and_b32_sdwa v54, v53, v218 dst_sel:DWORD dst_unused:UNUSED_PAD src0_sel:WORD_1 src1_sel:DWORD
	global_store_dwordx2 v[86:87], v[32:33], off nt
	v_lshl_add_u64 v[32:33], v[102:103], 0, v[118:119]
	v_add3_u32 v53, v53, v54, s80
	global_store_dwordx2 v[32:33], v[34:35], off nt
	v_lshl_add_u64 v[34:35], v[102:103], 0, v[116:117]
	v_and_b32_e32 v53, 0xffff0000, v53
	global_store_dwordx2 v[34:35], v[36:37], off nt
	v_lshl_add_u64 v[36:37], v[102:103], 0, v[114:115]
	v_or_b32_sdwa v39, v53, v39 dst_sel:DWORD dst_unused:UNUSED_PAD src0_sel:DWORD src1_sel:WORD_1
	global_store_dwordx2 v[36:37], v[38:39], off nt
	v_lshl_add_u64 v[64:65], v[76:77], 0, v[108:109]
	v_lshl_add_u64 v[38:39], v[88:89], 0, v[108:109]
	global_load_dwordx4 v[52:55], v[100:101], off offset:1024
	global_load_dwordx4 v[60:63], v[38:39], off
	s_nop 0
	global_load_dwordx4 v[64:67], v[64:65], off
	v_add_u32_e32 v104, s0, v104
	s_waitcnt vmcnt(2)
	v_mov_b32_e32 v69, v54
	s_waitcnt vmcnt(1)
	v_mov_b32_e32 v39, v62
	v_mov_b32_e32 v62, v61
	v_mov_b32_e32 v38, v60
	v_pk_add_f32 v[60:61], v[62:63], 1.0 op_sel_hi:[1,0]
	v_mov_b32_e32 v63, v18
	v_mov_b32_e32 v18, v17
	v_mov_b32_e32 v62, v16
	v_pk_mul_f32 v[16:17], v[18:19], v[80:81] op_sel_hi:[1,0]
	v_mov_b32_e32 v54, v53
	v_pk_mul_f32 v[62:63], v[62:63], v[80:81] op_sel_hi:[1,0]
	v_mov_b32_e32 v68, v52
	s_waitcnt vmcnt(0)
	v_mov_b32_e32 v71, v66
	v_pk_mul_f32 v[16:17], v[16:17], v[54:55]
	v_mov_b32_e32 v66, v65
	v_pk_add_f32 v[38:39], v[38:39], 1.0 op_sel_hi:[1,0]
	v_pk_mul_f32 v[62:63], v[62:63], v[68:69]
	v_mov_b32_e32 v70, v64
	v_pk_fma_f32 v[16:17], v[16:17], v[60:61], v[66:67]
	v_pk_fma_f32 v[62:63], v[62:63], v[38:39], v[70:71]
	v_cvt_pk_bf16_f32 v17, v63, v17
	v_cvt_pk_bf16_f32 v16, v62, v16
	global_store_dwordx2 v[86:87], v[16:17], off offset:512 nt
	v_mov_b32_e32 v16, v20
	v_mov_b32_e32 v17, v22
	v_pk_mul_f32 v[16:17], v[16:17], v[78:79] op_sel_hi:[1,0]
	v_mov_b32_e32 v22, v21
	v_pk_mul_f32 v[16:17], v[16:17], v[68:69]
	v_pk_mul_f32 v[18:19], v[22:23], v[78:79] op_sel_hi:[1,0]
	v_pk_fma_f32 v[16:17], v[16:17], v[38:39], v[70:71]
	v_pk_mul_f32 v[18:19], v[18:19], v[54:55]
	v_and_b32_sdwa v20, v17, v218 dst_sel:DWORD dst_unused:UNUSED_PAD src0_sel:WORD_1 src1_sel:DWORD
	v_pk_fma_f32 v[18:19], v[18:19], v[60:61], v[66:67]
	v_cvt_pk_bf16_f32 v16, v16, v18
	v_add3_u32 v17, v17, v20, s80
	v_and_b32_sdwa v20, v19, v218 dst_sel:DWORD dst_unused:UNUSED_PAD src0_sel:WORD_1 src1_sel:DWORD
	v_add3_u32 v19, v19, v20, s80
	v_and_b32_e32 v19, 0xffff0000, v19
	v_or_b32_sdwa v17, v19, v17 dst_sel:DWORD dst_unused:UNUSED_PAD src0_sel:DWORD src1_sel:WORD_1
	global_store_dwordx2 v[32:33], v[16:17], off offset:512 nt
	v_mov_b32_e32 v16, v56
	v_mov_b32_e32 v17, v58
	v_pk_mul_f32 v[16:17], v[16:17], v[84:85] op_sel_hi:[1,0]
	v_mov_b32_e32 v58, v57
	v_pk_mul_f32 v[16:17], v[16:17], v[68:69]
	v_pk_mul_f32 v[18:19], v[58:59], v[84:85] op_sel_hi:[1,0]
	v_pk_fma_f32 v[16:17], v[16:17], v[38:39], v[70:71]
	v_pk_mul_f32 v[18:19], v[18:19], v[54:55]
	v_and_b32_sdwa v20, v17, v218 dst_sel:DWORD dst_unused:UNUSED_PAD src0_sel:WORD_1 src1_sel:DWORD
	v_pk_fma_f32 v[18:19], v[18:19], v[60:61], v[66:67]
	v_cvt_pk_bf16_f32 v16, v16, v18
	v_add3_u32 v17, v17, v20, s80
	v_and_b32_sdwa v20, v19, v218 dst_sel:DWORD dst_unused:UNUSED_PAD src0_sel:WORD_1 src1_sel:DWORD
	v_add3_u32 v19, v19, v20, s80
	v_and_b32_e32 v19, 0xffff0000, v19
	v_or_b32_sdwa v17, v19, v17 dst_sel:DWORD dst_unused:UNUSED_PAD src0_sel:DWORD src1_sel:WORD_1
	global_store_dwordx2 v[34:35], v[16:17], off offset:512 nt
	v_mov_b32_e32 v16, v48
	v_mov_b32_e32 v17, v50
	v_pk_mul_f32 v[16:17], v[16:17], v[82:83] op_sel_hi:[1,0]
	v_mov_b32_e32 v50, v49
	v_pk_mul_f32 v[16:17], v[16:17], v[68:69]
	v_pk_mul_f32 v[18:19], v[50:51], v[82:83] op_sel_hi:[1,0]
	v_pk_fma_f32 v[16:17], v[16:17], v[38:39], v[70:71]
	v_pk_mul_f32 v[18:19], v[18:19], v[54:55]
	v_and_b32_sdwa v20, v17, v218 dst_sel:DWORD dst_unused:UNUSED_PAD src0_sel:WORD_1 src1_sel:DWORD
	v_pk_fma_f32 v[18:19], v[18:19], v[60:61], v[66:67]
	v_cvt_pk_bf16_f32 v16, v16, v18
	v_add3_u32 v17, v17, v20, s80
	v_and_b32_sdwa v20, v19, v218 dst_sel:DWORD dst_unused:UNUSED_PAD src0_sel:WORD_1 src1_sel:DWORD
	v_add3_u32 v19, v19, v20, s80
	v_and_b32_e32 v19, 0xffff0000, v19
	v_or_b32_sdwa v17, v19, v17 dst_sel:DWORD dst_unused:UNUSED_PAD src0_sel:DWORD src1_sel:WORD_1
	global_store_dwordx2 v[36:37], v[16:17], off offset:512 nt
	v_lshl_add_u64 v[20:21], v[88:89], 0, v[110:111]
	v_lshl_add_u64 v[38:39], v[76:77], 0, v[110:111]
	global_load_dwordx4 v[16:19], v[100:101], off offset:2048
	s_nop 0
	global_load_dwordx4 v[20:23], v[20:21], off
	s_nop 0
	global_load_dwordx4 v[48:51], v[38:39], off
	s_waitcnt vmcnt(2)
	v_mov_b32_e32 v53, v18
	s_waitcnt vmcnt(1)
	v_mov_b32_e32 v39, v22
	v_mov_b32_e32 v22, v21
	v_mov_b32_e32 v38, v20
	v_pk_add_f32 v[20:21], v[22:23], 1.0 op_sel_hi:[1,0]
	v_mov_b32_e32 v23, v10
	v_mov_b32_e32 v10, v9
	v_mov_b32_e32 v22, v8
	v_pk_mul_f32 v[8:9], v[10:11], v[80:81] op_sel_hi:[1,0]
	v_mov_b32_e32 v18, v17
	v_pk_mul_f32 v[22:23], v[22:23], v[80:81] op_sel_hi:[1,0]
	v_mov_b32_e32 v52, v16
	s_waitcnt vmcnt(0)
	v_mov_b32_e32 v55, v50
	v_pk_mul_f32 v[8:9], v[8:9], v[18:19]
	v_mov_b32_e32 v50, v49
	v_pk_add_f32 v[38:39], v[38:39], 1.0 op_sel_hi:[1,0]
	v_pk_mul_f32 v[22:23], v[22:23], v[52:53]
	v_mov_b32_e32 v54, v48
	v_pk_fma_f32 v[8:9], v[8:9], v[20:21], v[50:51]
	v_pk_fma_f32 v[22:23], v[22:23], v[38:39], v[54:55]
	v_cvt_pk_bf16_f32 v9, v23, v9
	v_cvt_pk_bf16_f32 v8, v22, v8
	global_store_dwordx2 v[86:87], v[8:9], off offset:1024 nt
	v_mov_b32_e32 v8, v12
	v_mov_b32_e32 v9, v14
	v_pk_mul_f32 v[8:9], v[8:9], v[78:79] op_sel_hi:[1,0]
	v_mov_b32_e32 v14, v13
	v_pk_mul_f32 v[8:9], v[8:9], v[52:53]
	v_pk_mul_f32 v[10:11], v[14:15], v[78:79] op_sel_hi:[1,0]
	v_pk_fma_f32 v[8:9], v[8:9], v[38:39], v[54:55]
	v_pk_mul_f32 v[10:11], v[10:11], v[18:19]
	v_and_b32_sdwa v12, v9, v218 dst_sel:DWORD dst_unused:UNUSED_PAD src0_sel:WORD_1 src1_sel:DWORD
	v_pk_fma_f32 v[10:11], v[10:11], v[20:21], v[50:51]
	v_cvt_pk_bf16_f32 v8, v8, v10
	v_add3_u32 v9, v9, v12, s80
	v_and_b32_sdwa v12, v11, v218 dst_sel:DWORD dst_unused:UNUSED_PAD src0_sel:WORD_1 src1_sel:DWORD
	v_add3_u32 v11, v11, v12, s80
	v_and_b32_e32 v11, 0xffff0000, v11
	v_or_b32_sdwa v9, v11, v9 dst_sel:DWORD dst_unused:UNUSED_PAD src0_sel:DWORD src1_sel:WORD_1
	global_store_dwordx2 v[32:33], v[8:9], off offset:1024 nt
	v_mov_b32_e32 v8, v40
	v_mov_b32_e32 v9, v42
	v_pk_mul_f32 v[8:9], v[8:9], v[84:85] op_sel_hi:[1,0]
	v_mov_b32_e32 v42, v41
	v_pk_mul_f32 v[8:9], v[8:9], v[52:53]
	v_pk_mul_f32 v[10:11], v[42:43], v[84:85] op_sel_hi:[1,0]
	v_pk_fma_f32 v[8:9], v[8:9], v[38:39], v[54:55]
	v_pk_mul_f32 v[10:11], v[10:11], v[18:19]
	v_and_b32_sdwa v12, v9, v218 dst_sel:DWORD dst_unused:UNUSED_PAD src0_sel:WORD_1 src1_sel:DWORD
	v_pk_fma_f32 v[10:11], v[10:11], v[20:21], v[50:51]
	v_cvt_pk_bf16_f32 v8, v8, v10
	v_add3_u32 v9, v9, v12, s80
	v_and_b32_sdwa v12, v11, v218 dst_sel:DWORD dst_unused:UNUSED_PAD src0_sel:WORD_1 src1_sel:DWORD
	v_add3_u32 v11, v11, v12, s80
	v_and_b32_e32 v11, 0xffff0000, v11
	v_or_b32_sdwa v9, v11, v9 dst_sel:DWORD dst_unused:UNUSED_PAD src0_sel:DWORD src1_sel:WORD_1
	global_store_dwordx2 v[34:35], v[8:9], off offset:1024 nt
	v_mov_b32_e32 v8, v44
	v_mov_b32_e32 v9, v46
	v_pk_mul_f32 v[8:9], v[8:9], v[82:83] op_sel_hi:[1,0]
	v_mov_b32_e32 v46, v45
	v_pk_mul_f32 v[8:9], v[8:9], v[52:53]
	v_pk_mul_f32 v[10:11], v[46:47], v[82:83] op_sel_hi:[1,0]
	v_pk_fma_f32 v[8:9], v[8:9], v[38:39], v[54:55]
	v_pk_mul_f32 v[10:11], v[10:11], v[18:19]
	v_and_b32_sdwa v12, v9, v218 dst_sel:DWORD dst_unused:UNUSED_PAD src0_sel:WORD_1 src1_sel:DWORD
	v_pk_fma_f32 v[10:11], v[10:11], v[20:21], v[50:51]
	v_cvt_pk_bf16_f32 v8, v8, v10
	v_add3_u32 v9, v9, v12, s80
	v_and_b32_sdwa v12, v11, v218 dst_sel:DWORD dst_unused:UNUSED_PAD src0_sel:WORD_1 src1_sel:DWORD
	v_add3_u32 v11, v11, v12, s80
	v_and_b32_e32 v11, 0xffff0000, v11
	v_or_b32_sdwa v9, v11, v9 dst_sel:DWORD dst_unused:UNUSED_PAD src0_sel:DWORD src1_sel:WORD_1
	global_store_dwordx2 v[36:37], v[8:9], off offset:1024 nt
	v_lshl_add_u64 v[12:13], v[88:89], 0, v[112:113]
	v_lshl_add_u64 v[16:17], v[76:77], 0, v[112:113]
	global_load_dwordx4 v[8:11], v[100:101], off offset:3072
	s_nop 0
	global_load_dwordx4 v[12:15], v[12:13], off
	s_nop 0
	global_load_dwordx4 v[16:19], v[16:17], off
	s_waitcnt vmcnt(2)
	v_mov_b32_e32 v23, v10
	s_waitcnt vmcnt(1)
	v_mov_b32_e32 v21, v14
	v_mov_b32_e32 v14, v13
	v_mov_b32_e32 v20, v12
	v_pk_add_f32 v[12:13], v[14:15], 1.0 op_sel_hi:[1,0]
	v_mov_b32_e32 v15, v2
	v_mov_b32_e32 v2, v1
	v_mov_b32_e32 v14, v0
	v_pk_mul_f32 v[0:1], v[2:3], v[80:81] op_sel_hi:[1,0]
	v_mov_b32_e32 v10, v9
	v_pk_mul_f32 v[14:15], v[14:15], v[80:81] op_sel_hi:[1,0]
	v_mov_b32_e32 v22, v8
	s_waitcnt vmcnt(0)
	v_mov_b32_e32 v39, v18
	v_pk_mul_f32 v[0:1], v[0:1], v[10:11]
	v_mov_b32_e32 v18, v17
	v_pk_add_f32 v[20:21], v[20:21], 1.0 op_sel_hi:[1,0]
	v_pk_mul_f32 v[14:15], v[14:15], v[22:23]
	v_mov_b32_e32 v38, v16
	v_pk_fma_f32 v[0:1], v[0:1], v[12:13], v[18:19]
	v_pk_fma_f32 v[14:15], v[14:15], v[20:21], v[38:39]
	v_cvt_pk_bf16_f32 v1, v15, v1
	v_cvt_pk_bf16_f32 v0, v14, v0
	global_store_dwordx2 v[86:87], v[0:1], off offset:1536 nt
	v_mov_b32_e32 v0, v4
	v_mov_b32_e32 v1, v6
	v_pk_mul_f32 v[0:1], v[0:1], v[78:79] op_sel_hi:[1,0]
	v_mov_b32_e32 v6, v5
	v_pk_mul_f32 v[0:1], v[0:1], v[22:23]
	v_pk_mul_f32 v[2:3], v[6:7], v[78:79] op_sel_hi:[1,0]
	v_pk_fma_f32 v[0:1], v[0:1], v[20:21], v[38:39]
	v_pk_mul_f32 v[2:3], v[2:3], v[10:11]
	v_and_b32_sdwa v4, v1, v218 dst_sel:DWORD dst_unused:UNUSED_PAD src0_sel:WORD_1 src1_sel:DWORD
	v_pk_fma_f32 v[2:3], v[2:3], v[12:13], v[18:19]
	v_cvt_pk_bf16_f32 v0, v0, v2
	v_add3_u32 v1, v1, v4, s80
	v_and_b32_sdwa v4, v3, v218 dst_sel:DWORD dst_unused:UNUSED_PAD src0_sel:WORD_1 src1_sel:DWORD
	v_add3_u32 v3, v3, v4, s80
	v_and_b32_e32 v3, 0xffff0000, v3
	v_or_b32_sdwa v1, v3, v1 dst_sel:DWORD dst_unused:UNUSED_PAD src0_sel:DWORD src1_sel:WORD_1
	global_store_dwordx2 v[32:33], v[0:1], off offset:1536 nt
	v_mov_b32_e32 v0, v24
	v_mov_b32_e32 v1, v26
	v_pk_mul_f32 v[0:1], v[0:1], v[84:85] op_sel_hi:[1,0]
	v_mov_b32_e32 v26, v25
	v_pk_mul_f32 v[0:1], v[0:1], v[22:23]
	v_pk_mul_f32 v[2:3], v[26:27], v[84:85] op_sel_hi:[1,0]
	v_pk_fma_f32 v[0:1], v[0:1], v[20:21], v[38:39]
	v_pk_mul_f32 v[2:3], v[2:3], v[10:11]
	v_and_b32_sdwa v4, v1, v218 dst_sel:DWORD dst_unused:UNUSED_PAD src0_sel:WORD_1 src1_sel:DWORD
	v_pk_fma_f32 v[2:3], v[2:3], v[12:13], v[18:19]
	v_cvt_pk_bf16_f32 v0, v0, v2
	v_add3_u32 v1, v1, v4, s80
	v_and_b32_sdwa v4, v3, v218 dst_sel:DWORD dst_unused:UNUSED_PAD src0_sel:WORD_1 src1_sel:DWORD
	v_add3_u32 v3, v3, v4, s80
	v_and_b32_e32 v3, 0xffff0000, v3
	v_or_b32_sdwa v1, v3, v1 dst_sel:DWORD dst_unused:UNUSED_PAD src0_sel:DWORD src1_sel:WORD_1
	global_store_dwordx2 v[34:35], v[0:1], off offset:1536 nt
	v_mov_b32_e32 v0, v28
	v_mov_b32_e32 v1, v30
	v_pk_mul_f32 v[0:1], v[0:1], v[82:83] op_sel_hi:[1,0]
	v_mov_b32_e32 v30, v29
	v_pk_mul_f32 v[0:1], v[0:1], v[22:23]
	v_pk_mul_f32 v[2:3], v[30:31], v[82:83] op_sel_hi:[1,0]
	v_pk_fma_f32 v[0:1], v[0:1], v[20:21], v[38:39]
	v_pk_mul_f32 v[2:3], v[2:3], v[10:11]
	v_and_b32_sdwa v4, v1, v218 dst_sel:DWORD dst_unused:UNUSED_PAD src0_sel:WORD_1 src1_sel:DWORD
	v_pk_fma_f32 v[2:3], v[2:3], v[12:13], v[18:19]
	v_cvt_pk_bf16_f32 v0, v0, v2
	v_add3_u32 v1, v1, v4, s80
	v_and_b32_sdwa v4, v3, v218 dst_sel:DWORD dst_unused:UNUSED_PAD src0_sel:WORD_1 src1_sel:DWORD
	v_add3_u32 v3, v3, v4, s80
	v_and_b32_e32 v3, 0xffff0000, v3
	v_or_b32_sdwa v1, v3, v1 dst_sel:DWORD dst_unused:UNUSED_PAD src0_sel:DWORD src1_sel:WORD_1
	global_store_dwordx2 v[36:37], v[0:1], off offset:1536 nt
	s_cbranch_scc1 .LBB0_179

.LBB0_182:
	v_min_i32_e32 v2, 0x4000, v16
	v_ashrrev_i32_e32 v2, 13, v2
	v_mov_b32_e32 v53, v193
	v_lshlrev_b64 v[60:61], 11, v[16:17]
	v_add_u32_e32 v2, s8, v2
	v_lshl_add_u64 v[0:1], v[0:1], 0, v[52:53]
	v_lshl_add_u64 v[16:17], v[44:45], 0, v[60:61]
	v_mul_hi_i32_i24_e32 v63, 0x6000, v2
	v_mul_i32_i24_e32 v62, 0x6000, v2
	global_load_dwordx4 v[12:15], v[0:1], off nt
	global_load_dwordx4 v[8:11], v[0:1], off offset:1024 nt
	global_load_dwordx4 v[4:7], v[0:1], off offset:2048 nt
	s_nop 0
	global_load_dwordx4 v[0:3], v[0:1], off offset:3072 nt
	s_nop 0
	global_load_dwordx2 v[24:25], v[16:17], off nt
	global_load_dwordx2 v[32:33], v[16:17], off offset:512 nt
	global_load_dwordx2 v[40:41], v[16:17], off offset:1024 nt
	global_load_dwordx2 v[76:77], v[16:17], off offset:1536 nt
	v_lshl_add_u64 v[18:19], s[90:91], 0, v[62:63]
	v_lshl_add_u64 v[20:21], v[18:19], 0, v[52:53]
	s_mov_b64 s[0:1], 0x345a000
	v_lshl_add_u64 v[84:85], v[20:21], 0, s[0:1]
	s_mov_b32 s0, 0x345a000
	v_add_co_u32_e32 v20, vcc, s0, v20
	global_load_dwordx4 v[16:19], v[46:47], off
	s_nop 0
	v_addc_co_u32_e32 v21, vcc, 0, v21, vcc
	global_load_dwordx4 v[20:23], v[20:21], off
	s_mov_b32 s0, 0x800000
	s_mov_b64 s[10:11], 0x3000
	v_mov_b32_e32 v59, v193
	s_waitcnt vmcnt(5)
	v_and_b32_e32 v67, 0xffff0000, v24
	s_waitcnt vmcnt(4)
	v_and_b32_e32 v69, 0xffff0000, v32
	v_lshlrev_b32_e32 v66, 16, v24
	v_lshlrev_b32_e32 v68, 16, v32
	v_mov_b32_e32 v34, v67
	v_mov_b32_e32 v35, v69
	v_lshlrev_b32_e32 v70, 16, v25
	v_and_b32_e32 v73, 0xffff0000, v33
	v_lshlrev_b32_e32 v72, 16, v33
	v_mov_b32_e32 v32, v66
	v_mov_b32_e32 v33, v68
	v_pk_mul_f32 v[34:35], v[34:35], v[34:35]
	v_and_b32_e32 v71, 0xffff0000, v25
	global_load_dwordx4 v[28:31], v[46:47], off offset:1024
	global_load_dwordx4 v[24:27], v[84:85], off offset:1024
	v_pk_fma_f32 v[32:33], v[32:33], v[32:33], v[34:35]
	v_mov_b32_e32 v34, v70
	v_mov_b32_e32 v35, v72
	v_mov_b32_e32 v36, v71
	v_mov_b32_e32 v37, v73
	v_pk_fma_f32 v[32:33], v[34:35], v[34:35], v[32:33]
	s_waitcnt vmcnt(5)
	v_and_b32_e32 v75, 0xffff0000, v40
	v_pk_fma_f32 v[78:79], v[36:37], v[36:37], v[32:33]
	global_load_dwordx4 v[36:39], v[46:47], off offset:2048
	global_load_dwordx4 v[32:35], v[84:85], off offset:2048
	v_lshlrev_b32_e32 v74, 16, v40
	v_and_b32_e32 v83, 0xffff0000, v41
	v_lshlrev_b32_e32 v82, 16, v41
	global_load_dwordx4 v[40:43], v[46:47], off offset:3072
	global_load_dwordx4 v[92:95], v[84:85], off offset:3072
	s_waitcnt vmcnt(8)
	v_and_b32_e32 v81, 0xffff0000, v76
	v_lshlrev_b32_e32 v80, 16, v76
	v_mov_b32_e32 v96, v75
	v_mov_b32_e32 v97, v81
	v_and_b32_e32 v85, 0xffff0000, v77
	v_lshlrev_b32_e32 v84, 16, v77
	v_mov_b32_e32 v76, v74
	v_mov_b32_e32 v77, v80
	v_pk_mul_f32 v[96:97], v[96:97], v[96:97]
	v_mov_b32_e32 v98, v83
	v_pk_fma_f32 v[76:77], v[76:77], v[76:77], v[96:97]
	v_mov_b32_e32 v96, v82
	v_mov_b32_e32 v97, v84
	v_mov_b32_e32 v99, v85
	v_pk_fma_f32 v[76:77], v[96:97], v[96:97], v[76:77]
	v_add_f32_e32 v55, v78, v79
	v_pk_fma_f32 v[76:77], v[98:99], v[98:99], v[76:77]
	s_nop 0
	v_add_f32_e32 v55, v55, v76
	v_add_f32_e32 v55, v55, v77
	ds_bpermute_b32 v57, v86, v55
	s_waitcnt lgkmcnt(0)
	v_add_f32_e32 v55, v55, v57
	ds_bpermute_b32 v57, v87, v55
	s_waitcnt lgkmcnt(0)
	v_add_f32_e32 v55, v55, v57
	ds_bpermute_b32 v57, v88, v55
	s_waitcnt lgkmcnt(0)
	v_add_f32_e32 v55, v55, v57
	ds_bpermute_b32 v57, v89, v55
	s_waitcnt lgkmcnt(0)
	v_add_f32_e32 v55, v55, v57
	ds_bpermute_b32 v57, v90, v55
	s_waitcnt lgkmcnt(0)
	v_add_f32_e32 v55, v55, v57
	ds_bpermute_b32 v57, v91, v55
	s_waitcnt lgkmcnt(0)
	v_add_f32_e32 v55, v55, v57
	v_fmamk_f32 v55, v55, 0x3a800000, v219
	v_cmp_gt_f32_e32 vcc, s0, v55
	v_mul_f32_e32 v57, 0x4b800000, v55
	s_nop 0
	v_cndmask_b32_e32 v55, v55, v57, vcc
	v_rsq_f32_e32 v55, v55
	s_nop 0
	v_mul_f32_e32 v57, 0x45800000, v55
	v_cndmask_b32_e32 v76, v55, v57, vcc
	v_pk_mul_f32 v[66:67], v[76:77], v[66:67] op_sel_hi:[0,1]
	s_waitcnt vmcnt(7)
	v_pk_mul_f32 v[16:17], v[16:17], v[66:67]
	v_pk_mul_f32 v[66:67], v[76:77], v[70:71] op_sel_hi:[0,1]
	s_waitcnt vmcnt(6)
	v_pk_fma_f32 v[12:13], v[20:21], v[16:17], v[12:13]
	v_pk_mul_f32 v[16:17], v[76:77], v[68:69] op_sel_hi:[0,1]
	v_pk_mul_f32 v[18:19], v[18:19], v[66:67]
	s_waitcnt vmcnt(5)
	v_pk_mul_f32 v[16:17], v[28:29], v[16:17]
	v_pk_fma_f32 v[14:15], v[22:23], v[18:19], v[14:15]
	v_pk_mul_f32 v[18:19], v[76:77], v[72:73] op_sel_hi:[0,1]
	s_waitcnt vmcnt(4)
	v_pk_fma_f32 v[8:9], v[24:25], v[16:17], v[8:9]
	v_pk_mul_f32 v[16:17], v[76:77], v[74:75] op_sel_hi:[0,1]
	v_pk_mul_f32 v[18:19], v[30:31], v[18:19]
	s_waitcnt vmcnt(3)
	v_pk_mul_f32 v[16:17], v[16:17], v[36:37]
	v_pk_fma_f32 v[10:11], v[26:27], v[18:19], v[10:11]
	v_pk_mul_f32 v[18:19], v[76:77], v[82:83] op_sel_hi:[0,1]
	s_waitcnt vmcnt(2)
	v_pk_fma_f32 v[4:5], v[16:17], v[32:33], v[4:5]
	v_pk_mul_f32 v[16:17], v[76:77], v[80:81] op_sel_hi:[0,1]
	v_mov_b32_e32 v22, v13
	v_mov_b32_e32 v23, v9
	v_pk_mul_f32 v[18:19], v[18:19], v[38:39]
	s_waitcnt vmcnt(1)
	v_pk_mul_f32 v[16:17], v[16:17], v[40:41]
	v_mov_b32_e32 v20, v12
	v_mov_b32_e32 v21, v8
	v_pk_mul_f32 v[22:23], v[22:23], v[22:23]
	v_pk_fma_f32 v[6:7], v[18:19], v[34:35], v[6:7]
	v_pk_mul_f32 v[18:19], v[76:77], v[84:85] op_sel_hi:[0,1]
	s_waitcnt vmcnt(0)
	v_pk_fma_f32 v[0:1], v[16:17], v[92:93], v[0:1]
	v_pk_fma_f32 v[20:21], v[20:21], v[20:21], v[22:23]
	v_mov_b32_e32 v22, v14
	v_mov_b32_e32 v23, v10
	v_pk_mul_f32 v[18:19], v[18:19], v[42:43]
	v_pk_fma_f32 v[20:21], v[22:23], v[22:23], v[20:21]
	v_mov_b32_e32 v22, v15
	v_mov_b32_e32 v23, v11
	v_mov_b32_e32 v24, v5
	v_mov_b32_e32 v25, v1
	v_pk_fma_f32 v[2:3], v[18:19], v[94:95], v[2:3]
	v_pk_fma_f32 v[20:21], v[22:23], v[22:23], v[20:21]
	v_mov_b32_e32 v22, v4
	v_mov_b32_e32 v23, v0
	v_pk_mul_f32 v[24:25], v[24:25], v[24:25]
	v_lshl_add_u64 v[16:17], v[64:65], 0, v[52:53]
	v_pk_fma_f32 v[22:23], v[22:23], v[22:23], v[24:25]
	v_mov_b32_e32 v24, v6
	v_mov_b32_e32 v25, v2
	v_pk_fma_f32 v[22:23], v[24:25], v[24:25], v[22:23]
	v_mov_b32_e32 v24, v7
	v_mov_b32_e32 v25, v3
	v_pk_fma_f32 v[22:23], v[24:25], v[24:25], v[22:23]
	v_add_f32_e32 v20, v20, v21
	global_store_dwordx4 v[16:17], v[12:15], off nt
	global_store_dwordx4 v[16:17], v[8:11], off offset:1024 nt
	global_store_dwordx4 v[16:17], v[4:7], off offset:2048 nt
	global_store_dwordx4 v[16:17], v[0:3], off offset:3072 nt
	v_lshl_add_u64 v[16:17], s[96:97], 0, v[62:63]
	v_add_f32_e32 v20, v20, v22
	v_lshl_add_u64 v[18:19], v[16:17], 0, s[10:11]
	v_add_f32_e32 v22, v20, v23
	s_mov_b64 s[10:11], 0x4000
	v_lshl_add_u64 v[20:21], v[16:17], 0, s[10:11]
	ds_bpermute_b32 v16, v86, v22
	v_lshl_add_u64 v[26:27], v[20:21], 0, v[52:53]
	v_lshl_add_u64 v[30:31], v[18:19], 0, v[52:53]
	v_mov_b32_e32 v34, v12
	v_mov_b32_e32 v35, v14
	s_waitcnt lgkmcnt(0)
	v_add_f32_e32 v16, v22, v16
	global_load_dwordx4 v[22:25], v[48:49], off
	s_nop 0
	global_load_dwordx4 v[26:29], v[26:27], off
	s_nop 0
	global_load_dwordx4 v[30:33], v[30:31], off
	ds_bpermute_b32 v17, v87, v16
	v_mov_b32_e32 v14, v13
	v_mov_b32_e32 v55, v193
	v_mov_b32_e32 v57, v193
	s_waitcnt lgkmcnt(0)
	v_add_f32_e32 v16, v16, v17
	ds_bpermute_b32 v17, v88, v16
	s_waitcnt lgkmcnt(0)
	v_add_f32_e32 v16, v16, v17
	ds_bpermute_b32 v17, v89, v16
	s_waitcnt lgkmcnt(0)
	v_add_f32_e32 v16, v16, v17
	ds_bpermute_b32 v17, v90, v16
	s_waitcnt lgkmcnt(0)
	v_add_f32_e32 v16, v16, v17
	ds_bpermute_b32 v17, v91, v16
	s_waitcnt lgkmcnt(0)
	v_add_f32_e32 v16, v16, v17
	v_fmamk_f32 v16, v16, 0x3a800000, v219
	v_cmp_gt_f32_e32 vcc, s0, v16
	v_mul_f32_e32 v17, 0x4b800000, v16
	v_readlane_b32 s0, v255, 11
	v_cndmask_b32_e32 v16, v16, v17, vcc
	v_rsq_f32_e32 v16, v16
	v_add_u32_e32 v192, s0, v192
	s_movk_i32 s0, 0x1ff
	v_readlane_b32 s1, v255, 12
	v_mul_f32_e32 v17, 0x45800000, v16
	v_cndmask_b32_e32 v16, v16, v17, vcc
	v_pk_mul_f32 v[34:35], v[34:35], v[16:17] op_sel_hi:[1,0]
	v_pk_mul_f32 v[12:13], v[14:15], v[16:17] op_sel_hi:[1,0]
	v_cmp_lt_i32_e32 vcc, s0, v192
	s_or_b64 s[6:7], vcc, s[6:7]
	s_waitcnt vmcnt(2)
	v_mov_b32_e32 v36, v22
	v_mov_b32_e32 v37, v24
	v_pk_mul_f32 v[34:35], v[36:37], v[34:35]
	s_waitcnt vmcnt(1)
	v_mov_b32_e32 v36, v26
	v_mov_b32_e32 v37, v28
	v_pk_add_f32 v[36:37], v[36:37], 1.0 op_sel_hi:[1,0]
	s_waitcnt vmcnt(0)
	v_mov_b32_e32 v38, v30
	v_mov_b32_e32 v39, v32
	v_mov_b32_e32 v24, v23
	v_mov_b32_e32 v28, v27
	v_pk_fma_f32 v[34:35], v[36:37], v[34:35], v[38:39]
	v_pk_mul_f32 v[12:13], v[24:25], v[12:13]
	v_pk_add_f32 v[14:15], v[28:29], 1.0 op_sel_hi:[1,0]
	v_mov_b32_e32 v32, v31
	v_pk_fma_f32 v[12:13], v[14:15], v[12:13], v[32:33]
	v_and_b32_sdwa v15, v34, v218 dst_sel:DWORD dst_unused:UNUSED_PAD src0_sel:WORD_1 src1_sel:DWORD
	v_add3_u32 v17, v34, v15, s80
	v_and_b32_sdwa v22, v12, v218 dst_sel:DWORD dst_unused:UNUSED_PAD src0_sel:WORD_1 src1_sel:DWORD
	v_cvt_pk_bf16_f32 v15, v35, v13
	v_add3_u32 v12, v12, v22, s80
	v_and_b32_e32 v12, 0xffff0000, v12
	v_or_b32_sdwa v14, v12, v17 dst_sel:DWORD dst_unused:UNUSED_PAD src0_sel:DWORD src1_sel:WORD_1
	v_lshl_add_u64 v[12:13], v[50:51], 0, v[60:61]
	global_store_dwordx2 v[12:13], v[14:15], off nt
	v_lshl_add_u64 v[30:31], v[18:19], 0, v[54:55]
	v_lshl_add_u64 v[14:15], v[20:21], 0, v[54:55]
	global_load_dwordx4 v[22:25], v[48:49], off offset:1024
	global_load_dwordx4 v[26:29], v[14:15], off
	s_nop 0
	global_load_dwordx4 v[30:33], v[30:31], off
	v_mov_b32_e32 v14, v8
	v_mov_b32_e32 v15, v10
	v_pk_mul_f32 v[14:15], v[14:15], v[16:17] op_sel_hi:[1,0]
	v_mov_b32_e32 v10, v9
	v_pk_mul_f32 v[8:9], v[10:11], v[16:17] op_sel_hi:[1,0]
	s_waitcnt vmcnt(2)
	v_mov_b32_e32 v34, v22
	v_mov_b32_e32 v35, v24
	v_pk_mul_f32 v[14:15], v[14:15], v[34:35]
	s_waitcnt vmcnt(1)
	v_mov_b32_e32 v34, v26
	v_mov_b32_e32 v35, v28
	v_pk_add_f32 v[34:35], v[34:35], 1.0 op_sel_hi:[1,0]
	s_waitcnt vmcnt(0)
	v_mov_b32_e32 v36, v30
	v_mov_b32_e32 v37, v32
	v_mov_b32_e32 v24, v23
	v_mov_b32_e32 v28, v27
	v_pk_fma_f32 v[14:15], v[14:15], v[34:35], v[36:37]
	v_pk_mul_f32 v[8:9], v[8:9], v[24:25]
	v_pk_add_f32 v[10:11], v[28:29], 1.0 op_sel_hi:[1,0]
	v_mov_b32_e32 v32, v31
	v_pk_fma_f32 v[8:9], v[8:9], v[10:11], v[32:33]
	v_cvt_pk_bf16_f32 v8, v14, v8
	v_cvt_pk_bf16_f32 v9, v15, v9
	global_store_dwordx2 v[12:13], v[8:9], off offset:512 nt
	v_lshl_add_u64 v[26:27], v[18:19], 0, v[56:57]
	v_lshl_add_u64 v[14:15], v[20:21], 0, v[56:57]
	global_load_dwordx4 v[8:11], v[48:49], off offset:2048
	global_load_dwordx4 v[22:25], v[14:15], off
	s_nop 0
	global_load_dwordx4 v[26:29], v[26:27], off
	v_mov_b32_e32 v14, v4
	v_mov_b32_e32 v15, v6
	v_pk_mul_f32 v[14:15], v[14:15], v[16:17] op_sel_hi:[1,0]
	v_mov_b32_e32 v6, v5
	v_pk_mul_f32 v[4:5], v[6:7], v[16:17] op_sel_hi:[1,0]
	s_waitcnt vmcnt(2)
	v_mov_b32_e32 v30, v8
	v_mov_b32_e32 v31, v10
	v_pk_mul_f32 v[14:15], v[14:15], v[30:31]
	s_waitcnt vmcnt(1)
	v_mov_b32_e32 v31, v24
	v_mov_b32_e32 v10, v9
	v_mov_b32_e32 v24, v23
	v_mov_b32_e32 v30, v22
	s_waitcnt vmcnt(0)
	v_mov_b32_e32 v33, v28
	v_pk_mul_f32 v[4:5], v[4:5], v[10:11]
	v_pk_add_f32 v[6:7], v[24:25], 1.0 op_sel_hi:[1,0]
	v_mov_b32_e32 v28, v27
	v_pk_add_f32 v[30:31], v[30:31], 1.0 op_sel_hi:[1,0]
	v_mov_b32_e32 v32, v26
	v_pk_fma_f32 v[4:5], v[4:5], v[6:7], v[28:29]
	v_pk_fma_f32 v[14:15], v[14:15], v[30:31], v[32:33]
	v_cvt_pk_bf16_f32 v5, v15, v5
	v_cvt_pk_bf16_f32 v4, v14, v4
	global_store_dwordx2 v[12:13], v[4:5], off offset:1024 nt
	v_lshl_add_u64 v[8:9], v[20:21], 0, v[58:59]
	v_lshl_add_u64 v[14:15], v[18:19], 0, v[58:59]
	global_load_dwordx4 v[4:7], v[48:49], off offset:3072
	s_nop 0
	global_load_dwordx4 v[8:11], v[8:9], off
	s_nop 0
	global_load_dwordx4 v[18:21], v[14:15], off
	v_mov_b32_e32 v14, v0
	v_mov_b32_e32 v15, v2
	v_pk_mul_f32 v[14:15], v[14:15], v[16:17] op_sel_hi:[1,0]
	v_mov_b32_e32 v2, v1
	v_pk_mul_f32 v[0:1], v[2:3], v[16:17] op_sel_hi:[1,0]
	s_waitcnt vmcnt(2)
	v_mov_b32_e32 v22, v4
	v_mov_b32_e32 v23, v6
	v_pk_mul_f32 v[14:15], v[14:15], v[22:23]
	s_waitcnt vmcnt(1)
	v_mov_b32_e32 v23, v10
	v_mov_b32_e32 v6, v5
	v_mov_b32_e32 v10, v9
	v_mov_b32_e32 v22, v8
	s_waitcnt vmcnt(0)
	v_mov_b32_e32 v25, v20
	v_pk_mul_f32 v[0:1], v[0:1], v[6:7]
	v_pk_add_f32 v[2:3], v[10:11], 1.0 op_sel_hi:[1,0]
	v_mov_b32_e32 v20, v19
	v_pk_add_f32 v[22:23], v[22:23], 1.0 op_sel_hi:[1,0]
	v_mov_b32_e32 v24, v18
	v_pk_fma_f32 v[0:1], v[0:1], v[2:3], v[20:21]
	v_pk_fma_f32 v[14:15], v[14:15], v[22:23], v[24:25]
	v_cvt_pk_bf16_f32 v1, v15, v1
	v_cvt_pk_bf16_f32 v0, v14, v0
	global_store_dwordx2 v[12:13], v[0:1], off offset:1536 nt
	s_andn2_b64 exec, exec, s[6:7]
	s_cbranch_execz .LBB0_188

.LBB0_204:
	s_abs_i32 s4, s0
	v_readlane_b32 s5, v254, 51
	s_mul_hi_u32 s5, s4, s5
	s_mul_i32 s6, s5, s8
	s_sub_i32 s4, s4, s6
	s_ashr_i32 s1, s0, 31
	s_add_i32 s6, s5, 1
	s_sub_i32 s7, s4, s8
	s_cmp_ge_u32 s4, s8
	s_cselect_b32 s5, s6, s5
	s_cselect_b32 s4, s7, s4
	s_add_i32 s6, s5, 1
	s_cmp_ge_u32 s4, s8
	s_cselect_b32 s4, s6, s5
	s_xor_b32 s4, s4, s1
	s_sub_i32 s4, s4, s1
	s_lshr_b32 s1, s1, 30
	s_add_i32 s1, s0, s1
	s_ashr_i32 s5, s1, 2
	s_abs_i32 s5, s5
	v_readlane_b32 s7, v254, 53
	s_mul_hi_u32 s7, s5, s7
	v_readlane_b32 s8, v254, 52
	s_mul_i32 s7, s7, s8
	s_and_b32 s6, s1, 0xfffffc
	s_sub_i32 s5, s5, s7
	s_sub_i32 s6, s0, s6
	s_ashr_i32 s1, s1, 31
	s_sub_i32 s7, s5, s8
	s_cmp_ge_u32 s5, s8
	s_cselect_b32 s5, s7, s5
	s_sub_i32 s7, s5, s8
	s_cmp_ge_u32 s5, s8
	s_cselect_b32 s5, s7, s5
	s_xor_b32 s5, s5, s1
	s_sub_i32 s1, s5, s1
	v_readlane_b32 s5, v254, 47
	s_add_i32 s5, s5, s1
	s_lshl_b32 s1, s4, 10
	s_lshl_b32 s4, s6, 8
	v_mov_b32_e32 v203, v208
	s_add_i32 s1, s1, s4
	v_readlane_b32 s6, v253, 34
	v_ashrrev_i32_e32 v4, 2, v203
	v_add_u32_e32 v0, s1, v4
	v_ashrrev_i32_e32 v1, 31, v0
	v_lshlrev_b64 v[0:1], 11, v[0:1]
	v_readlane_b32 s7, v253, 35
	v_lshlrev_b32_e32 v5, 4, v203
	s_mul_i32 s4, s5, 0xc0
	v_lshl_add_u64 v[0:1], s[6:7], 0, v[0:1]
	v_and_b32_e32 v192, 48, v5
	v_lshl_add_u64 v[100:101], v[0:1], 0, v[192:193]
	v_add_u32_e32 v0, s4, v4
	v_ashrrev_i32_e32 v1, 31, v0
	v_readlane_b32 s6, v253, 61
	s_mov_b32 s5, 0x20000
	v_lshlrev_b64 v[0:1], 11, v[0:1]
	v_readlane_b32 s7, v253, 62
	v_add_co_u32_e32 v8, vcc, s5, v100
	s_nop 0
	v_lshl_add_u64 v[0:1], s[6:7], 0, v[0:1]
	v_addc_co_u32_e32 v9, vcc, 0, v101, vcc
	s_mov_b32 s6, 0x40000
	v_add_co_u32_e32 v12, vcc, s6, v100
	v_lshl_add_u64 v[102:103], v[0:1], 0, v[192:193]
	s_nop 0
	v_addc_co_u32_e32 v13, vcc, 0, v101, vcc
	v_add_co_u32_e32 v16, vcc, s75, v100
	v_bfe_u32 v6, v203, 5, 1
	s_nop 0
	v_addc_co_u32_e32 v17, vcc, 0, v101, vcc
	v_lshrrev_b32_e32 v7, 2, v203
	v_bfe_u32 v10, v203, 2, 2
	v_add_co_u32_e32 v24, vcc, s5, v102
	v_lshlrev_b32_e32 v11, 1, v203
	v_bitop3_b32 v7, v6, v7, 3 bitop3:0x78
	v_bitop3_b32 v6, v6, v10, 2 bitop3:0x36
	v_and_b32_e32 v10, 0xffffffe0, v4
	v_addc_co_u32_e32 v25, vcc, 0, v103, vcc
	v_and_b32_e32 v192, 31, v203
	v_and_b32_e32 v204, 0x80, v11
	v_lshl_add_u32 v205, v10, 1, v10
	v_add_co_u32_e32 v28, vcc, s6, v102
	v_or_b32_e32 v11, v204, v192
	v_or_b32_e32 v10, v205, v192
	global_load_dwordx4 v[0:3], v[100:101], off
	global_load_dwordx4 v[32:35], v[8:9], off
	global_load_dwordx4 v[36:39], v[12:13], off
	global_load_dwordx4 v[40:43], v[16:17], off
	global_load_dwordx4 v[44:47], v[102:103], off
	v_addc_co_u32_e32 v29, vcc, 0, v103, vcc
	v_bitop3_b32 v5, v5, 48, v203 bitop3:0x48
	v_lshlrev_b32_e32 v11, 6, v11
	v_lshlrev_b32_e32 v7, 4, v7
	v_lshlrev_b32_e32 v6, 4, v6
	v_lshl_add_u32 v10, v10, 6, v214
	global_load_dwordx4 v[48:51], v[24:25], off
	global_load_dwordx4 v[52:55], v[28:29], off
	v_or_b32_e32 v114, v11, v7
	v_or_b32_e32 v115, v11, v6
	v_or_b32_e32 v116, v10, v7
	v_or_b32_e32 v117, v10, v6
	v_lshl_or_b32 v118, v4, 6, v5
	global_load_dwordx4 v[4:7], v[100:101], off offset:64
	s_nop 0
	global_load_dwordx4 v[8:11], v[8:9], off offset:64
	s_nop 0
	global_load_dwordx4 v[12:15], v[12:13], off offset:64
	s_nop 0
	global_load_dwordx4 v[16:19], v[16:17], off offset:64
	s_nop 0
	global_load_dwordx4 v[20:23], v[102:103], off offset:64
	s_nop 0
	global_load_dwordx4 v[24:27], v[24:25], off offset:64
	s_nop 0
	global_load_dwordx4 v[28:31], v[28:29], off offset:64
	v_accvgpr_mov_b32 a193, a192
	v_accvgpr_mov_b32 a194, a192
	v_accvgpr_mov_b32 a195, a192
	v_accvgpr_mov_b32 a196, a192
	v_accvgpr_mov_b32 a197, a192
	v_accvgpr_mov_b32 a198, a192
	v_accvgpr_mov_b32 a199, a192
	v_accvgpr_mov_b32 a200, a192
	v_accvgpr_mov_b32 a201, a192
	v_accvgpr_mov_b32 a202, a192
	v_accvgpr_mov_b32 a203, a192
	v_accvgpr_mov_b32 a204, a192
	v_accvgpr_mov_b32 a205, a192
	v_accvgpr_mov_b32 a206, a192
	v_accvgpr_mov_b32 a207, a192
	v_accvgpr_mov_b32 a0, a192
	v_accvgpr_mov_b32 a16, a192
	v_accvgpr_mov_b32 a32, a192
	v_accvgpr_write_b32 a63, 0
	v_accvgpr_write_b32 a62, 0
	v_accvgpr_write_b32 a61, 0
	v_accvgpr_write_b32 a60, 0
	v_accvgpr_write_b32 a59, 0
	v_accvgpr_write_b32 a58, 0
	v_accvgpr_write_b32 a57, 0
	v_accvgpr_write_b32 a56, 0
	v_accvgpr_write_b32 a55, 0
	v_accvgpr_write_b32 a54, 0
	v_accvgpr_write_b32 a53, 0
	v_accvgpr_write_b32 a52, 0
	v_accvgpr_write_b32 a51, 0
	v_accvgpr_write_b32 a50, 0
	v_accvgpr_write_b32 a49, 0
	v_accvgpr_write_b32 a48, 0
	v_accvgpr_write_b32 a79, 0
	v_accvgpr_write_b32 a78, 0
	v_accvgpr_write_b32 a77, 0
	v_accvgpr_write_b32 a76, 0
	v_accvgpr_write_b32 a75, 0
	v_accvgpr_write_b32 a74, 0
	v_accvgpr_write_b32 a73, 0
	v_accvgpr_write_b32 a72, 0
	v_accvgpr_write_b32 a71, 0
	v_accvgpr_write_b32 a70, 0
	v_accvgpr_write_b32 a69, 0
	v_accvgpr_write_b32 a68, 0
	v_accvgpr_write_b32 a67, 0
	v_accvgpr_write_b32 a66, 0
	v_accvgpr_write_b32 a65, 0
	v_accvgpr_write_b32 a64, 0
	v_accvgpr_write_b32 a95, 0
	v_accvgpr_write_b32 a94, 0
	v_accvgpr_write_b32 a93, 0
	v_accvgpr_write_b32 a92, 0
	v_accvgpr_write_b32 a91, 0
	v_accvgpr_write_b32 a90, 0
	v_accvgpr_write_b32 a89, 0
	v_accvgpr_write_b32 a88, 0
	v_accvgpr_write_b32 a87, 0
	v_accvgpr_write_b32 a86, 0
	v_accvgpr_write_b32 a85, 0
	v_accvgpr_write_b32 a84, 0
	v_accvgpr_write_b32 a83, 0
	v_accvgpr_write_b32 a82, 0
	v_accvgpr_write_b32 a81, 0
	v_accvgpr_write_b32 a80, 0
	v_accvgpr_write_b32 a111, 0
	v_accvgpr_write_b32 a110, 0
	v_accvgpr_write_b32 a109, 0
	v_accvgpr_write_b32 a108, 0
	v_accvgpr_write_b32 a107, 0
	v_accvgpr_write_b32 a106, 0
	v_accvgpr_write_b32 a105, 0
	v_accvgpr_write_b32 a104, 0
	v_accvgpr_write_b32 a103, 0
	v_accvgpr_write_b32 a102, 0
	v_accvgpr_write_b32 a101, 0
	v_accvgpr_write_b32 a100, 0
	v_accvgpr_write_b32 a99, 0
	v_accvgpr_write_b32 a98, 0
	v_accvgpr_write_b32 a97, 0
	v_accvgpr_write_b32 a96, 0
	v_accvgpr_write_b32 a127, 0
	v_accvgpr_write_b32 a126, 0
	v_accvgpr_write_b32 a125, 0
	v_accvgpr_write_b32 a124, 0
	v_accvgpr_write_b32 a123, 0
	v_accvgpr_write_b32 a122, 0
	v_accvgpr_write_b32 a121, 0
	v_accvgpr_write_b32 a120, 0
	v_accvgpr_write_b32 a119, 0
	v_accvgpr_write_b32 a118, 0
	v_accvgpr_write_b32 a117, 0
	v_accvgpr_write_b32 a116, 0
	v_accvgpr_write_b32 a115, 0
	v_accvgpr_write_b32 a114, 0
	v_accvgpr_write_b32 a113, 0
	v_accvgpr_write_b32 a112, 0
	v_accvgpr_write_b32 a143, 0
	v_accvgpr_write_b32 a142, 0
	v_accvgpr_write_b32 a141, 0
	v_accvgpr_write_b32 a140, 0
	v_accvgpr_write_b32 a139, 0
	v_accvgpr_write_b32 a138, 0
	v_accvgpr_write_b32 a137, 0
	v_accvgpr_write_b32 a136, 0
	v_accvgpr_write_b32 a135, 0
	v_accvgpr_write_b32 a134, 0
	v_accvgpr_write_b32 a133, 0
	v_accvgpr_write_b32 a132, 0
	v_accvgpr_write_b32 a131, 0
	v_accvgpr_write_b32 a130, 0
	v_accvgpr_write_b32 a129, 0
	v_accvgpr_write_b32 a128, 0
	v_accvgpr_write_b32 a159, 0
	v_accvgpr_write_b32 a158, 0
	v_accvgpr_write_b32 a157, 0
	v_accvgpr_write_b32 a156, 0
	v_accvgpr_write_b32 a155, 0
	v_accvgpr_write_b32 a154, 0
	v_accvgpr_write_b32 a153, 0
	v_accvgpr_write_b32 a152, 0
	v_accvgpr_write_b32 a151, 0
	v_accvgpr_write_b32 a150, 0
	v_accvgpr_write_b32 a149, 0
	v_accvgpr_write_b32 a148, 0
	v_accvgpr_write_b32 a147, 0
	v_accvgpr_write_b32 a146, 0
	v_accvgpr_write_b32 a145, 0
	v_accvgpr_write_b32 a144, 0
	v_accvgpr_write_b32 a175, 0
	v_accvgpr_write_b32 a174, 0
	v_accvgpr_write_b32 a173, 0
	v_accvgpr_write_b32 a172, 0
	v_accvgpr_write_b32 a171, 0
	v_accvgpr_write_b32 a170, 0
	v_accvgpr_write_b32 a169, 0
	v_accvgpr_write_b32 a168, 0
	v_accvgpr_write_b32 a167, 0
	v_accvgpr_write_b32 a166, 0
	v_accvgpr_write_b32 a165, 0
	v_accvgpr_write_b32 a164, 0
	v_accvgpr_write_b32 a163, 0
	v_accvgpr_write_b32 a162, 0
	v_accvgpr_write_b32 a161, 0
	v_accvgpr_write_b32 a160, 0
	v_accvgpr_write_b32 a191, 0
	v_accvgpr_write_b32 a190, 0
	v_accvgpr_write_b32 a189, 0
	v_accvgpr_write_b32 a188, 0
	v_accvgpr_write_b32 a187, 0
	v_accvgpr_write_b32 a186, 0
	v_accvgpr_write_b32 a185, 0
	v_accvgpr_write_b32 a184, 0
	v_accvgpr_write_b32 a183, 0
	v_accvgpr_write_b32 a182, 0
	v_accvgpr_write_b32 a181, 0
	v_accvgpr_write_b32 a180, 0
	v_accvgpr_write_b32 a179, 0
	v_accvgpr_write_b32 a178, 0
	v_accvgpr_write_b32 a177, 0
	v_accvgpr_write_b32 a176, 0
	v_accvgpr_mov_b32 a1, a193
	v_accvgpr_mov_b32 a2, a194
	v_accvgpr_mov_b32 a3, a195
	v_accvgpr_mov_b32 a4, a196
	v_accvgpr_mov_b32 a5, a197
	v_accvgpr_mov_b32 a6, a198
	v_accvgpr_mov_b32 a7, a199
	v_accvgpr_mov_b32 a8, a200
	v_accvgpr_mov_b32 a9, a201
	v_accvgpr_mov_b32 a10, a202
	v_accvgpr_mov_b32 a11, a203
	v_accvgpr_mov_b32 a12, a204
	v_accvgpr_mov_b32 a13, a205
	v_accvgpr_mov_b32 a14, a206
	v_accvgpr_mov_b32 a15, a207
	v_accvgpr_mov_b32 a17, a193
	v_accvgpr_mov_b32 a18, a194
	v_accvgpr_mov_b32 a19, a195
	v_accvgpr_mov_b32 a20, a196
	v_accvgpr_mov_b32 a21, a197
	v_accvgpr_mov_b32 a22, a198
	v_accvgpr_mov_b32 a23, a199
	v_accvgpr_mov_b32 a24, a200
	v_accvgpr_mov_b32 a25, a201
	v_accvgpr_mov_b32 a26, a202
	v_accvgpr_mov_b32 a27, a203
	v_accvgpr_mov_b32 a28, a204
	v_accvgpr_mov_b32 a29, a205
	v_accvgpr_mov_b32 a30, a206
	v_accvgpr_mov_b32 a31, a207
	v_accvgpr_mov_b32 a33, a193
	v_accvgpr_mov_b32 a34, a194
	v_accvgpr_mov_b32 a35, a195
	v_accvgpr_mov_b32 a36, a196
	v_accvgpr_mov_b32 a37, a197
	v_accvgpr_mov_b32 a38, a198
	v_accvgpr_mov_b32 a39, a199
	v_accvgpr_mov_b32 a40, a200
	v_accvgpr_mov_b32 a41, a201
	v_accvgpr_mov_b32 a42, a202
	v_accvgpr_mov_b32 a43, a203
	v_accvgpr_mov_b32 a44, a204
	v_accvgpr_mov_b32 a45, a205
	v_accvgpr_mov_b32 a46, a206
	v_accvgpr_mov_b32 a47, a207
	s_waitcnt vmcnt(13)
	ds_write_b128 v118, v[0:3] offset:0
	s_waitcnt vmcnt(12)
	ds_write_b128 v118, v[32:35] offset:0x1000
	s_waitcnt vmcnt(11)
	ds_write_b128 v118, v[36:39] offset:0x2000
	s_mov_b64 s[10:11], 0x20000
	s_mov_b64 s[8:9], 0x40000
	s_mov_b64 s[12:13], 0x60000
	v_mov_b32_e32 v0, 0
	s_waitcnt vmcnt(10)
	ds_write_b128 v118, v[40:43] offset:0x3000
	s_waitcnt vmcnt(9)
	ds_write_b128 v118, v[44:47] offset:0x4000
	s_waitcnt vmcnt(8)
	ds_write_b128 v118, v[48:51] offset:0x5000
	s_waitcnt vmcnt(7)
	ds_write_b128 v118, v[52:55] offset:0x6000
	s_waitcnt lgkmcnt(0)
	v_lshl_add_u64 v[104:105], v[100:101], 0, s[10:11]
	s_mov_b32 s6, 0
	v_lshl_add_u64 v[106:107], v[100:101], 0, s[8:9]
	v_lshl_add_u64 v[108:109], v[100:101], 0, s[12:13]
	v_lshl_add_u64 v[110:111], v[102:103], 0, s[10:11]
	v_lshl_add_u64 v[112:113], v[102:103], 0, s[8:9]
	s_mov_b32 s5, -2
	v_mov_b32_e32 v1, v0
	v_mov_b32_e32 v2, v0
	v_mov_b32_e32 v3, v0
	v_mov_b32_e32 v194, v0
	v_mov_b32_e32 v195, v0
	v_mov_b32_e32 v196, v0
	v_mov_b32_e32 v197, v0
	v_mov_b32_e32 v32, v0
	v_mov_b32_e32 v33, v0
	v_mov_b32_e32 v34, v0
	v_mov_b32_e32 v35, v0
	s_barrier

.LBB0_223:
	s_abs_i32 s2, s0
	v_readlane_b32 s3, v254, 58
	s_mul_hi_u32 s3, s2, s3
	s_mul_i32 s4, s3, s6
	s_sub_i32 s2, s2, s4
	s_ashr_i32 s1, s0, 31
	s_add_i32 s4, s3, 1
	s_sub_i32 s5, s2, s6
	s_cmp_ge_u32 s2, s6
	s_cselect_b32 s3, s4, s3
	s_cselect_b32 s2, s5, s2
	s_add_i32 s4, s3, 1
	s_cmp_ge_u32 s2, s6
	s_cselect_b32 s2, s4, s3
	s_xor_b32 s2, s2, s1
	s_sub_i32 s2, s2, s1
	s_lshr_b32 s1, s1, 30
	s_add_i32 s1, s0, s1
	s_ashr_i32 s3, s1, 2
	s_abs_i32 s3, s3
	v_readlane_b32 s5, v254, 60
	s_mul_hi_u32 s5, s3, s5
	v_readlane_b32 s6, v254, 59
	s_mul_i32 s5, s5, s6
	s_and_b32 s4, s1, 0xfffffc
	s_sub_i32 s3, s3, s5
	s_sub_i32 s4, s0, s4
	s_ashr_i32 s1, s1, 31
	s_sub_i32 s5, s3, s6
	s_cmp_ge_u32 s3, s6
	s_cselect_b32 s3, s5, s3
	s_sub_i32 s5, s3, s6
	s_cmp_ge_u32 s3, s6
	s_cselect_b32 s3, s5, s3
	s_xor_b32 s3, s3, s1
	s_sub_i32 s1, s3, s1
	v_readlane_b32 s3, v254, 54
	s_add_i32 s3, s3, s1
	s_lshl_b32 s1, s2, 10
	s_lshl_b32 s2, s4, 8
	v_mov_b32_e32 v136, v208
	s_add_i32 s1, s1, s2
	v_readlane_b32 s4, v253, 34
	v_ashrrev_i32_e32 v4, 2, v136
	v_add_u32_e32 v0, s1, v4
	v_ashrrev_i32_e32 v1, 31, v0
	s_lshl_b32 s2, s3, 7
	v_lshlrev_b64 v[0:1], 11, v[0:1]
	v_readlane_b32 s5, v253, 35
	v_lshlrev_b32_e32 v5, 4, v136
	s_addk_i32 s2, 0x3000
	v_lshl_add_u64 v[0:1], s[4:5], 0, v[0:1]
	v_and_b32_e32 v192, 48, v5
	v_lshl_add_u64 v[68:69], v[0:1], 0, v[192:193]
	v_add_u32_e32 v0, s2, v4
	v_ashrrev_i32_e32 v1, 31, v0
	v_readlane_b32 s4, v253, 61
	s_mov_b32 s3, 0x20000
	v_lshlrev_b64 v[0:1], 11, v[0:1]
	v_readlane_b32 s5, v253, 62
	v_add_co_u32_e32 v8, vcc, s3, v68
	s_nop 0
	v_lshl_add_u64 v[0:1], s[4:5], 0, v[0:1]
	v_addc_co_u32_e32 v9, vcc, 0, v69, vcc
	s_mov_b32 s4, 0x40000
	v_add_co_u32_e32 v12, vcc, s4, v68
	v_bfe_u32 v6, v136, 5, 1
	s_nop 0
	v_addc_co_u32_e32 v13, vcc, 0, v69, vcc
	v_lshrrev_b32_e32 v7, 2, v136
	v_bfe_u32 v10, v136, 2, 2
	v_add_co_u32_e32 v16, vcc, s75, v68
	v_lshlrev_b32_e32 v11, 1, v136
	v_bitop3_b32 v7, v6, v7, 3 bitop3:0x78
	v_bitop3_b32 v6, v6, v10, 2 bitop3:0x36
	v_ashrrev_i32_e32 v10, 1, v136
	v_lshl_add_u64 v[70:71], v[0:1], 0, v[192:193]
	v_addc_co_u32_e32 v17, vcc, 0, v69, vcc
	v_and_b32_e32 v137, 31, v136
	s_waitcnt vmcnt(7)
	v_and_b32_e32 v138, 0x80, v11
	v_and_b32_e32 v139, 0xffffffc0, v10
	v_add_co_u32_e32 v24, vcc, s3, v70
	v_or_b32_e32 v11, v138, v137
	v_or_b32_e32 v10, v139, v137
	global_load_dwordx4 v[0:3], v[68:69], off
	global_load_dwordx4 v[28:31], v[8:9], off
	global_load_dwordx4 v[32:35], v[12:13], off
	global_load_dwordx4 v[36:39], v[16:17], off
	global_load_dwordx4 v[40:43], v[70:71], off
	v_addc_co_u32_e32 v25, vcc, 0, v71, vcc
	v_bitop3_b32 v5, v5, 48, v136 bitop3:0x48
	v_lshlrev_b32_e32 v11, 6, v11
	v_lshlrev_b32_e32 v7, 4, v7
	v_lshlrev_b32_e32 v6, 4, v6
	v_lshl_add_u32 v10, v10, 6, v214
	global_load_dwordx4 v[44:47], v[24:25], off
	v_or_b32_e32 v80, v11, v7
	v_or_b32_e32 v81, v11, v6
	v_or_b32_e32 v82, v10, v7
	v_or_b32_e32 v83, v10, v6
	v_lshl_or_b32 v84, v4, 6, v5
	global_load_dwordx4 v[4:7], v[68:69], off offset:64
	s_nop 0
	global_load_dwordx4 v[8:11], v[8:9], off offset:64
	s_nop 0
	global_load_dwordx4 v[12:15], v[12:13], off offset:64
	s_nop 0
	global_load_dwordx4 v[16:19], v[16:17], off offset:64
	s_nop 0
	global_load_dwordx4 v[20:23], v[70:71], off offset:64
	s_nop 0
	global_load_dwordx4 v[24:27], v[24:25], off offset:64
	v_accvgpr_mov_b32 a193, a192
	v_accvgpr_mov_b32 a194, a192
	v_accvgpr_mov_b32 a195, a192
	v_accvgpr_mov_b32 a196, a192
	v_accvgpr_mov_b32 a197, a192
	v_accvgpr_mov_b32 a198, a192
	v_accvgpr_mov_b32 a199, a192
	v_accvgpr_mov_b32 a200, a192
	v_accvgpr_mov_b32 a201, a192
	v_accvgpr_mov_b32 a202, a192
	v_accvgpr_mov_b32 a203, a192
	v_accvgpr_mov_b32 a204, a192
	v_accvgpr_mov_b32 a205, a192
	v_accvgpr_mov_b32 a206, a192
	v_accvgpr_mov_b32 a207, a192
	v_accvgpr_mov_b32 a0, a192
	v_accvgpr_mov_b32 a16, a192
	v_accvgpr_write_b32 a47, 0
	v_accvgpr_write_b32 a46, 0
	v_accvgpr_write_b32 a45, 0
	v_accvgpr_write_b32 a44, 0
	v_accvgpr_write_b32 a43, 0
	v_accvgpr_write_b32 a42, 0
	v_accvgpr_write_b32 a41, 0
	v_accvgpr_write_b32 a40, 0
	v_accvgpr_write_b32 a39, 0
	v_accvgpr_write_b32 a38, 0
	v_accvgpr_write_b32 a37, 0
	v_accvgpr_write_b32 a36, 0
	v_accvgpr_write_b32 a35, 0
	v_accvgpr_write_b32 a34, 0
	v_accvgpr_write_b32 a33, 0
	v_accvgpr_write_b32 a32, 0
	v_accvgpr_write_b32 a63, 0
	v_accvgpr_write_b32 a62, 0
	v_accvgpr_write_b32 a61, 0
	v_accvgpr_write_b32 a60, 0
	v_accvgpr_write_b32 a59, 0
	v_accvgpr_write_b32 a58, 0
	v_accvgpr_write_b32 a57, 0
	v_accvgpr_write_b32 a56, 0
	v_accvgpr_write_b32 a55, 0
	v_accvgpr_write_b32 a54, 0
	v_accvgpr_write_b32 a53, 0
	v_accvgpr_write_b32 a52, 0
	v_accvgpr_write_b32 a51, 0
	v_accvgpr_write_b32 a50, 0
	v_accvgpr_write_b32 a49, 0
	v_accvgpr_write_b32 a48, 0
	v_accvgpr_write_b32 a79, 0
	v_accvgpr_write_b32 a78, 0
	v_accvgpr_write_b32 a77, 0
	v_accvgpr_write_b32 a76, 0
	v_accvgpr_write_b32 a75, 0
	v_accvgpr_write_b32 a74, 0
	v_accvgpr_write_b32 a73, 0
	v_accvgpr_write_b32 a72, 0
	v_accvgpr_write_b32 a71, 0
	v_accvgpr_write_b32 a70, 0
	v_accvgpr_write_b32 a69, 0
	v_accvgpr_write_b32 a68, 0
	v_accvgpr_write_b32 a67, 0
	v_accvgpr_write_b32 a66, 0
	v_accvgpr_write_b32 a65, 0
	v_accvgpr_write_b32 a64, 0
	v_accvgpr_write_b32 a95, 0
	v_accvgpr_write_b32 a94, 0
	v_accvgpr_write_b32 a93, 0
	v_accvgpr_write_b32 a92, 0
	v_accvgpr_write_b32 a91, 0
	v_accvgpr_write_b32 a90, 0
	v_accvgpr_write_b32 a89, 0
	v_accvgpr_write_b32 a88, 0
	v_accvgpr_write_b32 a87, 0
	v_accvgpr_write_b32 a86, 0
	v_accvgpr_write_b32 a85, 0
	v_accvgpr_write_b32 a84, 0
	v_accvgpr_write_b32 a83, 0
	v_accvgpr_write_b32 a82, 0
	v_accvgpr_write_b32 a81, 0
	v_accvgpr_write_b32 a80, 0
	v_accvgpr_write_b32 a111, 0
	v_accvgpr_write_b32 a110, 0
	v_accvgpr_write_b32 a109, 0
	v_accvgpr_write_b32 a108, 0
	v_accvgpr_write_b32 a107, 0
	v_accvgpr_write_b32 a106, 0
	v_accvgpr_write_b32 a105, 0
	v_accvgpr_write_b32 a104, 0
	v_accvgpr_write_b32 a103, 0
	v_accvgpr_write_b32 a102, 0
	v_accvgpr_write_b32 a101, 0
	v_accvgpr_write_b32 a100, 0
	v_accvgpr_write_b32 a99, 0
	v_accvgpr_write_b32 a98, 0
	v_accvgpr_write_b32 a97, 0
	v_accvgpr_write_b32 a96, 0
	v_accvgpr_write_b32 a127, 0
	v_accvgpr_write_b32 a126, 0
	v_accvgpr_write_b32 a125, 0
	v_accvgpr_write_b32 a124, 0
	v_accvgpr_write_b32 a123, 0
	v_accvgpr_write_b32 a122, 0
	v_accvgpr_write_b32 a121, 0
	v_accvgpr_write_b32 a120, 0
	v_accvgpr_write_b32 a119, 0
	v_accvgpr_write_b32 a118, 0
	v_accvgpr_write_b32 a117, 0
	v_accvgpr_write_b32 a116, 0
	v_accvgpr_write_b32 a115, 0
	v_accvgpr_write_b32 a114, 0
	v_accvgpr_write_b32 a113, 0
	v_accvgpr_write_b32 a112, 0
	v_accvgpr_mov_b32 a1, a193
	v_accvgpr_mov_b32 a2, a194
	v_accvgpr_mov_b32 a3, a195
	v_accvgpr_mov_b32 a4, a196
	v_accvgpr_mov_b32 a5, a197
	v_accvgpr_mov_b32 a6, a198
	v_accvgpr_mov_b32 a7, a199
	v_accvgpr_mov_b32 a8, a200
	v_accvgpr_mov_b32 a9, a201
	v_accvgpr_mov_b32 a10, a202
	v_accvgpr_mov_b32 a11, a203
	v_accvgpr_mov_b32 a12, a204
	v_accvgpr_mov_b32 a13, a205
	v_accvgpr_mov_b32 a14, a206
	v_accvgpr_mov_b32 a15, a207
	v_accvgpr_mov_b32 a17, a193
	v_accvgpr_mov_b32 a18, a194
	v_accvgpr_mov_b32 a19, a195
	v_accvgpr_mov_b32 a20, a196
	v_accvgpr_mov_b32 a21, a197
	v_accvgpr_mov_b32 a22, a198
	v_accvgpr_mov_b32 a23, a199
	v_accvgpr_mov_b32 a24, a200
	v_accvgpr_mov_b32 a25, a201
	v_accvgpr_mov_b32 a26, a202
	v_accvgpr_mov_b32 a27, a203
	v_accvgpr_mov_b32 a28, a204
	v_accvgpr_mov_b32 a29, a205
	v_accvgpr_mov_b32 a30, a206
	v_accvgpr_mov_b32 a31, a207
	s_waitcnt vmcnt(11)
	ds_write_b128 v84, v[0:3] offset:0
	s_waitcnt vmcnt(10)
	ds_write_b128 v84, v[28:31] offset:0x1000
	s_waitcnt vmcnt(9)
	ds_write_b128 v84, v[32:35] offset:0x2000
	s_mov_b64 s[6:7], 0x40000
	s_mov_b64 s[8:9], 0x20000
	v_lshl_add_u64 v[74:75], v[68:69], 0, s[6:7]
	s_mov_b64 s[6:7], 0x60000
	v_mov_b32_e32 v0, 0
	s_waitcnt vmcnt(8)
	ds_write_b128 v84, v[36:39] offset:0x3000
	s_waitcnt vmcnt(7)
	ds_write_b128 v84, v[40:43] offset:0x4000
	s_waitcnt vmcnt(6)
	ds_write_b128 v84, v[44:47] offset:0x5000
	s_waitcnt lgkmcnt(0)
	v_lshl_add_u64 v[72:73], v[68:69], 0, s[8:9]
	s_mov_b32 s4, 0
	v_lshl_add_u64 v[76:77], v[68:69], 0, s[6:7]
	v_lshl_add_u64 v[78:79], v[70:71], 0, s[8:9]
	s_mov_b32 s3, -2
	v_mov_b32_e32 v1, v0
	v_mov_b32_e32 v2, v0
	v_mov_b32_e32 v3, v0
	v_mov_b32_e32 v28, v0
	v_mov_b32_e32 v29, v0
	v_mov_b32_e32 v30, v0
	v_mov_b32_e32 v31, v0
	v_mov_b32_e32 v32, v0
	v_mov_b32_e32 v33, v0
	v_mov_b32_e32 v34, v0
	v_mov_b32_e32 v35, v0
	v_mov_b32_e32 v36, v0
	v_mov_b32_e32 v37, v0
	v_mov_b32_e32 v38, v0
	v_mov_b32_e32 v39, v0
	s_barrier

.LBB0_235:
	v_lshrrev_b32_e32 v0, 3, v108
	v_and_b32_e32 v9, 4, v0
	v_and_or_b32 v22, v107, 64, s1
	v_or_b32_e32 v0, s0, v106
	v_add_u32_e32 v6, v0, v109
	v_lshrrev_b32_e32 v0, 4, v22
	s_movk_i32 s3, 0x4200
	v_mul_lo_u32 v0, v0, s3
	v_ashrrev_i32_e32 v7, 31, v6
	v_ashrrev_i32_e32 v1, 31, v0
	v_lshl_add_u64 v[4:5], v[0:1], 0, v[6:7]
	v_readlane_b32 s6, v254, 3
	v_lshlrev_b64 v[4:5], 5, v[4:5]
	v_readlane_b32 s7, v254, 4
	v_lshlrev_b32_e32 v192, 1, v9
	v_or_b32_e32 v8, v9, v22
	v_lshl_add_u64 v[4:5], s[6:7], 0, v[4:5]
	v_lshl_add_u64 v[10:11], v[4:5], 0, v[192:193]
	global_load_dwordx2 v[10:11], v[10:11], off
	v_accvgpr_read_b32 v134, a32
	v_ashrrev_i32_e32 v9, 31, v8
	v_accvgpr_read_b32 v133, a33
	v_lshlrev_b64 v[14:15], 1, v[8:9]
	v_mul_f32_e32 v9, 0xbfb8aa3b, v134
	v_accvgpr_read_b32 v132, a34
	v_exp_f32_e32 v12, v9
	v_mul_f32_e32 v9, 0xbfb8aa3b, v133
	v_exp_f32_e32 v16, v9
	v_mul_f32_e32 v9, 0xbfb8aa3b, v132
	v_exp_f32_e32 v13, v9
	v_accvgpr_read_b32 v131, a35
	v_mul_f32_e32 v9, 0xbfb8aa3b, v131
	v_exp_f32_e32 v17, v9
	v_readlane_b32 s4, v253, 61
	v_lshlrev_b64 v[2:3], 11, v[6:7]
	v_readlane_b32 s5, v253, 62
	v_accvgpr_read_b32 v130, a36
	v_accvgpr_read_b32 v128, a38
	v_lshl_add_u64 v[2:3], s[4:5], 0, v[2:3]
	v_lshl_add_u64 v[2:3], v[2:3], 0, v[14:15]
	v_accvgpr_read_b32 v129, a37
	v_accvgpr_read_b32 v127, a39
	v_accvgpr_read_b32 v105, a40
	v_accvgpr_read_b32 v104, a41
	v_accvgpr_read_b32 v103, a42
	v_accvgpr_read_b32 v102, a43
	v_accvgpr_read_b32 v101, a44
	v_accvgpr_read_b32 v100, a45
	v_accvgpr_read_b32 v99, a46
	v_accvgpr_read_b32 v98, a47
	v_accvgpr_read_b32 v97, a48
	v_accvgpr_read_b32 v96, a49
	v_accvgpr_read_b32 v95, a50
	v_accvgpr_read_b32 v94, a51
	v_accvgpr_read_b32 v93, a52
	v_accvgpr_read_b32 v92, a53
	v_accvgpr_read_b32 v91, a54
	v_accvgpr_read_b32 v90, a55
	v_accvgpr_read_b32 v89, a56
	v_accvgpr_read_b32 v88, a57
	v_accvgpr_read_b32 v87, a58
	v_accvgpr_read_b32 v86, a59
	v_accvgpr_read_b32 v85, a60
	v_accvgpr_read_b32 v84, a61
	v_accvgpr_read_b32 v83, a62
	v_accvgpr_read_b32 v82, a63
	v_accvgpr_read_b32 v81, a0
	v_accvgpr_read_b32 v80, a1
	v_accvgpr_read_b32 v79, a2
	v_accvgpr_read_b32 v78, a3
	v_accvgpr_read_b32 v77, a4
	v_accvgpr_read_b32 v75, a6
	v_accvgpr_read_b32 v76, a5
	v_accvgpr_read_b32 v74, a7
	v_accvgpr_read_b32 v73, a8
	v_accvgpr_read_b32 v71, a10
	v_accvgpr_read_b32 v72, a9
	v_accvgpr_read_b32 v70, a11
	v_accvgpr_read_b32 v68, a13
	v_accvgpr_read_b32 v69, a12
	v_accvgpr_read_b32 v67, a14
	v_accvgpr_read_b32 v66, a15
	v_accvgpr_read_b32 v65, a16
	v_accvgpr_read_b32 v63, a18
	v_accvgpr_read_b32 v64, a17
	v_accvgpr_read_b32 v62, a19
	v_accvgpr_read_b32 v61, a20
	v_accvgpr_read_b32 v59, a22
	v_accvgpr_read_b32 v60, a21
	v_accvgpr_read_b32 v58, a23
	v_accvgpr_read_b32 v57, a24
	v_accvgpr_read_b32 v55, a26
	v_accvgpr_read_b32 v56, a25
	v_accvgpr_read_b32 v54, a27
	v_accvgpr_read_b32 v52, a29
	v_accvgpr_read_b32 v53, a28
	v_accvgpr_read_b32 v51, a30
	v_accvgpr_read_b32 v50, a31
	s_waitcnt vmcnt(0)
	v_lshlrev_b32_e32 v9, 16, v11
	v_lshlrev_b32_e32 v18, 16, v10
	v_and_b32_e32 v19, 0xffff0000, v11
	v_and_b32_e32 v20, 0xffff0000, v10
	v_pk_add_f32 v[10:11], v[12:13], 1.0 op_sel_hi:[1,0]
	s_nop 0
	v_rcp_f32_e32 v13, v10
	s_nop 0
	v_mul_f32_e32 v12, v18, v13
	v_rcp_f32_e32 v13, v11
	s_nop 0
	v_mul_f32_e32 v9, v9, v13
	v_pk_add_f32 v[10:11], v[16:17], 1.0 op_sel_hi:[1,0]
	s_nop 0
	v_rcp_f32_e32 v16, v10
	s_nop 0
	v_mul_f32_e32 v10, v20, v16
	v_rcp_f32_e32 v16, v11
	s_nop 0
	v_mul_f32_e32 v11, v19, v16
	v_cvt_pk_bf16_f32 v11, v9, v11
	v_cvt_pk_bf16_f32 v10, v12, v10
	v_bitop3_b32 v9, v8, 12, 8 bitop3:0xc8
	global_store_dwordx2 v[2:3], v[10:11], off
	v_lshlrev_b32_e32 v10, 1, v9
	v_mov_b32_e32 v11, v193
	v_lshl_add_u64 v[16:17], v[4:5], 0, v[10:11]
	global_load_dwordx2 v[16:17], v[16:17], off
	v_mul_f32_e32 v4, 0xbfb8aa3b, v130
	v_mul_f32_e32 v5, 0xbfb8aa3b, v128
	v_exp_f32_e32 v12, v4
	v_exp_f32_e32 v13, v5
	v_mul_f32_e32 v4, 0xbfb8aa3b, v129
	v_mul_f32_e32 v5, 0xbfb8aa3b, v127
	v_exp_f32_e32 v4, v4
	v_pk_add_f32 v[12:13], v[12:13], 1.0 op_sel_hi:[1,0]
	v_exp_f32_e32 v5, v5
	s_waitcnt vmcnt(0)
	v_lshlrev_b32_e32 v18, 16, v16
	v_rcp_f32_e32 v20, v12
	v_lshlrev_b32_e32 v9, 16, v17
	v_and_b32_e32 v16, 0xffff0000, v16
	v_pk_add_f32 v[4:5], v[4:5], 1.0 op_sel_hi:[1,0]
	v_mul_f32_e32 v12, v18, v20
	v_rcp_f32_e32 v19, v13
	v_and_b32_e32 v17, 0xffff0000, v17
	v_mul_f32_e32 v9, v9, v19
	v_rcp_f32_e32 v18, v4
	s_nop 0
	v_mul_f32_e32 v4, v16, v18
	v_rcp_f32_e32 v16, v5
	s_nop 0
	v_mul_f32_e32 v5, v17, v16
	v_cvt_pk_bf16_f32 v5, v9, v5
	v_cvt_pk_bf16_f32 v4, v12, v4
	global_store_dwordx2 v[2:3], v[4:5], off offset:16
	v_or_b32_e32 v4, 16, v22
	v_lshrrev_b32_e32 v4, 4, v4
	v_mul_lo_u32 v12, v4, s3
	v_ashrrev_i32_e32 v13, 31, v12
	v_lshl_add_u64 v[4:5], v[12:13], 0, v[6:7]
	v_lshlrev_b64 v[4:5], 5, v[4:5]
	v_lshl_add_u64 v[4:5], s[6:7], 0, v[4:5]
	v_lshl_add_u64 v[4:5], v[4:5], 0, v[192:193]
	global_load_dwordx2 v[20:21], v[4:5], off
	v_mul_f32_e32 v9, 0xbfb8aa3b, v105
	v_exp_f32_e32 v18, v9
	v_mul_f32_e32 v9, 0xbfb8aa3b, v104
	v_exp_f32_e32 v16, v9
	v_mul_f32_e32 v9, 0xbfb8aa3b, v103
	v_exp_f32_e32 v19, v9
	v_mul_f32_e32 v9, 0xbfb8aa3b, v102
	v_exp_f32_e32 v17, v9
	v_pk_add_f32 v[18:19], v[18:19], 1.0 op_sel_hi:[1,0]
	v_pk_add_f32 v[16:17], v[16:17], 1.0 op_sel_hi:[1,0]
	s_waitcnt vmcnt(0)
	v_lshlrev_b32_e32 v23, 16, v20
	v_rcp_f32_e32 v25, v18
	v_lshlrev_b32_e32 v9, 16, v21
	v_and_b32_e32 v20, 0xffff0000, v20
	v_and_b32_e32 v21, 0xffff0000, v21
	v_mul_f32_e32 v18, v23, v25
	v_rcp_f32_e32 v24, v19
	s_nop 0
	v_mul_f32_e32 v9, v9, v24
	v_rcp_f32_e32 v23, v16
	s_nop 0
	v_mul_f32_e32 v16, v20, v23
	v_rcp_f32_e32 v20, v17
	s_nop 0
	v_mul_f32_e32 v17, v21, v20
	v_cvt_pk_bf16_f32 v17, v9, v17
	v_cvt_pk_bf16_f32 v16, v18, v16
	global_store_dwordx2 v[2:3], v[16:17], off offset:32
	global_load_dwordx2 v[4:5], v[4:5], off offset:16
	v_mul_f32_e32 v9, 0xbfb8aa3b, v101
	v_exp_f32_e32 v16, v9
	v_mul_f32_e32 v9, 0xbfb8aa3b, v100
	v_exp_f32_e32 v18, v9
	v_mul_f32_e32 v9, 0xbfb8aa3b, v99
	v_exp_f32_e32 v17, v9
	v_mul_f32_e32 v9, 0xbfb8aa3b, v98
	v_exp_f32_e32 v19, v9
	s_waitcnt vmcnt(0)
	v_lshlrev_b32_e32 v9, 16, v5
	v_lshlrev_b32_e32 v20, 16, v4
	v_and_b32_e32 v21, 0xffff0000, v5
	v_and_b32_e32 v23, 0xffff0000, v4
	v_pk_add_f32 v[4:5], v[16:17], 1.0 op_sel_hi:[1,0]
	s_nop 0
	v_rcp_f32_e32 v17, v4
	s_nop 0
	v_mul_f32_e32 v16, v20, v17
	v_rcp_f32_e32 v17, v5
	s_nop 0
	v_mul_f32_e32 v9, v9, v17
	v_pk_add_f32 v[4:5], v[18:19], 1.0 op_sel_hi:[1,0]
	s_nop 0
	v_rcp_f32_e32 v18, v4
	s_nop 0
	v_mul_f32_e32 v4, v23, v18
	v_rcp_f32_e32 v18, v5
	s_nop 0
	v_mul_f32_e32 v5, v21, v18
	v_cvt_pk_bf16_f32 v5, v9, v5
	v_cvt_pk_bf16_f32 v4, v16, v4
	global_store_dwordx2 v[2:3], v[4:5], off offset:48
	v_or_b32_e32 v4, 32, v6
	v_ashrrev_i32_e32 v5, 31, v4
	v_lshl_add_u64 v[0:1], v[0:1], 0, v[4:5]
	v_lshlrev_b64 v[0:1], 5, v[0:1]
	v_lshl_add_u64 v[16:17], s[6:7], 0, v[0:1]
	v_lshl_add_u64 v[20:21], v[16:17], 0, v[192:193]
	global_load_dwordx2 v[20:21], v[20:21], off
	v_lshlrev_b64 v[18:19], 11, v[4:5]
	v_mul_f32_e32 v9, 0xbfb8aa3b, v97
	v_lshl_add_u64 v[0:1], s[4:5], 0, v[18:19]
	v_exp_f32_e32 v18, v9
	v_mul_f32_e32 v9, 0xbfb8aa3b, v96
	v_lshl_add_u64 v[0:1], v[0:1], 0, v[14:15]
	v_exp_f32_e32 v14, v9
	v_mul_f32_e32 v9, 0xbfb8aa3b, v95
	v_exp_f32_e32 v19, v9
	v_mul_f32_e32 v9, 0xbfb8aa3b, v94
	v_exp_f32_e32 v15, v9
	v_lshl_add_u64 v[16:17], v[16:17], 0, v[10:11]
	v_pk_add_f32 v[18:19], v[18:19], 1.0 op_sel_hi:[1,0]
	v_pk_add_f32 v[14:15], v[14:15], 1.0 op_sel_hi:[1,0]
	s_waitcnt vmcnt(0)
	v_lshlrev_b32_e32 v23, 16, v20
	v_rcp_f32_e32 v25, v18
	v_lshlrev_b32_e32 v9, 16, v21
	v_and_b32_e32 v20, 0xffff0000, v20
	v_and_b32_e32 v21, 0xffff0000, v21
	v_mul_f32_e32 v18, v23, v25
	v_rcp_f32_e32 v24, v19
	s_nop 0
	v_mul_f32_e32 v9, v9, v24
	v_rcp_f32_e32 v23, v14
	s_nop 0
	v_mul_f32_e32 v14, v20, v23
	v_rcp_f32_e32 v20, v15
	s_nop 0
	v_mul_f32_e32 v15, v21, v20
	v_cvt_pk_bf16_f32 v15, v9, v15
	v_cvt_pk_bf16_f32 v14, v18, v14
	global_store_dwordx2 v[0:1], v[14:15], off
	global_load_dwordx2 v[16:17], v[16:17], off
	v_mul_f32_e32 v9, 0xbfb8aa3b, v93
	v_exp_f32_e32 v14, v9
	v_mul_f32_e32 v9, 0xbfb8aa3b, v92
	v_exp_f32_e32 v10, v9
	v_mul_f32_e32 v9, 0xbfb8aa3b, v91
	v_exp_f32_e32 v15, v9
	v_mul_f32_e32 v9, 0xbfb8aa3b, v90
	v_exp_f32_e32 v11, v9
	v_pk_add_f32 v[14:15], v[14:15], 1.0 op_sel_hi:[1,0]
	v_pk_add_f32 v[10:11], v[10:11], 1.0 op_sel_hi:[1,0]
	s_waitcnt vmcnt(0)
	v_lshlrev_b32_e32 v18, 16, v16
	v_rcp_f32_e32 v20, v14
	v_lshlrev_b32_e32 v9, 16, v17
	v_and_b32_e32 v16, 0xffff0000, v16
	v_and_b32_e32 v17, 0xffff0000, v17
	v_mul_f32_e32 v14, v18, v20
	v_rcp_f32_e32 v19, v15
	s_nop 0
	v_mul_f32_e32 v9, v9, v19
	v_rcp_f32_e32 v18, v10
	s_nop 0
	v_mul_f32_e32 v10, v16, v18
	v_rcp_f32_e32 v16, v11
	s_nop 0
	v_mul_f32_e32 v11, v17, v16
	v_cvt_pk_bf16_f32 v11, v9, v11
	v_cvt_pk_bf16_f32 v10, v14, v10
	global_store_dwordx2 v[0:1], v[10:11], off offset:16
	v_lshl_add_u64 v[10:11], v[12:13], 0, v[4:5]
	v_lshlrev_b64 v[10:11], 5, v[10:11]
	v_lshl_add_u64 v[10:11], s[6:7], 0, v[10:11]
	v_lshl_add_u64 v[10:11], v[10:11], 0, v[192:193]
	global_load_dwordx2 v[16:17], v[10:11], off
	v_mul_f32_e32 v9, 0xbfb8aa3b, v89
	v_exp_f32_e32 v14, v9
	v_mul_f32_e32 v9, 0xbfb8aa3b, v88
	v_exp_f32_e32 v12, v9
	v_mul_f32_e32 v9, 0xbfb8aa3b, v87
	v_exp_f32_e32 v15, v9
	v_mul_f32_e32 v9, 0xbfb8aa3b, v86
	v_exp_f32_e32 v13, v9
	v_pk_add_f32 v[14:15], v[14:15], 1.0 op_sel_hi:[1,0]
	v_pk_add_f32 v[12:13], v[12:13], 1.0 op_sel_hi:[1,0]
	s_waitcnt vmcnt(0)
	v_lshlrev_b32_e32 v18, 16, v16
	v_rcp_f32_e32 v20, v14
	v_lshlrev_b32_e32 v9, 16, v17
	v_and_b32_e32 v16, 0xffff0000, v16
	v_and_b32_e32 v17, 0xffff0000, v17
	v_mul_f32_e32 v14, v18, v20
	v_rcp_f32_e32 v19, v15
	s_nop 0
	v_mul_f32_e32 v9, v9, v19
	v_rcp_f32_e32 v18, v12
	s_nop 0
	v_mul_f32_e32 v12, v16, v18
	v_rcp_f32_e32 v16, v13
	s_nop 0
	v_mul_f32_e32 v13, v17, v16
	v_cvt_pk_bf16_f32 v13, v9, v13
	v_cvt_pk_bf16_f32 v12, v14, v12
	global_store_dwordx2 v[0:1], v[12:13], off offset:32
	global_load_dwordx2 v[10:11], v[10:11], off offset:16
	v_mul_f32_e32 v9, 0xbfb8aa3b, v85
	v_exp_f32_e32 v12, v9
	v_mul_f32_e32 v9, 0xbfb8aa3b, v84
	v_exp_f32_e32 v14, v9
	v_mul_f32_e32 v9, 0xbfb8aa3b, v83
	v_exp_f32_e32 v13, v9
	v_mul_f32_e32 v9, 0xbfb8aa3b, v82
	v_exp_f32_e32 v15, v9
	s_waitcnt vmcnt(0)
	v_lshlrev_b32_e32 v9, 16, v11
	v_lshlrev_b32_e32 v16, 16, v10
	v_and_b32_e32 v17, 0xffff0000, v11
	v_and_b32_e32 v18, 0xffff0000, v10
	v_pk_add_f32 v[10:11], v[12:13], 1.0 op_sel_hi:[1,0]
	s_nop 0
	v_rcp_f32_e32 v13, v10
	s_nop 0
	v_mul_f32_e32 v12, v16, v13
	v_rcp_f32_e32 v13, v11
	s_nop 0
	v_mul_f32_e32 v9, v9, v13
	v_pk_add_f32 v[10:11], v[14:15], 1.0 op_sel_hi:[1,0]
	s_nop 0
	v_rcp_f32_e32 v14, v10
	s_nop 0
	v_mul_f32_e32 v10, v18, v14
	v_rcp_f32_e32 v14, v11
	s_nop 0
	v_mul_f32_e32 v11, v17, v14
	v_cvt_pk_bf16_f32 v11, v9, v11
	v_cvt_pk_bf16_f32 v10, v12, v10
	v_or_b32_e32 v9, 32, v22
	v_lshrrev_b32_e32 v9, 4, v9
	v_mul_lo_u32 v12, v9, s3
	v_ashrrev_i32_e32 v13, 31, v12
	global_store_dwordx2 v[0:1], v[10:11], off offset:48
	v_lshl_add_u64 v[10:11], v[12:13], 0, v[6:7]
	v_lshlrev_b64 v[10:11], 5, v[10:11]
	v_lshl_add_u64 v[10:11], s[6:7], 0, v[10:11]
	v_lshl_add_u64 v[16:17], v[10:11], 0, v[192:193]
	global_load_dwordx2 v[16:17], v[16:17], off
	v_mul_f32_e32 v9, 0xbfb8aa3b, v81
	v_exp_f32_e32 v14, v9
	v_mul_f32_e32 v9, 0xbfb8aa3b, v80
	v_exp_f32_e32 v10, v9
	v_mul_f32_e32 v9, 0xbfb8aa3b, v79
	v_exp_f32_e32 v15, v9
	v_mul_f32_e32 v9, 0xbfb8aa3b, v78
	v_exp_f32_e32 v11, v9
	v_pk_add_f32 v[14:15], v[14:15], 1.0 op_sel_hi:[1,0]
	v_pk_add_f32 v[10:11], v[10:11], 1.0 op_sel_hi:[1,0]
	s_waitcnt vmcnt(0)
	v_lshlrev_b32_e32 v18, 16, v16
	v_rcp_f32_e32 v20, v14
	v_lshlrev_b32_e32 v9, 16, v17
	v_and_b32_e32 v16, 0xffff0000, v16
	v_and_b32_e32 v17, 0xffff0000, v17
	v_mul_f32_e32 v14, v18, v20
	v_rcp_f32_e32 v19, v15
	s_nop 0
	v_mul_f32_e32 v9, v9, v19
	v_rcp_f32_e32 v18, v10
	s_nop 0
	v_mul_f32_e32 v10, v16, v18
	v_rcp_f32_e32 v16, v11
	s_nop 0
	v_mul_f32_e32 v11, v17, v16
	v_cvt_pk_bf16_f32 v11, v9, v11
	v_cvt_pk_bf16_f32 v10, v14, v10
	v_or_b32_e32 v9, 40, v8
	v_lshrrev_b32_e32 v9, 4, v9
	global_store_dwordx2 v[2:3], v[10:11], off offset:64
	v_mul_lo_u32 v10, v9, s3
	v_ashrrev_i32_e32 v11, 31, v10
	v_lshl_add_u64 v[14:15], v[10:11], 0, v[6:7]
	v_lshlrev_b64 v[14:15], 5, v[14:15]
	v_bitop3_b32 v8, v8, 12, 40 bitop3:0xc8
	v_lshl_add_u64 v[14:15], s[6:7], 0, v[14:15]
	v_lshlrev_b32_e32 v8, 1, v8
	v_mov_b32_e32 v9, v193
	v_lshl_add_u64 v[18:19], v[14:15], 0, v[8:9]
	global_load_dwordx2 v[18:19], v[18:19], off
	v_mul_f32_e32 v14, 0xbfb8aa3b, v77
	v_mul_f32_e32 v15, 0xbfb8aa3b, v75
	v_exp_f32_e32 v16, v14
	v_exp_f32_e32 v17, v15
	v_mul_f32_e32 v14, 0xbfb8aa3b, v76
	v_mul_f32_e32 v15, 0xbfb8aa3b, v74
	v_exp_f32_e32 v14, v14
	v_pk_add_f32 v[16:17], v[16:17], 1.0 op_sel_hi:[1,0]
	v_exp_f32_e32 v15, v15
	s_waitcnt vmcnt(0)
	v_lshlrev_b32_e32 v21, 16, v18
	v_rcp_f32_e32 v24, v16
	v_lshlrev_b32_e32 v20, 16, v19
	v_and_b32_e32 v18, 0xffff0000, v18
	v_pk_add_f32 v[14:15], v[14:15], 1.0 op_sel_hi:[1,0]
	v_mul_f32_e32 v16, v21, v24
	v_rcp_f32_e32 v23, v17
	v_and_b32_e32 v19, 0xffff0000, v19
	v_mul_f32_e32 v17, v20, v23
	v_rcp_f32_e32 v21, v14
	s_nop 0
	v_mul_f32_e32 v14, v18, v21
	v_rcp_f32_e32 v20, v15
	s_nop 0
	v_mul_f32_e32 v15, v19, v20
	v_cvt_pk_bf16_f32 v15, v17, v15
	v_cvt_pk_bf16_f32 v14, v16, v14
	global_store_dwordx2 v[2:3], v[14:15], off offset:80
	v_or_b32_e32 v14, 48, v22
	v_lshrrev_b32_e32 v14, 4, v14
	v_mul_lo_u32 v14, v14, s3
	v_ashrrev_i32_e32 v15, 31, v14
	v_lshl_add_u64 v[6:7], v[14:15], 0, v[6:7]
	v_lshlrev_b64 v[6:7], 5, v[6:7]
	v_lshl_add_u64 v[6:7], s[6:7], 0, v[6:7]
	v_lshl_add_u64 v[6:7], v[6:7], 0, v[192:193]
	global_load_dwordx2 v[20:21], v[6:7], off
	v_mul_f32_e32 v16, 0xbfb8aa3b, v73
	v_mul_f32_e32 v17, 0xbfb8aa3b, v71
	v_exp_f32_e32 v18, v16
	v_exp_f32_e32 v19, v17
	v_mul_f32_e32 v16, 0xbfb8aa3b, v72
	v_mul_f32_e32 v17, 0xbfb8aa3b, v70
	v_exp_f32_e32 v16, v16
	v_pk_add_f32 v[18:19], v[18:19], 1.0 op_sel_hi:[1,0]
	v_exp_f32_e32 v17, v17
	s_waitcnt vmcnt(0)
	v_lshlrev_b32_e32 v23, 16, v20
	v_rcp_f32_e32 v25, v18
	v_lshlrev_b32_e32 v22, 16, v21
	v_and_b32_e32 v20, 0xffff0000, v20
	v_pk_add_f32 v[16:17], v[16:17], 1.0 op_sel_hi:[1,0]
	v_mul_f32_e32 v18, v23, v25
	v_rcp_f32_e32 v24, v19
	v_and_b32_e32 v21, 0xffff0000, v21
	v_mul_f32_e32 v19, v22, v24
	v_rcp_f32_e32 v23, v16
	s_nop 0
	v_mul_f32_e32 v16, v20, v23
	v_rcp_f32_e32 v22, v17
	s_nop 0
	v_mul_f32_e32 v17, v21, v22
	v_cvt_pk_bf16_f32 v17, v19, v17
	v_cvt_pk_bf16_f32 v16, v18, v16
	global_store_dwordx2 v[2:3], v[16:17], off offset:96
	global_load_dwordx2 v[6:7], v[6:7], off offset:16
	v_mul_f32_e32 v17, 0xbfb8aa3b, v68
	v_mul_f32_e32 v16, 0xbfb8aa3b, v69
	v_exp_f32_e32 v18, v17
	v_mul_f32_e32 v17, 0xbfb8aa3b, v67
	v_exp_f32_e32 v16, v16
	v_exp_f32_e32 v17, v17
	v_mul_f32_e32 v19, 0xbfb8aa3b, v66
	v_exp_f32_e32 v19, v19
	s_waitcnt vmcnt(0)
	v_lshlrev_b32_e32 v20, 16, v7
	v_lshlrev_b32_e32 v21, 16, v6
	v_and_b32_e32 v22, 0xffff0000, v7
	v_and_b32_e32 v23, 0xffff0000, v6
	v_pk_add_f32 v[6:7], v[16:17], 1.0 op_sel_hi:[1,0]
	s_nop 0
	v_rcp_f32_e32 v17, v6
	s_nop 0
	v_mul_f32_e32 v16, v21, v17
	v_rcp_f32_e32 v17, v7
	s_nop 0
	v_mul_f32_e32 v17, v20, v17
	v_pk_add_f32 v[6:7], v[18:19], 1.0 op_sel_hi:[1,0]
	s_nop 0
	v_rcp_f32_e32 v19, v6
	s_nop 0
	v_mul_f32_e32 v6, v23, v19
	v_rcp_f32_e32 v19, v7
	s_nop 0
	v_mul_f32_e32 v7, v22, v19
	v_cvt_pk_bf16_f32 v7, v17, v7
	v_cvt_pk_bf16_f32 v6, v16, v6
	global_store_dwordx2 v[2:3], v[6:7], off offset:112
	v_lshl_add_u64 v[2:3], v[12:13], 0, v[4:5]
	v_lshlrev_b64 v[2:3], 5, v[2:3]
	v_lshl_add_u64 v[2:3], s[6:7], 0, v[2:3]
	v_lshl_add_u64 v[12:13], v[2:3], 0, v[192:193]
	global_load_dwordx2 v[12:13], v[12:13], off
	v_mul_f32_e32 v2, 0xbfb8aa3b, v65
	v_mul_f32_e32 v3, 0xbfb8aa3b, v63
	v_exp_f32_e32 v6, v2
	v_exp_f32_e32 v7, v3
	v_mul_f32_e32 v2, 0xbfb8aa3b, v64
	v_mul_f32_e32 v3, 0xbfb8aa3b, v62
	v_exp_f32_e32 v2, v2
	v_pk_add_f32 v[6:7], v[6:7], 1.0 op_sel_hi:[1,0]
	v_exp_f32_e32 v3, v3
	s_waitcnt vmcnt(0)
	v_lshlrev_b32_e32 v17, 16, v12
	v_rcp_f32_e32 v19, v6
	v_lshlrev_b32_e32 v16, 16, v13
	v_and_b32_e32 v12, 0xffff0000, v12
	v_pk_add_f32 v[2:3], v[2:3], 1.0 op_sel_hi:[1,0]
	v_mul_f32_e32 v6, v17, v19
	v_rcp_f32_e32 v18, v7
	v_and_b32_e32 v13, 0xffff0000, v13
	v_mul_f32_e32 v7, v16, v18
	v_rcp_f32_e32 v17, v2
	s_nop 0
	v_mul_f32_e32 v2, v12, v17
	v_rcp_f32_e32 v16, v3
	s_nop 0
	v_mul_f32_e32 v3, v13, v16
	v_cvt_pk_bf16_f32 v3, v7, v3
	v_cvt_pk_bf16_f32 v2, v6, v2
	global_store_dwordx2 v[0:1], v[2:3], off offset:64
	v_lshl_add_u64 v[2:3], v[10:11], 0, v[4:5]
	v_lshlrev_b64 v[2:3], 5, v[2:3]
	v_lshl_add_u64 v[2:3], s[6:7], 0, v[2:3]
	v_lshl_add_u64 v[8:9], v[2:3], 0, v[8:9]
	global_load_dwordx2 v[8:9], v[8:9], off
	v_mul_f32_e32 v2, 0xbfb8aa3b, v61
	v_mul_f32_e32 v3, 0xbfb8aa3b, v59
	v_exp_f32_e32 v6, v2
	v_exp_f32_e32 v7, v3
	v_mul_f32_e32 v2, 0xbfb8aa3b, v60
	v_mul_f32_e32 v3, 0xbfb8aa3b, v58
	v_exp_f32_e32 v2, v2
	v_pk_add_f32 v[6:7], v[6:7], 1.0 op_sel_hi:[1,0]
	v_exp_f32_e32 v3, v3
	s_waitcnt vmcnt(0)
	v_lshlrev_b32_e32 v11, 16, v8
	v_rcp_f32_e32 v13, v6
	v_lshlrev_b32_e32 v10, 16, v9
	v_and_b32_e32 v8, 0xffff0000, v8
	v_pk_add_f32 v[2:3], v[2:3], 1.0 op_sel_hi:[1,0]
	v_mul_f32_e32 v6, v11, v13
	v_rcp_f32_e32 v12, v7
	v_and_b32_e32 v9, 0xffff0000, v9
	v_mul_f32_e32 v7, v10, v12
	v_rcp_f32_e32 v11, v2
	s_nop 0
	v_mul_f32_e32 v2, v8, v11
	v_rcp_f32_e32 v10, v3
	s_nop 0
	v_mul_f32_e32 v3, v9, v10
	v_cvt_pk_bf16_f32 v3, v7, v3
	v_cvt_pk_bf16_f32 v2, v6, v2
	global_store_dwordx2 v[0:1], v[2:3], off offset:80
	v_lshl_add_u64 v[2:3], v[14:15], 0, v[4:5]
	v_lshlrev_b64 v[2:3], 5, v[2:3]
	v_lshl_add_u64 v[2:3], s[6:7], 0, v[2:3]
	v_lshl_add_u64 v[2:3], v[2:3], 0, v[192:193]
	global_load_dwordx2 v[8:9], v[2:3], off
	v_mul_f32_e32 v4, 0xbfb8aa3b, v57
	v_mul_f32_e32 v5, 0xbfb8aa3b, v55
	v_exp_f32_e32 v6, v4
	v_exp_f32_e32 v7, v5
	v_mul_f32_e32 v4, 0xbfb8aa3b, v56
	v_mul_f32_e32 v5, 0xbfb8aa3b, v54
	v_exp_f32_e32 v4, v4
	v_pk_add_f32 v[6:7], v[6:7], 1.0 op_sel_hi:[1,0]
	v_exp_f32_e32 v5, v5
	s_waitcnt vmcnt(0)
	v_lshlrev_b32_e32 v11, 16, v8
	v_rcp_f32_e32 v13, v6
	v_lshlrev_b32_e32 v10, 16, v9
	v_and_b32_e32 v8, 0xffff0000, v8
	v_pk_add_f32 v[4:5], v[4:5], 1.0 op_sel_hi:[1,0]
	v_mul_f32_e32 v6, v11, v13
	v_rcp_f32_e32 v12, v7
	v_and_b32_e32 v9, 0xffff0000, v9
	v_mul_f32_e32 v7, v10, v12
	v_rcp_f32_e32 v11, v4
	s_nop 0
	v_mul_f32_e32 v4, v8, v11
	v_rcp_f32_e32 v10, v5
	s_nop 0
	v_mul_f32_e32 v5, v9, v10
	v_cvt_pk_bf16_f32 v5, v7, v5
	v_cvt_pk_bf16_f32 v4, v6, v4
	global_store_dwordx2 v[0:1], v[4:5], off offset:96
	global_load_dwordx2 v[2:3], v[2:3], off offset:16
	v_mul_f32_e32 v5, 0xbfb8aa3b, v52
	v_mul_f32_e32 v4, 0xbfb8aa3b, v53
	v_exp_f32_e32 v6, v5
	v_mul_f32_e32 v5, 0xbfb8aa3b, v51
	v_exp_f32_e32 v4, v4
	v_exp_f32_e32 v5, v5
	v_mul_f32_e32 v7, 0xbfb8aa3b, v50
	v_exp_f32_e32 v7, v7
	s_waitcnt vmcnt(0)
	v_lshlrev_b32_e32 v8, 16, v3
	v_lshlrev_b32_e32 v9, 16, v2
	v_and_b32_e32 v10, 0xffff0000, v3
	v_and_b32_e32 v11, 0xffff0000, v2
	v_pk_add_f32 v[2:3], v[4:5], 1.0 op_sel_hi:[1,0]
	s_nop 0
	v_rcp_f32_e32 v5, v2
	s_nop 0
	v_mul_f32_e32 v4, v9, v5
	v_rcp_f32_e32 v5, v3
	s_nop 0
	v_mul_f32_e32 v5, v8, v5
	v_pk_add_f32 v[2:3], v[6:7], 1.0 op_sel_hi:[1,0]
	s_nop 0
	v_rcp_f32_e32 v7, v2
	s_nop 0
	v_mul_f32_e32 v2, v11, v7
	v_rcp_f32_e32 v7, v3
	s_nop 0
	v_mul_f32_e32 v3, v10, v7
	v_cvt_pk_bf16_f32 v3, v5, v3
	v_cvt_pk_bf16_f32 v2, v4, v2
	global_store_dwordx2 v[0:1], v[2:3], off offset:112

.LBB0_254:
	s_add_i32 s2, s1, 0x80
	s_min_u32 s3, s2, 0x2c0
	s_lshl_b32 s78, s3, 1
	v_lshl_add_u64 v[0:1], v[32:33], 0, s[78:79]
	v_lshl_add_u64 v[4:5], v[34:35], 0, s[78:79]
	v_lshl_add_u64 v[8:9], v[36:37], 0, s[78:79]
	v_lshl_add_u64 v[12:13], v[38:39], 0, s[78:79]
	v_lshl_add_u64 v[16:17], v[40:41], 0, s[78:79]
	v_lshl_add_u64 v[20:21], v[42:43], 0, s[78:79]
	v_lshl_add_u64 v[24:25], v[44:45], 0, s[78:79]
	v_lshl_add_u64 v[28:29], v[46:47], 0, s[78:79]
	global_load_dwordx4 v[0:3], v[0:1], off
	s_nop 0
	global_load_dwordx4 v[4:7], v[4:5], off
	s_nop 0
	global_load_dwordx4 v[8:11], v[8:9], off
	s_nop 0
	global_load_dwordx4 v[12:15], v[12:13], off
	s_nop 0
	global_load_dwordx4 v[16:19], v[16:17], off
	s_nop 0
	global_load_dwordx4 v[20:23], v[20:21], off
	s_nop 0
	global_load_dwordx4 v[24:27], v[24:25], off
	s_nop 0
	global_load_dwordx4 v[28:31], v[28:29], off
	ds_read_b128 v[68:71], v48 offset:0
	ds_read_b128 v[72:75], v48 offset:0x1000
	ds_read_b128 v[76:79], v52 offset:0
	ds_read_b128 v[80:83], v52 offset:0x1000
	s_min_u32 s1, s1, 0x200
	ds_read_b128 v[84:87], v49 offset:0
	ds_read_b128 v[88:91], v49 offset:0x1000
	ds_read_b128 v[92:95], v53 offset:0
	ds_read_b128 v[96:99], v53 offset:0x1000
	ds_read_b128 v[100:103], v50 offset:0
	ds_read_b128 v[104:107], v50 offset:0x1000
	ds_read_b128 v[108:111], v54 offset:0
	ds_read_b128 v[112:115], v54 offset:0x1000
	ds_read_b128 v[116:119], v51 offset:0
	ds_read_b128 v[120:123], v51 offset:0x1000
	ds_read_b128 v[124:127], v55 offset:0
	ds_read_b128 v[128:131], v55 offset:0x1000
	s_waitcnt lgkmcnt(12)
	s_lshl_b32 s78, s1, 1
	v_mfma_f32_32x32x16_bf16 a[32:47], v[68:71], v[76:79], a[32:47]
	v_add_u32_e32 v67, v56, v57
	s_waitcnt lgkmcnt(8)
	s_waitcnt lgkmcnt(4)
	v_add_u32_e32 v170, v58, v59
	v_add_u32_e32 v171, v60, v61
	v_add_u32_e32 v172, v62, v63
	s_waitcnt lgkmcnt(0)
	v_mfma_f32_32x32x16_bf16 a[48:63], v[68:71], v[80:83], a[48:63]
	v_lshl_add_u64 v[68:69], v[32:33], 0, s[78:79]
	v_lshl_add_u64 v[70:71], v[34:35], 0, s[78:79]
	s_waitcnt vmcnt(15)
	ds_write_b128 v67, v[138:141] offset:32768
	s_waitcnt vmcnt(14)
	ds_write_b128 v67, v[142:145] offset:49152
	s_waitcnt vmcnt(13)
	ds_write_b128 v170, v[146:149] offset:32768
	s_waitcnt vmcnt(12)
	ds_write_b128 v170, v[150:153] offset:49152
	s_waitcnt vmcnt(11)
	ds_write_b128 v171, v[154:157] offset:32768
	s_waitcnt vmcnt(10)
	ds_write_b128 v171, v[158:161] offset:49152
	s_waitcnt vmcnt(9)
	ds_write_b128 v172, v[162:165] offset:32768
	s_waitcnt vmcnt(8)
	ds_write_b128 v172, v[166:169] offset:49152
	s_waitcnt lgkmcnt(0)
	s_barrier
	v_mfma_f32_32x32x16_bf16 a[0:15], v[72:75], v[76:79], a[0:15]
	v_lshl_add_u64 v[76:77], v[40:41], 0, s[78:79]
	v_lshl_add_u64 v[78:79], v[42:43], 0, s[78:79]
	s_add_i32 s0, s0, 2
	s_mov_b32 s1, s2
	s_cmp_gt_u32 s0, 9
	v_mfma_f32_32x32x16_bf16 a[16:31], v[72:75], v[80:83], a[16:31]
	v_lshl_add_u64 v[72:73], v[36:37], 0, s[78:79]
	v_lshl_add_u64 v[74:75], v[38:39], 0, s[78:79]
	v_lshl_add_u64 v[80:81], v[44:45], 0, s[78:79]
	v_lshl_add_u64 v[82:83], v[46:47], 0, s[78:79]
	global_load_dwordx4 v[138:141], v[68:69], off offset:384
	global_load_dwordx4 v[142:145], v[70:71], off offset:384
	global_load_dwordx4 v[146:149], v[72:73], off offset:384
	global_load_dwordx4 v[150:153], v[74:75], off offset:384
	global_load_dwordx4 v[154:157], v[76:77], off offset:384
	global_load_dwordx4 v[158:161], v[78:79], off offset:384
	global_load_dwordx4 v[162:165], v[80:81], off offset:384
	global_load_dwordx4 v[166:169], v[82:83], off offset:384
	ds_read_b128 v[68:71], v48 offset:0x8000
	v_mfma_f32_32x32x16_bf16 a[32:47], v[84:87], v[92:95], a[32:47]
	ds_read_b128 v[72:75], v48 offset:0x9000
	ds_read_b128 v[76:79], v52 offset:0x8000
	ds_read_b128 v[80:83], v52 offset:0x9000
	v_mfma_f32_32x32x16_bf16 a[48:63], v[84:87], v[96:99], a[48:63]
	ds_read_b128 v[84:87], v49 offset:0x8000
	v_mfma_f32_32x32x16_bf16 a[0:15], v[88:91], v[92:95], a[0:15]
	v_mfma_f32_32x32x16_bf16 a[16:31], v[88:91], v[96:99], a[16:31]
	ds_read_b128 v[88:91], v49 offset:0x9000
	ds_read_b128 v[92:95], v53 offset:0x8000
	ds_read_b128 v[96:99], v53 offset:0x9000
	v_mfma_f32_32x32x16_bf16 a[32:47], v[100:103], v[108:111], a[32:47]
	v_mfma_f32_32x32x16_bf16 a[48:63], v[100:103], v[112:115], a[48:63]
	ds_read_b128 v[100:103], v50 offset:0x8000
	v_mfma_f32_32x32x16_bf16 a[0:15], v[104:107], v[108:111], a[0:15]
	v_mfma_f32_32x32x16_bf16 a[16:31], v[104:107], v[112:115], a[16:31]
	ds_read_b128 v[104:107], v50 offset:0x9000
	ds_read_b128 v[108:111], v54 offset:0x8000
	ds_read_b128 v[112:115], v54 offset:0x9000
	v_mfma_f32_32x32x16_bf16 a[32:47], v[116:119], v[124:127], a[32:47]
	v_mfma_f32_32x32x16_bf16 a[48:63], v[116:119], v[128:131], a[48:63]
	ds_read_b128 v[116:119], v51 offset:0x8000
	v_mfma_f32_32x32x16_bf16 a[0:15], v[120:123], v[124:127], a[0:15]
	v_mfma_f32_32x32x16_bf16 a[16:31], v[120:123], v[128:131], a[16:31]
	ds_read_b128 v[120:123], v51 offset:0x9000
	ds_read_b128 v[124:127], v55 offset:0x8000
	ds_read_b128 v[128:131], v55 offset:0x9000
	s_waitcnt lgkmcnt(12)
	s_waitcnt lgkmcnt(8)
	s_waitcnt lgkmcnt(4)
	s_nop 0
	v_mfma_f32_32x32x16_bf16 a[32:47], v[68:71], v[76:79], a[32:47]
	s_waitcnt lgkmcnt(0)
	s_waitcnt vmcnt(15)
	ds_write_b128 v67, v[0:3]
	s_waitcnt vmcnt(14)
	ds_write_b128 v67, v[4:7] offset:16384
	s_waitcnt vmcnt(13)
	ds_write_b128 v170, v[8:11]
	s_waitcnt vmcnt(12)
	ds_write_b128 v170, v[12:15] offset:16384
	s_waitcnt vmcnt(11)
	ds_write_b128 v171, v[16:19]
	s_waitcnt vmcnt(10)
	ds_write_b128 v171, v[20:23] offset:16384
	s_waitcnt vmcnt(9)
	ds_write_b128 v172, v[24:27]
	s_waitcnt vmcnt(8)
	ds_write_b128 v172, v[28:31] offset:16384
	s_waitcnt lgkmcnt(0)
	s_barrier
	v_mfma_f32_32x32x16_bf16 a[48:63], v[68:71], v[80:83], a[48:63]
	v_mfma_f32_32x32x16_bf16 a[0:15], v[72:75], v[76:79], a[0:15]
	v_mfma_f32_32x32x16_bf16 a[16:31], v[72:75], v[80:83], a[16:31]
	v_mfma_f32_32x32x16_bf16 a[32:47], v[84:87], v[92:95], a[32:47]
	v_mfma_f32_32x32x16_bf16 a[48:63], v[84:87], v[96:99], a[48:63]
	v_mfma_f32_32x32x16_bf16 a[0:15], v[88:91], v[92:95], a[0:15]
	v_mfma_f32_32x32x16_bf16 a[16:31], v[88:91], v[96:99], a[16:31]
	v_mfma_f32_32x32x16_bf16 a[32:47], v[100:103], v[108:111], a[32:47]
	v_mfma_f32_32x32x16_bf16 a[48:63], v[100:103], v[112:115], a[48:63]
	v_mfma_f32_32x32x16_bf16 a[0:15], v[104:107], v[108:111], a[0:15]
	v_mfma_f32_32x32x16_bf16 a[16:31], v[104:107], v[112:115], a[16:31]
	v_mfma_f32_32x32x16_bf16 a[32:47], v[116:119], v[124:127], a[32:47]
	v_mfma_f32_32x32x16_bf16 a[48:63], v[116:119], v[128:131], a[48:63]
	v_mfma_f32_32x32x16_bf16 a[0:15], v[120:123], v[124:127], a[0:15]
	v_mfma_f32_32x32x16_bf16 a[16:31], v[120:123], v[128:131], a[16:31]
	s_cbranch_scc0 .LBB0_254
	v_or_b32_e32 v65, s5, v65
	v_add_u32_e32 v121, v65, v66
	v_lshrrev_b32_e32 v65, 3, v64
	s_nop 7
	v_accvgpr_read_b32 v0, a16
	v_accvgpr_read_b32 v31, a15
	v_accvgpr_read_b32 v32, a48
	v_accvgpr_read_b32 v63, a47
	v_and_b32_e32 v103, 4, v65
	v_and_or_b32 v104, v64, 64, s4
	s_movk_i32 s0, 0x210
	v_lshlrev_b32_e32 v64, 5, v121
	v_accvgpr_read_b32 v86, a16
	v_accvgpr_read_b32 v85, a17
	v_accvgpr_read_b32 v84, a18
	v_accvgpr_read_b32 v83, a19
	v_accvgpr_read_b32 v81, a20
	v_accvgpr_read_b32 v80, a21
	v_accvgpr_read_b32 v79, a22
	v_accvgpr_read_b32 v78, a23
	v_accvgpr_read_b32 v77, a24
	v_accvgpr_read_b32 v76, a25
	v_accvgpr_read_b32 v75, a26
	v_accvgpr_read_b32 v74, a27
	v_accvgpr_read_b32 v73, a28
	v_accvgpr_read_b32 v72, a29
	v_accvgpr_read_b32 v71, a30
	v_accvgpr_read_b32 v70, a31
	v_accvgpr_read_b32 v102, a0
	v_accvgpr_read_b32 v101, a1
	v_accvgpr_read_b32 v100, a2
	v_accvgpr_read_b32 v99, a3
	v_accvgpr_read_b32 v98, a4
	v_accvgpr_read_b32 v97, a5
	v_accvgpr_read_b32 v96, a6
	v_accvgpr_read_b32 v95, a7
	v_accvgpr_read_b32 v94, a8
	v_accvgpr_read_b32 v93, a9
	v_accvgpr_read_b32 v92, a10
	v_accvgpr_read_b32 v91, a11
	v_accvgpr_read_b32 v90, a12
	v_accvgpr_read_b32 v89, a13
	v_accvgpr_read_b32 v88, a14
	v_accvgpr_read_b32 v87, a15
	v_accvgpr_read_b32 v120, a48
	v_accvgpr_read_b32 v119, a49
	v_accvgpr_read_b32 v118, a50
	v_accvgpr_read_b32 v117, a51
	v_accvgpr_read_b32 v116, a52
	v_accvgpr_read_b32 v115, a53
	v_accvgpr_read_b32 v114, a54
	v_accvgpr_read_b32 v113, a55
	v_accvgpr_read_b32 v112, a56
	v_accvgpr_read_b32 v111, a57
	v_accvgpr_read_b32 v110, a58
	v_accvgpr_read_b32 v109, a59
	v_accvgpr_read_b32 v108, a60
	v_accvgpr_read_b32 v107, a61
	v_accvgpr_read_b32 v106, a62
	v_accvgpr_read_b32 v105, a63
	v_accvgpr_read_b32 v137, a32
	v_accvgpr_read_b32 v136, a33
	v_accvgpr_read_b32 v135, a34
	v_accvgpr_read_b32 v134, a35
	v_accvgpr_read_b32 v133, a36
	v_accvgpr_read_b32 v132, a37
	v_accvgpr_read_b32 v131, a38
	v_accvgpr_read_b32 v130, a39
	v_accvgpr_read_b32 v129, a40
	v_accvgpr_read_b32 v128, a41
	v_accvgpr_read_b32 v127, a42
	v_accvgpr_read_b32 v126, a43
	v_accvgpr_read_b32 v125, a44
	v_accvgpr_read_b32 v124, a45
	v_accvgpr_read_b32 v123, a46
	v_accvgpr_read_b32 v122, a47
	v_accvgpr_read_b32 v1, a17
	v_accvgpr_read_b32 v2, a18
	v_accvgpr_read_b32 v3, a19
	v_accvgpr_read_b32 v4, a20
	v_accvgpr_read_b32 v5, a21
	v_accvgpr_read_b32 v6, a22
	v_accvgpr_read_b32 v7, a23
	v_accvgpr_read_b32 v8, a24
	v_accvgpr_read_b32 v9, a25
	v_accvgpr_read_b32 v10, a26
	v_accvgpr_read_b32 v11, a27
	v_accvgpr_read_b32 v12, a28
	v_accvgpr_read_b32 v13, a29
	v_accvgpr_read_b32 v14, a30
	v_accvgpr_read_b32 v15, a31
	v_accvgpr_read_b32 v30, a14
	v_accvgpr_read_b32 v29, a13
	v_accvgpr_read_b32 v28, a12
	v_accvgpr_read_b32 v27, a11
	v_accvgpr_read_b32 v26, a10
	v_accvgpr_read_b32 v25, a9
	v_accvgpr_read_b32 v24, a8
	v_accvgpr_read_b32 v23, a7
	v_accvgpr_read_b32 v22, a6
	v_accvgpr_read_b32 v21, a5
	v_accvgpr_read_b32 v20, a4
	v_accvgpr_read_b32 v19, a3
	v_accvgpr_read_b32 v18, a2
	v_accvgpr_read_b32 v17, a1
	v_accvgpr_read_b32 v16, a0
	v_accvgpr_read_b32 v33, a49
	v_accvgpr_read_b32 v34, a50
	v_accvgpr_read_b32 v35, a51
	v_accvgpr_read_b32 v36, a52
	v_accvgpr_read_b32 v37, a53
	v_accvgpr_read_b32 v38, a54
	v_accvgpr_read_b32 v39, a55
	v_accvgpr_read_b32 v40, a56
	v_accvgpr_read_b32 v41, a57
	v_accvgpr_read_b32 v42, a58
	v_accvgpr_read_b32 v43, a59
	v_accvgpr_read_b32 v44, a60
	v_accvgpr_read_b32 v45, a61
	v_accvgpr_read_b32 v46, a62
	v_accvgpr_read_b32 v47, a63
	v_accvgpr_read_b32 v62, a46
	v_accvgpr_read_b32 v61, a45
	v_accvgpr_read_b32 v60, a44
	v_accvgpr_read_b32 v59, a43
	v_accvgpr_read_b32 v58, a42
	v_accvgpr_read_b32 v57, a41
	v_accvgpr_read_b32 v56, a40
	v_accvgpr_read_b32 v55, a39
	v_accvgpr_read_b32 v54, a38
	v_accvgpr_read_b32 v53, a37
	v_accvgpr_read_b32 v52, a36
	v_accvgpr_read_b32 v51, a35
	v_accvgpr_read_b32 v50, a34
	v_accvgpr_read_b32 v49, a33
	v_accvgpr_read_b32 v48, a32
	v_cmp_gt_i32_e64 s[2:3], s0, v121
	v_ashrrev_i32_e32 v65, 31, v64
	v_lshrrev_b32_e32 v82, 4, v104
	v_lshlrev_b32_e32 v192, 1, v103
	s_and_saveexec_b64 s[0:1], s[2:3]
	s_cbranch_execz .LBB0_257
	s_waitcnt vmcnt(7)
	v_mul_f32_e32 v138, 0x3d372713, v137
	v_mul_f32_e32 v138, v137, v138
	v_fma_f32 v137, v137, v138, v137
	v_mul_f32_e32 v137, 0x3f4c422a, v137
	v_add_f32_e32 v137, v137, v137
	v_mul_f32_e32 v137, 0x3fb8aa3b, v137
	v_exp_f32_e32 v138, v137
	v_mul_f32_e32 v137, 0x3d372713, v136
	v_mul_f32_e32 v137, v136, v137
	v_fma_f32 v136, v136, v137, v136
	v_mul_f32_e32 v137, 0x3d372713, v135
	v_mul_f32_e32 v137, v135, v137
	v_fma_f32 v135, v135, v137, v135
	v_mul_f32_e32 v135, 0x3f4c422a, v135
	v_add_f32_e32 v135, v135, v135
	v_mul_f32_e32 v135, 0x3fb8aa3b, v135
	v_exp_f32_e32 v139, v135
	v_mul_f32_e32 v135, 0x3d372713, v134
	v_mul_f32_e32 v135, v134, v135
	v_fma_f32 v134, v134, v135, v134
	v_mul_f32_e32 v134, 0x3f4c422a, v134
	v_add_f32_e32 v134, v134, v134
	v_mul_f32_e32 v134, 0x3fb8aa3b, v134
	v_exp_f32_e32 v137, v134
	v_pk_add_f32 v[134:135], v[138:139], 1.0 op_sel_hi:[1,0]
	v_mul_f32_e32 v136, 0x3f4c422a, v136
	v_rcp_f32_e32 v139, v135
	v_add_f32_e32 v136, v136, v136
	v_mul_f32_e32 v136, 0x3fb8aa3b, v136
	v_exp_f32_e32 v136, v136
	s_waitcnt vmcnt(6)
	v_mul_f32_e32 v135, 2.0, v139
	v_rcp_f32_e32 v139, v134
	v_pk_add_f32 v[136:137], v[136:137], 1.0 op_sel_hi:[1,0]
	v_mad_i64_i32 v[66:67], s[4:5], s7, v215, v[64:65]
	v_mul_f32_e32 v134, 2.0, v139
	v_mov_b32_e32 v138, v48
	v_mov_b32_e32 v139, v50
	v_rcp_f32_e32 v50, v137
	v_pk_add_f32 v[134:135], v[134:135], 1.0 op_sel_hi:[1,0] neg_lo:[1,0] neg_hi:[1,0]
	v_pk_mul_f32 v[138:139], v[138:139], 0.5 op_sel_hi:[1,0]
	v_pk_add_f32 v[134:135], v[134:135], 1.0 op_sel_hi:[1,0]
	v_or_b32_e32 v66, v82, v66
	v_pk_mul_f32 v[134:135], v[138:139], v[134:135]
	v_mul_f32_e32 v137, 2.0, v50
	v_rcp_f32_e32 v50, v136
	v_readlane_b32 s8, v254, 3
	v_lshlrev_b64 v[68:69], 5, v[66:67]
	v_readlane_b32 s9, v254, 4
	v_mul_f32_e32 v136, 2.0, v50
	v_pk_add_f32 v[136:137], v[136:137], 1.0 op_sel_hi:[1,0] neg_lo:[1,0] neg_hi:[1,0]
	v_mov_b32_e32 v50, v49
	v_pk_mul_f32 v[48:49], v[50:51], 0.5 op_sel_hi:[1,0]
	v_pk_add_f32 v[50:51], v[136:137], 1.0 op_sel_hi:[1,0]
	v_lshl_add_u64 v[68:69], s[8:9], 0, v[68:69]
	v_pk_mul_f32 v[48:49], v[48:49], v[50:51]
	v_cvt_pk_bf16_f32 v48, v134, v48
	v_cvt_pk_bf16_f32 v49, v135, v49
	v_lshl_add_u64 v[68:69], v[68:69], 0, v[192:193]
	global_store_dwordx2 v[68:69], v[48:49], off
	v_mul_f32_e32 v49, 0x3d372713, v132
	v_mul_f32_e32 v49, v132, v49
	v_fma_f32 v49, v132, v49, v132
	v_mul_f32_e32 v49, 0x3f4c422a, v49
	v_add_f32_e32 v49, v49, v49
	v_mul_f32_e32 v49, 0x3fb8aa3b, v49
	v_mul_f32_e32 v48, 0x3d372713, v133
	v_exp_f32_e32 v50, v49
	v_mul_f32_e32 v49, 0x3d372713, v131
	v_mul_f32_e32 v48, v133, v48
	v_mul_f32_e32 v49, v131, v49
	v_fma_f32 v48, v133, v48, v133
	v_fma_f32 v49, v131, v49, v131
	v_mul_f32_e32 v48, 0x3f4c422a, v48
	v_mul_f32_e32 v49, 0x3f4c422a, v49
	v_add_f32_e32 v48, v48, v48
	v_add_f32_e32 v49, v49, v49
	v_mul_f32_e32 v48, 0x3fb8aa3b, v48
	v_mul_f32_e32 v49, 0x3fb8aa3b, v49
	v_exp_f32_e32 v48, v48
	v_exp_f32_e32 v49, v49
	v_mul_f32_e32 v51, 0x3d372713, v130
	v_mul_f32_e32 v51, v130, v51
	v_fma_f32 v51, v130, v51, v130
	v_pk_add_f32 v[48:49], v[48:49], 1.0 op_sel_hi:[1,0]
	v_mul_f32_e32 v51, 0x3f4c422a, v51
	v_rcp_f32_e32 v131, v49
	v_add_f32_e32 v51, v51, v51
	v_mul_f32_e32 v51, 0x3fb8aa3b, v51
	v_exp_f32_e32 v51, v51
	v_mul_f32_e32 v49, 2.0, v131
	v_rcp_f32_e32 v131, v48
	v_pk_add_f32 v[50:51], v[50:51], 1.0 op_sel_hi:[1,0]
	v_or_b32_e32 v66, 1, v66
	v_mul_f32_e32 v48, 2.0, v131
	v_mov_b32_e32 v130, v52
	v_mov_b32_e32 v131, v54
	v_rcp_f32_e32 v54, v51
	v_pk_add_f32 v[48:49], v[48:49], 1.0 op_sel_hi:[1,0] neg_lo:[1,0] neg_hi:[1,0]
	v_pk_mul_f32 v[130:131], v[130:131], 0.5 op_sel_hi:[1,0]
	v_pk_add_f32 v[48:49], v[48:49], 1.0 op_sel_hi:[1,0]
	s_nop 0
	v_pk_mul_f32 v[48:49], v[130:131], v[48:49]
	v_mul_f32_e32 v51, 2.0, v54
	v_rcp_f32_e32 v54, v50
	s_nop 0
	v_mul_f32_e32 v50, 2.0, v54
	v_pk_add_f32 v[50:51], v[50:51], 1.0 op_sel_hi:[1,0] neg_lo:[1,0] neg_hi:[1,0]
	v_mov_b32_e32 v54, v53
	v_pk_mul_f32 v[52:53], v[54:55], 0.5 op_sel_hi:[1,0]
	v_pk_add_f32 v[50:51], v[50:51], 1.0 op_sel_hi:[1,0]
	s_nop 0
	v_pk_mul_f32 v[50:51], v[52:53], v[50:51]
	v_cvt_pk_bf16_f32 v49, v49, v51
	v_mul_f32_e32 v51, 0x3d372713, v128
	v_mul_f32_e32 v51, v128, v51
	v_cvt_pk_bf16_f32 v48, v48, v50
	v_fma_f32 v51, v128, v51, v128
	v_mul_f32_e32 v51, 0x3f4c422a, v51
	v_add_f32_e32 v51, v51, v51
	v_mul_f32_e32 v51, 0x3fb8aa3b, v51
	v_mul_f32_e32 v50, 0x3d372713, v129
	v_exp_f32_e32 v52, v51
	v_mul_f32_e32 v51, 0x3d372713, v127
	v_mul_f32_e32 v50, v129, v50
	v_mul_f32_e32 v51, v127, v51
	v_fma_f32 v50, v129, v50, v129
	v_fma_f32 v51, v127, v51, v127
	v_mul_f32_e32 v50, 0x3f4c422a, v50
	v_mul_f32_e32 v51, 0x3f4c422a, v51
	v_add_f32_e32 v50, v50, v50
	v_add_f32_e32 v51, v51, v51
	v_mul_f32_e32 v50, 0x3fb8aa3b, v50
	v_mul_f32_e32 v51, 0x3fb8aa3b, v51
	v_exp_f32_e32 v50, v50
	v_exp_f32_e32 v51, v51
	global_store_dwordx2 v[68:69], v[48:49], off offset:16
	v_lshlrev_b64 v[48:49], 5, v[66:67]
	v_mul_f32_e32 v53, 0x3d372713, v126
	v_pk_add_f32 v[50:51], v[50:51], 1.0 op_sel_hi:[1,0]
	v_mul_f32_e32 v53, v126, v53
	v_rcp_f32_e32 v55, v51
	v_fma_f32 v53, v126, v53, v126
	v_mul_f32_e32 v53, 0x3f4c422a, v53
	v_add_f32_e32 v53, v53, v53
	v_mul_f32_e32 v51, 2.0, v55
	v_rcp_f32_e32 v55, v50
	v_mul_f32_e32 v53, 0x3fb8aa3b, v53
	v_exp_f32_e32 v53, v53
	v_lshl_add_u64 v[48:49], s[8:9], 0, v[48:49]
	v_mul_f32_e32 v50, 2.0, v55
	v_pk_add_f32 v[50:51], v[50:51], 1.0 op_sel_hi:[1,0] neg_lo:[1,0] neg_hi:[1,0]
	v_mov_b32_e32 v54, v56
	v_mov_b32_e32 v55, v58
	v_pk_mul_f32 v[54:55], v[54:55], 0.5 op_sel_hi:[1,0]
	v_pk_add_f32 v[50:51], v[50:51], 1.0 op_sel_hi:[1,0]
	v_pk_add_f32 v[52:53], v[52:53], 1.0 op_sel_hi:[1,0]
	v_pk_mul_f32 v[50:51], v[54:55], v[50:51]
	v_rcp_f32_e32 v55, v53
	v_lshl_add_u64 v[48:49], v[48:49], 0, v[192:193]
	v_mul_f32_e32 v53, 2.0, v55
	v_rcp_f32_e32 v55, v52
	s_nop 0
	v_mul_f32_e32 v52, 2.0, v55
	v_pk_add_f32 v[52:53], v[52:53], 1.0 op_sel_hi:[1,0] neg_lo:[1,0] neg_hi:[1,0]
	v_mov_b32_e32 v58, v57
	v_pk_mul_f32 v[54:55], v[58:59], 0.5 op_sel_hi:[1,0]
	v_pk_add_f32 v[52:53], v[52:53], 1.0 op_sel_hi:[1,0]
	s_nop 0
	v_pk_mul_f32 v[52:53], v[54:55], v[52:53]
	v_cvt_pk_bf16_f32 v51, v51, v53
	v_cvt_pk_bf16_f32 v50, v50, v52
	global_store_dwordx2 v[48:49], v[50:51], off
	v_mul_f32_e32 v51, 0x3d372713, v124
	v_mul_f32_e32 v51, v124, v51
	v_fma_f32 v51, v124, v51, v124
	v_mul_f32_e32 v51, 0x3f4c422a, v51
	v_add_f32_e32 v51, v51, v51
	v_mul_f32_e32 v51, 0x3fb8aa3b, v51
	v_mul_f32_e32 v50, 0x3d372713, v125
	v_exp_f32_e32 v52, v51
	v_mul_f32_e32 v51, 0x3d372713, v123
	v_mul_f32_e32 v50, v125, v50
	v_mul_f32_e32 v51, v123, v51
	v_fma_f32 v50, v125, v50, v125
	v_fma_f32 v51, v123, v51, v123
	v_mul_f32_e32 v50, 0x3f4c422a, v50
	v_mul_f32_e32 v51, 0x3f4c422a, v51
	v_add_f32_e32 v50, v50, v50
	v_add_f32_e32 v51, v51, v51
	v_mul_f32_e32 v50, 0x3fb8aa3b, v50
	v_mul_f32_e32 v51, 0x3fb8aa3b, v51
	v_exp_f32_e32 v50, v50
	v_exp_f32_e32 v51, v51
	v_mul_f32_e32 v53, 0x3d372713, v122
	v_mul_f32_e32 v53, v122, v53
	v_fma_f32 v53, v122, v53, v122
	v_pk_add_f32 v[50:51], v[50:51], 1.0 op_sel_hi:[1,0]
	v_mul_f32_e32 v53, 0x3f4c422a, v53
	v_rcp_f32_e32 v55, v51
	v_add_f32_e32 v53, v53, v53
	v_mul_f32_e32 v53, 0x3fb8aa3b, v53
	v_exp_f32_e32 v53, v53
	v_mul_f32_e32 v51, 2.0, v55
	v_rcp_f32_e32 v55, v50
	v_pk_add_f32 v[52:53], v[52:53], 1.0 op_sel_hi:[1,0]
	v_mul_f32_e32 v50, 2.0, v55
	v_pk_add_f32 v[50:51], v[50:51], 1.0 op_sel_hi:[1,0] neg_lo:[1,0] neg_hi:[1,0]
	v_mov_b32_e32 v54, v60
	v_mov_b32_e32 v55, v62
	v_pk_mul_f32 v[54:55], v[54:55], 0.5 op_sel_hi:[1,0]
	v_pk_add_f32 v[50:51], v[50:51], 1.0 op_sel_hi:[1,0]
	v_mov_b32_e32 v62, v61
	v_pk_mul_f32 v[50:51], v[54:55], v[50:51]
	v_rcp_f32_e32 v55, v53
	s_nop 0
	v_mul_f32_e32 v53, 2.0, v55
	v_rcp_f32_e32 v55, v52
	s_nop 0
	v_mul_f32_e32 v52, 2.0, v55
	v_pk_add_f32 v[52:53], v[52:53], 1.0 op_sel_hi:[1,0] neg_lo:[1,0] neg_hi:[1,0]
	v_pk_mul_f32 v[54:55], v[62:63], 0.5 op_sel_hi:[1,0]
	v_pk_add_f32 v[52:53], v[52:53], 1.0 op_sel_hi:[1,0]
	s_nop 0
	v_pk_mul_f32 v[52:53], v[54:55], v[52:53]
	v_cvt_pk_bf16_f32 v51, v51, v53
	v_cvt_pk_bf16_f32 v50, v50, v52
	global_store_dwordx2 v[48:49], v[50:51], off offset:16
.LBB0_257:
	s_or_b64 exec, exec, s[0:1]
	s_movk_i32 s0, 0x1f0
	v_or_b32_e32 v48, 0x400, v64
	v_cmp_gt_i32_e64 s[4:5], s0, v121
	v_ashrrev_i32_e32 v49, 31, v48
	s_and_saveexec_b64 s[0:1], s[4:5]
	s_cbranch_execz .LBB0_259
	v_mul_f32_e32 v53, 0x3d372713, v119
	v_mul_f32_e32 v53, v119, v53
	v_fma_f32 v53, v119, v53, v119
	v_mul_f32_e32 v53, 0x3f4c422a, v53
	v_add_f32_e32 v53, v53, v53
	v_mul_f32_e32 v53, 0x3fb8aa3b, v53
	v_mul_f32_e32 v52, 0x3d372713, v120
	v_exp_f32_e32 v54, v53
	v_mul_f32_e32 v53, 0x3d372713, v118
	v_mul_f32_e32 v52, v120, v52
	v_mul_f32_e32 v53, v118, v53
	v_fma_f32 v52, v120, v52, v120
	v_fma_f32 v53, v118, v53, v118
	v_mul_f32_e32 v52, 0x3f4c422a, v52
	v_mul_f32_e32 v53, 0x3f4c422a, v53
	v_add_f32_e32 v52, v52, v52
	v_add_f32_e32 v53, v53, v53
	v_mul_f32_e32 v52, 0x3fb8aa3b, v52
	v_mul_f32_e32 v53, 0x3fb8aa3b, v53
	v_exp_f32_e32 v52, v52
	v_exp_f32_e32 v53, v53
	s_mul_hi_i32 s8, s7, 0x4200
	s_mul_i32 s9, s7, 0x4200
	v_or_b32_e32 v50, s9, v82
	v_pk_add_f32 v[52:53], v[52:53], 1.0 op_sel_hi:[1,0]
	v_mov_b32_e32 v51, s8
	v_rcp_f32_e32 v57, v53
	v_mul_f32_e32 v55, 0x3d372713, v117
	v_mul_f32_e32 v55, v117, v55
	v_fma_f32 v55, v117, v55, v117
	v_mul_f32_e32 v53, 2.0, v57
	v_rcp_f32_e32 v57, v52
	v_mul_f32_e32 v55, 0x3f4c422a, v55
	v_add_f32_e32 v55, v55, v55
	v_mul_f32_e32 v55, 0x3fb8aa3b, v55
	v_exp_f32_e32 v55, v55
	s_nop 0
	v_pk_add_f32 v[54:55], v[54:55], 1.0 op_sel_hi:[1,0]
	v_mul_f32_e32 v52, 2.0, v57
	v_mov_b32_e32 v56, v32
	v_mov_b32_e32 v57, v34
	v_rcp_f32_e32 v34, v55
	v_pk_add_f32 v[52:53], v[52:53], 1.0 op_sel_hi:[1,0] neg_lo:[1,0] neg_hi:[1,0]
	v_pk_mul_f32 v[56:57], v[56:57], 0.5 op_sel_hi:[1,0]
	v_pk_add_f32 v[52:53], v[52:53], 1.0 op_sel_hi:[1,0]
	v_lshl_add_u64 v[50:51], v[50:51], 0, v[48:49]
	v_pk_mul_f32 v[52:53], v[56:57], v[52:53]
	v_mul_f32_e32 v55, 2.0, v34
	v_rcp_f32_e32 v34, v54
	v_readlane_b32 s10, v254, 3
	v_lshlrev_b64 v[50:51], 5, v[50:51]
	v_readlane_b32 s11, v254, 4
	v_mul_f32_e32 v54, 2.0, v34
	v_pk_add_f32 v[54:55], v[54:55], 1.0 op_sel_hi:[1,0] neg_lo:[1,0] neg_hi:[1,0]
	v_mov_b32_e32 v34, v33
	v_pk_mul_f32 v[32:33], v[34:35], 0.5 op_sel_hi:[1,0]
	v_pk_add_f32 v[34:35], v[54:55], 1.0 op_sel_hi:[1,0]
	v_lshl_add_u64 v[50:51], s[10:11], 0, v[50:51]
	v_pk_mul_f32 v[32:33], v[32:33], v[34:35]
	v_cvt_pk_bf16_f32 v32, v52, v32
	v_cvt_pk_bf16_f32 v33, v53, v33
	v_lshl_add_u64 v[50:51], v[50:51], 0, v[192:193]
	global_store_dwordx2 v[50:51], v[32:33], off
	v_mul_f32_e32 v33, 0x3d372713, v115
	v_mul_f32_e32 v33, v115, v33
	v_fma_f32 v33, v115, v33, v115
	v_mul_f32_e32 v33, 0x3f4c422a, v33
	v_add_f32_e32 v33, v33, v33
	v_mul_f32_e32 v33, 0x3fb8aa3b, v33
	v_mul_f32_e32 v32, 0x3d372713, v116
	v_exp_f32_e32 v34, v33
	v_mul_f32_e32 v33, 0x3d372713, v114
	v_mul_f32_e32 v32, v116, v32
	v_mul_f32_e32 v33, v114, v33
	v_fma_f32 v32, v116, v32, v116
	v_fma_f32 v33, v114, v33, v114
	v_mul_f32_e32 v32, 0x3f4c422a, v32
	v_mul_f32_e32 v33, 0x3f4c422a, v33
	v_add_f32_e32 v32, v32, v32
	v_add_f32_e32 v33, v33, v33
	v_mul_f32_e32 v32, 0x3fb8aa3b, v32
	v_mul_f32_e32 v33, 0x3fb8aa3b, v33
	v_exp_f32_e32 v32, v32
	v_exp_f32_e32 v33, v33
	v_mul_f32_e32 v35, 0x3d372713, v113
	v_mul_f32_e32 v35, v113, v35
	v_fma_f32 v35, v113, v35, v113
	v_pk_add_f32 v[32:33], v[32:33], 1.0 op_sel_hi:[1,0]
	v_mul_f32_e32 v35, 0x3f4c422a, v35
	v_rcp_f32_e32 v53, v33
	v_add_f32_e32 v35, v35, v35
	v_mul_f32_e32 v35, 0x3fb8aa3b, v35
	v_exp_f32_e32 v35, v35
	v_mul_f32_e32 v33, 2.0, v53
	v_rcp_f32_e32 v53, v32
	v_pk_add_f32 v[34:35], v[34:35], 1.0 op_sel_hi:[1,0]
	v_mul_f32_e32 v32, 2.0, v53
	v_mov_b32_e32 v52, v36
	v_mov_b32_e32 v53, v38
	v_rcp_f32_e32 v38, v35
	v_pk_add_f32 v[32:33], v[32:33], 1.0 op_sel_hi:[1,0] neg_lo:[1,0] neg_hi:[1,0]
	v_pk_mul_f32 v[52:53], v[52:53], 0.5 op_sel_hi:[1,0]
	v_pk_add_f32 v[32:33], v[32:33], 1.0 op_sel_hi:[1,0]
	s_nop 0
	v_pk_mul_f32 v[32:33], v[52:53], v[32:33]
	v_mul_f32_e32 v35, 2.0, v38
	v_rcp_f32_e32 v38, v34
	s_nop 0
	v_mul_f32_e32 v34, 2.0, v38
	v_pk_add_f32 v[34:35], v[34:35], 1.0 op_sel_hi:[1,0] neg_lo:[1,0] neg_hi:[1,0]
	v_mov_b32_e32 v38, v37
	v_pk_mul_f32 v[36:37], v[38:39], 0.5 op_sel_hi:[1,0]
	v_pk_add_f32 v[34:35], v[34:35], 1.0 op_sel_hi:[1,0]
	s_nop 0
	v_pk_mul_f32 v[34:35], v[36:37], v[34:35]
	v_cvt_pk_bf16_f32 v33, v33, v35
	v_mul_f32_e32 v35, 0x3d372713, v111
	v_mul_f32_e32 v35, v111, v35
	v_cvt_pk_bf16_f32 v32, v32, v34
	v_fma_f32 v35, v111, v35, v111
	v_mul_f32_e32 v35, 0x3f4c422a, v35
	v_add_f32_e32 v35, v35, v35
	v_mul_f32_e32 v35, 0x3fb8aa3b, v35
	v_mul_f32_e32 v34, 0x3d372713, v112
	v_exp_f32_e32 v36, v35
	v_mul_f32_e32 v35, 0x3d372713, v110
	v_mul_f32_e32 v34, v112, v34
	v_mul_f32_e32 v35, v110, v35
	v_fma_f32 v34, v112, v34, v112
	v_fma_f32 v35, v110, v35, v110
	v_mul_f32_e32 v34, 0x3f4c422a, v34
	v_mul_f32_e32 v35, 0x3f4c422a, v35
	v_add_f32_e32 v34, v34, v34
	v_add_f32_e32 v35, v35, v35
	v_mul_f32_e32 v34, 0x3fb8aa3b, v34
	v_mul_f32_e32 v35, 0x3fb8aa3b, v35
	v_exp_f32_e32 v34, v34
	v_exp_f32_e32 v35, v35
	global_store_dwordx2 v[50:51], v[32:33], off offset:16
	v_mul_f32_e32 v37, 0x3d372713, v109
	v_mul_f32_e32 v37, v109, v37
	v_pk_add_f32 v[34:35], v[34:35], 1.0 op_sel_hi:[1,0]
	v_fma_f32 v37, v109, v37, v109
	v_rcp_f32_e32 v39, v35
	v_mul_f32_e32 v37, 0x3f4c422a, v37
	v_add_f32_e32 v37, v37, v37
	v_mul_f32_e32 v37, 0x3fb8aa3b, v37
	v_mul_f32_e32 v35, 2.0, v39
	v_rcp_f32_e32 v39, v34
	v_exp_f32_e32 v37, v37
	v_mad_i64_i32 v[32:33], s[8:9], s7, v215, v[48:49]
	v_mul_f32_e32 v34, 2.0, v39
	v_pk_add_f32 v[34:35], v[34:35], 1.0 op_sel_hi:[1,0] neg_lo:[1,0] neg_hi:[1,0]
	v_mov_b32_e32 v38, v40
	v_mov_b32_e32 v39, v42
	v_pk_mul_f32 v[38:39], v[38:39], 0.5 op_sel_hi:[1,0]
	v_pk_add_f32 v[34:35], v[34:35], 1.0 op_sel_hi:[1,0]
	v_pk_add_f32 v[36:37], v[36:37], 1.0 op_sel_hi:[1,0]
	v_pk_mul_f32 v[34:35], v[38:39], v[34:35]
	v_rcp_f32_e32 v39, v37
	v_or3_b32 v32, v82, v32, 1
	v_lshlrev_b64 v[32:33], 5, v[32:33]
	v_lshl_add_u64 v[32:33], s[10:11], 0, v[32:33]
	v_mul_f32_e32 v37, 2.0, v39
	v_rcp_f32_e32 v39, v36
	v_lshl_add_u64 v[32:33], v[32:33], 0, v[192:193]
	v_mul_f32_e32 v36, 2.0, v39
	v_pk_add_f32 v[36:37], v[36:37], 1.0 op_sel_hi:[1,0] neg_lo:[1,0] neg_hi:[1,0]
	v_mov_b32_e32 v42, v41
	v_pk_mul_f32 v[38:39], v[42:43], 0.5 op_sel_hi:[1,0]
	v_pk_add_f32 v[36:37], v[36:37], 1.0 op_sel_hi:[1,0]
	s_nop 0
	v_pk_mul_f32 v[36:37], v[38:39], v[36:37]
	v_cvt_pk_bf16_f32 v35, v35, v37
	v_cvt_pk_bf16_f32 v34, v34, v36
	global_store_dwordx2 v[32:33], v[34:35], off
	v_mul_f32_e32 v35, 0x3d372713, v107
	v_mul_f32_e32 v35, v107, v35
	v_fma_f32 v35, v107, v35, v107
	v_mul_f32_e32 v35, 0x3f4c422a, v35
	v_add_f32_e32 v35, v35, v35
	v_mul_f32_e32 v35, 0x3fb8aa3b, v35
	v_mul_f32_e32 v34, 0x3d372713, v108
	v_exp_f32_e32 v36, v35
	v_mul_f32_e32 v35, 0x3d372713, v106
	v_mul_f32_e32 v34, v108, v34
	v_mul_f32_e32 v35, v106, v35
	v_fma_f32 v34, v108, v34, v108
	v_fma_f32 v35, v106, v35, v106
	v_mul_f32_e32 v34, 0x3f4c422a, v34
	v_mul_f32_e32 v35, 0x3f4c422a, v35
	v_add_f32_e32 v34, v34, v34
	v_add_f32_e32 v35, v35, v35
	v_mul_f32_e32 v34, 0x3fb8aa3b, v34
	v_mul_f32_e32 v35, 0x3fb8aa3b, v35
	v_exp_f32_e32 v34, v34
	v_exp_f32_e32 v35, v35
	v_mul_f32_e32 v37, 0x3d372713, v105
	v_mul_f32_e32 v37, v105, v37
	v_fma_f32 v37, v105, v37, v105
	v_pk_add_f32 v[34:35], v[34:35], 1.0 op_sel_hi:[1,0]
	v_mul_f32_e32 v37, 0x3f4c422a, v37
	v_rcp_f32_e32 v39, v35
	v_add_f32_e32 v37, v37, v37
	v_mul_f32_e32 v37, 0x3fb8aa3b, v37
	v_exp_f32_e32 v37, v37
	v_mul_f32_e32 v35, 2.0, v39
	v_rcp_f32_e32 v39, v34
	v_pk_add_f32 v[36:37], v[36:37], 1.0 op_sel_hi:[1,0]
	v_mul_f32_e32 v34, 2.0, v39
	v_pk_add_f32 v[34:35], v[34:35], 1.0 op_sel_hi:[1,0] neg_lo:[1,0] neg_hi:[1,0]
	v_mov_b32_e32 v38, v44
	v_mov_b32_e32 v39, v46
	v_pk_mul_f32 v[38:39], v[38:39], 0.5 op_sel_hi:[1,0]
	v_pk_add_f32 v[34:35], v[34:35], 1.0 op_sel_hi:[1,0]
	v_mov_b32_e32 v46, v45
	v_pk_mul_f32 v[34:35], v[38:39], v[34:35]
	v_rcp_f32_e32 v39, v37
	s_nop 0
	v_mul_f32_e32 v37, 2.0, v39
	v_rcp_f32_e32 v39, v36
	s_nop 0
	v_mul_f32_e32 v36, 2.0, v39
	v_pk_add_f32 v[36:37], v[36:37], 1.0 op_sel_hi:[1,0] neg_lo:[1,0] neg_hi:[1,0]
	v_pk_mul_f32 v[38:39], v[46:47], 0.5 op_sel_hi:[1,0]
	v_pk_add_f32 v[36:37], v[36:37], 1.0 op_sel_hi:[1,0]
	s_nop 0
	v_pk_mul_f32 v[36:37], v[38:39], v[36:37]
	v_cvt_pk_bf16_f32 v35, v35, v37
	v_cvt_pk_bf16_f32 v34, v34, v36
	global_store_dwordx2 v[32:33], v[34:35], off offset:16
.LBB0_259:
	s_or_b64 exec, exec, s[0:1]
	v_or3_b32 v32, v103, v104, 32
	v_lshrrev_b32_e32 v34, 4, v32
	s_and_saveexec_b64 s[0:1], s[2:3]
	s_cbranch_execz .LBB0_261
	v_mul_f32_e32 v35, 0x3d372713, v102
	v_mul_f32_e32 v35, v102, v35
	v_fma_f32 v35, v102, v35, v102
	v_mul_f32_e32 v35, 0x3f4c422a, v35
	v_add_f32_e32 v35, v35, v35
	v_mul_f32_e32 v35, 0x3fb8aa3b, v35
	v_exp_f32_e32 v38, v35
	v_mul_f32_e32 v35, 0x3d372713, v101
	v_mul_f32_e32 v35, v101, v35
	v_fma_f32 v35, v101, v35, v101
	v_mul_f32_e32 v35, 0x3f4c422a, v35
	v_add_f32_e32 v35, v35, v35
	v_mul_f32_e32 v35, 0x3fb8aa3b, v35
	v_exp_f32_e32 v40, v35
	v_mul_f32_e32 v35, 0x3d372713, v100
	v_mul_f32_e32 v35, v100, v35
	v_fma_f32 v35, v100, v35, v100
	v_mul_f32_e32 v35, 0x3f4c422a, v35
	v_add_f32_e32 v35, v35, v35
	v_mul_f32_e32 v35, 0x3fb8aa3b, v35
	v_exp_f32_e32 v39, v35
	v_mul_f32_e32 v35, 0x3d372713, v99
	v_mul_f32_e32 v35, v99, v35
	v_fma_f32 v35, v99, v35, v99
	v_mul_f32_e32 v35, 0x3f4c422a, v35
	v_add_f32_e32 v35, v35, v35
	v_mul_f32_e32 v35, 0x3fb8aa3b, v35
	v_pk_add_f32 v[38:39], v[38:39], 1.0 op_sel_hi:[1,0]
	v_exp_f32_e32 v41, v35
	v_rcp_f32_e32 v42, v39
	v_pk_add_f32 v[40:41], v[40:41], 1.0 op_sel_hi:[1,0]
	v_mad_i64_i32 v[32:33], s[2:3], s7, v215, v[64:65]
	v_mul_f32_e32 v39, 2.0, v42
	v_rcp_f32_e32 v42, v38
	v_or_b32_e32 v36, v32, v34
	v_mov_b32_e32 v37, v33
	v_readlane_b32 s8, v254, 3
	v_mul_f32_e32 v35, 2.0, v42
	v_mov_b32_e32 v42, v16
	v_mov_b32_e32 v43, v18
	v_rcp_f32_e32 v18, v41
	v_mov_b32_e32 v38, v35
	v_pk_add_f32 v[38:39], v[38:39], 1.0 op_sel_hi:[1,0] neg_lo:[1,0] neg_hi:[1,0]
	v_pk_mul_f32 v[42:43], v[42:43], 0.5 op_sel_hi:[1,0]
	v_pk_add_f32 v[38:39], v[38:39], 1.0 op_sel_hi:[1,0]
	v_pk_mul_f32 v[38:39], v[42:43], v[38:39]
	v_mul_f32_e32 v41, 2.0, v18
	v_rcp_f32_e32 v18, v40
	v_lshlrev_b64 v[36:37], 5, v[36:37]
	v_readlane_b32 s9, v254, 4
	v_mul_f32_e32 v40, 2.0, v18
	v_pk_add_f32 v[40:41], v[40:41], 1.0 op_sel_hi:[1,0] neg_lo:[1,0] neg_hi:[1,0]
	v_mov_b32_e32 v18, v17
	v_pk_mul_f32 v[16:17], v[18:19], 0.5 op_sel_hi:[1,0]
	v_pk_add_f32 v[18:19], v[40:41], 1.0 op_sel_hi:[1,0]
	v_lshl_add_u64 v[36:37], s[8:9], 0, v[36:37]
	v_pk_mul_f32 v[16:17], v[16:17], v[18:19]
	v_cvt_pk_bf16_f32 v16, v38, v16
	v_mul_f32_e32 v19, 0x3d372713, v97
	v_mul_f32_e32 v19, v97, v19
	v_fma_f32 v19, v97, v19, v97
	v_cvt_pk_bf16_f32 v17, v39, v17
	v_mul_f32_e32 v19, 0x3f4c422a, v19
	v_add_f32_e32 v19, v19, v19
	v_lshl_add_u64 v[36:37], v[36:37], 0, v[192:193]
	v_mul_f32_e32 v19, 0x3fb8aa3b, v19
	global_store_dwordx2 v[36:37], v[16:17], off
	v_mul_f32_e32 v18, 0x3d372713, v98
	v_exp_f32_e32 v36, v19
	v_mul_f32_e32 v19, 0x3d372713, v96
	v_mul_f32_e32 v18, v98, v18
	v_mul_f32_e32 v19, v96, v19
	v_fma_f32 v18, v98, v18, v98
	v_fma_f32 v19, v96, v19, v96
	v_or_b32_e32 v35, v82, v32
	v_mul_f32_e32 v18, 0x3f4c422a, v18
	v_mul_f32_e32 v19, 0x3f4c422a, v19
	v_or_b32_e32 v32, 2, v35
	v_add_f32_e32 v18, v18, v18
	v_add_f32_e32 v19, v19, v19
	v_lshlrev_b64 v[16:17], 5, v[32:33]
	v_mul_f32_e32 v18, 0x3fb8aa3b, v18
	v_mul_f32_e32 v19, 0x3fb8aa3b, v19
	v_mul_f32_e32 v32, 0x3d372713, v95
	v_exp_f32_e32 v18, v18
	v_exp_f32_e32 v19, v19
	v_mul_f32_e32 v32, v95, v32
	v_fma_f32 v32, v95, v32, v95
	v_mul_f32_e32 v32, 0x3f4c422a, v32
	v_add_f32_e32 v32, v32, v32
	v_mul_f32_e32 v32, 0x3fb8aa3b, v32
	v_pk_add_f32 v[18:19], v[18:19], 1.0 op_sel_hi:[1,0]
	v_exp_f32_e32 v37, v32
	v_rcp_f32_e32 v38, v19
	v_pk_add_f32 v[36:37], v[36:37], 1.0 op_sel_hi:[1,0]
	v_lshl_add_u64 v[16:17], s[8:9], 0, v[16:17]
	v_lshl_add_u64 v[16:17], v[16:17], 0, v[192:193]
	v_mul_f32_e32 v19, 2.0, v38
	v_rcp_f32_e32 v38, v18
	s_nop 0
	v_mul_f32_e32 v32, 2.0, v38
	v_mov_b32_e32 v38, v20
	v_mov_b32_e32 v39, v22
	v_rcp_f32_e32 v22, v37
	v_mov_b32_e32 v18, v32
	v_pk_add_f32 v[18:19], v[18:19], 1.0 op_sel_hi:[1,0] neg_lo:[1,0] neg_hi:[1,0]
	v_pk_mul_f32 v[38:39], v[38:39], 0.5 op_sel_hi:[1,0]
	v_pk_add_f32 v[18:19], v[18:19], 1.0 op_sel_hi:[1,0]
	v_pk_mul_f32 v[18:19], v[38:39], v[18:19]
	v_mul_f32_e32 v37, 2.0, v22
	v_rcp_f32_e32 v22, v36
	s_nop 0
	v_mul_f32_e32 v36, 2.0, v22
	v_pk_add_f32 v[36:37], v[36:37], 1.0 op_sel_hi:[1,0] neg_lo:[1,0] neg_hi:[1,0]
	v_mov_b32_e32 v22, v21
	v_pk_mul_f32 v[20:21], v[22:23], 0.5 op_sel_hi:[1,0]
	v_pk_add_f32 v[22:23], v[36:37], 1.0 op_sel_hi:[1,0]
	v_or_b32_e32 v32, 3, v35
	v_pk_mul_f32 v[20:21], v[20:21], v[22:23]
	v_cvt_pk_bf16_f32 v19, v19, v21
	v_cvt_pk_bf16_f32 v18, v18, v20
	global_store_dwordx2 v[16:17], v[18:19], off offset:16
	v_mul_f32_e32 v19, 0x3d372713, v93
	v_mul_f32_e32 v19, v93, v19
	v_fma_f32 v19, v93, v19, v93
	v_mul_f32_e32 v19, 0x3f4c422a, v19
	v_add_f32_e32 v19, v19, v19
	v_mul_f32_e32 v19, 0x3fb8aa3b, v19
	v_mul_f32_e32 v18, 0x3d372713, v94
	v_exp_f32_e32 v20, v19
	v_mul_f32_e32 v19, 0x3d372713, v92
	v_mul_f32_e32 v18, v94, v18
	v_mul_f32_e32 v19, v92, v19
	v_fma_f32 v18, v94, v18, v94
	v_fma_f32 v19, v92, v19, v92
	v_mul_f32_e32 v18, 0x3f4c422a, v18
	v_mul_f32_e32 v19, 0x3f4c422a, v19
	v_add_f32_e32 v18, v18, v18
	v_add_f32_e32 v19, v19, v19
	v_mul_f32_e32 v18, 0x3fb8aa3b, v18
	v_mul_f32_e32 v19, 0x3fb8aa3b, v19
	v_exp_f32_e32 v18, v18
	v_exp_f32_e32 v19, v19
	v_lshlrev_b64 v[16:17], 5, v[32:33]
	v_mul_f32_e32 v21, 0x3d372713, v91
	v_mul_f32_e32 v21, v91, v21
	v_pk_add_f32 v[18:19], v[18:19], 1.0 op_sel_hi:[1,0]
	v_fma_f32 v21, v91, v21, v91
	v_rcp_f32_e32 v23, v19
	v_mul_f32_e32 v21, 0x3f4c422a, v21
	v_add_f32_e32 v21, v21, v21
	v_mul_f32_e32 v21, 0x3fb8aa3b, v21
	v_mul_f32_e32 v19, 2.0, v23
	v_rcp_f32_e32 v23, v18
	v_exp_f32_e32 v21, v21
	v_lshl_add_u64 v[16:17], s[8:9], 0, v[16:17]
	v_lshl_add_u64 v[16:17], v[16:17], 0, v[192:193]
	v_mul_f32_e32 v18, 2.0, v23
	v_pk_add_f32 v[18:19], v[18:19], 1.0 op_sel_hi:[1,0] neg_lo:[1,0] neg_hi:[1,0]
	v_mov_b32_e32 v22, v24
	v_mov_b32_e32 v23, v26
	v_pk_mul_f32 v[22:23], v[22:23], 0.5 op_sel_hi:[1,0]
	v_pk_add_f32 v[18:19], v[18:19], 1.0 op_sel_hi:[1,0]
	v_pk_add_f32 v[20:21], v[20:21], 1.0 op_sel_hi:[1,0]
	v_pk_mul_f32 v[18:19], v[22:23], v[18:19]
	v_rcp_f32_e32 v23, v21
	s_nop 0
	v_mul_f32_e32 v21, 2.0, v23
	v_rcp_f32_e32 v23, v20
	s_nop 0
	v_mul_f32_e32 v20, 2.0, v23
	v_pk_add_f32 v[20:21], v[20:21], 1.0 op_sel_hi:[1,0] neg_lo:[1,0] neg_hi:[1,0]
	v_mov_b32_e32 v26, v25
	v_pk_mul_f32 v[22:23], v[26:27], 0.5 op_sel_hi:[1,0]
	v_pk_add_f32 v[20:21], v[20:21], 1.0 op_sel_hi:[1,0]
	s_nop 0
	v_pk_mul_f32 v[20:21], v[22:23], v[20:21]
	v_cvt_pk_bf16_f32 v19, v19, v21
	v_cvt_pk_bf16_f32 v18, v18, v20
	global_store_dwordx2 v[16:17], v[18:19], off
	v_mul_f32_e32 v19, 0x3d372713, v89
	v_mul_f32_e32 v19, v89, v19
	v_fma_f32 v19, v89, v19, v89
	v_mul_f32_e32 v19, 0x3f4c422a, v19
	v_add_f32_e32 v19, v19, v19
	v_mul_f32_e32 v19, 0x3fb8aa3b, v19
	v_mul_f32_e32 v18, 0x3d372713, v90
	v_exp_f32_e32 v20, v19
	v_mul_f32_e32 v19, 0x3d372713, v88
	v_mul_f32_e32 v18, v90, v18
	v_mul_f32_e32 v19, v88, v19
	v_fma_f32 v18, v90, v18, v90
	v_fma_f32 v19, v88, v19, v88
	v_mul_f32_e32 v18, 0x3f4c422a, v18
	v_mul_f32_e32 v19, 0x3f4c422a, v19
	v_add_f32_e32 v18, v18, v18
	v_add_f32_e32 v19, v19, v19
	v_mul_f32_e32 v18, 0x3fb8aa3b, v18
	v_mul_f32_e32 v19, 0x3fb8aa3b, v19
	v_exp_f32_e32 v18, v18
	v_exp_f32_e32 v19, v19
	v_mul_f32_e32 v21, 0x3d372713, v87
	v_mul_f32_e32 v21, v87, v21
	v_fma_f32 v21, v87, v21, v87
	v_pk_add_f32 v[18:19], v[18:19], 1.0 op_sel_hi:[1,0]
	v_mul_f32_e32 v21, 0x3f4c422a, v21
	v_rcp_f32_e32 v23, v19
	v_add_f32_e32 v21, v21, v21
	v_mul_f32_e32 v21, 0x3fb8aa3b, v21
	v_exp_f32_e32 v21, v21
	v_mul_f32_e32 v19, 2.0, v23
	v_rcp_f32_e32 v23, v18
	v_pk_add_f32 v[20:21], v[20:21], 1.0 op_sel_hi:[1,0]
	v_mul_f32_e32 v18, 2.0, v23
	v_pk_add_f32 v[18:19], v[18:19], 1.0 op_sel_hi:[1,0] neg_lo:[1,0] neg_hi:[1,0]
	v_mov_b32_e32 v22, v28
	v_mov_b32_e32 v23, v30
	v_pk_mul_f32 v[22:23], v[22:23], 0.5 op_sel_hi:[1,0]
	v_pk_add_f32 v[18:19], v[18:19], 1.0 op_sel_hi:[1,0]
	v_mov_b32_e32 v30, v29
	v_pk_mul_f32 v[18:19], v[22:23], v[18:19]
	v_rcp_f32_e32 v23, v21
	s_nop 0
	v_mul_f32_e32 v21, 2.0, v23
	v_rcp_f32_e32 v23, v20
	s_nop 0
	v_mul_f32_e32 v20, 2.0, v23
	v_pk_add_f32 v[20:21], v[20:21], 1.0 op_sel_hi:[1,0] neg_lo:[1,0] neg_hi:[1,0]
	v_pk_mul_f32 v[22:23], v[30:31], 0.5 op_sel_hi:[1,0]
	v_pk_add_f32 v[20:21], v[20:21], 1.0 op_sel_hi:[1,0]
	s_nop 0
	v_pk_mul_f32 v[20:21], v[22:23], v[20:21]
	v_cvt_pk_bf16_f32 v19, v19, v21
	v_cvt_pk_bf16_f32 v18, v18, v20
	global_store_dwordx2 v[16:17], v[18:19], off offset:16
.LBB0_261:
	s_or_b64 exec, exec, s[0:1]
	s_and_saveexec_b64 s[0:1], s[4:5]
	s_cbranch_execz .LBB0_248
	v_mul_f32_e32 v21, 0x3d372713, v85
	v_mul_f32_e32 v21, v85, v21
	v_fma_f32 v21, v85, v21, v85
	v_mul_f32_e32 v21, 0x3f4c422a, v21
	v_add_f32_e32 v21, v21, v21
	v_mul_f32_e32 v21, 0x3fb8aa3b, v21
	v_mul_f32_e32 v20, 0x3d372713, v86
	v_exp_f32_e32 v22, v21
	v_mul_f32_e32 v21, 0x3d372713, v84
	v_mul_f32_e32 v20, v86, v20
	v_mul_f32_e32 v21, v84, v21
	v_fma_f32 v20, v86, v20, v86
	v_fma_f32 v21, v84, v21, v84
	v_mul_f32_e32 v20, 0x3f4c422a, v20
	v_mul_f32_e32 v21, 0x3f4c422a, v21
	v_add_f32_e32 v20, v20, v20
	v_add_f32_e32 v21, v21, v21
	v_mul_f32_e32 v20, 0x3fb8aa3b, v20
	v_mul_f32_e32 v21, 0x3fb8aa3b, v21
	v_exp_f32_e32 v20, v20
	v_exp_f32_e32 v21, v21
	v_mul_f32_e32 v23, 0x3d372713, v83
	v_mul_f32_e32 v23, v83, v23
	v_fma_f32 v23, v83, v23, v83
	v_pk_add_f32 v[20:21], v[20:21], 1.0 op_sel_hi:[1,0]
	v_mul_f32_e32 v23, 0x3f4c422a, v23
	v_rcp_f32_e32 v25, v21
	v_add_f32_e32 v23, v23, v23
	v_mul_f32_e32 v23, 0x3fb8aa3b, v23
	v_exp_f32_e32 v23, v23
	v_mul_f32_e32 v21, 2.0, v25
	v_rcp_f32_e32 v25, v20
	v_pk_add_f32 v[22:23], v[22:23], 1.0 op_sel_hi:[1,0]
	v_mad_i64_i32 v[16:17], s[2:3], s7, v215, v[48:49]
	v_mul_f32_e32 v20, 2.0, v25
	v_mov_b32_e32 v24, v0
	v_mov_b32_e32 v25, v2
	v_rcp_f32_e32 v2, v23
	v_pk_add_f32 v[20:21], v[20:21], 1.0 op_sel_hi:[1,0] neg_lo:[1,0] neg_hi:[1,0]
	v_pk_mul_f32 v[24:25], v[24:25], 0.5 op_sel_hi:[1,0]
	v_pk_add_f32 v[20:21], v[20:21], 1.0 op_sel_hi:[1,0]
	v_or_b32_e32 v18, v16, v34
	v_pk_mul_f32 v[20:21], v[24:25], v[20:21]
	v_mul_f32_e32 v23, 2.0, v2
	v_rcp_f32_e32 v2, v22
	v_mov_b32_e32 v19, v17
	v_readlane_b32 s4, v254, 3
	v_lshlrev_b64 v[18:19], 5, v[18:19]
	v_mul_f32_e32 v22, 2.0, v2
	v_pk_add_f32 v[22:23], v[22:23], 1.0 op_sel_hi:[1,0] neg_lo:[1,0] neg_hi:[1,0]
	v_mov_b32_e32 v2, v1
	v_pk_mul_f32 v[0:1], v[2:3], 0.5 op_sel_hi:[1,0]
	v_pk_add_f32 v[2:3], v[22:23], 1.0 op_sel_hi:[1,0]
	v_readlane_b32 s5, v254, 4
	v_pk_mul_f32 v[0:1], v[0:1], v[2:3]
	v_cvt_pk_bf16_f32 v1, v21, v1
	v_cvt_pk_bf16_f32 v0, v20, v0
	v_mul_f32_e32 v3, 0x3d372713, v80
	v_mul_f32_e32 v3, v80, v3
	v_fma_f32 v3, v80, v3, v80
	v_mul_f32_e32 v3, 0x3f4c422a, v3
	v_lshl_add_u64 v[18:19], s[4:5], 0, v[18:19]
	v_add_f32_e32 v3, v3, v3
	v_lshl_add_u64 v[18:19], v[18:19], 0, v[192:193]
	v_mul_f32_e32 v3, 0x3fb8aa3b, v3
	global_store_dwordx2 v[18:19], v[0:1], off
	v_mul_f32_e32 v2, 0x3d372713, v81
	v_exp_f32_e32 v18, v3
	v_mul_f32_e32 v3, 0x3d372713, v79
	v_mul_f32_e32 v2, v81, v2
	v_mul_f32_e32 v3, v79, v3
	v_fma_f32 v2, v81, v2, v81
	v_fma_f32 v3, v79, v3, v79
	v_or_b32_e32 v22, v82, v16
	v_mul_f32_e32 v2, 0x3f4c422a, v2
	v_mul_f32_e32 v3, 0x3f4c422a, v3
	v_or_b32_e32 v16, 2, v22
	v_add_f32_e32 v2, v2, v2
	v_add_f32_e32 v3, v3, v3
	v_lshlrev_b64 v[0:1], 5, v[16:17]
	v_mul_f32_e32 v2, 0x3fb8aa3b, v2
	v_mul_f32_e32 v3, 0x3fb8aa3b, v3
	v_mul_f32_e32 v16, 0x3d372713, v78
	v_exp_f32_e32 v2, v2
	v_exp_f32_e32 v3, v3
	v_mul_f32_e32 v16, v78, v16
	v_fma_f32 v16, v78, v16, v78
	v_mul_f32_e32 v16, 0x3f4c422a, v16
	v_add_f32_e32 v16, v16, v16
	v_mul_f32_e32 v16, 0x3fb8aa3b, v16
	v_pk_add_f32 v[2:3], v[2:3], 1.0 op_sel_hi:[1,0]
	v_exp_f32_e32 v19, v16
	v_rcp_f32_e32 v20, v3
	v_pk_add_f32 v[18:19], v[18:19], 1.0 op_sel_hi:[1,0]
	v_lshl_add_u64 v[0:1], s[4:5], 0, v[0:1]
	v_lshl_add_u64 v[0:1], v[0:1], 0, v[192:193]
	v_mul_f32_e32 v3, 2.0, v20
	v_rcp_f32_e32 v20, v2
	s_nop 0
	v_mul_f32_e32 v16, 2.0, v20
	v_mov_b32_e32 v20, v4
	v_mov_b32_e32 v21, v6
	v_rcp_f32_e32 v6, v19
	v_mov_b32_e32 v2, v16
	v_pk_add_f32 v[2:3], v[2:3], 1.0 op_sel_hi:[1,0] neg_lo:[1,0] neg_hi:[1,0]
	v_pk_mul_f32 v[20:21], v[20:21], 0.5 op_sel_hi:[1,0]
	v_pk_add_f32 v[2:3], v[2:3], 1.0 op_sel_hi:[1,0]
	v_pk_mul_f32 v[2:3], v[20:21], v[2:3]
	v_mul_f32_e32 v19, 2.0, v6
	v_rcp_f32_e32 v6, v18
	s_nop 0
	v_mul_f32_e32 v18, 2.0, v6
	v_pk_add_f32 v[18:19], v[18:19], 1.0 op_sel_hi:[1,0] neg_lo:[1,0] neg_hi:[1,0]
	v_mov_b32_e32 v6, v5
	v_pk_mul_f32 v[4:5], v[6:7], 0.5 op_sel_hi:[1,0]
	v_pk_add_f32 v[6:7], v[18:19], 1.0 op_sel_hi:[1,0]
	v_or_b32_e32 v16, 3, v22
	v_pk_mul_f32 v[4:5], v[4:5], v[6:7]
	v_cvt_pk_bf16_f32 v3, v3, v5
	v_cvt_pk_bf16_f32 v2, v2, v4
	global_store_dwordx2 v[0:1], v[2:3], off offset:16
	v_mul_f32_e32 v3, 0x3d372713, v76
	v_mul_f32_e32 v3, v76, v3
	v_fma_f32 v3, v76, v3, v76
	v_mul_f32_e32 v3, 0x3f4c422a, v3
	v_add_f32_e32 v3, v3, v3
	v_mul_f32_e32 v3, 0x3fb8aa3b, v3
	v_mul_f32_e32 v2, 0x3d372713, v77
	v_exp_f32_e32 v4, v3
	v_mul_f32_e32 v3, 0x3d372713, v75
	v_mul_f32_e32 v2, v77, v2
	v_mul_f32_e32 v3, v75, v3
	v_fma_f32 v2, v77, v2, v77
	v_fma_f32 v3, v75, v3, v75
	v_mul_f32_e32 v2, 0x3f4c422a, v2
	v_mul_f32_e32 v3, 0x3f4c422a, v3
	v_add_f32_e32 v2, v2, v2
	v_add_f32_e32 v3, v3, v3
	v_mul_f32_e32 v2, 0x3fb8aa3b, v2
	v_mul_f32_e32 v3, 0x3fb8aa3b, v3
	v_exp_f32_e32 v2, v2
	v_exp_f32_e32 v3, v3
	v_lshlrev_b64 v[0:1], 5, v[16:17]
	v_mul_f32_e32 v5, 0x3d372713, v74
	v_mul_f32_e32 v5, v74, v5
	v_pk_add_f32 v[2:3], v[2:3], 1.0 op_sel_hi:[1,0]
	v_fma_f32 v5, v74, v5, v74
	v_rcp_f32_e32 v7, v3
	v_mul_f32_e32 v5, 0x3f4c422a, v5
	v_add_f32_e32 v5, v5, v5
	v_mul_f32_e32 v5, 0x3fb8aa3b, v5
	v_mul_f32_e32 v3, 2.0, v7
	v_rcp_f32_e32 v7, v2
	v_exp_f32_e32 v5, v5
	v_lshl_add_u64 v[0:1], s[4:5], 0, v[0:1]
	v_lshl_add_u64 v[0:1], v[0:1], 0, v[192:193]
	v_mul_f32_e32 v2, 2.0, v7
	v_pk_add_f32 v[2:3], v[2:3], 1.0 op_sel_hi:[1,0] neg_lo:[1,0] neg_hi:[1,0]
	v_mov_b32_e32 v6, v8
	v_mov_b32_e32 v7, v10
	v_pk_mul_f32 v[6:7], v[6:7], 0.5 op_sel_hi:[1,0]
	v_pk_add_f32 v[2:3], v[2:3], 1.0 op_sel_hi:[1,0]
	v_pk_add_f32 v[4:5], v[4:5], 1.0 op_sel_hi:[1,0]
	v_pk_mul_f32 v[2:3], v[6:7], v[2:3]
	v_rcp_f32_e32 v7, v5
	s_nop 0
	v_mul_f32_e32 v5, 2.0, v7
	v_rcp_f32_e32 v7, v4
	s_nop 0
	v_mul_f32_e32 v4, 2.0, v7
	v_pk_add_f32 v[4:5], v[4:5], 1.0 op_sel_hi:[1,0] neg_lo:[1,0] neg_hi:[1,0]
	v_mov_b32_e32 v10, v9
	v_pk_mul_f32 v[6:7], v[10:11], 0.5 op_sel_hi:[1,0]
	v_pk_add_f32 v[4:5], v[4:5], 1.0 op_sel_hi:[1,0]
	s_nop 0
	v_pk_mul_f32 v[4:5], v[6:7], v[4:5]
	v_cvt_pk_bf16_f32 v3, v3, v5
	v_cvt_pk_bf16_f32 v2, v2, v4
	global_store_dwordx2 v[0:1], v[2:3], off
	v_mul_f32_e32 v3, 0x3d372713, v72
	v_mul_f32_e32 v3, v72, v3
	v_fma_f32 v3, v72, v3, v72
	v_mul_f32_e32 v3, 0x3f4c422a, v3
	v_add_f32_e32 v3, v3, v3
	v_mul_f32_e32 v3, 0x3fb8aa3b, v3
	v_mul_f32_e32 v2, 0x3d372713, v73
	v_exp_f32_e32 v4, v3
	v_mul_f32_e32 v3, 0x3d372713, v71
	v_mul_f32_e32 v2, v73, v2
	v_mul_f32_e32 v3, v71, v3
	v_fma_f32 v2, v73, v2, v73
	v_fma_f32 v3, v71, v3, v71
	v_mul_f32_e32 v2, 0x3f4c422a, v2
	v_mul_f32_e32 v3, 0x3f4c422a, v3
	v_add_f32_e32 v2, v2, v2
	v_add_f32_e32 v3, v3, v3
	v_mul_f32_e32 v2, 0x3fb8aa3b, v2
	v_mul_f32_e32 v3, 0x3fb8aa3b, v3
	v_exp_f32_e32 v2, v2
	v_exp_f32_e32 v3, v3
	v_mul_f32_e32 v5, 0x3d372713, v70
	v_mul_f32_e32 v5, v70, v5
	v_fma_f32 v5, v70, v5, v70
	v_pk_add_f32 v[2:3], v[2:3], 1.0 op_sel_hi:[1,0]
	v_mul_f32_e32 v5, 0x3f4c422a, v5
	v_rcp_f32_e32 v7, v3
	v_add_f32_e32 v5, v5, v5
	v_mul_f32_e32 v5, 0x3fb8aa3b, v5
	v_exp_f32_e32 v5, v5
	v_mul_f32_e32 v3, 2.0, v7
	v_rcp_f32_e32 v7, v2
	v_pk_add_f32 v[4:5], v[4:5], 1.0 op_sel_hi:[1,0]
	v_mul_f32_e32 v2, 2.0, v7
	v_pk_add_f32 v[2:3], v[2:3], 1.0 op_sel_hi:[1,0] neg_lo:[1,0] neg_hi:[1,0]
	v_mov_b32_e32 v6, v12
	v_mov_b32_e32 v7, v14
	v_pk_mul_f32 v[6:7], v[6:7], 0.5 op_sel_hi:[1,0]
	v_pk_add_f32 v[2:3], v[2:3], 1.0 op_sel_hi:[1,0]
	v_mov_b32_e32 v14, v13
	v_pk_mul_f32 v[2:3], v[6:7], v[2:3]
	v_rcp_f32_e32 v7, v5
	s_nop 0
	v_mul_f32_e32 v5, 2.0, v7
	v_rcp_f32_e32 v7, v4
	s_nop 0
	v_mul_f32_e32 v4, 2.0, v7
	v_pk_add_f32 v[4:5], v[4:5], 1.0 op_sel_hi:[1,0] neg_lo:[1,0] neg_hi:[1,0]
	v_pk_mul_f32 v[6:7], v[14:15], 0.5 op_sel_hi:[1,0]
	v_pk_add_f32 v[4:5], v[4:5], 1.0 op_sel_hi:[1,0]
	s_nop 0
	v_pk_mul_f32 v[4:5], v[6:7], v[4:5]
	v_cvt_pk_bf16_f32 v3, v3, v5
	v_cvt_pk_bf16_f32 v2, v2, v4
	global_store_dwordx2 v[0:1], v[2:3], off offset:16
	s_branch .LBB0_248

.LBB0_363:
	v_cmp_lt_i32_e32 vcc, v212, v210
	s_waitcnt vmcnt(21)
	v_accvgpr_read_b32 v31, a3
	v_accvgpr_read_b32 v30, a2
	v_cndmask_b32_e32 v32, v209, v212, vcc
	v_lshlrev_b32_e32 v33, 2, v32
	ds_bpermute_b32 v32, v33, v88
	v_cmp_lt_i32_e32 vcc, v211, v210
	v_accvgpr_read_b32 v28, a0
	v_accvgpr_read_b32 v29, a1
	v_cndmask_b32_e32 v34, v209, v211, vcc
	s_waitcnt lgkmcnt(0)
	v_add_f32_e32 v32, v88, v32
	s_waitcnt vmcnt(11)
	v_lshlrev_b32_e32 v38, 2, v34
	ds_bpermute_b32 v34, v38, v32
	v_ashrrev_i32_e32 v83, 31, v82
	v_mov_b32_e32 v85, v193
	v_accvgpr_read_b32 v27, a7
	v_accvgpr_read_b32 v26, a6
	s_waitcnt lgkmcnt(0)
	v_add_f32_e32 v32, v32, v34
	v_rcp_f32_e32 v35, v32
	s_mov_b32 s0, 0x5780000
	v_accvgpr_read_b32 v24, a4
	v_accvgpr_read_b32 v25, a5
	v_mul_f32_e32 v32, 1.0, v35
	v_mov_b32_e32 v36, v28
	v_mov_b32_e32 v37, v30
	v_pk_mul_f32 v[36:37], v[36:37], v[32:33] op_sel_hi:[1,0]
	v_mov_b32_e32 v30, v29
	v_pk_mul_f32 v[28:29], v[30:31], v[32:33] op_sel_hi:[1,0]
	v_cvt_pk_bf16_f32 v28, v36, v28
	v_cvt_pk_bf16_f32 v29, v37, v29
	v_lshlrev_b64 v[34:35], 11, v[82:83]
	v_lshl_add_u64 v[34:35], s[90:91], 0, v[34:35]
	v_lshl_add_u64 v[30:31], s[2:3], 1, v[34:35]
	v_lshl_add_u64 v[30:31], v[30:31], 0, v[84:85]
	v_add_co_u32_e32 v34, vcc, s0, v30
	v_accvgpr_read_b32 v23, a11
	s_nop 0
	v_addc_co_u32_e32 v35, vcc, 0, v31, vcc
	global_store_dwordx2 v[34:35], v[28:29], off offset:1280
	v_mov_b32_e32 v28, v24
	v_mov_b32_e32 v29, v26
	v_pk_mul_f32 v[28:29], v[28:29], v[32:33] op_sel_hi:[1,0]
	v_mov_b32_e32 v26, v25
	v_pk_mul_f32 v[24:25], v[26:27], v[32:33] op_sel_hi:[1,0]
	v_cvt_pk_bf16_f32 v24, v28, v24
	v_cvt_pk_bf16_f32 v25, v29, v25
	v_accvgpr_read_b32 v22, a10
	v_accvgpr_read_b32 v20, a8
	v_accvgpr_read_b32 v21, a9
	global_store_dwordx2 v[34:35], v[24:25], off offset:1312
	v_mov_b32_e32 v24, v20
	v_mov_b32_e32 v25, v22
	v_pk_mul_f32 v[24:25], v[24:25], v[32:33] op_sel_hi:[1,0]
	v_mov_b32_e32 v22, v21
	v_pk_mul_f32 v[20:21], v[22:23], v[32:33] op_sel_hi:[1,0]
	v_cvt_pk_bf16_f32 v20, v24, v20
	v_cvt_pk_bf16_f32 v21, v25, v21
	v_accvgpr_read_b32 v19, a15
	v_accvgpr_read_b32 v18, a14
	v_accvgpr_read_b32 v16, a12
	v_accvgpr_read_b32 v17, a13
	global_store_dwordx2 v[34:35], v[20:21], off offset:1344
	v_mov_b32_e32 v20, v16
	v_mov_b32_e32 v21, v18
	v_pk_mul_f32 v[20:21], v[20:21], v[32:33] op_sel_hi:[1,0]
	v_mov_b32_e32 v18, v17
	v_pk_mul_f32 v[16:17], v[18:19], v[32:33] op_sel_hi:[1,0]
	v_cvt_pk_bf16_f32 v16, v20, v16
	v_cvt_pk_bf16_f32 v17, v21, v17
	global_store_dwordx2 v[34:35], v[16:17], off offset:1376
	ds_bpermute_b32 v16, v33, v89
	s_waitcnt vmcnt(4)
	v_accvgpr_read_b32 v12, a16
	v_accvgpr_read_b32 v13, a17
	v_accvgpr_read_b32 v14, a18
	v_accvgpr_read_b32 v15, a19
	s_waitcnt lgkmcnt(0)
	v_add_f32_e32 v16, v89, v16
	ds_bpermute_b32 v17, v38, v16
	v_accvgpr_read_b32 v8, a20
	v_accvgpr_read_b32 v10, a22
	v_accvgpr_read_b32 v9, a21
	v_accvgpr_read_b32 v11, a23
	s_waitcnt lgkmcnt(0)
	v_add_f32_e32 v16, v16, v17
	v_div_scale_f32 v17, s[0:1], v16, v16, 1.0
	v_rcp_f32_e32 v18, v17
	s_mov_b32 s0, 0x57a0000
	v_accvgpr_read_b32 v4, a24
	v_accvgpr_read_b32 v6, a26
	v_fma_f32 v19, -v17, v18, 1.0
	v_fmac_f32_e32 v18, v19, v18
	v_div_scale_f32 v19, vcc, 1.0, v16, 1.0
	v_mul_f32_e32 v20, v19, v18
	v_fma_f32 v21, -v17, v20, v19
	v_fmac_f32_e32 v20, v21, v18
	v_fma_f32 v17, -v17, v20, v19
	v_div_fmas_f32 v17, v17, v18, v20
	v_div_fixup_f32 v16, v17, v16, 1.0
	v_mov_b32_e32 v18, v12
	v_mov_b32_e32 v19, v14
	v_mov_b32_e32 v14, v13
	v_pk_mul_f32 v[18:19], v[18:19], v[16:17] op_sel_hi:[1,0]
	v_pk_mul_f32 v[12:13], v[14:15], v[16:17] op_sel_hi:[1,0]
	v_and_b32_sdwa v17, v13, v218 dst_sel:DWORD dst_unused:UNUSED_PAD src0_sel:WORD_1 src1_sel:DWORD
	v_and_b32_sdwa v14, v19, v218 dst_sel:DWORD dst_unused:UNUSED_PAD src0_sel:WORD_1 src1_sel:DWORD
	v_cvt_pk_bf16_f32 v12, v18, v12
	v_add3_u32 v13, v13, v17, s80
	v_add3_u32 v14, v19, v14, s80
	v_and_b32_e32 v13, 0xffff0000, v13
	v_or_b32_sdwa v13, v13, v14 dst_sel:DWORD dst_unused:UNUSED_PAD src0_sel:DWORD src1_sel:WORD_1
	v_add_co_u32_e32 v14, vcc, s0, v30
	s_nop 0
	s_nop 0
	v_addc_co_u32_e32 v15, vcc, 0, v31, vcc
	global_store_dwordx2 v[14:15], v[12:13], off offset:1280
	v_mov_b32_e32 v12, v8
	v_mov_b32_e32 v13, v10
	v_pk_mul_f32 v[12:13], v[12:13], v[16:17] op_sel_hi:[1,0]
	v_mov_b32_e32 v10, v9
	v_pk_mul_f32 v[8:9], v[10:11], v[16:17] op_sel_hi:[1,0]
	v_cvt_pk_bf16_f32 v8, v12, v8
	v_cvt_pk_bf16_f32 v9, v13, v9
	v_accvgpr_read_b32 v5, a25
	global_store_dwordx2 v[14:15], v[8:9], off offset:1312
	v_mov_b32_e32 v8, v4
	v_mov_b32_e32 v9, v6
	v_accvgpr_read_b32 v7, a27
	v_pk_mul_f32 v[8:9], v[8:9], v[16:17] op_sel_hi:[1,0]
	v_mov_b32_e32 v6, v5
	v_pk_mul_f32 v[4:5], v[6:7], v[16:17] op_sel_hi:[1,0]
	v_cvt_pk_bf16_f32 v4, v8, v4
	v_cvt_pk_bf16_f32 v5, v9, v5
	v_accvgpr_read_b32 v0, a28
	v_accvgpr_read_b32 v2, a30
	v_accvgpr_read_b32 v1, a29
	global_store_dwordx2 v[14:15], v[4:5], off offset:1344
	v_mov_b32_e32 v4, v0
	v_mov_b32_e32 v5, v2
	v_accvgpr_read_b32 v3, a31
	v_pk_mul_f32 v[4:5], v[4:5], v[16:17] op_sel_hi:[1,0]
	v_mov_b32_e32 v2, v1
	v_pk_mul_f32 v[0:1], v[2:3], v[16:17] op_sel_hi:[1,0]
	v_cvt_pk_bf16_f32 v0, v4, v0
	v_cvt_pk_bf16_f32 v1, v5, v1
	global_store_dwordx2 v[14:15], v[0:1], off offset:1376

.LBB0_391:
	v_add_co_u32_e32 v8, vcc, s73, v34
	v_lshl_add_u64 v[16:17], s[90:91], 0, v[32:33]
	s_nop 0
	v_addc_co_u32_e32 v9, vcc, 0, v35, vcc
	global_load_dwordx4 v[36:39], v[8:9], off offset:64
	global_load_dwordx4 v[40:43], v[8:9], off
	global_load_dwordx4 v[102:105], v[34:35], off offset:64
	global_load_dwordx4 v[106:109], v[34:35], off
	s_mov_b32 s3, 0xabb0000
	v_add_co_u32_e32 v12, vcc, s3, v16
	s_mov_b32 s3, 0xabb3000
	s_nop 0
	v_addc_co_u32_e32 v13, vcc, 0, v17, vcc
	v_add_co_u32_e32 v20, vcc, s3, v16
	v_lshl_add_u64 v[34:35], s[90:91], 0, v[30:31]
	s_nop 0
	v_addc_co_u32_e32 v21, vcc, 0, v17, vcc
	s_mov_b32 s3, 0xb810000
	v_accvgpr_read_b32 v91, a3
	v_accvgpr_read_b32 v90, a2
	v_accvgpr_read_b32 v111, a1
	v_accvgpr_read_b32 v110, a0
	v_add_co_u32_e32 v50, vcc, s3, v34
	v_accvgpr_read_b32 v113, a7
	v_accvgpr_read_b32 v112, a6
	v_accvgpr_read_b32 v115, a5
	v_accvgpr_read_b32 v114, a4
	v_addc_co_u32_e32 v51, vcc, 0, v35, vcc
	s_mov_b32 s3, 0xb812000
	global_load_dwordx4 v[8:11], v[12:13], off
	s_nop 0
	global_load_dwordx4 v[12:15], v[12:13], off offset:64
	s_nop 0
	global_load_dwordx4 v[16:19], v[20:21], off
	s_nop 0
	global_load_dwordx4 v[20:23], v[20:21], off offset:64
	s_nop 0
	global_load_dwordx2 v[82:83], v[50:51], off offset:64
	global_load_dwordx2 v[84:85], v[50:51], off offset:96
	v_add_co_u32_e32 v50, vcc, s3, v34
	s_mov_b32 s3, 0xb814000
	s_nop 0
	v_addc_co_u32_e32 v51, vcc, 0, v35, vcc
	global_load_dwordx2 v[86:87], v[50:51], off offset:64
	global_load_dwordx2 v[88:89], v[50:51], off offset:96
	v_add_co_u32_e32 v50, vcc, s3, v34
	s_mov_b32 s3, 0xb816000
	s_nop 0
	v_addc_co_u32_e32 v51, vcc, 0, v35, vcc
	v_add_co_u32_e32 v34, vcc, s3, v34
	global_load_dwordx2 v[94:95], v[50:51], off offset:64
	global_load_dwordx2 v[96:97], v[50:51], off offset:96
	v_addc_co_u32_e32 v35, vcc, 0, v35, vcc
	global_load_dwordx2 v[98:99], v[34:35], off offset:64
	global_load_dwordx2 v[100:101], v[34:35], off offset:96
	v_accvgpr_read_b32 v117, a11
	v_accvgpr_read_b32 v116, a10
	v_accvgpr_read_b32 v119, a9
	v_accvgpr_read_b32 v118, a8
	v_accvgpr_read_b32 v121, a15
	v_accvgpr_read_b32 v120, a14
	v_accvgpr_read_b32 v123, a13
	v_accvgpr_read_b32 v122, a12
	s_add_i32 s3, s2, 4
	s_min_u32 s3, s3, 7
	s_lshl_b32 s78, s3, 6
	s_mov_b64 s[4:5], 0x80
	s_add_i32 s2, s2, 2
	v_lshl_add_u64 v[30:31], v[30:31], 0, s[4:5]
	s_mov_b64 s[4:5], 0xc000
	v_lshl_add_u64 v[32:33], v[32:33], 0, s[4:5]
	s_cmp_lt_u32 s2, 6
	s_waitcnt vmcnt(14)
	v_mfma_f32_16x16x32_bf16 a[4:7], v[40:43], v[0:3], 0
	s_waitcnt vmcnt(12)
	v_mfma_f32_16x16x32_bf16 a[0:3], v[106:109], v[0:3], 0
	v_mfma_f32_16x16x32_bf16 a[0:3], v[102:105], v[4:7], a[0:3]
	v_mfma_f32_16x16x32_bf16 a[4:7], v[36:39], v[4:7], a[4:7]
	s_waitcnt vmcnt(9)
	v_mfma_f32_16x16x32_bf16 a[12:15], v[16:19], v[0:3], 0
	s_nop 4
	s_nop 3
	v_accvgpr_read_b32 v34, a0
	v_accvgpr_read_b32 v35, a1
	v_accvgpr_read_b32 v36, a2
	v_accvgpr_read_b32 v37, a3
	v_max_f32_e32 v38, v35, v35
	v_max_f32_e32 v39, v34, v34
	v_accvgpr_read_b32 v42, a6
	v_accvgpr_read_b32 v43, a7
	v_max_f32_e32 v38, v39, v38
	v_max_f32_e32 v39, v37, v37
	v_max_f32_e32 v40, v36, v36
	v_max_f32_e32 v49, v43, v43
	v_max_f32_e32 v50, v42, v42
	v_max_f32_e32 v39, v40, v39
	v_accvgpr_read_b32 v40, a4
	v_accvgpr_read_b32 v41, a5
	v_max_f32_e32 v49, v50, v49
	v_max3_f32 v49, v40, v41, v49
	v_max3_f32 v38, v38, v39, v49
	ds_bpermute_b32 v39, v46, v38
	s_waitcnt vmcnt(8)
	v_mfma_f32_16x16x32_bf16 a[12:15], v[20:23], v[4:7], a[12:15]
	s_waitcnt lgkmcnt(0)
	v_max_f32_e32 v39, v39, v39
	v_max_f32_e32 v38, v38, v39
	ds_bpermute_b32 v39, v45, v38
	s_waitcnt lgkmcnt(0)
	v_max3_f32 v50, v48, v38, v39
	v_sub_f32_e32 v35, v35, v50
	v_mul_f32_e32 v35, 0x3fb8aa3b, v35
	v_exp_f32_e32 v51, v35
	v_sub_f32_e32 v35, v36, v50
	v_mul_f32_e32 v35, 0x3fb8aa3b, v35
	v_exp_f32_e32 v124, v35
	v_sub_f32_e32 v35, v37, v50
	v_sub_f32_e32 v34, v34, v50
	v_mul_f32_e32 v35, 0x3fb8aa3b, v35
	v_mul_f32_e32 v34, 0x3fb8aa3b, v34
	v_exp_f32_e32 v125, v35
	v_sub_f32_e32 v35, v40, v50
	v_sub_f32_e32 v38, v48, v50
	v_exp_f32_e32 v48, v34
	v_mul_f32_e32 v35, 0x3fb8aa3b, v35
	v_exp_f32_e32 v126, v35
	v_sub_f32_e32 v35, v41, v50
	v_mul_f32_e32 v35, 0x3fb8aa3b, v35
	v_exp_f32_e32 v127, v35
	v_sub_f32_e32 v35, v42, v50
	v_add_f32_e32 v34, 0, v48
	v_mul_f32_e32 v35, 0x3fb8aa3b, v35
	v_add_f32_e32 v34, v51, v34
	v_exp_f32_e32 v128, v35
	v_sub_f32_e32 v35, v43, v50
	v_add_f32_e32 v34, v124, v34
	v_mul_f32_e32 v35, 0x3fb8aa3b, v35
	v_mul_f32_e32 v38, 0x3fb8aa3b, v38
	v_add_f32_e32 v34, v125, v34
	v_exp_f32_e32 v43, v35
	v_add_f32_e32 v34, v126, v34
	v_exp_f32_e32 v42, v38
	v_add_f32_e32 v34, v127, v34
	v_add_f32_e32 v34, v128, v34
	v_add_f32_e32 v49, v43, v34
	v_fmac_f32_e32 v49, v47, v42
	v_pk_mul_f32 v[36:37], v[90:91], v[42:43] op_sel_hi:[1,0]
	v_pk_mul_f32 v[34:35], v[110:111], v[42:43] op_sel_hi:[1,0]
	v_pk_mul_f32 v[40:41], v[112:113], v[42:43] op_sel_hi:[1,0]
	v_pk_mul_f32 v[38:39], v[114:115], v[42:43] op_sel_hi:[1,0]
	v_pk_mul_f32 v[104:105], v[116:117], v[42:43] op_sel_hi:[1,0]
	v_pk_mul_f32 v[102:103], v[118:119], v[42:43] op_sel_hi:[1,0]
	v_pk_mul_f32 v[108:109], v[120:121], v[42:43] op_sel_hi:[1,0]
	v_pk_mul_f32 v[106:107], v[122:123], v[42:43] op_sel_hi:[1,0]
	v_cvt_pk_bf16_f32 v111, v124, v125
	v_bfe_u32 v112, v51, 16, 1
	v_bfe_u32 v113, v48, 16, 1
	v_add3_u32 v48, v48, v113, s80
	v_add3_u32 v51, v51, v112, s80
	v_accvgpr_write_b32 a0, v34
	v_cvt_pk_bf16_f32 v113, v128, v43
	v_cvt_pk_bf16_f32 v112, v126, v127
	v_perm_b32 v110, v51, v48, s6
	v_accvgpr_write_b32 a1, v35
	v_accvgpr_write_b32 a2, v36
	v_accvgpr_write_b32 a3, v37
	v_accvgpr_read_b32 v16, a14
	v_accvgpr_read_b32 v17, a15
	v_mfma_f32_16x16x32_bf16 a[0:3], v[52:55], v[110:113], a[0:3]
	v_max_f32_e32 v18, v17, v17
	v_max_f32_e32 v19, v16, v16
	v_max_f32_e32 v18, v19, v18
	v_lshl_or_b32 v34, s3, 5, v44
	v_mul_u32_u24_e32 v192, 0x300, v34
	v_lshl_add_u64 v[34:35], v[28:29], 0, v[192:193]
	s_nop 1
	s_nop 3
	v_accvgpr_read_b32 v37, a3
	v_accvgpr_read_b32 v36, a2
	v_accvgpr_write_b32 a2, v38
	v_accvgpr_write_b32 a3, v39
	v_accvgpr_write_b32 a4, v40
	v_accvgpr_write_b32 a5, v41
	s_nop 1
	v_mfma_f32_16x16x32_bf16 a[2:5], v[56:59], v[110:113], a[2:5]
	s_nop 7
	s_nop 3
	v_accvgpr_read_b32 v39, a5
	v_accvgpr_read_b32 v38, a4
	v_accvgpr_write_b32 a4, v102
	v_accvgpr_write_b32 a5, v103
	v_accvgpr_write_b32 a6, v104
	v_accvgpr_write_b32 a7, v105
	s_nop 1
	v_mfma_f32_16x16x32_bf16 a[4:7], v[60:63], v[110:113], a[4:7]
	s_nop 7
	s_nop 3
	v_accvgpr_read_b32 v41, a7
	v_accvgpr_read_b32 v40, a6
	v_accvgpr_write_b32 a6, v106
	v_accvgpr_write_b32 a7, v107
	v_accvgpr_write_b32 a8, v108
	v_accvgpr_write_b32 a9, v109
	s_nop 1
	v_mfma_f32_16x16x32_bf16 a[6:9], v[64:67], v[110:113], a[6:9]
	v_lshl_add_u64 v[64:65], v[26:27], 0, s[78:79]
	v_add_co_u32_e32 v58, vcc, s7, v64
	global_load_dwordx2 v[52:53], v[64:65], off
	global_load_dwordx2 v[54:55], v[64:65], off offset:32
	v_addc_co_u32_e32 v59, vcc, 0, v65, vcc
	v_add_co_u32_e32 v62, vcc, s8, v64
	global_load_dwordx2 v[56:57], v[58:59], off
	s_nop 0
	global_load_dwordx2 v[58:59], v[58:59], off offset:32
	v_addc_co_u32_e32 v63, vcc, 0, v65, vcc
	v_add_co_u32_e32 v66, vcc, s82, v64
	global_load_dwordx2 v[60:61], v[62:63], off
	s_nop 0
	global_load_dwordx2 v[62:63], v[62:63], off offset:32
	v_addc_co_u32_e32 v67, vcc, 0, v65, vcc
	global_load_dwordx2 v[64:65], v[66:67], off
	s_nop 0
	global_load_dwordx2 v[66:67], v[66:67], off offset:32
	v_accvgpr_read_b32 v43, a9
	v_accvgpr_read_b32 v42, a8
	v_mfma_f32_16x16x32_bf16 a[8:11], v[8:11], v[0:3], 0
	v_mfma_f32_16x16x32_bf16 a[8:11], v[12:15], v[4:7], a[8:11]
	v_accvgpr_read_b32 v15, a13
	s_nop 6
	s_nop 3
	v_accvgpr_read_b32 v8, a8
	v_accvgpr_read_b32 v9, a9
	v_accvgpr_read_b32 v10, a10
	v_accvgpr_read_b32 v11, a11
	v_max_f32_e32 v12, v9, v9
	v_max_f32_e32 v13, v8, v8
	v_max_f32_e32 v12, v13, v12
	v_max_f32_e32 v13, v11, v11
	v_max_f32_e32 v14, v10, v10
	v_max_f32_e32 v13, v14, v13
	v_accvgpr_read_b32 v14, a12
	v_max3_f32 v18, v14, v15, v18
	v_max3_f32 v12, v12, v13, v18
	ds_bpermute_b32 v13, v46, v12
	s_waitcnt lgkmcnt(0)
	v_max_f32_e32 v13, v13, v13
	v_max_f32_e32 v12, v12, v13
	ds_bpermute_b32 v13, v45, v12
	s_waitcnt lgkmcnt(0)
	v_max3_f32 v48, v50, v12, v13
	v_sub_f32_e32 v9, v9, v48
	v_mul_f32_e32 v9, 0x3fb8aa3b, v9
	v_exp_f32_e32 v51, v9
	v_sub_f32_e32 v9, v10, v48
	v_mul_f32_e32 v9, 0x3fb8aa3b, v9
	v_exp_f32_e32 v90, v9
	v_sub_f32_e32 v9, v11, v48
	v_sub_f32_e32 v8, v8, v48
	v_mul_f32_e32 v9, 0x3fb8aa3b, v9
	v_mul_f32_e32 v8, 0x3fb8aa3b, v8
	v_exp_f32_e32 v91, v9
	v_sub_f32_e32 v9, v14, v48
	v_sub_f32_e32 v12, v50, v48
	v_exp_f32_e32 v50, v8
	v_mul_f32_e32 v9, 0x3fb8aa3b, v9
	v_exp_f32_e32 v102, v9
	v_sub_f32_e32 v9, v15, v48
	v_mul_f32_e32 v9, 0x3fb8aa3b, v9
	v_exp_f32_e32 v103, v9
	v_sub_f32_e32 v9, v16, v48
	v_add_f32_e32 v8, 0, v50
	v_mul_f32_e32 v9, 0x3fb8aa3b, v9
	v_add_f32_e32 v8, v51, v8
	v_exp_f32_e32 v104, v9
	v_sub_f32_e32 v9, v17, v48
	v_mul_f32_e32 v12, 0x3fb8aa3b, v12
	v_add_f32_e32 v8, v90, v8
	v_mul_f32_e32 v9, 0x3fb8aa3b, v9
	v_add_f32_e32 v8, v91, v8
	v_exp_f32_e32 v105, v9
	v_exp_f32_e32 v20, v12
	v_add_f32_e32 v8, v102, v8
	v_add_f32_e32 v8, v103, v8
	v_add_f32_e32 v8, v104, v8
	v_add_f32_e32 v47, v105, v8
	v_pk_mul_f32 v[10:11], v[36:37], v[20:21] op_sel_hi:[1,0]
	v_accvgpr_read_b32 v9, a1
	v_accvgpr_read_b32 v13, a3
	v_accvgpr_read_b32 v17, a5
	v_accvgpr_read_b32 v37, a7
	v_accvgpr_read_b32 v8, a0
	v_accvgpr_read_b32 v12, a2
	v_accvgpr_read_b32 v16, a4
	v_accvgpr_read_b32 v36, a6
	v_fmac_f32_e32 v47, v49, v20
	v_pk_mul_f32 v[8:9], v[8:9], v[20:21] op_sel_hi:[1,0]
	v_pk_mul_f32 v[14:15], v[38:39], v[20:21] op_sel_hi:[1,0]
	v_pk_mul_f32 v[12:13], v[12:13], v[20:21] op_sel_hi:[1,0]
	v_pk_mul_f32 v[18:19], v[40:41], v[20:21] op_sel_hi:[1,0]
	v_pk_mul_f32 v[16:17], v[16:17], v[20:21] op_sel_hi:[1,0]
	v_pk_mul_f32 v[22:23], v[42:43], v[20:21] op_sel_hi:[1,0]
	v_pk_mul_f32 v[20:21], v[36:37], v[20:21] op_sel_hi:[1,0]
	v_cvt_pk_bf16_f32 v38, v102, v103
	v_accvgpr_write_b32 a0, v8
	v_accvgpr_write_b32 a4, v12
	v_accvgpr_write_b32 a8, v16
	v_accvgpr_write_b32 a12, v20
	v_cvt_pk_bf16_f32 v39, v104, v105
	v_cvt_pk_bf16_f32 v37, v90, v91
	v_cvt_pk_bf16_f32 v36, v50, v51
	v_accvgpr_write_b32 a1, v9
	v_accvgpr_write_b32 a2, v10
	v_accvgpr_write_b32 a3, v11
	v_accvgpr_write_b32 a5, v13
	v_accvgpr_write_b32 a6, v14
	v_accvgpr_write_b32 a7, v15
	v_accvgpr_write_b32 a9, v17
	v_accvgpr_write_b32 a10, v18
	v_accvgpr_write_b32 a11, v19
	v_accvgpr_write_b32 a13, v21
	v_accvgpr_write_b32 a14, v22
	v_accvgpr_write_b32 a15, v23
	s_waitcnt vmcnt(14)
	v_mfma_f32_16x16x32_bf16 a[0:3], v[82:85], v[36:39], a[0:3]
	s_waitcnt vmcnt(12)
	v_mfma_f32_16x16x32_bf16 a[4:7], v[86:89], v[36:39], a[4:7]
	s_waitcnt vmcnt(10)
	v_mfma_f32_16x16x32_bf16 a[8:11], v[94:97], v[36:39], a[8:11]
	s_waitcnt vmcnt(8)
	v_mfma_f32_16x16x32_bf16 a[12:15], v[98:101], v[36:39], a[12:15]
	s_cbranch_scc1 .LBB0_391
	ds_bpermute_b32 v16, v46, v47
	v_accvgpr_read_b32 v15, a3
	v_accvgpr_read_b32 v14, a2
	v_accvgpr_read_b32 v12, a0
	v_accvgpr_read_b32 v13, a1
	s_waitcnt lgkmcnt(0)
	v_add_f32_e32 v16, v47, v16
	ds_bpermute_b32 v17, v45, v16
	v_lshlrev_b32_e32 v192, 1, v72
	v_accvgpr_read_b32 v11, a7
	v_accvgpr_read_b32 v10, a6
	v_accvgpr_read_b32 v8, a4
	s_waitcnt lgkmcnt(0)
	v_add_f32_e32 v16, v16, v17
	v_div_scale_f32 v17, s[2:3], v16, v16, 1.0
	v_rcp_f32_e32 v18, v17
	v_accvgpr_read_b32 v9, a5
	v_accvgpr_read_b32 v4, a8
	v_accvgpr_read_b32 v6, a10
	v_fma_f32 v19, -v17, v18, 1.0
	v_fmac_f32_e32 v18, v19, v18
	v_div_scale_f32 v19, vcc, 1.0, v16, 1.0
	v_mul_f32_e32 v20, v19, v18
	v_fma_f32 v21, -v17, v20, v19
	v_fmac_f32_e32 v20, v21, v18
	v_fma_f32 v17, -v17, v20, v19
	v_div_fmas_f32 v17, v17, v18, v20
	v_div_fixup_f32 v16, v17, v16, 1.0
	v_mov_b32_e32 v20, v12
	v_mov_b32_e32 v21, v14
	v_pk_mul_f32 v[20:21], v[20:21], v[16:17] op_sel_hi:[1,0]
	v_mov_b32_e32 v14, v13
	v_pk_mul_f32 v[12:13], v[14:15], v[16:17] op_sel_hi:[1,0]
	v_and_b32_sdwa v17, v13, v218 dst_sel:DWORD dst_unused:UNUSED_PAD src0_sel:WORD_1 src1_sel:DWORD
	v_cvt_pk_bf16_f32 v12, v20, v12
	v_lshlrev_b64 v[18:19], 11, v[24:25]
	v_and_b32_sdwa v14, v21, v218 dst_sel:DWORD dst_unused:UNUSED_PAD src0_sel:WORD_1 src1_sel:DWORD
	v_add3_u32 v13, v13, v17, s80
	v_lshl_add_u64 v[18:19], s[90:91], 0, v[18:19]
	v_add3_u32 v14, v21, v14, s80
	v_and_b32_e32 v13, 0xffff0000, v13
	v_or_b32_sdwa v13, v13, v14 dst_sel:DWORD dst_unused:UNUSED_PAD src0_sel:DWORD src1_sel:WORD_1
	v_lshl_add_u64 v[14:15], s[0:1], 1, v[18:19]
	v_lshl_add_u64 v[14:15], v[14:15], 0, v[192:193]
	s_mov_b32 s0, 0x5780000
	v_add_co_u32_e32 v14, vcc, s0, v14
	v_accvgpr_read_b32 v5, a9
	s_nop 0
	v_addc_co_u32_e32 v15, vcc, 0, v15, vcc
	global_store_dwordx2 v[14:15], v[12:13], off offset:1280
	v_mov_b32_e32 v12, v8
	v_mov_b32_e32 v13, v10
	v_pk_mul_f32 v[12:13], v[12:13], v[16:17] op_sel_hi:[1,0]
	v_mov_b32_e32 v10, v9
	v_pk_mul_f32 v[8:9], v[10:11], v[16:17] op_sel_hi:[1,0]
	v_cvt_pk_bf16_f32 v8, v12, v8
	v_cvt_pk_bf16_f32 v9, v13, v9
	global_store_dwordx2 v[14:15], v[8:9], off offset:1312
	v_mov_b32_e32 v8, v4
	v_mov_b32_e32 v9, v6
	v_accvgpr_read_b32 v7, a11
	v_pk_mul_f32 v[8:9], v[8:9], v[16:17] op_sel_hi:[1,0]
	v_mov_b32_e32 v6, v5
	v_pk_mul_f32 v[4:5], v[6:7], v[16:17] op_sel_hi:[1,0]
	v_cvt_pk_bf16_f32 v4, v8, v4
	v_cvt_pk_bf16_f32 v5, v9, v5
	v_accvgpr_read_b32 v0, a12
	v_accvgpr_read_b32 v2, a14
	v_accvgpr_read_b32 v1, a13
	global_store_dwordx2 v[14:15], v[4:5], off offset:1344
	v_mov_b32_e32 v4, v0
	v_mov_b32_e32 v5, v2
	v_accvgpr_read_b32 v3, a15
	v_pk_mul_f32 v[4:5], v[4:5], v[16:17] op_sel_hi:[1,0]
	v_mov_b32_e32 v2, v1
	v_pk_mul_f32 v[0:1], v[2:3], v[16:17] op_sel_hi:[1,0]
	v_cvt_pk_bf16_f32 v0, v4, v0
	v_cvt_pk_bf16_f32 v1, v5, v1
	global_store_dwordx2 v[14:15], v[0:1], off offset:1376

.LBB0_414:
	s_add_u32 s29, s90, s4
	s_addc_u32 s30, s91, s5
	s_lshl_b64 s[4:5], s[6:7], vcc_lo
	s_add_u32 s4, s29, s4
	s_addc_u32 s5, s30, s5
	s_waitcnt vmcnt(16)
	v_lshl_add_u64 v[64:65], v[16:17], 1, s[4:5]
	v_lshl_add_u64 v[16:17], v[18:19], 0, v[68:69]
	s_movk_i32 s29, 0x300
	v_mad_u64_u32 v[24:25], s[4:5], v16, s29, v[86:87]
	v_mov_b32_e32 v16, v25
	v_mul_u32_u24_e32 v66, s28, v68
	v_mad_u64_u32 v[26:27], s[4:5], v17, s29, v[16:17]
	v_lshlrev_b32_e32 v192, 1, v66
	v_mov_b32_e32 v25, v26
	v_lshl_add_u64 v[64:65], v[64:65], 0, v[192:193]
	v_mov_b32_e32 v85, v193
	global_load_dwordx4 v[16:19], v[24:25], off
	global_load_dwordx4 v[20:23], v[24:25], off offset:64
	v_add_co_u32_e32 v24, vcc, s93, v24
	v_lshl_add_u64 v[64:65], v[64:65], 0, v[84:85]
	s_lshl_b32 s78, s28, 5
	v_addc_co_u32_e32 v25, vcc, 0, v26, vcc
	v_lshl_add_u64 v[66:67], v[64:65], 0, s[78:79]
	global_load_dwordx4 v[28:31], v[24:25], off
	s_nop 0
	global_load_dwordx4 v[24:27], v[24:25], off offset:64
	s_nop 0
	global_load_dwordx2 v[134:135], v[64:65], off
	global_load_dwordx2 v[136:137], v[64:65], off offset:32
	global_load_dwordx2 v[130:131], v[66:67], off
	global_load_dwordx2 v[132:133], v[66:67], off offset:32
	v_lshl_add_u64 v[64:65], v[66:67], 0, s[78:79]
	v_lshl_add_u64 v[66:67], v[64:65], 0, s[78:79]
	global_load_dwordx2 v[126:127], v[64:65], off
	global_load_dwordx2 v[128:129], v[64:65], off offset:32
	global_load_dwordx2 v[122:123], v[66:67], off
	global_load_dwordx2 v[124:125], v[66:67], off offset:32
	s_cmp_ge_i32 s71, s94
	s_mov_b64 s[28:29], -1
	s_cbranch_scc0 .LBB0_416
	s_waitcnt vmcnt(12)
	v_mfma_f32_16x16x32_bf16 a[0:3], v[146:149], v[0:3], 0
	v_cmp_lt_i32_e32 vcc, v212, v210
	s_mov_b32 s4, 0x7060302
	s_mov_b64 s[28:29], 0
	v_mfma_f32_16x16x32_bf16 a[0:3], v[142:145], v[4:7], a[0:3]
	v_mfma_f32_16x16x32_bf16 a[8:11], v[146:149], v[8:11], 0
	v_mfma_f32_16x16x32_bf16 a[12:15], v[150:153], v[8:11], 0
	s_nop 5
	s_nop 3
	v_accvgpr_read_b32 v64, a0
	v_accvgpr_read_b32 v65, a1
	v_accvgpr_read_b32 v66, a2
	v_accvgpr_read_b32 v67, a3
	v_mfma_f32_16x16x32_bf16 a[0:3], v[150:153], v[0:3], 0
	v_max_f32_e32 v85, v65, v65
	v_max_f32_e32 v90, v64, v64
	v_max_f32_e32 v85, v90, v85
	v_mfma_f32_16x16x32_bf16 a[0:3], v[138:141], v[4:7], a[0:3]
	v_max_f32_e32 v90, v67, v67
	v_max_f32_e32 v91, v66, v66
	v_max_f32_e32 v90, v91, v90
	v_mfma_f32_16x16x32_bf16 a[8:11], v[142:145], v[12:15], a[8:11]
	v_mfma_f32_16x16x32_bf16 a[12:15], v[138:141], v[12:15], a[12:15]
	s_nop 2
	s_nop 3
	v_accvgpr_read_b32 v154, a2
	v_accvgpr_read_b32 v155, a3
	v_max_f32_e32 v103, v155, v155
	v_max_f32_e32 v156, v154, v154
	v_accvgpr_read_b32 v91, a0
	v_accvgpr_read_b32 v105, a1
	v_max_f32_e32 v103, v156, v103
	v_max3_f32 v103, v91, v105, v103
	v_max3_f32 v85, v85, v90, v103
	v_cndmask_b32_e32 v90, v209, v212, vcc
	v_lshlrev_b32_e32 v90, 2, v90
	ds_bpermute_b32 v103, v90, v85
	v_cmp_lt_i32_e32 vcc, v211, v210
	v_accvgpr_read_b32 v165, a11
	v_accvgpr_read_b32 v173, a15
	v_accvgpr_read_b32 v167, a12
	s_waitcnt lgkmcnt(0)
	v_max_f32_e32 v103, v103, v103
	v_max_f32_e32 v85, v85, v103
	v_cndmask_b32_e32 v103, v209, v211, vcc
	v_lshlrev_b32_e32 v159, 2, v103
	ds_bpermute_b32 v103, v159, v85
	v_accvgpr_read_b32 v169, a13
	s_waitcnt lgkmcnt(0)
	v_max3_f32 v103, v102, v85, v103
	v_sub_f32_e32 v64, v64, v103
	v_mul_f32_e32 v64, 0x3fb8aa3b, v64
	v_exp_f32_e32 v158, v64
	v_sub_f32_e32 v64, v65, v103
	v_mul_f32_e32 v64, 0x3fb8aa3b, v64
	v_exp_f32_e32 v160, v64
	v_sub_f32_e32 v64, v66, v103
	v_mul_f32_e32 v64, 0x3fb8aa3b, v64
	v_exp_f32_e32 v162, v64
	v_sub_f32_e32 v64, v67, v103
	v_mul_f32_e32 v64, 0x3fb8aa3b, v64
	v_exp_f32_e32 v164, v64
	v_sub_f32_e32 v64, v91, v103
	v_mul_f32_e32 v64, 0x3fb8aa3b, v64
	v_exp_f32_e32 v166, v64
	v_sub_f32_e32 v64, v105, v103
	v_sub_f32_e32 v85, v102, v103
	v_mul_f32_e32 v64, 0x3fb8aa3b, v64
	v_mul_f32_e32 v85, 0x3fb8aa3b, v85
	v_exp_f32_e32 v168, v64
	v_sub_f32_e32 v64, v154, v103
	v_sub_f32_e32 v65, v155, v103
	v_mul_f32_e32 v64, 0x3fb8aa3b, v64
	v_exp_f32_e32 v170, v85
	v_mul_f32_e32 v65, 0x3fb8aa3b, v65
	v_exp_f32_e32 v172, v65
	v_exp_f32_e32 v174, v64
	v_pk_mul_f32 v[64:65], v[60:61], v[170:171] op_sel_hi:[1,0]
	v_pk_mul_f32 v[66:67], v[62:63], v[170:171] op_sel_hi:[1,0]
	v_cvt_pk_bf16_f32 v156, v166, v168
	v_accvgpr_write_b32 a0, v64
	v_accvgpr_write_b32 a1, v65
	v_accvgpr_write_b32 a2, v66
	v_accvgpr_write_b32 a3, v67
	v_pk_mul_f32 v[64:65], v[56:57], v[170:171] op_sel_hi:[1,0]
	v_cvt_pk_bf16_f32 v157, v174, v172
	v_pk_mul_f32 v[66:67], v[58:59], v[170:171] op_sel_hi:[1,0]
	v_accvgpr_read_b32 v85, a8
	v_accvgpr_write_b32 a4, v64
	v_accvgpr_read_b32 v91, a9
	v_cvt_pk_bf16_f32 v155, v162, v164
	v_accvgpr_write_b32 a5, v65
	v_accvgpr_write_b32 a6, v66
	v_accvgpr_write_b32 a7, v67
	v_accvgpr_read_b32 v163, a10
	v_max_f32_e32 v64, v91, v91
	v_max_f32_e32 v65, v85, v85
	v_max_f32_e32 v64, v65, v64
	v_max_f32_e32 v65, v165, v165
	v_max_f32_e32 v66, v163, v163
	v_accvgpr_read_b32 v171, a14
	v_max_f32_e32 v65, v66, v65
	v_max_f32_e32 v66, v173, v173
	v_max_f32_e32 v67, v171, v171
	v_max_f32_e32 v66, v67, v66
	v_max3_f32 v66, v167, v169, v66
	v_max3_f32 v105, v64, v65, v66
	ds_bpermute_b32 v90, v90, v105
	v_pk_mul_f32 v[64:65], v[52:53], v[170:171] op_sel_hi:[1,0]
	v_pk_mul_f32 v[66:67], v[54:55], v[170:171] op_sel_hi:[1,0]
	v_accvgpr_write_b32 a8, v64
	v_accvgpr_write_b32 a9, v65
	v_accvgpr_write_b32 a10, v66
	v_accvgpr_write_b32 a11, v67
	s_waitcnt lgkmcnt(0)
	v_max_f32_e32 v64, v90, v90
	v_max_f32_e32 v90, v105, v64
	ds_bpermute_b32 v105, v159, v90
	v_pk_mul_f32 v[64:65], v[48:49], v[170:171] op_sel_hi:[1,0]
	v_pk_mul_f32 v[66:67], v[50:51], v[170:171] op_sel_hi:[1,0]
	v_cvt_pk_bf16_f32 v154, v158, v160
	v_accvgpr_write_b32 a12, v64
	s_waitcnt lgkmcnt(0)
	v_max3_f32 v105, v104, v90, v105
	v_accvgpr_write_b32 a13, v65
	v_accvgpr_write_b32 a14, v66
	v_accvgpr_write_b32 a15, v67
	v_sub_f32_e32 v65, v85, v105
	v_mul_f32_e32 v65, 0x3fb8aa3b, v65
	v_sub_f32_e32 v67, v165, v105
	v_exp_f32_e32 v159, v65
	v_sub_f32_e32 v65, v91, v105
	v_mul_f32_e32 v67, 0x3fb8aa3b, v67
	v_mul_f32_e32 v65, 0x3fb8aa3b, v65
	v_exp_f32_e32 v165, v67
	v_sub_f32_e32 v67, v167, v105
	v_exp_f32_e32 v161, v65
	v_sub_f32_e32 v65, v163, v105
	v_mul_f32_e32 v67, 0x3fb8aa3b, v67
	v_mul_f32_e32 v65, 0x3fb8aa3b, v65
	v_exp_f32_e32 v167, v67
	v_sub_f32_e32 v67, v169, v105
	v_exp_f32_e32 v163, v65
	v_mul_f32_e32 v67, 0x3fb8aa3b, v67
	v_sub_f32_e32 v64, v104, v105
	v_exp_f32_e32 v169, v67
	v_sub_f32_e32 v67, v171, v105
	v_mul_f32_e32 v66, 0x3fb8aa3b, v64
	v_pk_add_f32 v[64:65], v[158:159], 0 op_sel_hi:[1,0]
	v_mul_f32_e32 v67, 0x3fb8aa3b, v67
	v_pk_add_f32 v[64:65], v[160:161], v[64:65]
	v_exp_f32_e32 v175, v67
	v_sub_f32_e32 v67, v173, v105
	v_pk_add_f32 v[64:65], v[162:163], v[64:65]
	v_mul_f32_e32 v67, 0x3fb8aa3b, v67
	v_exp_f32_e32 v173, v67
	v_exp_f32_e32 v171, v66
	v_pk_add_f32 v[64:65], v[164:165], v[64:65]
	v_bfe_u32 v164, v159, 16, 1
	v_pk_add_f32 v[64:65], v[166:167], v[64:65]
	v_mov_b32_e32 v158, v171
	v_pk_add_f32 v[64:65], v[168:169], v[64:65]
	v_pk_mul_f32 v[66:67], v[46:47], v[158:159] op_sel_hi:[1,0]
	v_pk_add_f32 v[64:65], v[174:175], v[64:65]
	v_mfma_f32_16x16x32_bf16 a[0:3], v[118:121], v[154:157], a[0:3]
	v_add_f32_e64 v64, v172, v64
	v_add_f32_e64 v65, v173, v65
	v_pk_fma_f32 v[90:91], v[88:89], v[170:171], v[64:65]
	v_pk_mul_f32 v[64:65], v[44:45], v[158:159] op_sel_hi:[1,0]
	v_add3_u32 v159, v159, v164, s80
	v_accvgpr_write_b32 a16, v64
	v_accvgpr_write_b32 a17, v65
	v_accvgpr_write_b32 a18, v66
	v_accvgpr_write_b32 a19, v67
	v_pk_mul_f32 v[64:65], v[40:41], v[158:159] op_sel_hi:[1,0]
	v_pk_mul_f32 v[66:67], v[42:43], v[158:159] op_sel_hi:[1,0]
	v_mfma_f32_16x16x32_bf16 a[4:7], v[114:117], v[154:157], a[4:7]
	v_accvgpr_write_b32 a20, v64
	v_accvgpr_write_b32 a21, v65
	v_accvgpr_write_b32 a22, v66
	v_accvgpr_write_b32 a23, v67
	v_pk_mul_f32 v[64:65], v[36:37], v[158:159] op_sel_hi:[1,0]
	v_pk_mul_f32 v[66:67], v[38:39], v[158:159] op_sel_hi:[1,0]
	v_mfma_f32_16x16x32_bf16 a[8:11], v[110:113], v[154:157], a[8:11]
	v_accvgpr_write_b32 a24, v64
	v_bfe_u32 v162, v161, 16, 1
	v_mfma_f32_16x16x32_bf16 a[12:15], v[106:109], v[154:157], a[12:15]
	v_cvt_pk_bf16_f32 v156, v167, v169
	v_accvgpr_write_b32 a25, v65
	v_accvgpr_write_b32 a26, v66
	v_accvgpr_write_b32 a27, v67
	v_pk_mul_f32 v[64:65], v[32:33], v[158:159] op_sel_hi:[1,0]
	v_add3_u32 v161, v161, v162, s80
	v_pk_mul_f32 v[66:67], v[34:35], v[158:159] op_sel_hi:[1,0]
	v_cvt_pk_bf16_f32 v157, v175, v173
	v_accvgpr_write_b32 a28, v64
	v_cvt_pk_bf16_f32 v155, v163, v165
	v_perm_b32 v154, v161, v159, s4
	v_accvgpr_write_b32 a29, v65
	v_accvgpr_write_b32 a30, v66
	v_accvgpr_write_b32 a31, v67
	v_mfma_f32_16x16x32_bf16 a[16:19], v[118:121], v[154:157], a[16:19]
	v_mfma_f32_16x16x32_bf16 a[20:23], v[114:117], v[154:157], a[20:23]
	v_mfma_f32_16x16x32_bf16 a[24:27], v[110:113], v[154:157], a[24:27]
	v_mfma_f32_16x16x32_bf16 a[28:31], v[106:109], v[154:157], a[28:31]

.LBB0_436:
	s_nop 5
	v_accvgpr_read_b32 v105, a0
	v_accvgpr_read_b32 v91, a1
	v_accvgpr_read_b32 v90, a2
	v_accvgpr_read_b32 v85, a3
	v_max_f32_e32 v103, v91, v91
	v_max_f32_e32 v154, v105, v105
	v_accvgpr_read_b32 v65, a6
	v_accvgpr_read_b32 v64, a7
	v_max_f32_e32 v103, v154, v103
	v_max_f32_e32 v154, v85, v85
	v_max_f32_e32 v155, v90, v90
	v_max_f32_e32 v154, v155, v154
	v_max_f32_e32 v155, v64, v64
	v_max_f32_e32 v156, v65, v65
	v_accvgpr_read_b32 v67, a4
	v_accvgpr_read_b32 v66, a5
	v_max_f32_e32 v155, v156, v155
	v_max3_f32 v155, v67, v66, v155
	v_cmp_lt_i32_e32 vcc, v212, v210
	v_max3_f32 v103, v103, v154, v155
	s_mov_b32 s4, 0x7060302
	v_cndmask_b32_e32 v154, v209, v212, vcc
	v_lshlrev_b32_e32 v154, 2, v154
	ds_bpermute_b32 v154, v154, v103
	v_cmp_lt_i32_e32 vcc, v211, v210
	s_waitcnt lgkmcnt(0)
	v_max_f32_e32 v154, v154, v154
	v_max_f32_e32 v103, v103, v154
	v_cndmask_b32_e32 v154, v209, v211, vcc
	v_lshlrev_b32_e32 v154, 2, v154
	ds_bpermute_b32 v154, v154, v103
	s_waitcnt lgkmcnt(0)
	v_max3_f32 v103, v102, v103, v154
	v_sub_f32_e32 v105, v105, v103
	v_mul_f32_e32 v105, 0x3fb8aa3b, v105
	v_sub_f32_e32 v91, v91, v103
	v_exp_f32_e32 v105, v105
	v_mul_f32_e32 v91, 0x3fb8aa3b, v91
	v_sub_f32_e32 v90, v90, v103
	v_exp_f32_e32 v91, v91
	v_mul_f32_e32 v90, 0x3fb8aa3b, v90
	v_sub_f32_e32 v85, v85, v103
	v_exp_f32_e32 v90, v90
	v_mul_f32_e32 v85, 0x3fb8aa3b, v85
	v_sub_f32_e32 v67, v67, v103
	v_exp_f32_e32 v85, v85
	v_mul_f32_e32 v67, 0x3fb8aa3b, v67
	v_sub_f32_e32 v66, v66, v103
	v_add_f32_e32 v154, 0, v105
	v_exp_f32_e32 v67, v67
	v_mul_f32_e32 v66, 0x3fb8aa3b, v66
	v_sub_f32_e32 v65, v65, v103
	v_add_f32_e32 v154, v91, v154
	v_exp_f32_e32 v66, v66
	v_mul_f32_e32 v65, 0x3fb8aa3b, v65
	v_sub_f32_e32 v64, v64, v103
	v_sub_f32_e32 v102, v102, v103
	v_add_f32_e32 v154, v90, v154
	v_exp_f32_e32 v65, v65
	v_mul_f32_e32 v64, 0x3fb8aa3b, v64
	v_mul_f32_e32 v102, 0x3fb8aa3b, v102
	v_add_f32_e32 v154, v85, v154
	v_exp_f32_e32 v155, v64
	v_add_f32_e32 v154, v67, v154
	v_exp_f32_e32 v64, v102
	v_add_f32_e32 v154, v66, v154
	v_add_f32_e32 v154, v65, v154
	v_add_f32_e32 v154, v155, v154
	v_fmac_f32_e32 v154, v88, v64
	v_pk_mul_f32 v[62:63], v[62:63], v[64:65] op_sel_hi:[1,0]
	v_pk_mul_f32 v[60:61], v[60:61], v[64:65] op_sel_hi:[1,0]
	v_pk_mul_f32 v[58:59], v[58:59], v[64:65] op_sel_hi:[1,0]
	v_pk_mul_f32 v[56:57], v[56:57], v[64:65] op_sel_hi:[1,0]
	v_pk_mul_f32 v[54:55], v[54:55], v[64:65] op_sel_hi:[1,0]
	v_pk_mul_f32 v[52:53], v[52:53], v[64:65] op_sel_hi:[1,0]
	v_pk_mul_f32 v[50:51], v[50:51], v[64:65] op_sel_hi:[1,0]
	v_pk_mul_f32 v[48:49], v[48:49], v[64:65] op_sel_hi:[1,0]
	v_bfe_u32 v64, v155, 16, 1
	v_bfe_u32 v88, v65, 16, 1
	v_cvt_pk_bf16_f32 v66, v67, v66
	v_bfe_u32 v157, v85, 16, 1
	v_bfe_u32 v158, v90, 16, 1
	v_bfe_u32 v159, v91, 16, 1
	v_bfe_u32 v160, v105, 16, 1
	v_add3_u32 v105, v105, v160, s80
	v_add3_u32 v91, v91, v159, s80
	v_add3_u32 v90, v90, v158, s80
	v_add3_u32 v85, v85, v157, s80
	v_add3_u32 v65, v65, v88, s80
	v_add3_u32 v64, v155, v64, s80
	v_accvgpr_write_b32 a0, v60
	v_accvgpr_write_b32 a4, v56
	v_accvgpr_write_b32 a8, v52
	v_accvgpr_write_b32 a12, v48
	v_perm_b32 v67, v64, v65, s4
	v_perm_b32 v65, v85, v90, s4
	v_perm_b32 v64, v91, v105, s4
	v_accvgpr_write_b32 a1, v61
	v_accvgpr_write_b32 a2, v62
	v_accvgpr_write_b32 a3, v63
	v_accvgpr_write_b32 a5, v57
	v_accvgpr_write_b32 a6, v58
	v_accvgpr_write_b32 a7, v59
	v_accvgpr_write_b32 a9, v53
	v_accvgpr_write_b32 a10, v54
	v_accvgpr_write_b32 a11, v55
	v_accvgpr_write_b32 a13, v49
	v_accvgpr_write_b32 a14, v50
	v_accvgpr_write_b32 a15, v51
	v_mfma_f32_16x16x32_bf16 a[0:3], v[118:121], v[64:67], a[0:3]
	v_mov_b32_e32 v88, v154
	v_mfma_f32_16x16x32_bf16 a[4:7], v[114:117], v[64:67], a[4:7]
	v_mfma_f32_16x16x32_bf16 a[8:11], v[110:113], v[64:67], a[8:11]
	v_mfma_f32_16x16x32_bf16 a[12:15], v[106:109], v[64:67], a[12:15]
	s_add_i32 s4, s83, s71
	s_cmp_lt_u32 s4, s33
	s_cbranch_scc0 .LBB0_438
	s_branch .LBB0_457

.LBB0_456:
	s_nop 5
	v_accvgpr_read_b32 v55, a16
	v_accvgpr_read_b32 v54, a17
	v_accvgpr_read_b32 v53, a18
	v_accvgpr_read_b32 v52, a19
	v_max_f32_e32 v56, v54, v54
	v_max_f32_e32 v57, v55, v55
	v_accvgpr_read_b32 v49, a22
	v_accvgpr_read_b32 v48, a23
	v_max_f32_e32 v56, v57, v56
	v_max_f32_e32 v57, v52, v52
	v_max_f32_e32 v58, v53, v53
	v_max_f32_e32 v57, v58, v57
	v_max_f32_e32 v58, v48, v48
	v_max_f32_e32 v59, v49, v49
	v_accvgpr_read_b32 v51, a20
	v_accvgpr_read_b32 v50, a21
	v_max_f32_e32 v58, v59, v58
	v_max3_f32 v58, v51, v50, v58
	v_cmp_lt_i32_e32 vcc, v212, v210
	v_max3_f32 v56, v56, v57, v58
	s_mov_b32 s4, 0x7060302
	v_cndmask_b32_e32 v57, v209, v212, vcc
	v_lshlrev_b32_e32 v57, 2, v57
	ds_bpermute_b32 v57, v57, v56
	v_cmp_lt_i32_e32 vcc, v211, v210
	s_waitcnt lgkmcnt(0)
	v_max_f32_e32 v57, v57, v57
	v_max_f32_e32 v56, v56, v57
	v_cndmask_b32_e32 v57, v209, v211, vcc
	v_lshlrev_b32_e32 v57, 2, v57
	ds_bpermute_b32 v57, v57, v56
	s_waitcnt lgkmcnt(0)
	v_max3_f32 v56, v104, v56, v57
	v_sub_f32_e32 v55, v55, v56
	v_mul_f32_e32 v55, 0x3fb8aa3b, v55
	v_sub_f32_e32 v54, v54, v56
	v_exp_f32_e32 v55, v55
	v_mul_f32_e32 v54, 0x3fb8aa3b, v54
	v_sub_f32_e32 v53, v53, v56
	v_exp_f32_e32 v54, v54
	v_mul_f32_e32 v53, 0x3fb8aa3b, v53
	v_sub_f32_e32 v52, v52, v56
	v_exp_f32_e32 v53, v53
	v_mul_f32_e32 v52, 0x3fb8aa3b, v52
	v_sub_f32_e32 v51, v51, v56
	v_exp_f32_e32 v52, v52
	v_mul_f32_e32 v51, 0x3fb8aa3b, v51
	v_sub_f32_e32 v50, v50, v56
	v_add_f32_e32 v58, 0, v55
	v_exp_f32_e32 v51, v51
	v_mul_f32_e32 v50, 0x3fb8aa3b, v50
	v_sub_f32_e32 v49, v49, v56
	v_add_f32_e32 v58, v54, v58
	v_exp_f32_e32 v50, v50
	v_mul_f32_e32 v49, 0x3fb8aa3b, v49
	v_sub_f32_e32 v48, v48, v56
	v_sub_f32_e32 v57, v104, v56
	v_add_f32_e32 v58, v53, v58
	v_exp_f32_e32 v49, v49
	v_mul_f32_e32 v48, 0x3fb8aa3b, v48
	v_mul_f32_e32 v57, 0x3fb8aa3b, v57
	v_add_f32_e32 v58, v52, v58
	v_exp_f32_e32 v59, v48
	v_add_f32_e32 v58, v51, v58
	v_exp_f32_e32 v48, v57
	v_add_f32_e32 v58, v50, v58
	v_add_f32_e32 v58, v49, v58
	v_add_f32_e32 v58, v59, v58
	v_fmac_f32_e32 v58, v89, v48
	v_pk_mul_f32 v[46:47], v[46:47], v[48:49] op_sel_hi:[1,0]
	v_pk_mul_f32 v[44:45], v[44:45], v[48:49] op_sel_hi:[1,0]
	v_pk_mul_f32 v[42:43], v[42:43], v[48:49] op_sel_hi:[1,0]
	v_pk_mul_f32 v[40:41], v[40:41], v[48:49] op_sel_hi:[1,0]
	v_pk_mul_f32 v[38:39], v[38:39], v[48:49] op_sel_hi:[1,0]
	v_pk_mul_f32 v[36:37], v[36:37], v[48:49] op_sel_hi:[1,0]
	v_pk_mul_f32 v[34:35], v[34:35], v[48:49] op_sel_hi:[1,0]
	v_pk_mul_f32 v[32:33], v[32:33], v[48:49] op_sel_hi:[1,0]
	v_bfe_u32 v48, v59, 16, 1
	v_bfe_u32 v57, v49, 16, 1
	v_cvt_pk_bf16_f32 v50, v51, v50
	v_bfe_u32 v62, v52, 16, 1
	v_bfe_u32 v63, v53, 16, 1
	v_bfe_u32 v64, v54, 16, 1
	v_bfe_u32 v65, v55, 16, 1
	v_add3_u32 v55, v55, v65, s80
	v_add3_u32 v54, v54, v64, s80
	v_add3_u32 v53, v53, v63, s80
	v_add3_u32 v52, v52, v62, s80
	v_add3_u32 v49, v49, v57, s80
	v_add3_u32 v48, v59, v48, s80
	v_accvgpr_write_b32 a16, v44
	v_perm_b32 v51, v48, v49, s4
	v_perm_b32 v49, v52, v53, s4
	v_perm_b32 v48, v54, v55, s4
	v_accvgpr_write_b32 a17, v45
	v_accvgpr_write_b32 a18, v46
	v_accvgpr_write_b32 a19, v47
	v_mov_b32_e32 v89, v58
	v_mov_b32_e32 v104, v56
	v_mfma_f32_16x16x32_bf16 a[32:35], v[118:121], v[48:51], a[16:19]
	s_nop 2
	v_accvgpr_write_b32 a16, v40
	v_accvgpr_write_b32 a17, v41
	v_accvgpr_write_b32 a18, v42
	v_accvgpr_write_b32 a19, v43
	s_nop 1
	v_mfma_f32_16x16x32_bf16 a[36:39], v[114:117], v[48:51], a[16:19]
	s_nop 2
	v_accvgpr_write_b32 a16, v36
	v_accvgpr_write_b32 a17, v37
	v_accvgpr_write_b32 a18, v38
	v_accvgpr_write_b32 a19, v39
	s_nop 1
	v_mfma_f32_16x16x32_bf16 a[40:43], v[110:113], v[48:51], a[16:19]
	s_nop 2
	v_accvgpr_write_b32 a16, v32
	v_accvgpr_write_b32 a17, v33
	v_accvgpr_write_b32 a18, v34
	v_accvgpr_write_b32 a19, v35
	s_nop 1
	v_mfma_f32_16x16x32_bf16 a[44:47], v[106:109], v[48:51], a[16:19]

.LBB0_463:
	s_add_u32 s29, s90, vcc_lo
	s_addc_u32 s77, s91, vcc_hi
	s_lshl_b64 s[4:5], s[6:7], s4
	s_add_u32 s4, s29, s4
	s_addc_u32 s5, s77, s5
	v_lshl_add_u64 v[66:67], v[66:67], 0, v[68:69]
	s_movk_i32 s29, 0x300
	v_lshl_add_u64 v[64:65], v[64:65], 1, s[4:5]
	v_mad_u64_u32 v[88:89], s[4:5], v66, s29, v[86:87]
	v_mov_b32_e32 v66, v89
	v_mad_u64_u32 v[66:67], s[4:5], v67, s29, v[66:67]
	v_mov_b32_e32 v89, v66
	global_load_dwordx4 v[146:149], v[88:89], off
	global_load_dwordx4 v[142:145], v[88:89], off offset:64
	v_add_co_u32_e32 v88, vcc, s93, v88
	v_mov_b32_e32 v85, v193
	s_nop 0
	v_addc_co_u32_e32 v89, vcc, 0, v66, vcc
	v_mul_u32_u24_e32 v66, s28, v68
	v_lshlrev_b32_e32 v192, 1, v66
	v_lshl_add_u64 v[64:65], v[64:65], 0, v[192:193]
	v_lshl_add_u64 v[64:65], v[64:65], 0, v[84:85]
	s_lshl_b32 s78, s28, 5
	v_lshl_add_u64 v[66:67], v[64:65], 0, s[78:79]
	global_load_dwordx4 v[150:153], v[88:89], off
	global_load_dwordx4 v[138:141], v[88:89], off offset:64
	global_load_dwordx2 v[118:119], v[64:65], off
	global_load_dwordx2 v[120:121], v[64:65], off offset:32
	global_load_dwordx2 v[114:115], v[66:67], off
	global_load_dwordx2 v[116:117], v[66:67], off offset:32
	v_lshl_add_u64 v[64:65], v[66:67], 0, s[78:79]
	v_lshl_add_u64 v[66:67], v[64:65], 0, s[78:79]
	global_load_dwordx2 v[110:111], v[64:65], off
	global_load_dwordx2 v[112:113], v[64:65], off offset:32
	global_load_dwordx2 v[106:107], v[66:67], off
	global_load_dwordx2 v[108:109], v[66:67], off offset:32
	s_cmp_ge_i32 s31, s76
	s_cbranch_scc1 .LBB0_487
	s_mov_b64 s[28:29], -1
	s_and_b64 vcc, exec, s[26:27]
	s_cbranch_vccz .LBB0_466
	s_waitcnt vmcnt(23)
	v_mfma_f32_16x16x32_bf16 a[32:35], v[16:19], v[0:3], 0
	v_cmp_lt_i32_e32 vcc, v212, v210
	s_mov_b32 s4, 0x7060302
	s_mov_b64 s[28:29], 0
	s_waitcnt vmcnt(22)
	v_mfma_f32_16x16x32_bf16 a[32:35], v[20:23], v[4:7], a[32:35]
	v_mfma_f32_16x16x32_bf16 a[40:43], v[16:19], v[8:11], 0
	s_waitcnt vmcnt(21)
	v_mfma_f32_16x16x32_bf16 a[44:47], v[28:31], v[8:11], 0
	s_nop 4
	s_nop 3
	v_accvgpr_read_b32 v64, a32
	v_accvgpr_read_b32 v65, a33
	v_accvgpr_read_b32 v66, a34
	v_accvgpr_read_b32 v67, a35
	v_mfma_f32_16x16x32_bf16 a[32:35], v[28:31], v[0:3], 0
	v_max_f32_e32 v85, v65, v65
	v_max_f32_e32 v88, v64, v64
	v_max_f32_e32 v85, v88, v85
	s_waitcnt vmcnt(20)
	v_mfma_f32_16x16x32_bf16 a[32:35], v[24:27], v[4:7], a[32:35]
	v_max_f32_e32 v88, v67, v67
	v_max_f32_e32 v89, v66, v66
	v_max_f32_e32 v88, v89, v88
	v_mfma_f32_16x16x32_bf16 a[40:43], v[20:23], v[12:15], a[40:43]
	v_mfma_f32_16x16x32_bf16 a[44:47], v[24:27], v[12:15], a[44:47]
	s_nop 2
	s_nop 3
	v_accvgpr_read_b32 v154, a34
	v_accvgpr_read_b32 v155, a35
	v_max_f32_e32 v102, v155, v155
	v_max_f32_e32 v156, v154, v154
	v_accvgpr_read_b32 v89, a32
	v_accvgpr_read_b32 v104, a33
	v_max_f32_e32 v102, v156, v102
	v_max3_f32 v102, v89, v104, v102
	v_max3_f32 v85, v85, v88, v102
	v_cndmask_b32_e32 v88, v209, v212, vcc
	v_lshlrev_b32_e32 v159, 2, v88
	ds_bpermute_b32 v88, v159, v85
	v_cmp_lt_i32_e32 vcc, v211, v210
	v_accvgpr_read_b32 v167, a43
	v_accvgpr_read_b32 v173, a46
	v_accvgpr_read_b32 v174, a47
	s_waitcnt lgkmcnt(0)
	v_max_f32_e32 v88, v88, v88
	v_max_f32_e32 v85, v85, v88
	v_cndmask_b32_e32 v88, v209, v211, vcc
	v_lshlrev_b32_e32 v161, 2, v88
	ds_bpermute_b32 v88, v161, v85
	v_accvgpr_read_b32 v171, a45
	s_waitcnt lgkmcnt(0)
	v_max3_f32 v102, v103, v85, v88
	v_sub_f32_e32 v64, v64, v102
	v_mul_f32_e32 v64, 0x3fb8aa3b, v64
	v_exp_f32_e32 v88, v64
	v_sub_f32_e32 v64, v65, v102
	v_mul_f32_e32 v64, 0x3fb8aa3b, v64
	v_exp_f32_e32 v158, v64
	v_sub_f32_e32 v64, v66, v102
	v_mul_f32_e32 v64, 0x3fb8aa3b, v64
	v_exp_f32_e32 v160, v64
	v_sub_f32_e32 v64, v67, v102
	v_mul_f32_e32 v64, 0x3fb8aa3b, v64
	v_exp_f32_e32 v162, v64
	v_sub_f32_e32 v64, v89, v102
	v_mul_f32_e32 v64, 0x3fb8aa3b, v64
	v_exp_f32_e32 v164, v64
	v_sub_f32_e32 v64, v104, v102
	v_sub_f32_e32 v85, v103, v102
	v_mul_f32_e32 v64, 0x3fb8aa3b, v64
	v_mul_f32_e32 v85, 0x3fb8aa3b, v85
	v_exp_f32_e32 v166, v64
	v_sub_f32_e32 v64, v154, v102
	v_sub_f32_e32 v65, v155, v102
	v_mul_f32_e32 v64, 0x3fb8aa3b, v64
	v_exp_f32_e32 v168, v85
	v_mul_f32_e32 v65, 0x3fb8aa3b, v65
	v_exp_f32_e32 v170, v65
	v_exp_f32_e32 v172, v64
	v_pk_mul_f32 v[64:65], v[60:61], v[168:169] op_sel_hi:[1,0]
	v_pk_mul_f32 v[66:67], v[62:63], v[168:169] op_sel_hi:[1,0]
	v_cvt_pk_bf16_f32 v154, v88, v158
	v_accvgpr_write_b32 a32, v64
	v_accvgpr_write_b32 a33, v65
	v_accvgpr_write_b32 a34, v66
	v_accvgpr_write_b32 a35, v67
	v_pk_mul_f32 v[64:65], v[56:57], v[168:169] op_sel_hi:[1,0]
	v_cvt_pk_bf16_f32 v157, v172, v170
	v_pk_mul_f32 v[66:67], v[58:59], v[168:169] op_sel_hi:[1,0]
	v_accvgpr_read_b32 v85, a40
	v_accvgpr_write_b32 a36, v64
	v_accvgpr_read_b32 v163, a41
	v_cvt_pk_bf16_f32 v155, v160, v162
	v_accvgpr_write_b32 a37, v65
	v_accvgpr_write_b32 a38, v66
	v_accvgpr_write_b32 a39, v67
	v_accvgpr_read_b32 v165, a42
	v_max_f32_e32 v64, v163, v163
	v_max_f32_e32 v65, v85, v85
	v_max_f32_e32 v64, v65, v64
	v_max_f32_e32 v65, v167, v167
	v_max_f32_e32 v66, v165, v165
	v_max_f32_e32 v65, v66, v65
	v_max_f32_e32 v66, v174, v174
	v_max_f32_e32 v67, v173, v173
	v_cvt_pk_bf16_f32 v156, v164, v166
	v_accvgpr_read_b32 v169, a44
	v_max_f32_e32 v66, v67, v66
	v_max3_f32 v66, v169, v171, v66
	v_max3_f32 v89, v64, v65, v66
	ds_bpermute_b32 v104, v159, v89
	v_pk_mul_f32 v[64:65], v[52:53], v[168:169] op_sel_hi:[1,0]
	v_pk_mul_f32 v[66:67], v[54:55], v[168:169] op_sel_hi:[1,0]
	s_waitcnt vmcnt(18)
	v_mfma_f32_16x16x32_bf16 a[32:35], v[134:137], v[154:157], a[32:35]
	v_accvgpr_write_b32 a40, v64
	v_accvgpr_write_b32 a41, v65
	v_accvgpr_write_b32 a42, v66
	v_accvgpr_write_b32 a43, v67
	s_waitcnt lgkmcnt(0)
	v_max_f32_e32 v64, v104, v104
	v_max_f32_e32 v89, v89, v64
	ds_bpermute_b32 v104, v161, v89
	v_pk_mul_f32 v[64:65], v[48:49], v[168:169] op_sel_hi:[1,0]
	v_pk_mul_f32 v[66:67], v[50:51], v[168:169] op_sel_hi:[1,0]
	s_waitcnt vmcnt(16)
	v_mfma_f32_16x16x32_bf16 a[36:39], v[130:133], v[154:157], a[36:39]
	v_accvgpr_write_b32 a44, v64
	s_waitcnt lgkmcnt(0)
	v_max3_f32 v104, v105, v89, v104
	v_accvgpr_write_b32 a45, v65
	v_accvgpr_write_b32 a46, v66
	v_accvgpr_write_b32 a47, v67
	v_sub_f32_e32 v65, v85, v104
	v_mul_f32_e32 v65, 0x3fb8aa3b, v65
	v_exp_f32_e32 v89, v65
	v_sub_f32_e32 v65, v163, v104
	v_mul_f32_e32 v65, 0x3fb8aa3b, v65
	v_exp_f32_e32 v159, v65
	v_sub_f32_e32 v65, v165, v104
	v_mul_f32_e32 v65, 0x3fb8aa3b, v65
	v_exp_f32_e32 v161, v65
	v_sub_f32_e32 v65, v167, v104
	v_mul_f32_e32 v65, 0x3fb8aa3b, v65
	v_exp_f32_e32 v163, v65
	v_sub_f32_e32 v65, v169, v104
	v_mul_f32_e32 v65, 0x3fb8aa3b, v65
	v_exp_f32_e32 v165, v65
	v_sub_f32_e32 v65, v171, v104
	v_mul_f32_e32 v65, 0x3fb8aa3b, v65
	v_exp_f32_e32 v167, v65
	v_sub_f32_e32 v65, v173, v104
	v_sub_f32_e32 v64, v105, v104
	v_mul_f32_e32 v65, 0x3fb8aa3b, v65
	v_mul_f32_e32 v64, 0x3fb8aa3b, v64
	v_exp_f32_e32 v173, v65
	v_sub_f32_e32 v65, v174, v104
	v_mul_f32_e32 v65, 0x3fb8aa3b, v65
	v_exp_f32_e32 v169, v64
	v_exp_f32_e32 v171, v65
	s_waitcnt vmcnt(14)
	v_mfma_f32_16x16x32_bf16 a[40:43], v[126:129], v[154:157], a[40:43]
	v_add_f32_e64 v64, v88, 0
	v_add_f32_e64 v65, v89, 0
	v_mov_b32_e32 v66, v169
	v_pk_add_f32 v[64:65], v[158:159], v[64:65]
	s_waitcnt vmcnt(12)
	v_mfma_f32_16x16x32_bf16 a[44:47], v[122:125], v[154:157], a[44:47]
	v_mul_f32_e64 v156, v46, v66
	v_mul_f32_e64 v157, v47, v66
	v_pk_mul_f32 v[154:155], v[44:45], v[66:67] op_sel_hi:[1,0]
	v_bfe_u32 v67, v171, 16, 1
	v_add3_u32 v67, v171, v67, s80
	v_accvgpr_write_b32 a48, v154
	v_accvgpr_write_b32 a49, v155
	v_accvgpr_write_b32 a50, v156
	v_accvgpr_write_b32 a51, v157
	v_pk_mul_f32 v[154:155], v[40:41], v[66:67] op_sel_hi:[1,0]
	v_pk_add_f32 v[64:65], v[160:161], v[64:65]
	v_pk_mul_f32 v[156:157], v[42:43], v[66:67] op_sel_hi:[1,0]
	v_pk_add_f32 v[64:65], v[162:163], v[64:65]
	v_accvgpr_write_b32 a52, v154
	v_accvgpr_write_b32 a53, v155
	v_accvgpr_write_b32 a54, v156
	v_accvgpr_write_b32 a55, v157
	v_pk_mul_f32 v[154:155], v[36:37], v[66:67] op_sel_hi:[1,0]
	v_pk_add_f32 v[64:65], v[164:165], v[64:65]
	v_pk_mul_f32 v[156:157], v[38:39], v[66:67] op_sel_hi:[1,0]
	v_pk_add_f32 v[64:65], v[166:167], v[64:65]
	v_accvgpr_write_b32 a56, v154
	v_bfe_u32 v85, v173, 16, 1
	v_bfe_u32 v160, v163, 16, 1
	v_bfe_u32 v162, v161, 16, 1
	v_bfe_u32 v164, v159, 16, 1
	v_bfe_u32 v166, v89, 16, 1
	v_accvgpr_write_b32 a57, v155
	v_accvgpr_write_b32 a58, v156
	v_accvgpr_write_b32 a59, v157
	v_pk_mul_f32 v[154:155], v[32:33], v[66:67] op_sel_hi:[1,0]
	v_pk_add_f32 v[64:65], v[172:173], v[64:65]
	v_add3_u32 v89, v89, v166, s80
	v_add3_u32 v164, v159, v164, s80
	v_add3_u32 v159, v161, v162, s80
	v_add3_u32 v162, v163, v160, s80
	v_add3_u32 v85, v173, v85, s80
	v_pk_mul_f32 v[156:157], v[34:35], v[66:67] op_sel_hi:[1,0]
	v_pk_add_f32 v[64:65], v[170:171], v[64:65]
	v_accvgpr_write_b32 a60, v154
	v_perm_b32 v161, v67, v85, s4
	v_cvt_pk_bf16_f32 v160, v165, v167
	v_perm_b32 v159, v162, v159, s4
	v_perm_b32 v158, v164, v89, s4
	v_accvgpr_write_b32 a61, v155
	v_accvgpr_write_b32 a62, v156
	v_accvgpr_write_b32 a63, v157
	v_pk_fma_f32 v[64:65], v[90:91], v[168:169], v[64:65]
	v_mfma_f32_16x16x32_bf16 a[48:51], v[134:137], v[158:161], a[48:51]
	v_mfma_f32_16x16x32_bf16 a[52:55], v[130:133], v[158:161], a[52:55]
	v_mfma_f32_16x16x32_bf16 a[56:59], v[126:129], v[158:161], a[56:59]
	v_mfma_f32_16x16x32_bf16 a[60:63], v[122:125], v[158:161], a[60:63]

.LBB0_486:
	s_nop 4
	v_accvgpr_read_b32 v104, a0
	v_accvgpr_read_b32 v89, a1
	v_accvgpr_read_b32 v88, a2
	v_accvgpr_read_b32 v85, a3
	v_max_f32_e32 v102, v89, v89
	v_max_f32_e32 v154, v104, v104
	v_accvgpr_read_b32 v65, a6
	v_accvgpr_read_b32 v64, a7
	v_max_f32_e32 v102, v154, v102
	v_max_f32_e32 v154, v85, v85
	v_max_f32_e32 v155, v88, v88
	v_max_f32_e32 v154, v155, v154
	v_max_f32_e32 v155, v64, v64
	v_max_f32_e32 v156, v65, v65
	v_accvgpr_read_b32 v67, a4
	v_accvgpr_read_b32 v66, a5
	v_max_f32_e32 v155, v156, v155
	v_max3_f32 v155, v67, v66, v155
	v_cmp_lt_i32_e32 vcc, v212, v210
	v_max3_f32 v102, v102, v154, v155
	s_mov_b32 s4, 0x7060302
	v_cndmask_b32_e32 v154, v209, v212, vcc
	v_lshlrev_b32_e32 v154, 2, v154
	ds_bpermute_b32 v154, v154, v102
	v_cmp_lt_i32_e32 vcc, v211, v210
	s_waitcnt lgkmcnt(0)
	v_max_f32_e32 v154, v154, v154
	v_max_f32_e32 v102, v102, v154
	v_cndmask_b32_e32 v154, v209, v211, vcc
	v_lshlrev_b32_e32 v154, 2, v154
	ds_bpermute_b32 v154, v154, v102
	s_waitcnt lgkmcnt(0)
	v_max3_f32 v102, v103, v102, v154
	v_sub_f32_e32 v104, v104, v102
	v_mul_f32_e32 v104, 0x3fb8aa3b, v104
	v_sub_f32_e32 v89, v89, v102
	v_exp_f32_e32 v104, v104
	v_mul_f32_e32 v89, 0x3fb8aa3b, v89
	v_sub_f32_e32 v88, v88, v102
	v_exp_f32_e32 v89, v89
	v_mul_f32_e32 v88, 0x3fb8aa3b, v88
	v_sub_f32_e32 v85, v85, v102
	v_exp_f32_e32 v88, v88
	v_mul_f32_e32 v85, 0x3fb8aa3b, v85
	v_sub_f32_e32 v67, v67, v102
	v_exp_f32_e32 v85, v85
	v_mul_f32_e32 v67, 0x3fb8aa3b, v67
	v_sub_f32_e32 v66, v66, v102
	v_add_f32_e32 v154, 0, v104
	v_exp_f32_e32 v67, v67
	v_mul_f32_e32 v66, 0x3fb8aa3b, v66
	v_sub_f32_e32 v65, v65, v102
	v_add_f32_e32 v154, v89, v154
	v_exp_f32_e32 v66, v66
	v_mul_f32_e32 v65, 0x3fb8aa3b, v65
	v_sub_f32_e32 v64, v64, v102
	v_sub_f32_e32 v103, v103, v102
	v_add_f32_e32 v154, v88, v154
	v_exp_f32_e32 v65, v65
	v_mul_f32_e32 v64, 0x3fb8aa3b, v64
	v_mul_f32_e32 v103, 0x3fb8aa3b, v103
	v_add_f32_e32 v154, v85, v154
	v_exp_f32_e32 v155, v64
	v_add_f32_e32 v154, v67, v154
	v_exp_f32_e32 v64, v103
	v_add_f32_e32 v154, v66, v154
	v_add_f32_e32 v154, v65, v154
	v_add_f32_e32 v154, v155, v154
	v_fmac_f32_e32 v154, v90, v64
	v_pk_mul_f32 v[62:63], v[62:63], v[64:65] op_sel_hi:[1,0]
	v_pk_mul_f32 v[60:61], v[60:61], v[64:65] op_sel_hi:[1,0]
	v_pk_mul_f32 v[58:59], v[58:59], v[64:65] op_sel_hi:[1,0]
	v_pk_mul_f32 v[56:57], v[56:57], v[64:65] op_sel_hi:[1,0]
	v_pk_mul_f32 v[54:55], v[54:55], v[64:65] op_sel_hi:[1,0]
	v_pk_mul_f32 v[52:53], v[52:53], v[64:65] op_sel_hi:[1,0]
	v_pk_mul_f32 v[50:51], v[50:51], v[64:65] op_sel_hi:[1,0]
	v_pk_mul_f32 v[48:49], v[48:49], v[64:65] op_sel_hi:[1,0]
	v_bfe_u32 v64, v155, 16, 1
	v_bfe_u32 v90, v65, 16, 1
	v_cvt_pk_bf16_f32 v66, v67, v66
	v_bfe_u32 v157, v85, 16, 1
	v_bfe_u32 v158, v88, 16, 1
	v_bfe_u32 v159, v89, 16, 1
	v_bfe_u32 v160, v104, 16, 1
	v_add3_u32 v104, v104, v160, s80
	v_add3_u32 v89, v89, v159, s80
	v_add3_u32 v88, v88, v158, s80
	v_add3_u32 v85, v85, v157, s80
	v_add3_u32 v65, v65, v90, s80
	v_add3_u32 v64, v155, v64, s80
	v_accvgpr_write_b32 a0, v60
	v_perm_b32 v67, v64, v65, s4
	v_perm_b32 v65, v85, v88, s4
	v_perm_b32 v64, v89, v104, s4
	v_accvgpr_write_b32 a1, v61
	v_accvgpr_write_b32 a2, v62
	v_accvgpr_write_b32 a3, v63
	v_mov_b32_e32 v90, v154
	s_waitcnt vmcnt(18)
	v_mfma_f32_16x16x32_bf16 a[32:35], v[134:137], v[64:67], a[0:3]
	s_nop 2
	v_accvgpr_write_b32 a0, v56
	v_accvgpr_write_b32 a1, v57
	v_accvgpr_write_b32 a2, v58
	v_accvgpr_write_b32 a3, v59
	s_waitcnt vmcnt(16)
	s_nop 0
	v_mfma_f32_16x16x32_bf16 a[36:39], v[130:133], v[64:67], a[0:3]
	s_nop 2
	v_accvgpr_write_b32 a0, v52
	v_accvgpr_write_b32 a1, v53
	v_accvgpr_write_b32 a2, v54
	v_accvgpr_write_b32 a3, v55
	s_waitcnt vmcnt(14)
	s_nop 0
	v_mfma_f32_16x16x32_bf16 a[40:43], v[126:129], v[64:67], a[0:3]
	s_nop 2
	v_accvgpr_write_b32 a0, v48
	v_accvgpr_write_b32 a1, v49
	v_accvgpr_write_b32 a2, v50
	v_accvgpr_write_b32 a3, v51
	s_waitcnt vmcnt(12)
	s_nop 0
	v_mfma_f32_16x16x32_bf16 a[44:47], v[122:125], v[64:67], a[0:3]
	s_add_i32 s4, s83, s71
	s_add_i32 s4, s4, 1
	s_cmp_lt_u32 s4, s33
	s_cbranch_scc0 .LBB0_489
	s_branch .LBB0_508

.LBB0_507:
	s_nop 4
	v_accvgpr_read_b32 v23, a0
	v_accvgpr_read_b32 v22, a1
	v_accvgpr_read_b32 v21, a2
	v_accvgpr_read_b32 v20, a3
	v_max_f32_e32 v24, v22, v22
	v_max_f32_e32 v25, v23, v23
	v_accvgpr_read_b32 v17, a6
	v_accvgpr_read_b32 v16, a7
	v_max_f32_e32 v24, v25, v24
	v_max_f32_e32 v25, v20, v20
	v_max_f32_e32 v26, v21, v21
	v_max_f32_e32 v25, v26, v25
	v_max_f32_e32 v26, v16, v16
	v_max_f32_e32 v27, v17, v17
	v_accvgpr_read_b32 v19, a4
	v_accvgpr_read_b32 v18, a5
	v_max_f32_e32 v26, v27, v26
	v_max3_f32 v26, v19, v18, v26
	v_cmp_lt_i32_e32 vcc, v212, v210
	v_max3_f32 v24, v24, v25, v26
	s_mov_b32 s4, 0x7060302
	v_cndmask_b32_e32 v25, v209, v212, vcc
	v_lshlrev_b32_e32 v25, 2, v25
	ds_bpermute_b32 v25, v25, v24
	v_cmp_lt_i32_e32 vcc, v211, v210
	s_waitcnt lgkmcnt(0)
	v_max_f32_e32 v25, v25, v25
	v_max_f32_e32 v24, v24, v25
	v_cndmask_b32_e32 v25, v209, v211, vcc
	v_lshlrev_b32_e32 v25, 2, v25
	ds_bpermute_b32 v25, v25, v24
	s_waitcnt lgkmcnt(0)
	v_max3_f32 v48, v105, v24, v25
	v_sub_f32_e32 v23, v23, v48
	v_mul_f32_e32 v23, 0x3fb8aa3b, v23
	v_sub_f32_e32 v22, v22, v48
	v_exp_f32_e32 v49, v23
	v_mul_f32_e32 v22, 0x3fb8aa3b, v22
	v_sub_f32_e32 v21, v21, v48
	v_exp_f32_e32 v50, v22
	v_mul_f32_e32 v21, 0x3fb8aa3b, v21
	v_sub_f32_e32 v20, v20, v48
	v_exp_f32_e32 v51, v21
	v_mul_f32_e32 v20, 0x3fb8aa3b, v20
	v_sub_f32_e32 v19, v19, v48
	v_exp_f32_e32 v52, v20
	v_mul_f32_e32 v19, 0x3fb8aa3b, v19
	v_sub_f32_e32 v18, v18, v48
	v_add_f32_e32 v23, 0, v49
	v_exp_f32_e32 v53, v19
	v_mul_f32_e32 v18, 0x3fb8aa3b, v18
	v_sub_f32_e32 v17, v17, v48
	v_add_f32_e32 v22, v50, v23
	v_exp_f32_e32 v54, v18
	v_mul_f32_e32 v17, 0x3fb8aa3b, v17
	v_sub_f32_e32 v16, v16, v48
	v_sub_f32_e32 v24, v105, v48
	v_add_f32_e32 v21, v51, v22
	v_exp_f32_e32 v55, v17
	v_mul_f32_e32 v16, 0x3fb8aa3b, v16
	v_mul_f32_e32 v24, 0x3fb8aa3b, v24
	v_add_f32_e32 v20, v52, v21
	v_exp_f32_e32 v56, v16
	v_add_f32_e32 v19, v53, v20
	v_exp_f32_e32 v28, v24
	v_add_f32_e32 v18, v54, v19
	v_add_f32_e32 v17, v55, v18
	v_add_f32_e32 v57, v56, v17
	v_fmac_f32_e32 v57, v91, v28
	v_pk_mul_f32 v[18:19], v[46:47], v[28:29] op_sel_hi:[1,0]
	v_pk_mul_f32 v[16:17], v[44:45], v[28:29] op_sel_hi:[1,0]
	v_pk_mul_f32 v[22:23], v[42:43], v[28:29] op_sel_hi:[1,0]
	v_pk_mul_f32 v[20:21], v[40:41], v[28:29] op_sel_hi:[1,0]
	v_pk_mul_f32 v[26:27], v[38:39], v[28:29] op_sel_hi:[1,0]
	v_pk_mul_f32 v[24:25], v[36:37], v[28:29] op_sel_hi:[1,0]
	v_pk_mul_f32 v[30:31], v[34:35], v[28:29] op_sel_hi:[1,0]
	v_pk_mul_f32 v[28:29], v[32:33], v[28:29] op_sel_hi:[1,0]
	v_cvt_pk_bf16_f32 v34, v53, v54
	v_accvgpr_write_b32 a0, v16
	v_cvt_pk_bf16_f32 v35, v55, v56
	v_cvt_pk_bf16_f32 v33, v51, v52
	v_cvt_pk_bf16_f32 v32, v49, v50
	v_accvgpr_write_b32 a1, v17
	v_accvgpr_write_b32 a2, v18
	v_accvgpr_write_b32 a3, v19
	v_mov_b32_e32 v91, v57
	v_mov_b32_e32 v105, v48
	s_waitcnt vmcnt(18)
	v_mfma_f32_16x16x32_bf16 a[16:19], v[134:137], v[32:35], a[0:3]
	s_nop 2
	v_accvgpr_write_b32 a0, v20
	v_accvgpr_write_b32 a1, v21
	v_accvgpr_write_b32 a2, v22
	v_accvgpr_write_b32 a3, v23
	s_waitcnt vmcnt(16)
	s_nop 0
	v_mfma_f32_16x16x32_bf16 a[20:23], v[130:133], v[32:35], a[0:3]
	s_nop 2
	v_accvgpr_write_b32 a0, v24
	v_accvgpr_write_b32 a1, v25
	v_accvgpr_write_b32 a2, v26
	v_accvgpr_write_b32 a3, v27
	s_waitcnt vmcnt(14)
	s_nop 0
	v_mfma_f32_16x16x32_bf16 a[24:27], v[126:129], v[32:35], a[0:3]
	s_nop 2
	v_accvgpr_write_b32 a0, v28
	v_accvgpr_write_b32 a1, v29
	v_accvgpr_write_b32 a2, v30
	v_accvgpr_write_b32 a3, v31
	s_waitcnt vmcnt(12)
	s_nop 0
	v_mfma_f32_16x16x32_bf16 a[28:31], v[122:125], v[32:35], a[0:3]

.LBB0_550:
	s_or_b64 exec, exec, s[18:19]
	v_accvgpr_read_b32 v175, a114
	v_accvgpr_read_b32 v174, a112
	v_accvgpr_read_b32 v173, a115
	v_accvgpr_read_b32 v172, a113
	v_pk_mul_f32 v[174:175], v[16:17], v[174:175] op_sel_hi:[0,1]
	v_pk_mul_f32 v[172:173], v[16:17], v[172:173] op_sel_hi:[0,1]
	v_cvt_pk_bf16_f32 v172, v174, v172
	v_accvgpr_read_b32 v171, a118
	v_accvgpr_read_b32 v170, a116
	v_accvgpr_read_b32 v169, a119
	v_accvgpr_read_b32 v168, a117
	v_pk_mul_f32 v[170:171], v[16:17], v[170:171] op_sel_hi:[0,1]
	v_pk_mul_f32 v[168:169], v[16:17], v[168:169] op_sel_hi:[0,1]
	v_cvt_pk_bf16_f32 v173, v175, v173
	v_cvt_pk_bf16_f32 v168, v170, v168
	v_accvgpr_read_b32 v167, a122
	v_accvgpr_read_b32 v166, a120
	v_accvgpr_read_b32 v165, a123
	v_accvgpr_read_b32 v164, a121
	v_pk_mul_f32 v[166:167], v[16:17], v[166:167] op_sel_hi:[0,1]
	s_and_b64 s[0:1], vcc, exec
	v_cvt_pk_bf16_f32 v169, v171, v169
	v_pk_mul_f32 v[164:165], v[16:17], v[164:165] op_sel_hi:[0,1]
	s_mov_b32 s0, 0x9350000
	v_cvt_pk_bf16_f32 v164, v166, v164
	v_accvgpr_read_b32 v163, a126
	v_accvgpr_read_b32 v162, a124
	s_cselect_b32 s0, s0, 0x9fb0000
	v_accvgpr_read_b32 v161, a127
	v_accvgpr_read_b32 v160, a125
	s_add_u32 s0, s90, s0
	v_cvt_pk_bf16_f32 v165, v167, v165
	v_pk_mul_f32 v[162:163], v[16:17], v[162:163] op_sel_hi:[0,1]
	s_addc_u32 s1, s91, 0
	v_pk_mul_f32 v[160:161], v[16:17], v[160:161] op_sel_hi:[0,1]
	v_mov_b64_e32 v[178:179], s[0:1]
	s_movk_i32 s0, 0x300
	v_cvt_pk_bf16_f32 v160, v162, v160
	v_mad_i64_i32 v[178:179], s[0:1], v176, s0, v[178:179]
	v_cvt_pk_bf16_f32 v161, v163, v161
	v_lshl_add_u64 v[178:179], v[194:195], 1, v[178:179]
	v_lshlrev_b32_e32 v192, 1, v202
	v_lshl_add_u64 v[178:179], v[178:179], 0, v[192:193]
	global_store_dwordx2 v[178:179], v[172:173], off
	global_store_dwordx2 v[178:179], v[168:169], off offset:16
	global_store_dwordx2 v[178:179], v[164:165], off offset:32
	global_store_dwordx2 v[178:179], v[160:161], off offset:48

.LBB0_552:
	s_andn2_saveexec_b64 s[8:9], s[14:15]
	s_cbranch_execz .LBB0_554
	v_ashrrev_i32_e32 v177, 31, v176
	v_lshlrev_b64 v[178:179], 9, v[176:177]
	v_lshl_add_u64 v[178:179], s[90:91], 0, v[178:179]
	v_mov_b32_e32 v197, v193
	v_and_b32_sdwa v144, v163, v218 dst_sel:DWORD dst_unused:UNUSED_PAD src0_sel:WORD_1 src1_sel:DWORD
	v_cvt_pk_bf16_f32 v160, v160, v161
	v_lshl_add_u64 v[178:179], v[196:197], 1, v[178:179]
	v_and_b32_sdwa v48, v162, v218 dst_sel:DWORD dst_unused:UNUSED_PAD src0_sel:WORD_1 src1_sel:DWORD
	v_add3_u32 v144, v163, v144, s80
	s_mov_b32 s0, 0x8b0f000
	v_add3_u32 v48, v162, v48, s80
	v_and_b32_e32 v144, 0xffff0000, v144
	v_add_co_u32_e64 v162, s[0:1], s0, v178
	v_or_b32_sdwa v161, v144, v48 dst_sel:DWORD dst_unused:UNUSED_PAD src0_sel:DWORD src1_sel:WORD_1
	s_nop 0
	v_addc_co_u32_e64 v163, s[0:1], 0, v179, s[0:1]
	global_store_dwordx2 v[162:163], v[160:161], off offset:3328
	v_cvt_pk_bf16_f32 v161, v166, v167
	v_cvt_pk_bf16_f32 v160, v164, v165
	global_store_dwordx2 v[162:163], v[160:161], off offset:3344
	v_cvt_pk_bf16_f32 v161, v170, v171
	v_cvt_pk_bf16_f32 v160, v168, v169
	global_store_dwordx2 v[162:163], v[160:161], off offset:3360
	v_cvt_pk_bf16_f32 v161, v174, v175
	v_cvt_pk_bf16_f32 v160, v172, v173
	global_store_dwordx2 v[162:163], v[160:161], off offset:3376

.LBB0_555:
	s_or_saveexec_b64 s[8:9], s[12:13]
	v_lshlrev_b16_e32 v48, 2, v239
	v_ashrrev_i32_e32 v80, 5, v176
	v_lshrrev_b32_e32 v184, 4, v112
	v_lshlrev_b32_e32 v180, 5, v207
	v_lshlrev_b32_e32 v178, 1, v202
	v_lshlrev_b32_e32 v182, 1, v48
	s_xor_b64 exec, exec, s[8:9]
	s_cbranch_execz .LBB0_557
	s_movk_i32 s0, 0x210
	v_mad_u64_u32 v[186:187], s[0:1], v184, s0, v[80:81]
	v_readlane_b32 s0, v254, 7
	v_readlane_b32 s1, v254, 8
	v_and_b32_sdwa v48, v162, v218 dst_sel:DWORD dst_unused:UNUSED_PAD src0_sel:WORD_1 src1_sel:DWORD
	v_and_b32_sdwa v144, v160, v218 dst_sel:DWORD dst_unused:UNUSED_PAD src0_sel:WORD_1 src1_sel:DWORD
	v_mov_b64_e32 v[188:189], s[0:1]
	v_add3_u32 v144, v160, v144, s80
	v_add3_u32 v48, v162, v48, s80
	v_and_b32_sdwa v160, v163, v218 dst_sel:DWORD dst_unused:UNUSED_PAD src0_sel:WORD_1 src1_sel:DWORD
	v_and_b32_sdwa v162, v161, v218 dst_sel:DWORD dst_unused:UNUSED_PAD src0_sel:WORD_1 src1_sel:DWORD
	v_mad_i64_i32 v[190:191], s[0:1], v186, s68, v[188:189]
	v_mov_b32_e32 v181, v193
	v_add3_u32 v160, v163, v160, s80
	v_add3_u32 v161, v161, v162, s80
	v_lshl_add_u64 v[190:191], v[190:191], 0, v[180:181]
	v_mov_b32_e32 v179, v193
	v_and_b32_e32 v160, 0xffff0000, v160
	v_and_b32_e32 v162, 0xffff0000, v161
	v_lshl_add_u64 v[190:191], v[190:191], 0, v[178:179]
	v_or_b32_sdwa v161, v160, v48 dst_sel:DWORD dst_unused:UNUSED_PAD src0_sel:DWORD src1_sel:WORD_1
	v_or_b32_sdwa v160, v162, v144 dst_sel:DWORD dst_unused:UNUSED_PAD src0_sel:DWORD src1_sel:WORD_1
	global_store_dwordx2 v[190:191], v[160:161], off
	v_mov_b64_e32 v[160:161], s[90:91]
	v_mad_i64_i32 v[160:161], s[0:1], v186, s68, v[160:161]
	v_lshl_add_u64 v[160:161], v[160:161], 0, v[180:181]
	v_and_b32_sdwa v163, v165, v218 dst_sel:DWORD dst_unused:UNUSED_PAD src0_sel:WORD_1 src1_sel:DWORD
	v_lshl_add_u64 v[160:161], v[160:161], 0, v[178:179]
	v_and_b32_sdwa v144, v164, v218 dst_sel:DWORD dst_unused:UNUSED_PAD src0_sel:WORD_1 src1_sel:DWORD
	v_add3_u32 v163, v165, v163, s80
	v_add3_u32 v144, v164, v144, s80
	v_and_b32_e32 v164, 0xffff0000, v163
	v_add_co_u32_e64 v160, s[0:1], s92, v160
	v_cvt_pk_bf16_f32 v163, v166, v167
	v_or_b32_sdwa v162, v164, v144 dst_sel:DWORD dst_unused:UNUSED_PAD src0_sel:DWORD src1_sel:WORD_1
	v_addc_co_u32_e64 v161, s[0:1], 0, v161, s[0:1]
	v_add_u32_e32 v48, 0x210, v186
	global_store_dwordx2 v[160:161], v[162:163], off offset:16
	v_mad_i64_i32 v[160:161], s[0:1], v48, s68, v[188:189]
	v_lshl_add_u64 v[160:161], v[160:161], 0, v[180:181]
	v_lshl_add_u64 v[162:163], v[160:161], 0, v[178:179]
	v_cvt_pk_bf16_f32 v165, v170, v171
	v_cvt_pk_bf16_f32 v164, v168, v169
	global_store_dwordx2 v[162:163], v[164:165], off
	v_mov_b32_e32 v183, v193
	v_lshl_add_u64 v[160:161], v[160:161], 0, v[182:183]
	v_cvt_pk_bf16_f32 v163, v174, v175
	v_cvt_pk_bf16_f32 v162, v172, v173
	global_store_dwordx2 v[160:161], v[162:163], off offset:16

.LBB0_580:
	s_or_b64 exec, exec, s[16:17]
	s_and_b64 s[0:1], vcc, exec
	s_mov_b32 s0, 0x9350000
	v_accvgpr_read_b32 v143, a98
	v_accvgpr_read_b32 v142, a96
	s_cselect_b32 s0, s0, 0x9fb0000
	v_accvgpr_read_b32 v141, a99
	v_accvgpr_read_b32 v140, a97
	s_add_u32 s0, s90, s0
	v_pk_mul_f32 v[142:143], v[16:17], v[142:143] op_sel_hi:[0,1]
	s_addc_u32 s1, s91, 0
	v_pk_mul_f32 v[140:141], v[16:17], v[140:141] op_sel_hi:[0,1]
	v_cvt_pk_bf16_f32 v140, v142, v140
	v_mov_b64_e32 v[146:147], s[0:1]
	s_movk_i32 s0, 0x300
	v_cvt_pk_bf16_f32 v141, v143, v141
	v_mad_i64_i32 v[146:147], s[0:1], v144, s0, v[146:147]
	v_accvgpr_read_b32 v139, a102
	v_accvgpr_read_b32 v138, a100
	v_lshl_add_u64 v[146:147], v[194:195], 1, v[146:147]
	v_mov_b32_e32 v179, v193
	v_accvgpr_read_b32 v137, a103
	v_accvgpr_read_b32 v136, a101
	v_lshl_add_u64 v[146:147], v[146:147], 0, v[178:179]
	v_pk_mul_f32 v[138:139], v[16:17], v[138:139] op_sel_hi:[0,1]
	global_store_dwordx2 v[146:147], v[140:141], off
	v_pk_mul_f32 v[136:137], v[16:17], v[136:137] op_sel_hi:[0,1]
	v_cvt_pk_bf16_f32 v136, v138, v136
	v_cvt_pk_bf16_f32 v137, v139, v137
	v_accvgpr_read_b32 v135, a106
	v_accvgpr_read_b32 v134, a104
	v_accvgpr_read_b32 v133, a107
	v_accvgpr_read_b32 v132, a105
	v_pk_mul_f32 v[134:135], v[16:17], v[134:135] op_sel_hi:[0,1]
	global_store_dwordx2 v[146:147], v[136:137], off offset:16
	v_pk_mul_f32 v[132:133], v[16:17], v[132:133] op_sel_hi:[0,1]
	v_cvt_pk_bf16_f32 v132, v134, v132
	v_cvt_pk_bf16_f32 v133, v135, v133
	v_accvgpr_read_b32 v131, a110
	v_accvgpr_read_b32 v130, a108
	v_accvgpr_read_b32 v129, a111
	v_accvgpr_read_b32 v128, a109
	v_pk_mul_f32 v[130:131], v[16:17], v[130:131] op_sel_hi:[0,1]
	global_store_dwordx2 v[146:147], v[132:133], off offset:32
	v_pk_mul_f32 v[128:129], v[16:17], v[128:129] op_sel_hi:[0,1]
	v_cvt_pk_bf16_f32 v128, v130, v128
	v_cvt_pk_bf16_f32 v129, v131, v129
	global_store_dwordx2 v[146:147], v[128:129], off offset:48

.LBB0_582:
	s_andn2_saveexec_b64 s[6:7], s[12:13]
	s_cbranch_execz .LBB0_584
	v_ashrrev_i32_e32 v145, 31, v144
	v_and_b32_sdwa v48, v130, v218 dst_sel:DWORD dst_unused:UNUSED_PAD src0_sel:WORD_1 src1_sel:DWORD
	v_lshlrev_b64 v[146:147], 9, v[144:145]
	v_cvt_pk_bf16_f32 v128, v128, v129
	v_add3_u32 v48, v130, v48, s80
	v_and_b32_sdwa v130, v131, v218 dst_sel:DWORD dst_unused:UNUSED_PAD src0_sel:WORD_1 src1_sel:DWORD
	v_lshl_add_u64 v[146:147], s[90:91], 0, v[146:147]
	v_mov_b32_e32 v197, v193
	v_add3_u32 v130, v131, v130, s80
	v_lshl_add_u64 v[146:147], v[196:197], 1, v[146:147]
	v_and_b32_e32 v130, 0xffff0000, v130
	s_mov_b32 s0, 0x8b0f000
	v_or_b32_sdwa v129, v130, v48 dst_sel:DWORD dst_unused:UNUSED_PAD src0_sel:DWORD src1_sel:WORD_1
	v_add_co_u32_e64 v130, s[0:1], s0, v146
	s_nop 0
	s_nop 0
	v_addc_co_u32_e64 v131, s[0:1], 0, v147, s[0:1]
	global_store_dwordx2 v[130:131], v[128:129], off offset:3328
	v_cvt_pk_bf16_f32 v128, v132, v133
	v_cvt_pk_bf16_f32 v129, v134, v135
	global_store_dwordx2 v[130:131], v[128:129], off offset:3344
	v_cvt_pk_bf16_f32 v129, v138, v139
	v_cvt_pk_bf16_f32 v128, v136, v137
	global_store_dwordx2 v[130:131], v[128:129], off offset:3360
	v_cvt_pk_bf16_f32 v129, v142, v143
	v_cvt_pk_bf16_f32 v128, v140, v141
	global_store_dwordx2 v[130:131], v[128:129], off offset:3376

.LBB0_585:
	s_or_saveexec_b64 s[6:7], s[8:9]
	v_ashrrev_i32_e32 v48, 5, v144
	s_xor_b64 exec, exec, s[6:7]
	s_cbranch_execz .LBB0_587
	s_movk_i32 s0, 0x210
	v_mad_u64_u32 v[146:147], s[0:1], v184, s0, v[48:49]
	v_readlane_b32 s0, v254, 7
	v_readlane_b32 s1, v254, 8
	v_and_b32_sdwa v145, v130, v218 dst_sel:DWORD dst_unused:UNUSED_PAD src0_sel:WORD_1 src1_sel:DWORD
	v_cvt_pk_bf16_f32 v128, v128, v129
	v_mov_b64_e32 v[148:149], s[0:1]
	v_add3_u32 v130, v130, v145, s80
	v_and_b32_sdwa v145, v131, v218 dst_sel:DWORD dst_unused:UNUSED_PAD src0_sel:WORD_1 src1_sel:DWORD
	v_mad_i64_i32 v[150:151], s[0:1], v146, s68, v[148:149]
	v_mov_b32_e32 v181, v193
	v_add3_u32 v131, v131, v145, s80
	v_lshl_add_u64 v[150:151], v[150:151], 0, v[180:181]
	v_mov_b32_e32 v179, v193
	v_and_b32_e32 v131, 0xffff0000, v131
	v_lshl_add_u64 v[150:151], v[150:151], 0, v[178:179]
	v_or_b32_sdwa v129, v131, v130 dst_sel:DWORD dst_unused:UNUSED_PAD src0_sel:DWORD src1_sel:WORD_1
	global_store_dwordx2 v[150:151], v[128:129], off
	v_mov_b64_e32 v[128:129], s[90:91]
	v_mad_i64_i32 v[128:129], s[0:1], v146, s68, v[128:129]
	v_and_b32_sdwa v131, v132, v218 dst_sel:DWORD dst_unused:UNUSED_PAD src0_sel:WORD_1 src1_sel:DWORD
	v_lshl_add_u64 v[128:129], v[128:129], 0, v[180:181]
	v_add3_u32 v132, v132, v131, s80
	v_cvt_pk_bf16_f32 v131, v134, v135
	v_and_b32_sdwa v134, v133, v218 dst_sel:DWORD dst_unused:UNUSED_PAD src0_sel:WORD_1 src1_sel:DWORD
	v_lshl_add_u64 v[128:129], v[128:129], 0, v[178:179]
	v_add3_u32 v133, v133, v134, s80
	v_and_b32_e32 v133, 0xffff0000, v133
	v_add_co_u32_e64 v128, s[0:1], s92, v128
	v_or_b32_sdwa v130, v133, v132 dst_sel:DWORD dst_unused:UNUSED_PAD src0_sel:DWORD src1_sel:WORD_1
	s_nop 0
	v_addc_co_u32_e64 v129, s[0:1], 0, v129, s[0:1]
	global_store_dwordx2 v[128:129], v[130:131], off offset:16
	v_add_u32_e32 v128, 0x210, v146
	v_mad_i64_i32 v[128:129], s[0:1], v128, s68, v[148:149]
	v_cvt_pk_bf16_f32 v131, v138, v139
	v_lshl_add_u64 v[128:129], v[128:129], 0, v[180:181]
	v_mov_b32_e32 v183, v193
	v_lshl_add_u64 v[128:129], v[128:129], 0, v[182:183]
	v_cvt_pk_bf16_f32 v130, v136, v137
	global_store_dwordx2 v[128:129], v[130:131], off
	v_cvt_pk_bf16_f32 v131, v142, v143
	v_cvt_pk_bf16_f32 v130, v140, v141
	global_store_dwordx2 v[128:129], v[130:131], off offset:16

.LBB0_610:
	s_or_b64 exec, exec, s[18:19]
	s_and_b64 s[0:1], vcc, exec
	s_mov_b32 s0, 0x9350000
	s_cselect_b32 s0, s0, 0x9fb0000
	s_add_u32 s0, s90, s0
	s_addc_u32 s1, s91, 0
	v_accvgpr_read_b32 v111, a82
	v_accvgpr_read_b32 v110, a80
	v_mov_b64_e32 v[114:115], s[0:1]
	s_movk_i32 s0, 0x300
	s_ashr_i32 s11, s10, 31
	v_ashrrev_i32_e32 v113, 31, v112
	v_accvgpr_read_b32 v109, a83
	v_accvgpr_read_b32 v108, a81
	v_mad_i64_i32 v[114:115], s[0:1], v176, s0, v[114:115]
	v_lshl_add_u64 v[116:117], v[112:113], 0, s[10:11]
	v_pk_mul_f32 v[110:111], v[16:17], v[110:111] op_sel_hi:[0,1]
	v_lshl_add_u64 v[114:115], v[116:117], 1, v[114:115]
	v_pk_mul_f32 v[108:109], v[16:17], v[108:109] op_sel_hi:[0,1]
	v_cvt_pk_bf16_f32 v109, v111, v109
	v_cvt_pk_bf16_f32 v108, v110, v108
	v_accvgpr_read_b32 v107, a86
	v_accvgpr_read_b32 v106, a84
	v_mov_b32_e32 v179, v193
	v_accvgpr_read_b32 v105, a87
	v_accvgpr_read_b32 v104, a85
	v_lshl_add_u64 v[114:115], v[114:115], 0, v[178:179]
	v_pk_mul_f32 v[106:107], v[16:17], v[106:107] op_sel_hi:[0,1]
	global_store_dwordx2 v[114:115], v[108:109], off offset:64
	v_pk_mul_f32 v[104:105], v[16:17], v[104:105] op_sel_hi:[0,1]
	v_cvt_pk_bf16_f32 v105, v107, v105
	v_cvt_pk_bf16_f32 v104, v106, v104
	v_accvgpr_read_b32 v103, a90
	v_accvgpr_read_b32 v102, a88
	v_accvgpr_read_b32 v101, a91
	v_accvgpr_read_b32 v100, a89
	v_pk_mul_f32 v[102:103], v[16:17], v[102:103] op_sel_hi:[0,1]
	global_store_dwordx2 v[114:115], v[104:105], off offset:80
	v_pk_mul_f32 v[100:101], v[16:17], v[100:101] op_sel_hi:[0,1]
	v_cvt_pk_bf16_f32 v101, v103, v101
	v_cvt_pk_bf16_f32 v100, v102, v100
	v_accvgpr_read_b32 v99, a94
	v_accvgpr_read_b32 v98, a92
	v_accvgpr_read_b32 v97, a95
	v_accvgpr_read_b32 v96, a93
	v_pk_mul_f32 v[98:99], v[16:17], v[98:99] op_sel_hi:[0,1]
	global_store_dwordx2 v[114:115], v[100:101], off offset:96
	v_pk_mul_f32 v[96:97], v[16:17], v[96:97] op_sel_hi:[0,1]
	v_cvt_pk_bf16_f32 v97, v99, v97
	v_cvt_pk_bf16_f32 v96, v98, v96
	global_store_dwordx2 v[114:115], v[96:97], off offset:112

.LBB0_612:
	s_andn2_saveexec_b64 s[8:9], s[14:15]
	s_cbranch_execz .LBB0_614
	v_ashrrev_i32_e32 v177, 31, v176
	v_and_b32_sdwa v113, v98, v218 dst_sel:DWORD dst_unused:UNUSED_PAD src0_sel:WORD_1 src1_sel:DWORD
	v_lshlrev_b64 v[114:115], 9, v[176:177]
	v_cvt_pk_bf16_f32 v96, v96, v97
	v_add3_u32 v98, v98, v113, s80
	v_and_b32_sdwa v113, v99, v218 dst_sel:DWORD dst_unused:UNUSED_PAD src0_sel:WORD_1 src1_sel:DWORD
	v_lshl_add_u64 v[114:115], s[90:91], 0, v[114:115]
	v_add_u32_e32 v192, v112, v202
	v_add3_u32 v99, v99, v113, s80
	v_lshl_add_u64 v[114:115], v[192:193], 1, v[114:115]
	v_and_b32_e32 v99, 0xffff0000, v99
	s_mov_b32 s0, 0x8b0f000
	v_or_b32_sdwa v97, v99, v98 dst_sel:DWORD dst_unused:UNUSED_PAD src0_sel:DWORD src1_sel:WORD_1
	v_add_co_u32_e64 v98, s[0:1], s0, v114
	s_nop 0
	s_nop 0
	v_addc_co_u32_e64 v99, s[0:1], 0, v115, s[0:1]
	global_store_dwordx2 v[98:99], v[96:97], off offset:3392
	v_and_b32_sdwa v97, v100, v218 dst_sel:DWORD dst_unused:UNUSED_PAD src0_sel:WORD_1 src1_sel:DWORD
	v_add3_u32 v100, v100, v97, s80
	v_cvt_pk_bf16_f32 v97, v102, v103
	v_and_b32_sdwa v102, v101, v218 dst_sel:DWORD dst_unused:UNUSED_PAD src0_sel:WORD_1 src1_sel:DWORD
	v_add3_u32 v101, v101, v102, s80
	v_and_b32_e32 v101, 0xffff0000, v101
	v_or_b32_sdwa v96, v101, v100 dst_sel:DWORD dst_unused:UNUSED_PAD src0_sel:DWORD src1_sel:WORD_1
	global_store_dwordx2 v[98:99], v[96:97], off offset:3408
	v_cvt_pk_bf16_f32 v97, v106, v107
	v_cvt_pk_bf16_f32 v96, v104, v105
	global_store_dwordx2 v[98:99], v[96:97], off offset:3424
	v_cvt_pk_bf16_f32 v97, v110, v111
	v_cvt_pk_bf16_f32 v96, v108, v109
	global_store_dwordx2 v[98:99], v[96:97], off offset:3440

.LBB0_618:
	s_movk_i32 s0, 0x210
	v_mad_u64_u32 v[82:83], s[0:1], v113, s0, v[48:49]
	v_readlane_b32 s0, v254, 7
	v_readlane_b32 s1, v254, 8
	v_and_b32_sdwa v81, v66, v218 dst_sel:DWORD dst_unused:UNUSED_PAD src0_sel:WORD_1 src1_sel:DWORD
	v_cvt_pk_bf16_f32 v64, v64, v65
	v_mov_b64_e32 v[84:85], s[0:1]
	v_add3_u32 v66, v66, v81, s80
	v_and_b32_sdwa v81, v67, v218 dst_sel:DWORD dst_unused:UNUSED_PAD src0_sel:WORD_1 src1_sel:DWORD
	v_mad_i64_i32 v[86:87], s[0:1], v82, s68, v[84:85]
	v_mov_b32_e32 v181, v193
	v_add3_u32 v67, v67, v81, s80
	v_lshl_add_u64 v[86:87], v[86:87], 0, v[180:181]
	v_mov_b32_e32 v179, v193
	v_and_b32_e32 v67, 0xffff0000, v67
	v_lshl_add_u64 v[86:87], v[86:87], 0, v[178:179]
	v_or_b32_sdwa v65, v67, v66 dst_sel:DWORD dst_unused:UNUSED_PAD src0_sel:DWORD src1_sel:WORD_1
	global_store_dwordx2 v[86:87], v[64:65], off
	v_mov_b64_e32 v[64:65], s[90:91]
	v_mad_i64_i32 v[64:65], s[0:1], v82, s68, v[64:65]
	v_and_b32_sdwa v67, v68, v218 dst_sel:DWORD dst_unused:UNUSED_PAD src0_sel:WORD_1 src1_sel:DWORD
	v_lshl_add_u64 v[64:65], v[64:65], 0, v[180:181]
	v_add3_u32 v68, v68, v67, s80
	v_cvt_pk_bf16_f32 v67, v70, v71
	v_and_b32_sdwa v70, v69, v218 dst_sel:DWORD dst_unused:UNUSED_PAD src0_sel:WORD_1 src1_sel:DWORD
	v_lshl_add_u64 v[64:65], v[64:65], 0, v[178:179]
	v_add3_u32 v69, v69, v70, s80
	v_and_b32_e32 v69, 0xffff0000, v69
	v_add_co_u32_e64 v64, s[0:1], s92, v64
	v_or_b32_sdwa v66, v69, v68 dst_sel:DWORD dst_unused:UNUSED_PAD src0_sel:DWORD src1_sel:WORD_1
	s_nop 0
	v_addc_co_u32_e64 v65, s[0:1], 0, v65, s[0:1]
	global_store_dwordx2 v[64:65], v[66:67], off offset:16
	s_movk_i32 s0, 0x630
	v_add3_u32 v64, v48, v114, s0
	v_mad_i64_i32 v[64:65], s[0:1], v64, s68, v[84:85]
	v_cvt_pk_bf16_f32 v67, v74, v75
	v_lshl_add_u64 v[64:65], v[64:65], 0, v[180:181]
	v_mov_b32_e32 v183, v193
	v_lshl_add_u64 v[64:65], v[64:65], 0, v[182:183]
	v_cvt_pk_bf16_f32 v66, v72, v73
	global_store_dwordx2 v[64:65], v[66:67], off
	v_cvt_pk_bf16_f32 v67, v78, v79
	v_cvt_pk_bf16_f32 v66, v76, v77
	global_store_dwordx2 v[64:65], v[66:67], off offset:16

.LBB0_623:
	s_movk_i32 s0, 0x210
	v_mad_u64_u32 v[18:19], s[0:1], v49, s0, v[48:49]
	v_readlane_b32 s0, v254, 7
	v_readlane_b32 s1, v254, 8
	v_and_b32_sdwa v17, v2, v218 dst_sel:DWORD dst_unused:UNUSED_PAD src0_sel:WORD_1 src1_sel:DWORD
	v_cvt_pk_bf16_f32 v0, v0, v1
	v_mov_b64_e32 v[20:21], s[0:1]
	v_add3_u32 v2, v2, v17, s80
	v_and_b32_sdwa v17, v3, v218 dst_sel:DWORD dst_unused:UNUSED_PAD src0_sel:WORD_1 src1_sel:DWORD
	v_mad_i64_i32 v[22:23], s[0:1], v18, s68, v[20:21]
	v_mov_b32_e32 v181, v193
	v_add3_u32 v3, v3, v17, s80
	v_lshl_add_u64 v[22:23], v[22:23], 0, v[180:181]
	v_mov_b32_e32 v179, v193
	v_and_b32_e32 v3, 0xffff0000, v3
	v_lshl_add_u64 v[22:23], v[22:23], 0, v[178:179]
	v_or_b32_sdwa v1, v3, v2 dst_sel:DWORD dst_unused:UNUSED_PAD src0_sel:DWORD src1_sel:WORD_1
	global_store_dwordx2 v[22:23], v[0:1], off
	v_mov_b64_e32 v[0:1], s[90:91]
	v_mad_i64_i32 v[0:1], s[0:1], v18, s68, v[0:1]
	v_and_b32_sdwa v3, v4, v218 dst_sel:DWORD dst_unused:UNUSED_PAD src0_sel:WORD_1 src1_sel:DWORD
	v_lshl_add_u64 v[0:1], v[0:1], 0, v[180:181]
	v_add3_u32 v4, v4, v3, s80
	v_cvt_pk_bf16_f32 v3, v6, v7
	v_and_b32_sdwa v6, v5, v218 dst_sel:DWORD dst_unused:UNUSED_PAD src0_sel:WORD_1 src1_sel:DWORD
	v_lshl_add_u64 v[0:1], v[0:1], 0, v[178:179]
	v_add3_u32 v5, v5, v6, s80
	v_and_b32_e32 v5, 0xffff0000, v5
	v_add_co_u32_e64 v0, s[0:1], s92, v0
	v_or_b32_sdwa v2, v5, v4 dst_sel:DWORD dst_unused:UNUSED_PAD src0_sel:DWORD src1_sel:WORD_1
	s_nop 0
	v_addc_co_u32_e64 v1, s[0:1], 0, v1, s[0:1]
	global_store_dwordx2 v[0:1], v[2:3], off offset:16
	s_movk_i32 s0, 0xa50
	v_add3_u32 v0, v48, v114, s0
	v_mad_i64_i32 v[0:1], s[0:1], v0, s68, v[20:21]
	v_cvt_pk_bf16_f32 v3, v10, v11
	v_lshl_add_u64 v[0:1], v[0:1], 0, v[180:181]
	v_mov_b32_e32 v183, v193
	v_lshl_add_u64 v[0:1], v[0:1], 0, v[182:183]
	v_cvt_pk_bf16_f32 v2, v8, v9
	global_store_dwordx2 v[0:1], v[2:3], off
	v_cvt_pk_bf16_f32 v3, v14, v15
	v_cvt_pk_bf16_f32 v2, v12, v13
	global_store_dwordx2 v[0:1], v[2:3], off offset:16

.LBB0_647:
	s_or_b64 exec, exec, s[18:19]
	s_and_b64 s[0:1], vcc, exec
	s_mov_b32 s0, 0x9350000
	s_cselect_b32 s0, s0, 0x9fb0000
	s_add_u32 s0, s90, s0
	s_addc_u32 s1, s91, 0
	v_accvgpr_read_b32 v15, a34
	v_accvgpr_read_b32 v14, a32
	v_mov_b64_e32 v[18:19], s[0:1]
	s_movk_i32 s0, 0x300
	s_ashr_i32 s11, s10, 31
	v_ashrrev_i32_e32 v113, 31, v112
	v_accvgpr_read_b32 v13, a35
	v_accvgpr_read_b32 v12, a33
	v_mad_i64_i32 v[18:19], s[0:1], v176, s0, v[18:19]
	v_lshl_add_u64 v[20:21], v[112:113], 0, s[10:11]
	v_pk_mul_f32 v[14:15], v[16:17], v[14:15] op_sel_hi:[0,1]
	v_lshl_add_u64 v[18:19], v[20:21], 1, v[18:19]
	v_pk_mul_f32 v[12:13], v[16:17], v[12:13] op_sel_hi:[0,1]
	v_cvt_pk_bf16_f32 v13, v15, v13
	v_cvt_pk_bf16_f32 v12, v14, v12
	v_accvgpr_read_b32 v11, a38
	v_accvgpr_read_b32 v10, a36
	v_mov_b32_e32 v179, v193
	v_accvgpr_read_b32 v9, a39
	v_accvgpr_read_b32 v8, a37
	v_lshl_add_u64 v[18:19], v[18:19], 0, v[178:179]
	v_pk_mul_f32 v[10:11], v[16:17], v[10:11] op_sel_hi:[0,1]
	global_store_dwordx2 v[18:19], v[12:13], off offset:192
	v_pk_mul_f32 v[8:9], v[16:17], v[8:9] op_sel_hi:[0,1]
	v_cvt_pk_bf16_f32 v9, v11, v9
	v_cvt_pk_bf16_f32 v8, v10, v8
	v_accvgpr_read_b32 v7, a42
	v_accvgpr_read_b32 v6, a40
	v_accvgpr_read_b32 v5, a43
	v_accvgpr_read_b32 v4, a41
	v_pk_mul_f32 v[6:7], v[16:17], v[6:7] op_sel_hi:[0,1]
	global_store_dwordx2 v[18:19], v[8:9], off offset:208
	v_pk_mul_f32 v[4:5], v[16:17], v[4:5] op_sel_hi:[0,1]
	v_cvt_pk_bf16_f32 v5, v7, v5
	v_cvt_pk_bf16_f32 v4, v6, v4
	v_accvgpr_read_b32 v3, a46
	v_accvgpr_read_b32 v2, a44
	v_accvgpr_read_b32 v1, a47
	v_accvgpr_read_b32 v0, a45
	v_pk_mul_f32 v[2:3], v[16:17], v[2:3] op_sel_hi:[0,1]
	global_store_dwordx2 v[18:19], v[4:5], off offset:224
	v_pk_mul_f32 v[0:1], v[16:17], v[0:1] op_sel_hi:[0,1]
	v_cvt_pk_bf16_f32 v1, v3, v1
	v_cvt_pk_bf16_f32 v0, v2, v0
	global_store_dwordx2 v[18:19], v[0:1], off offset:240

.LBB0_649:
	s_andn2_saveexec_b64 s[8:9], s[14:15]
	s_cbranch_execz .LBB0_651
	v_ashrrev_i32_e32 v177, 31, v176
	v_and_b32_sdwa v20, v2, v218 dst_sel:DWORD dst_unused:UNUSED_PAD src0_sel:WORD_1 src1_sel:DWORD
	v_lshlrev_b64 v[18:19], 9, v[176:177]
	v_cvt_pk_bf16_f32 v0, v0, v1
	v_add3_u32 v2, v2, v20, s80
	v_and_b32_sdwa v20, v3, v218 dst_sel:DWORD dst_unused:UNUSED_PAD src0_sel:WORD_1 src1_sel:DWORD
	v_lshl_add_u64 v[18:19], s[90:91], 0, v[18:19]
	v_add_u32_e32 v192, v112, v202
	v_add3_u32 v3, v3, v20, s80
	v_lshl_add_u64 v[18:19], v[192:193], 1, v[18:19]
	v_and_b32_e32 v3, 0xffff0000, v3
	s_mov_b32 s0, 0x8b0f000
	v_or_b32_sdwa v1, v3, v2 dst_sel:DWORD dst_unused:UNUSED_PAD src0_sel:DWORD src1_sel:WORD_1
	v_add_co_u32_e64 v2, s[0:1], s0, v18
	s_nop 0
	s_nop 0
	v_addc_co_u32_e64 v3, s[0:1], 0, v19, s[0:1]
	global_store_dwordx2 v[2:3], v[0:1], off offset:3520
	v_and_b32_sdwa v1, v4, v218 dst_sel:DWORD dst_unused:UNUSED_PAD src0_sel:WORD_1 src1_sel:DWORD
	v_add3_u32 v4, v4, v1, s80
	v_cvt_pk_bf16_f32 v1, v6, v7
	v_and_b32_sdwa v6, v5, v218 dst_sel:DWORD dst_unused:UNUSED_PAD src0_sel:WORD_1 src1_sel:DWORD
	v_add3_u32 v5, v5, v6, s80
	v_and_b32_e32 v5, 0xffff0000, v5
	v_or_b32_sdwa v0, v5, v4 dst_sel:DWORD dst_unused:UNUSED_PAD src0_sel:DWORD src1_sel:WORD_1
	global_store_dwordx2 v[2:3], v[0:1], off offset:3536
	v_cvt_pk_bf16_f32 v1, v10, v11
	v_cvt_pk_bf16_f32 v0, v8, v9
	global_store_dwordx2 v[2:3], v[0:1], off offset:3552
	v_cvt_pk_bf16_f32 v1, v14, v15
	v_cvt_pk_bf16_f32 v0, v12, v13
	global_store_dwordx2 v[2:3], v[0:1], off offset:3568

.LBB0_652:
	s_or_saveexec_b64 s[8:9], s[12:13]
	v_lshrrev_b32_e32 v17, 4, v17
	s_xor_b64 exec, exec, s[8:9]
	s_cbranch_execz .LBB0_654
	s_movk_i32 s0, 0x210
	v_mad_u64_u32 v[18:19], s[0:1], v17, s0, v[80:81]
	v_readlane_b32 s0, v254, 7
	v_readlane_b32 s1, v254, 8
	v_and_b32_sdwa v19, v2, v218 dst_sel:DWORD dst_unused:UNUSED_PAD src0_sel:WORD_1 src1_sel:DWORD
	v_cvt_pk_bf16_f32 v0, v0, v1
	v_mov_b64_e32 v[20:21], s[0:1]
	v_add3_u32 v2, v2, v19, s80
	v_and_b32_sdwa v19, v3, v218 dst_sel:DWORD dst_unused:UNUSED_PAD src0_sel:WORD_1 src1_sel:DWORD
	v_mad_i64_i32 v[22:23], s[0:1], v18, s68, v[20:21]
	v_mov_b32_e32 v181, v193
	v_add3_u32 v3, v3, v19, s80
	v_lshl_add_u64 v[22:23], v[22:23], 0, v[180:181]
	v_mov_b32_e32 v179, v193
	v_and_b32_e32 v3, 0xffff0000, v3
	v_lshl_add_u64 v[22:23], v[22:23], 0, v[178:179]
	v_or_b32_sdwa v1, v3, v2 dst_sel:DWORD dst_unused:UNUSED_PAD src0_sel:DWORD src1_sel:WORD_1
	global_store_dwordx2 v[22:23], v[0:1], off
	v_mov_b64_e32 v[0:1], s[90:91]
	v_mad_i64_i32 v[0:1], s[0:1], v18, s68, v[0:1]
	v_lshl_add_u64 v[0:1], v[0:1], 0, v[180:181]
	v_and_b32_sdwa v3, v4, v218 dst_sel:DWORD dst_unused:UNUSED_PAD src0_sel:WORD_1 src1_sel:DWORD
	v_lshl_add_u64 v[0:1], v[0:1], 0, v[178:179]
	v_add3_u32 v4, v4, v3, s80
	v_cvt_pk_bf16_f32 v3, v6, v7
	v_and_b32_sdwa v6, v5, v218 dst_sel:DWORD dst_unused:UNUSED_PAD src0_sel:WORD_1 src1_sel:DWORD
	v_add3_u32 v5, v5, v6, s80
	v_add_co_u32_e64 v0, s[0:1], s92, v0
	v_and_b32_e32 v5, 0xffff0000, v5
	s_nop 0
	v_addc_co_u32_e64 v1, s[0:1], 0, v1, s[0:1]
	v_or_b32_sdwa v2, v5, v4 dst_sel:DWORD dst_unused:UNUSED_PAD src0_sel:DWORD src1_sel:WORD_1
	s_movk_i32 s0, 0xe70
	global_store_dwordx2 v[0:1], v[2:3], off offset:16
	v_add3_u32 v0, v80, v114, s0
	v_mad_i64_i32 v[0:1], s[0:1], v0, s68, v[20:21]
	v_cvt_pk_bf16_f32 v5, v10, v11
	v_lshl_add_u64 v[0:1], v[0:1], 0, v[180:181]
	v_lshl_add_u64 v[2:3], v[0:1], 0, v[178:179]
	v_cvt_pk_bf16_f32 v4, v8, v9
	global_store_dwordx2 v[2:3], v[4:5], off
	v_cvt_pk_bf16_f32 v3, v14, v15
	v_mov_b32_e32 v183, v193
	v_lshl_add_u64 v[0:1], v[0:1], 0, v[182:183]
	v_cvt_pk_bf16_f32 v2, v12, v13
	global_store_dwordx2 v[0:1], v[2:3], off offset:16

.LBB0_656:
	v_mad_u64_u32 v[116:117], s[0:1], v113, s0, v[80:81]
	v_readlane_b32 s0, v254, 7
	v_readlane_b32 s1, v254, 8
	v_and_b32_sdwa v115, v98, v218 dst_sel:DWORD dst_unused:UNUSED_PAD src0_sel:WORD_1 src1_sel:DWORD
	v_cvt_pk_bf16_f32 v96, v96, v97
	v_mov_b64_e32 v[118:119], s[0:1]
	v_add3_u32 v98, v98, v115, s80
	v_and_b32_sdwa v115, v99, v218 dst_sel:DWORD dst_unused:UNUSED_PAD src0_sel:WORD_1 src1_sel:DWORD
	v_mad_i64_i32 v[120:121], s[0:1], v116, s68, v[118:119]
	v_mov_b32_e32 v181, v193
	v_add3_u32 v99, v99, v115, s80
	v_lshl_add_u64 v[120:121], v[120:121], 0, v[180:181]
	v_mov_b32_e32 v179, v193
	v_and_b32_e32 v99, 0xffff0000, v99
	v_lshl_add_u64 v[120:121], v[120:121], 0, v[178:179]
	v_or_b32_sdwa v97, v99, v98 dst_sel:DWORD dst_unused:UNUSED_PAD src0_sel:DWORD src1_sel:WORD_1
	global_store_dwordx2 v[120:121], v[96:97], off
	v_mov_b64_e32 v[96:97], s[90:91]
	v_mad_i64_i32 v[96:97], s[0:1], v116, s68, v[96:97]
	v_lshl_add_u64 v[96:97], v[96:97], 0, v[180:181]
	v_and_b32_sdwa v99, v100, v218 dst_sel:DWORD dst_unused:UNUSED_PAD src0_sel:WORD_1 src1_sel:DWORD
	v_lshl_add_u64 v[96:97], v[96:97], 0, v[178:179]
	v_add3_u32 v100, v100, v99, s80
	v_cvt_pk_bf16_f32 v99, v102, v103
	v_and_b32_sdwa v102, v101, v218 dst_sel:DWORD dst_unused:UNUSED_PAD src0_sel:WORD_1 src1_sel:DWORD
	v_add3_u32 v101, v101, v102, s80
	v_add_co_u32_e64 v96, s[0:1], s92, v96
	v_and_b32_e32 v101, 0xffff0000, v101
	s_nop 0
	v_addc_co_u32_e64 v97, s[0:1], 0, v97, s[0:1]
	v_or_b32_sdwa v98, v101, v100 dst_sel:DWORD dst_unused:UNUSED_PAD src0_sel:DWORD src1_sel:WORD_1
	s_movk_i32 s0, 0x630
	global_store_dwordx2 v[96:97], v[98:99], off offset:16
	v_add3_u32 v96, v80, v114, s0
	v_mad_i64_i32 v[96:97], s[0:1], v96, s68, v[118:119]
	v_cvt_pk_bf16_f32 v101, v106, v107
	v_lshl_add_u64 v[96:97], v[96:97], 0, v[180:181]
	v_lshl_add_u64 v[98:99], v[96:97], 0, v[178:179]
	v_cvt_pk_bf16_f32 v100, v104, v105
	global_store_dwordx2 v[98:99], v[100:101], off
	v_cvt_pk_bf16_f32 v99, v110, v111
	v_mov_b32_e32 v183, v193
	v_lshl_add_u64 v[96:97], v[96:97], 0, v[182:183]
	v_cvt_pk_bf16_f32 v98, v108, v109
	global_store_dwordx2 v[96:97], v[98:99], off offset:16
	s_or_b64 exec, exec, s[8:9]
	s_and_saveexec_b64 s[0:1], s[6:7]
	s_xor_b64 s[8:9], exec, s[0:1]
	s_cbranch_execz .LBB0_617

.LBB0_679:
	s_or_b64 exec, exec, s[16:17]
	s_and_b64 s[0:1], vcc, exec
	s_mov_b32 s0, 0x9350000
	s_cselect_b32 s0, s0, 0x9fb0000
	s_add_u32 s0, s90, s0
	s_addc_u32 s1, s91, 0
	v_accvgpr_read_b32 v79, a66
	v_accvgpr_read_b32 v78, a64
	v_mov_b64_e32 v[82:83], s[0:1]
	s_movk_i32 s0, 0x300
	s_ashr_i32 s11, s10, 31
	v_ashrrev_i32_e32 v113, 31, v112
	v_accvgpr_read_b32 v77, a67
	v_accvgpr_read_b32 v76, a65
	v_mad_i64_i32 v[82:83], s[0:1], v144, s0, v[82:83]
	v_lshl_add_u64 v[84:85], v[112:113], 0, s[10:11]
	v_pk_mul_f32 v[78:79], v[16:17], v[78:79] op_sel_hi:[0,1]
	v_lshl_add_u64 v[82:83], v[84:85], 1, v[82:83]
	v_pk_mul_f32 v[76:77], v[16:17], v[76:77] op_sel_hi:[0,1]
	v_cvt_pk_bf16_f32 v77, v79, v77
	v_cvt_pk_bf16_f32 v76, v78, v76
	v_accvgpr_read_b32 v75, a70
	v_accvgpr_read_b32 v74, a68
	v_mov_b32_e32 v179, v193
	v_accvgpr_read_b32 v73, a71
	v_accvgpr_read_b32 v72, a69
	v_lshl_add_u64 v[82:83], v[82:83], 0, v[178:179]
	v_pk_mul_f32 v[74:75], v[16:17], v[74:75] op_sel_hi:[0,1]
	global_store_dwordx2 v[82:83], v[76:77], off offset:64
	v_pk_mul_f32 v[72:73], v[16:17], v[72:73] op_sel_hi:[0,1]
	v_cvt_pk_bf16_f32 v73, v75, v73
	v_cvt_pk_bf16_f32 v72, v74, v72
	v_accvgpr_read_b32 v71, a74
	v_accvgpr_read_b32 v70, a72
	v_accvgpr_read_b32 v69, a75
	v_accvgpr_read_b32 v68, a73
	v_pk_mul_f32 v[70:71], v[16:17], v[70:71] op_sel_hi:[0,1]
	global_store_dwordx2 v[82:83], v[72:73], off offset:80
	v_pk_mul_f32 v[68:69], v[16:17], v[68:69] op_sel_hi:[0,1]
	v_cvt_pk_bf16_f32 v69, v71, v69
	v_cvt_pk_bf16_f32 v68, v70, v68
	v_accvgpr_read_b32 v67, a78
	v_accvgpr_read_b32 v66, a76
	v_accvgpr_read_b32 v65, a79
	v_accvgpr_read_b32 v64, a77
	v_pk_mul_f32 v[66:67], v[16:17], v[66:67] op_sel_hi:[0,1]
	global_store_dwordx2 v[82:83], v[68:69], off offset:96
	v_pk_mul_f32 v[64:65], v[16:17], v[64:65] op_sel_hi:[0,1]
	v_cvt_pk_bf16_f32 v65, v67, v65
	v_cvt_pk_bf16_f32 v64, v66, v64
	global_store_dwordx2 v[82:83], v[64:65], off offset:112

.LBB0_681:
	s_andn2_saveexec_b64 s[6:7], s[12:13]
	s_cbranch_execz .LBB0_683
	v_ashrrev_i32_e32 v145, 31, v144
	v_and_b32_sdwa v81, v66, v218 dst_sel:DWORD dst_unused:UNUSED_PAD src0_sel:WORD_1 src1_sel:DWORD
	v_lshlrev_b64 v[82:83], 9, v[144:145]
	v_cvt_pk_bf16_f32 v64, v64, v65
	v_add3_u32 v66, v66, v81, s80
	v_and_b32_sdwa v81, v67, v218 dst_sel:DWORD dst_unused:UNUSED_PAD src0_sel:WORD_1 src1_sel:DWORD
	v_lshl_add_u64 v[82:83], s[90:91], 0, v[82:83]
	v_add_u32_e32 v192, v112, v202
	v_add3_u32 v67, v67, v81, s80
	v_lshl_add_u64 v[82:83], v[192:193], 1, v[82:83]
	v_and_b32_e32 v67, 0xffff0000, v67
	s_mov_b32 s0, 0x8b0f000
	v_or_b32_sdwa v65, v67, v66 dst_sel:DWORD dst_unused:UNUSED_PAD src0_sel:DWORD src1_sel:WORD_1
	v_add_co_u32_e64 v66, s[0:1], s0, v82
	s_nop 0
	s_nop 0
	v_addc_co_u32_e64 v67, s[0:1], 0, v83, s[0:1]
	global_store_dwordx2 v[66:67], v[64:65], off offset:3392
	v_and_b32_sdwa v65, v68, v218 dst_sel:DWORD dst_unused:UNUSED_PAD src0_sel:WORD_1 src1_sel:DWORD
	v_add3_u32 v68, v68, v65, s80
	v_cvt_pk_bf16_f32 v65, v70, v71
	v_and_b32_sdwa v70, v69, v218 dst_sel:DWORD dst_unused:UNUSED_PAD src0_sel:WORD_1 src1_sel:DWORD
	v_add3_u32 v69, v69, v70, s80
	v_and_b32_e32 v69, 0xffff0000, v69
	v_or_b32_sdwa v64, v69, v68 dst_sel:DWORD dst_unused:UNUSED_PAD src0_sel:DWORD src1_sel:WORD_1
	global_store_dwordx2 v[66:67], v[64:65], off offset:3408
	v_cvt_pk_bf16_f32 v65, v74, v75
	v_cvt_pk_bf16_f32 v64, v72, v73
	global_store_dwordx2 v[66:67], v[64:65], off offset:3424
	v_cvt_pk_bf16_f32 v65, v78, v79
	v_cvt_pk_bf16_f32 v64, v76, v77
	global_store_dwordx2 v[66:67], v[64:65], off offset:3440

.LBB0_706:
	s_or_b64 exec, exec, s[18:19]
	s_and_b64 s[0:1], vcc, exec
	s_mov_b32 s0, 0x9350000
	s_cselect_b32 s0, s0, 0x9fb0000
	s_add_u32 s0, s90, s0
	s_addc_u32 s1, s91, 0
	v_accvgpr_read_b32 v47, a50
	v_accvgpr_read_b32 v46, a48
	v_mov_b64_e32 v[50:51], s[0:1]
	s_movk_i32 s0, 0x300
	s_ashr_i32 s11, s10, 31
	v_ashrrev_i32_e32 v113, 31, v112
	v_accvgpr_read_b32 v45, a51
	v_accvgpr_read_b32 v44, a49
	v_mad_i64_i32 v[50:51], s[0:1], v176, s0, v[50:51]
	v_lshl_add_u64 v[52:53], v[112:113], 0, s[10:11]
	v_pk_mul_f32 v[46:47], v[16:17], v[46:47] op_sel_hi:[0,1]
	v_lshl_add_u64 v[50:51], v[52:53], 1, v[50:51]
	v_pk_mul_f32 v[44:45], v[16:17], v[44:45] op_sel_hi:[0,1]
	v_cvt_pk_bf16_f32 v45, v47, v45
	v_cvt_pk_bf16_f32 v44, v46, v44
	v_accvgpr_read_b32 v43, a54
	v_accvgpr_read_b32 v42, a52
	v_mov_b32_e32 v179, v193
	v_accvgpr_read_b32 v41, a55
	v_accvgpr_read_b32 v40, a53
	v_lshl_add_u64 v[50:51], v[50:51], 0, v[178:179]
	v_pk_mul_f32 v[42:43], v[16:17], v[42:43] op_sel_hi:[0,1]
	global_store_dwordx2 v[50:51], v[44:45], off offset:128
	v_pk_mul_f32 v[40:41], v[16:17], v[40:41] op_sel_hi:[0,1]
	v_cvt_pk_bf16_f32 v41, v43, v41
	v_cvt_pk_bf16_f32 v40, v42, v40
	v_accvgpr_read_b32 v39, a58
	v_accvgpr_read_b32 v38, a56
	v_accvgpr_read_b32 v37, a59
	v_accvgpr_read_b32 v36, a57
	v_pk_mul_f32 v[38:39], v[16:17], v[38:39] op_sel_hi:[0,1]
	global_store_dwordx2 v[50:51], v[40:41], off offset:144
	v_pk_mul_f32 v[36:37], v[16:17], v[36:37] op_sel_hi:[0,1]
	v_cvt_pk_bf16_f32 v37, v39, v37
	v_cvt_pk_bf16_f32 v36, v38, v36
	v_accvgpr_read_b32 v35, a62
	v_accvgpr_read_b32 v34, a60
	v_accvgpr_read_b32 v33, a63
	v_accvgpr_read_b32 v32, a61
	v_pk_mul_f32 v[34:35], v[16:17], v[34:35] op_sel_hi:[0,1]
	global_store_dwordx2 v[50:51], v[36:37], off offset:160
	v_pk_mul_f32 v[32:33], v[16:17], v[32:33] op_sel_hi:[0,1]
	v_cvt_pk_bf16_f32 v33, v35, v33
	v_cvt_pk_bf16_f32 v32, v34, v32
	global_store_dwordx2 v[50:51], v[32:33], off offset:176

.LBB0_708:
	s_andn2_saveexec_b64 s[8:9], s[14:15]
	s_cbranch_execz .LBB0_710
	v_ashrrev_i32_e32 v177, 31, v176
	v_and_b32_sdwa v49, v34, v218 dst_sel:DWORD dst_unused:UNUSED_PAD src0_sel:WORD_1 src1_sel:DWORD
	v_lshlrev_b64 v[50:51], 9, v[176:177]
	v_cvt_pk_bf16_f32 v32, v32, v33
	v_add3_u32 v34, v34, v49, s80
	v_and_b32_sdwa v49, v35, v218 dst_sel:DWORD dst_unused:UNUSED_PAD src0_sel:WORD_1 src1_sel:DWORD
	v_lshl_add_u64 v[50:51], s[90:91], 0, v[50:51]
	v_add_u32_e32 v192, v112, v202
	v_add3_u32 v35, v35, v49, s80
	v_lshl_add_u64 v[50:51], v[192:193], 1, v[50:51]
	v_and_b32_e32 v35, 0xffff0000, v35
	s_mov_b32 s0, 0x8b0f000
	v_or_b32_sdwa v33, v35, v34 dst_sel:DWORD dst_unused:UNUSED_PAD src0_sel:DWORD src1_sel:WORD_1
	v_add_co_u32_e64 v34, s[0:1], s0, v50
	s_nop 0
	s_nop 0
	v_addc_co_u32_e64 v35, s[0:1], 0, v51, s[0:1]
	global_store_dwordx2 v[34:35], v[32:33], off offset:3456
	v_and_b32_sdwa v33, v36, v218 dst_sel:DWORD dst_unused:UNUSED_PAD src0_sel:WORD_1 src1_sel:DWORD
	v_add3_u32 v36, v36, v33, s80
	v_cvt_pk_bf16_f32 v33, v38, v39
	v_and_b32_sdwa v38, v37, v218 dst_sel:DWORD dst_unused:UNUSED_PAD src0_sel:WORD_1 src1_sel:DWORD
	v_add3_u32 v37, v37, v38, s80
	v_and_b32_e32 v37, 0xffff0000, v37
	v_or_b32_sdwa v32, v37, v36 dst_sel:DWORD dst_unused:UNUSED_PAD src0_sel:DWORD src1_sel:WORD_1
	global_store_dwordx2 v[34:35], v[32:33], off offset:3472
	v_cvt_pk_bf16_f32 v33, v42, v43
	v_cvt_pk_bf16_f32 v32, v40, v41
	global_store_dwordx2 v[34:35], v[32:33], off offset:3488
	v_cvt_pk_bf16_f32 v33, v46, v47
	v_cvt_pk_bf16_f32 v32, v44, v45
	global_store_dwordx2 v[34:35], v[32:33], off offset:3504

.LBB0_711:
	s_movk_i32 s0, 0x210
	v_mad_u64_u32 v[50:51], s[0:1], v49, s0, v[80:81]
	v_readlane_b32 s0, v254, 7
	v_readlane_b32 s1, v254, 8
	v_and_b32_sdwa v51, v34, v218 dst_sel:DWORD dst_unused:UNUSED_PAD src0_sel:WORD_1 src1_sel:DWORD
	v_cvt_pk_bf16_f32 v32, v32, v33
	v_mov_b64_e32 v[52:53], s[0:1]
	v_add3_u32 v34, v34, v51, s80
	v_and_b32_sdwa v51, v35, v218 dst_sel:DWORD dst_unused:UNUSED_PAD src0_sel:WORD_1 src1_sel:DWORD
	v_mad_i64_i32 v[54:55], s[0:1], v50, s68, v[52:53]
	v_mov_b32_e32 v181, v193
	v_add3_u32 v35, v35, v51, s80
	v_lshl_add_u64 v[54:55], v[54:55], 0, v[180:181]
	v_mov_b32_e32 v179, v193
	v_and_b32_e32 v35, 0xffff0000, v35
	v_lshl_add_u64 v[54:55], v[54:55], 0, v[178:179]
	v_or_b32_sdwa v33, v35, v34 dst_sel:DWORD dst_unused:UNUSED_PAD src0_sel:DWORD src1_sel:WORD_1
	global_store_dwordx2 v[54:55], v[32:33], off
	v_mov_b64_e32 v[32:33], s[90:91]
	v_mad_i64_i32 v[32:33], s[0:1], v50, s68, v[32:33]
	v_lshl_add_u64 v[32:33], v[32:33], 0, v[180:181]
	v_and_b32_sdwa v35, v36, v218 dst_sel:DWORD dst_unused:UNUSED_PAD src0_sel:WORD_1 src1_sel:DWORD
	v_lshl_add_u64 v[32:33], v[32:33], 0, v[178:179]
	v_add3_u32 v36, v36, v35, s80
	v_cvt_pk_bf16_f32 v35, v38, v39
	v_and_b32_sdwa v38, v37, v218 dst_sel:DWORD dst_unused:UNUSED_PAD src0_sel:WORD_1 src1_sel:DWORD
	v_add3_u32 v37, v37, v38, s80
	v_add_co_u32_e64 v32, s[0:1], s92, v32
	v_and_b32_e32 v37, 0xffff0000, v37
	s_nop 0
	v_addc_co_u32_e64 v33, s[0:1], 0, v33, s[0:1]
	v_or_b32_sdwa v34, v37, v36 dst_sel:DWORD dst_unused:UNUSED_PAD src0_sel:DWORD src1_sel:WORD_1
	s_movk_i32 s0, 0xa50
	global_store_dwordx2 v[32:33], v[34:35], off offset:16
	v_add3_u32 v32, v80, v114, s0
	v_mad_i64_i32 v[32:33], s[0:1], v32, s68, v[52:53]
	v_cvt_pk_bf16_f32 v37, v42, v43
	v_lshl_add_u64 v[32:33], v[32:33], 0, v[180:181]
	v_lshl_add_u64 v[34:35], v[32:33], 0, v[178:179]
	v_cvt_pk_bf16_f32 v36, v40, v41
	global_store_dwordx2 v[34:35], v[36:37], off
	v_cvt_pk_bf16_f32 v35, v46, v47
	v_mov_b32_e32 v183, v193
	v_lshl_add_u64 v[32:33], v[32:33], 0, v[182:183]
	v_cvt_pk_bf16_f32 v34, v44, v45
	global_store_dwordx2 v[32:33], v[34:35], off offset:16
	s_or_b64 exec, exec, s[8:9]
	s_and_saveexec_b64 s[0:1], s[6:7]
	s_xor_b64 s[8:9], exec, s[0:1]
	s_cbranch_execz .LBB0_622

.LBB0_734:
	s_or_b64 exec, exec, s[16:17]
	s_and_b64 s[0:1], vcc, exec
	s_mov_b32 s0, 0x9350000
	s_cselect_b32 s0, s0, 0x9fb0000
	s_add_u32 s0, s90, s0
	s_addc_u32 s1, s91, 0
	v_accvgpr_read_b32 v15, a18
	v_accvgpr_read_b32 v14, a16
	v_mov_b64_e32 v[18:19], s[0:1]
	s_movk_i32 s0, 0x300
	s_ashr_i32 s11, s10, 31
	v_ashrrev_i32_e32 v113, 31, v112
	v_accvgpr_read_b32 v13, a19
	v_accvgpr_read_b32 v12, a17
	v_mad_i64_i32 v[18:19], s[0:1], v144, s0, v[18:19]
	v_lshl_add_u64 v[20:21], v[112:113], 0, s[10:11]
	v_pk_mul_f32 v[14:15], v[16:17], v[14:15] op_sel_hi:[0,1]
	v_lshl_add_u64 v[18:19], v[20:21], 1, v[18:19]
	v_pk_mul_f32 v[12:13], v[16:17], v[12:13] op_sel_hi:[0,1]
	v_and_b32_sdwa v17, v15, v218 dst_sel:DWORD dst_unused:UNUSED_PAD src0_sel:WORD_1 src1_sel:DWORD
	v_cvt_pk_bf16_f32 v12, v14, v12
	v_add3_u32 v15, v15, v17, s80
	v_and_b32_sdwa v17, v13, v218 dst_sel:DWORD dst_unused:UNUSED_PAD src0_sel:WORD_1 src1_sel:DWORD
	v_add3_u32 v13, v13, v17, s80
	v_accvgpr_read_b32 v11, a22
	v_accvgpr_read_b32 v10, a20
	v_mov_b32_e32 v179, v193
	v_and_b32_e32 v13, 0xffff0000, v13
	v_accvgpr_read_b32 v9, a23
	v_accvgpr_read_b32 v8, a21
	v_lshl_add_u64 v[18:19], v[18:19], 0, v[178:179]
	v_or_b32_sdwa v13, v13, v15 dst_sel:DWORD dst_unused:UNUSED_PAD src0_sel:DWORD src1_sel:WORD_1
	v_pk_mul_f32 v[10:11], v[16:17], v[10:11] op_sel_hi:[0,1]
	global_store_dwordx2 v[18:19], v[12:13], off offset:128
	v_pk_mul_f32 v[8:9], v[16:17], v[8:9] op_sel_hi:[0,1]
	v_cvt_pk_bf16_f32 v9, v11, v9
	v_cvt_pk_bf16_f32 v8, v10, v8
	v_accvgpr_read_b32 v7, a26
	v_accvgpr_read_b32 v6, a24
	v_accvgpr_read_b32 v5, a27
	v_accvgpr_read_b32 v4, a25
	v_pk_mul_f32 v[6:7], v[16:17], v[6:7] op_sel_hi:[0,1]
	global_store_dwordx2 v[18:19], v[8:9], off offset:144
	v_pk_mul_f32 v[4:5], v[16:17], v[4:5] op_sel_hi:[0,1]
	v_cvt_pk_bf16_f32 v5, v7, v5
	v_cvt_pk_bf16_f32 v4, v6, v4
	v_accvgpr_read_b32 v3, a30
	v_accvgpr_read_b32 v2, a28
	v_accvgpr_read_b32 v1, a31
	v_accvgpr_read_b32 v0, a29
	v_pk_mul_f32 v[2:3], v[16:17], v[2:3] op_sel_hi:[0,1]
	global_store_dwordx2 v[18:19], v[4:5], off offset:160
	v_pk_mul_f32 v[0:1], v[16:17], v[0:1] op_sel_hi:[0,1]
	v_cvt_pk_bf16_f32 v1, v3, v1
	v_cvt_pk_bf16_f32 v0, v2, v0
	global_store_dwordx2 v[18:19], v[0:1], off offset:176

.LBB0_736:
	s_andn2_saveexec_b64 s[6:7], s[12:13]
	s_cbranch_execz .LBB0_738
	v_ashrrev_i32_e32 v145, 31, v144
	v_and_b32_sdwa v17, v2, v218 dst_sel:DWORD dst_unused:UNUSED_PAD src0_sel:WORD_1 src1_sel:DWORD
	v_lshlrev_b64 v[18:19], 9, v[144:145]
	v_cvt_pk_bf16_f32 v0, v0, v1
	v_add3_u32 v2, v2, v17, s80
	v_and_b32_sdwa v17, v3, v218 dst_sel:DWORD dst_unused:UNUSED_PAD src0_sel:WORD_1 src1_sel:DWORD
	v_lshl_add_u64 v[18:19], s[90:91], 0, v[18:19]
	v_add_u32_e32 v192, v112, v202
	v_add3_u32 v3, v3, v17, s80
	v_lshl_add_u64 v[18:19], v[192:193], 1, v[18:19]
	v_and_b32_e32 v3, 0xffff0000, v3
	s_mov_b32 s0, 0x8b0f000
	v_or_b32_sdwa v1, v3, v2 dst_sel:DWORD dst_unused:UNUSED_PAD src0_sel:DWORD src1_sel:WORD_1
	v_add_co_u32_e64 v2, s[0:1], s0, v18
	s_nop 0
	s_nop 0
	v_addc_co_u32_e64 v3, s[0:1], 0, v19, s[0:1]
	global_store_dwordx2 v[2:3], v[0:1], off offset:3456
	v_and_b32_sdwa v1, v4, v218 dst_sel:DWORD dst_unused:UNUSED_PAD src0_sel:WORD_1 src1_sel:DWORD
	v_add3_u32 v4, v4, v1, s80
	v_cvt_pk_bf16_f32 v1, v6, v7
	v_and_b32_sdwa v6, v5, v218 dst_sel:DWORD dst_unused:UNUSED_PAD src0_sel:WORD_1 src1_sel:DWORD
	v_add3_u32 v5, v5, v6, s80
	v_and_b32_e32 v5, 0xffff0000, v5
	v_or_b32_sdwa v0, v5, v4 dst_sel:DWORD dst_unused:UNUSED_PAD src0_sel:DWORD src1_sel:WORD_1
	global_store_dwordx2 v[2:3], v[0:1], off offset:3472
	v_cvt_pk_bf16_f32 v1, v10, v11
	v_cvt_pk_bf16_f32 v0, v8, v9
	global_store_dwordx2 v[2:3], v[0:1], off offset:3488
	v_cvt_pk_bf16_f32 v1, v14, v15
	v_cvt_pk_bf16_f32 v0, v12, v13
	global_store_dwordx2 v[2:3], v[0:1], off offset:3504

.LBB0_761:
	s_or_b64 exec, exec, s[12:13]
	s_and_b64 s[0:1], vcc, exec
	s_mov_b32 s0, 0x9350000
	s_cselect_b32 s0, s0, 0x9fb0000
	s_add_u32 s0, s90, s0
	s_addc_u32 s1, s91, 0
	v_accvgpr_read_b32 v15, a2
	v_accvgpr_read_b32 v14, a0
	v_mov_b64_e32 v[18:19], s[0:1]
	s_movk_i32 s0, 0x300
	s_ashr_i32 s11, s10, 31
	v_ashrrev_i32_e32 v113, 31, v112
	v_accvgpr_read_b32 v13, a3
	v_accvgpr_read_b32 v12, a1
	v_mad_i64_i32 v[18:19], s[0:1], v144, s0, v[18:19]
	v_lshl_add_u64 v[20:21], v[112:113], 0, s[10:11]
	v_pk_mul_f32 v[14:15], v[16:17], v[14:15] op_sel_hi:[0,1]
	v_lshl_add_u64 v[18:19], v[20:21], 1, v[18:19]
	v_pk_mul_f32 v[12:13], v[16:17], v[12:13] op_sel_hi:[0,1]
	v_and_b32_sdwa v17, v15, v218 dst_sel:DWORD dst_unused:UNUSED_PAD src0_sel:WORD_1 src1_sel:DWORD
	v_cvt_pk_bf16_f32 v12, v14, v12
	v_add3_u32 v15, v15, v17, s80
	v_and_b32_sdwa v17, v13, v218 dst_sel:DWORD dst_unused:UNUSED_PAD src0_sel:WORD_1 src1_sel:DWORD
	v_add3_u32 v13, v13, v17, s80
	v_accvgpr_read_b32 v11, a6
	v_accvgpr_read_b32 v10, a4
	v_mov_b32_e32 v179, v193
	v_and_b32_e32 v13, 0xffff0000, v13
	v_accvgpr_read_b32 v9, a7
	v_accvgpr_read_b32 v8, a5
	v_lshl_add_u64 v[18:19], v[18:19], 0, v[178:179]
	v_or_b32_sdwa v13, v13, v15 dst_sel:DWORD dst_unused:UNUSED_PAD src0_sel:DWORD src1_sel:WORD_1
	v_pk_mul_f32 v[10:11], v[16:17], v[10:11] op_sel_hi:[0,1]
	global_store_dwordx2 v[18:19], v[12:13], off offset:192
	v_pk_mul_f32 v[8:9], v[16:17], v[8:9] op_sel_hi:[0,1]
	v_cvt_pk_bf16_f32 v9, v11, v9
	v_cvt_pk_bf16_f32 v8, v10, v8
	v_accvgpr_read_b32 v7, a10
	v_accvgpr_read_b32 v6, a8
	v_accvgpr_read_b32 v5, a11
	v_accvgpr_read_b32 v4, a9
	v_pk_mul_f32 v[6:7], v[16:17], v[6:7] op_sel_hi:[0,1]
	global_store_dwordx2 v[18:19], v[8:9], off offset:208
	v_pk_mul_f32 v[4:5], v[16:17], v[4:5] op_sel_hi:[0,1]
	v_cvt_pk_bf16_f32 v5, v7, v5
	v_cvt_pk_bf16_f32 v4, v6, v4
	v_accvgpr_read_b32 v3, a14
	v_accvgpr_read_b32 v2, a12
	v_accvgpr_read_b32 v1, a15
	v_accvgpr_read_b32 v0, a13
	v_pk_mul_f32 v[2:3], v[16:17], v[2:3] op_sel_hi:[0,1]
	global_store_dwordx2 v[18:19], v[4:5], off offset:224
	v_pk_mul_f32 v[0:1], v[16:17], v[0:1] op_sel_hi:[0,1]
	v_cvt_pk_bf16_f32 v1, v3, v1
	v_cvt_pk_bf16_f32 v0, v2, v0
	global_store_dwordx2 v[18:19], v[0:1], off offset:240

.LBB0_763:
	s_andn2_saveexec_b64 s[0:1], s[8:9]
	s_cbranch_execz .LBB0_765
	v_ashrrev_i32_e32 v145, 31, v144
	v_and_b32_sdwa v18, v2, v218 dst_sel:DWORD dst_unused:UNUSED_PAD src0_sel:WORD_1 src1_sel:DWORD
	v_lshlrev_b64 v[16:17], 9, v[144:145]
	v_cvt_pk_bf16_f32 v0, v0, v1
	v_add3_u32 v2, v2, v18, s80
	v_and_b32_sdwa v18, v3, v218 dst_sel:DWORD dst_unused:UNUSED_PAD src0_sel:WORD_1 src1_sel:DWORD
	v_lshl_add_u64 v[16:17], s[90:91], 0, v[16:17]
	v_add_u32_e32 v192, v112, v202
	v_add3_u32 v3, v3, v18, s80
	v_lshl_add_u64 v[16:17], v[192:193], 1, v[16:17]
	v_and_b32_e32 v3, 0xffff0000, v3
	s_mov_b32 s2, 0x8b0f000
	v_or_b32_sdwa v1, v3, v2 dst_sel:DWORD dst_unused:UNUSED_PAD src0_sel:DWORD src1_sel:WORD_1
	v_add_co_u32_e32 v2, vcc, s2, v16
	s_nop 0
	s_nop 0
	v_addc_co_u32_e32 v3, vcc, 0, v17, vcc
	global_store_dwordx2 v[2:3], v[0:1], off offset:3520
	v_and_b32_sdwa v1, v4, v218 dst_sel:DWORD dst_unused:UNUSED_PAD src0_sel:WORD_1 src1_sel:DWORD
	v_add3_u32 v4, v4, v1, s80
	v_cvt_pk_bf16_f32 v1, v6, v7
	v_and_b32_sdwa v6, v5, v218 dst_sel:DWORD dst_unused:UNUSED_PAD src0_sel:WORD_1 src1_sel:DWORD
	v_add3_u32 v5, v5, v6, s80
	v_and_b32_e32 v5, 0xffff0000, v5
	v_or_b32_sdwa v0, v5, v4 dst_sel:DWORD dst_unused:UNUSED_PAD src0_sel:DWORD src1_sel:WORD_1
	global_store_dwordx2 v[2:3], v[0:1], off offset:3536
	v_cvt_pk_bf16_f32 v1, v10, v11
	v_cvt_pk_bf16_f32 v0, v8, v9
	global_store_dwordx2 v[2:3], v[0:1], off offset:3552
	v_cvt_pk_bf16_f32 v1, v14, v15
	v_cvt_pk_bf16_f32 v0, v12, v13
	global_store_dwordx2 v[2:3], v[0:1], off offset:3568

.LBB0_766:
	s_movk_i32 s2, 0x210
	v_mad_u64_u32 v[16:17], s[2:3], v17, s2, v[48:49]
	v_readlane_b32 s2, v254, 7
	v_readlane_b32 s3, v254, 8
	v_and_b32_sdwa v17, v2, v218 dst_sel:DWORD dst_unused:UNUSED_PAD src0_sel:WORD_1 src1_sel:DWORD
	v_cvt_pk_bf16_f32 v0, v0, v1
	v_mov_b64_e32 v[18:19], s[2:3]
	v_add3_u32 v2, v2, v17, s80
	v_and_b32_sdwa v17, v3, v218 dst_sel:DWORD dst_unused:UNUSED_PAD src0_sel:WORD_1 src1_sel:DWORD
	v_mad_i64_i32 v[20:21], s[2:3], v16, s68, v[18:19]
	v_mov_b32_e32 v181, v193
	v_add3_u32 v3, v3, v17, s80
	v_lshl_add_u64 v[20:21], v[20:21], 0, v[180:181]
	v_mov_b32_e32 v179, v193
	v_and_b32_e32 v3, 0xffff0000, v3
	v_lshl_add_u64 v[20:21], v[20:21], 0, v[178:179]
	v_or_b32_sdwa v1, v3, v2 dst_sel:DWORD dst_unused:UNUSED_PAD src0_sel:DWORD src1_sel:WORD_1
	global_store_dwordx2 v[20:21], v[0:1], off
	v_mov_b64_e32 v[0:1], s[90:91]
	v_mad_i64_i32 v[0:1], s[2:3], v16, s68, v[0:1]
	v_and_b32_sdwa v3, v4, v218 dst_sel:DWORD dst_unused:UNUSED_PAD src0_sel:WORD_1 src1_sel:DWORD
	v_lshl_add_u64 v[0:1], v[0:1], 0, v[180:181]
	v_add3_u32 v4, v4, v3, s80
	v_cvt_pk_bf16_f32 v3, v6, v7
	v_and_b32_sdwa v6, v5, v218 dst_sel:DWORD dst_unused:UNUSED_PAD src0_sel:WORD_1 src1_sel:DWORD
	v_lshl_add_u64 v[0:1], v[0:1], 0, v[178:179]
	v_add3_u32 v5, v5, v6, s80
	v_and_b32_e32 v5, 0xffff0000, v5
	v_add_co_u32_e32 v0, vcc, s92, v0
	v_or_b32_sdwa v2, v5, v4 dst_sel:DWORD dst_unused:UNUSED_PAD src0_sel:DWORD src1_sel:WORD_1
	s_nop 0
	v_addc_co_u32_e32 v1, vcc, 0, v1, vcc
	global_store_dwordx2 v[0:1], v[2:3], off offset:16
	s_movk_i32 s2, 0xe70
	v_add3_u32 v0, v48, v114, s2
	v_mad_i64_i32 v[0:1], s[2:3], v0, s68, v[18:19]
	v_cvt_pk_bf16_f32 v3, v10, v11
	v_lshl_add_u64 v[0:1], v[0:1], 0, v[180:181]
	v_mov_b32_e32 v183, v193
	v_lshl_add_u64 v[0:1], v[0:1], 0, v[182:183]
	v_cvt_pk_bf16_f32 v2, v8, v9
	global_store_dwordx2 v[0:1], v[2:3], off
	v_cvt_pk_bf16_f32 v3, v14, v15
	v_cvt_pk_bf16_f32 v2, v12, v13
	global_store_dwordx2 v[0:1], v[2:3], off offset:16
	s_branch .LBB0_521

.LBB0_772:
	s_abs_i32 s1, s20
	v_readlane_b32 s2, v255, 3
	s_mul_hi_u32 s2, s1, s2
	s_mul_i32 s3, s2, s5
	s_sub_i32 s1, s1, s3
	s_ashr_i32 s0, s20, 31
	s_add_i32 s3, s2, 1
	s_sub_i32 s4, s1, s5
	s_cmp_ge_u32 s1, s5
	s_cselect_b32 s2, s3, s2
	s_cselect_b32 s1, s4, s1
	s_add_i32 s3, s2, 1
	s_cmp_ge_u32 s1, s5
	s_cselect_b32 s1, s3, s2
	s_xor_b32 s1, s1, s0
	s_sub_i32 s0, s1, s0
	s_mul_hi_i32 s1, s20, 0x92492493
	s_add_i32 s1, s1, s20
	s_lshr_b32 s2, s1, 31
	s_ashr_i32 s1, s1, 2
	s_add_i32 s1, s1, s2
	s_mul_i32 s2, s1, 7
	s_mul_i32 s0, s0, 7
	s_sub_i32 s2, s20, s2
	s_add_i32 s0, s0, s2
	s_ashr_i32 s2, s1, 31
	s_abs_i32 s1, s1
	v_readlane_b32 s3, v255, 5
	s_mul_hi_u32 s3, s1, s3
	v_readlane_b32 s4, v255, 4
	s_mul_i32 s3, s3, s4
	s_sub_i32 s1, s1, s3
	s_sub_i32 s3, s1, s4
	s_cmp_ge_u32 s1, s4
	s_cselect_b32 s1, s3, s1
	s_sub_i32 s3, s1, s4
	s_cmp_ge_u32 s1, s4
	v_mov_b32_e32 v4, v208
	s_cselect_b32 s1, s3, s1
	s_lshl_b32 s0, s0, 8
	s_xor_b32 s1, s1, s2
	v_ashrrev_i32_e32 v5, 2, v4
	v_add_u32_e32 v0, s0, v5
	s_sub_i32 s1, s1, s2
	v_readlane_b32 s2, v254, 62
	v_ashrrev_i32_e32 v1, 31, v0
	s_add_i32 s1, s2, s1
	v_lshlrev_b64 v[0:1], 11, v[0:1]
	v_lshlrev_b32_e32 v6, 4, v4
	s_lshl_b32 s1, s1, 7
	v_lshl_add_u64 v[0:1], s[90:91], 0, v[0:1]
	v_and_b32_e32 v192, 48, v6
	s_waitcnt vmcnt(0)
	v_lshl_add_u64 v[64:65], v[0:1], 0, v[192:193]
	v_add_u32_e32 v0, s1, v5
	v_ashrrev_i32_e32 v1, 31, v0
	v_readlane_b32 s2, v253, 16
	v_lshlrev_b64 v[0:1], 11, v[0:1]
	v_readlane_b32 s3, v253, 17
	v_bitop3_b32 v6, v6, 48, v4 bitop3:0x48
	v_and_b32_e32 v207, 31, v4
	v_lshl_add_u64 v[0:1], s[2:3], 0, v[0:1]
	s_mov_b32 s2, 0x20000
	v_add_co_u32_e32 v8, vcc, s2, v64
	s_mov_b32 s3, 0x40000
	s_nop 0
	v_addc_co_u32_e32 v9, vcc, 0, v65, vcc
	v_add_co_u32_e32 v12, vcc, s3, v64
	v_lshrrev_b32_e32 v7, 5, v4
	s_nop 0
	v_addc_co_u32_e32 v13, vcc, 0, v65, vcc
	v_add_co_u32_e32 v16, vcc, s75, v64
	v_bfe_u32 v239, v4, 5, 1
	v_bfe_u32 v10, v4, 2, 2
	v_lshlrev_b32_e32 v11, 1, v4
	v_ashrrev_i32_e32 v4, 1, v4
	v_lshl_add_u64 v[66:67], v[0:1], 0, v[192:193]
	v_addc_co_u32_e32 v17, vcc, 0, v65, vcc
	v_and_b32_e32 v192, 0x80, v11
	v_and_b32_e32 v242, 0xffffffc0, v4
	v_add_co_u32_e32 v24, vcc, s2, v66
	v_or_b32_e32 v11, v192, v207
	v_bitop3_b32 v7, v7, v10, 1 bitop3:0x6c
	v_bitop3_b32 v10, v239, v10, 2 bitop3:0x36
	v_or_b32_e32 v4, v242, v207
	global_load_dwordx4 v[0:3], v[64:65], off
	global_load_dwordx4 v[28:31], v[8:9], off
	global_load_dwordx4 v[32:35], v[12:13], off
	global_load_dwordx4 v[36:39], v[16:17], off
	global_load_dwordx4 v[40:43], v[66:67], off
	v_addc_co_u32_e32 v25, vcc, 0, v67, vcc
	v_lshlrev_b32_e32 v11, 6, v11
	v_lshlrev_b32_e32 v7, 4, v7
	v_lshlrev_b32_e32 v10, 4, v10
	v_lshl_add_u32 v4, v4, 6, v214
	global_load_dwordx4 v[44:47], v[24:25], off
	v_or_b32_e32 v76, v11, v7
	v_or_b32_e32 v77, v11, v10
	v_or_b32_e32 v78, v4, v7
	v_or_b32_e32 v79, v4, v10
	v_lshl_or_b32 v80, v5, 6, v6
	global_load_dwordx4 v[4:7], v[64:65], off offset:64
	s_nop 0
	global_load_dwordx4 v[8:11], v[8:9], off offset:64
	s_nop 0
	global_load_dwordx4 v[12:15], v[12:13], off offset:64
	s_nop 0
	global_load_dwordx4 v[16:19], v[16:17], off offset:64
	s_nop 0
	global_load_dwordx4 v[20:23], v[66:67], off offset:64
	s_nop 0
	global_load_dwordx4 v[24:27], v[24:25], off offset:64
	v_accvgpr_mov_b32 a193, a192
	v_accvgpr_mov_b32 a194, a192
	v_accvgpr_mov_b32 a195, a192
	v_accvgpr_mov_b32 a196, a192
	v_accvgpr_mov_b32 a197, a192
	v_accvgpr_mov_b32 a198, a192
	v_accvgpr_mov_b32 a199, a192
	v_accvgpr_mov_b32 a200, a192
	v_accvgpr_mov_b32 a201, a192
	v_accvgpr_mov_b32 a202, a192
	v_accvgpr_mov_b32 a203, a192
	v_accvgpr_mov_b32 a204, a192
	v_accvgpr_mov_b32 a205, a192
	v_accvgpr_mov_b32 a206, a192
	v_accvgpr_mov_b32 a207, a192
	v_accvgpr_mov_b32 a128, a192
	v_accvgpr_mov_b32 a0, a192
	v_accvgpr_write_b32 a127, 0
	v_accvgpr_write_b32 a126, 0
	v_accvgpr_write_b32 a125, 0
	v_accvgpr_write_b32 a124, 0
	v_accvgpr_write_b32 a123, 0
	v_accvgpr_write_b32 a122, 0
	v_accvgpr_write_b32 a121, 0
	v_accvgpr_write_b32 a120, 0
	v_accvgpr_write_b32 a119, 0
	v_accvgpr_write_b32 a118, 0
	v_accvgpr_write_b32 a117, 0
	v_accvgpr_write_b32 a116, 0
	v_accvgpr_write_b32 a115, 0
	v_accvgpr_write_b32 a114, 0
	v_accvgpr_write_b32 a113, 0
	v_accvgpr_write_b32 a112, 0
	v_accvgpr_write_b32 a111, 0
	v_accvgpr_write_b32 a110, 0
	v_accvgpr_write_b32 a109, 0
	v_accvgpr_write_b32 a108, 0
	v_accvgpr_write_b32 a107, 0
	v_accvgpr_write_b32 a106, 0
	v_accvgpr_write_b32 a105, 0
	v_accvgpr_write_b32 a104, 0
	v_accvgpr_write_b32 a103, 0
	v_accvgpr_write_b32 a102, 0
	v_accvgpr_write_b32 a101, 0
	v_accvgpr_write_b32 a100, 0
	v_accvgpr_write_b32 a99, 0
	v_accvgpr_write_b32 a98, 0
	v_accvgpr_write_b32 a97, 0
	v_accvgpr_write_b32 a96, 0
	v_accvgpr_write_b32 a95, 0
	v_accvgpr_write_b32 a94, 0
	v_accvgpr_write_b32 a93, 0
	v_accvgpr_write_b32 a92, 0
	v_accvgpr_write_b32 a91, 0
	v_accvgpr_write_b32 a90, 0
	v_accvgpr_write_b32 a89, 0
	v_accvgpr_write_b32 a88, 0
	v_accvgpr_write_b32 a87, 0
	v_accvgpr_write_b32 a86, 0
	v_accvgpr_write_b32 a85, 0
	v_accvgpr_write_b32 a84, 0
	v_accvgpr_write_b32 a83, 0
	v_accvgpr_write_b32 a82, 0
	v_accvgpr_write_b32 a81, 0
	v_accvgpr_write_b32 a80, 0
	v_accvgpr_write_b32 a79, 0
	v_accvgpr_write_b32 a78, 0
	v_accvgpr_write_b32 a77, 0
	v_accvgpr_write_b32 a76, 0
	v_accvgpr_write_b32 a75, 0
	v_accvgpr_write_b32 a74, 0
	v_accvgpr_write_b32 a73, 0
	v_accvgpr_write_b32 a72, 0
	v_accvgpr_write_b32 a71, 0
	v_accvgpr_write_b32 a70, 0
	v_accvgpr_write_b32 a69, 0
	v_accvgpr_write_b32 a68, 0
	v_accvgpr_write_b32 a67, 0
	v_accvgpr_write_b32 a66, 0
	v_accvgpr_write_b32 a65, 0
	v_accvgpr_write_b32 a64, 0
	v_accvgpr_write_b32 a63, 0
	v_accvgpr_write_b32 a62, 0
	v_accvgpr_write_b32 a61, 0
	v_accvgpr_write_b32 a60, 0
	v_accvgpr_write_b32 a59, 0
	v_accvgpr_write_b32 a58, 0
	v_accvgpr_write_b32 a57, 0
	v_accvgpr_write_b32 a56, 0
	v_accvgpr_write_b32 a55, 0
	v_accvgpr_write_b32 a54, 0
	v_accvgpr_write_b32 a53, 0
	v_accvgpr_write_b32 a52, 0
	v_accvgpr_write_b32 a51, 0
	v_accvgpr_write_b32 a50, 0
	v_accvgpr_write_b32 a49, 0
	v_accvgpr_write_b32 a48, 0
	v_accvgpr_write_b32 a31, 0
	v_accvgpr_write_b32 a30, 0
	v_accvgpr_write_b32 a29, 0
	v_accvgpr_write_b32 a28, 0
	v_accvgpr_write_b32 a27, 0
	v_accvgpr_write_b32 a26, 0
	v_accvgpr_write_b32 a25, 0
	v_accvgpr_write_b32 a24, 0
	v_accvgpr_write_b32 a23, 0
	v_accvgpr_write_b32 a22, 0
	v_accvgpr_write_b32 a21, 0
	v_accvgpr_write_b32 a20, 0
	v_accvgpr_write_b32 a19, 0
	v_accvgpr_write_b32 a18, 0
	v_accvgpr_write_b32 a17, 0
	v_accvgpr_write_b32 a16, 0
	v_accvgpr_mov_b32 a129, a193
	v_accvgpr_mov_b32 a130, a194
	v_accvgpr_mov_b32 a131, a195
	v_accvgpr_mov_b32 a132, a196
	v_accvgpr_mov_b32 a133, a197
	v_accvgpr_mov_b32 a134, a198
	v_accvgpr_mov_b32 a135, a199
	v_accvgpr_mov_b32 a136, a200
	v_accvgpr_mov_b32 a137, a201
	v_accvgpr_mov_b32 a138, a202
	v_accvgpr_mov_b32 a139, a203
	v_accvgpr_mov_b32 a140, a204
	v_accvgpr_mov_b32 a141, a205
	v_accvgpr_mov_b32 a142, a206
	v_accvgpr_mov_b32 a143, a207
	v_accvgpr_mov_b32 a1, a193
	v_accvgpr_mov_b32 a2, a194
	v_accvgpr_mov_b32 a3, a195
	v_accvgpr_mov_b32 a4, a196
	v_accvgpr_mov_b32 a5, a197
	v_accvgpr_mov_b32 a6, a198
	v_accvgpr_mov_b32 a7, a199
	v_accvgpr_mov_b32 a8, a200
	v_accvgpr_mov_b32 a9, a201
	v_accvgpr_mov_b32 a10, a202
	v_accvgpr_mov_b32 a11, a203
	v_accvgpr_mov_b32 a12, a204
	v_accvgpr_mov_b32 a13, a205
	v_accvgpr_mov_b32 a14, a206
	v_accvgpr_mov_b32 a15, a207
	s_waitcnt vmcnt(11)
	ds_write_b128 v80, v[0:3] offset:0
	s_waitcnt vmcnt(10)
	ds_write_b128 v80, v[28:31] offset:0x1000
	s_waitcnt vmcnt(9)
	ds_write_b128 v80, v[32:35] offset:0x2000
	s_mov_b64 s[4:5], 0x40000
	s_mov_b64 s[6:7], 0x20000
	v_lshl_add_u64 v[70:71], v[64:65], 0, s[4:5]
	s_mov_b64 s[4:5], 0x60000
	v_mov_b32_e32 v0, 0
	s_waitcnt vmcnt(8)
	ds_write_b128 v80, v[36:39] offset:0x3000
	s_waitcnt vmcnt(7)
	ds_write_b128 v80, v[40:43] offset:0x4000
	s_waitcnt vmcnt(6)
	ds_write_b128 v80, v[44:47] offset:0x5000
	s_waitcnt lgkmcnt(0)
	v_lshl_add_u64 v[68:69], v[64:65], 0, s[6:7]
	s_mov_b32 s3, 0
	v_lshl_add_u64 v[72:73], v[64:65], 0, s[4:5]
	v_lshl_add_u64 v[74:75], v[66:67], 0, s[6:7]
	s_mov_b32 s2, -2
	v_mov_b32_e32 v1, v0
	v_mov_b32_e32 v2, v0
	v_mov_b32_e32 v3, v0
	v_mov_b32_e32 v28, v0
	v_mov_b32_e32 v29, v0
	v_mov_b32_e32 v30, v0
	v_mov_b32_e32 v31, v0
	v_mov_b32_e32 v32, v0
	v_mov_b32_e32 v33, v0
	v_mov_b32_e32 v34, v0
	v_mov_b32_e32 v35, v0
	v_mov_b32_e32 v36, v0
	v_mov_b32_e32 v37, v0
	v_mov_b32_e32 v38, v0
	v_mov_b32_e32 v39, v0
	s_barrier

.LBB0_932:
	s_andn2_saveexec_b64 s[0:1], s[6:7]
	s_cbranch_execz .LBB0_771
	s_movk_i32 s2, 0x210
	v_mad_u64_u32 v[16:17], s[2:3], v17, s2, v[48:49]
	v_readlane_b32 s2, v254, 7
	v_readlane_b32 s3, v254, 8
	v_and_b32_sdwa v17, v2, v218 dst_sel:DWORD dst_unused:UNUSED_PAD src0_sel:WORD_1 src1_sel:DWORD
	v_cvt_pk_bf16_f32 v0, v0, v1
	v_mov_b64_e32 v[18:19], s[2:3]
	v_add3_u32 v2, v2, v17, s80
	v_and_b32_sdwa v17, v3, v218 dst_sel:DWORD dst_unused:UNUSED_PAD src0_sel:WORD_1 src1_sel:DWORD
	v_mad_i64_i32 v[20:21], s[2:3], v16, s68, v[18:19]
	v_mov_b32_e32 v181, v193
	v_add3_u32 v3, v3, v17, s80
	v_lshl_add_u64 v[20:21], v[20:21], 0, v[180:181]
	v_mov_b32_e32 v179, v193
	v_and_b32_e32 v3, 0xffff0000, v3
	v_lshl_add_u64 v[20:21], v[20:21], 0, v[178:179]
	v_or_b32_sdwa v1, v3, v2 dst_sel:DWORD dst_unused:UNUSED_PAD src0_sel:DWORD src1_sel:WORD_1
	global_store_dwordx2 v[20:21], v[0:1], off
	v_mov_b64_e32 v[0:1], s[90:91]
	v_mad_i64_i32 v[0:1], s[2:3], v16, s68, v[0:1]
	v_and_b32_sdwa v3, v4, v218 dst_sel:DWORD dst_unused:UNUSED_PAD src0_sel:WORD_1 src1_sel:DWORD
	v_lshl_add_u64 v[0:1], v[0:1], 0, v[180:181]
	v_add3_u32 v4, v4, v3, s80
	v_cvt_pk_bf16_f32 v3, v6, v7
	v_and_b32_sdwa v6, v5, v218 dst_sel:DWORD dst_unused:UNUSED_PAD src0_sel:WORD_1 src1_sel:DWORD
	v_lshl_add_u64 v[0:1], v[0:1], 0, v[178:179]
	v_add3_u32 v5, v5, v6, s80
	v_and_b32_e32 v5, 0xffff0000, v5
	v_add_co_u32_e32 v0, vcc, s92, v0
	v_or_b32_sdwa v2, v5, v4 dst_sel:DWORD dst_unused:UNUSED_PAD src0_sel:DWORD src1_sel:WORD_1
	s_nop 0
	v_addc_co_u32_e32 v1, vcc, 0, v1, vcc
	global_store_dwordx2 v[0:1], v[2:3], off offset:16
	s_movk_i32 s2, 0xe70
	v_add3_u32 v0, v48, v114, s2
	v_mad_i64_i32 v[0:1], s[2:3], v0, s68, v[18:19]
	v_cvt_pk_bf16_f32 v3, v10, v11
	v_lshl_add_u64 v[0:1], v[0:1], 0, v[180:181]
	v_mov_b32_e32 v183, v193
	v_lshl_add_u64 v[0:1], v[0:1], 0, v[182:183]
	v_cvt_pk_bf16_f32 v2, v8, v9
	global_store_dwordx2 v[0:1], v[2:3], off
	v_cvt_pk_bf16_f32 v3, v14, v15
	v_cvt_pk_bf16_f32 v2, v12, v13
	global_store_dwordx2 v[0:1], v[2:3], off offset:16
	s_branch .LBB0_771

.LBB0_1018:
	s_ashr_i32 s1, s0, 5
	s_and_b32 s4, s0, 31
	v_mov_b32_e32 v2, v208
	s_lshl_b32 s2, s1, 9
	s_lshl_b32 s3, s4, 4
	s_or_b32 s2, s2, s3
	v_ashrrev_i32_e32 v0, 4, v2
	v_add_u32_e32 v4, s2, v0
	v_readlane_b32 s2, v253, 18
	v_readlane_b32 s3, v253, 19
	s_mul_i32 s1, s1, 63
	v_and_b32_e32 v3, 15, v2
	v_mov_b64_e32 v[0:1], s[2:3]
	s_add_i32 s1, s4, s1
	v_mad_i64_i32 v[0:1], s[2:3], v4, s68, v[0:1]
	v_lshlrev_b32_e32 v192, 6, v3
	s_add_i32 s1, s1, 31
	v_lshlrev_b32_e32 v22, 1, v3
	v_lshl_add_u64 v[8:9], v[0:1], 0, v[192:193]
	v_and_b32_e32 v0, -16, v2
	v_sub_u32_e32 v2, s1, v22
	v_ashrrev_i32_e32 v3, 31, v2
	v_readlane_b32 s2, v253, 20
	v_ashrrev_i32_e32 v1, 31, v0
	v_lshlrev_b64 v[2:3], 10, v[2:3]
	v_readlane_b32 s3, v253, 21
	v_lshlrev_b64 v[0:1], 2, v[0:1]
	s_add_i32 s0, s0, s93
	v_lshl_add_u64 v[2:3], s[2:3], 0, v[2:3]
	v_lshl_add_u64 v[6:7], v[2:3], 0, v[0:1]
	global_load_dwordx4 v[2:5], v[6:7], off offset:48
	global_load_dwordx4 v[10:13], v[6:7], off offset:32
	global_load_dwordx4 v[14:17], v[6:7], off offset:16
	global_load_dwordx4 v[18:21], v[6:7], off
	s_cmpk_gt_i32 s0, 0x2ff
	s_waitcnt vmcnt(0)
	v_and_b32_sdwa v6, v20, v218 dst_sel:DWORD dst_unused:UNUSED_PAD src0_sel:WORD_1 src1_sel:DWORD
	v_and_b32_sdwa v7, v18, v218 dst_sel:DWORD dst_unused:UNUSED_PAD src0_sel:WORD_1 src1_sel:DWORD
	v_add3_u32 v7, v18, v7, s80
	v_add3_u32 v6, v20, v6, s80
	v_and_b32_sdwa v18, v21, v218 dst_sel:DWORD dst_unused:UNUSED_PAD src0_sel:WORD_1 src1_sel:DWORD
	v_and_b32_sdwa v20, v19, v218 dst_sel:DWORD dst_unused:UNUSED_PAD src0_sel:WORD_1 src1_sel:DWORD
	v_add3_u32 v18, v21, v18, s80
	v_add3_u32 v19, v19, v20, s80
	v_and_b32_e32 v18, 0xffff0000, v18
	v_and_b32_e32 v20, 0xffff0000, v19
	v_or_b32_sdwa v19, v18, v6 dst_sel:DWORD dst_unused:UNUSED_PAD src0_sel:DWORD src1_sel:WORD_1
	v_or_b32_sdwa v18, v20, v7 dst_sel:DWORD dst_unused:UNUSED_PAD src0_sel:DWORD src1_sel:WORD_1
	v_cvt_pk_bf16_f32 v20, v14, v15
	v_cvt_pk_bf16_f32 v21, v16, v17
	v_and_b32_sdwa v6, v12, v218 dst_sel:DWORD dst_unused:UNUSED_PAD src0_sel:WORD_1 src1_sel:DWORD
	v_and_b32_sdwa v7, v10, v218 dst_sel:DWORD dst_unused:UNUSED_PAD src0_sel:WORD_1 src1_sel:DWORD
	v_add3_u32 v7, v10, v7, s80
	v_add3_u32 v6, v12, v6, s80
	v_and_b32_sdwa v10, v13, v218 dst_sel:DWORD dst_unused:UNUSED_PAD src0_sel:WORD_1 src1_sel:DWORD
	v_and_b32_sdwa v12, v11, v218 dst_sel:DWORD dst_unused:UNUSED_PAD src0_sel:WORD_1 src1_sel:DWORD
	v_add3_u32 v10, v13, v10, s80
	v_add3_u32 v11, v11, v12, s80
	v_and_b32_e32 v10, 0xffff0000, v10
	v_and_b32_e32 v12, 0xffff0000, v11
	v_or_b32_sdwa v11, v10, v6 dst_sel:DWORD dst_unused:UNUSED_PAD src0_sel:DWORD src1_sel:WORD_1
	v_or_b32_sdwa v10, v12, v7 dst_sel:DWORD dst_unused:UNUSED_PAD src0_sel:DWORD src1_sel:WORD_1
	v_cvt_pk_bf16_f32 v12, v2, v3
	v_cvt_pk_bf16_f32 v13, v4, v5
	v_xad_u32 v2, v22, -1, s1
	v_ashrrev_i32_e32 v3, 31, v2
	v_lshlrev_b64 v[2:3], 10, v[2:3]
	v_lshl_add_u64 v[2:3], s[2:3], 0, v[2:3]
	global_store_dwordx4 v[8:9], v[18:21], off
	global_store_dwordx4 v[8:9], v[10:13], off offset:16
	v_lshl_add_u64 v[14:15], v[2:3], 0, v[0:1]
	global_load_dwordx4 v[0:3], v[14:15], off offset:48
	global_load_dwordx4 v[4:7], v[14:15], off offset:32
	global_load_dwordx4 v[10:13], v[14:15], off offset:16
	s_nop 0
	global_load_dwordx4 v[14:17], v[14:15], off
	s_waitcnt vmcnt(0)
	v_and_b32_sdwa v18, v16, v218 dst_sel:DWORD dst_unused:UNUSED_PAD src0_sel:WORD_1 src1_sel:DWORD
	v_cvt_pk_bf16_f32 v14, v14, v15
	v_add3_u32 v16, v16, v18, s80
	v_and_b32_sdwa v18, v17, v218 dst_sel:DWORD dst_unused:UNUSED_PAD src0_sel:WORD_1 src1_sel:DWORD
	v_add3_u32 v17, v17, v18, s80
	v_and_b32_e32 v17, 0xffff0000, v17
	v_or_b32_sdwa v15, v17, v16 dst_sel:DWORD dst_unused:UNUSED_PAD src0_sel:DWORD src1_sel:WORD_1
	v_and_b32_sdwa v17, v10, v218 dst_sel:DWORD dst_unused:UNUSED_PAD src0_sel:WORD_1 src1_sel:DWORD
	v_add3_u32 v10, v10, v17, s80
	v_and_b32_sdwa v17, v11, v218 dst_sel:DWORD dst_unused:UNUSED_PAD src0_sel:WORD_1 src1_sel:DWORD
	v_and_b32_sdwa v16, v12, v218 dst_sel:DWORD dst_unused:UNUSED_PAD src0_sel:WORD_1 src1_sel:DWORD
	v_add3_u32 v11, v11, v17, s80
	v_add3_u32 v12, v12, v16, s80
	v_and_b32_sdwa v16, v13, v218 dst_sel:DWORD dst_unused:UNUSED_PAD src0_sel:WORD_1 src1_sel:DWORD
	v_and_b32_e32 v11, 0xffff0000, v11
	v_add3_u32 v13, v13, v16, s80
	v_or_b32_sdwa v16, v11, v10 dst_sel:DWORD dst_unused:UNUSED_PAD src0_sel:DWORD src1_sel:WORD_1
	v_and_b32_sdwa v10, v6, v218 dst_sel:DWORD dst_unused:UNUSED_PAD src0_sel:WORD_1 src1_sel:DWORD
	v_cvt_pk_bf16_f32 v4, v4, v5
	v_add3_u32 v6, v6, v10, s80
	v_and_b32_sdwa v10, v7, v218 dst_sel:DWORD dst_unused:UNUSED_PAD src0_sel:WORD_1 src1_sel:DWORD
	v_add3_u32 v7, v7, v10, s80
	v_and_b32_e32 v7, 0xffff0000, v7
	v_or_b32_sdwa v5, v7, v6 dst_sel:DWORD dst_unused:UNUSED_PAD src0_sel:DWORD src1_sel:WORD_1
	v_and_b32_sdwa v6, v2, v218 dst_sel:DWORD dst_unused:UNUSED_PAD src0_sel:WORD_1 src1_sel:DWORD
	v_and_b32_sdwa v7, v0, v218 dst_sel:DWORD dst_unused:UNUSED_PAD src0_sel:WORD_1 src1_sel:DWORD
	v_add3_u32 v0, v0, v7, s80
	v_add3_u32 v2, v2, v6, s80
	v_and_b32_sdwa v6, v3, v218 dst_sel:DWORD dst_unused:UNUSED_PAD src0_sel:WORD_1 src1_sel:DWORD
	v_and_b32_sdwa v7, v1, v218 dst_sel:DWORD dst_unused:UNUSED_PAD src0_sel:WORD_1 src1_sel:DWORD
	v_and_b32_e32 v13, 0xffff0000, v13
	v_add3_u32 v3, v3, v6, s80
	v_add3_u32 v1, v1, v7, s80
	v_or_b32_sdwa v17, v13, v12 dst_sel:DWORD dst_unused:UNUSED_PAD src0_sel:DWORD src1_sel:WORD_1
	v_and_b32_e32 v3, 0xffff0000, v3
	v_and_b32_e32 v1, 0xffff0000, v1
	v_or_b32_sdwa v7, v3, v2 dst_sel:DWORD dst_unused:UNUSED_PAD src0_sel:DWORD src1_sel:WORD_1
	v_or_b32_sdwa v6, v1, v0 dst_sel:DWORD dst_unused:UNUSED_PAD src0_sel:DWORD src1_sel:WORD_1
	global_store_dwordx4 v[8:9], v[14:17], off offset:32
	global_store_dwordx4 v[8:9], v[4:7], off offset:48
	s_cbranch_scc0 .LBB0_1018

.LBB0_1023:
	s_or_b64 exec, exec, s[0:1]
	v_lshl_add_u64 v[0:1], v[0:1], 0, v[192:193]
	global_load_dwordx4 v[60:63], v[0:1], off nt
	global_load_dwordx4 v[44:47], v[0:1], off offset:1024 nt
	global_load_dwordx4 v[28:31], v[0:1], off offset:2048 nt
	global_load_dwordx4 v[12:15], v[0:1], off offset:3072 nt
	v_add_co_u32_e32 v2, vcc, 0x1000, v0
	v_min_i32_e32 v67, 0x4000, v80
	s_nop 0
	v_addc_co_u32_e32 v3, vcc, 0, v1, vcc
	global_load_dwordx4 v[56:59], v[2:3], off nt
	global_load_dwordx4 v[40:43], v[2:3], off offset:1024 nt
	global_load_dwordx4 v[24:27], v[2:3], off offset:2048 nt
	global_load_dwordx4 v[8:11], v[2:3], off offset:3072 nt
	v_add_co_u32_e32 v2, vcc, 0x2000, v0
	s_mov_b64 s[0:1], vcc
	s_nop 0
	v_addc_co_u32_e64 v3, s[0:1], 0, v1, s[0:1]
	global_load_dwordx4 v[52:55], v[2:3], off nt
	global_load_dwordx4 v[36:39], v[2:3], off offset:1024 nt
	global_load_dwordx4 v[20:23], v[2:3], off offset:2048 nt
	global_load_dwordx4 v[4:7], v[2:3], off offset:3072 nt
	v_add_co_u32_e32 v0, vcc, 0x3000, v0
	v_ashrrev_i32_e32 v67, 13, v67
	s_nop 0
	v_addc_co_u32_e32 v1, vcc, 0, v1, vcc
	global_load_dwordx4 v[48:51], v[0:1], off nt
	global_load_dwordx4 v[32:35], v[0:1], off offset:1024 nt
	global_load_dwordx4 v[16:19], v[0:1], off offset:2048 nt
	s_nop 0
	global_load_dwordx4 v[0:3], v[0:1], off offset:3072 nt
	s_mov_b64 s[0:1], 0x1000
	s_mov_b32 s6, 0x3a800000
	s_mov_b32 s2, 0x800000
	v_mov_b32_e32 v85, v193
	v_mov_b32_e32 v87, v193
	s_add_i32 s4, s4, s93
	s_cmpk_gt_i32 s4, 0x3ff
	s_waitcnt vmcnt(15)
	v_mov_b32_e32 v94, v61
	s_waitcnt vmcnt(14)
	v_mov_b32_e32 v95, v45
	s_waitcnt vmcnt(13)
	v_mov_b32_e32 v102, v29
	s_waitcnt vmcnt(12)
	v_mov_b32_e32 v103, v13
	v_mov_b32_e32 v90, v60
	v_mov_b32_e32 v91, v44
	v_mov_b32_e32 v100, v28
	v_mov_b32_e32 v101, v12
	v_pk_mul_f32 v[94:95], v[94:95], v[94:95]
	v_pk_mul_f32 v[102:103], v[102:103], v[102:103]
	v_mov_b32_e32 v96, v62
	v_mov_b32_e32 v97, v46
	v_pk_fma_f32 v[90:91], v[90:91], v[90:91], v[94:95]
	v_pk_fma_f32 v[94:95], v[100:101], v[100:101], v[102:103]
	s_waitcnt vmcnt(11)
	v_mov_b32_e32 v102, v57
	s_waitcnt vmcnt(10)
	v_mov_b32_e32 v103, v41
	v_mov_b32_e32 v100, v56
	v_mov_b32_e32 v101, v40
	s_waitcnt vmcnt(9)
	v_mov_b32_e32 v114, v25
	s_waitcnt vmcnt(8)
	v_mov_b32_e32 v115, v9
	v_pk_fma_f32 v[90:91], v[96:97], v[96:97], v[90:91]
	v_pk_mul_f32 v[96:97], v[102:103], v[102:103]
	v_mov_b32_e32 v98, v63
	v_mov_b32_e32 v99, v47
	v_mov_b32_e32 v108, v58
	v_mov_b32_e32 v109, v42
	v_mov_b32_e32 v112, v24
	v_mov_b32_e32 v113, v8
	v_pk_mul_f32 v[102:103], v[114:115], v[114:115]
	v_pk_fma_f32 v[96:97], v[100:101], v[100:101], v[96:97]
	v_mov_b32_e32 v104, v30
	v_mov_b32_e32 v105, v14
	v_mov_b32_e32 v110, v59
	v_mov_b32_e32 v111, v43
	v_mov_b32_e32 v116, v26
	v_mov_b32_e32 v117, v10
	v_pk_fma_f32 v[90:91], v[98:99], v[98:99], v[90:91]
	v_pk_fma_f32 v[98:99], v[112:113], v[112:113], v[102:103]
	v_pk_fma_f32 v[96:97], v[108:109], v[108:109], v[96:97]
	v_mov_b32_e32 v106, v31
	v_mov_b32_e32 v107, v15
	v_mov_b32_e32 v118, v27
	v_mov_b32_e32 v119, v11
	v_pk_fma_f32 v[94:95], v[104:105], v[104:105], v[94:95]
	v_pk_fma_f32 v[98:99], v[116:117], v[116:117], v[98:99]
	v_pk_fma_f32 v[96:97], v[110:111], v[110:111], v[96:97]
	v_pk_fma_f32 v[94:95], v[106:107], v[106:107], v[94:95]
	v_mov_b32_e32 v101, v90
	v_pk_fma_f32 v[98:99], v[118:119], v[118:119], v[98:99]
	v_mov_b32_e32 v100, v96
	v_mov_b32_e32 v90, v97
	v_mov_b32_e32 v103, v94
	v_mov_b32_e32 v102, v98
	v_pk_add_f32 v[90:91], v[100:101], v[90:91]
	v_mov_b32_e32 v94, v99
	v_pk_add_f32 v[90:91], v[90:91], v[102:103]
	v_add_u32_e32 v96, 1, v80
	v_pk_add_f32 v[90:91], v[90:91], v[94:95]
	ds_bpermute_b32 v95, v65, v91
	ds_bpermute_b32 v94, v65, v90
	v_ashrrev_i32_e32 v97, 31, v96
	v_mul_hi_i32_i24_e32 v105, 0x6000, v67
	v_mul_i32_i24_e32 v104, 0x6000, v67
	v_lshlrev_b64 v[102:103], 11, v[96:97]
	s_waitcnt lgkmcnt(0)
	v_pk_add_f32 v[90:91], v[90:91], v[94:95]
	ds_bpermute_b32 v95, v71, v91
	ds_bpermute_b32 v94, v71, v90
	v_lshl_add_u64 v[96:97], s[96:97], 0, v[104:105]
	s_waitcnt vmcnt(7)
	v_mov_b32_e32 v104, v52
	s_waitcnt vmcnt(6)
	v_mov_b32_e32 v105, v36
	s_waitcnt vmcnt(1)
	v_mov_b32_e32 v108, v17
	s_waitcnt lgkmcnt(0)
	v_pk_add_f32 v[90:91], v[90:91], v[94:95]
	ds_bpermute_b32 v95, v73, v91
	ds_bpermute_b32 v94, v73, v90
	s_waitcnt vmcnt(0)
	v_mov_b32_e32 v109, v1
	v_pk_mul_f32 v[108:109], v[108:109], v[108:109]
	v_mov_b32_e32 v128, v19
	v_mov_b32_e32 v129, v3
	s_waitcnt lgkmcnt(0)
	v_pk_add_f32 v[116:117], v[90:91], v[94:95]
	v_mov_b32_e32 v90, v53
	v_mov_b32_e32 v91, v37
	v_pk_mul_f32 v[90:91], v[90:91], v[90:91]
	v_mov_b32_e32 v94, v54
	v_pk_fma_f32 v[90:91], v[104:105], v[104:105], v[90:91]
	v_mov_b32_e32 v95, v38
	v_pk_fma_f32 v[90:91], v[94:95], v[94:95], v[90:91]
	v_mov_b32_e32 v94, v55
	v_mov_b32_e32 v95, v39
	v_pk_fma_f32 v[120:121], v[94:95], v[94:95], v[90:91]
	v_mov_b32_e32 v94, v21
	v_mov_b32_e32 v95, v5
	v_mov_b32_e32 v90, v20
	v_mov_b32_e32 v91, v4
	v_pk_mul_f32 v[94:95], v[94:95], v[94:95]
	ds_bpermute_b32 v119, v75, v117
	v_pk_fma_f32 v[90:91], v[90:91], v[90:91], v[94:95]
	v_mov_b32_e32 v94, v22
	v_mov_b32_e32 v95, v6
	v_pk_fma_f32 v[90:91], v[94:95], v[94:95], v[90:91]
	v_mov_b32_e32 v94, v23
	v_mov_b32_e32 v95, v7
	v_pk_fma_f32 v[122:123], v[94:95], v[94:95], v[90:91]
	v_mov_b32_e32 v94, v49
	v_mov_b32_e32 v95, v33
	v_mov_b32_e32 v90, v48
	v_mov_b32_e32 v91, v32
	v_pk_mul_f32 v[94:95], v[94:95], v[94:95]
	ds_bpermute_b32 v118, v75, v116
	v_pk_fma_f32 v[90:91], v[90:91], v[90:91], v[94:95]
	v_mov_b32_e32 v94, v50
	v_mov_b32_e32 v95, v34
	v_pk_fma_f32 v[90:91], v[94:95], v[94:95], v[90:91]
	v_mov_b32_e32 v94, v51
	v_mov_b32_e32 v95, v35
	v_pk_fma_f32 v[124:125], v[94:95], v[94:95], v[90:91]
	v_lshl_add_u64 v[90:91], v[96:97], 0, s[0:1]
	v_lshl_add_u64 v[104:105], v[90:91], 0, v[192:193]
	v_mov_b32_e32 v94, v16
	v_mov_b32_e32 v95, v0
	global_load_dwordx4 v[104:107], v[104:105], off
	v_pk_fma_f32 v[94:95], v[94:95], v[94:95], v[108:109]
	v_mov_b32_e32 v108, v18
	v_mov_b32_e32 v109, v2
	v_pk_fma_f32 v[126:127], v[108:109], v[108:109], v[94:95]
	global_load_dwordx4 v[108:111], v[76:77], off
	v_lshl_add_u64 v[94:95], v[96:97], 0, v[192:193]
	global_load_dwordx4 v[112:115], v[94:95], off
	v_pk_fma_f32 v[96:97], v[128:129], v[128:129], v[126:127]
	v_mov_b32_e32 v126, v124
	v_mov_b32_e32 v127, v120
	v_mov_b32_e32 v120, v125
	v_pk_add_f32 v[120:121], v[126:127], v[120:121]
	v_mov_b32_e32 v124, v96
	v_mov_b32_e32 v125, v122
	v_pk_add_f32 v[120:121], v[120:121], v[124:125]
	v_mov_b32_e32 v122, v97
	v_pk_add_f32 v[96:97], v[120:121], v[122:123]
	ds_bpermute_b32 v121, v65, v97
	ds_bpermute_b32 v120, v65, v96
	v_add_u32_e32 v100, 2, v80
	v_ashrrev_i32_e32 v101, 31, v100
	v_lshlrev_b64 v[122:123], 11, v[100:101]
	s_waitcnt lgkmcnt(2)
	v_pk_add_f32 v[100:101], v[116:117], v[118:119]
	s_waitcnt lgkmcnt(0)
	v_pk_add_f32 v[96:97], v[96:97], v[120:121]
	ds_bpermute_b32 v119, v71, v97
	ds_bpermute_b32 v118, v71, v96
	ds_bpermute_b32 v117, v89, v101
	ds_bpermute_b32 v116, v89, v100
	s_mov_b32 s0, 0x358637bd
	v_lshlrev_b64 v[98:99], 11, v[80:81]
	s_waitcnt lgkmcnt(2)
	v_pk_add_f32 v[96:97], v[96:97], v[118:119]
	ds_bpermute_b32 v119, v73, v97
	ds_bpermute_b32 v118, v73, v96
	s_waitcnt lgkmcnt(2)
	v_pk_add_f32 v[100:101], v[100:101], v[116:117]
	ds_bpermute_b32 v117, v93, v101
	ds_bpermute_b32 v116, v93, v100
	v_add_u32_e32 v120, 3, v80
	s_waitcnt lgkmcnt(2)
	v_pk_add_f32 v[96:97], v[96:97], v[118:119]
	ds_bpermute_b32 v119, v75, v97
	ds_bpermute_b32 v118, v75, v96
	s_waitcnt lgkmcnt(2)
	v_pk_add_f32 v[100:101], v[100:101], v[116:117]
	v_mov_b64_e32 v[116:117], s[0:1]
	v_pk_fma_f32 v[100:101], v[100:101], s[6:7], v[116:117] op_sel_hi:[1,0,0]
	v_lshl_add_u64 v[98:99], v[78:79], 0, v[98:99]
	s_waitcnt lgkmcnt(0)
	v_pk_add_f32 v[96:97], v[96:97], v[118:119]
	ds_bpermute_b32 v119, v89, v97
	ds_bpermute_b32 v118, v89, v96
	v_mul_f32_e32 v67, 0x4b800000, v101
	v_cmp_gt_f32_e32 vcc, s2, v101
	v_mul_f32_e32 v69, 0x4b800000, v100
	v_cmp_gt_f32_e64 s[0:1], s2, v100
	s_waitcnt lgkmcnt(0)
	v_pk_add_f32 v[96:97], v[96:97], v[118:119]
	ds_bpermute_b32 v119, v93, v97
	ds_bpermute_b32 v118, v93, v96
	v_cndmask_b32_e32 v67, v101, v67, vcc
	v_rsq_f32_e32 v67, v67
	v_cndmask_b32_e64 v69, v100, v69, s[0:1]
	v_rsq_f32_e32 v69, v69
	s_waitcnt lgkmcnt(0)
	v_pk_add_f32 v[96:97], v[96:97], v[118:119]
	v_mul_f32_e32 v81, 0x45800000, v67
	v_pk_fma_f32 v[96:97], v[96:97], s[6:7], v[116:117] op_sel_hi:[1,0,0]
	v_cndmask_b32_e32 v100, v67, v81, vcc
	v_mul_f32_e32 v81, 0x4b800000, v97
	v_cmp_gt_f32_e32 vcc, s2, v97
	v_mul_f32_e32 v83, 0x4b800000, v96
	v_cmp_gt_f32_e64 s[2:3], s2, v96
	v_cndmask_b32_e32 v81, v97, v81, vcc
	v_rsq_f32_e32 v81, v81
	v_cndmask_b32_e64 v83, v96, v83, s[2:3]
	v_rsq_f32_e32 v83, v83
	v_mul_f32_e32 v67, 0x45800000, v69
	v_cndmask_b32_e64 v96, v69, v67, s[0:1]
	v_mul_f32_e32 v67, 0x45800000, v81
	v_cndmask_b32_e32 v92, v81, v67, vcc
	v_mul_f32_e32 v67, 0x45800000, v83
	v_cndmask_b32_e64 v88, v83, v67, s[2:3]
	v_ashrrev_i32_e32 v121, 31, v120
	v_lshlrev_b64 v[120:121], 11, v[120:121]
	v_mov_b32_e32 v83, v193
	s_waitcnt vmcnt(2)
	v_mov_b32_e32 v117, v106
	v_mov_b32_e32 v106, v105
	v_mov_b32_e32 v116, v104
	v_pk_add_f32 v[104:105], v[106:107], 1.0 op_sel_hi:[1,0]
	v_mov_b32_e32 v107, v62
	v_mov_b32_e32 v62, v61
	v_mov_b32_e32 v106, v60
	s_waitcnt vmcnt(1)
	v_mov_b32_e32 v119, v110
	v_pk_mul_f32 v[60:61], v[62:63], v[100:101] op_sel_hi:[1,0]
	v_mov_b32_e32 v110, v109
	v_pk_mul_f32 v[106:107], v[106:107], v[100:101] op_sel_hi:[1,0]
	v_mov_b32_e32 v118, v108
	s_waitcnt vmcnt(0)
	v_mov_b32_e32 v125, v114
	v_pk_mul_f32 v[60:61], v[60:61], v[110:111]
	v_mov_b32_e32 v114, v113
	v_pk_add_f32 v[116:117], v[116:117], 1.0 op_sel_hi:[1,0]
	v_pk_mul_f32 v[106:107], v[106:107], v[118:119]
	v_mov_b32_e32 v124, v112
	v_pk_fma_f32 v[60:61], v[60:61], v[104:105], v[114:115]
	v_pk_fma_f32 v[106:107], v[106:107], v[116:117], v[124:125]
	v_cvt_pk_bf16_f32 v61, v107, v61
	v_cvt_pk_bf16_f32 v60, v106, v60
	v_mov_b32_e32 v62, v56
	v_mov_b32_e32 v63, v58
	v_pk_mul_f32 v[62:63], v[62:63], v[96:97] op_sel_hi:[1,0]
	v_mov_b32_e32 v58, v57
	v_pk_mul_f32 v[62:63], v[62:63], v[118:119]
	v_pk_mul_f32 v[56:57], v[58:59], v[96:97] op_sel_hi:[1,0]
	v_pk_fma_f32 v[62:63], v[62:63], v[116:117], v[124:125]
	v_pk_mul_f32 v[56:57], v[56:57], v[110:111]
	v_pk_fma_f32 v[56:57], v[56:57], v[104:105], v[114:115]
	v_cvt_pk_bf16_f32 v56, v62, v56
	v_cvt_pk_bf16_f32 v57, v63, v57
	v_mov_b32_e32 v58, v52
	v_mov_b32_e32 v59, v54
	v_pk_mul_f32 v[58:59], v[58:59], v[92:93] op_sel_hi:[1,0]
	v_mov_b32_e32 v54, v53
	v_pk_mul_f32 v[58:59], v[118:119], v[58:59]
	v_pk_mul_f32 v[52:53], v[54:55], v[92:93] op_sel_hi:[1,0]
	v_pk_fma_f32 v[58:59], v[58:59], v[116:117], v[124:125]
	v_pk_mul_f32 v[52:53], v[110:111], v[52:53]
	v_pk_fma_f32 v[52:53], v[52:53], v[104:105], v[114:115]
	v_cvt_pk_bf16_f32 v52, v58, v52
	v_cvt_pk_bf16_f32 v53, v59, v53
	v_mov_b32_e32 v54, v48
	v_mov_b32_e32 v55, v50
	v_pk_mul_f32 v[54:55], v[54:55], v[88:89] op_sel_hi:[1,0]
	v_mov_b32_e32 v50, v49
	v_pk_mul_f32 v[54:55], v[118:119], v[54:55]
	v_pk_mul_f32 v[48:49], v[50:51], v[88:89] op_sel_hi:[1,0]
	v_pk_fma_f32 v[54:55], v[116:117], v[54:55], v[124:125]
	v_pk_mul_f32 v[48:49], v[110:111], v[48:49]
	v_pk_fma_f32 v[48:49], v[104:105], v[48:49], v[114:115]
	v_cvt_pk_bf16_f32 v48, v54, v48
	v_cvt_pk_bf16_f32 v49, v55, v49
	global_store_dwordx2 v[98:99], v[60:61], off nt
	v_lshl_add_u64 v[60:61], v[78:79], 0, v[102:103]
	global_store_dwordx2 v[60:61], v[56:57], off nt
	v_lshl_add_u64 v[56:57], v[78:79], 0, v[122:123]
	global_store_dwordx2 v[56:57], v[52:53], off nt
	v_lshl_add_u64 v[52:53], v[78:79], 0, v[120:121]
	global_store_dwordx2 v[52:53], v[48:49], off nt
	v_lshl_add_u64 v[48:49], v[90:91], 0, v[82:83]
	global_load_dwordx4 v[48:51], v[48:49], off
	s_nop 0
	global_load_dwordx4 v[102:105], v[76:77], off offset:1024
	global_load_dwordx4 v[106:109], v[94:95], off offset:1024
	v_readlane_b32 s0, v255, 7
	s_waitcnt vmcnt(2)
	v_mov_b32_e32 v55, v50
	v_mov_b32_e32 v50, v49
	v_mov_b32_e32 v54, v48
	v_pk_add_f32 v[48:49], v[50:51], 1.0 op_sel_hi:[1,0]
	v_mov_b32_e32 v50, v44
	v_mov_b32_e32 v51, v46
	v_pk_mul_f32 v[50:51], v[50:51], v[100:101] op_sel_hi:[1,0]
	s_waitcnt vmcnt(1)
	v_mov_b32_e32 v58, v102
	v_mov_b32_e32 v59, v104
	v_mov_b32_e32 v46, v45
	v_pk_add_f32 v[54:55], v[54:55], 1.0 op_sel_hi:[1,0]
	v_pk_mul_f32 v[50:51], v[50:51], v[58:59]
	s_waitcnt vmcnt(0)
	v_mov_b32_e32 v62, v106
	v_mov_b32_e32 v63, v108
	v_pk_mul_f32 v[44:45], v[46:47], v[100:101] op_sel_hi:[1,0]
	v_mov_b32_e32 v104, v103
	v_pk_fma_f32 v[50:51], v[50:51], v[54:55], v[62:63]
	v_pk_mul_f32 v[44:45], v[44:45], v[104:105]
	v_mov_b32_e32 v108, v107
	v_pk_fma_f32 v[44:45], v[44:45], v[48:49], v[108:109]
	v_cvt_pk_bf16_f32 v44, v50, v44
	v_cvt_pk_bf16_f32 v45, v51, v45
	global_store_dwordx2 v[98:99], v[44:45], off offset:512 nt
	v_mov_b32_e32 v44, v40
	v_mov_b32_e32 v45, v42
	v_pk_mul_f32 v[44:45], v[44:45], v[96:97] op_sel_hi:[1,0]
	v_mov_b32_e32 v42, v41
	v_pk_mul_f32 v[44:45], v[44:45], v[58:59]
	v_pk_mul_f32 v[40:41], v[42:43], v[96:97] op_sel_hi:[1,0]
	v_pk_fma_f32 v[44:45], v[44:45], v[54:55], v[62:63]
	v_pk_mul_f32 v[40:41], v[40:41], v[104:105]
	v_pk_fma_f32 v[40:41], v[40:41], v[48:49], v[108:109]
	v_cvt_pk_bf16_f32 v40, v44, v40
	v_cvt_pk_bf16_f32 v41, v45, v41
	global_store_dwordx2 v[60:61], v[40:41], off offset:512 nt
	v_mov_b32_e32 v40, v36
	v_mov_b32_e32 v41, v38
	v_pk_mul_f32 v[40:41], v[40:41], v[92:93] op_sel_hi:[1,0]
	v_mov_b32_e32 v38, v37
	v_pk_mul_f32 v[40:41], v[40:41], v[58:59]
	v_pk_mul_f32 v[36:37], v[38:39], v[92:93] op_sel_hi:[1,0]
	v_pk_fma_f32 v[40:41], v[40:41], v[54:55], v[62:63]
	v_pk_mul_f32 v[36:37], v[36:37], v[104:105]
	v_pk_fma_f32 v[36:37], v[36:37], v[48:49], v[108:109]
	v_cvt_pk_bf16_f32 v36, v40, v36
	v_cvt_pk_bf16_f32 v37, v41, v37
	global_store_dwordx2 v[56:57], v[36:37], off offset:512 nt
	v_mov_b32_e32 v36, v32
	v_mov_b32_e32 v37, v34
	v_pk_mul_f32 v[36:37], v[36:37], v[88:89] op_sel_hi:[1,0]
	v_mov_b32_e32 v34, v33
	v_pk_mul_f32 v[36:37], v[36:37], v[58:59]
	v_pk_mul_f32 v[32:33], v[34:35], v[88:89] op_sel_hi:[1,0]
	v_pk_fma_f32 v[36:37], v[36:37], v[54:55], v[62:63]
	v_pk_mul_f32 v[32:33], v[32:33], v[104:105]
	v_pk_fma_f32 v[32:33], v[32:33], v[48:49], v[108:109]
	v_cvt_pk_bf16_f32 v32, v36, v32
	v_cvt_pk_bf16_f32 v33, v37, v33
	global_store_dwordx2 v[52:53], v[32:33], off offset:512 nt
	v_lshl_add_u64 v[32:33], v[90:91], 0, v[84:85]
	global_load_dwordx4 v[32:35], v[32:33], off
	s_nop 0
	global_load_dwordx4 v[36:39], v[76:77], off offset:2048
	global_load_dwordx4 v[40:43], v[94:95], off offset:2048
	v_add_u32_e32 v80, s0, v80
	s_waitcnt vmcnt(2)
	v_mov_b32_e32 v45, v34
	v_mov_b32_e32 v34, v33
	v_mov_b32_e32 v44, v32
	v_pk_add_f32 v[32:33], v[34:35], 1.0 op_sel_hi:[1,0]
	v_mov_b32_e32 v34, v28
	v_mov_b32_e32 v35, v30
	v_pk_mul_f32 v[34:35], v[34:35], v[100:101] op_sel_hi:[1,0]
	s_waitcnt vmcnt(1)
	v_mov_b32_e32 v46, v36
	v_mov_b32_e32 v47, v38
	v_mov_b32_e32 v30, v29
	v_pk_add_f32 v[44:45], v[44:45], 1.0 op_sel_hi:[1,0]
	v_pk_mul_f32 v[34:35], v[34:35], v[46:47]
	s_waitcnt vmcnt(0)
	v_mov_b32_e32 v48, v40
	v_mov_b32_e32 v49, v42
	v_pk_mul_f32 v[28:29], v[30:31], v[100:101] op_sel_hi:[1,0]
	v_mov_b32_e32 v38, v37
	v_pk_fma_f32 v[34:35], v[34:35], v[44:45], v[48:49]
	v_pk_mul_f32 v[28:29], v[28:29], v[38:39]
	v_mov_b32_e32 v42, v41
	v_pk_fma_f32 v[28:29], v[28:29], v[32:33], v[42:43]
	v_cvt_pk_bf16_f32 v28, v34, v28
	v_cvt_pk_bf16_f32 v29, v35, v29
	global_store_dwordx2 v[98:99], v[28:29], off offset:1024 nt
	v_mov_b32_e32 v28, v24
	v_mov_b32_e32 v29, v26
	v_pk_mul_f32 v[28:29], v[28:29], v[96:97] op_sel_hi:[1,0]
	v_mov_b32_e32 v26, v25
	v_pk_mul_f32 v[28:29], v[28:29], v[46:47]
	v_pk_mul_f32 v[24:25], v[26:27], v[96:97] op_sel_hi:[1,0]
	v_pk_fma_f32 v[28:29], v[28:29], v[44:45], v[48:49]
	v_pk_mul_f32 v[24:25], v[24:25], v[38:39]
	v_pk_fma_f32 v[24:25], v[24:25], v[32:33], v[42:43]
	v_cvt_pk_bf16_f32 v24, v28, v24
	v_cvt_pk_bf16_f32 v25, v29, v25
	global_store_dwordx2 v[60:61], v[24:25], off offset:1024 nt
	v_mov_b32_e32 v24, v20
	v_mov_b32_e32 v25, v22
	v_pk_mul_f32 v[24:25], v[24:25], v[92:93] op_sel_hi:[1,0]
	v_mov_b32_e32 v22, v21
	v_pk_mul_f32 v[24:25], v[24:25], v[46:47]
	v_pk_mul_f32 v[20:21], v[22:23], v[92:93] op_sel_hi:[1,0]
	v_pk_fma_f32 v[24:25], v[24:25], v[44:45], v[48:49]
	v_pk_mul_f32 v[20:21], v[20:21], v[38:39]
	v_pk_fma_f32 v[20:21], v[20:21], v[32:33], v[42:43]
	v_cvt_pk_bf16_f32 v20, v24, v20
	v_cvt_pk_bf16_f32 v21, v25, v21
	global_store_dwordx2 v[56:57], v[20:21], off offset:1024 nt
	v_mov_b32_e32 v20, v16
	v_mov_b32_e32 v21, v18
	v_pk_mul_f32 v[20:21], v[20:21], v[88:89] op_sel_hi:[1,0]
	v_mov_b32_e32 v18, v17
	v_pk_mul_f32 v[20:21], v[20:21], v[46:47]
	v_pk_mul_f32 v[16:17], v[18:19], v[88:89] op_sel_hi:[1,0]
	v_pk_fma_f32 v[20:21], v[20:21], v[44:45], v[48:49]
	v_pk_mul_f32 v[16:17], v[16:17], v[38:39]
	v_pk_fma_f32 v[16:17], v[16:17], v[32:33], v[42:43]
	v_cvt_pk_bf16_f32 v16, v20, v16
	v_cvt_pk_bf16_f32 v17, v21, v17
	global_store_dwordx2 v[52:53], v[16:17], off offset:1024 nt
	v_lshl_add_u64 v[16:17], v[90:91], 0, v[86:87]
	global_load_dwordx4 v[16:19], v[16:17], off
	s_nop 0
	global_load_dwordx4 v[20:23], v[76:77], off offset:3072
	global_load_dwordx4 v[24:27], v[94:95], off offset:3072
	s_waitcnt vmcnt(2)
	v_mov_b32_e32 v29, v18
	v_mov_b32_e32 v18, v17
	v_mov_b32_e32 v28, v16
	v_pk_add_f32 v[16:17], v[18:19], 1.0 op_sel_hi:[1,0]
	v_mov_b32_e32 v18, v12
	v_mov_b32_e32 v19, v14
	v_pk_mul_f32 v[18:19], v[18:19], v[100:101] op_sel_hi:[1,0]
	s_waitcnt vmcnt(1)
	v_mov_b32_e32 v30, v20
	v_mov_b32_e32 v31, v22
	v_mov_b32_e32 v14, v13
	v_pk_add_f32 v[28:29], v[28:29], 1.0 op_sel_hi:[1,0]
	v_pk_mul_f32 v[18:19], v[18:19], v[30:31]
	s_waitcnt vmcnt(0)
	v_mov_b32_e32 v32, v24
	v_mov_b32_e32 v33, v26
	v_pk_mul_f32 v[12:13], v[14:15], v[100:101] op_sel_hi:[1,0]
	v_mov_b32_e32 v22, v21
	v_pk_fma_f32 v[18:19], v[18:19], v[28:29], v[32:33]
	v_pk_mul_f32 v[12:13], v[12:13], v[22:23]
	v_mov_b32_e32 v26, v25
	v_pk_fma_f32 v[12:13], v[12:13], v[16:17], v[26:27]
	v_cvt_pk_bf16_f32 v12, v18, v12
	v_cvt_pk_bf16_f32 v13, v19, v13
	global_store_dwordx2 v[98:99], v[12:13], off offset:1536 nt
	v_mov_b32_e32 v12, v8
	v_mov_b32_e32 v13, v10
	v_pk_mul_f32 v[12:13], v[12:13], v[96:97] op_sel_hi:[1,0]
	v_mov_b32_e32 v10, v9
	v_pk_mul_f32 v[12:13], v[12:13], v[30:31]
	v_pk_mul_f32 v[8:9], v[10:11], v[96:97] op_sel_hi:[1,0]
	v_pk_fma_f32 v[12:13], v[12:13], v[28:29], v[32:33]
	v_pk_mul_f32 v[8:9], v[8:9], v[22:23]
	v_pk_fma_f32 v[8:9], v[8:9], v[16:17], v[26:27]
	v_cvt_pk_bf16_f32 v8, v12, v8
	v_cvt_pk_bf16_f32 v9, v13, v9
	global_store_dwordx2 v[60:61], v[8:9], off offset:1536 nt
	v_mov_b32_e32 v8, v4
	v_mov_b32_e32 v9, v6
	v_pk_mul_f32 v[8:9], v[8:9], v[92:93] op_sel_hi:[1,0]
	v_mov_b32_e32 v6, v5
	v_pk_mul_f32 v[8:9], v[8:9], v[30:31]
	v_pk_mul_f32 v[4:5], v[6:7], v[92:93] op_sel_hi:[1,0]
	v_pk_fma_f32 v[8:9], v[8:9], v[28:29], v[32:33]
	v_pk_mul_f32 v[4:5], v[4:5], v[22:23]
	v_pk_fma_f32 v[4:5], v[4:5], v[16:17], v[26:27]
	v_cvt_pk_bf16_f32 v4, v8, v4
	v_cvt_pk_bf16_f32 v5, v9, v5
	global_store_dwordx2 v[56:57], v[4:5], off offset:1536 nt
	v_mov_b32_e32 v4, v0
	v_mov_b32_e32 v5, v2
	v_pk_mul_f32 v[4:5], v[4:5], v[88:89] op_sel_hi:[1,0]
	v_mov_b32_e32 v2, v1
	v_pk_mul_f32 v[4:5], v[4:5], v[30:31]
	v_pk_mul_f32 v[0:1], v[2:3], v[88:89] op_sel_hi:[1,0]
	v_pk_fma_f32 v[4:5], v[4:5], v[28:29], v[32:33]
	v_pk_mul_f32 v[0:1], v[0:1], v[22:23]
	v_pk_fma_f32 v[0:1], v[0:1], v[16:17], v[26:27]
	v_cvt_pk_bf16_f32 v0, v4, v0
	v_cvt_pk_bf16_f32 v1, v5, v1
	global_store_dwordx2 v[52:53], v[0:1], off offset:1536 nt
	s_cbranch_scc1 .LBB0_1028

.LBB0_1030:
	s_or_b64 exec, exec, s[4:5]
	v_lshl_add_u64 v[0:1], v[0:1], 0, v[192:193]
	global_load_dwordx4 v[36:39], v[0:1], off nt
	global_load_dwordx4 v[8:11], v[0:1], off offset:1024 nt
	global_load_dwordx4 v[4:7], v[0:1], off offset:2048 nt
	s_nop 0
	global_load_dwordx4 v[0:3], v[0:1], off offset:3072 nt
	s_nop 0
	global_load_dwordx4 v[40:43], v[14:15], off
	v_min_i32_e32 v13, 0x4000, v28
	v_ashrrev_i32_e32 v13, 13, v13
	v_mul_hi_i32_i24_e32 v25, 0x6000, v13
	v_mul_i32_i24_e32 v24, 0x6000, v13
	v_lshl_add_u64 v[26:27], s[96:97], 0, v[24:25]
	s_mov_b64 s[4:5], 0x1000
	v_lshl_add_u64 v[24:25], v[26:27], 0, v[192:193]
	v_lshl_add_u64 v[26:27], v[26:27], 0, s[4:5]
	v_lshl_add_u64 v[48:49], v[26:27], 0, v[192:193]
	global_load_dwordx4 v[44:47], v[24:25], off
	s_mov_b32 s4, 0x800000
	global_load_dwordx4 v[48:51], v[48:49], off
	v_lshlrev_b64 v[28:29], 11, v[28:29]
	v_lshl_add_u64 v[28:29], v[16:17], 0, v[28:29]
	s_waitcnt vmcnt(6)
	v_mov_b32_e32 v54, v37
	s_waitcnt vmcnt(5)
	v_mov_b32_e32 v55, v9
	v_mov_b32_e32 v52, v36
	v_mov_b32_e32 v53, v8
	s_waitcnt vmcnt(4)
	v_mov_b32_e32 v62, v5
	s_waitcnt vmcnt(3)
	v_mov_b32_e32 v63, v1
	v_pk_mul_f32 v[54:55], v[54:55], v[54:55]
	v_mov_b32_e32 v56, v38
	v_mov_b32_e32 v57, v10
	v_mov_b32_e32 v60, v4
	v_mov_b32_e32 v61, v0
	v_pk_mul_f32 v[62:63], v[62:63], v[62:63]
	v_pk_fma_f32 v[52:53], v[52:53], v[52:53], v[54:55]
	v_mov_b32_e32 v58, v39
	v_mov_b32_e32 v59, v11
	v_mov_b32_e32 v64, v6
	v_mov_b32_e32 v65, v2
	v_pk_fma_f32 v[54:55], v[60:61], v[60:61], v[62:63]
	v_pk_fma_f32 v[52:53], v[56:57], v[56:57], v[52:53]
	v_mov_b32_e32 v66, v7
	v_mov_b32_e32 v67, v3
	v_pk_fma_f32 v[54:55], v[64:65], v[64:65], v[54:55]
	v_pk_fma_f32 v[52:53], v[58:59], v[58:59], v[52:53]
	v_pk_fma_f32 v[54:55], v[66:67], v[66:67], v[54:55]
	v_add_f32_e32 v13, v52, v53
	v_add_f32_e32 v13, v13, v54
	v_add_f32_e32 v13, v13, v55
	ds_bpermute_b32 v19, v30, v13
	s_waitcnt vmcnt(2)
	v_mov_b32_e32 v53, v42
	v_mov_b32_e32 v42, v41
	v_mov_b32_e32 v41, v38
	v_mov_b32_e32 v38, v37
	s_waitcnt lgkmcnt(0)
	v_add_f32_e32 v13, v13, v19
	ds_bpermute_b32 v19, v31, v13
	s_waitcnt vmcnt(1)
	v_mov_b32_e32 v37, v46
	v_mov_b32_e32 v46, v45
	s_waitcnt vmcnt(0)
	v_mov_b32_e32 v45, v50
	v_mov_b32_e32 v50, v49
	s_waitcnt lgkmcnt(0)
	v_add_f32_e32 v13, v13, v19
	ds_bpermute_b32 v21, v32, v13
	v_mov_b32_e32 v52, v40
	v_mov_b32_e32 v40, v36
	v_mov_b32_e32 v36, v44
	v_mov_b32_e32 v44, v48
	s_waitcnt lgkmcnt(0)
	v_add_f32_e32 v13, v13, v21
	ds_bpermute_b32 v21, v33, v13
	v_pk_add_f32 v[48:49], v[50:51], 1.0 op_sel_hi:[1,0]
	v_pk_add_f32 v[44:45], v[44:45], 1.0 op_sel_hi:[1,0]
	v_mov_b32_e32 v19, v193
	s_waitcnt lgkmcnt(0)
	v_add_f32_e32 v13, v13, v21
	ds_bpermute_b32 v21, v34, v13
	s_waitcnt lgkmcnt(0)
	v_add_f32_e32 v13, v13, v21
	ds_bpermute_b32 v21, v35, v13
	s_waitcnt lgkmcnt(0)
	v_add_f32_e32 v13, v13, v21
	v_fmamk_f32 v13, v13, 0x3a800000, v219
	v_mul_f32_e32 v21, 0x4b800000, v13
	v_cmp_gt_f32_e32 vcc, s4, v13
	v_readlane_b32 s4, v255, 11
	v_readlane_b32 s5, v255, 12
	v_cndmask_b32_e32 v13, v13, v21, vcc
	v_rsq_f32_e32 v13, v13
	v_add_u32_e32 v12, s4, v12
	s_movk_i32 s4, 0x1ff
	v_mul_f32_e32 v21, 0x45800000, v13
	v_cndmask_b32_e32 v50, v13, v21, vcc
	v_pk_mul_f32 v[40:41], v[40:41], v[50:51] op_sel_hi:[1,0]
	v_pk_mul_f32 v[38:39], v[38:39], v[50:51] op_sel_hi:[1,0]
	v_pk_mul_f32 v[40:41], v[52:53], v[40:41]
	v_pk_mul_f32 v[38:39], v[42:43], v[38:39]
	v_pk_fma_f32 v[36:37], v[44:45], v[40:41], v[36:37]
	v_pk_fma_f32 v[38:39], v[48:49], v[38:39], v[46:47]
	v_cvt_pk_bf16_f32 v36, v36, v38
	v_cvt_pk_bf16_f32 v37, v37, v39
	global_store_dwordx2 v[28:29], v[36:37], off nt
	global_load_dwordx4 v[36:39], v[14:15], off offset:1024
	v_lshl_add_u64 v[40:41], v[26:27], 0, v[18:19]
	global_load_dwordx4 v[40:43], v[40:41], off
	s_nop 0
	global_load_dwordx4 v[44:47], v[24:25], off offset:1024
	v_mov_b32_e32 v48, v8
	v_mov_b32_e32 v49, v10
	v_mov_b32_e32 v10, v9
	v_pk_mul_f32 v[8:9], v[48:49], v[50:51] op_sel_hi:[1,0]
	v_pk_mul_f32 v[10:11], v[10:11], v[50:51] op_sel_hi:[1,0]
	v_mov_b32_e32 v21, v193
	v_cmp_lt_i32_e32 vcc, s4, v12
	s_or_b64 s[2:3], vcc, s[2:3]
	s_waitcnt vmcnt(2)
	v_mov_b32_e32 v49, v38
	s_waitcnt vmcnt(1)
	v_mov_b32_e32 v53, v42
	v_mov_b32_e32 v38, v37
	v_mov_b32_e32 v42, v41
	v_mov_b32_e32 v48, v36
	v_mov_b32_e32 v52, v40
	s_waitcnt vmcnt(0)
	v_mov_b32_e32 v55, v46
	v_mov_b32_e32 v46, v45
	v_pk_mul_f32 v[10:11], v[10:11], v[38:39]
	v_pk_add_f32 v[38:39], v[42:43], 1.0 op_sel_hi:[1,0]
	v_mov_b32_e32 v54, v44
	v_pk_mul_f32 v[8:9], v[8:9], v[48:49]
	v_pk_add_f32 v[36:37], v[52:53], 1.0 op_sel_hi:[1,0]
	v_pk_fma_f32 v[10:11], v[10:11], v[38:39], v[46:47]
	v_pk_fma_f32 v[8:9], v[8:9], v[36:37], v[54:55]
	v_cvt_pk_bf16_f32 v9, v9, v11
	v_cvt_pk_bf16_f32 v8, v8, v10
	global_store_dwordx2 v[28:29], v[8:9], off offset:512 nt
	global_load_dwordx4 v[8:11], v[14:15], off offset:2048
	v_lshl_add_u64 v[36:37], v[26:27], 0, v[20:21]
	global_load_dwordx4 v[36:39], v[36:37], off
	s_nop 0
	global_load_dwordx4 v[40:43], v[24:25], off offset:2048
	v_mov_b32_e32 v44, v4
	v_mov_b32_e32 v45, v6
	v_mov_b32_e32 v6, v5
	v_pk_mul_f32 v[4:5], v[44:45], v[50:51] op_sel_hi:[1,0]
	v_pk_mul_f32 v[6:7], v[6:7], v[50:51] op_sel_hi:[1,0]
	v_mov_b32_e32 v23, v193
	s_waitcnt vmcnt(2)
	v_mov_b32_e32 v45, v10
	s_waitcnt vmcnt(1)
	v_mov_b32_e32 v47, v38
	v_mov_b32_e32 v10, v9
	v_mov_b32_e32 v38, v37
	v_mov_b32_e32 v44, v8
	v_mov_b32_e32 v46, v36
	s_waitcnt vmcnt(0)
	v_mov_b32_e32 v49, v42
	v_mov_b32_e32 v42, v41
	v_pk_mul_f32 v[6:7], v[6:7], v[10:11]
	v_pk_add_f32 v[10:11], v[38:39], 1.0 op_sel_hi:[1,0]
	v_mov_b32_e32 v48, v40
	v_pk_mul_f32 v[4:5], v[4:5], v[44:45]
	v_pk_add_f32 v[8:9], v[46:47], 1.0 op_sel_hi:[1,0]
	v_pk_fma_f32 v[6:7], v[6:7], v[10:11], v[42:43]
	v_pk_fma_f32 v[4:5], v[4:5], v[8:9], v[48:49]
	v_cvt_pk_bf16_f32 v5, v5, v7
	v_cvt_pk_bf16_f32 v4, v4, v6
	global_store_dwordx2 v[28:29], v[4:5], off offset:1024 nt
	global_load_dwordx4 v[4:7], v[14:15], off offset:3072
	v_lshl_add_u64 v[8:9], v[26:27], 0, v[22:23]
	global_load_dwordx4 v[8:11], v[8:9], off
	s_nop 0
	global_load_dwordx4 v[24:27], v[24:25], off offset:3072
	v_mov_b32_e32 v36, v0
	v_mov_b32_e32 v37, v2
	v_mov_b32_e32 v2, v1
	v_pk_mul_f32 v[0:1], v[36:37], v[50:51] op_sel_hi:[1,0]
	v_pk_mul_f32 v[2:3], v[2:3], v[50:51] op_sel_hi:[1,0]
	s_waitcnt vmcnt(2)
	v_mov_b32_e32 v37, v6
	s_waitcnt vmcnt(1)
	v_mov_b32_e32 v39, v10
	v_mov_b32_e32 v6, v5
	v_mov_b32_e32 v10, v9
	v_mov_b32_e32 v36, v4
	v_mov_b32_e32 v38, v8
	s_waitcnt vmcnt(0)
	v_mov_b32_e32 v41, v26
	v_mov_b32_e32 v26, v25
	v_pk_mul_f32 v[2:3], v[2:3], v[6:7]
	v_pk_add_f32 v[6:7], v[10:11], 1.0 op_sel_hi:[1,0]
	v_mov_b32_e32 v40, v24
	v_pk_mul_f32 v[0:1], v[0:1], v[36:37]
	v_pk_add_f32 v[4:5], v[38:39], 1.0 op_sel_hi:[1,0]
	v_pk_fma_f32 v[2:3], v[2:3], v[6:7], v[26:27]
	v_pk_fma_f32 v[0:1], v[0:1], v[4:5], v[40:41]
	v_cvt_pk_bf16_f32 v1, v1, v3
	v_cvt_pk_bf16_f32 v0, v0, v2
	global_store_dwordx2 v[28:29], v[0:1], off offset:1536 nt
	s_andn2_b64 exec, exec, s[2:3]
	s_cbranch_execz .LBB0_1035

.LBB0_1036:
	s_ashr_i32 s1, s0, 5
	v_mov_b32_e32 v2, v208
	s_and_b32 s2, s0, 31
	s_lshl_b32 s3, s1, 9
	s_mul_i32 s1, s1, 63
	s_lshl_b32 s4, s2, 4
	v_and_b32_e32 v4, 15, v2
	s_add_i32 s1, s2, s1
	v_ashrrev_i32_e32 v3, 4, v2
	s_or_b32 s3, s3, s4
	s_add_i32 s1, s1, 31
	v_lshlrev_b32_e32 v6, 1, v4
	v_mov_b64_e32 v[0:1], s[6:7]
	v_add_u32_e32 v5, s3, v3
	v_lshlrev_b32_e32 v192, 6, v4
	v_sub_u32_e32 v4, s1, v6
	v_and_b32_e32 v2, -16, v2
	v_mad_i64_i32 v[0:1], s[2:3], v5, s68, v[0:1]
	v_xad_u32 v6, v6, -1, s1
	v_ashrrev_i32_e32 v5, 31, v4
	v_ashrrev_i32_e32 v3, 31, v2
	v_lshl_add_u64 v[16:17], v[0:1], 0, v[192:193]
	v_ashrrev_i32_e32 v7, 31, v6
	v_lshlrev_b64 v[0:1], 10, v[4:5]
	v_lshlrev_b64 v[2:3], 2, v[2:3]
	v_lshlrev_b64 v[4:5], 10, v[6:7]
	v_lshl_add_u64 v[0:1], s[8:9], 0, v[0:1]
	v_lshl_add_u64 v[4:5], s[8:9], 0, v[4:5]
	v_lshl_add_u64 v[12:13], v[0:1], 0, v[2:3]
	v_lshl_add_u64 v[18:19], v[4:5], 0, v[2:3]
	global_load_dwordx4 v[0:3], v[12:13], off
	global_load_dwordx4 v[4:7], v[12:13], off offset:16
	global_load_dwordx4 v[8:11], v[12:13], off offset:32
	s_nop 0
	global_load_dwordx4 v[12:15], v[12:13], off offset:48
	s_add_i32 s0, s0, s93
	s_cmpk_gt_i32 s0, 0x2ff
	s_waitcnt vmcnt(3)
	v_and_b32_sdwa v22, v3, v218 dst_sel:DWORD dst_unused:UNUSED_PAD src0_sel:WORD_1 src1_sel:DWORD
	s_waitcnt vmcnt(2)
	v_and_b32_sdwa v26, v7, v218 dst_sel:DWORD dst_unused:UNUSED_PAD src0_sel:WORD_1 src1_sel:DWORD
	v_and_b32_sdwa v27, v5, v218 dst_sel:DWORD dst_unused:UNUSED_PAD src0_sel:WORD_1 src1_sel:DWORD
	v_and_b32_sdwa v20, v2, v218 dst_sel:DWORD dst_unused:UNUSED_PAD src0_sel:WORD_1 src1_sel:DWORD
	v_cvt_pk_bf16_f32 v0, v0, v1
	v_and_b32_sdwa v24, v6, v218 dst_sel:DWORD dst_unused:UNUSED_PAD src0_sel:WORD_1 src1_sel:DWORD
	v_and_b32_sdwa v25, v4, v218 dst_sel:DWORD dst_unused:UNUSED_PAD src0_sel:WORD_1 src1_sel:DWORD
	s_waitcnt vmcnt(1)
	v_and_b32_sdwa v30, v11, v218 dst_sel:DWORD dst_unused:UNUSED_PAD src0_sel:WORD_1 src1_sel:DWORD
	v_and_b32_sdwa v31, v9, v218 dst_sel:DWORD dst_unused:UNUSED_PAD src0_sel:WORD_1 src1_sel:DWORD
	s_waitcnt vmcnt(0)
	v_and_b32_sdwa v34, v15, v218 dst_sel:DWORD dst_unused:UNUSED_PAD src0_sel:WORD_1 src1_sel:DWORD
	v_and_b32_sdwa v35, v13, v218 dst_sel:DWORD dst_unused:UNUSED_PAD src0_sel:WORD_1 src1_sel:DWORD
	v_add3_u32 v3, v3, v22, s80
	v_add3_u32 v7, v7, v26, s80
	v_add3_u32 v5, v5, v27, s80
	v_and_b32_sdwa v28, v10, v218 dst_sel:DWORD dst_unused:UNUSED_PAD src0_sel:WORD_1 src1_sel:DWORD
	v_and_b32_sdwa v29, v8, v218 dst_sel:DWORD dst_unused:UNUSED_PAD src0_sel:WORD_1 src1_sel:DWORD
	v_and_b32_sdwa v32, v14, v218 dst_sel:DWORD dst_unused:UNUSED_PAD src0_sel:WORD_1 src1_sel:DWORD
	v_and_b32_sdwa v33, v12, v218 dst_sel:DWORD dst_unused:UNUSED_PAD src0_sel:WORD_1 src1_sel:DWORD
	v_add3_u32 v2, v2, v20, s80
	v_add3_u32 v4, v4, v25, s80
	v_add3_u32 v6, v6, v24, s80
	v_add3_u32 v11, v11, v30, s80
	v_add3_u32 v9, v9, v31, s80
	v_add3_u32 v15, v15, v34, s80
	v_add3_u32 v13, v13, v35, s80
	v_and_b32_e32 v3, 0xffff0000, v3
	v_and_b32_e32 v7, 0xffff0000, v7
	v_and_b32_e32 v5, 0xffff0000, v5
	v_add3_u32 v8, v8, v29, s80
	v_add3_u32 v10, v10, v28, s80
	v_add3_u32 v12, v12, v33, s80
	v_add3_u32 v14, v14, v32, s80
	v_and_b32_e32 v11, 0xffff0000, v11
	v_and_b32_e32 v9, 0xffff0000, v9
	v_and_b32_e32 v15, 0xffff0000, v15
	v_and_b32_e32 v13, 0xffff0000, v13
	v_or_b32_sdwa v1, v3, v2 dst_sel:DWORD dst_unused:UNUSED_PAD src0_sel:DWORD src1_sel:WORD_1
	v_or_b32_sdwa v3, v7, v6 dst_sel:DWORD dst_unused:UNUSED_PAD src0_sel:DWORD src1_sel:WORD_1
	v_or_b32_sdwa v2, v5, v4 dst_sel:DWORD dst_unused:UNUSED_PAD src0_sel:DWORD src1_sel:WORD_1
	v_or_b32_sdwa v5, v11, v10 dst_sel:DWORD dst_unused:UNUSED_PAD src0_sel:DWORD src1_sel:WORD_1
	v_or_b32_sdwa v4, v9, v8 dst_sel:DWORD dst_unused:UNUSED_PAD src0_sel:DWORD src1_sel:WORD_1
	v_or_b32_sdwa v7, v15, v14 dst_sel:DWORD dst_unused:UNUSED_PAD src0_sel:DWORD src1_sel:WORD_1
	v_or_b32_sdwa v6, v13, v12 dst_sel:DWORD dst_unused:UNUSED_PAD src0_sel:DWORD src1_sel:WORD_1
	global_store_dwordx4 v[16:17], v[0:3], off
	global_store_dwordx4 v[16:17], v[4:7], off offset:16
	global_load_dwordx4 v[0:3], v[18:19], off
	s_nop 0
	global_load_dwordx4 v[4:7], v[18:19], off offset:16
	global_load_dwordx4 v[8:11], v[18:19], off offset:32
	global_load_dwordx4 v[12:15], v[18:19], off offset:48
	s_waitcnt vmcnt(3)
	v_and_b32_sdwa v20, v3, v218 dst_sel:DWORD dst_unused:UNUSED_PAD src0_sel:WORD_1 src1_sel:DWORD
	s_waitcnt vmcnt(2)
	v_and_b32_sdwa v24, v7, v218 dst_sel:DWORD dst_unused:UNUSED_PAD src0_sel:WORD_1 src1_sel:DWORD
	v_and_b32_sdwa v25, v5, v218 dst_sel:DWORD dst_unused:UNUSED_PAD src0_sel:WORD_1 src1_sel:DWORD
	v_and_b32_sdwa v18, v2, v218 dst_sel:DWORD dst_unused:UNUSED_PAD src0_sel:WORD_1 src1_sel:DWORD
	v_cvt_pk_bf16_f32 v0, v0, v1
	v_and_b32_sdwa v22, v6, v218 dst_sel:DWORD dst_unused:UNUSED_PAD src0_sel:WORD_1 src1_sel:DWORD
	v_and_b32_sdwa v23, v4, v218 dst_sel:DWORD dst_unused:UNUSED_PAD src0_sel:WORD_1 src1_sel:DWORD
	s_waitcnt vmcnt(1)
	v_and_b32_sdwa v28, v11, v218 dst_sel:DWORD dst_unused:UNUSED_PAD src0_sel:WORD_1 src1_sel:DWORD
	v_and_b32_sdwa v29, v9, v218 dst_sel:DWORD dst_unused:UNUSED_PAD src0_sel:WORD_1 src1_sel:DWORD
	s_waitcnt vmcnt(0)
	v_and_b32_sdwa v32, v15, v218 dst_sel:DWORD dst_unused:UNUSED_PAD src0_sel:WORD_1 src1_sel:DWORD
	v_and_b32_sdwa v33, v13, v218 dst_sel:DWORD dst_unused:UNUSED_PAD src0_sel:WORD_1 src1_sel:DWORD
	v_add3_u32 v3, v3, v20, s80
	v_add3_u32 v7, v7, v24, s80
	v_add3_u32 v5, v5, v25, s80
	v_and_b32_sdwa v26, v10, v218 dst_sel:DWORD dst_unused:UNUSED_PAD src0_sel:WORD_1 src1_sel:DWORD
	v_and_b32_sdwa v27, v8, v218 dst_sel:DWORD dst_unused:UNUSED_PAD src0_sel:WORD_1 src1_sel:DWORD
	v_and_b32_sdwa v30, v14, v218 dst_sel:DWORD dst_unused:UNUSED_PAD src0_sel:WORD_1 src1_sel:DWORD
	v_and_b32_sdwa v31, v12, v218 dst_sel:DWORD dst_unused:UNUSED_PAD src0_sel:WORD_1 src1_sel:DWORD
	v_add3_u32 v2, v2, v18, s80
	v_add3_u32 v4, v4, v23, s80
	v_add3_u32 v6, v6, v22, s80
	v_add3_u32 v11, v11, v28, s80
	v_add3_u32 v9, v9, v29, s80
	v_add3_u32 v15, v15, v32, s80
	v_add3_u32 v13, v13, v33, s80
	v_and_b32_e32 v3, 0xffff0000, v3
	v_and_b32_e32 v7, 0xffff0000, v7
	v_and_b32_e32 v5, 0xffff0000, v5
	v_add3_u32 v8, v8, v27, s80
	v_add3_u32 v10, v10, v26, s80
	v_add3_u32 v12, v12, v31, s80
	v_add3_u32 v14, v14, v30, s80
	v_and_b32_e32 v11, 0xffff0000, v11
	v_and_b32_e32 v9, 0xffff0000, v9
	v_and_b32_e32 v15, 0xffff0000, v15
	v_and_b32_e32 v13, 0xffff0000, v13
	v_or_b32_sdwa v1, v3, v2 dst_sel:DWORD dst_unused:UNUSED_PAD src0_sel:DWORD src1_sel:WORD_1
	v_or_b32_sdwa v3, v7, v6 dst_sel:DWORD dst_unused:UNUSED_PAD src0_sel:DWORD src1_sel:WORD_1
	v_or_b32_sdwa v2, v5, v4 dst_sel:DWORD dst_unused:UNUSED_PAD src0_sel:DWORD src1_sel:WORD_1
	v_or_b32_sdwa v5, v11, v10 dst_sel:DWORD dst_unused:UNUSED_PAD src0_sel:DWORD src1_sel:WORD_1
	v_or_b32_sdwa v4, v9, v8 dst_sel:DWORD dst_unused:UNUSED_PAD src0_sel:DWORD src1_sel:WORD_1
	v_or_b32_sdwa v7, v15, v14 dst_sel:DWORD dst_unused:UNUSED_PAD src0_sel:DWORD src1_sel:WORD_1
	v_or_b32_sdwa v6, v13, v12 dst_sel:DWORD dst_unused:UNUSED_PAD src0_sel:DWORD src1_sel:WORD_1
	global_store_dwordx4 v[16:17], v[0:3], off offset:32
	global_store_dwordx4 v[16:17], v[4:7], off offset:48
	s_cbranch_scc0 .LBB0_1036

.LBB0_1084:
	v_add_u32_e32 v28, s0, v5
	ds_read2_b32 v[22:23], v28 offset1:32
	v_add_u32_e32 v24, v18, v20
	v_add_u32_e32 v25, v19, v20
	v_add_u32_e32 v26, v7, v20
	v_add_u32_e32 v27, v8, v20
	v_add_u32_e32 v29, v9, v20
	v_add_u32_e32 v30, v10, v20
	v_add_u32_e32 v31, v11, v20
	v_and_b32_e32 v32, 63, v24
	v_and_b32_e32 v33, 62, v25
	ds_read2_b32 v[24:25], v28 offset0:64 offset1:96
	v_and_b32_e32 v21, 56, v20
	v_and_b32_e32 v34, 61, v26
	v_and_b32_e32 v35, 60, v27
	v_and_b32_e32 v36, 59, v29
	v_and_b32_e32 v30, 58, v30
	v_and_b32_e32 v31, 57, v31
	v_lshlrev_b32_e32 v21, 2, v21
	ds_read2_b32 v[26:27], v28 offset0:128 offset1:160
	v_lshlrev_b32_e32 v32, 2, v32
	v_lshlrev_b32_e32 v33, 2, v33
	v_lshlrev_b32_e32 v34, 2, v34
	v_lshlrev_b32_e32 v35, 2, v35
	v_lshlrev_b32_e32 v36, 2, v36
	v_lshlrev_b32_e32 v30, 2, v30
	v_lshlrev_b32_e32 v31, 2, v31
	ds_read2_b32 v[28:29], v28 offset0:192 offset1:224
	ds_read_b32 v21, v21 offset:8192
	ds_read_b32 v32, v32 offset:8192
	ds_read_b32 v33, v33 offset:8192
	ds_read_b32 v34, v34 offset:8192
	ds_read_b32 v35, v35 offset:8192
	ds_read_b32 v36, v36 offset:8192
	ds_read_b32 v30, v30 offset:8192
	ds_read_b32 v31, v31 offset:8192
	s_waitcnt lgkmcnt(7)
	v_fmac_f32_e32 v0, v21, v22
	s_waitcnt lgkmcnt(6)
	v_fmac_f32_e32 v0, v32, v23
	s_waitcnt lgkmcnt(5)
	v_fmac_f32_e32 v0, v33, v24
	s_waitcnt lgkmcnt(4)
	v_fmac_f32_e32 v0, v34, v25
	s_waitcnt lgkmcnt(3)
	v_fmac_f32_e32 v0, v35, v26
	s_waitcnt lgkmcnt(2)
	v_fmac_f32_e32 v0, v36, v27
	s_addk_i32 s0, 0x400
	s_waitcnt lgkmcnt(1)
	v_fmac_f32_e32 v0, v30, v28
	v_add_u32_e32 v20, v20, v12
	s_cmpk_lg_i32 s0, 0x2000
	s_waitcnt lgkmcnt(0)
	v_fmac_f32_e32 v0, v31, v29
	s_cbranch_scc1 .LBB0_1084
	v_cvt_pk_bf16_f32 v7, v13, v14
	v_cvt_pk_bf16_f32 v9, v17, v0
	v_add_u32_e32 v0, s4, v1
	v_cvt_pk_bf16_f32 v6, v3, v6
	v_ashrrev_i32_e32 v1, 31, v0
	v_readlane_b32 s0, v253, 22
	v_lshlrev_b64 v[0:1], 10, v[0:1]
	v_readlane_b32 s1, v253, 23
	s_nop 1
	v_lshl_add_u64 v[0:1], s[0:1], 0, v[0:1]
	s_and_b32 s0, s3, 0x7fffff00
	s_lshl_b32 s78, s0, 1
	v_and_b32_e32 v2, 56, v2
	v_cvt_pk_bf16_f32 v8, v15, v16
	v_lshl_add_u64 v[0:1], v[0:1], 0, s[78:79]
	s_lshl_b32 s78, s2, 1
	v_lshl_add_u64 v[0:1], v[0:1], 0, s[78:79]
	v_lshlrev_b32_e32 v192, 1, v2
	v_lshl_add_u64 v[0:1], v[0:1], 0, v[192:193]
	global_store_dwordx4 v[0:1], v[6:9], off
	s_barrier
	s_mov_b64 s[0:1], 0
.LBB0_1086:
	s_and_b64 vcc, exec, s[0:1]
	s_cbranch_vccz .LBB0_1088
	s_add_i32 s0, s74, 0xffffe8b6
	s_bfe_u32 s2, s0, 0x10003
	s_lshr_b32 s3, s0, 4
	s_mul_i32 s1, s2, 24
	s_add_i32 s1, s1, s3
	s_lshl_b32 s4, s1, 2
	v_mov_b32_e32 v0, s4
	global_load_dword v5, v0, s[58:59]
	s_lshl_b32 s5, s1, 6
	v_and_or_b32 v192, v4, 63, s5
	v_lshlrev_b64 v[0:1], 2, v[192:193]
	v_lshl_add_u64 v[2:3], s[54:55], 0, v[0:1]
	v_lshl_add_u64 v[0:1], s[56:57], 0, v[0:1]
	global_load_dword v2, v[2:3], off
	s_nop 0
	global_load_dword v3, v[0:1], off
	v_ashrrev_i32_e32 v0, 6, v4
	s_and_b32 s4, s0, 7
	s_mov_b32 s6, 0x3fb8aa3b
	v_lshl_add_u32 v0, s4, 2, v0
	s_cmp_eq_u32 s2, 0
	v_sub_u32_e32 v1, 31, v0
	s_cselect_b64 vcc, -1, 0
	v_cndmask_b32_e32 v0, v0, v1, vcc
	v_cvt_f32_i32_e32 v6, v0
	s_mov_b32 s7, 0xc2ce8ed0
	s_mov_b32 s9, 0x42b17218
	v_cvt_f64_i32_e32 v[0:1], v0
	s_mov_b32 s0, 0x6dc9c883
	s_mov_b32 s1, 0x3fc45f30
	v_lshlrev_b32_e32 v16, 3, v4
	s_lshl_b32 s78, s4, 7
	s_waitcnt vmcnt(2)
	v_mul_f32_e32 v7, 0x3fb8aa3b, v5
	v_fma_f32 v10, v5, s6, -v7
	v_rndne_f32_e32 v8, v7
	v_fmac_f32_e32 v10, 0x32a5705f, v5
	v_sub_f32_e32 v11, v7, v8
	v_add_f32_e32 v10, v11, v10
	v_cvt_i32_f32_e32 v12, v8
	v_exp_f32_e32 v11, v10
	s_waitcnt vmcnt(1)
	v_mul_f32_e32 v13, v2, v6
	s_waitcnt vmcnt(0)
	v_cvt_f64_f32_e32 v[6:7], v3
	v_pk_mul_f32 v[8:9], v[2:3], v[2:3]
	v_mov_b32_e32 v10, v3
	v_ldexp_f32 v3, v11, v12
	v_cmp_ngt_f32_e32 vcc, s7, v5
	v_mul_f64 v[0:1], v[0:1], v[6:7]
	v_pk_add_f32 v[8:9], v[8:9], v[8:9] op_sel:[0,1] op_sel_hi:[0,1]
	v_cndmask_b32_e32 v3, 0, v3, vcc
	v_cmp_nlt_f32_e32 vcc, s9, v5
	s_nop 1
	v_cndmask_b32_e32 v3, v228, v3, vcc
	v_mul_f32_e32 v5, v13, v3
	v_cvt_f64_f32_e32 v[12:13], v3
	v_mul_f32_e32 v3, v2, v3
	v_mul_f32_e32 v11, 0x3fb8aa3b, v5
	v_mul_f64 v[0:1], v[0:1], v[12:13]
	v_mul_f32_e32 v17, 0x3fb8aa3b, v3
	v_fma_f32 v18, v5, s6, -v11
	v_rndne_f32_e32 v19, v11
	v_mul_f64 v[6:7], v[6:7], v[12:13]
	v_mul_f64 v[12:13], v[0:1], s[0:1]
	v_fma_f32 v20, v3, s6, -v17
	v_rndne_f32_e32 v21, v17
	v_fmac_f32_e32 v18, 0x32a5705f, v5
	v_sub_f32_e32 v11, v11, v19
	v_rndne_f64_e32 v[12:13], v[12:13]
	v_fmac_f32_e32 v20, 0x32a5705f, v3
	v_sub_f32_e32 v17, v17, v21
	v_add_f32_e32 v11, v11, v18
	v_cvt_i32_f32_e32 v19, v19
	v_fma_f64 v[0:1], v[0:1], s[0:1], -v[12:13]
	v_add_f32_e32 v12, v17, v20
	v_exp_f32_e32 v11, v11
	v_mul_f64 v[14:15], v[6:7], s[0:1]
	v_cvt_i32_f32_e32 v21, v21
	v_cvt_f32_f64_e32 v0, v[0:1]
	v_exp_f32_e32 v1, v12
	v_rndne_f64_e32 v[14:15], v[14:15]
	v_fma_f64 v[6:7], v[6:7], s[0:1], -v[14:15]
	v_cvt_f32_f64_e32 v6, v[6:7]
	v_cos_f32_e32 v7, v0
	v_sin_f32_e32 v12, v0
	v_ldexp_f32 v0, v11, v19
	v_cmp_ngt_f32_e32 vcc, s7, v5
	v_cos_f32_e32 v14, v6
	v_sin_f32_e32 v13, v6
	v_ldexp_f32 v1, v1, v21
	v_cndmask_b32_e32 v0, 0, v0, vcc
	v_cmp_ngt_f32_e32 vcc, s7, v3
	s_nop 1
	v_cndmask_b32_e32 v1, 0, v1, vcc
	v_cmp_nlt_f32_e32 vcc, s9, v5
	s_nop 1
	v_cndmask_b32_e32 v5, v228, v0, vcc
	v_cmp_nlt_f32_e32 vcc, s9, v3
	v_mul_f32_e32 v6, v5, v12
	v_mul_f32_e32 v0, v5, v7
	v_cndmask_b32_e32 v1, v228, v1, vcc
	v_mul_f32_e32 v13, v1, v13
	v_fma_f32 v12, v1, v14, -1.0
	v_pk_mul_f32 v[10:11], v[10:11], v[12:13] op_sel:[0,1] op_sel_hi:[0,0]
	v_pk_fma_f32 v[14:15], v[2:3], v[12:13], v[10:11]
	v_pk_fma_f32 v[2:3], v[2:3], v[12:13], v[10:11] op_sel_hi:[0,1,1] neg_lo:[0,0,1] neg_hi:[0,0,1]
	v_div_scale_f32 v1, s[0:1], v9, v9, v3
	v_div_scale_f32 v5, s[0:1], v8, v8, v14
	v_rcp_f32_e32 v7, v1
	v_rcp_f32_e32 v10, v5
	v_div_scale_f32 v2, vcc, v3, v9, v3
	v_fma_f32 v12, -v1, v7, 1.0
	v_fma_f32 v13, -v5, v10, 1.0
	v_fmac_f32_e32 v7, v12, v7
	v_div_scale_f32 v11, s[0:1], v14, v8, v14
	v_fmac_f32_e32 v10, v13, v10
	v_mul_f32_e32 v12, v2, v7
	v_mul_f32_e32 v13, v11, v10
	v_fma_f32 v15, -v1, v12, v2
	v_fma_f32 v17, -v5, v13, v11
	v_fmac_f32_e32 v12, v15, v7
	v_fmac_f32_e32 v13, v17, v10
	v_fma_f32 v1, -v1, v12, v2
	v_fma_f32 v2, -v5, v13, v11
	v_div_fmas_f32 v1, v1, v7, v12
	s_mov_b64 vcc, s[0:1]
	v_div_fixup_f32 v3, v1, v9, v3
	v_div_fmas_f32 v1, v2, v10, v13
	v_div_fixup_f32 v2, v1, v8, v14
	v_pk_mul_f32 v[6:7], v[6:7], v[2:3] op_sel:[0,1] op_sel_hi:[0,0]
	v_pk_fma_f32 v[8:9], v[0:1], v[2:3], v[6:7] neg_lo:[0,0,1] neg_hi:[0,0,1]
	v_pk_fma_f32 v[0:1], v[0:1], v[2:3], v[6:7] op_sel_hi:[0,1,1]
	v_ashrrev_i32_e32 v2, 2, v4
	v_add_u32_e32 v0, s5, v2
	v_mov_b32_e32 v9, v1
	v_ashrrev_i32_e32 v1, 31, v0
	v_lshlrev_b64 v[0:1], 6, v[0:1]
	ds_write_b64 v16, v[8:9]
	v_lshl_add_u64 v[8:9], s[60:61], 0, v[0:1]
	s_waitcnt lgkmcnt(0)
	s_barrier
	global_load_dwordx4 v[12:15], v[8:9], off
	v_lshl_add_u64 v[10:11], s[62:63], 0, v[0:1]
	global_load_dwordx4 v[16:19], v[10:11], off
	global_load_dwordx4 v[20:23], v[8:9], off offset:16
	global_load_dwordx4 v[24:27], v[10:11], off offset:16
	global_load_dwordx4 v[32:35], v[10:11], off offset:32
	global_load_dwordx4 v[28:31], v[8:9], off offset:32
	global_load_dwordx4 v[36:39], v[8:9], off offset:48
	global_load_dwordx4 v[40:43], v[10:11], off offset:48
	s_lshl_b32 s0, s3, 8
	s_lshl_b32 s1, s2, 7
	v_ashrrev_i32_e32 v0, 1, v4
	s_or_b32 s0, s1, s0
	v_and_b32_e32 v1, 1, v4
	v_lshlrev_b32_e32 v2, 3, v2
	v_add_u32_e32 v0, s0, v0
	v_lshl_add_u32 v2, v1, 10, v2
	v_lshlrev_b32_e32 v192, 6, v1
	v_ashrrev_i32_e32 v1, 31, v0
	v_readlane_b32 s0, v253, 24
	v_lshlrev_b64 v[0:1], 10, v[0:1]
	v_readlane_b32 s1, v253, 25
	v_and_b32_e32 v5, 2, v4
	v_cmp_eq_u32_e32 vcc, 0, v5
	v_lshl_add_u64 v[0:1], s[0:1], 0, v[0:1]
	v_lshl_add_u64 v[0:1], v[0:1], 0, s[78:79]
	v_lshl_add_u64 v[6:7], v[0:1], 0, v[192:193]
	ds_read2st64_b64 v[0:3], v2 offset1:1
	s_waitcnt vmcnt(6)
	v_mov_b32_e32 v46, v16
	v_mov_b32_e32 v47, v18
	v_mov_b32_e32 v48, v12
	v_mov_b32_e32 v49, v18
	v_mov_b32_e32 v18, v17
	v_mov_b32_e32 v44, v12
	v_mov_b32_e32 v45, v14
	v_mov_b32_e32 v50, v16
	v_mov_b32_e32 v51, v14
	v_mov_b32_e32 v14, v13
	s_waitcnt vmcnt(4)
	v_mov_b32_e32 v54, v24
	v_mov_b32_e32 v55, v26
	v_mov_b32_e32 v56, v20
	v_mov_b32_e32 v57, v26
	v_mov_b32_e32 v26, v25
	s_waitcnt lgkmcnt(0)
	v_pk_mul_f32 v[46:47], v[0:1], v[46:47] op_sel:[1,0]
	v_pk_mul_f32 v[48:49], v[0:1], v[48:49] op_sel:[1,0] op_sel_hi:[0,1]
	v_pk_mul_f32 v[60:61], v[0:1], v[18:19] op_sel:[1,0]
	v_mov_b32_e32 v18, v13
	v_mov_b32_e32 v52, v20
	v_mov_b32_e32 v53, v22
	v_mov_b32_e32 v58, v24
	v_mov_b32_e32 v59, v22
	v_mov_b32_e32 v22, v21
	v_pk_mul_f32 v[12:13], v[0:1], v[54:55] op_sel:[1,0]
	v_pk_mul_f32 v[54:55], v[0:1], v[56:57] op_sel:[1,0] op_sel_hi:[0,1]
	v_pk_mul_f32 v[56:57], v[0:1], v[26:27] op_sel:[1,0]
	v_mov_b32_e32 v26, v21
	v_pk_fma_f32 v[20:21], v[0:1], v[44:45], v[46:47] op_sel_hi:[0,1,1] neg_lo:[0,0,1] neg_hi:[0,0,1]
	v_pk_fma_f32 v[44:45], v[0:1], v[50:51], v[48:49]
	v_pk_fma_f32 v[46:47], v[0:1], v[14:15], v[60:61] op_sel_hi:[0,1,1] neg_lo:[0,0,1] neg_hi:[0,0,1]
	v_pk_mul_f32 v[18:19], v[0:1], v[18:19] op_sel:[1,0] op_sel_hi:[0,1]
	v_mov_b32_e32 v14, v17
	v_pk_fma_f32 v[12:13], v[0:1], v[52:53], v[12:13] op_sel_hi:[0,1,1] neg_lo:[0,0,1] neg_hi:[0,0,1]
	v_pk_fma_f32 v[16:17], v[0:1], v[58:59], v[54:55]
	v_cndmask_b32_e32 v5, v44, v20, vcc
	v_pk_fma_f32 v[14:15], v[0:1], v[14:15], v[18:19]
	v_cndmask_b32_e32 v17, v17, v13, vcc
	v_cndmask_b32_e32 v13, v15, v47, vcc
	v_and_b32_sdwa v15, v5, v218 dst_sel:DWORD dst_unused:UNUSED_PAD src0_sel:WORD_1 src1_sel:DWORD
	v_cndmask_b32_e32 v20, v45, v21, vcc
	v_cndmask_b32_e32 v16, v16, v12, vcc
	v_cndmask_b32_e32 v12, v14, v46, vcc
	v_add3_u32 v5, v5, v15, s80
	v_cvt_pk_bf16_f32 v13, v20, v13
	v_and_b32_sdwa v18, v12, v218 dst_sel:DWORD dst_unused:UNUSED_PAD src0_sel:WORD_1 src1_sel:DWORD
	v_pk_fma_f32 v[48:49], v[0:1], v[22:23], v[56:57] op_sel_hi:[0,1,1] neg_lo:[0,0,1] neg_hi:[0,0,1]
	v_pk_mul_f32 v[26:27], v[0:1], v[26:27] op_sel:[1,0] op_sel_hi:[0,1]
	v_add3_u32 v12, v12, v18, s80
	v_mov_b32_e32 v22, v25
	v_and_b32_e32 v12, 0xffff0000, v12
	v_pk_fma_f32 v[14:15], v[0:1], v[22:23], v[26:27]
	v_or_b32_sdwa v12, v12, v5 dst_sel:DWORD dst_unused:UNUSED_PAD src0_sel:DWORD src1_sel:WORD_1
	v_cndmask_b32_e32 v5, v14, v48, vcc
	v_cndmask_b32_e32 v14, v15, v49, vcc
	v_and_b32_sdwa v18, v16, v218 dst_sel:DWORD dst_unused:UNUSED_PAD src0_sel:WORD_1 src1_sel:DWORD
	v_add3_u32 v16, v16, v18, s80
	v_cvt_pk_bf16_f32 v15, v17, v14
	v_and_b32_sdwa v18, v5, v218 dst_sel:DWORD dst_unused:UNUSED_PAD src0_sel:WORD_1 src1_sel:DWORD
	v_add3_u32 v5, v5, v18, s80
	v_and_b32_e32 v5, 0xffff0000, v5
	s_waitcnt vmcnt(3)
	v_mov_b32_e32 v18, v32
	v_mov_b32_e32 v19, v34
	v_or_b32_sdwa v14, v5, v16 dst_sel:DWORD dst_unused:UNUSED_PAD src0_sel:DWORD src1_sel:WORD_1
	s_waitcnt vmcnt(2)
	v_mov_b32_e32 v16, v28
	v_mov_b32_e32 v17, v30
	v_pk_mul_f32 v[18:19], v[0:1], v[18:19] op_sel:[1,0]
	v_mov_b32_e32 v20, v32
	v_pk_fma_f32 v[16:17], v[0:1], v[16:17], v[18:19] op_sel_hi:[0,1,1] neg_lo:[0,0,1] neg_hi:[0,0,1]
	v_mov_b32_e32 v18, v28
	v_mov_b32_e32 v19, v34
	v_pk_mul_f32 v[18:19], v[0:1], v[18:19] op_sel:[1,0] op_sel_hi:[0,1]
	v_mov_b32_e32 v21, v30
	v_pk_fma_f32 v[18:19], v[0:1], v[20:21], v[18:19]
	v_mov_b32_e32 v34, v33
	v_cndmask_b32_e32 v5, v18, v16, vcc
	v_cndmask_b32_e32 v20, v19, v17, vcc
	v_mov_b32_e32 v30, v29
	v_pk_mul_f32 v[16:17], v[0:1], v[34:35] op_sel:[1,0]
	v_mov_b32_e32 v34, v29
	v_pk_fma_f32 v[16:17], v[0:1], v[30:31], v[16:17] op_sel_hi:[0,1,1] neg_lo:[0,0,1] neg_hi:[0,0,1]
	v_pk_mul_f32 v[18:19], v[0:1], v[34:35] op_sel:[1,0] op_sel_hi:[0,1]
	v_mov_b32_e32 v30, v33
	v_pk_fma_f32 v[18:19], v[0:1], v[30:31], v[18:19]
	s_waitcnt vmcnt(0)
	v_mov_b32_e32 v21, v42
	v_cndmask_b32_e32 v17, v19, v17, vcc
	v_and_b32_sdwa v19, v5, v218 dst_sel:DWORD dst_unused:UNUSED_PAD src0_sel:WORD_1 src1_sel:DWORD
	v_cndmask_b32_e32 v16, v18, v16, vcc
	v_add3_u32 v5, v5, v19, s80
	v_cvt_pk_bf16_f32 v17, v20, v17
	v_and_b32_sdwa v20, v16, v218 dst_sel:DWORD dst_unused:UNUSED_PAD src0_sel:WORD_1 src1_sel:DWORD
	v_add3_u32 v16, v16, v20, s80
	v_mov_b32_e32 v20, v40
	v_mov_b32_e32 v18, v36
	v_mov_b32_e32 v19, v38
	v_pk_mul_f32 v[20:21], v[0:1], v[20:21] op_sel:[1,0]
	v_mov_b32_e32 v22, v40
	v_pk_fma_f32 v[18:19], v[0:1], v[18:19], v[20:21] op_sel_hi:[0,1,1] neg_lo:[0,0,1] neg_hi:[0,0,1]
	v_mov_b32_e32 v20, v36
	v_mov_b32_e32 v21, v42
	v_pk_mul_f32 v[20:21], v[0:1], v[20:21] op_sel:[1,0] op_sel_hi:[0,1]
	v_mov_b32_e32 v23, v38
	v_and_b32_e32 v16, 0xffff0000, v16
	v_pk_fma_f32 v[20:21], v[0:1], v[22:23], v[20:21]
	v_mov_b32_e32 v42, v41
	v_or_b32_sdwa v16, v16, v5 dst_sel:DWORD dst_unused:UNUSED_PAD src0_sel:DWORD src1_sel:WORD_1
	v_cndmask_b32_e32 v5, v20, v18, vcc
	v_cndmask_b32_e32 v22, v21, v19, vcc
	v_mov_b32_e32 v38, v37
	v_pk_mul_f32 v[18:19], v[0:1], v[42:43] op_sel:[1,0]
	v_mov_b32_e32 v42, v37
	v_pk_fma_f32 v[18:19], v[0:1], v[38:39], v[18:19] op_sel_hi:[0,1,1] neg_lo:[0,0,1] neg_hi:[0,0,1]
	v_pk_mul_f32 v[20:21], v[0:1], v[42:43] op_sel:[1,0] op_sel_hi:[0,1]
	v_mov_b32_e32 v38, v41
	v_pk_fma_f32 v[0:1], v[0:1], v[38:39], v[20:21]
	s_nop 0
	v_cndmask_b32_e32 v0, v0, v18, vcc
	v_cndmask_b32_e32 v1, v1, v19, vcc
	v_and_b32_sdwa v19, v5, v218 dst_sel:DWORD dst_unused:UNUSED_PAD src0_sel:WORD_1 src1_sel:DWORD
	v_add3_u32 v5, v5, v19, s80
	v_and_b32_sdwa v20, v0, v218 dst_sel:DWORD dst_unused:UNUSED_PAD src0_sel:WORD_1 src1_sel:DWORD
	v_cvt_pk_bf16_f32 v19, v22, v1
	v_add3_u32 v0, v0, v20, s80
	v_and_b32_e32 v0, 0xffff0000, v0
	v_or_b32_sdwa v18, v0, v5 dst_sel:DWORD dst_unused:UNUSED_PAD src0_sel:DWORD src1_sel:WORD_1
	global_store_dwordx4 v[6:7], v[12:15], off
	global_store_dwordx4 v[6:7], v[16:19], off offset:16
	global_load_dwordx4 v[12:15], v[8:9], off
	s_nop 0
	global_load_dwordx4 v[16:19], v[10:11], off
	global_load_dwordx4 v[20:23], v[8:9], off offset:16
	global_load_dwordx4 v[24:27], v[10:11], off offset:16
	global_load_dwordx4 v[28:31], v[8:9], off offset:32
	global_load_dwordx4 v[32:35], v[10:11], off offset:32
	global_load_dwordx4 v[36:39], v[8:9], off offset:48
	s_nop 0
	global_load_dwordx4 v[8:11], v[10:11], off offset:48
	s_waitcnt vmcnt(7)
	v_mov_b32_e32 v0, v12
	s_waitcnt vmcnt(6)
	v_mov_b32_e32 v40, v16
	v_mov_b32_e32 v41, v18
	v_mov_b32_e32 v1, v14
	v_pk_mul_f32 v[40:41], v[2:3], v[40:41] op_sel:[1,0]
	v_mov_b32_e32 v42, v16
	v_pk_fma_f32 v[0:1], v[2:3], v[0:1], v[40:41] op_sel_hi:[0,1,1] neg_lo:[0,0,1] neg_hi:[0,0,1]
	v_mov_b32_e32 v40, v12
	v_mov_b32_e32 v41, v18
	v_pk_mul_f32 v[40:41], v[2:3], v[40:41] op_sel:[1,0] op_sel_hi:[0,1]
	v_mov_b32_e32 v43, v14
	v_pk_fma_f32 v[40:41], v[2:3], v[42:43], v[40:41]
	v_mov_b32_e32 v18, v17
	v_cndmask_b32_e32 v5, v40, v0, vcc
	v_cndmask_b32_e32 v16, v41, v1, vcc
	v_mov_b32_e32 v14, v13
	v_pk_mul_f32 v[0:1], v[2:3], v[18:19] op_sel:[1,0]
	v_mov_b32_e32 v18, v13
	v_pk_fma_f32 v[0:1], v[2:3], v[14:15], v[0:1] op_sel_hi:[0,1,1] neg_lo:[0,0,1] neg_hi:[0,0,1]
	v_pk_mul_f32 v[12:13], v[2:3], v[18:19] op_sel:[1,0] op_sel_hi:[0,1]
	v_mov_b32_e32 v14, v17
	v_pk_fma_f32 v[12:13], v[2:3], v[14:15], v[12:13]
	s_waitcnt vmcnt(4)
	v_mov_b32_e32 v15, v26
	v_cndmask_b32_e32 v0, v12, v0, vcc
	v_cndmask_b32_e32 v1, v13, v1, vcc
	v_and_b32_sdwa v13, v5, v218 dst_sel:DWORD dst_unused:UNUSED_PAD src0_sel:WORD_1 src1_sel:DWORD
	v_add3_u32 v5, v5, v13, s80
	v_and_b32_sdwa v14, v0, v218 dst_sel:DWORD dst_unused:UNUSED_PAD src0_sel:WORD_1 src1_sel:DWORD
	v_cvt_pk_bf16_f32 v13, v16, v1
	v_add3_u32 v0, v0, v14, s80
	v_and_b32_e32 v0, 0xffff0000, v0
	v_mov_b32_e32 v14, v24
	v_or_b32_sdwa v12, v0, v5 dst_sel:DWORD dst_unused:UNUSED_PAD src0_sel:DWORD src1_sel:WORD_1
	v_mov_b32_e32 v0, v20
	v_mov_b32_e32 v1, v22
	v_pk_mul_f32 v[14:15], v[2:3], v[14:15] op_sel:[1,0]
	v_mov_b32_e32 v16, v24
	v_pk_fma_f32 v[0:1], v[2:3], v[0:1], v[14:15] op_sel_hi:[0,1,1] neg_lo:[0,0,1] neg_hi:[0,0,1]
	v_mov_b32_e32 v14, v20
	v_mov_b32_e32 v15, v26
	v_pk_mul_f32 v[14:15], v[2:3], v[14:15] op_sel:[1,0] op_sel_hi:[0,1]
	v_mov_b32_e32 v17, v22
	v_pk_fma_f32 v[14:15], v[2:3], v[16:17], v[14:15]
	v_mov_b32_e32 v26, v25
	v_cndmask_b32_e32 v5, v14, v0, vcc
	v_cndmask_b32_e32 v16, v15, v1, vcc
	v_mov_b32_e32 v22, v21
	v_pk_mul_f32 v[0:1], v[2:3], v[26:27] op_sel:[1,0]
	v_mov_b32_e32 v26, v21
	v_pk_fma_f32 v[0:1], v[2:3], v[22:23], v[0:1] op_sel_hi:[0,1,1] neg_lo:[0,0,1] neg_hi:[0,0,1]
	v_pk_mul_f32 v[14:15], v[2:3], v[26:27] op_sel:[1,0] op_sel_hi:[0,1]
	v_mov_b32_e32 v22, v25
	v_pk_fma_f32 v[14:15], v[2:3], v[22:23], v[14:15]
	s_waitcnt vmcnt(2)
	v_mov_b32_e32 v17, v34
	v_cndmask_b32_e32 v0, v14, v0, vcc
	v_cndmask_b32_e32 v1, v15, v1, vcc
	v_and_b32_sdwa v15, v5, v218 dst_sel:DWORD dst_unused:UNUSED_PAD src0_sel:WORD_1 src1_sel:DWORD
	v_add3_u32 v5, v5, v15, s80
	v_cvt_pk_bf16_f32 v15, v16, v1
	v_and_b32_sdwa v16, v0, v218 dst_sel:DWORD dst_unused:UNUSED_PAD src0_sel:WORD_1 src1_sel:DWORD
	v_add3_u32 v0, v0, v16, s80
	v_and_b32_e32 v0, 0xffff0000, v0
	v_mov_b32_e32 v16, v32
	v_or_b32_sdwa v14, v0, v5 dst_sel:DWORD dst_unused:UNUSED_PAD src0_sel:DWORD src1_sel:WORD_1
	v_mov_b32_e32 v0, v28
	v_mov_b32_e32 v1, v30
	v_pk_mul_f32 v[16:17], v[2:3], v[16:17] op_sel:[1,0]
	v_mov_b32_e32 v18, v32
	v_pk_fma_f32 v[0:1], v[2:3], v[0:1], v[16:17] op_sel_hi:[0,1,1] neg_lo:[0,0,1] neg_hi:[0,0,1]
	v_mov_b32_e32 v16, v28
	v_mov_b32_e32 v17, v34
	v_pk_mul_f32 v[16:17], v[2:3], v[16:17] op_sel:[1,0] op_sel_hi:[0,1]
	v_mov_b32_e32 v19, v30
	v_pk_fma_f32 v[16:17], v[2:3], v[18:19], v[16:17]
	v_mov_b32_e32 v34, v33
	v_cndmask_b32_e32 v5, v16, v0, vcc
	v_cndmask_b32_e32 v18, v17, v1, vcc
	v_mov_b32_e32 v30, v29
	v_pk_mul_f32 v[0:1], v[2:3], v[34:35] op_sel:[1,0]
	v_mov_b32_e32 v34, v29
	v_pk_fma_f32 v[0:1], v[2:3], v[30:31], v[0:1] op_sel_hi:[0,1,1] neg_lo:[0,0,1] neg_hi:[0,0,1]
	v_pk_mul_f32 v[16:17], v[2:3], v[34:35] op_sel:[1,0] op_sel_hi:[0,1]
	v_mov_b32_e32 v30, v33
	v_pk_fma_f32 v[16:17], v[2:3], v[30:31], v[16:17]
	s_waitcnt vmcnt(0)
	v_mov_b32_e32 v19, v10
	v_cndmask_b32_e32 v1, v17, v1, vcc
	v_and_b32_sdwa v17, v5, v218 dst_sel:DWORD dst_unused:UNUSED_PAD src0_sel:WORD_1 src1_sel:DWORD
	v_cndmask_b32_e32 v0, v16, v0, vcc
	v_add3_u32 v5, v5, v17, s80
	v_cvt_pk_bf16_f32 v1, v18, v1
	v_and_b32_sdwa v18, v0, v218 dst_sel:DWORD dst_unused:UNUSED_PAD src0_sel:WORD_1 src1_sel:DWORD
	v_add3_u32 v0, v0, v18, s80
	v_mov_b32_e32 v18, v8
	v_mov_b32_e32 v16, v36
	v_mov_b32_e32 v17, v38
	v_pk_mul_f32 v[18:19], v[2:3], v[18:19] op_sel:[1,0]
	v_mov_b32_e32 v20, v8
	v_pk_fma_f32 v[16:17], v[2:3], v[16:17], v[18:19] op_sel_hi:[0,1,1] neg_lo:[0,0,1] neg_hi:[0,0,1]
	v_mov_b32_e32 v18, v36
	v_mov_b32_e32 v19, v10
	v_pk_mul_f32 v[18:19], v[2:3], v[18:19] op_sel:[1,0] op_sel_hi:[0,1]
	v_mov_b32_e32 v21, v38
	v_and_b32_e32 v0, 0xffff0000, v0
	v_pk_fma_f32 v[18:19], v[2:3], v[20:21], v[18:19]
	v_mov_b32_e32 v10, v9
	v_or_b32_sdwa v0, v0, v5 dst_sel:DWORD dst_unused:UNUSED_PAD src0_sel:DWORD src1_sel:WORD_1
	v_cndmask_b32_e32 v5, v18, v16, vcc
	v_cndmask_b32_e32 v8, v19, v17, vcc
	v_mov_b32_e32 v38, v37
	v_pk_mul_f32 v[16:17], v[2:3], v[10:11] op_sel:[1,0]
	v_mov_b32_e32 v10, v37
	v_pk_fma_f32 v[16:17], v[2:3], v[38:39], v[16:17] op_sel_hi:[0,1,1] neg_lo:[0,0,1] neg_hi:[0,0,1]
	v_pk_mul_f32 v[10:11], v[2:3], v[10:11] op_sel:[1,0] op_sel_hi:[0,1]
	v_mov_b32_e32 v38, v9
	v_pk_fma_f32 v[2:3], v[2:3], v[38:39], v[10:11]
	v_and_b32_sdwa v9, v8, v218 dst_sel:DWORD dst_unused:UNUSED_PAD src0_sel:WORD_1 src1_sel:DWORD
	v_cndmask_b32_e32 v2, v2, v16, vcc
	v_cndmask_b32_e32 v3, v3, v17, vcc
	v_cvt_pk_bf16_f32 v2, v5, v2
	v_add3_u32 v8, v8, v9, s80
	v_and_b32_sdwa v9, v3, v218 dst_sel:DWORD dst_unused:UNUSED_PAD src0_sel:WORD_1 src1_sel:DWORD
	v_add3_u32 v3, v3, v9, s80
	v_and_b32_e32 v3, 0xffff0000, v3
	v_or_b32_sdwa v3, v3, v8 dst_sel:DWORD dst_unused:UNUSED_PAD src0_sel:DWORD src1_sel:WORD_1
	global_store_dwordx4 v[6:7], v[12:15], off offset:32
	global_store_dwordx4 v[6:7], v[0:3], off offset:48
	s_barrier

.LBB0_1110:
	s_andn2_b64 vcc, exec, s[0:1]
	s_cbranch_vccnz .LBB0_1131
	s_lshl_b32 s9, s8, 1
	s_cmpk_gt_u32 s8, 0xdf
	s_mov_b64 s[0:1], -1
	s_cbranch_scc0 .LBB0_1129
	s_cmpk_gt_u32 s8, 0x15f
	s_cbranch_scc0 .LBB0_1126
	s_cmpk_gt_u32 s8, 0x171
	s_cbranch_scc0 .LBB0_1123
	s_cmpk_gt_u32 s8, 0x2d1
	s_cbranch_scc0 .LBB0_1120
	s_cmpk_gt_u32 s8, 0x431
	s_cbranch_scc0 .LBB0_1117
	s_add_i32 s0, s9, 0xf79c
	s_sext_i32_i16 s1, s0
	s_bfe_u32 s1, s1, 0x4001b
	s_add_i32 s1, s0, s1
	s_sext_i32_i16 s2, s1
	s_and_b32 s1, s1, 0xfff0
	s_sub_i32 s0, s0, s1
	s_sext_i32_i16 s0, s0
	s_lshl_b32 s4, s0, 6
	s_add_i32 s0, s9, 0xf79d
	s_sext_i32_i16 s1, s0
	s_bfe_u32 s1, s1, 0x4001b
	s_lshl_b32 s2, s2, 2
	s_add_i32 s1, s0, s1
	s_and_b32 s6, s2, 0xffffffc0
	s_sext_i32_i16 s2, s1
	s_and_b32 s1, s1, 0xfff0
	s_waitcnt vmcnt(6)
	v_mov_b32_e32 v40, v208
	s_sub_i32 s0, s0, s1
	s_sext_i32_i16 s0, s0
	v_lshlrev_b32_e32 v0, 4, v40
	v_add_u32_e32 v41, 0x100, v40
	v_add_u32_e32 v10, 0x200, v40
	v_add_u32_e32 v12, 0x300, v40
	v_and_b32_e32 v192, 0xf0, v0
	v_ashrrev_i32_e32 v32, 4, v40
	v_ashrrev_i32_e32 v34, 4, v41
	v_ashrrev_i32_e32 v36, 4, v10
	v_ashrrev_i32_e32 v38, 4, v12
	s_lshl_b32 s2, s2, 2
	s_lshl_b32 s0, s0, 6
	v_lshl_add_u64 v[16:17], s[86:87], 0, v[192:193]
	s_ashr_i32 s5, s4, 31
	v_add_u32_e32 v0, s6, v32
	v_add_u32_e32 v2, s6, v34
	v_add_u32_e32 v10, s6, v36
	v_add_u32_e32 v12, s6, v38
	s_andn2_b32 s2, s2, 63
	s_ashr_i32 s1, s0, 31
	v_lshl_add_u64 v[8:9], s[4:5], 2, v[16:17]
	v_ashrrev_i32_e32 v1, 31, v0
	v_ashrrev_i32_e32 v3, 31, v2
	v_ashrrev_i32_e32 v11, 31, v10
	v_ashrrev_i32_e32 v13, 31, v12
	v_lshl_add_u64 v[28:29], s[0:1], 2, v[16:17]
	v_add_u32_e32 v16, s2, v32
	v_lshlrev_b64 v[0:1], 12, v[0:1]
	v_lshlrev_b64 v[2:3], 12, v[2:3]
	v_lshlrev_b64 v[10:11], 12, v[10:11]
	v_lshlrev_b64 v[12:13], 12, v[12:13]
	v_ashrrev_i32_e32 v17, 31, v16
	v_lshl_add_u64 v[0:1], v[8:9], 0, v[0:1]
	v_lshl_add_u64 v[4:5], v[8:9], 0, v[2:3]
	v_lshl_add_u64 v[10:11], v[8:9], 0, v[10:11]
	v_lshl_add_u64 v[12:13], v[8:9], 0, v[12:13]
	v_lshlrev_b64 v[16:17], 12, v[16:17]
	v_add_u32_e32 v20, s2, v34
	global_load_dwordx4 v[0:3], v[0:1], off nt
	s_nop 0
	global_load_dwordx4 v[4:7], v[4:5], off nt
	s_nop 0
	global_load_dwordx4 v[8:11], v[10:11], off nt
	s_nop 0
	global_load_dwordx4 v[12:15], v[12:13], off nt
	v_lshl_add_u64 v[16:17], v[28:29], 0, v[16:17]
	v_ashrrev_i32_e32 v21, 31, v20
	global_load_dwordx4 v[16:19], v[16:17], off nt
	v_lshlrev_b64 v[20:21], 12, v[20:21]
	v_add_u32_e32 v24, s2, v36
	v_lshl_add_u64 v[20:21], v[28:29], 0, v[20:21]
	v_ashrrev_i32_e32 v25, 31, v24
	global_load_dwordx4 v[20:23], v[20:21], off nt
	v_lshlrev_b64 v[24:25], 12, v[24:25]
	v_add_u32_e32 v30, s2, v38
	v_lshl_add_u64 v[24:25], v[28:29], 0, v[24:25]
	v_ashrrev_i32_e32 v31, 31, v30
	global_load_dwordx4 v[24:27], v[24:25], off nt
	v_lshlrev_b64 v[30:31], 12, v[30:31]
	v_lshl_add_u64 v[28:29], v[28:29], 0, v[30:31]
	global_load_dwordx4 v[28:31], v[28:29], off nt
	s_movk_i32 s1, 0x104
	v_mad_u64_u32 v[32:33], s[10:11], v32, s1, v[192:193]
	v_mad_u64_u32 v[34:35], s[10:11], v34, s1, v[192:193]
	v_mad_u64_u32 v[36:37], s[10:11], v36, s1, v[192:193]
	v_mad_u64_u32 v[38:39], s[10:11], v38, s1, v[192:193]
	v_readlane_b32 s10, v253, 28
	v_readlane_b32 s11, v253, 29
	s_ashr_i32 s7, s6, 31
	s_movk_i32 s1, 0x1600
	s_ashr_i32 s3, s2, 31
	s_waitcnt vmcnt(7)
	ds_write2_b32 v32, v0, v1 offset1:1
	ds_write2_b32 v32, v2, v3 offset0:2 offset1:3
	s_waitcnt vmcnt(6)
	ds_write2_b32 v34, v4, v5 offset1:1
	ds_write2_b32 v34, v6, v7 offset0:2 offset1:3
	s_waitcnt vmcnt(5)
	ds_write2_b32 v36, v8, v9 offset1:1
	ds_write2_b32 v36, v10, v11 offset0:2 offset1:3
	s_waitcnt vmcnt(4)
	ds_write2_b32 v38, v12, v13 offset1:1
	ds_write2_b32 v38, v14, v15 offset0:2 offset1:3
	v_add_u32_e32 v0, 0x4100, v32
	v_ashrrev_i32_e32 v14, 3, v40
	s_waitcnt vmcnt(3)
	ds_write2_b32 v0, v16, v17 offset1:1
	v_add_u32_e32 v0, 0x4108, v32
	ds_write2_b32 v0, v18, v19 offset1:1
	v_add_u32_e32 v0, 0x4100, v34
	v_add_u32_e32 v12, s4, v14
	s_waitcnt vmcnt(2)
	ds_write2_b32 v0, v20, v21 offset1:1
	v_add_u32_e32 v0, 0x4108, v34
	ds_write2_b32 v0, v22, v23 offset1:1
	v_add_u32_e32 v0, 0x4100, v36
	s_waitcnt vmcnt(1)
	ds_write2_b32 v0, v24, v25 offset1:1
	v_add_u32_e32 v0, 0x4108, v36
	ds_write2_b32 v0, v26, v27 offset1:1
	v_add_u32_e32 v0, 0x4100, v38
	s_waitcnt vmcnt(0)
	ds_write2_b32 v0, v28, v29 offset1:1
	v_add_u32_e32 v0, 0x4108, v38
	ds_write2_b32 v0, v30, v31 offset1:1
	v_lshlrev_b32_e32 v0, 3, v40
	v_and_b32_e32 v0, 56, v0
	v_mul_u32_u24_e32 v1, 0x41, v0
	v_lshlrev_b32_e32 v15, 2, v1
	v_lshl_add_u32 v16, v14, 2, v15
	s_waitcnt lgkmcnt(0)
	s_barrier
	v_lshlrev_b32_e32 v192, 1, v0
	ds_read2_b32 v[0:1], v16 offset1:65
	ds_read2_b32 v[2:3], v16 offset0:130 offset1:195
	v_add_u32_e32 v10, 0x400, v16
	ds_read2_b32 v[8:9], v10 offset0:4 offset1:69
	ds_read2_b32 v[10:11], v10 offset0:134 offset1:199
	v_lshl_add_u64 v[4:5], s[10:11], 0, v[192:193]
	s_waitcnt lgkmcnt(3)
	v_cvt_pk_bf16_f32 v0, v0, v1
	s_waitcnt lgkmcnt(2)
	v_and_b32_sdwa v17, v2, v218 dst_sel:DWORD dst_unused:UNUSED_PAD src0_sel:WORD_1 src1_sel:DWORD
	v_add3_u32 v2, v2, v17, s80
	v_and_b32_sdwa v17, v3, v218 dst_sel:DWORD dst_unused:UNUSED_PAD src0_sel:WORD_1 src1_sel:DWORD
	v_add3_u32 v3, v3, v17, s80
	v_and_b32_e32 v3, 0xffff0000, v3
	v_or_b32_sdwa v1, v3, v2 dst_sel:DWORD dst_unused:UNUSED_PAD src0_sel:DWORD src1_sel:WORD_1
	s_waitcnt lgkmcnt(0)
	v_and_b32_sdwa v3, v8, v218 dst_sel:DWORD dst_unused:UNUSED_PAD src0_sel:WORD_1 src1_sel:DWORD
	v_add3_u32 v8, v8, v3, s80
	v_cvt_pk_bf16_f32 v3, v10, v11
	v_and_b32_sdwa v10, v9, v218 dst_sel:DWORD dst_unused:UNUSED_PAD src0_sel:WORD_1 src1_sel:DWORD
	v_add3_u32 v9, v9, v10, s80
	v_lshl_add_u64 v[6:7], s[6:7], 1, v[4:5]
	v_and_b32_e32 v9, 0xffff0000, v9
	v_mad_i64_i32 v[12:13], s[6:7], v12, s1, v[6:7]
	v_or_b32_sdwa v2, v9, v8 dst_sel:DWORD dst_unused:UNUSED_PAD src0_sel:DWORD src1_sel:WORD_1
	global_store_dwordx4 v[12:13], v[0:3], off
	v_ashrrev_i32_e32 v12, 3, v41
	v_lshl_add_u32 v15, v12, 2, v15
	ds_read2_b32 v[0:1], v15 offset1:65
	ds_read2_b32 v[2:3], v15 offset0:130 offset1:195
	v_add_u32_e32 v10, 0x400, v15
	v_add_u32_e32 v13, s4, v12
	ds_read2_b32 v[8:9], v10 offset0:4 offset1:69
	ds_read2_b32 v[10:11], v10 offset0:134 offset1:199
	v_mad_i64_i32 v[6:7], s[4:5], v13, s1, v[6:7]
	s_waitcnt lgkmcnt(2)
	v_and_b32_sdwa v13, v2, v218 dst_sel:DWORD dst_unused:UNUSED_PAD src0_sel:WORD_1 src1_sel:DWORD
	v_cvt_pk_bf16_f32 v0, v0, v1
	v_add3_u32 v2, v2, v13, s80
	v_and_b32_sdwa v13, v3, v218 dst_sel:DWORD dst_unused:UNUSED_PAD src0_sel:WORD_1 src1_sel:DWORD
	v_add3_u32 v3, v3, v13, s80
	v_and_b32_e32 v3, 0xffff0000, v3
	v_or_b32_sdwa v1, v3, v2 dst_sel:DWORD dst_unused:UNUSED_PAD src0_sel:DWORD src1_sel:WORD_1
	s_waitcnt lgkmcnt(0)
	v_and_b32_sdwa v3, v8, v218 dst_sel:DWORD dst_unused:UNUSED_PAD src0_sel:WORD_1 src1_sel:DWORD
	v_add3_u32 v8, v8, v3, s80
	v_cvt_pk_bf16_f32 v3, v10, v11
	v_and_b32_sdwa v10, v9, v218 dst_sel:DWORD dst_unused:UNUSED_PAD src0_sel:WORD_1 src1_sel:DWORD
	v_add3_u32 v9, v9, v10, s80
	v_and_b32_e32 v9, 0xffff0000, v9
	v_or_b32_sdwa v2, v9, v8 dst_sel:DWORD dst_unused:UNUSED_PAD src0_sel:DWORD src1_sel:WORD_1
	global_store_dwordx4 v[6:7], v[0:3], off
	v_add_u32_e32 v6, 0x4400, v16
	v_add_u32_e32 v8, 0x4600, v16
	v_add_u32_e32 v2, 0x4200, v16
	v_add_u32_e32 v0, 0x4000, v16
	ds_read2_b32 v[2:3], v2 offset0:66 offset1:131
	ds_read2_b32 v[0:1], v0 offset0:64 offset1:129
	ds_read2_b32 v[6:7], v6 offset0:68 offset1:133
	ds_read2_b32 v[8:9], v8 offset0:70 offset1:135
	v_add_u32_e32 v10, s0, v14
	s_waitcnt lgkmcnt(3)
	v_and_b32_sdwa v13, v2, v218 dst_sel:DWORD dst_unused:UNUSED_PAD src0_sel:WORD_1 src1_sel:DWORD
	s_waitcnt lgkmcnt(2)
	v_cvt_pk_bf16_f32 v0, v0, v1
	v_add3_u32 v2, v2, v13, s80
	v_and_b32_sdwa v13, v3, v218 dst_sel:DWORD dst_unused:UNUSED_PAD src0_sel:WORD_1 src1_sel:DWORD
	v_add3_u32 v3, v3, v13, s80
	v_and_b32_e32 v3, 0xffff0000, v3
	v_or_b32_sdwa v1, v3, v2 dst_sel:DWORD dst_unused:UNUSED_PAD src0_sel:DWORD src1_sel:WORD_1
	s_waitcnt lgkmcnt(0)
	v_and_b32_sdwa v3, v6, v218 dst_sel:DWORD dst_unused:UNUSED_PAD src0_sel:WORD_1 src1_sel:DWORD
	v_add3_u32 v6, v6, v3, s80
	v_cvt_pk_bf16_f32 v3, v8, v9
	v_and_b32_sdwa v8, v7, v218 dst_sel:DWORD dst_unused:UNUSED_PAD src0_sel:WORD_1 src1_sel:DWORD
	v_add3_u32 v7, v7, v8, s80
	v_lshl_add_u64 v[4:5], s[2:3], 1, v[4:5]
	v_and_b32_e32 v7, 0xffff0000, v7
	v_mad_i64_i32 v[10:11], s[2:3], v10, s1, v[4:5]
	v_or_b32_sdwa v2, v7, v6 dst_sel:DWORD dst_unused:UNUSED_PAD src0_sel:DWORD src1_sel:WORD_1
	global_store_dwordx4 v[10:11], v[0:3], off
	v_add_u32_e32 v6, 0x4400, v15
	v_add_u32_e32 v8, 0x4600, v15
	v_add_u32_e32 v2, 0x4200, v15
	v_add_u32_e32 v0, 0x4000, v15
	ds_read2_b32 v[2:3], v2 offset0:66 offset1:131
	ds_read2_b32 v[0:1], v0 offset0:64 offset1:129
	v_add_u32_e32 v10, s0, v12
	ds_read2_b32 v[6:7], v6 offset0:68 offset1:133
	ds_read2_b32 v[8:9], v8 offset0:70 offset1:135
	v_mad_i64_i32 v[4:5], s[0:1], v10, s1, v[4:5]
	s_waitcnt lgkmcnt(3)
	v_and_b32_sdwa v10, v2, v218 dst_sel:DWORD dst_unused:UNUSED_PAD src0_sel:WORD_1 src1_sel:DWORD
	s_waitcnt lgkmcnt(2)
	v_cvt_pk_bf16_f32 v0, v0, v1
	v_add3_u32 v2, v2, v10, s80
	v_and_b32_sdwa v10, v3, v218 dst_sel:DWORD dst_unused:UNUSED_PAD src0_sel:WORD_1 src1_sel:DWORD
	v_add3_u32 v3, v3, v10, s80
	v_and_b32_e32 v3, 0xffff0000, v3
	v_or_b32_sdwa v1, v3, v2 dst_sel:DWORD dst_unused:UNUSED_PAD src0_sel:DWORD src1_sel:WORD_1
	s_waitcnt lgkmcnt(0)
	v_and_b32_sdwa v3, v6, v218 dst_sel:DWORD dst_unused:UNUSED_PAD src0_sel:WORD_1 src1_sel:DWORD
	v_add3_u32 v6, v6, v3, s80
	v_cvt_pk_bf16_f32 v3, v8, v9
	v_and_b32_sdwa v8, v7, v218 dst_sel:DWORD dst_unused:UNUSED_PAD src0_sel:WORD_1 src1_sel:DWORD
	v_add3_u32 v7, v7, v8, s80
	v_and_b32_e32 v7, 0xffff0000, v7
	v_or_b32_sdwa v2, v7, v6 dst_sel:DWORD dst_unused:UNUSED_PAD src0_sel:DWORD src1_sel:WORD_1
	global_store_dwordx4 v[4:5], v[0:3], off
	s_barrier
	s_mov_b64 s[0:1], 0
.LBB0_1117:
	s_andn2_b64 vcc, exec, s[0:1]
	s_cbranch_vccnz .LBB0_1119
	s_add_i32 s0, s9, 0xfa5c
	s_sext_i32_i16 s1, s0
	s_mulk_i32 s1, 0xba3
	s_lshr_b32 s2, s1, 31
	s_ashr_i32 s1, s1, 17
	s_add_i32 s1, s1, s2
	s_lshl_b32 s6, s1, 6
	s_mul_i32 s1, s1, 44
	s_waitcnt vmcnt(6)
	v_mov_b32_e32 v40, v208
	s_sub_i32 s0, s0, s1
	s_sext_i32_i16 s0, s0
	v_lshlrev_b32_e32 v0, 4, v40
	v_and_b32_e32 v192, 0xf0, v0
	s_lshl_b32 s4, s0, 6
	v_add_u32_e32 v41, 0x100, v40
	v_add_u32_e32 v10, 0x200, v40
	v_add_u32_e32 v12, 0x300, v40
	v_lshl_add_u64 v[16:17], s[84:85], 0, v[192:193]
	v_ashrrev_i32_e32 v32, 4, v40
	s_ashr_i32 s5, s4, 31
	v_ashrrev_i32_e32 v34, 4, v41
	v_ashrrev_i32_e32 v36, 4, v10
	v_ashrrev_i32_e32 v38, 4, v12
	v_lshl_add_u64 v[8:9], s[4:5], 2, v[16:17]
	v_add_u32_e32 v0, s6, v32
	s_movk_i32 s3, 0x2c00
	v_add_u32_e32 v2, s6, v34
	v_add_u32_e32 v10, s6, v36
	v_add_u32_e32 v12, s6, v38
	v_mad_i64_i32 v[0:1], s[0:1], v0, s3, v[8:9]
	v_mad_i64_i32 v[4:5], s[0:1], v2, s3, v[8:9]
	v_mad_i64_i32 v[10:11], s[0:1], v10, s3, v[8:9]
	v_mad_i64_i32 v[12:13], s[0:1], v12, s3, v[8:9]
	s_add_i32 s0, s9, 0xfa5d
	s_sext_i32_i16 s1, s0
	s_mulk_i32 s1, 0xba3
	s_lshr_b32 s2, s1, 31
	s_ashr_i32 s1, s1, 17
	s_add_i32 s1, s1, s2
	s_lshl_b32 s2, s1, 6
	s_mul_i32 s1, s1, 44
	s_sub_i32 s0, s0, s1
	s_sext_i32_i16 s0, s0
	s_lshl_b32 s0, s0, 6
	s_ashr_i32 s1, s0, 31
	v_lshl_add_u64 v[28:29], s[0:1], 2, v[16:17]
	v_add_u32_e32 v16, s2, v32
	v_add_u32_e32 v18, s2, v34
	v_mad_i64_i32 v[16:17], s[10:11], v16, s3, v[28:29]
	v_mad_i64_i32 v[20:21], s[10:11], v18, s3, v[28:29]
	v_add_u32_e32 v24, s2, v36
	global_load_dwordx4 v[0:3], v[0:1], off nt
	s_nop 0
	global_load_dwordx4 v[4:7], v[4:5], off nt
	s_nop 0
	global_load_dwordx4 v[8:11], v[10:11], off nt
	s_nop 0
	global_load_dwordx4 v[12:15], v[12:13], off nt
	s_nop 0
	global_load_dwordx4 v[16:19], v[16:17], off nt
	s_nop 0
	global_load_dwordx4 v[20:23], v[20:21], off nt
	v_mad_i64_i32 v[24:25], s[10:11], v24, s3, v[28:29]
	global_load_dwordx4 v[24:27], v[24:25], off nt
	v_add_u32_e32 v30, s2, v38
	v_mad_i64_i32 v[28:29], s[10:11], v30, s3, v[28:29]
	global_load_dwordx4 v[28:31], v[28:29], off nt
	s_movk_i32 s1, 0x104
	v_mad_u64_u32 v[32:33], s[10:11], v32, s1, v[192:193]
	v_mad_u64_u32 v[34:35], s[10:11], v34, s1, v[192:193]
	v_mad_u64_u32 v[36:37], s[10:11], v36, s1, v[192:193]
	v_mad_u64_u32 v[38:39], s[10:11], v38, s1, v[192:193]
	v_add_u32_e32 v33, 0x4100, v32
	v_add_u32_e32 v35, 0x4108, v32
	v_add_u32_e32 v37, 0x4100, v34
	v_add_u32_e32 v39, 0x4108, v34
	v_readlane_b32 s10, v253, 30
	s_movk_i32 s1, 0xffc0
	v_readlane_b32 s11, v253, 31
	s_ashr_i32 s7, s6, 31
	s_ashr_i32 s3, s2, 31
	s_waitcnt vmcnt(7)
	ds_write2_b32 v32, v0, v1 offset1:1
	ds_write2_b32 v32, v2, v3 offset0:2 offset1:3
	s_waitcnt vmcnt(6)
	ds_write2_b32 v34, v4, v5 offset1:1
	ds_write2_b32 v34, v6, v7 offset0:2 offset1:3
	s_waitcnt vmcnt(5)
	ds_write2_b32 v36, v8, v9 offset1:1
	ds_write2_b32 v36, v10, v11 offset0:2 offset1:3
	s_waitcnt vmcnt(4)
	ds_write2_b32 v38, v12, v13 offset1:1
	ds_write2_b32 v38, v14, v15 offset0:2 offset1:3
	s_waitcnt vmcnt(3)
	ds_write2_b32 v33, v16, v17 offset1:1
	ds_write2_b32 v35, v18, v19 offset1:1
	s_waitcnt vmcnt(2)
	ds_write2_b32 v37, v20, v21 offset1:1
	ds_write2_b32 v39, v22, v23 offset1:1
	v_add_u32_e32 v0, 0x4100, v36
	v_ashrrev_i32_e32 v16, 3, v40
	s_waitcnt vmcnt(1)
	ds_write2_b32 v0, v24, v25 offset1:1
	v_add_u32_e32 v0, 0x4108, v36
	ds_write2_b32 v0, v26, v27 offset1:1
	v_add_u32_e32 v0, 0x4100, v38
	s_waitcnt vmcnt(0)
	ds_write2_b32 v0, v28, v29 offset1:1
	v_add_u32_e32 v0, 0x4108, v38
	ds_write2_b32 v0, v30, v31 offset1:1
	v_lshlrev_b32_e32 v0, 3, v40
	v_and_b32_e32 v0, 56, v0
	v_mul_u32_u24_e32 v1, 0x41, v0
	v_lshlrev_b32_e32 v17, 2, v1
	v_lshl_add_u32 v19, v16, 2, v17
	s_waitcnt lgkmcnt(0)
	s_barrier
	ds_read2_b32 v[2:3], v19 offset1:65
	ds_read2_b32 v[8:9], v19 offset0:130 offset1:195
	v_lshlrev_b32_e32 v192, 1, v0
	v_add_lshl_u32 v0, v16, s4, 1
	v_and_or_b32 v18, v16, 31, 32
	v_and_or_b32 v0, v0, s1, v18
	v_add_u32_e32 v1, 0x400, v19
	v_lshl_add_u64 v[4:5], s[10:11], 0, v[192:193]
	ds_read2_b32 v[10:11], v1 offset0:4 offset1:69
	ds_read2_b32 v[12:13], v1 offset0:134 offset1:199
	v_ashrrev_i32_e32 v1, 31, v0
	v_lshl_add_u64 v[6:7], s[6:7], 1, v[4:5]
	v_lshlrev_b64 v[0:1], 11, v[0:1]
	v_lshl_add_u64 v[14:15], v[6:7], 0, v[0:1]
	s_waitcnt lgkmcnt(2)
	v_and_b32_sdwa v1, v2, v218 dst_sel:DWORD dst_unused:UNUSED_PAD src0_sel:WORD_1 src1_sel:DWORD
	v_add3_u32 v2, v2, v1, s80
	v_cvt_pk_bf16_f32 v1, v8, v9
	v_and_b32_sdwa v8, v3, v218 dst_sel:DWORD dst_unused:UNUSED_PAD src0_sel:WORD_1 src1_sel:DWORD
	v_add3_u32 v3, v3, v8, s80
	v_and_b32_e32 v3, 0xffff0000, v3
	v_or_b32_sdwa v0, v3, v2 dst_sel:DWORD dst_unused:UNUSED_PAD src0_sel:DWORD src1_sel:WORD_1
	s_waitcnt lgkmcnt(1)
	s_waitcnt lgkmcnt(0)
	v_cvt_pk_bf16_f32 v3, v12, v13
	v_cvt_pk_bf16_f32 v2, v10, v11
	global_store_dwordx4 v[14:15], v[0:3], off
	v_ashrrev_i32_e32 v14, 3, v41
	v_lshl_add_u32 v17, v14, 2, v17
	ds_read2_b32 v[2:3], v17 offset1:65
	ds_read2_b32 v[8:9], v17 offset0:130 offset1:195
	v_add_lshl_u32 v0, v14, s4, 1
	v_and_or_b32 v15, v14, 31, 32
	v_and_or_b32 v0, v0, s1, v15
	v_add_u32_e32 v1, 0x400, v17
	ds_read2_b32 v[10:11], v1 offset0:4 offset1:69
	ds_read2_b32 v[12:13], v1 offset0:134 offset1:199
	v_ashrrev_i32_e32 v1, 31, v0
	v_lshlrev_b64 v[0:1], 11, v[0:1]
	v_lshl_add_u64 v[6:7], v[6:7], 0, v[0:1]
	s_waitcnt lgkmcnt(2)
	v_and_b32_sdwa v1, v2, v218 dst_sel:DWORD dst_unused:UNUSED_PAD src0_sel:WORD_1 src1_sel:DWORD
	v_add3_u32 v2, v2, v1, s80
	v_cvt_pk_bf16_f32 v1, v8, v9
	v_and_b32_sdwa v8, v3, v218 dst_sel:DWORD dst_unused:UNUSED_PAD src0_sel:WORD_1 src1_sel:DWORD
	v_add3_u32 v3, v3, v8, s80
	v_and_b32_e32 v3, 0xffff0000, v3
	v_or_b32_sdwa v0, v3, v2 dst_sel:DWORD dst_unused:UNUSED_PAD src0_sel:DWORD src1_sel:WORD_1
	s_waitcnt lgkmcnt(1)
	s_waitcnt lgkmcnt(0)
	v_cvt_pk_bf16_f32 v3, v12, v13
	v_cvt_pk_bf16_f32 v2, v10, v11
	global_store_dwordx4 v[6:7], v[0:3], off
	v_lshl_add_u64 v[4:5], s[2:3], 1, v[4:5]
	s_nop 0
	v_add_u32_e32 v1, 0x4000, v19
	ds_read2_b32 v[2:3], v1 offset0:64 offset1:129
	v_add_u32_e32 v1, 0x4200, v19
	ds_read2_b32 v[6:7], v1 offset0:66 offset1:131
	v_add_lshl_u32 v0, v16, s0, 1
	v_add_u32_e32 v1, 0x4400, v19
	v_and_or_b32 v0, v0, s1, v18
	ds_read2_b32 v[8:9], v1 offset0:68 offset1:133
	v_add_u32_e32 v1, 0x4600, v19
	ds_read2_b32 v[10:11], v1 offset0:70 offset1:135
	v_ashrrev_i32_e32 v1, 31, v0
	v_lshlrev_b64 v[0:1], 11, v[0:1]
	v_lshl_add_u64 v[12:13], v[4:5], 0, v[0:1]
	s_waitcnt lgkmcnt(2)
	v_and_b32_sdwa v1, v2, v218 dst_sel:DWORD dst_unused:UNUSED_PAD src0_sel:WORD_1 src1_sel:DWORD
	v_add3_u32 v2, v2, v1, s80
	v_cvt_pk_bf16_f32 v1, v6, v7
	v_and_b32_sdwa v6, v3, v218 dst_sel:DWORD dst_unused:UNUSED_PAD src0_sel:WORD_1 src1_sel:DWORD
	v_add3_u32 v3, v3, v6, s80
	v_and_b32_e32 v3, 0xffff0000, v3
	v_or_b32_sdwa v0, v3, v2 dst_sel:DWORD dst_unused:UNUSED_PAD src0_sel:DWORD src1_sel:WORD_1
	s_waitcnt lgkmcnt(1)
	s_waitcnt lgkmcnt(0)
	v_cvt_pk_bf16_f32 v3, v10, v11
	v_cvt_pk_bf16_f32 v2, v8, v9
	global_store_dwordx4 v[12:13], v[0:3], off
	s_nop 1
	v_add_u32_e32 v1, 0x4000, v17
	ds_read2_b32 v[2:3], v1 offset0:64 offset1:129
	v_add_u32_e32 v1, 0x4200, v17
	ds_read2_b32 v[6:7], v1 offset0:66 offset1:131
	v_add_lshl_u32 v0, v14, s0, 1
	v_add_u32_e32 v1, 0x4400, v17
	v_and_or_b32 v0, v0, s1, v15
	ds_read2_b32 v[8:9], v1 offset0:68 offset1:133
	v_add_u32_e32 v1, 0x4600, v17
	ds_read2_b32 v[10:11], v1 offset0:70 offset1:135
	v_ashrrev_i32_e32 v1, 31, v0
	v_lshlrev_b64 v[0:1], 11, v[0:1]
	v_lshl_add_u64 v[4:5], v[4:5], 0, v[0:1]
	s_waitcnt lgkmcnt(2)
	v_and_b32_sdwa v1, v2, v218 dst_sel:DWORD dst_unused:UNUSED_PAD src0_sel:WORD_1 src1_sel:DWORD
	v_add3_u32 v2, v2, v1, s80
	v_cvt_pk_bf16_f32 v1, v6, v7
	v_and_b32_sdwa v6, v3, v218 dst_sel:DWORD dst_unused:UNUSED_PAD src0_sel:WORD_1 src1_sel:DWORD
	v_add3_u32 v3, v3, v6, s80
	v_and_b32_e32 v3, 0xffff0000, v3
	v_or_b32_sdwa v0, v3, v2 dst_sel:DWORD dst_unused:UNUSED_PAD src0_sel:DWORD src1_sel:WORD_1
	s_waitcnt lgkmcnt(1)
	s_waitcnt lgkmcnt(0)
	v_cvt_pk_bf16_f32 v3, v10, v11
	v_cvt_pk_bf16_f32 v2, v8, v9
	global_store_dwordx4 v[4:5], v[0:3], off
	s_barrier

.LBB0_1120:
	s_andn2_b64 vcc, exec, s[0:1]
	s_cbranch_vccnz .LBB0_1122
	s_add_i32 s0, s9, 0xfd1c
	s_sext_i32_i16 s1, s0
	s_mulk_i32 s1, 0xba3
	s_lshr_b32 s2, s1, 31
	s_ashr_i32 s1, s1, 17
	s_add_i32 s1, s1, s2
	s_lshl_b32 s6, s1, 6
	s_mul_i32 s1, s1, 44
	s_waitcnt vmcnt(6)
	v_mov_b32_e32 v40, v208
	s_sub_i32 s0, s0, s1
	v_readlane_b32 s12, v253, 0
	v_lshlrev_b32_e32 v0, 4, v40
	s_sext_i32_i16 s0, s0
	v_and_b32_e32 v192, 0xf0, v0
	v_readlane_b32 s26, v253, 14
	v_readlane_b32 s27, v253, 15
	s_lshl_b32 s4, s0, 6
	v_add_u32_e32 v41, 0x100, v40
	v_add_u32_e32 v10, 0x200, v40
	v_add_u32_e32 v12, 0x300, v40
	v_lshl_add_u64 v[16:17], s[26:27], 0, v[192:193]
	v_ashrrev_i32_e32 v32, 4, v40
	s_ashr_i32 s5, s4, 31
	v_ashrrev_i32_e32 v34, 4, v41
	v_ashrrev_i32_e32 v36, 4, v10
	v_ashrrev_i32_e32 v38, 4, v12
	v_lshl_add_u64 v[8:9], s[4:5], 2, v[16:17]
	v_add_u32_e32 v0, s6, v32
	s_movk_i32 s3, 0x2c00
	v_add_u32_e32 v2, s6, v34
	v_add_u32_e32 v10, s6, v36
	v_add_u32_e32 v12, s6, v38
	v_mad_i64_i32 v[0:1], s[0:1], v0, s3, v[8:9]
	v_mad_i64_i32 v[4:5], s[0:1], v2, s3, v[8:9]
	v_mad_i64_i32 v[10:11], s[0:1], v10, s3, v[8:9]
	v_mad_i64_i32 v[12:13], s[0:1], v12, s3, v[8:9]
	s_add_i32 s0, s9, 0xfd1d
	s_sext_i32_i16 s1, s0
	s_mulk_i32 s1, 0xba3
	s_lshr_b32 s2, s1, 31
	s_ashr_i32 s1, s1, 17
	s_add_i32 s1, s1, s2
	s_lshl_b32 s2, s1, 6
	s_mul_i32 s1, s1, 44
	s_sub_i32 s0, s0, s1
	s_sext_i32_i16 s0, s0
	s_lshl_b32 s0, s0, 6
	s_ashr_i32 s1, s0, 31
	v_lshl_add_u64 v[28:29], s[0:1], 2, v[16:17]
	v_add_u32_e32 v16, s2, v32
	v_add_u32_e32 v18, s2, v34
	v_mad_i64_i32 v[16:17], s[10:11], v16, s3, v[28:29]
	v_mad_i64_i32 v[20:21], s[10:11], v18, s3, v[28:29]
	v_add_u32_e32 v24, s2, v36
	global_load_dwordx4 v[0:3], v[0:1], off nt
	s_nop 0
	global_load_dwordx4 v[4:7], v[4:5], off nt
	s_nop 0
	global_load_dwordx4 v[8:11], v[10:11], off nt
	s_nop 0
	global_load_dwordx4 v[12:15], v[12:13], off nt
	s_nop 0
	global_load_dwordx4 v[16:19], v[16:17], off nt
	s_nop 0
	global_load_dwordx4 v[20:23], v[20:21], off nt
	v_mad_i64_i32 v[24:25], s[10:11], v24, s3, v[28:29]
	global_load_dwordx4 v[24:27], v[24:25], off nt
	v_add_u32_e32 v30, s2, v38
	v_mad_i64_i32 v[28:29], s[10:11], v30, s3, v[28:29]
	global_load_dwordx4 v[28:31], v[28:29], off nt
	s_movk_i32 s1, 0x104
	v_mad_u64_u32 v[32:33], s[10:11], v32, s1, v[192:193]
	v_mad_u64_u32 v[34:35], s[10:11], v34, s1, v[192:193]
	v_mad_u64_u32 v[36:37], s[10:11], v36, s1, v[192:193]
	v_mad_u64_u32 v[38:39], s[10:11], v38, s1, v[192:193]
	v_add_u32_e32 v33, 0x4100, v32
	v_add_u32_e32 v35, 0x4108, v32
	v_add_u32_e32 v37, 0x4100, v34
	v_add_u32_e32 v39, 0x4108, v34
	v_readlane_b32 s10, v253, 30
	s_movk_i32 s1, 0xffc0
	v_readlane_b32 s11, v253, 31
	s_ashr_i32 s7, s6, 31
	s_ashr_i32 s3, s2, 31
	v_readlane_b32 s13, v253, 1
	v_readlane_b32 s14, v253, 2
	v_readlane_b32 s15, v253, 3
	v_readlane_b32 s16, v253, 4
	v_readlane_b32 s17, v253, 5
	v_readlane_b32 s18, v253, 6
	v_readlane_b32 s19, v253, 7
	v_readlane_b32 s20, v253, 8
	v_readlane_b32 s21, v253, 9
	v_readlane_b32 s22, v253, 10
	v_readlane_b32 s23, v253, 11
	v_readlane_b32 s24, v253, 12
	v_readlane_b32 s25, v253, 13
	s_waitcnt vmcnt(7)
	ds_write2_b32 v32, v0, v1 offset1:1
	ds_write2_b32 v32, v2, v3 offset0:2 offset1:3
	s_waitcnt vmcnt(6)
	ds_write2_b32 v34, v4, v5 offset1:1
	ds_write2_b32 v34, v6, v7 offset0:2 offset1:3
	s_waitcnt vmcnt(5)
	ds_write2_b32 v36, v8, v9 offset1:1
	ds_write2_b32 v36, v10, v11 offset0:2 offset1:3
	s_waitcnt vmcnt(4)
	ds_write2_b32 v38, v12, v13 offset1:1
	ds_write2_b32 v38, v14, v15 offset0:2 offset1:3
	s_waitcnt vmcnt(3)
	ds_write2_b32 v33, v16, v17 offset1:1
	ds_write2_b32 v35, v18, v19 offset1:1
	s_waitcnt vmcnt(2)
	ds_write2_b32 v37, v20, v21 offset1:1
	ds_write2_b32 v39, v22, v23 offset1:1
	v_add_u32_e32 v0, 0x4100, v36
	v_ashrrev_i32_e32 v16, 3, v40
	s_waitcnt vmcnt(1)
	ds_write2_b32 v0, v24, v25 offset1:1
	v_add_u32_e32 v0, 0x4108, v36
	ds_write2_b32 v0, v26, v27 offset1:1
	v_add_u32_e32 v0, 0x4100, v38
	s_waitcnt vmcnt(0)
	ds_write2_b32 v0, v28, v29 offset1:1
	v_add_u32_e32 v0, 0x4108, v38
	ds_write2_b32 v0, v30, v31 offset1:1
	v_lshlrev_b32_e32 v0, 3, v40
	v_and_b32_e32 v0, 56, v0
	v_mul_u32_u24_e32 v1, 0x41, v0
	v_lshlrev_b32_e32 v17, 2, v1
	v_lshl_add_u32 v19, v16, 2, v17
	s_waitcnt lgkmcnt(0)
	s_barrier
	ds_read2_b32 v[2:3], v19 offset1:65
	ds_read2_b32 v[8:9], v19 offset0:130 offset1:195
	v_lshlrev_b32_e32 v192, 1, v0
	v_add_lshl_u32 v0, v16, s4, 1
	v_and_b32_e32 v18, 31, v16
	v_and_or_b32 v0, v0, s1, v18
	v_add_u32_e32 v1, 0x400, v19
	v_lshl_add_u64 v[4:5], s[10:11], 0, v[192:193]
	ds_read2_b32 v[10:11], v1 offset0:4 offset1:69
	ds_read2_b32 v[12:13], v1 offset0:134 offset1:199
	v_ashrrev_i32_e32 v1, 31, v0
	v_lshl_add_u64 v[6:7], s[6:7], 1, v[4:5]
	v_lshlrev_b64 v[0:1], 11, v[0:1]
	v_lshl_add_u64 v[14:15], v[6:7], 0, v[0:1]
	s_waitcnt lgkmcnt(2)
	v_and_b32_sdwa v1, v2, v218 dst_sel:DWORD dst_unused:UNUSED_PAD src0_sel:WORD_1 src1_sel:DWORD
	v_add3_u32 v2, v2, v1, s80
	v_cvt_pk_bf16_f32 v1, v8, v9
	v_and_b32_sdwa v8, v3, v218 dst_sel:DWORD dst_unused:UNUSED_PAD src0_sel:WORD_1 src1_sel:DWORD
	v_add3_u32 v3, v3, v8, s80
	v_and_b32_e32 v3, 0xffff0000, v3
	v_or_b32_sdwa v0, v3, v2 dst_sel:DWORD dst_unused:UNUSED_PAD src0_sel:DWORD src1_sel:WORD_1
	s_waitcnt lgkmcnt(1)
	s_waitcnt lgkmcnt(0)
	v_cvt_pk_bf16_f32 v3, v12, v13
	v_cvt_pk_bf16_f32 v2, v10, v11
	global_store_dwordx4 v[14:15], v[0:3], off
	v_ashrrev_i32_e32 v14, 3, v41
	v_lshl_add_u32 v17, v14, 2, v17
	ds_read2_b32 v[2:3], v17 offset1:65
	ds_read2_b32 v[8:9], v17 offset0:130 offset1:195
	v_add_lshl_u32 v0, v14, s4, 1
	v_and_b32_e32 v15, 31, v14
	v_and_or_b32 v0, v0, s1, v15
	v_add_u32_e32 v1, 0x400, v17
	ds_read2_b32 v[10:11], v1 offset0:4 offset1:69
	ds_read2_b32 v[12:13], v1 offset0:134 offset1:199
	v_ashrrev_i32_e32 v1, 31, v0
	v_lshlrev_b64 v[0:1], 11, v[0:1]
	v_lshl_add_u64 v[6:7], v[6:7], 0, v[0:1]
	s_waitcnt lgkmcnt(2)
	v_and_b32_sdwa v1, v2, v218 dst_sel:DWORD dst_unused:UNUSED_PAD src0_sel:WORD_1 src1_sel:DWORD
	v_add3_u32 v2, v2, v1, s80
	v_cvt_pk_bf16_f32 v1, v8, v9
	v_and_b32_sdwa v8, v3, v218 dst_sel:DWORD dst_unused:UNUSED_PAD src0_sel:WORD_1 src1_sel:DWORD
	v_add3_u32 v3, v3, v8, s80
	v_and_b32_e32 v3, 0xffff0000, v3
	v_or_b32_sdwa v0, v3, v2 dst_sel:DWORD dst_unused:UNUSED_PAD src0_sel:DWORD src1_sel:WORD_1
	s_waitcnt lgkmcnt(1)
	s_waitcnt lgkmcnt(0)
	v_cvt_pk_bf16_f32 v3, v12, v13
	v_cvt_pk_bf16_f32 v2, v10, v11
	global_store_dwordx4 v[6:7], v[0:3], off
	v_lshl_add_u64 v[4:5], s[2:3], 1, v[4:5]
	s_nop 0
	v_add_u32_e32 v1, 0x4000, v19
	ds_read2_b32 v[2:3], v1 offset0:64 offset1:129
	v_add_u32_e32 v1, 0x4200, v19
	ds_read2_b32 v[6:7], v1 offset0:66 offset1:131
	v_add_lshl_u32 v0, v16, s0, 1
	v_add_u32_e32 v1, 0x4400, v19
	v_and_or_b32 v0, v0, s1, v18
	ds_read2_b32 v[8:9], v1 offset0:68 offset1:133
	v_add_u32_e32 v1, 0x4600, v19
	ds_read2_b32 v[10:11], v1 offset0:70 offset1:135
	v_ashrrev_i32_e32 v1, 31, v0
	v_lshlrev_b64 v[0:1], 11, v[0:1]
	v_lshl_add_u64 v[12:13], v[4:5], 0, v[0:1]
	s_waitcnt lgkmcnt(2)
	v_and_b32_sdwa v1, v2, v218 dst_sel:DWORD dst_unused:UNUSED_PAD src0_sel:WORD_1 src1_sel:DWORD
	v_add3_u32 v2, v2, v1, s80
	v_cvt_pk_bf16_f32 v1, v6, v7
	v_and_b32_sdwa v6, v3, v218 dst_sel:DWORD dst_unused:UNUSED_PAD src0_sel:WORD_1 src1_sel:DWORD
	v_add3_u32 v3, v3, v6, s80
	v_and_b32_e32 v3, 0xffff0000, v3
	v_or_b32_sdwa v0, v3, v2 dst_sel:DWORD dst_unused:UNUSED_PAD src0_sel:DWORD src1_sel:WORD_1
	s_waitcnt lgkmcnt(1)
	s_waitcnt lgkmcnt(0)
	v_cvt_pk_bf16_f32 v3, v10, v11
	v_cvt_pk_bf16_f32 v2, v8, v9
	global_store_dwordx4 v[12:13], v[0:3], off
	s_nop 1
	v_add_u32_e32 v1, 0x4000, v17
	ds_read2_b32 v[2:3], v1 offset0:64 offset1:129
	v_add_u32_e32 v1, 0x4200, v17
	ds_read2_b32 v[6:7], v1 offset0:66 offset1:131
	v_add_lshl_u32 v0, v14, s0, 1
	v_add_u32_e32 v1, 0x4400, v17
	v_and_or_b32 v0, v0, s1, v15
	ds_read2_b32 v[8:9], v1 offset0:68 offset1:133
	v_add_u32_e32 v1, 0x4600, v17
	ds_read2_b32 v[10:11], v1 offset0:70 offset1:135
	v_ashrrev_i32_e32 v1, 31, v0
	v_lshlrev_b64 v[0:1], 11, v[0:1]
	v_lshl_add_u64 v[4:5], v[4:5], 0, v[0:1]
	s_waitcnt lgkmcnt(2)
	v_and_b32_sdwa v1, v2, v218 dst_sel:DWORD dst_unused:UNUSED_PAD src0_sel:WORD_1 src1_sel:DWORD
	v_add3_u32 v2, v2, v1, s80
	v_cvt_pk_bf16_f32 v1, v6, v7
	v_and_b32_sdwa v6, v3, v218 dst_sel:DWORD dst_unused:UNUSED_PAD src0_sel:WORD_1 src1_sel:DWORD
	v_add3_u32 v3, v3, v6, s80
	v_and_b32_e32 v3, 0xffff0000, v3
	v_or_b32_sdwa v0, v3, v2 dst_sel:DWORD dst_unused:UNUSED_PAD src0_sel:DWORD src1_sel:WORD_1
	s_waitcnt lgkmcnt(1)
	s_waitcnt lgkmcnt(0)
	v_cvt_pk_bf16_f32 v3, v10, v11
	v_cvt_pk_bf16_f32 v2, v8, v9
	global_store_dwordx4 v[4:5], v[0:3], off
	s_barrier

.LBB0_1123:
	s_andn2_b64 vcc, exec, s[0:1]
	s_cbranch_vccnz .LBB0_1125
	s_add_i32 s0, s9, 0xfd40
	s_sext_i32_i16 s1, s0
	s_mulk_i32 s1, 0x2aab
	s_lshr_b32 s2, s1, 31
	s_lshr_b32 s1, s1, 16
	s_add_i32 s1, s1, s2
	s_sext_i32_i16 s2, s1
	s_mul_i32 s1, s1, 6
	s_waitcnt vmcnt(6)
	v_mov_b32_e32 v40, v208
	s_sub_i32 s0, s0, s1
	v_readlane_b32 s12, v253, 0
	v_lshlrev_b32_e32 v0, 4, v40
	s_sext_i32_i16 s0, s0
	v_and_b32_e32 v192, 0xf0, v0
	v_readlane_b32 s14, v253, 2
	v_readlane_b32 s15, v253, 3
	s_lshl_b32 s4, s0, 6
	v_add_u32_e32 v41, 0x100, v40
	v_add_u32_e32 v10, 0x200, v40
	v_add_u32_e32 v12, 0x300, v40
	v_lshl_add_u64 v[16:17], s[14:15], 0, v[192:193]
	v_ashrrev_i32_e32 v32, 4, v40
	s_lshl_b32 s6, s2, 6
	s_ashr_i32 s5, s4, 31
	v_ashrrev_i32_e32 v34, 4, v41
	v_ashrrev_i32_e32 v36, 4, v10
	v_ashrrev_i32_e32 v38, 4, v12
	v_lshl_add_u64 v[8:9], s[4:5], 2, v[16:17]
	v_add_u32_e32 v0, s6, v32
	v_add_u32_e32 v2, s6, v34
	v_add_u32_e32 v10, s6, v36
	v_add_u32_e32 v12, s6, v38
	v_mad_i64_i32 v[0:1], s[0:1], v0, s68, v[8:9]
	v_mad_i64_i32 v[4:5], s[0:1], v2, s68, v[8:9]
	v_mad_i64_i32 v[10:11], s[0:1], v10, s68, v[8:9]
	v_mad_i64_i32 v[12:13], s[0:1], v12, s68, v[8:9]
	s_add_i32 s0, s9, 0xfd41
	s_sext_i32_i16 s1, s0
	s_mulk_i32 s1, 0x2aab
	s_lshr_b32 s2, s1, 31
	s_lshr_b32 s1, s1, 16
	s_add_i32 s1, s1, s2
	s_sext_i32_i16 s2, s1
	s_mul_i32 s1, s1, 6
	s_sub_i32 s0, s0, s1
	s_sext_i32_i16 s0, s0
	s_lshl_b32 s0, s0, 6
	s_lshl_b32 s2, s2, 6
	s_ashr_i32 s1, s0, 31
	v_lshl_add_u64 v[28:29], s[0:1], 2, v[16:17]
	v_add_u32_e32 v16, s2, v32
	v_add_u32_e32 v20, s2, v34
	global_load_dwordx4 v[0:3], v[0:1], off nt
	s_nop 0
	global_load_dwordx4 v[4:7], v[4:5], off nt
	s_nop 0
	global_load_dwordx4 v[8:11], v[10:11], off nt
	s_nop 0
	global_load_dwordx4 v[12:15], v[12:13], off nt
	v_mad_i64_i32 v[16:17], s[10:11], v16, s68, v[28:29]
	v_mad_i64_i32 v[20:21], s[10:11], v20, s68, v[28:29]
	v_add_u32_e32 v24, s2, v36
	global_load_dwordx4 v[16:19], v[16:17], off nt
	v_mad_i64_i32 v[24:25], s[10:11], v24, s68, v[28:29]
	global_load_dwordx4 v[20:23], v[20:21], off nt
	v_add_u32_e32 v30, s2, v38
	global_load_dwordx4 v[24:27], v[24:25], off nt
	v_mad_i64_i32 v[28:29], s[10:11], v30, s68, v[28:29]
	global_load_dwordx4 v[28:31], v[28:29], off nt
	s_movk_i32 s1, 0x104
	v_mad_u64_u32 v[32:33], s[10:11], v32, s1, v[192:193]
	v_mad_u64_u32 v[34:35], s[10:11], v34, s1, v[192:193]
	v_mad_u64_u32 v[36:37], s[10:11], v36, s1, v[192:193]
	v_mad_u64_u32 v[38:39], s[10:11], v38, s1, v[192:193]
	v_add_u32_e32 v33, 0x4100, v32
	v_add_u32_e32 v35, 0x4108, v32
	v_add_u32_e32 v37, 0x4100, v34
	v_readlane_b32 s10, v253, 32
	v_readlane_b32 s11, v253, 33
	s_ashr_i32 s7, s6, 31
	s_movk_i32 s1, 0x300
	s_ashr_i32 s3, s2, 31
	v_readlane_b32 s13, v253, 1
	v_readlane_b32 s16, v253, 4
	v_readlane_b32 s17, v253, 5
	v_readlane_b32 s18, v253, 6
	v_readlane_b32 s19, v253, 7
	v_readlane_b32 s20, v253, 8
	s_waitcnt vmcnt(7)
	ds_write2_b32 v32, v0, v1 offset1:1
	ds_write2_b32 v32, v2, v3 offset0:2 offset1:3
	s_waitcnt vmcnt(6)
	ds_write2_b32 v34, v4, v5 offset1:1
	ds_write2_b32 v34, v6, v7 offset0:2 offset1:3
	s_waitcnt vmcnt(5)
	ds_write2_b32 v36, v8, v9 offset1:1
	ds_write2_b32 v36, v10, v11 offset0:2 offset1:3
	s_waitcnt vmcnt(4)
	ds_write2_b32 v38, v12, v13 offset1:1
	ds_write2_b32 v38, v14, v15 offset0:2 offset1:3
	s_waitcnt vmcnt(3)
	ds_write2_b32 v33, v16, v17 offset1:1
	ds_write2_b32 v35, v18, v19 offset1:1
	s_waitcnt vmcnt(2)
	ds_write2_b32 v37, v20, v21 offset1:1
	v_add_u32_e32 v0, 0x4108, v34
	v_ashrrev_i32_e32 v14, 3, v40
	v_add_u32_e32 v12, s4, v14
	v_readlane_b32 s21, v253, 9
	v_readlane_b32 s22, v253, 10
	v_readlane_b32 s23, v253, 11
	v_readlane_b32 s24, v253, 12
	v_readlane_b32 s25, v253, 13
	ds_write2_b32 v0, v22, v23 offset1:1
	v_add_u32_e32 v0, 0x4100, v36
	s_waitcnt vmcnt(1)
	ds_write2_b32 v0, v24, v25 offset1:1
	v_add_u32_e32 v0, 0x4108, v36
	ds_write2_b32 v0, v26, v27 offset1:1
	v_add_u32_e32 v0, 0x4100, v38
	s_waitcnt vmcnt(0)
	ds_write2_b32 v0, v28, v29 offset1:1
	v_add_u32_e32 v0, 0x4108, v38
	ds_write2_b32 v0, v30, v31 offset1:1
	v_lshlrev_b32_e32 v0, 3, v40
	v_and_b32_e32 v0, 56, v0
	v_mul_u32_u24_e32 v1, 0x41, v0
	v_lshlrev_b32_e32 v15, 2, v1
	v_lshl_add_u32 v16, v14, 2, v15
	s_waitcnt lgkmcnt(0)
	s_barrier
	v_lshlrev_b32_e32 v192, 1, v0
	ds_read2_b32 v[0:1], v16 offset1:65
	ds_read2_b32 v[2:3], v16 offset0:130 offset1:195
	v_add_u32_e32 v10, 0x400, v16
	ds_read2_b32 v[8:9], v10 offset0:4 offset1:69
	ds_read2_b32 v[10:11], v10 offset0:134 offset1:199
	v_lshl_add_u64 v[4:5], s[10:11], 0, v[192:193]
	s_waitcnt lgkmcnt(3)
	v_cvt_pk_bf16_f32 v0, v0, v1
	s_waitcnt lgkmcnt(2)
	v_and_b32_sdwa v17, v2, v218 dst_sel:DWORD dst_unused:UNUSED_PAD src0_sel:WORD_1 src1_sel:DWORD
	v_add3_u32 v2, v2, v17, s80
	v_and_b32_sdwa v17, v3, v218 dst_sel:DWORD dst_unused:UNUSED_PAD src0_sel:WORD_1 src1_sel:DWORD
	v_add3_u32 v3, v3, v17, s80
	v_and_b32_e32 v3, 0xffff0000, v3
	v_or_b32_sdwa v1, v3, v2 dst_sel:DWORD dst_unused:UNUSED_PAD src0_sel:DWORD src1_sel:WORD_1
	s_waitcnt lgkmcnt(0)
	v_and_b32_sdwa v3, v8, v218 dst_sel:DWORD dst_unused:UNUSED_PAD src0_sel:WORD_1 src1_sel:DWORD
	v_add3_u32 v8, v8, v3, s80
	v_cvt_pk_bf16_f32 v3, v10, v11
	v_and_b32_sdwa v10, v9, v218 dst_sel:DWORD dst_unused:UNUSED_PAD src0_sel:WORD_1 src1_sel:DWORD
	v_add3_u32 v9, v9, v10, s80
	v_lshl_add_u64 v[6:7], s[6:7], 1, v[4:5]
	v_and_b32_e32 v9, 0xffff0000, v9
	v_mad_i64_i32 v[12:13], s[6:7], v12, s1, v[6:7]
	v_or_b32_sdwa v2, v9, v8 dst_sel:DWORD dst_unused:UNUSED_PAD src0_sel:DWORD src1_sel:WORD_1
	global_store_dwordx4 v[12:13], v[0:3], off
	v_ashrrev_i32_e32 v12, 3, v41
	v_lshl_add_u32 v15, v12, 2, v15
	ds_read2_b32 v[0:1], v15 offset1:65
	ds_read2_b32 v[2:3], v15 offset0:130 offset1:195
	v_add_u32_e32 v10, 0x400, v15
	v_add_u32_e32 v13, s4, v12
	ds_read2_b32 v[8:9], v10 offset0:4 offset1:69
	ds_read2_b32 v[10:11], v10 offset0:134 offset1:199
	v_mad_i64_i32 v[6:7], s[4:5], v13, s1, v[6:7]
	s_waitcnt lgkmcnt(2)
	v_and_b32_sdwa v13, v2, v218 dst_sel:DWORD dst_unused:UNUSED_PAD src0_sel:WORD_1 src1_sel:DWORD
	v_cvt_pk_bf16_f32 v0, v0, v1
	v_add3_u32 v2, v2, v13, s80
	v_and_b32_sdwa v13, v3, v218 dst_sel:DWORD dst_unused:UNUSED_PAD src0_sel:WORD_1 src1_sel:DWORD
	v_add3_u32 v3, v3, v13, s80
	v_and_b32_e32 v3, 0xffff0000, v3
	v_or_b32_sdwa v1, v3, v2 dst_sel:DWORD dst_unused:UNUSED_PAD src0_sel:DWORD src1_sel:WORD_1
	s_waitcnt lgkmcnt(0)
	v_and_b32_sdwa v3, v8, v218 dst_sel:DWORD dst_unused:UNUSED_PAD src0_sel:WORD_1 src1_sel:DWORD
	v_add3_u32 v8, v8, v3, s80
	v_cvt_pk_bf16_f32 v3, v10, v11
	v_and_b32_sdwa v10, v9, v218 dst_sel:DWORD dst_unused:UNUSED_PAD src0_sel:WORD_1 src1_sel:DWORD
	v_add3_u32 v9, v9, v10, s80
	v_and_b32_e32 v9, 0xffff0000, v9
	v_or_b32_sdwa v2, v9, v8 dst_sel:DWORD dst_unused:UNUSED_PAD src0_sel:DWORD src1_sel:WORD_1
	global_store_dwordx4 v[6:7], v[0:3], off
	v_add_u32_e32 v6, 0x4400, v16
	v_add_u32_e32 v8, 0x4600, v16
	v_add_u32_e32 v2, 0x4200, v16
	v_add_u32_e32 v0, 0x4000, v16
	ds_read2_b32 v[2:3], v2 offset0:66 offset1:131
	ds_read2_b32 v[0:1], v0 offset0:64 offset1:129
	ds_read2_b32 v[6:7], v6 offset0:68 offset1:133
	ds_read2_b32 v[8:9], v8 offset0:70 offset1:135
	v_add_u32_e32 v10, s0, v14
	s_waitcnt lgkmcnt(3)
	v_and_b32_sdwa v13, v2, v218 dst_sel:DWORD dst_unused:UNUSED_PAD src0_sel:WORD_1 src1_sel:DWORD
	s_waitcnt lgkmcnt(2)
	v_cvt_pk_bf16_f32 v0, v0, v1
	v_add3_u32 v2, v2, v13, s80
	v_and_b32_sdwa v13, v3, v218 dst_sel:DWORD dst_unused:UNUSED_PAD src0_sel:WORD_1 src1_sel:DWORD
	v_add3_u32 v3, v3, v13, s80
	v_and_b32_e32 v3, 0xffff0000, v3
	v_or_b32_sdwa v1, v3, v2 dst_sel:DWORD dst_unused:UNUSED_PAD src0_sel:DWORD src1_sel:WORD_1
	s_waitcnt lgkmcnt(0)
	v_and_b32_sdwa v3, v6, v218 dst_sel:DWORD dst_unused:UNUSED_PAD src0_sel:WORD_1 src1_sel:DWORD
	v_add3_u32 v6, v6, v3, s80
	v_cvt_pk_bf16_f32 v3, v8, v9
	v_and_b32_sdwa v8, v7, v218 dst_sel:DWORD dst_unused:UNUSED_PAD src0_sel:WORD_1 src1_sel:DWORD
	v_add3_u32 v7, v7, v8, s80
	v_lshl_add_u64 v[4:5], s[2:3], 1, v[4:5]
	v_and_b32_e32 v7, 0xffff0000, v7
	v_mad_i64_i32 v[10:11], s[2:3], v10, s1, v[4:5]
	v_or_b32_sdwa v2, v7, v6 dst_sel:DWORD dst_unused:UNUSED_PAD src0_sel:DWORD src1_sel:WORD_1
	global_store_dwordx4 v[10:11], v[0:3], off
	v_add_u32_e32 v6, 0x4400, v15
	v_add_u32_e32 v8, 0x4600, v15
	v_add_u32_e32 v2, 0x4200, v15
	v_add_u32_e32 v0, 0x4000, v15
	ds_read2_b32 v[2:3], v2 offset0:66 offset1:131
	ds_read2_b32 v[0:1], v0 offset0:64 offset1:129
	v_add_u32_e32 v10, s0, v12
	ds_read2_b32 v[6:7], v6 offset0:68 offset1:133
	ds_read2_b32 v[8:9], v8 offset0:70 offset1:135
	v_mad_i64_i32 v[4:5], s[0:1], v10, s1, v[4:5]
	s_waitcnt lgkmcnt(3)
	v_and_b32_sdwa v10, v2, v218 dst_sel:DWORD dst_unused:UNUSED_PAD src0_sel:WORD_1 src1_sel:DWORD
	s_waitcnt lgkmcnt(2)
	v_cvt_pk_bf16_f32 v0, v0, v1
	v_add3_u32 v2, v2, v10, s80
	v_and_b32_sdwa v10, v3, v218 dst_sel:DWORD dst_unused:UNUSED_PAD src0_sel:WORD_1 src1_sel:DWORD
	v_add3_u32 v3, v3, v10, s80
	v_and_b32_e32 v3, 0xffff0000, v3
	v_or_b32_sdwa v1, v3, v2 dst_sel:DWORD dst_unused:UNUSED_PAD src0_sel:DWORD src1_sel:WORD_1
	s_waitcnt lgkmcnt(0)
	v_and_b32_sdwa v3, v6, v218 dst_sel:DWORD dst_unused:UNUSED_PAD src0_sel:WORD_1 src1_sel:DWORD
	v_add3_u32 v6, v6, v3, s80
	v_cvt_pk_bf16_f32 v3, v8, v9
	v_and_b32_sdwa v8, v7, v218 dst_sel:DWORD dst_unused:UNUSED_PAD src0_sel:WORD_1 src1_sel:DWORD
	v_add3_u32 v7, v7, v8, s80
	v_and_b32_e32 v7, 0xffff0000, v7
	v_or_b32_sdwa v2, v7, v6 dst_sel:DWORD dst_unused:UNUSED_PAD src0_sel:DWORD src1_sel:WORD_1
	v_readlane_b32 s26, v253, 14
	v_readlane_b32 s27, v253, 15
	global_store_dwordx4 v[4:5], v[0:3], off
	s_barrier

.LBB0_1126:
	s_andn2_b64 vcc, exec, s[0:1]
	s_cbranch_vccnz .LBB0_1128
	s_add_i32 s0, s9, 0xfe40
	s_sext_i32_i16 s1, s0
	s_bfe_u32 s1, s1, 0x4001b
	s_add_i32 s1, s0, s1
	s_sext_i32_i16 s2, s1
	s_and_b32 s1, s1, 0xfff0
	s_sub_i32 s0, s0, s1
	s_sext_i32_i16 s0, s0
	s_lshl_b32 s4, s0, 6
	s_add_i32 s0, s9, 0xfe41
	s_sext_i32_i16 s1, s0
	s_bfe_u32 s1, s1, 0x4001b
	s_lshl_b32 s2, s2, 2
	s_add_i32 s1, s0, s1
	s_and_b32 s6, s2, 0xffffffc0
	s_sext_i32_i16 s2, s1
	s_and_b32 s1, s1, 0xfff0
	s_waitcnt vmcnt(6)
	v_mov_b32_e32 v40, v208
	s_sub_i32 s0, s0, s1
	v_readlane_b32 s12, v253, 0
	v_lshlrev_b32_e32 v0, 4, v40
	v_add_u32_e32 v41, 0x100, v40
	v_add_u32_e32 v10, 0x200, v40
	v_add_u32_e32 v12, 0x300, v40
	s_sext_i32_i16 s0, s0
	v_and_b32_e32 v192, 0xf0, v0
	v_readlane_b32 s20, v253, 8
	v_readlane_b32 s21, v253, 9
	v_ashrrev_i32_e32 v32, 4, v40
	v_ashrrev_i32_e32 v34, 4, v41
	v_ashrrev_i32_e32 v36, 4, v10
	v_ashrrev_i32_e32 v38, 4, v12
	s_lshl_b32 s2, s2, 2
	s_lshl_b32 s0, s0, 6
	v_lshl_add_u64 v[16:17], s[20:21], 0, v[192:193]
	s_ashr_i32 s5, s4, 31
	v_add_u32_e32 v0, s6, v32
	v_add_u32_e32 v2, s6, v34
	v_add_u32_e32 v10, s6, v36
	v_add_u32_e32 v12, s6, v38
	s_andn2_b32 s2, s2, 63
	s_ashr_i32 s1, s0, 31
	v_lshl_add_u64 v[8:9], s[4:5], 2, v[16:17]
	v_ashrrev_i32_e32 v1, 31, v0
	v_ashrrev_i32_e32 v3, 31, v2
	v_ashrrev_i32_e32 v11, 31, v10
	v_ashrrev_i32_e32 v13, 31, v12
	v_lshl_add_u64 v[28:29], s[0:1], 2, v[16:17]
	v_add_u32_e32 v16, s2, v32
	v_lshlrev_b64 v[0:1], 12, v[0:1]
	v_lshlrev_b64 v[2:3], 12, v[2:3]
	v_lshlrev_b64 v[10:11], 12, v[10:11]
	v_lshlrev_b64 v[12:13], 12, v[12:13]
	v_ashrrev_i32_e32 v17, 31, v16
	v_lshl_add_u64 v[0:1], v[8:9], 0, v[0:1]
	v_lshl_add_u64 v[4:5], v[8:9], 0, v[2:3]
	v_lshl_add_u64 v[10:11], v[8:9], 0, v[10:11]
	v_lshl_add_u64 v[12:13], v[8:9], 0, v[12:13]
	v_lshlrev_b64 v[16:17], 12, v[16:17]
	v_add_u32_e32 v20, s2, v34
	global_load_dwordx4 v[0:3], v[0:1], off nt
	s_nop 0
	global_load_dwordx4 v[4:7], v[4:5], off nt
	s_nop 0
	global_load_dwordx4 v[8:11], v[10:11], off nt
	s_nop 0
	global_load_dwordx4 v[12:15], v[12:13], off nt
	v_lshl_add_u64 v[16:17], v[28:29], 0, v[16:17]
	v_ashrrev_i32_e32 v21, 31, v20
	global_load_dwordx4 v[16:19], v[16:17], off nt
	v_lshlrev_b64 v[20:21], 12, v[20:21]
	v_add_u32_e32 v24, s2, v36
	v_lshl_add_u64 v[20:21], v[28:29], 0, v[20:21]
	v_ashrrev_i32_e32 v25, 31, v24
	global_load_dwordx4 v[20:23], v[20:21], off nt
	v_lshlrev_b64 v[24:25], 12, v[24:25]
	v_add_u32_e32 v30, s2, v38
	v_lshl_add_u64 v[24:25], v[28:29], 0, v[24:25]
	v_ashrrev_i32_e32 v31, 31, v30
	global_load_dwordx4 v[24:27], v[24:25], off nt
	v_lshlrev_b64 v[30:31], 12, v[30:31]
	v_lshl_add_u64 v[28:29], v[28:29], 0, v[30:31]
	global_load_dwordx4 v[28:31], v[28:29], off nt
	s_movk_i32 s1, 0x104
	v_mad_u64_u32 v[32:33], s[10:11], v32, s1, v[192:193]
	v_mad_u64_u32 v[34:35], s[10:11], v34, s1, v[192:193]
	v_mad_u64_u32 v[36:37], s[10:11], v36, s1, v[192:193]
	v_mad_u64_u32 v[38:39], s[10:11], v38, s1, v[192:193]
	v_readlane_b32 s10, v253, 34
	v_readlane_b32 s11, v253, 35
	s_ashr_i32 s7, s6, 31
	s_waitcnt vmcnt(7)
	ds_write2_b32 v32, v0, v1 offset1:1
	ds_write2_b32 v32, v2, v3 offset0:2 offset1:3
	s_waitcnt vmcnt(6)
	ds_write2_b32 v34, v4, v5 offset1:1
	ds_write2_b32 v34, v6, v7 offset0:2 offset1:3
	s_waitcnt vmcnt(5)
	ds_write2_b32 v36, v8, v9 offset1:1
	ds_write2_b32 v36, v10, v11 offset0:2 offset1:3
	s_waitcnt vmcnt(4)
	ds_write2_b32 v38, v12, v13 offset1:1
	ds_write2_b32 v38, v14, v15 offset0:2 offset1:3
	v_add_u32_e32 v0, 0x4100, v32
	s_ashr_i32 s3, s2, 31
	s_waitcnt vmcnt(3)
	ds_write2_b32 v0, v16, v17 offset1:1
	v_add_u32_e32 v0, 0x4108, v32
	ds_write2_b32 v0, v18, v19 offset1:1
	v_add_u32_e32 v0, 0x4100, v34
	v_ashrrev_i32_e32 v16, 3, v40
	s_waitcnt vmcnt(2)
	ds_write2_b32 v0, v20, v21 offset1:1
	v_add_u32_e32 v0, 0x4108, v34
	ds_write2_b32 v0, v22, v23 offset1:1
	v_add_u32_e32 v0, 0x4100, v36
	v_readlane_b32 s13, v253, 1
	s_waitcnt vmcnt(1)
	ds_write2_b32 v0, v24, v25 offset1:1
	v_add_u32_e32 v0, 0x4108, v36
	ds_write2_b32 v0, v26, v27 offset1:1
	v_add_u32_e32 v0, 0x4100, v38
	s_waitcnt vmcnt(0)
	ds_write2_b32 v0, v28, v29 offset1:1
	v_add_u32_e32 v0, 0x4108, v38
	ds_write2_b32 v0, v30, v31 offset1:1
	v_lshlrev_b32_e32 v0, 3, v40
	v_and_b32_e32 v0, 56, v0
	v_mul_u32_u24_e32 v1, 0x41, v0
	v_lshlrev_b32_e32 v17, 2, v1
	v_lshl_add_u32 v18, v16, 2, v17
	s_waitcnt lgkmcnt(0)
	s_barrier
	ds_read2_b32 v[2:3], v18 offset1:65
	ds_read2_b32 v[8:9], v18 offset0:130 offset1:195
	v_lshlrev_b32_e32 v192, 1, v0
	v_add_u32_e32 v0, s4, v16
	v_add_u32_e32 v1, 0x400, v18
	v_lshl_add_u64 v[4:5], s[10:11], 0, v[192:193]
	ds_read2_b32 v[10:11], v1 offset0:4 offset1:69
	ds_read2_b32 v[12:13], v1 offset0:134 offset1:199
	v_ashrrev_i32_e32 v1, 31, v0
	v_lshl_add_u64 v[6:7], s[6:7], 1, v[4:5]
	v_lshlrev_b64 v[0:1], 11, v[0:1]
	v_lshl_add_u64 v[14:15], v[6:7], 0, v[0:1]
	s_waitcnt lgkmcnt(2)
	v_and_b32_sdwa v1, v2, v218 dst_sel:DWORD dst_unused:UNUSED_PAD src0_sel:WORD_1 src1_sel:DWORD
	v_add3_u32 v2, v2, v1, s80
	v_cvt_pk_bf16_f32 v1, v8, v9
	v_and_b32_sdwa v8, v3, v218 dst_sel:DWORD dst_unused:UNUSED_PAD src0_sel:WORD_1 src1_sel:DWORD
	v_add3_u32 v3, v3, v8, s80
	v_and_b32_e32 v3, 0xffff0000, v3
	v_or_b32_sdwa v0, v3, v2 dst_sel:DWORD dst_unused:UNUSED_PAD src0_sel:DWORD src1_sel:WORD_1
	s_waitcnt lgkmcnt(1)
	s_waitcnt lgkmcnt(0)
	v_cvt_pk_bf16_f32 v3, v12, v13
	v_cvt_pk_bf16_f32 v2, v10, v11
	global_store_dwordx4 v[14:15], v[0:3], off
	v_ashrrev_i32_e32 v14, 3, v41
	v_lshl_add_u32 v15, v14, 2, v17
	ds_read2_b32 v[2:3], v15 offset1:65
	ds_read2_b32 v[8:9], v15 offset0:130 offset1:195
	v_add_u32_e32 v0, s4, v14
	v_add_u32_e32 v1, 0x400, v15
	ds_read2_b32 v[10:11], v1 offset0:4 offset1:69
	ds_read2_b32 v[12:13], v1 offset0:134 offset1:199
	v_ashrrev_i32_e32 v1, 31, v0
	v_lshlrev_b64 v[0:1], 11, v[0:1]
	v_lshl_add_u64 v[6:7], v[6:7], 0, v[0:1]
	s_waitcnt lgkmcnt(2)
	v_and_b32_sdwa v1, v2, v218 dst_sel:DWORD dst_unused:UNUSED_PAD src0_sel:WORD_1 src1_sel:DWORD
	v_add3_u32 v2, v2, v1, s80
	v_cvt_pk_bf16_f32 v1, v8, v9
	v_and_b32_sdwa v8, v3, v218 dst_sel:DWORD dst_unused:UNUSED_PAD src0_sel:WORD_1 src1_sel:DWORD
	v_add3_u32 v3, v3, v8, s80
	v_and_b32_e32 v3, 0xffff0000, v3
	v_or_b32_sdwa v0, v3, v2 dst_sel:DWORD dst_unused:UNUSED_PAD src0_sel:DWORD src1_sel:WORD_1
	s_waitcnt lgkmcnt(1)
	s_waitcnt lgkmcnt(0)
	v_cvt_pk_bf16_f32 v3, v12, v13
	v_cvt_pk_bf16_f32 v2, v10, v11
	global_store_dwordx4 v[6:7], v[0:3], off
	v_lshl_add_u64 v[4:5], s[2:3], 1, v[4:5]
	v_readlane_b32 s14, v253, 2
	v_add_u32_e32 v1, 0x4000, v18
	ds_read2_b32 v[2:3], v1 offset0:64 offset1:129
	v_add_u32_e32 v1, 0x4200, v18
	ds_read2_b32 v[6:7], v1 offset0:66 offset1:131
	v_add_u32_e32 v1, 0x4400, v18
	v_add_u32_e32 v0, s0, v16
	ds_read2_b32 v[8:9], v1 offset0:68 offset1:133
	v_add_u32_e32 v1, 0x4600, v18
	ds_read2_b32 v[10:11], v1 offset0:70 offset1:135
	v_ashrrev_i32_e32 v1, 31, v0
	v_lshlrev_b64 v[0:1], 11, v[0:1]
	v_lshl_add_u64 v[12:13], v[4:5], 0, v[0:1]
	s_waitcnt lgkmcnt(2)
	v_and_b32_sdwa v1, v2, v218 dst_sel:DWORD dst_unused:UNUSED_PAD src0_sel:WORD_1 src1_sel:DWORD
	v_add3_u32 v2, v2, v1, s80
	v_cvt_pk_bf16_f32 v1, v6, v7
	v_and_b32_sdwa v6, v3, v218 dst_sel:DWORD dst_unused:UNUSED_PAD src0_sel:WORD_1 src1_sel:DWORD
	v_add3_u32 v3, v3, v6, s80
	v_and_b32_e32 v3, 0xffff0000, v3
	v_or_b32_sdwa v0, v3, v2 dst_sel:DWORD dst_unused:UNUSED_PAD src0_sel:DWORD src1_sel:WORD_1
	s_waitcnt lgkmcnt(1)
	s_waitcnt lgkmcnt(0)
	v_cvt_pk_bf16_f32 v3, v10, v11
	v_cvt_pk_bf16_f32 v2, v8, v9
	global_store_dwordx4 v[12:13], v[0:3], off
	v_readlane_b32 s15, v253, 3
	v_readlane_b32 s16, v253, 4
	v_add_u32_e32 v1, 0x4000, v15
	ds_read2_b32 v[2:3], v1 offset0:64 offset1:129
	v_add_u32_e32 v1, 0x4200, v15
	ds_read2_b32 v[6:7], v1 offset0:66 offset1:131
	v_add_u32_e32 v1, 0x4400, v15
	v_add_u32_e32 v0, s0, v14
	ds_read2_b32 v[8:9], v1 offset0:68 offset1:133
	v_add_u32_e32 v1, 0x4600, v15
	ds_read2_b32 v[10:11], v1 offset0:70 offset1:135
	v_ashrrev_i32_e32 v1, 31, v0
	v_lshlrev_b64 v[0:1], 11, v[0:1]
	v_lshl_add_u64 v[4:5], v[4:5], 0, v[0:1]
	s_waitcnt lgkmcnt(2)
	v_and_b32_sdwa v1, v2, v218 dst_sel:DWORD dst_unused:UNUSED_PAD src0_sel:WORD_1 src1_sel:DWORD
	v_add3_u32 v2, v2, v1, s80
	v_cvt_pk_bf16_f32 v1, v6, v7
	v_and_b32_sdwa v6, v3, v218 dst_sel:DWORD dst_unused:UNUSED_PAD src0_sel:WORD_1 src1_sel:DWORD
	v_add3_u32 v3, v3, v6, s80
	v_and_b32_e32 v3, 0xffff0000, v3
	v_or_b32_sdwa v0, v3, v2 dst_sel:DWORD dst_unused:UNUSED_PAD src0_sel:DWORD src1_sel:WORD_1
	s_waitcnt lgkmcnt(1)
	s_waitcnt lgkmcnt(0)
	v_cvt_pk_bf16_f32 v3, v10, v11
	v_cvt_pk_bf16_f32 v2, v8, v9
	v_readlane_b32 s17, v253, 5
	v_readlane_b32 s18, v253, 6
	v_readlane_b32 s19, v253, 7
	v_readlane_b32 s22, v253, 10
	v_readlane_b32 s23, v253, 11
	v_readlane_b32 s24, v253, 12
	v_readlane_b32 s25, v253, 13
	v_readlane_b32 s26, v253, 14
	v_readlane_b32 s27, v253, 15
	global_store_dwordx4 v[4:5], v[0:3], off
	s_barrier

.LBB0_1129:
	s_andn2_b64 vcc, exec, s[0:1]
	s_cbranch_vccnz .LBB0_1131
	s_bfe_u32 s0, s8, 0x70001
	s_mulk_i32 s0, 0x93
	s_lshr_b32 s4, s0, 10
	s_bfe_u32 s0, s9, 0xe0002
	s_mul_i32 s3, s0, 0x4925
	s_lshr_b32 s0, s3, 17
	s_mul_i32 s5, s0, 28
	s_waitcnt vmcnt(6)
	v_mov_b32_e32 v40, v208
	s_sub_i32 s0, s9, s5
	s_lshl_b32 s0, s0, 6
	v_lshlrev_b32_e32 v0, 4, v40
	v_and_b32_e32 v192, 0xf0, v0
	s_and_b32 s6, s0, 0xffc0
	v_add_u32_e32 v41, 0x100, v40
	v_add_u32_e32 v10, 0x200, v40
	v_add_u32_e32 v12, 0x300, v40
	v_lshl_add_u64 v[16:17], s[52:53], 0, v[192:193]
	v_ashrrev_i32_e32 v32, 4, v40
	s_lshl_b32 s2, s4, 6
	s_lshl_b32 s78, s6, 2
	v_ashrrev_i32_e32 v34, 4, v41
	v_ashrrev_i32_e32 v36, 4, v10
	v_ashrrev_i32_e32 v38, 4, v12
	v_lshl_add_u64 v[8:9], v[16:17], 0, s[78:79]
	v_add_u32_e32 v0, s2, v32
	s_movk_i32 s7, 0x1c00
	v_add_u32_e32 v2, s2, v34
	v_add_u32_e32 v10, s2, v36
	v_add_u32_e32 v12, s2, v38
	v_mad_i64_i32 v[0:1], s[0:1], v0, s7, v[8:9]
	v_mad_i64_i32 v[4:5], s[0:1], v2, s7, v[8:9]
	v_mad_i64_i32 v[10:11], s[0:1], v10, s7, v[8:9]
	v_mad_i64_i32 v[12:13], s[0:1], v12, s7, v[8:9]
	s_lshr_b32 s0, s3, 11
	s_and_b32 s1, s0, 0xffc0
	s_or_b32 s0, s9, 1
	s_sub_i32 s0, s0, s5
	s_lshl_b32 s0, s0, 6
	s_and_b32 s0, s0, 0xffc0
	s_lshl_b32 s78, s0, 2
	v_lshl_add_u64 v[28:29], v[16:17], 0, s[78:79]
	v_add_u32_e32 v16, s1, v32
	v_add_u32_e32 v18, s1, v34
	v_mad_i64_i32 v[16:17], s[2:3], v16, s7, v[28:29]
	v_mad_i64_i32 v[20:21], s[2:3], v18, s7, v[28:29]
	v_add_u32_e32 v24, s1, v36
	v_add_u32_e32 v30, s1, v38
	global_load_dwordx4 v[0:3], v[0:1], off nt
	s_nop 0
	global_load_dwordx4 v[4:7], v[4:5], off nt
	s_nop 0
	global_load_dwordx4 v[8:11], v[10:11], off nt
	s_nop 0
	global_load_dwordx4 v[12:15], v[12:13], off nt
	s_nop 0
	global_load_dwordx4 v[16:19], v[16:17], off nt
	s_nop 0
	global_load_dwordx4 v[20:23], v[20:21], off nt
	v_mad_i64_i32 v[24:25], s[2:3], v24, s7, v[28:29]
	v_mad_i64_i32 v[28:29], s[2:3], v30, s7, v[28:29]
	global_load_dwordx4 v[24:27], v[24:25], off nt
	s_movk_i32 s5, 0x104
	global_load_dwordx4 v[28:31], v[28:29], off nt
	v_mad_u64_u32 v[32:33], s[2:3], v32, s5, v[192:193]
	v_mad_u64_u32 v[34:35], s[2:3], v34, s5, v[192:193]
	v_mad_u64_u32 v[36:37], s[2:3], v36, s5, v[192:193]
	v_mad_u64_u32 v[38:39], s[2:3], v38, s5, v[192:193]
	v_add_u32_e32 v33, 0x4100, v32
	v_add_u32_e32 v35, 0x4108, v32
	v_add_u32_e32 v37, 0x4100, v34
	v_add_u32_e32 v39, 0x4108, v34
	v_add_u32_e32 v42, 0x4100, v36
	v_add_u32_e32 v43, 0x4108, v36
	s_lshl_b32 s78, s4, 7
	s_waitcnt vmcnt(7)
	ds_write2_b32 v32, v0, v1 offset1:1
	ds_write2_b32 v32, v2, v3 offset0:2 offset1:3
	s_waitcnt vmcnt(6)
	ds_write2_b32 v34, v4, v5 offset1:1
	ds_write2_b32 v34, v6, v7 offset0:2 offset1:3
	s_waitcnt vmcnt(5)
	ds_write2_b32 v36, v8, v9 offset1:1
	ds_write2_b32 v36, v10, v11 offset0:2 offset1:3
	s_waitcnt vmcnt(4)
	ds_write2_b32 v38, v12, v13 offset1:1
	ds_write2_b32 v38, v14, v15 offset0:2 offset1:3
	s_waitcnt vmcnt(3)
	ds_write2_b32 v33, v16, v17 offset1:1
	ds_write2_b32 v35, v18, v19 offset1:1
	s_waitcnt vmcnt(2)
	ds_write2_b32 v37, v20, v21 offset1:1
	ds_write2_b32 v39, v22, v23 offset1:1
	s_waitcnt vmcnt(1)
	ds_write2_b32 v42, v24, v25 offset1:1
	ds_write2_b32 v43, v26, v27 offset1:1
	v_add_u32_e32 v0, 0x4100, v38
	v_ashrrev_i32_e32 v16, 3, v40
	s_waitcnt vmcnt(0)
	ds_write2_b32 v0, v28, v29 offset1:1
	v_add_u32_e32 v0, 0x4108, v38
	ds_write2_b32 v0, v30, v31 offset1:1
	v_lshlrev_b32_e32 v0, 3, v40
	v_and_b32_e32 v0, 56, v0
	v_mul_u32_u24_e32 v1, 0x41, v0
	v_lshlrev_b32_e32 v17, 2, v1
	v_lshl_add_u32 v18, v16, 2, v17
	s_waitcnt lgkmcnt(0)
	s_barrier
	ds_read2_b32 v[2:3], v18 offset1:65
	ds_read2_b32 v[8:9], v18 offset0:130 offset1:195
	v_lshlrev_b32_e32 v192, 1, v0
	v_add_u32_e32 v0, s6, v16
	v_add_u32_e32 v1, 0x400, v18
	v_lshl_add_u64 v[4:5], s[90:91], 0, v[192:193]
	ds_read2_b32 v[10:11], v1 offset0:4 offset1:69
	ds_read2_b32 v[12:13], v1 offset0:134 offset1:199
	v_ashrrev_i32_e32 v1, 31, v0
	v_lshl_add_u64 v[6:7], v[4:5], 0, s[78:79]
	v_lshlrev_b64 v[0:1], 11, v[0:1]
	v_lshl_add_u64 v[14:15], v[6:7], 0, v[0:1]
	s_waitcnt lgkmcnt(2)
	v_and_b32_sdwa v1, v2, v218 dst_sel:DWORD dst_unused:UNUSED_PAD src0_sel:WORD_1 src1_sel:DWORD
	v_add3_u32 v2, v2, v1, s80
	v_cvt_pk_bf16_f32 v1, v8, v9
	v_and_b32_sdwa v8, v3, v218 dst_sel:DWORD dst_unused:UNUSED_PAD src0_sel:WORD_1 src1_sel:DWORD
	v_add3_u32 v3, v3, v8, s80
	v_and_b32_e32 v3, 0xffff0000, v3
	v_or_b32_sdwa v0, v3, v2 dst_sel:DWORD dst_unused:UNUSED_PAD src0_sel:DWORD src1_sel:WORD_1
	s_waitcnt lgkmcnt(1)
	s_waitcnt lgkmcnt(0)
	v_cvt_pk_bf16_f32 v3, v12, v13
	v_cvt_pk_bf16_f32 v2, v10, v11
	global_store_dwordx4 v[14:15], v[0:3], off
	v_ashrrev_i32_e32 v14, 3, v41
	v_lshl_add_u32 v15, v14, 2, v17
	ds_read2_b32 v[2:3], v15 offset1:65
	ds_read2_b32 v[8:9], v15 offset0:130 offset1:195
	v_add_u32_e32 v0, s6, v14
	v_add_u32_e32 v1, 0x400, v15
	ds_read2_b32 v[10:11], v1 offset0:4 offset1:69
	ds_read2_b32 v[12:13], v1 offset0:134 offset1:199
	v_ashrrev_i32_e32 v1, 31, v0
	v_lshlrev_b64 v[0:1], 11, v[0:1]
	v_lshl_add_u64 v[6:7], v[6:7], 0, v[0:1]
	s_waitcnt lgkmcnt(2)
	v_and_b32_sdwa v1, v2, v218 dst_sel:DWORD dst_unused:UNUSED_PAD src0_sel:WORD_1 src1_sel:DWORD
	v_add3_u32 v2, v2, v1, s80
	v_cvt_pk_bf16_f32 v1, v8, v9
	v_and_b32_sdwa v8, v3, v218 dst_sel:DWORD dst_unused:UNUSED_PAD src0_sel:WORD_1 src1_sel:DWORD
	v_add3_u32 v3, v3, v8, s80
	v_and_b32_e32 v3, 0xffff0000, v3
	v_or_b32_sdwa v0, v3, v2 dst_sel:DWORD dst_unused:UNUSED_PAD src0_sel:DWORD src1_sel:WORD_1
	s_waitcnt lgkmcnt(1)
	s_waitcnt lgkmcnt(0)
	v_cvt_pk_bf16_f32 v3, v12, v13
	v_cvt_pk_bf16_f32 v2, v10, v11
	global_store_dwordx4 v[6:7], v[0:3], off
	s_lshl_b32 s78, s1, 1
	v_lshl_add_u64 v[4:5], v[4:5], 0, s[78:79]
	v_add_u32_e32 v1, 0x4000, v18
	ds_read2_b32 v[2:3], v1 offset0:64 offset1:129
	v_add_u32_e32 v1, 0x4200, v18
	ds_read2_b32 v[6:7], v1 offset0:66 offset1:131
	v_add_u32_e32 v1, 0x4400, v18
	v_add_u32_e32 v0, s0, v16
	ds_read2_b32 v[8:9], v1 offset0:68 offset1:133
	v_add_u32_e32 v1, 0x4600, v18
	ds_read2_b32 v[10:11], v1 offset0:70 offset1:135
	v_ashrrev_i32_e32 v1, 31, v0
	v_lshlrev_b64 v[0:1], 11, v[0:1]
	v_lshl_add_u64 v[12:13], v[4:5], 0, v[0:1]
	s_waitcnt lgkmcnt(2)
	v_and_b32_sdwa v1, v2, v218 dst_sel:DWORD dst_unused:UNUSED_PAD src0_sel:WORD_1 src1_sel:DWORD
	v_add3_u32 v2, v2, v1, s80
	v_cvt_pk_bf16_f32 v1, v6, v7
	v_and_b32_sdwa v6, v3, v218 dst_sel:DWORD dst_unused:UNUSED_PAD src0_sel:WORD_1 src1_sel:DWORD
	v_add3_u32 v3, v3, v6, s80
	v_and_b32_e32 v3, 0xffff0000, v3
	v_or_b32_sdwa v0, v3, v2 dst_sel:DWORD dst_unused:UNUSED_PAD src0_sel:DWORD src1_sel:WORD_1
	s_waitcnt lgkmcnt(1)
	s_waitcnt lgkmcnt(0)
	v_cvt_pk_bf16_f32 v3, v10, v11
	v_cvt_pk_bf16_f32 v2, v8, v9
	global_store_dwordx4 v[12:13], v[0:3], off
	s_nop 1
	v_add_u32_e32 v1, 0x4000, v15
	ds_read2_b32 v[2:3], v1 offset0:64 offset1:129
	v_add_u32_e32 v1, 0x4200, v15
	ds_read2_b32 v[6:7], v1 offset0:66 offset1:131
	v_add_u32_e32 v1, 0x4400, v15
	v_add_u32_e32 v0, s0, v14
	ds_read2_b32 v[8:9], v1 offset0:68 offset1:133
	v_add_u32_e32 v1, 0x4600, v15
	ds_read2_b32 v[10:11], v1 offset0:70 offset1:135
	v_ashrrev_i32_e32 v1, 31, v0
	v_lshlrev_b64 v[0:1], 11, v[0:1]
	v_lshl_add_u64 v[4:5], v[4:5], 0, v[0:1]
	s_waitcnt lgkmcnt(2)
	v_and_b32_sdwa v1, v2, v218 dst_sel:DWORD dst_unused:UNUSED_PAD src0_sel:WORD_1 src1_sel:DWORD
	v_add3_u32 v2, v2, v1, s80
	v_cvt_pk_bf16_f32 v1, v6, v7
	v_and_b32_sdwa v6, v3, v218 dst_sel:DWORD dst_unused:UNUSED_PAD src0_sel:WORD_1 src1_sel:DWORD
	v_add3_u32 v3, v3, v6, s80
	v_and_b32_e32 v3, 0xffff0000, v3
	v_or_b32_sdwa v0, v3, v2 dst_sel:DWORD dst_unused:UNUSED_PAD src0_sel:DWORD src1_sel:WORD_1
	s_waitcnt lgkmcnt(1)
	s_waitcnt lgkmcnt(0)
	v_cvt_pk_bf16_f32 v3, v10, v11
	v_cvt_pk_bf16_f32 v2, v8, v9
	global_store_dwordx4 v[4:5], v[0:3], off
	s_barrier
